# v96 + all stores write-through (sc1) and the L2 write-back (buffer_wbl2) dropped from the grid barrier and the scan-unit flag release
# speedup vs baseline: 1.0135x; 1.0131x over previous
; #define GAS __attribute__((address_space(1)))
; __device__ __forceinline__ float lx_get(float v, int src) { return __int_as_float(__builtin_amdgcn_readlane(__float_as_int(v), src)); }
; __device__ __forceinline__ void p_final(Frame& F) {
;     ...
;     for (int grp = gw; grp < MLAT / 16; grp += NGW) { const int rowb = grp * 16;
;         f32x4 qs = *(const GAS f32x4*)(RQ + (size_t)(F.lane >> 2) * MROWS + rowb + 4 * (F.lane & 3));
; #pragma unroll
;         for (int c = 0; c < 4; ++c) { float v = qs[c];
;             v += __int_as_float(__builtin_amdgcn_update_dpp(0, __float_as_int(v), 0x124, 0xF, 0xF, false)); v += __int_as_float(__builtin_amdgcn_update_dpp(0, __float_as_int(v), 0x128, 0xF, 0xF, false));
;             { auto r = __builtin_amdgcn_permlane16_swap(__float_as_uint(v), __float_as_uint(v), false, false); v = __uint_as_float(r[0]) + __uint_as_float(r[1]); }
;             { auto r = __builtin_amdgcn_permlane32_swap(__float_as_uint(v), __float_as_uint(v), false, false); v = __uint_as_float(r[0]) + __uint_as_float(r[1]); }
;             qs[c] = __builtin_amdgcn_rsqf(v * (1.f / 1024.f) + EPS); }
; #pragma unroll
;         for (int trip = 0; trip < 4; ++trip) {
;             h16x4 xv[4][4];
; #pragma unroll
;             for (int t = 0; t < 4; ++t)
; #pragma unroll
;                 for (int j = 0; j < 4; ++j) xv[t][j] = *(const GAS h16x4*)(X16 + (size_t)(rowb + 4 * trip + t) * D + j * 256 + F.lane * 4);
; #pragma unroll
;             for (int t = 0; t < 4; ++t) { const float rs = lx_get(qs[t], trip); float* orow = p.out + (size_t)(rowb + 4 * trip + t) * D;
; #pragma unroll
;                 for (int j = 0; j < 4; ++j) { const h16x4 v = xv[t][j];
;                     *(GAS f32x4*)(orow + j * 256 + F.lane * 4) = (f32x4){(float)v[0], (float)v[1], (float)v[2], (float)v[3]} * rs * gf[j]; } } }
.LBB0_19:
	s_add_i32 s4, s2, -15
	s_ashr_i32 s5, s4, 31
	v_lshl_add_u64 v[24:25], s[4:5], 2, v[18:19]
	global_load_dwordx4 v[24:27], v[24:25], off
	s_lshl_b64 s[6:7], s[4:5], 11
	s_add_i32 s10, s2, -14
	s_ashr_i32 s11, s10, 31
	s_add_i32 s8, s2, -13
	s_ashr_i32 s9, s8, 31
	s_lshl_b64 s[4:5], s[4:5], 12
	v_lshl_add_u64 v[64:65], v[22:23], 0, s[4:5]
	s_ashr_i32 s3, s2, 31
	s_add_i32 s12, s12, s78
	s_waitcnt vmcnt(0)
	v_add_f32_dpp v0, v24, v24 row_ror:4 row_mask:0xf bank_mask:0xf bound_ctrl:1
	s_nop 1
	v_add_f32_dpp v0, v0, v0 row_ror:8 row_mask:0xf bank_mask:0xf bound_ctrl:1
	v_mov_b32_e32 v24, v0
	s_nop 1
	v_permlane16_swap_b32_e32 v0, v24
	v_add_f32_e32 v0, v0, v24
	v_mov_b32_e32 v24, v0
	s_nop 1
	v_permlane32_swap_b32_e32 v0, v24
	v_add_f32_e32 v0, v0, v24
	v_fmamk_f32 v0, v0, 0x3a800000, v229
	v_rsq_f32_e32 v34, v0
	s_nop 0
	v_add_f32_dpp v0, v25, v25 row_ror:4 row_mask:0xf bank_mask:0xf bound_ctrl:1
	s_nop 1
	v_add_f32_dpp v0, v0, v0 row_ror:8 row_mask:0xf bank_mask:0xf bound_ctrl:1
	v_mov_b32_e32 v24, v0
	s_nop 1
	v_permlane16_swap_b32_e32 v0, v24
	v_add_f32_e32 v0, v0, v24
	v_mov_b32_e32 v24, v0
	s_nop 1
	v_permlane32_swap_b32_e32 v0, v24
	v_add_f32_e32 v0, v0, v24
	v_fmamk_f32 v0, v0, 0x3a800000, v229
	v_rsq_f32_e32 v33, v0
	s_nop 0
	v_add_f32_dpp v0, v26, v26 row_ror:4 row_mask:0xf bank_mask:0xf bound_ctrl:1
	v_readlane_b32 s4, v33, 0
	s_nop 0
	v_add_f32_dpp v0, v0, v0 row_ror:8 row_mask:0xf bank_mask:0xf bound_ctrl:1
	v_mov_b32_e32 v24, v0
	s_nop 1
	v_permlane16_swap_b32_e32 v0, v24
	v_add_f32_e32 v0, v0, v24
	v_mov_b32_e32 v24, v0
	s_nop 1
	v_permlane32_swap_b32_e32 v0, v24
	v_add_f32_e32 v0, v0, v24
	v_fmamk_f32 v0, v0, 0x3a800000, v229
	v_rsq_f32_e32 v32, v0
	s_nop 0
	v_add_f32_dpp v0, v27, v27 row_ror:4 row_mask:0xf bank_mask:0xf bound_ctrl:1
	s_nop 1
	v_add_f32_dpp v0, v0, v0 row_ror:8 row_mask:0xf bank_mask:0xf bound_ctrl:1
	v_mov_b32_e32 v24, v0
	s_nop 1
	v_permlane16_swap_b32_e32 v0, v24
	v_add_f32_e32 v0, v0, v24
	v_mov_b32_e32 v24, v0
	s_nop 1
	v_permlane32_swap_b32_e32 v0, v24
	v_add_f32_e32 v0, v0, v24
	v_lshl_add_u64 v[24:25], v[20:21], 0, s[6:7]
	global_load_dwordx2 v[30:31], v[24:25], off
	global_load_dwordx2 v[28:29], v[24:25], off offset:512
	global_load_dwordx2 v[26:27], v[24:25], off offset:1024
	s_nop 0
	global_load_dwordx2 v[24:25], v[24:25], off offset:1536
	s_lshl_b64 s[6:7], s[10:11], 11
	v_lshl_add_u64 v[36:37], v[20:21], 0, s[6:7]
	global_load_dwordx2 v[40:41], v[36:37], off
	global_load_dwordx2 v[42:43], v[36:37], off offset:512
	global_load_dwordx2 v[44:45], v[36:37], off offset:1024
	global_load_dwordx2 v[46:47], v[36:37], off offset:1536
	s_lshl_b64 s[6:7], s[8:9], 11
	v_lshl_add_u64 v[36:37], v[20:21], 0, s[6:7]
	global_load_dwordx2 v[48:49], v[36:37], off
	global_load_dwordx2 v[50:51], v[36:37], off offset:512
	global_load_dwordx2 v[52:53], v[36:37], off offset:1024
	global_load_dwordx2 v[54:55], v[36:37], off offset:1536
	s_add_i32 s6, s2, -12
	s_ashr_i32 s7, s6, 31
	s_lshl_b64 s[14:15], s[6:7], 11
	v_lshl_add_u64 v[36:37], v[20:21], 0, s[14:15]
	global_load_dwordx2 v[56:57], v[36:37], off
	global_load_dwordx2 v[58:59], v[36:37], off offset:512
	global_load_dwordx2 v[60:61], v[36:37], off offset:1024
	global_load_dwordx2 v[62:63], v[36:37], off offset:1536
	v_readlane_b32 s14, v34, 0
	s_lshl_b64 s[10:11], s[10:11], 12
	s_lshl_b64 s[8:9], s[8:9], 12
	v_fmamk_f32 v0, v0, 0x3a800000, v229
	v_rsq_f32_e32 v0, v0
	s_lshl_b64 s[6:7], s[6:7], 12
	s_waitcnt vmcnt(15)
	v_cvt_f32_f16_e32 v36, v30
	v_cvt_f32_f16_sdwa v37, v30 dst_sel:DWORD dst_unused:UNUSED_PAD src0_sel:WORD_1
	v_cvt_f32_f16_e32 v30, v31
	v_cvt_f32_f16_sdwa v31, v31 dst_sel:DWORD dst_unused:UNUSED_PAD src0_sel:WORD_1
	v_pk_mul_f32 v[36:37], v[36:37], s[14:15] op_sel_hi:[1,0]
	s_nop 0
	v_pk_mul_f32 v[36:37], v[2:3], v[36:37]
	v_pk_mul_f32 v[30:31], v[30:31], s[14:15] op_sel_hi:[1,0]
	s_nop 0
	v_pk_mul_f32 v[38:39], v[4:5], v[30:31]
	s_waitcnt vmcnt(14)
	v_cvt_f32_f16_e32 v30, v28
	v_cvt_f32_f16_sdwa v31, v28 dst_sel:DWORD dst_unused:UNUSED_PAD src0_sel:WORD_1
	v_cvt_f32_f16_e32 v28, v29
	v_cvt_f32_f16_sdwa v29, v29 dst_sel:DWORD dst_unused:UNUSED_PAD src0_sel:WORD_1
	global_store_dwordx4 v[64:65], v[36:39], off sc1
	v_pk_mul_f32 v[28:29], v[28:29], s[14:15] op_sel_hi:[1,0]
	s_nop 0
	v_pk_mul_f32 v[36:37], v[30:31], s[14:15] op_sel_hi:[1,0]
	v_pk_mul_f32 v[30:31], v[8:9], v[28:29]
	v_pk_mul_f32 v[28:29], v[6:7], v[36:37]
	global_store_dwordx4 v[64:65], v[28:31], off offset:1024 sc1
	s_waitcnt vmcnt(15)
	s_nop 0
	v_cvt_f32_f16_e32 v28, v26
	v_cvt_f32_f16_sdwa v29, v26 dst_sel:DWORD dst_unused:UNUSED_PAD src0_sel:WORD_1
	v_cvt_f32_f16_e32 v26, v27
	v_cvt_f32_f16_sdwa v27, v27 dst_sel:DWORD dst_unused:UNUSED_PAD src0_sel:WORD_1
	v_pk_mul_f32 v[30:31], v[28:29], s[14:15] op_sel_hi:[1,0]
	v_pk_mul_f32 v[26:27], v[26:27], s[14:15] op_sel_hi:[1,0]
	s_nop 0
	v_pk_mul_f32 v[28:29], v[12:13], v[26:27]
	v_pk_mul_f32 v[26:27], v[10:11], v[30:31]
	global_store_dwordx4 v[64:65], v[26:29], off offset:2048 sc1
	s_waitcnt vmcnt(15)
	s_nop 0
	v_cvt_f32_f16_e32 v26, v24
	v_cvt_f32_f16_sdwa v27, v24 dst_sel:DWORD dst_unused:UNUSED_PAD src0_sel:WORD_1
	v_cvt_f32_f16_e32 v24, v25
	v_cvt_f32_f16_sdwa v25, v25 dst_sel:DWORD dst_unused:UNUSED_PAD src0_sel:WORD_1
	v_pk_mul_f32 v[28:29], v[26:27], s[14:15] op_sel_hi:[1,0]
	v_pk_mul_f32 v[24:25], v[24:25], s[14:15] op_sel_hi:[1,0]
	s_nop 0
	v_pk_mul_f32 v[26:27], v[16:17], v[24:25]
	v_pk_mul_f32 v[24:25], v[14:15], v[28:29]
	global_store_dwordx4 v[64:65], v[24:27], off offset:3072 sc1
	v_lshl_add_u64 v[28:29], v[22:23], 0, s[10:11]
	s_add_i32 s10, s2, -11
	s_waitcnt vmcnt(15)
; #define GAS __attribute__((address_space(1)))
; __device__ __forceinline__ float lx_get(float v, int src) { return __int_as_float(__builtin_amdgcn_readlane(__float_as_int(v), src)); }
; __device__ __forceinline__ void p_final(Frame& F) {
;     ...
;         for (int trip = 0; trip < 4; ++trip) {
;             h16x4 xv[4][4];
; #pragma unroll
;             for (int t = 0; t < 4; ++t)
; #pragma unroll
;                 for (int j = 0; j < 4; ++j) xv[t][j] = *(const GAS h16x4*)(X16 + (size_t)(rowb + 4 * trip + t) * D + j * 256 + F.lane * 4);
; #pragma unroll
;             for (int t = 0; t < 4; ++t) { const float rs = lx_get(qs[t], trip); float* orow = p.out + (size_t)(rowb + 4 * trip + t) * D;
; #pragma unroll
;                 for (int j = 0; j < 4; ++j) { const h16x4 v = xv[t][j];
;                     *(GAS f32x4*)(orow + j * 256 + F.lane * 4) = (f32x4){(float)v[0], (float)v[1], (float)v[2], (float)v[3]} * rs * gf[j]; } } }
	v_cvt_f32_f16_e32 v24, v40
	v_cvt_f32_f16_sdwa v25, v40 dst_sel:DWORD dst_unused:UNUSED_PAD src0_sel:WORD_1
	v_cvt_f32_f16_e32 v26, v41
	v_cvt_f32_f16_sdwa v27, v41 dst_sel:DWORD dst_unused:UNUSED_PAD src0_sel:WORD_1
	s_ashr_i32 s11, s10, 31
	v_pk_mul_f32 v[24:25], v[24:25], s[4:5] op_sel_hi:[1,0]
	v_pk_mul_f32 v[26:27], v[26:27], s[4:5] op_sel_hi:[1,0]
	s_nop 0
	v_pk_mul_f32 v[26:27], v[4:5], v[26:27]
	v_pk_mul_f32 v[24:25], v[2:3], v[24:25]
	global_store_dwordx4 v[28:29], v[24:27], off sc1
	s_waitcnt vmcnt(15)
	s_nop 0
	v_cvt_f32_f16_e32 v24, v42
	v_cvt_f32_f16_sdwa v25, v42 dst_sel:DWORD dst_unused:UNUSED_PAD src0_sel:WORD_1
	v_cvt_f32_f16_e32 v26, v43
	v_cvt_f32_f16_sdwa v27, v43 dst_sel:DWORD dst_unused:UNUSED_PAD src0_sel:WORD_1
	v_pk_mul_f32 v[24:25], v[24:25], s[4:5] op_sel_hi:[1,0]
	s_nop 0
	v_pk_mul_f32 v[24:25], v[6:7], v[24:25]
	v_pk_mul_f32 v[26:27], v[26:27], s[4:5] op_sel_hi:[1,0]
	s_nop 0
	v_pk_mul_f32 v[26:27], v[8:9], v[26:27]
	global_store_dwordx4 v[28:29], v[24:27], off offset:1024 sc1
	s_waitcnt vmcnt(15)
	s_nop 0
	v_cvt_f32_f16_e32 v24, v44
	v_cvt_f32_f16_sdwa v25, v44 dst_sel:DWORD dst_unused:UNUSED_PAD src0_sel:WORD_1
	v_cvt_f32_f16_e32 v26, v45
	v_cvt_f32_f16_sdwa v27, v45 dst_sel:DWORD dst_unused:UNUSED_PAD src0_sel:WORD_1
	v_pk_mul_f32 v[24:25], v[24:25], s[4:5] op_sel_hi:[1,0]
	s_nop 0
	v_pk_mul_f32 v[24:25], v[10:11], v[24:25]
	v_pk_mul_f32 v[26:27], v[26:27], s[4:5] op_sel_hi:[1,0]
	s_nop 0
	v_pk_mul_f32 v[26:27], v[12:13], v[26:27]
	global_store_dwordx4 v[28:29], v[24:27], off offset:2048 sc1
	s_waitcnt vmcnt(15)
	s_nop 0
	v_cvt_f32_f16_e32 v24, v46
	v_cvt_f32_f16_sdwa v25, v46 dst_sel:DWORD dst_unused:UNUSED_PAD src0_sel:WORD_1
	v_cvt_f32_f16_e32 v26, v47
	v_cvt_f32_f16_sdwa v27, v47 dst_sel:DWORD dst_unused:UNUSED_PAD src0_sel:WORD_1
	v_pk_mul_f32 v[24:25], v[24:25], s[4:5] op_sel_hi:[1,0]
	s_nop 0
	v_pk_mul_f32 v[24:25], v[14:15], v[24:25]
	v_pk_mul_f32 v[26:27], v[26:27], s[4:5] op_sel_hi:[1,0]
	v_readlane_b32 s4, v32, 0
	v_pk_mul_f32 v[26:27], v[16:17], v[26:27]
	global_store_dwordx4 v[28:29], v[24:27], off offset:3072 sc1
	v_lshl_add_u64 v[28:29], v[22:23], 0, s[8:9]
	s_add_i32 s8, s2, -10
	s_waitcnt vmcnt(15)
	v_cvt_f32_f16_e32 v24, v48
	v_cvt_f32_f16_sdwa v25, v48 dst_sel:DWORD dst_unused:UNUSED_PAD src0_sel:WORD_1
	v_cvt_f32_f16_e32 v26, v49
	v_cvt_f32_f16_sdwa v27, v49 dst_sel:DWORD dst_unused:UNUSED_PAD src0_sel:WORD_1
	s_ashr_i32 s9, s8, 31
	v_pk_mul_f32 v[24:25], v[24:25], s[4:5] op_sel_hi:[1,0]
	v_pk_mul_f32 v[26:27], v[26:27], s[4:5] op_sel_hi:[1,0]
	s_nop 0
	v_pk_mul_f32 v[26:27], v[4:5], v[26:27]
	v_pk_mul_f32 v[24:25], v[2:3], v[24:25]
	global_store_dwordx4 v[28:29], v[24:27], off sc1
	s_waitcnt vmcnt(15)
	s_nop 0
	v_cvt_f32_f16_e32 v24, v50
	v_cvt_f32_f16_sdwa v25, v50 dst_sel:DWORD dst_unused:UNUSED_PAD src0_sel:WORD_1
	v_cvt_f32_f16_e32 v26, v51
	v_cvt_f32_f16_sdwa v27, v51 dst_sel:DWORD dst_unused:UNUSED_PAD src0_sel:WORD_1
	v_pk_mul_f32 v[24:25], v[24:25], s[4:5] op_sel_hi:[1,0]
	s_nop 0
	v_pk_mul_f32 v[24:25], v[6:7], v[24:25]
	v_pk_mul_f32 v[26:27], v[26:27], s[4:5] op_sel_hi:[1,0]
	s_nop 0
	v_pk_mul_f32 v[26:27], v[8:9], v[26:27]
	global_store_dwordx4 v[28:29], v[24:27], off offset:1024 sc1
	s_waitcnt vmcnt(15)
	s_nop 0
	v_cvt_f32_f16_e32 v24, v52
	v_cvt_f32_f16_sdwa v25, v52 dst_sel:DWORD dst_unused:UNUSED_PAD src0_sel:WORD_1
	v_cvt_f32_f16_e32 v26, v53
	v_cvt_f32_f16_sdwa v27, v53 dst_sel:DWORD dst_unused:UNUSED_PAD src0_sel:WORD_1
	v_pk_mul_f32 v[24:25], v[24:25], s[4:5] op_sel_hi:[1,0]
	s_nop 0
	v_pk_mul_f32 v[24:25], v[10:11], v[24:25]
	v_pk_mul_f32 v[26:27], v[26:27], s[4:5] op_sel_hi:[1,0]
	s_nop 0
	v_pk_mul_f32 v[26:27], v[12:13], v[26:27]
	global_store_dwordx4 v[28:29], v[24:27], off offset:2048 sc1
	s_waitcnt vmcnt(15)
	s_nop 0
	v_cvt_f32_f16_e32 v24, v54
	v_cvt_f32_f16_sdwa v25, v54 dst_sel:DWORD dst_unused:UNUSED_PAD src0_sel:WORD_1
	v_cvt_f32_f16_e32 v26, v55
	v_cvt_f32_f16_sdwa v27, v55 dst_sel:DWORD dst_unused:UNUSED_PAD src0_sel:WORD_1
	v_pk_mul_f32 v[24:25], v[24:25], s[4:5] op_sel_hi:[1,0]
	s_nop 0
	v_pk_mul_f32 v[24:25], v[14:15], v[24:25]
	v_pk_mul_f32 v[26:27], v[26:27], s[4:5] op_sel_hi:[1,0]
	v_readlane_b32 s4, v0, 0
	v_pk_mul_f32 v[26:27], v[16:17], v[26:27]
	global_store_dwordx4 v[28:29], v[24:27], off offset:3072 sc1
	v_lshl_add_u64 v[28:29], v[22:23], 0, s[6:7]
	s_add_i32 s6, s2, -9
	s_waitcnt vmcnt(15)
	v_cvt_f32_f16_e32 v24, v56
	v_cvt_f32_f16_sdwa v25, v56 dst_sel:DWORD dst_unused:UNUSED_PAD src0_sel:WORD_1
	v_cvt_f32_f16_e32 v26, v57
	v_cvt_f32_f16_sdwa v27, v57 dst_sel:DWORD dst_unused:UNUSED_PAD src0_sel:WORD_1
	s_ashr_i32 s7, s6, 31
	v_pk_mul_f32 v[24:25], v[24:25], s[4:5] op_sel_hi:[1,0]
	v_pk_mul_f32 v[26:27], v[26:27], s[4:5] op_sel_hi:[1,0]
	s_nop 0
	v_pk_mul_f32 v[26:27], v[4:5], v[26:27]
	v_pk_mul_f32 v[24:25], v[2:3], v[24:25]
	global_store_dwordx4 v[28:29], v[24:27], off sc1
	s_waitcnt vmcnt(15)
	s_nop 0
	v_cvt_f32_f16_e32 v24, v58
	v_cvt_f32_f16_sdwa v25, v58 dst_sel:DWORD dst_unused:UNUSED_PAD src0_sel:WORD_1
	v_cvt_f32_f16_e32 v26, v59
	v_cvt_f32_f16_sdwa v27, v59 dst_sel:DWORD dst_unused:UNUSED_PAD src0_sel:WORD_1
	v_pk_mul_f32 v[24:25], v[24:25], s[4:5] op_sel_hi:[1,0]
	s_nop 0
	v_pk_mul_f32 v[24:25], v[6:7], v[24:25]
	v_pk_mul_f32 v[26:27], v[26:27], s[4:5] op_sel_hi:[1,0]
	s_nop 0
	v_pk_mul_f32 v[26:27], v[8:9], v[26:27]
	global_store_dwordx4 v[28:29], v[24:27], off offset:1024 sc1
	s_waitcnt vmcnt(15)
; #define GAS __attribute__((address_space(1)))
; __device__ __forceinline__ float lx_get(float v, int src) { return __int_as_float(__builtin_amdgcn_readlane(__float_as_int(v), src)); }
; __device__ __forceinline__ void p_final(Frame& F) {
;     ...
;         for (int trip = 0; trip < 4; ++trip) {
;             h16x4 xv[4][4];
; #pragma unroll
;             for (int t = 0; t < 4; ++t)
; #pragma unroll
;                 for (int j = 0; j < 4; ++j) xv[t][j] = *(const GAS h16x4*)(X16 + (size_t)(rowb + 4 * trip + t) * D + j * 256 + F.lane * 4);
; #pragma unroll
;             for (int t = 0; t < 4; ++t) { const float rs = lx_get(qs[t], trip); float* orow = p.out + (size_t)(rowb + 4 * trip + t) * D;
; #pragma unroll
;                 for (int j = 0; j < 4; ++j) { const h16x4 v = xv[t][j];
;                     *(GAS f32x4*)(orow + j * 256 + F.lane * 4) = (f32x4){(float)v[0], (float)v[1], (float)v[2], (float)v[3]} * rs * gf[j]; } } }
	s_nop 0
	v_cvt_f32_f16_e32 v24, v60
	v_cvt_f32_f16_sdwa v25, v60 dst_sel:DWORD dst_unused:UNUSED_PAD src0_sel:WORD_1
	v_cvt_f32_f16_e32 v26, v61
	v_cvt_f32_f16_sdwa v27, v61 dst_sel:DWORD dst_unused:UNUSED_PAD src0_sel:WORD_1
	v_pk_mul_f32 v[24:25], v[24:25], s[4:5] op_sel_hi:[1,0]
	s_nop 0
	v_pk_mul_f32 v[24:25], v[10:11], v[24:25]
	v_pk_mul_f32 v[26:27], v[26:27], s[4:5] op_sel_hi:[1,0]
	s_nop 0
	v_pk_mul_f32 v[26:27], v[12:13], v[26:27]
	global_store_dwordx4 v[28:29], v[24:27], off offset:2048 sc1
	s_waitcnt vmcnt(15)
	s_nop 0
	v_cvt_f32_f16_e32 v24, v62
	v_cvt_f32_f16_sdwa v25, v62 dst_sel:DWORD dst_unused:UNUSED_PAD src0_sel:WORD_1
	v_cvt_f32_f16_e32 v26, v63
	v_cvt_f32_f16_sdwa v27, v63 dst_sel:DWORD dst_unused:UNUSED_PAD src0_sel:WORD_1
	v_pk_mul_f32 v[24:25], v[24:25], s[4:5] op_sel_hi:[1,0]
	s_nop 0
	v_pk_mul_f32 v[24:25], v[14:15], v[24:25]
	v_pk_mul_f32 v[26:27], v[26:27], s[4:5] op_sel_hi:[1,0]
	s_lshl_b64 s[4:5], s[10:11], 11
	v_pk_mul_f32 v[26:27], v[16:17], v[26:27]
	global_store_dwordx4 v[28:29], v[24:27], off offset:3072 sc1
	s_lshl_b64 s[10:11], s[10:11], 12
	v_lshl_add_u64 v[62:63], v[22:23], 0, s[10:11]
	v_lshl_add_u64 v[24:25], v[20:21], 0, s[4:5]
	global_load_dwordx2 v[26:27], v[24:25], off
	global_load_dwordx2 v[28:29], v[24:25], off offset:512
	global_load_dwordx2 v[30:31], v[24:25], off offset:1024
	global_load_dwordx2 v[36:37], v[24:25], off offset:1536
	s_lshl_b64 s[4:5], s[8:9], 11
	v_lshl_add_u64 v[24:25], v[20:21], 0, s[4:5]
	global_load_dwordx2 v[38:39], v[24:25], off
	global_load_dwordx2 v[40:41], v[24:25], off offset:512
	global_load_dwordx2 v[42:43], v[24:25], off offset:1024
	global_load_dwordx2 v[44:45], v[24:25], off offset:1536
	s_lshl_b64 s[4:5], s[6:7], 11
	v_lshl_add_u64 v[24:25], v[20:21], 0, s[4:5]
	global_load_dwordx2 v[46:47], v[24:25], off
	global_load_dwordx2 v[48:49], v[24:25], off offset:512
	global_load_dwordx2 v[50:51], v[24:25], off offset:1024
	global_load_dwordx2 v[52:53], v[24:25], off offset:1536
	s_add_i32 s4, s2, -8
	s_ashr_i32 s5, s4, 31
	s_lshl_b64 s[14:15], s[4:5], 11
	v_lshl_add_u64 v[24:25], v[20:21], 0, s[14:15]
	global_load_dwordx2 v[54:55], v[24:25], off
	global_load_dwordx2 v[56:57], v[24:25], off offset:512
	global_load_dwordx2 v[58:59], v[24:25], off offset:1024
	global_load_dwordx2 v[60:61], v[24:25], off offset:1536
	v_readlane_b32 s14, v34, 1
	v_readlane_b32 s10, v33, 1
	s_lshl_b64 s[8:9], s[8:9], 12
	s_lshl_b64 s[6:7], s[6:7], 12
	s_lshl_b64 s[4:5], s[4:5], 12
	s_waitcnt vmcnt(15)
	v_cvt_f32_f16_e32 v24, v26
	v_cvt_f32_f16_sdwa v25, v26 dst_sel:DWORD dst_unused:UNUSED_PAD src0_sel:WORD_1
	v_cvt_f32_f16_e32 v26, v27
	v_cvt_f32_f16_sdwa v27, v27 dst_sel:DWORD dst_unused:UNUSED_PAD src0_sel:WORD_1
	v_pk_mul_f32 v[24:25], v[24:25], s[14:15] op_sel_hi:[1,0]
	s_nop 0
	v_pk_mul_f32 v[24:25], v[2:3], v[24:25]
	v_pk_mul_f32 v[26:27], v[26:27], s[14:15] op_sel_hi:[1,0]
	s_nop 0
	v_pk_mul_f32 v[26:27], v[4:5], v[26:27]
	global_store_dwordx4 v[62:63], v[24:27], off sc1
	s_waitcnt vmcnt(15)
	s_nop 0
	v_cvt_f32_f16_e32 v24, v28
	v_cvt_f32_f16_sdwa v25, v28 dst_sel:DWORD dst_unused:UNUSED_PAD src0_sel:WORD_1
	v_cvt_f32_f16_e32 v26, v29
	v_cvt_f32_f16_sdwa v27, v29 dst_sel:DWORD dst_unused:UNUSED_PAD src0_sel:WORD_1
	v_lshl_add_u64 v[28:29], v[22:23], 0, s[8:9]
	v_pk_mul_f32 v[24:25], v[24:25], s[14:15] op_sel_hi:[1,0]
	v_readlane_b32 s8, v32, 1
	v_pk_mul_f32 v[26:27], v[26:27], s[14:15] op_sel_hi:[1,0]
	v_pk_mul_f32 v[24:25], v[6:7], v[24:25]
	v_pk_mul_f32 v[26:27], v[8:9], v[26:27]
	global_store_dwordx4 v[62:63], v[24:27], off offset:1024 sc1
	s_waitcnt vmcnt(15)
	s_nop 0
	v_cvt_f32_f16_e32 v24, v30
	v_cvt_f32_f16_sdwa v25, v30 dst_sel:DWORD dst_unused:UNUSED_PAD src0_sel:WORD_1
	v_cvt_f32_f16_e32 v26, v31
	v_cvt_f32_f16_sdwa v27, v31 dst_sel:DWORD dst_unused:UNUSED_PAD src0_sel:WORD_1
	v_pk_mul_f32 v[24:25], v[24:25], s[14:15] op_sel_hi:[1,0]
	s_nop 0
	v_pk_mul_f32 v[24:25], v[10:11], v[24:25]
	v_pk_mul_f32 v[26:27], v[26:27], s[14:15] op_sel_hi:[1,0]
	s_nop 0
	v_pk_mul_f32 v[26:27], v[12:13], v[26:27]
	global_store_dwordx4 v[62:63], v[24:27], off offset:2048 sc1
	s_waitcnt vmcnt(15)
	s_nop 0
	v_cvt_f32_f16_e32 v24, v36
	v_cvt_f32_f16_sdwa v25, v36 dst_sel:DWORD dst_unused:UNUSED_PAD src0_sel:WORD_1
	v_cvt_f32_f16_e32 v26, v37
	v_cvt_f32_f16_sdwa v27, v37 dst_sel:DWORD dst_unused:UNUSED_PAD src0_sel:WORD_1
	v_pk_mul_f32 v[24:25], v[24:25], s[14:15] op_sel_hi:[1,0]
	s_nop 0
	v_pk_mul_f32 v[24:25], v[14:15], v[24:25]
	v_pk_mul_f32 v[26:27], v[26:27], s[14:15] op_sel_hi:[1,0]
	s_nop 0
	v_pk_mul_f32 v[26:27], v[16:17], v[26:27]
	global_store_dwordx4 v[62:63], v[24:27], off offset:3072 sc1
	s_waitcnt vmcnt(15)
	s_nop 0
	v_cvt_f32_f16_e32 v24, v38
	v_cvt_f32_f16_sdwa v25, v38 dst_sel:DWORD dst_unused:UNUSED_PAD src0_sel:WORD_1
	v_cvt_f32_f16_e32 v26, v39
	v_cvt_f32_f16_sdwa v27, v39 dst_sel:DWORD dst_unused:UNUSED_PAD src0_sel:WORD_1
	v_pk_mul_f32 v[24:25], v[24:25], s[10:11] op_sel_hi:[1,0]
	s_nop 0
	v_pk_mul_f32 v[24:25], v[2:3], v[24:25]
	v_pk_mul_f32 v[26:27], v[26:27], s[10:11] op_sel_hi:[1,0]
	s_nop 0
	v_pk_mul_f32 v[26:27], v[4:5], v[26:27]
	global_store_dwordx4 v[28:29], v[24:27], off sc1
	s_waitcnt vmcnt(15)
	s_nop 0
	v_cvt_f32_f16_e32 v24, v40
	v_cvt_f32_f16_sdwa v25, v40 dst_sel:DWORD dst_unused:UNUSED_PAD src0_sel:WORD_1
	v_cvt_f32_f16_e32 v26, v41
	v_cvt_f32_f16_sdwa v27, v41 dst_sel:DWORD dst_unused:UNUSED_PAD src0_sel:WORD_1
	v_pk_mul_f32 v[24:25], v[24:25], s[10:11] op_sel_hi:[1,0]
	s_nop 0
	v_pk_mul_f32 v[24:25], v[6:7], v[24:25]
	v_pk_mul_f32 v[26:27], v[26:27], s[10:11] op_sel_hi:[1,0]
	s_nop 0
	v_pk_mul_f32 v[26:27], v[8:9], v[26:27]
	global_store_dwordx4 v[28:29], v[24:27], off offset:1024 sc1
	s_waitcnt vmcnt(15)
; #define GAS __attribute__((address_space(1)))
; __device__ __forceinline__ float lx_get(float v, int src) { return __int_as_float(__builtin_amdgcn_readlane(__float_as_int(v), src)); }
; __device__ __forceinline__ void p_final(Frame& F) {
;     ...
;         for (int trip = 0; trip < 4; ++trip) {
;             h16x4 xv[4][4];
; #pragma unroll
;             for (int t = 0; t < 4; ++t)
; #pragma unroll
;                 for (int j = 0; j < 4; ++j) xv[t][j] = *(const GAS h16x4*)(X16 + (size_t)(rowb + 4 * trip + t) * D + j * 256 + F.lane * 4);
; #pragma unroll
;             for (int t = 0; t < 4; ++t) { const float rs = lx_get(qs[t], trip); float* orow = p.out + (size_t)(rowb + 4 * trip + t) * D;
; #pragma unroll
;                 for (int j = 0; j < 4; ++j) { const h16x4 v = xv[t][j];
;                     *(GAS f32x4*)(orow + j * 256 + F.lane * 4) = (f32x4){(float)v[0], (float)v[1], (float)v[2], (float)v[3]} * rs * gf[j]; } } }
	s_nop 0
	v_cvt_f32_f16_e32 v24, v42
	v_cvt_f32_f16_sdwa v25, v42 dst_sel:DWORD dst_unused:UNUSED_PAD src0_sel:WORD_1
	v_cvt_f32_f16_e32 v26, v43
	v_cvt_f32_f16_sdwa v27, v43 dst_sel:DWORD dst_unused:UNUSED_PAD src0_sel:WORD_1
	v_pk_mul_f32 v[24:25], v[24:25], s[10:11] op_sel_hi:[1,0]
	s_nop 0
	v_pk_mul_f32 v[24:25], v[10:11], v[24:25]
	v_pk_mul_f32 v[26:27], v[26:27], s[10:11] op_sel_hi:[1,0]
	s_nop 0
	v_pk_mul_f32 v[26:27], v[12:13], v[26:27]
	global_store_dwordx4 v[28:29], v[24:27], off offset:2048 sc1
	s_waitcnt vmcnt(15)
	s_nop 0
	v_cvt_f32_f16_e32 v24, v44
	v_cvt_f32_f16_sdwa v25, v44 dst_sel:DWORD dst_unused:UNUSED_PAD src0_sel:WORD_1
	v_cvt_f32_f16_e32 v26, v45
	v_cvt_f32_f16_sdwa v27, v45 dst_sel:DWORD dst_unused:UNUSED_PAD src0_sel:WORD_1
	v_pk_mul_f32 v[24:25], v[24:25], s[10:11] op_sel_hi:[1,0]
	s_nop 0
	v_pk_mul_f32 v[24:25], v[14:15], v[24:25]
	v_pk_mul_f32 v[26:27], v[26:27], s[10:11] op_sel_hi:[1,0]
	s_add_i32 s10, s2, -7
	v_pk_mul_f32 v[26:27], v[16:17], v[26:27]
	global_store_dwordx4 v[28:29], v[24:27], off offset:3072 sc1
	v_lshl_add_u64 v[28:29], v[22:23], 0, s[6:7]
	v_readlane_b32 s6, v0, 1
	s_waitcnt vmcnt(15)
	v_cvt_f32_f16_e32 v24, v46
	v_cvt_f32_f16_sdwa v25, v46 dst_sel:DWORD dst_unused:UNUSED_PAD src0_sel:WORD_1
	v_cvt_f32_f16_e32 v26, v47
	v_cvt_f32_f16_sdwa v27, v47 dst_sel:DWORD dst_unused:UNUSED_PAD src0_sel:WORD_1
	s_ashr_i32 s11, s10, 31
	v_pk_mul_f32 v[24:25], v[24:25], s[8:9] op_sel_hi:[1,0]
	v_pk_mul_f32 v[26:27], v[26:27], s[8:9] op_sel_hi:[1,0]
	s_nop 0
	v_pk_mul_f32 v[26:27], v[4:5], v[26:27]
	v_pk_mul_f32 v[24:25], v[2:3], v[24:25]
	global_store_dwordx4 v[28:29], v[24:27], off sc1
	s_waitcnt vmcnt(15)
	s_nop 0
	v_cvt_f32_f16_e32 v24, v48
	v_cvt_f32_f16_sdwa v25, v48 dst_sel:DWORD dst_unused:UNUSED_PAD src0_sel:WORD_1
	v_cvt_f32_f16_e32 v26, v49
	v_cvt_f32_f16_sdwa v27, v49 dst_sel:DWORD dst_unused:UNUSED_PAD src0_sel:WORD_1
	v_pk_mul_f32 v[24:25], v[24:25], s[8:9] op_sel_hi:[1,0]
	s_nop 0
	v_pk_mul_f32 v[24:25], v[6:7], v[24:25]
	v_pk_mul_f32 v[26:27], v[26:27], s[8:9] op_sel_hi:[1,0]
	s_nop 0
	v_pk_mul_f32 v[26:27], v[8:9], v[26:27]
	global_store_dwordx4 v[28:29], v[24:27], off offset:1024 sc1
	s_waitcnt vmcnt(15)
	s_nop 0
	v_cvt_f32_f16_e32 v24, v50
	v_cvt_f32_f16_sdwa v25, v50 dst_sel:DWORD dst_unused:UNUSED_PAD src0_sel:WORD_1
	v_cvt_f32_f16_e32 v26, v51
	v_cvt_f32_f16_sdwa v27, v51 dst_sel:DWORD dst_unused:UNUSED_PAD src0_sel:WORD_1
	v_pk_mul_f32 v[24:25], v[24:25], s[8:9] op_sel_hi:[1,0]
	s_nop 0
	v_pk_mul_f32 v[24:25], v[10:11], v[24:25]
	v_pk_mul_f32 v[26:27], v[26:27], s[8:9] op_sel_hi:[1,0]
	s_nop 0
	v_pk_mul_f32 v[26:27], v[12:13], v[26:27]
	global_store_dwordx4 v[28:29], v[24:27], off offset:2048 sc1
	s_waitcnt vmcnt(15)
	s_nop 0
	v_cvt_f32_f16_e32 v24, v52
	v_cvt_f32_f16_sdwa v25, v52 dst_sel:DWORD dst_unused:UNUSED_PAD src0_sel:WORD_1
	v_cvt_f32_f16_e32 v26, v53
	v_cvt_f32_f16_sdwa v27, v53 dst_sel:DWORD dst_unused:UNUSED_PAD src0_sel:WORD_1
	v_pk_mul_f32 v[24:25], v[24:25], s[8:9] op_sel_hi:[1,0]
	s_nop 0
	v_pk_mul_f32 v[24:25], v[14:15], v[24:25]
	v_pk_mul_f32 v[26:27], v[26:27], s[8:9] op_sel_hi:[1,0]
	s_add_i32 s8, s2, -6
	v_pk_mul_f32 v[26:27], v[16:17], v[26:27]
	global_store_dwordx4 v[28:29], v[24:27], off offset:3072 sc1
	v_lshl_add_u64 v[28:29], v[22:23], 0, s[4:5]
	s_lshl_b64 s[4:5], s[10:11], 11
	s_waitcnt vmcnt(15)
	v_cvt_f32_f16_e32 v24, v54
	v_cvt_f32_f16_sdwa v25, v54 dst_sel:DWORD dst_unused:UNUSED_PAD src0_sel:WORD_1
	v_cvt_f32_f16_e32 v26, v55
	v_cvt_f32_f16_sdwa v27, v55 dst_sel:DWORD dst_unused:UNUSED_PAD src0_sel:WORD_1
	s_ashr_i32 s9, s8, 31
	v_pk_mul_f32 v[24:25], v[24:25], s[6:7] op_sel_hi:[1,0]
	s_lshl_b64 s[10:11], s[10:11], 12
	v_pk_mul_f32 v[26:27], v[26:27], s[6:7] op_sel_hi:[1,0]
	v_pk_mul_f32 v[24:25], v[2:3], v[24:25]
	v_pk_mul_f32 v[26:27], v[4:5], v[26:27]
	global_store_dwordx4 v[28:29], v[24:27], off sc1
	v_lshl_add_u64 v[62:63], v[22:23], 0, s[10:11]
	v_readlane_b32 s10, v33, 2
	s_waitcnt vmcnt(15)
	v_cvt_f32_f16_e32 v24, v56
	v_cvt_f32_f16_sdwa v25, v56 dst_sel:DWORD dst_unused:UNUSED_PAD src0_sel:WORD_1
	v_cvt_f32_f16_e32 v26, v57
	v_cvt_f32_f16_sdwa v27, v57 dst_sel:DWORD dst_unused:UNUSED_PAD src0_sel:WORD_1
	v_pk_mul_f32 v[24:25], v[24:25], s[6:7] op_sel_hi:[1,0]
	s_nop 0
	v_pk_mul_f32 v[24:25], v[6:7], v[24:25]
	v_pk_mul_f32 v[26:27], v[26:27], s[6:7] op_sel_hi:[1,0]
	s_nop 0
	v_pk_mul_f32 v[26:27], v[8:9], v[26:27]
	global_store_dwordx4 v[28:29], v[24:27], off offset:1024 sc1
	s_waitcnt vmcnt(15)
	s_nop 0
	v_cvt_f32_f16_e32 v24, v58
	v_cvt_f32_f16_sdwa v25, v58 dst_sel:DWORD dst_unused:UNUSED_PAD src0_sel:WORD_1
	v_cvt_f32_f16_e32 v26, v59
	v_cvt_f32_f16_sdwa v27, v59 dst_sel:DWORD dst_unused:UNUSED_PAD src0_sel:WORD_1
	v_pk_mul_f32 v[24:25], v[24:25], s[6:7] op_sel_hi:[1,0]
	s_nop 0
	v_pk_mul_f32 v[24:25], v[10:11], v[24:25]
	v_pk_mul_f32 v[26:27], v[26:27], s[6:7] op_sel_hi:[1,0]
	s_nop 0
	v_pk_mul_f32 v[26:27], v[12:13], v[26:27]
	global_store_dwordx4 v[28:29], v[24:27], off offset:2048 sc1
	s_waitcnt vmcnt(15)
; #define GAS __attribute__((address_space(1)))
; __device__ __forceinline__ float lx_get(float v, int src) { return __int_as_float(__builtin_amdgcn_readlane(__float_as_int(v), src)); }
; __device__ __forceinline__ void p_final(Frame& F) {
;     ...
;         for (int trip = 0; trip < 4; ++trip) {
;             h16x4 xv[4][4];
; #pragma unroll
;             for (int t = 0; t < 4; ++t)
; #pragma unroll
;                 for (int j = 0; j < 4; ++j) xv[t][j] = *(const GAS h16x4*)(X16 + (size_t)(rowb + 4 * trip + t) * D + j * 256 + F.lane * 4);
; #pragma unroll
;             for (int t = 0; t < 4; ++t) { const float rs = lx_get(qs[t], trip); float* orow = p.out + (size_t)(rowb + 4 * trip + t) * D;
; #pragma unroll
;                 for (int j = 0; j < 4; ++j) { const h16x4 v = xv[t][j];
;                     *(GAS f32x4*)(orow + j * 256 + F.lane * 4) = (f32x4){(float)v[0], (float)v[1], (float)v[2], (float)v[3]} * rs * gf[j]; } } }
	s_nop 0
	v_cvt_f32_f16_e32 v24, v60
	v_cvt_f32_f16_sdwa v25, v60 dst_sel:DWORD dst_unused:UNUSED_PAD src0_sel:WORD_1
	v_cvt_f32_f16_e32 v26, v61
	v_cvt_f32_f16_sdwa v27, v61 dst_sel:DWORD dst_unused:UNUSED_PAD src0_sel:WORD_1
	v_pk_mul_f32 v[24:25], v[24:25], s[6:7] op_sel_hi:[1,0]
	s_nop 0
	v_pk_mul_f32 v[24:25], v[14:15], v[24:25]
	v_pk_mul_f32 v[26:27], v[26:27], s[6:7] op_sel_hi:[1,0]
	s_add_i32 s6, s2, -5
	v_pk_mul_f32 v[26:27], v[16:17], v[26:27]
	global_store_dwordx4 v[28:29], v[24:27], off offset:3072 sc1
	s_ashr_i32 s7, s6, 31
	s_nop 0
	v_lshl_add_u64 v[24:25], v[20:21], 0, s[4:5]
	global_load_dwordx2 v[26:27], v[24:25], off
	global_load_dwordx2 v[28:29], v[24:25], off offset:512
	global_load_dwordx2 v[30:31], v[24:25], off offset:1024
	global_load_dwordx2 v[36:37], v[24:25], off offset:1536
	s_lshl_b64 s[4:5], s[8:9], 11
	v_lshl_add_u64 v[24:25], v[20:21], 0, s[4:5]
	global_load_dwordx2 v[38:39], v[24:25], off
	global_load_dwordx2 v[40:41], v[24:25], off offset:512
	global_load_dwordx2 v[42:43], v[24:25], off offset:1024
	global_load_dwordx2 v[44:45], v[24:25], off offset:1536
	s_lshl_b64 s[4:5], s[6:7], 11
	v_lshl_add_u64 v[24:25], v[20:21], 0, s[4:5]
	global_load_dwordx2 v[46:47], v[24:25], off
	global_load_dwordx2 v[48:49], v[24:25], off offset:512
	global_load_dwordx2 v[50:51], v[24:25], off offset:1024
	global_load_dwordx2 v[52:53], v[24:25], off offset:1536
	s_add_i32 s4, s2, -4
	s_ashr_i32 s5, s4, 31
	s_lshl_b64 s[14:15], s[4:5], 11
	v_lshl_add_u64 v[24:25], v[20:21], 0, s[14:15]
	global_load_dwordx2 v[54:55], v[24:25], off
	global_load_dwordx2 v[56:57], v[24:25], off offset:512
	global_load_dwordx2 v[58:59], v[24:25], off offset:1024
	global_load_dwordx2 v[60:61], v[24:25], off offset:1536
	v_readlane_b32 s14, v34, 2
	s_lshl_b64 s[8:9], s[8:9], 12
	s_lshl_b64 s[6:7], s[6:7], 12
	s_lshl_b64 s[4:5], s[4:5], 12
	s_waitcnt vmcnt(15)
	v_cvt_f32_f16_e32 v24, v26
	v_cvt_f32_f16_sdwa v25, v26 dst_sel:DWORD dst_unused:UNUSED_PAD src0_sel:WORD_1
	v_cvt_f32_f16_e32 v26, v27
	v_cvt_f32_f16_sdwa v27, v27 dst_sel:DWORD dst_unused:UNUSED_PAD src0_sel:WORD_1
	v_pk_mul_f32 v[24:25], v[24:25], s[14:15] op_sel_hi:[1,0]
	s_nop 0
	v_pk_mul_f32 v[24:25], v[2:3], v[24:25]
	v_pk_mul_f32 v[26:27], v[26:27], s[14:15] op_sel_hi:[1,0]
	s_nop 0
	v_pk_mul_f32 v[26:27], v[4:5], v[26:27]
	global_store_dwordx4 v[62:63], v[24:27], off sc1
	s_waitcnt vmcnt(15)
	s_nop 0
	v_cvt_f32_f16_e32 v24, v28
	v_cvt_f32_f16_sdwa v25, v28 dst_sel:DWORD dst_unused:UNUSED_PAD src0_sel:WORD_1
	v_cvt_f32_f16_e32 v26, v29
	v_cvt_f32_f16_sdwa v27, v29 dst_sel:DWORD dst_unused:UNUSED_PAD src0_sel:WORD_1
	v_lshl_add_u64 v[28:29], v[22:23], 0, s[8:9]
	v_pk_mul_f32 v[24:25], v[24:25], s[14:15] op_sel_hi:[1,0]
	v_readlane_b32 s8, v32, 2
	v_pk_mul_f32 v[26:27], v[26:27], s[14:15] op_sel_hi:[1,0]
	v_pk_mul_f32 v[24:25], v[6:7], v[24:25]
	v_pk_mul_f32 v[26:27], v[8:9], v[26:27]
	global_store_dwordx4 v[62:63], v[24:27], off offset:1024 sc1
	s_waitcnt vmcnt(15)
	s_nop 0
	v_cvt_f32_f16_e32 v24, v30
	v_cvt_f32_f16_sdwa v25, v30 dst_sel:DWORD dst_unused:UNUSED_PAD src0_sel:WORD_1
	v_cvt_f32_f16_e32 v26, v31
	v_cvt_f32_f16_sdwa v27, v31 dst_sel:DWORD dst_unused:UNUSED_PAD src0_sel:WORD_1
	v_pk_mul_f32 v[24:25], v[24:25], s[14:15] op_sel_hi:[1,0]
	s_nop 0
	v_pk_mul_f32 v[24:25], v[10:11], v[24:25]
	v_pk_mul_f32 v[26:27], v[26:27], s[14:15] op_sel_hi:[1,0]
	s_nop 0
	v_pk_mul_f32 v[26:27], v[12:13], v[26:27]
	global_store_dwordx4 v[62:63], v[24:27], off offset:2048 sc1
	s_waitcnt vmcnt(15)
	s_nop 0
	v_cvt_f32_f16_e32 v24, v36
	v_cvt_f32_f16_sdwa v25, v36 dst_sel:DWORD dst_unused:UNUSED_PAD src0_sel:WORD_1
	v_cvt_f32_f16_e32 v26, v37
	v_cvt_f32_f16_sdwa v27, v37 dst_sel:DWORD dst_unused:UNUSED_PAD src0_sel:WORD_1
	v_pk_mul_f32 v[24:25], v[24:25], s[14:15] op_sel_hi:[1,0]
	s_nop 0
	v_pk_mul_f32 v[24:25], v[14:15], v[24:25]
	v_pk_mul_f32 v[26:27], v[26:27], s[14:15] op_sel_hi:[1,0]
	s_nop 0
	v_pk_mul_f32 v[26:27], v[16:17], v[26:27]
	global_store_dwordx4 v[62:63], v[24:27], off offset:3072 sc1
	s_waitcnt vmcnt(15)
	s_nop 0
	v_cvt_f32_f16_e32 v24, v38
	v_cvt_f32_f16_sdwa v25, v38 dst_sel:DWORD dst_unused:UNUSED_PAD src0_sel:WORD_1
	v_cvt_f32_f16_e32 v26, v39
	v_cvt_f32_f16_sdwa v27, v39 dst_sel:DWORD dst_unused:UNUSED_PAD src0_sel:WORD_1
	v_pk_mul_f32 v[24:25], v[24:25], s[10:11] op_sel_hi:[1,0]
	s_nop 0
	v_pk_mul_f32 v[24:25], v[2:3], v[24:25]
	v_pk_mul_f32 v[26:27], v[26:27], s[10:11] op_sel_hi:[1,0]
	s_nop 0
	v_pk_mul_f32 v[26:27], v[4:5], v[26:27]
	global_store_dwordx4 v[28:29], v[24:27], off sc1
	s_waitcnt vmcnt(15)
	s_nop 0
	v_cvt_f32_f16_e32 v24, v40
	v_cvt_f32_f16_sdwa v25, v40 dst_sel:DWORD dst_unused:UNUSED_PAD src0_sel:WORD_1
	v_cvt_f32_f16_e32 v26, v41
	v_cvt_f32_f16_sdwa v27, v41 dst_sel:DWORD dst_unused:UNUSED_PAD src0_sel:WORD_1
	v_pk_mul_f32 v[24:25], v[24:25], s[10:11] op_sel_hi:[1,0]
	s_nop 0
	v_pk_mul_f32 v[24:25], v[6:7], v[24:25]
	v_pk_mul_f32 v[26:27], v[26:27], s[10:11] op_sel_hi:[1,0]
	s_nop 0
	v_pk_mul_f32 v[26:27], v[8:9], v[26:27]
	global_store_dwordx4 v[28:29], v[24:27], off offset:1024 sc1
	s_waitcnt vmcnt(15)
	s_nop 0
	v_cvt_f32_f16_e32 v24, v42
	v_cvt_f32_f16_sdwa v25, v42 dst_sel:DWORD dst_unused:UNUSED_PAD src0_sel:WORD_1
	v_cvt_f32_f16_e32 v26, v43
	v_cvt_f32_f16_sdwa v27, v43 dst_sel:DWORD dst_unused:UNUSED_PAD src0_sel:WORD_1
	v_pk_mul_f32 v[24:25], v[24:25], s[10:11] op_sel_hi:[1,0]
	s_nop 0
	v_pk_mul_f32 v[24:25], v[10:11], v[24:25]
	v_pk_mul_f32 v[26:27], v[26:27], s[10:11] op_sel_hi:[1,0]
	s_nop 0
	v_pk_mul_f32 v[26:27], v[12:13], v[26:27]
	global_store_dwordx4 v[28:29], v[24:27], off offset:2048 sc1
	s_waitcnt vmcnt(15)
; #define GAS __attribute__((address_space(1)))
; __device__ __forceinline__ float lx_get(float v, int src) { return __int_as_float(__builtin_amdgcn_readlane(__float_as_int(v), src)); }
; __device__ __forceinline__ void p_final(Frame& F) {
;     ...
;         for (int trip = 0; trip < 4; ++trip) {
;             h16x4 xv[4][4];
; #pragma unroll
;             for (int t = 0; t < 4; ++t)
; #pragma unroll
;                 for (int j = 0; j < 4; ++j) xv[t][j] = *(const GAS h16x4*)(X16 + (size_t)(rowb + 4 * trip + t) * D + j * 256 + F.lane * 4);
; #pragma unroll
;             for (int t = 0; t < 4; ++t) { const float rs = lx_get(qs[t], trip); float* orow = p.out + (size_t)(rowb + 4 * trip + t) * D;
; #pragma unroll
;                 for (int j = 0; j < 4; ++j) { const h16x4 v = xv[t][j];
;                     *(GAS f32x4*)(orow + j * 256 + F.lane * 4) = (f32x4){(float)v[0], (float)v[1], (float)v[2], (float)v[3]} * rs * gf[j]; } } }
	s_nop 0
	v_cvt_f32_f16_e32 v24, v44
	v_cvt_f32_f16_sdwa v25, v44 dst_sel:DWORD dst_unused:UNUSED_PAD src0_sel:WORD_1
	v_cvt_f32_f16_e32 v26, v45
	v_cvt_f32_f16_sdwa v27, v45 dst_sel:DWORD dst_unused:UNUSED_PAD src0_sel:WORD_1
	v_pk_mul_f32 v[24:25], v[24:25], s[10:11] op_sel_hi:[1,0]
	s_nop 0
	v_pk_mul_f32 v[24:25], v[14:15], v[24:25]
	v_pk_mul_f32 v[26:27], v[26:27], s[10:11] op_sel_hi:[1,0]
	s_nop 0
	v_pk_mul_f32 v[26:27], v[16:17], v[26:27]
	global_store_dwordx4 v[28:29], v[24:27], off offset:3072 sc1
	v_lshl_add_u64 v[28:29], v[22:23], 0, s[6:7]
	v_readlane_b32 s6, v0, 2
	s_waitcnt vmcnt(15)
	v_cvt_f32_f16_e32 v24, v46
	v_cvt_f32_f16_sdwa v25, v46 dst_sel:DWORD dst_unused:UNUSED_PAD src0_sel:WORD_1
	v_cvt_f32_f16_e32 v26, v47
	v_cvt_f32_f16_sdwa v27, v47 dst_sel:DWORD dst_unused:UNUSED_PAD src0_sel:WORD_1
	v_pk_mul_f32 v[24:25], v[24:25], s[8:9] op_sel_hi:[1,0]
	s_nop 0
	v_pk_mul_f32 v[24:25], v[2:3], v[24:25]
	v_pk_mul_f32 v[26:27], v[26:27], s[8:9] op_sel_hi:[1,0]
	s_nop 0
	v_pk_mul_f32 v[26:27], v[4:5], v[26:27]
	global_store_dwordx4 v[28:29], v[24:27], off sc1
	s_waitcnt vmcnt(15)
	s_nop 0
	v_cvt_f32_f16_e32 v24, v48
	v_cvt_f32_f16_sdwa v25, v48 dst_sel:DWORD dst_unused:UNUSED_PAD src0_sel:WORD_1
	v_cvt_f32_f16_e32 v26, v49
	v_cvt_f32_f16_sdwa v27, v49 dst_sel:DWORD dst_unused:UNUSED_PAD src0_sel:WORD_1
	v_pk_mul_f32 v[24:25], v[24:25], s[8:9] op_sel_hi:[1,0]
	s_nop 0
	v_pk_mul_f32 v[24:25], v[6:7], v[24:25]
	v_pk_mul_f32 v[26:27], v[26:27], s[8:9] op_sel_hi:[1,0]
	s_nop 0
	v_pk_mul_f32 v[26:27], v[8:9], v[26:27]
	global_store_dwordx4 v[28:29], v[24:27], off offset:1024 sc1
	s_waitcnt vmcnt(15)
	s_nop 0
	v_cvt_f32_f16_e32 v24, v50
	v_cvt_f32_f16_sdwa v25, v50 dst_sel:DWORD dst_unused:UNUSED_PAD src0_sel:WORD_1
	v_cvt_f32_f16_e32 v26, v51
	v_cvt_f32_f16_sdwa v27, v51 dst_sel:DWORD dst_unused:UNUSED_PAD src0_sel:WORD_1
	v_pk_mul_f32 v[24:25], v[24:25], s[8:9] op_sel_hi:[1,0]
	s_nop 0
	v_pk_mul_f32 v[24:25], v[10:11], v[24:25]
	v_pk_mul_f32 v[26:27], v[26:27], s[8:9] op_sel_hi:[1,0]
	s_nop 0
	v_pk_mul_f32 v[26:27], v[12:13], v[26:27]
	global_store_dwordx4 v[28:29], v[24:27], off offset:2048 sc1
	s_waitcnt vmcnt(15)
	s_nop 0
	v_cvt_f32_f16_e32 v24, v52
	v_cvt_f32_f16_sdwa v25, v52 dst_sel:DWORD dst_unused:UNUSED_PAD src0_sel:WORD_1
	v_cvt_f32_f16_e32 v26, v53
	v_cvt_f32_f16_sdwa v27, v53 dst_sel:DWORD dst_unused:UNUSED_PAD src0_sel:WORD_1
	v_pk_mul_f32 v[24:25], v[24:25], s[8:9] op_sel_hi:[1,0]
	s_nop 0
	v_pk_mul_f32 v[24:25], v[14:15], v[24:25]
	v_pk_mul_f32 v[26:27], v[26:27], s[8:9] op_sel_hi:[1,0]
	s_add_i32 s8, s2, -3
	v_pk_mul_f32 v[26:27], v[16:17], v[26:27]
	global_store_dwordx4 v[28:29], v[24:27], off offset:3072 sc1
	v_lshl_add_u64 v[28:29], v[22:23], 0, s[4:5]
	s_ashr_i32 s9, s8, 31
	s_waitcnt vmcnt(15)
	v_cvt_f32_f16_e32 v24, v54
	v_cvt_f32_f16_sdwa v25, v54 dst_sel:DWORD dst_unused:UNUSED_PAD src0_sel:WORD_1
	v_cvt_f32_f16_e32 v26, v55
	v_cvt_f32_f16_sdwa v27, v55 dst_sel:DWORD dst_unused:UNUSED_PAD src0_sel:WORD_1
	s_lshl_b64 s[4:5], s[8:9], 11
	v_pk_mul_f32 v[24:25], v[24:25], s[6:7] op_sel_hi:[1,0]
	s_lshl_b64 s[8:9], s[8:9], 12
	v_pk_mul_f32 v[26:27], v[26:27], s[6:7] op_sel_hi:[1,0]
	v_pk_mul_f32 v[24:25], v[2:3], v[24:25]
	v_pk_mul_f32 v[26:27], v[4:5], v[26:27]
	global_store_dwordx4 v[28:29], v[24:27], off sc1
	s_waitcnt vmcnt(15)
	s_nop 0
	v_cvt_f32_f16_e32 v24, v56
	v_cvt_f32_f16_sdwa v25, v56 dst_sel:DWORD dst_unused:UNUSED_PAD src0_sel:WORD_1
	v_cvt_f32_f16_e32 v26, v57
	v_cvt_f32_f16_sdwa v27, v57 dst_sel:DWORD dst_unused:UNUSED_PAD src0_sel:WORD_1
	v_pk_mul_f32 v[24:25], v[24:25], s[6:7] op_sel_hi:[1,0]
	s_nop 0
	v_pk_mul_f32 v[24:25], v[6:7], v[24:25]
	v_pk_mul_f32 v[26:27], v[26:27], s[6:7] op_sel_hi:[1,0]
	s_nop 0
	v_pk_mul_f32 v[26:27], v[8:9], v[26:27]
	global_store_dwordx4 v[28:29], v[24:27], off offset:1024 sc1
	s_waitcnt vmcnt(15)
	s_nop 0
	v_cvt_f32_f16_e32 v24, v58
	v_cvt_f32_f16_sdwa v25, v58 dst_sel:DWORD dst_unused:UNUSED_PAD src0_sel:WORD_1
	v_cvt_f32_f16_e32 v26, v59
	v_cvt_f32_f16_sdwa v27, v59 dst_sel:DWORD dst_unused:UNUSED_PAD src0_sel:WORD_1
	v_pk_mul_f32 v[24:25], v[24:25], s[6:7] op_sel_hi:[1,0]
	s_nop 0
	v_pk_mul_f32 v[24:25], v[10:11], v[24:25]
	v_pk_mul_f32 v[26:27], v[26:27], s[6:7] op_sel_hi:[1,0]
	s_nop 0
	v_pk_mul_f32 v[26:27], v[12:13], v[26:27]
	global_store_dwordx4 v[28:29], v[24:27], off offset:2048 sc1
	s_waitcnt vmcnt(15)
	s_nop 0
	v_cvt_f32_f16_e32 v24, v60
	v_cvt_f32_f16_sdwa v25, v60 dst_sel:DWORD dst_unused:UNUSED_PAD src0_sel:WORD_1
	v_cvt_f32_f16_e32 v26, v61
	v_cvt_f32_f16_sdwa v27, v61 dst_sel:DWORD dst_unused:UNUSED_PAD src0_sel:WORD_1
	v_pk_mul_f32 v[24:25], v[24:25], s[6:7] op_sel_hi:[1,0]
	s_nop 0
	v_pk_mul_f32 v[24:25], v[14:15], v[24:25]
	v_pk_mul_f32 v[26:27], v[26:27], s[6:7] op_sel_hi:[1,0]
	s_add_i32 s6, s2, -2
	v_pk_mul_f32 v[26:27], v[16:17], v[26:27]
	global_store_dwordx4 v[28:29], v[24:27], off offset:3072 sc1
	s_ashr_i32 s7, s6, 31
	s_nop 0
	v_lshl_add_u64 v[24:25], v[20:21], 0, s[4:5]
	global_load_dwordx2 v[26:27], v[24:25], off
	global_load_dwordx2 v[28:29], v[24:25], off offset:512
	global_load_dwordx2 v[30:31], v[24:25], off offset:1024
	global_load_dwordx2 v[36:37], v[24:25], off offset:1536
	s_lshl_b64 s[4:5], s[6:7], 11
	v_lshl_add_u64 v[24:25], v[20:21], 0, s[4:5]
	global_load_dwordx2 v[38:39], v[24:25], off
	global_load_dwordx2 v[40:41], v[24:25], off offset:512
	global_load_dwordx2 v[42:43], v[24:25], off offset:1024
	global_load_dwordx2 v[44:45], v[24:25], off offset:1536
	s_add_i32 s4, s2, -1
	s_ashr_i32 s5, s4, 31
	s_lshl_b64 s[10:11], s[4:5], 11
	v_lshl_add_u64 v[24:25], v[20:21], 0, s[10:11]
	global_load_dwordx2 v[46:47], v[24:25], off
	global_load_dwordx2 v[48:49], v[24:25], off offset:512
	global_load_dwordx2 v[50:51], v[24:25], off offset:1024
	global_load_dwordx2 v[52:53], v[24:25], off offset:1536
	s_lshl_b64 s[10:11], s[2:3], 11
	v_lshl_add_u64 v[24:25], v[20:21], 0, s[10:11]
	global_load_dwordx2 v[54:55], v[24:25], off
	global_load_dwordx2 v[56:57], v[24:25], off offset:512
	global_load_dwordx2 v[58:59], v[24:25], off offset:1024
	global_load_dwordx2 v[60:61], v[24:25], off offset:1536
	v_readlane_b32 s10, v34, 3
	v_lshl_add_u64 v[34:35], v[22:23], 0, s[8:9]
	v_readlane_b32 s8, v33, 3
	s_lshl_b64 s[6:7], s[6:7], 12
	s_lshl_b64 s[4:5], s[4:5], 12
	s_waitcnt vmcnt(15)
; #define GAS __attribute__((address_space(1)))
; __device__ __forceinline__ float lx_get(float v, int src) { return __int_as_float(__builtin_amdgcn_readlane(__float_as_int(v), src)); }
; __device__ __forceinline__ void p_final(Frame& F) {
;     ...
;         for (int trip = 0; trip < 4; ++trip) {
;             h16x4 xv[4][4];
; #pragma unroll
;             for (int t = 0; t < 4; ++t)
; #pragma unroll
;                 for (int j = 0; j < 4; ++j) xv[t][j] = *(const GAS h16x4*)(X16 + (size_t)(rowb + 4 * trip + t) * D + j * 256 + F.lane * 4);
; #pragma unroll
;             for (int t = 0; t < 4; ++t) { const float rs = lx_get(qs[t], trip); float* orow = p.out + (size_t)(rowb + 4 * trip + t) * D;
; #pragma unroll
;                 for (int j = 0; j < 4; ++j) { const h16x4 v = xv[t][j];
;                     *(GAS f32x4*)(orow + j * 256 + F.lane * 4) = (f32x4){(float)v[0], (float)v[1], (float)v[2], (float)v[3]} * rs * gf[j]; } } }
	v_cvt_f32_f16_e32 v24, v26
	v_cvt_f32_f16_sdwa v25, v26 dst_sel:DWORD dst_unused:UNUSED_PAD src0_sel:WORD_1
	v_cvt_f32_f16_e32 v26, v27
	v_cvt_f32_f16_sdwa v27, v27 dst_sel:DWORD dst_unused:UNUSED_PAD src0_sel:WORD_1
	v_pk_mul_f32 v[24:25], v[24:25], s[10:11] op_sel_hi:[1,0]
	s_nop 0
	v_pk_mul_f32 v[24:25], v[2:3], v[24:25]
	v_pk_mul_f32 v[26:27], v[26:27], s[10:11] op_sel_hi:[1,0]
	s_nop 0
	v_pk_mul_f32 v[26:27], v[4:5], v[26:27]
	global_store_dwordx4 v[34:35], v[24:27], off sc1
	s_waitcnt vmcnt(15)
	s_nop 0
	v_cvt_f32_f16_e32 v24, v28
	v_cvt_f32_f16_sdwa v25, v28 dst_sel:DWORD dst_unused:UNUSED_PAD src0_sel:WORD_1
	v_cvt_f32_f16_e32 v26, v29
	v_cvt_f32_f16_sdwa v27, v29 dst_sel:DWORD dst_unused:UNUSED_PAD src0_sel:WORD_1
	v_lshl_add_u64 v[28:29], v[22:23], 0, s[6:7]
	v_pk_mul_f32 v[24:25], v[24:25], s[10:11] op_sel_hi:[1,0]
	v_readlane_b32 s6, v32, 3
	v_pk_mul_f32 v[26:27], v[26:27], s[10:11] op_sel_hi:[1,0]
	v_pk_mul_f32 v[24:25], v[6:7], v[24:25]
	v_pk_mul_f32 v[26:27], v[8:9], v[26:27]
	global_store_dwordx4 v[34:35], v[24:27], off offset:1024 sc1
	s_waitcnt vmcnt(15)
	s_nop 0
	v_cvt_f32_f16_e32 v24, v30
	v_cvt_f32_f16_sdwa v25, v30 dst_sel:DWORD dst_unused:UNUSED_PAD src0_sel:WORD_1
	v_cvt_f32_f16_e32 v26, v31
	v_cvt_f32_f16_sdwa v27, v31 dst_sel:DWORD dst_unused:UNUSED_PAD src0_sel:WORD_1
	v_pk_mul_f32 v[24:25], v[24:25], s[10:11] op_sel_hi:[1,0]
	s_nop 0
	v_pk_mul_f32 v[24:25], v[10:11], v[24:25]
	v_pk_mul_f32 v[26:27], v[26:27], s[10:11] op_sel_hi:[1,0]
	s_nop 0
	v_pk_mul_f32 v[26:27], v[12:13], v[26:27]
	global_store_dwordx4 v[34:35], v[24:27], off offset:2048 sc1
	s_waitcnt vmcnt(15)
	s_nop 0
	v_cvt_f32_f16_e32 v24, v36
	v_cvt_f32_f16_sdwa v25, v36 dst_sel:DWORD dst_unused:UNUSED_PAD src0_sel:WORD_1
	v_cvt_f32_f16_e32 v26, v37
	v_cvt_f32_f16_sdwa v27, v37 dst_sel:DWORD dst_unused:UNUSED_PAD src0_sel:WORD_1
	v_pk_mul_f32 v[24:25], v[24:25], s[10:11] op_sel_hi:[1,0]
	s_nop 0
	v_pk_mul_f32 v[24:25], v[14:15], v[24:25]
	v_pk_mul_f32 v[26:27], v[26:27], s[10:11] op_sel_hi:[1,0]
	s_nop 0
	v_pk_mul_f32 v[26:27], v[16:17], v[26:27]
	global_store_dwordx4 v[34:35], v[24:27], off offset:3072 sc1
	s_waitcnt vmcnt(15)
	s_nop 0
	v_cvt_f32_f16_e32 v24, v38
	v_cvt_f32_f16_sdwa v25, v38 dst_sel:DWORD dst_unused:UNUSED_PAD src0_sel:WORD_1
	v_cvt_f32_f16_e32 v26, v39
	v_cvt_f32_f16_sdwa v27, v39 dst_sel:DWORD dst_unused:UNUSED_PAD src0_sel:WORD_1
	v_pk_mul_f32 v[24:25], v[24:25], s[8:9] op_sel_hi:[1,0]
	s_nop 0
	v_pk_mul_f32 v[24:25], v[2:3], v[24:25]
	v_pk_mul_f32 v[26:27], v[26:27], s[8:9] op_sel_hi:[1,0]
	s_nop 0
	v_pk_mul_f32 v[26:27], v[4:5], v[26:27]
	global_store_dwordx4 v[28:29], v[24:27], off sc1
	s_waitcnt vmcnt(15)
	s_nop 0
	v_cvt_f32_f16_e32 v24, v40
	v_cvt_f32_f16_sdwa v25, v40 dst_sel:DWORD dst_unused:UNUSED_PAD src0_sel:WORD_1
	v_cvt_f32_f16_e32 v26, v41
	v_cvt_f32_f16_sdwa v27, v41 dst_sel:DWORD dst_unused:UNUSED_PAD src0_sel:WORD_1
	v_pk_mul_f32 v[24:25], v[24:25], s[8:9] op_sel_hi:[1,0]
	s_nop 0
	v_pk_mul_f32 v[24:25], v[6:7], v[24:25]
	v_pk_mul_f32 v[26:27], v[26:27], s[8:9] op_sel_hi:[1,0]
	s_nop 0
	v_pk_mul_f32 v[26:27], v[8:9], v[26:27]
	global_store_dwordx4 v[28:29], v[24:27], off offset:1024 sc1
	s_waitcnt vmcnt(15)
	s_nop 0
	v_cvt_f32_f16_e32 v24, v42
	v_cvt_f32_f16_sdwa v25, v42 dst_sel:DWORD dst_unused:UNUSED_PAD src0_sel:WORD_1
	v_cvt_f32_f16_e32 v26, v43
	v_cvt_f32_f16_sdwa v27, v43 dst_sel:DWORD dst_unused:UNUSED_PAD src0_sel:WORD_1
	v_pk_mul_f32 v[24:25], v[24:25], s[8:9] op_sel_hi:[1,0]
	s_nop 0
	v_pk_mul_f32 v[24:25], v[10:11], v[24:25]
	v_pk_mul_f32 v[26:27], v[26:27], s[8:9] op_sel_hi:[1,0]
	s_nop 0
	v_pk_mul_f32 v[26:27], v[12:13], v[26:27]
	global_store_dwordx4 v[28:29], v[24:27], off offset:2048 sc1
	s_waitcnt vmcnt(15)
	s_nop 0
	v_cvt_f32_f16_e32 v24, v44
	v_cvt_f32_f16_sdwa v25, v44 dst_sel:DWORD dst_unused:UNUSED_PAD src0_sel:WORD_1
	v_cvt_f32_f16_e32 v26, v45
	v_cvt_f32_f16_sdwa v27, v45 dst_sel:DWORD dst_unused:UNUSED_PAD src0_sel:WORD_1
	v_pk_mul_f32 v[24:25], v[24:25], s[8:9] op_sel_hi:[1,0]
	s_nop 0
	v_pk_mul_f32 v[24:25], v[14:15], v[24:25]
	v_pk_mul_f32 v[26:27], v[26:27], s[8:9] op_sel_hi:[1,0]
	s_nop 0
	v_pk_mul_f32 v[26:27], v[16:17], v[26:27]
	global_store_dwordx4 v[28:29], v[24:27], off offset:3072 sc1
	v_lshl_add_u64 v[28:29], v[22:23], 0, s[4:5]
	v_readlane_b32 s4, v0, 3
	s_waitcnt vmcnt(15)
; #define GAS __attribute__((address_space(1)))
; __device__ __forceinline__ float lx_get(float v, int src) { return __int_as_float(__builtin_amdgcn_readlane(__float_as_int(v), src)); }
; __device__ __forceinline__ void p_final(Frame& F) {
;     ...
;     for (int grp = gw; grp < MLAT / 16; grp += NGW) { const int rowb = grp * 16;
;         f32x4 qs = *(const GAS f32x4*)(RQ + (size_t)(F.lane >> 2) * MROWS + rowb + 4 * (F.lane & 3));
; #pragma unroll
;         for (int c = 0; c < 4; ++c) { float v = qs[c];
;             v += __int_as_float(__builtin_amdgcn_update_dpp(0, __float_as_int(v), 0x124, 0xF, 0xF, false)); v += __int_as_float(__builtin_amdgcn_update_dpp(0, __float_as_int(v), 0x128, 0xF, 0xF, false));
;             { auto r = __builtin_amdgcn_permlane16_swap(__float_as_uint(v), __float_as_uint(v), false, false); v = __uint_as_float(r[0]) + __uint_as_float(r[1]); }
;             { auto r = __builtin_amdgcn_permlane32_swap(__float_as_uint(v), __float_as_uint(v), false, false); v = __uint_as_float(r[0]) + __uint_as_float(r[1]); }
;             qs[c] = __builtin_amdgcn_rsqf(v * (1.f / 1024.f) + EPS); }
; #pragma unroll
;         for (int trip = 0; trip < 4; ++trip) {
;             h16x4 xv[4][4];
; #pragma unroll
;             for (int t = 0; t < 4; ++t)
; #pragma unroll
;                 for (int j = 0; j < 4; ++j) xv[t][j] = *(const GAS h16x4*)(X16 + (size_t)(rowb + 4 * trip + t) * D + j * 256 + F.lane * 4);
; #pragma unroll
;             for (int t = 0; t < 4; ++t) { const float rs = lx_get(qs[t], trip); float* orow = p.out + (size_t)(rowb + 4 * trip + t) * D;
; #pragma unroll
;                 for (int j = 0; j < 4; ++j) { const h16x4 v = xv[t][j];
;                     *(GAS f32x4*)(orow + j * 256 + F.lane * 4) = (f32x4){(float)v[0], (float)v[1], (float)v[2], (float)v[3]} * rs * gf[j]; } } }
	v_cvt_f32_f16_e32 v24, v46
	v_cvt_f32_f16_sdwa v25, v46 dst_sel:DWORD dst_unused:UNUSED_PAD src0_sel:WORD_1
	v_cvt_f32_f16_e32 v26, v47
	v_cvt_f32_f16_sdwa v27, v47 dst_sel:DWORD dst_unused:UNUSED_PAD src0_sel:WORD_1
	v_pk_mul_f32 v[24:25], v[24:25], s[6:7] op_sel_hi:[1,0]
	s_nop 0
	v_pk_mul_f32 v[24:25], v[2:3], v[24:25]
	v_pk_mul_f32 v[26:27], v[26:27], s[6:7] op_sel_hi:[1,0]
	s_nop 0
	v_pk_mul_f32 v[26:27], v[4:5], v[26:27]
	global_store_dwordx4 v[28:29], v[24:27], off sc1
	s_waitcnt vmcnt(15)
	s_nop 0
	v_cvt_f32_f16_e32 v24, v48
	v_cvt_f32_f16_sdwa v25, v48 dst_sel:DWORD dst_unused:UNUSED_PAD src0_sel:WORD_1
	v_cvt_f32_f16_e32 v26, v49
	v_cvt_f32_f16_sdwa v27, v49 dst_sel:DWORD dst_unused:UNUSED_PAD src0_sel:WORD_1
	v_pk_mul_f32 v[24:25], v[24:25], s[6:7] op_sel_hi:[1,0]
	s_nop 0
	v_pk_mul_f32 v[24:25], v[6:7], v[24:25]
	v_pk_mul_f32 v[26:27], v[26:27], s[6:7] op_sel_hi:[1,0]
	s_nop 0
	v_pk_mul_f32 v[26:27], v[8:9], v[26:27]
	global_store_dwordx4 v[28:29], v[24:27], off offset:1024 sc1
	s_waitcnt vmcnt(15)
	s_nop 0
	v_cvt_f32_f16_e32 v24, v50
	v_cvt_f32_f16_sdwa v25, v50 dst_sel:DWORD dst_unused:UNUSED_PAD src0_sel:WORD_1
	v_cvt_f32_f16_e32 v26, v51
	v_cvt_f32_f16_sdwa v27, v51 dst_sel:DWORD dst_unused:UNUSED_PAD src0_sel:WORD_1
	v_pk_mul_f32 v[24:25], v[24:25], s[6:7] op_sel_hi:[1,0]
	s_nop 0
	v_pk_mul_f32 v[24:25], v[10:11], v[24:25]
	v_pk_mul_f32 v[26:27], v[26:27], s[6:7] op_sel_hi:[1,0]
	s_nop 0
	v_pk_mul_f32 v[26:27], v[12:13], v[26:27]
	global_store_dwordx4 v[28:29], v[24:27], off offset:2048 sc1
	s_waitcnt vmcnt(15)
	s_nop 0
	v_cvt_f32_f16_e32 v24, v52
	v_cvt_f32_f16_sdwa v25, v52 dst_sel:DWORD dst_unused:UNUSED_PAD src0_sel:WORD_1
	v_cvt_f32_f16_e32 v26, v53
	v_cvt_f32_f16_sdwa v27, v53 dst_sel:DWORD dst_unused:UNUSED_PAD src0_sel:WORD_1
	v_pk_mul_f32 v[24:25], v[24:25], s[6:7] op_sel_hi:[1,0]
	s_nop 0
	v_pk_mul_f32 v[24:25], v[14:15], v[24:25]
	v_pk_mul_f32 v[26:27], v[26:27], s[6:7] op_sel_hi:[1,0]
	s_lshl_b64 s[6:7], s[2:3], 12
	v_pk_mul_f32 v[26:27], v[16:17], v[26:27]
	global_store_dwordx4 v[28:29], v[24:27], off offset:3072 sc1
	v_lshl_add_u64 v[28:29], v[22:23], 0, s[6:7]
	s_add_i32 s2, s2, s13
	s_waitcnt vmcnt(15)
	v_cvt_f32_f16_e32 v24, v54
	v_cvt_f32_f16_sdwa v25, v54 dst_sel:DWORD dst_unused:UNUSED_PAD src0_sel:WORD_1
	v_cvt_f32_f16_e32 v26, v55
	v_cvt_f32_f16_sdwa v27, v55 dst_sel:DWORD dst_unused:UNUSED_PAD src0_sel:WORD_1
	s_cmpk_gt_i32 s12, 0x7ff
	v_pk_mul_f32 v[24:25], v[24:25], s[4:5] op_sel_hi:[1,0]
	v_pk_mul_f32 v[26:27], v[26:27], s[4:5] op_sel_hi:[1,0]
	s_nop 0
	v_pk_mul_f32 v[26:27], v[4:5], v[26:27]
	v_pk_mul_f32 v[24:25], v[2:3], v[24:25]
	global_store_dwordx4 v[28:29], v[24:27], off sc1
	s_waitcnt vmcnt(15)
	s_nop 0
	v_cvt_f32_f16_e32 v24, v56
	v_cvt_f32_f16_sdwa v25, v56 dst_sel:DWORD dst_unused:UNUSED_PAD src0_sel:WORD_1
	v_cvt_f32_f16_e32 v26, v57
	v_cvt_f32_f16_sdwa v27, v57 dst_sel:DWORD dst_unused:UNUSED_PAD src0_sel:WORD_1
	v_pk_mul_f32 v[24:25], v[24:25], s[4:5] op_sel_hi:[1,0]
	s_nop 0
	v_pk_mul_f32 v[24:25], v[6:7], v[24:25]
	v_pk_mul_f32 v[26:27], v[26:27], s[4:5] op_sel_hi:[1,0]
	s_nop 0
	v_pk_mul_f32 v[26:27], v[8:9], v[26:27]
	global_store_dwordx4 v[28:29], v[24:27], off offset:1024 sc1
	s_waitcnt vmcnt(15)
	s_nop 0
	v_cvt_f32_f16_e32 v24, v58
	v_cvt_f32_f16_sdwa v25, v58 dst_sel:DWORD dst_unused:UNUSED_PAD src0_sel:WORD_1
	v_cvt_f32_f16_e32 v26, v59
	v_cvt_f32_f16_sdwa v27, v59 dst_sel:DWORD dst_unused:UNUSED_PAD src0_sel:WORD_1
	v_pk_mul_f32 v[24:25], v[24:25], s[4:5] op_sel_hi:[1,0]
	s_nop 0
	v_pk_mul_f32 v[24:25], v[10:11], v[24:25]
	v_pk_mul_f32 v[26:27], v[26:27], s[4:5] op_sel_hi:[1,0]
	s_nop 0
	v_pk_mul_f32 v[26:27], v[12:13], v[26:27]
	global_store_dwordx4 v[28:29], v[24:27], off offset:2048 sc1
	s_waitcnt vmcnt(15)
	s_nop 0
	v_cvt_f32_f16_e32 v24, v60
	v_cvt_f32_f16_sdwa v25, v60 dst_sel:DWORD dst_unused:UNUSED_PAD src0_sel:WORD_1
	v_cvt_f32_f16_e32 v26, v61
	v_cvt_f32_f16_sdwa v27, v61 dst_sel:DWORD dst_unused:UNUSED_PAD src0_sel:WORD_1
	v_pk_mul_f32 v[24:25], v[24:25], s[4:5] op_sel_hi:[1,0]
	s_nop 0
	v_pk_mul_f32 v[24:25], v[14:15], v[24:25]
	v_pk_mul_f32 v[26:27], v[26:27], s[4:5] op_sel_hi:[1,0]
	s_nop 0
	v_pk_mul_f32 v[26:27], v[16:17], v[26:27]
	global_store_dwordx4 v[28:29], v[24:27], off offset:3072 sc1
	s_cbranch_scc0 .LBB0_19

; #define LAS __attribute__((address_space(3)))
; __device__ __forceinline__ void gmlp_unit(unsigned char* ws, h16* Y, const h16* Ws16  , const float* bs  , size_t r0, LAS unsigned char* lds, int tid) {
;     const int lane = tid & 63, wid = __builtin_amdgcn_readfirstlane(tid >> 6), r32 = lane & 31, hi = lane >> 5;
;     const h16* VN = (const h16*)(ws + WS_VN); const h16* GU = (const h16*)(ws + WS_GU); const h16* SZ = (const h16*)(ws + WS_SZ);
;     const int g = wid >> 1, ph = wid & 1; const h16* Wg = Ws16 + (size_t)g * 128 * 128;
;     u32x4 stg[8];
; #pragma unroll
;     for (int j = 0; j < 8; ++j) { const int i = tid + 512 * j, row = i >> 5, c8 = i & 31; stg[j] = *(const GAS u32x4*)(VN + (r0 + row) * 256 + c8 * 8); }
;     s16x8 af[2][8];
; #pragma unroll
;     for (int q = 0; q < 2; ++q)
; #pragma unroll
;     ...
;         if (u < o_attn) {
;             mx::scan_unit(ws, u >> 3, (u >> 1) & 3, u & 1, chain + 64 * u, lds, tid); warm = false;
;         } else if (u < o_gmlp) {
;             const bool isl = u < o_attc; const int a = isl ? u - o_attn : u - o_attc;
;             const int qb = isl ? (a & 7) : 0, g = isl ? (a >> 3) : a, hq = g & 3, kvh = (g >> 2) & 1, b = g >> 3, h = kvh * 4 + hq;
;             const h16* Q = (const h16*)(ws + WS_Q); const h16* KB = (const h16*)(ws + WS_KB); const h16* VB = (const h16*)(ws + WS_VB); const h16* BZ = (const h16*)(ws + WS_BZ); h16* Y = (h16*)F.p.out;
;             const size_t row0 = isl ? (size_t)b * SEQ + qb * 256 : (size_t)MLAT + (size_t)b * CTXL; const size_t kvo = ((size_t)(b * 2 + kvh) * NKEY) * 64;
;             const attn_body::Seam sm{o_attn, o_attc, o_gmlp, Q, KB, VB, (volatile LAS int*)(F.lds + MISC_OFF + 384)};
;             if (mfx <= -1.f) warm = attn_body::attn_unit<8, true>(Q + row0 * 512 + h * 64, KB + kvo, VB + kvo, isl ? NKEY / 64 : CTXL / 64, Y + row0 * D + 256 + h * 64, BZ + row0 * 512 + h * 64, (char*)lds, tid, mfx, warm, nxt, sm);
;             else warm = attn_body::attn_unit<8, false>(Q + row0 * 512 + h * 64, KB + kvo, VB + kvo, isl ? NKEY / 64 : CTXL / 64, Y + row0 * D + 256 + h * 64, BZ + row0 * 512 + h * 64, (char*)lds, tid, mfx, warm, nxt, sm);
;         } else if (u < o_mout) {
;             mx::gmlp_unit(ws, (h16*)F.p.out, (const h16*)(ws + WS_WS16) + (size_t)l * 4 * 128 * 128, F.p.bsp + l * 512, (size_t)(u - o_gmlp) * 128, lds, tid); warm = false;
.LBB0_47:
	s_or_b64 exec, exec, s[0:1]
	v_mov_b32_e32 v247, v212
	s_mov_b32 s50, s40
	s_xor_b64 s[0:1], s[2:3], -1
	s_add_i32 s41, s74, s50
	v_readlane_b32 s22, v253, 0
	v_mov_b32_e32 v211, 0x2880000
	v_readlane_b32 s23, v253, 1
	s_cmpk_gt_i32 s84, 0x7f
	s_mov_b64 s[6:7], -1
	s_cbranch_scc0 .LBB0_228
	s_mov_b64 s[2:3], -1
	s_cmp_ge_i32 s84, s78
	v_lshlrev_b32_e32 v131, 3, v247
	v_bfe_u32 v248, v247, 5, 1
	s_cbranch_scc0 .LBB0_50
	v_readlane_b32 s2, v253, 14
	v_readlane_b32 s3, v253, 15
	s_add_u32 s13, s22, s2
	s_addc_u32 s14, s23, s3
	s_sub_i32 s2, s84, s78
	s_mov_b32 s3, s40
	v_lshlrev_b32_e32 v171, 4, v247
	v_ashrrev_i32_e32 v4, 5, v247
	s_lshl_b64 s[2:3], s[2:3], 7
	v_and_b32_e32 v0, 0x1f0, v171
	v_ashrrev_i32_e32 v5, 31, v4
	v_lshl_add_u64 v[2:3], s[22:23], 0, v[0:1]
	s_mov_b64 s[10:11], 0x9780000
	v_lshl_add_u64 v[4:5], s[2:3], 0, v[4:5]
	v_lshl_add_u64 v[2:3], v[2:3], 0, s[10:11]
	v_lshlrev_b64 v[4:5], 9, v[4:5]
	v_lshl_add_u64 v[4:5], v[2:3], 0, v[4:5]
	global_load_dwordx4 v[160:163], v[4:5], off
	v_add_u32_e32 v0, 0x200, v247
	v_ashrrev_i32_e32 v4, 5, v0
	v_ashrrev_i32_e32 v5, 31, v4
	v_lshl_add_u64 v[4:5], s[2:3], 0, v[4:5]
	v_lshlrev_b64 v[4:5], 9, v[4:5]
	v_lshl_add_u64 v[4:5], v[2:3], 0, v[4:5]
	v_add_u32_e32 v0, 0x400, v247
	global_load_dwordx4 v[156:159], v[4:5], off
	v_ashrrev_i32_e32 v4, 5, v0
	v_ashrrev_i32_e32 v5, 31, v4
	v_lshl_add_u64 v[4:5], s[2:3], 0, v[4:5]
	v_lshlrev_b64 v[4:5], 9, v[4:5]
	v_lshl_add_u64 v[4:5], v[2:3], 0, v[4:5]
	v_add_u32_e32 v0, 0x600, v247
	global_load_dwordx4 v[152:155], v[4:5], off
	v_ashrrev_i32_e32 v4, 5, v0
	v_ashrrev_i32_e32 v5, 31, v4
	v_lshl_add_u64 v[4:5], s[2:3], 0, v[4:5]
	v_lshlrev_b64 v[4:5], 9, v[4:5]
	v_lshl_add_u64 v[4:5], v[2:3], 0, v[4:5]
	v_add_u32_e32 v0, 0x800, v247
	global_load_dwordx4 v[148:151], v[4:5], off
	v_ashrrev_i32_e32 v4, 5, v0
	v_ashrrev_i32_e32 v5, 31, v4
	v_lshl_add_u64 v[4:5], s[2:3], 0, v[4:5]
	v_lshlrev_b64 v[4:5], 9, v[4:5]
	v_lshl_add_u64 v[4:5], v[2:3], 0, v[4:5]
	v_add_u32_e32 v0, 0xa00, v247
	global_load_dwordx4 v[14:17], v[4:5], off
	v_ashrrev_i32_e32 v4, 5, v0
	v_ashrrev_i32_e32 v5, 31, v4
	v_lshl_add_u64 v[4:5], s[2:3], 0, v[4:5]
	v_lshlrev_b64 v[4:5], 9, v[4:5]
	v_lshl_add_u64 v[4:5], v[2:3], 0, v[4:5]
	v_add_u32_e32 v0, 0xc00, v247
	v_readfirstlane_b32 s15, v247
	s_add_u32 s8, s22, 0x8580000
	global_load_dwordx4 v[10:13], v[4:5], off
	v_ashrrev_i32_e32 v4, 5, v0
	s_addc_u32 s9, s23, 0
	s_ashr_i32 s4, s15, 7
	v_ashrrev_i32_e32 v5, 31, v4
	s_ashr_i32 s5, s4, 31
	v_lshl_add_u64 v[4:5], s[2:3], 0, v[4:5]
	s_ashr_i32 s12, s15, 6
	s_lshl_b64 s[6:7], s[4:5], 15
	v_lshlrev_b64 v[4:5], 9, v[4:5]
	s_and_b32 s16, s12, 1
	v_lshl_add_u64 v[4:5], v[2:3], 0, v[4:5]
	v_add_u32_e32 v0, 0xe00, v247
	s_add_u32 s6, s13, s6
	v_and_b32_e32 v169, 31, v247
	global_load_dwordx4 v[6:9], v[4:5], off
	v_ashrrev_i32_e32 v4, 5, v0
	s_addc_u32 s7, s14, s7
	v_lshlrev_b32_e32 v0, 4, v248
	v_lshl_add_u64 v[18:19], s[6:7], 0, v[0:1]
	v_lshlrev_b32_e32 v0, 8, v169
	v_lshl_or_b32 v0, s16, 14, v0
	v_lshl_add_u64 v[18:19], v[18:19], 0, v[0:1]
	s_mov_b64 s[6:7], 0x2500000
	s_mov_b32 s5, 0x2500000
	s_add_u32 s10, s22, 0xa980000
	v_lshl_add_u64 v[20:21], v[18:19], 0, s[6:7]
	s_waitcnt vmcnt(9)
	v_add_co_u32_e32 v22, vcc, s5, v18
	s_addc_u32 s11, s23, 0
	s_and_b32 s6, s15, 0xffffff80
	v_ashrrev_i32_e32 v5, 31, v4
	v_addc_co_u32_e32 v23, vcc, 0, v19, vcc
	s_mov_b32 s5, 0x2502000
	s_ashr_i32 s7, s6, 31
	v_lshl_add_u64 v[4:5], s[2:3], 0, v[4:5]
	v_add_co_u32_e32 v18, vcc, s5, v18
	s_lshl_b64 s[6:7], s[6:7], 2
	v_readlane_b32 s5, v253, 18
	v_lshlrev_b64 v[4:5], 9, v[4:5]
	v_bfe_u32 v167, v247, 3, 3
	s_add_u32 s6, s5, s6
	v_readlane_b32 s5, v253, 20
	v_lshl_add_u64 v[2:3], v[2:3], 0, v[4:5]
	v_addc_co_u32_e32 v19, vcc, 0, v19, vcc
	s_addc_u32 s7, s5, s7
	v_lshlrev_b32_e32 v0, 2, v167
	global_load_dwordx4 v[2:5], v[2:3], off
	s_nop 0
	global_load_dwordx4 v[140:143], v[22:23], off
	global_load_dwordx4 v[144:147], v[20:21], off offset:32
	global_load_dwordx4 v[136:139], v[20:21], off offset:64
	global_load_dwordx4 v[132:135], v[20:21], off offset:96
	global_load_dwordx4 v[126:129], v[20:21], off offset:128
	global_load_dwordx4 v[122:125], v[20:21], off offset:160
	global_load_dwordx4 v[118:121], v[20:21], off offset:192
	global_load_dwordx4 v[114:117], v[20:21], off offset:224
	global_load_dwordx4 v[78:81], v[18:19], off
	global_load_dwordx4 v[74:77], v[18:19], off offset:32
	global_load_dwordx4 v[70:73], v[18:19], off offset:64
	global_load_dwordx4 v[66:69], v[18:19], off offset:96
	global_load_dwordx4 v[62:65], v[18:19], off offset:128
	global_load_dwordx4 v[58:61], v[18:19], off offset:160
	global_load_dwordx4 v[54:57], v[18:19], off offset:192
	global_load_dwordx4 v[50:53], v[18:19], off offset:224
	s_lshl_b32 s5, s16, 6
	v_lshl_add_u64 v[18:19], s[6:7], 0, v[0:1]
	v_or_b32_e32 v28, s2, v167
	s_lshl_b32 s6, s4, 6
	s_ashr_i32 s7, s6, 31
	v_and_b32_e32 v0, 56, v131
	v_or_b32_e32 v164, s5, v28
	v_mov_b32_e32 v165, s3
	v_or_b32_e32 v20, s6, v0
	v_mov_b32_e32 v21, s7
	v_lshlrev_b64 v[22:23], 8, v[164:165]
	v_lshl_add_u64 v[22:23], v[22:23], 0, v[20:21]
	v_lshlrev_b64 v[22:23], 1, v[22:23]
	s_lshl_b32 s14, s16, 8
	s_mov_b32 s15, s40
	v_lshl_add_u64 v[24:25], s[8:9], 0, v[22:23]
	v_lshl_add_u64 v[18:19], v[18:19], 0, s[14:15]
	global_load_dwordx4 v[106:109], v[24:25], off
	v_lshl_add_u64 v[24:25], s[10:11], 0, v[22:23]
	s_mov_b64 s[14:15], 0x1000
	global_load_dword v180, v[18:19], off
	global_load_dwordx4 v[110:113], v[24:25], off
	global_load_dword v178, v[18:19], off offset:32
	v_lshl_add_u64 v[24:25], v[22:23], 0, s[14:15]
	v_lshl_add_u64 v[26:27], s[8:9], 0, v[24:25]
	v_lshl_add_u64 v[24:25], s[10:11], 0, v[24:25]
	s_mov_b64 s[16:17], 0x2000
	global_load_dwordx4 v[98:101], v[26:27], off
	global_load_dwordx4 v[102:105], v[24:25], off
	global_load_dword v176, v[18:19], off offset:64
	v_lshl_add_u64 v[24:25], v[22:23], 0, s[16:17]
	s_mov_b64 s[18:19], 0x3000
	v_lshl_add_u64 v[26:27], s[8:9], 0, v[24:25]
	v_lshl_add_u64 v[24:25], s[10:11], 0, v[24:25]
	v_lshl_add_u64 v[22:23], v[22:23], 0, s[18:19]
	s_or_b32 s3, s5, 32
	global_load_dwordx4 v[90:93], v[26:27], off
	global_load_dwordx4 v[94:97], v[24:25], off
	global_load_dword v174, v[18:19], off offset:96
	v_lshl_add_u64 v[24:25], s[8:9], 0, v[22:23]
	v_lshl_add_u64 v[22:23], s[10:11], 0, v[22:23]
	v_or_b32_e32 v164, s3, v28
	global_load_dwordx4 v[82:85], v[24:25], off
	global_load_dwordx4 v[86:89], v[22:23], off
	v_lshlrev_b64 v[22:23], 8, v[164:165]
	v_lshl_add_u64 v[20:21], v[22:23], 0, v[20:21]
	v_lshlrev_b64 v[20:21], 1, v[20:21]
	v_lshl_add_u64 v[22:23], s[8:9], 0, v[20:21]
	global_load_dwordx4 v[42:45], v[22:23], off
	v_lshl_add_u64 v[22:23], s[10:11], 0, v[20:21]
	global_load_dword v172, v[18:19], off offset:128
	global_load_dwordx4 v[46:49], v[22:23], off
	global_load_dword v170, v[18:19], off offset:160
	v_lshl_add_u64 v[22:23], v[20:21], 0, s[14:15]
	v_lshl_add_u64 v[24:25], s[8:9], 0, v[22:23]
	v_lshl_add_u64 v[22:23], s[10:11], 0, v[22:23]
	s_waitcnt vmcnt(39)
; #define LAS __attribute__((address_space(3)))
; #define GAS __attribute__((address_space(1)))
; __device__ __forceinline__ float geluf(float x) { return x * __builtin_amdgcn_rcpf(1.f + __builtin_amdgcn_exp2f(x * (-0.10294324f * x * x - 2.3022082f))); }
; __device__ __forceinline__ float lx_xor(float v, int m, int lane) { return __int_as_float(__builtin_amdgcn_ds_bpermute((lane ^ m) << 2, __float_as_int(v))); }
; __device__ __forceinline__ unsigned cvtpk_h(float lo, float hi) { f32x2 v = {lo, hi}; h16x2 b = __builtin_convertvector(v, h16x2); return __builtin_bit_cast(unsigned, b); }
; __device__ __forceinline__ void gmlp_unit(unsigned char* ws, h16* Y, const h16* Ws16  , const float* bs  , size_t r0, LAS unsigned char* lds, int tid) {
;     ...
;         for (int ps = 0; ps < 4; ++ps) { bias[q][ps] = *(const GAS float*)(bs + g * 128 + 32 * (2 * ph + q) + 8 * ps + erow);
;             const size_t go = (r0 + 32 * (2 * ph + q) + 8 * ps + erow) * 256 + g * 64 + 8 * ech;
;             gu[q][ps] = *(const GAS h16x8*)(GU + go); sz[q][ps] = *(const GAS h16x8*)(SZ + go); }
; #pragma unroll
;     for (int j = 0; j < 8; ++j) { const int i = tid + 512 * j, row = i >> 5, c8 = i & 31, gg = c8 >> 3, cg = (c8 & 7) * 8;
;         const h16x8 hv = __builtin_bit_cast(h16x8, stg[j]); float x[8]; float sm = 0.f;
; #pragma unroll
;         for (int k = 0; k < 8; ++k) { x[k] = geluf((float)hv[k]); sm += x[k]; }
;         sm += lx_xor(sm, 1, lane); sm += lx_xor(sm, 2, lane); sm += lx_xor(sm, 4, lane);
;         const float mu = sm * (1.f / 64.f); float q = 0.f;
; #pragma unroll
;         for (int k = 0; k < 8; ++k) { x[k] -= mu; q += x[k] * x[k]; }
;         q += lx_xor(q, 1, lane); q += lx_xor(q, 2, lane); q += lx_xor(q, 4, lane);
;         const float rd = __builtin_amdgcn_rsqf(q * (1.f / 64.f) + EPS);
;         u32x4 o; o.x = cvtpk_h(x[0] * rd, x[1] * rd); o.y = cvtpk_h(x[2] * rd, x[3] * rd); o.z = cvtpk_h(x[4] * rd, x[5] * rd); o.w = cvtpk_h(x[6] * rd, x[7] * rd);
;         *(LAS u32x4*)(lds + gg * 16384 + (cg >> 5) * 8192 + row * 64 + (cg & 31) * 2) = o; }
	v_cvt_f32_f16_e32 v192, v161
	v_cvt_f32_f16_sdwa v193, v161 dst_sel:DWORD dst_unused:UNUSED_PAD src0_sel:WORD_1
	global_load_dwordx4 v[34:37], v[24:25], off
	global_load_dwordx4 v[38:41], v[22:23], off
	global_load_dword v168, v[18:19], off offset:192
	v_lshl_add_u64 v[22:23], v[20:21], 0, s[16:17]
	v_lshl_add_u64 v[24:25], s[8:9], 0, v[22:23]
	v_lshl_add_u64 v[22:23], s[10:11], 0, v[22:23]
	global_load_dwordx4 v[26:29], v[24:25], off
	global_load_dwordx4 v[30:33], v[22:23], off
	global_load_dword v166, v[18:19], off offset:224
	v_lshl_add_u64 v[22:23], v[20:21], 0, s[18:19]
	v_lshl_add_u64 v[18:19], s[8:9], 0, v[22:23]
	v_cvt_f32_f16_e32 v182, v163
	v_cvt_f32_f16_sdwa v183, v163 dst_sel:DWORD dst_unused:UNUSED_PAD src0_sel:WORD_1
	s_mov_b32 s9, 0xc0135761
	v_mul_f32_e32 v194, 0x3dd2d3e8, v192
	v_mul_f32_e32 v195, 0x3dd2d3e8, v193
	v_fma_mix_f32 v194, -v194, v161, s9 op_sel_hi:[0,1,0]
	v_fma_mix_f32 v161, -v195, v161, s9 op_sel:[0,1,0] op_sel_hi:[0,1,0]
	v_mul_f32_e32 v161, v161, v193
	v_exp_f32_e32 v161, v161
	v_mul_f32_e32 v184, 0x3dd2d3e8, v182
	v_mul_f32_e32 v185, 0x3dd2d3e8, v183
	v_cvt_f32_f16_e32 v198, v160
	v_fma_mix_f32 v184, -v184, v163, s9 op_sel_hi:[0,1,0]
	v_fma_mix_f32 v163, -v185, v163, s9 op_sel:[0,1,0] op_sel_hi:[0,1,0]
	v_mul_f32_e32 v163, v163, v183
	v_exp_f32_e32 v163, v163
	v_add_f32_e32 v161, 1.0, v161
	v_cvt_f32_f16_e32 v186, v162
	v_rcp_f32_e32 v195, v161
	v_mul_f32_e32 v161, 0x3dd2d3e8, v198
	v_fma_mix_f32 v161, -v161, v160, s9 op_sel_hi:[0,1,0]
	v_mul_f32_e32 v161, v161, v198
	v_add_f32_e32 v163, 1.0, v163
	v_exp_f32_e32 v161, v161
	v_rcp_f32_e32 v185, v163
	v_mul_f32_e32 v163, 0x3dd2d3e8, v186
	v_cvt_f32_f16_sdwa v199, v160 dst_sel:DWORD dst_unused:UNUSED_PAD src0_sel:WORD_1
	v_fma_mix_f32 v163, -v163, v162, s9 op_sel_hi:[0,1,0]
	v_mul_f32_e32 v163, v163, v186
	v_exp_f32_e32 v163, v163
	v_add_f32_e32 v161, 1.0, v161
	v_cvt_f32_f16_sdwa v187, v162 dst_sel:DWORD dst_unused:UNUSED_PAD src0_sel:WORD_1
	v_rcp_f32_e32 v200, v161
	v_mul_f32_e32 v161, 0x3dd2d3e8, v199
	v_fma_mix_f32 v160, -v161, v160, s9 op_sel:[0,1,0] op_sel_hi:[0,1,0]
	v_mul_f32_e32 v160, v160, v199
	v_add_f32_e32 v163, 1.0, v163
	v_exp_f32_e32 v160, v160
	v_rcp_f32_e32 v190, v163
	v_mul_f32_e32 v163, 0x3dd2d3e8, v187
	v_mul_f32_e32 v194, v194, v192
	v_fma_mix_f32 v162, -v163, v162, s9 op_sel:[0,1,0] op_sel_hi:[0,1,0]
	v_exp_f32_e32 v194, v194
	v_mul_f32_e32 v162, v162, v187
	v_exp_f32_e32 v162, v162
	v_add_f32_e32 v160, 1.0, v160
	v_mul_f32_e32 v184, v184, v182
	v_rcp_f32_e32 v201, v160
	v_exp_f32_e32 v184, v184
	v_add_f32_e32 v194, 1.0, v194
	v_rcp_f32_e32 v194, v194
	v_add_f32_e32 v162, 1.0, v162
	v_rcp_f32_e32 v191, v162
	v_pk_mul_f32 v[160:161], v[200:201], v[198:199]
	v_add_f32_e32 v184, 1.0, v184
	v_add_f32_e32 v160, 0, v160
	v_rcp_f32_e32 v184, v184
	v_pk_mul_f32 v[196:197], v[194:195], v[192:193]
	v_add_f32_e32 v160, v161, v160
	v_add_f32_e32 v160, v196, v160
	v_pk_mul_f32 v[162:163], v[190:191], v[186:187]
	v_add_f32_e32 v160, v197, v160
	v_add_f32_e32 v160, v162, v160
	v_and_b32_e32 v173, 63, v247
	v_pk_mul_f32 v[188:189], v[184:185], v[182:183]
	v_add_f32_e32 v160, v163, v160
	v_lshlrev_b32_e32 v164, 2, v173
	v_add_f32_e32 v160, v188, v160
	v_xor_b32_e32 v177, 4, v164
	v_add_f32_e32 v160, v189, v160
	s_nop 0
	v_xor_b32_e32 v175, 8, v164
	v_xor_b32_e32 v173, 16, v164
	v_lshlrev_b32_e32 v179, 11, v247
	v_and_b32_e32 v181, 0xc000, v179
	s_nop 1
	v_add_f32_dpp v160, v160, v160 quad_perm:[1,0,3,2] row_mask:0xf bank_mask:0xf
	s_nop 0
	v_and_b32_e32 v179, 0x2000, v179
	v_add3_u32 v179, s41, v181, v179
	v_lshlrev_b32_e32 v181, 1, v247
	v_and_b32_e32 v202, 48, v171
	s_nop 1
	v_add_f32_dpp v160, v160, v160 quad_perm:[2,3,0,1] row_mask:0xf bank_mask:0xf
	s_nop 0
	v_and_b32_e32 v181, 0xffffffc0, v181
	v_add3_u32 v179, v179, v202, v181
	s_lshl_b32 s4, s4, 14
	v_lshl_add_u64 v[22:23], s[10:11], 0, v[22:23]
	s_nop 1
	v_add_f32_dpp v160, v160, v160 row_half_mirror row_mask:0xf bank_mask:0xf
	v_mul_f32_e32 v160, 0x3c800000, v160
	v_pk_fma_f32 v[162:163], v[200:201], v[198:199], v[160:161] op_sel_hi:[1,1,0] neg_lo:[0,0,1] neg_hi:[0,0,1]
	v_pk_fma_f32 v[192:193], v[194:195], v[192:193], v[160:161] op_sel_hi:[1,1,0] neg_lo:[0,0,1] neg_hi:[0,0,1]
	v_pk_mul_f32 v[188:189], v[162:163], v[162:163]
	v_pk_mul_f32 v[194:195], v[192:193], v[192:193]
	v_pk_fma_f32 v[182:183], v[184:185], v[182:183], v[160:161] op_sel_hi:[1,1,0] neg_lo:[0,0,1] neg_hi:[0,0,1]
	v_add_f32_e32 v184, v188, v189
	v_pk_fma_f32 v[186:187], v[190:191], v[186:187], v[160:161] op_sel_hi:[1,1,0] neg_lo:[0,0,1] neg_hi:[0,0,1]
	v_add_f32_e32 v184, v194, v184
	v_pk_mul_f32 v[190:191], v[186:187], v[186:187]
	v_add_f32_e32 v184, v195, v184
	v_add_f32_e32 v184, v190, v184
	v_pk_mul_f32 v[160:161], v[182:183], v[182:183]
	v_add_f32_e32 v184, v191, v184
	v_add_f32_e32 v160, v160, v184
	v_add_f32_e32 v160, v161, v160
	s_nop 0
	s_waitcnt vmcnt(44)
; #define LAS __attribute__((address_space(3)))
; __device__ __forceinline__ float geluf(float x) { return x * __builtin_amdgcn_rcpf(1.f + __builtin_amdgcn_exp2f(x * (-0.10294324f * x * x - 2.3022082f))); }
; __device__ __forceinline__ float lx_xor(float v, int m, int lane) { return __int_as_float(__builtin_amdgcn_ds_bpermute((lane ^ m) << 2, __float_as_int(v))); }
; __device__ __forceinline__ unsigned cvtpk_h(float lo, float hi) { f32x2 v = {lo, hi}; h16x2 b = __builtin_convertvector(v, h16x2); return __builtin_bit_cast(unsigned, b); }
; __device__ __forceinline__ void gmlp_unit(unsigned char* ws, h16* Y, const h16* Ws16  , const float* bs  , size_t r0, LAS unsigned char* lds, int tid) {
;     ...
;     for (int j = 0; j < 8; ++j) { const int i = tid + 512 * j, row = i >> 5, c8 = i & 31, gg = c8 >> 3, cg = (c8 & 7) * 8;
;         const h16x8 hv = __builtin_bit_cast(h16x8, stg[j]); float x[8]; float sm = 0.f;
; #pragma unroll
;         for (int k = 0; k < 8; ++k) { x[k] = geluf((float)hv[k]); sm += x[k]; }
;         sm += lx_xor(sm, 1, lane); sm += lx_xor(sm, 2, lane); sm += lx_xor(sm, 4, lane);
;         const float mu = sm * (1.f / 64.f); float q = 0.f;
; #pragma unroll
;         for (int k = 0; k < 8; ++k) { x[k] -= mu; q += x[k] * x[k]; }
;         q += lx_xor(q, 1, lane); q += lx_xor(q, 2, lane); q += lx_xor(q, 4, lane);
;         const float rd = __builtin_amdgcn_rsqf(q * (1.f / 64.f) + EPS);
;         u32x4 o; o.x = cvtpk_h(x[0] * rd, x[1] * rd); o.y = cvtpk_h(x[2] * rd, x[3] * rd); o.z = cvtpk_h(x[4] * rd, x[5] * rd); o.w = cvtpk_h(x[6] * rd, x[7] * rd);
;         *(LAS u32x4*)(lds + gg * 16384 + (cg >> 5) * 8192 + row * 64 + (cg & 31) * 2) = o; }
	v_cvt_f32_f16_e32 v188, v157
	v_cvt_f32_f16_sdwa v189, v157 dst_sel:DWORD dst_unused:UNUSED_PAD src0_sel:WORD_1
	v_cvt_f32_f16_e32 v194, v156
	v_cvt_f32_f16_sdwa v195, v156 dst_sel:DWORD dst_unused:UNUSED_PAD src0_sel:WORD_1
	s_nop 1
	v_add_f32_dpp v160, v160, v160 quad_perm:[1,0,3,2] row_mask:0xf bank_mask:0xf
	s_nop 0
	v_mul_f32_e32 v181, 0x3dd2d3e8, v188
	v_fma_mix_f32 v181, -v181, v157, s9 op_sel_hi:[0,1,0]
	v_mul_f32_e32 v181, v181, v188
	v_exp_f32_e32 v181, v181
	s_nop 1
	v_add_f32_dpp v160, v160, v160 quad_perm:[2,3,0,1] row_mask:0xf bank_mask:0xf
	s_nop 0
	s_add_i32 s4, s41, s4
	v_add_f32_e32 v181, 1.0, v181
	v_rcp_f32_e32 v190, v181
	v_mul_f32_e32 v181, 0x3dd2d3e8, v189
	s_nop 1
	v_add_f32_dpp v160, v160, v160 row_half_mirror row_mask:0xf bank_mask:0xf
	v_fmamk_f32 v160, v160, 0x3c800000, v229
	v_rsq_f32_e32 v184, v160
	v_fma_mix_f32 v157, -v181, v157, s9 op_sel:[0,1,0] op_sel_hi:[0,1,0]
	v_mul_f32_e32 v157, v157, v189
	v_exp_f32_e32 v157, v157
	v_pk_mul_f32 v[160:161], v[162:163], v[184:185] op_sel_hi:[1,0]
	v_pk_mul_f32 v[162:163], v[192:193], v[184:185] op_sel_hi:[1,0]
	v_cvt_pk_f16_f32 v160, v160, v161
	v_cvt_pk_f16_f32 v161, v162, v163
	v_pk_mul_f32 v[162:163], v[186:187], v[184:185] op_sel_hi:[1,0]
	v_pk_mul_f32 v[182:183], v[182:183], v[184:185] op_sel_hi:[1,0]
	v_cvt_pk_f16_f32 v162, v162, v163
	v_cvt_pk_f16_f32 v163, v182, v183
	ds_write_b128 v179, v[160:163]
	v_cvt_f32_f16_e32 v160, v159
	v_cvt_f32_f16_sdwa v161, v159 dst_sel:DWORD dst_unused:UNUSED_PAD src0_sel:WORD_1
	v_add_f32_e32 v157, 1.0, v157
	v_cvt_f32_f16_e32 v184, v158
	v_mul_f32_e32 v162, 0x3dd2d3e8, v160
	v_mul_f32_e32 v163, 0x3dd2d3e8, v161
	v_fma_mix_f32 v162, -v162, v159, s9 op_sel_hi:[0,1,0]
	v_fma_mix_f32 v159, -v163, v159, s9 op_sel:[0,1,0] op_sel_hi:[0,1,0]
	v_mul_f32_e32 v159, v159, v161
	v_exp_f32_e32 v159, v159
	v_rcp_f32_e32 v191, v157
	v_mul_f32_e32 v157, 0x3dd2d3e8, v194
	v_fma_mix_f32 v157, -v157, v156, s9 op_sel_hi:[0,1,0]
	v_mul_f32_e32 v157, v157, v194
	v_add_f32_e32 v159, 1.0, v159
	v_exp_f32_e32 v157, v157
	v_rcp_f32_e32 v163, v159
	v_mul_f32_e32 v159, 0x3dd2d3e8, v184
	v_fma_mix_f32 v159, -v159, v158, s9 op_sel_hi:[0,1,0]
	v_mul_f32_e32 v159, v159, v184
	v_exp_f32_e32 v159, v159
	v_add_f32_e32 v157, 1.0, v157
	v_cvt_f32_f16_sdwa v185, v158 dst_sel:DWORD dst_unused:UNUSED_PAD src0_sel:WORD_1
	v_rcp_f32_e32 v196, v157
	v_mul_f32_e32 v157, 0x3dd2d3e8, v195
	v_fma_mix_f32 v156, -v157, v156, s9 op_sel:[0,1,0] op_sel_hi:[0,1,0]
	v_mul_f32_e32 v156, v156, v195
	v_add_f32_e32 v159, 1.0, v159
	v_exp_f32_e32 v156, v156
	v_rcp_f32_e32 v186, v159
	v_mul_f32_e32 v159, 0x3dd2d3e8, v185
	v_fma_mix_f32 v158, -v159, v158, s9 op_sel:[0,1,0] op_sel_hi:[0,1,0]
	v_mul_f32_e32 v158, v158, v185
	v_exp_f32_e32 v158, v158
	v_add_f32_e32 v156, 1.0, v156
	v_mul_f32_e32 v162, v162, v160
	v_rcp_f32_e32 v197, v156
	v_exp_f32_e32 v162, v162
	v_add_f32_e32 v158, 1.0, v158
	v_rcp_f32_e32 v187, v158
	v_pk_mul_f32 v[156:157], v[196:197], v[194:195]
	v_add_f32_e32 v162, 1.0, v162
	v_add_f32_e32 v156, 0, v156
	v_rcp_f32_e32 v162, v162
	v_pk_mul_f32 v[192:193], v[190:191], v[188:189]
	v_add_f32_e32 v156, v157, v156
	v_add_f32_e32 v156, v192, v156
	v_pk_mul_f32 v[158:159], v[186:187], v[184:185]
	v_add_f32_e32 v156, v193, v156
	v_add_f32_e32 v156, v158, v156
	v_pk_mul_f32 v[182:183], v[162:163], v[160:161]
	v_add_f32_e32 v156, v159, v156
	v_add_f32_e32 v156, v182, v156
	v_add_f32_e32 v156, v183, v156
	s_nop 0
	global_load_dwordx4 v[18:21], v[18:19], off
	s_mulk_i32 s12, 0x1200
	global_load_dwordx4 v[22:25], v[22:23], off
	s_add_i32 s8, s41, s12
	s_nop 1
	v_add_f32_dpp v156, v156, v156 quad_perm:[1,0,3,2] row_mask:0xf bank_mask:0xf
	s_nop 0
	s_add_i32 s8, s8, 0x10000
	s_lshl_b64 s[6:7], s[6:7], 1
	v_readlane_b32 s12, v251, 0
	v_readlane_b32 s13, v251, 1
	s_nop 1
	v_add_f32_dpp v156, v156, v156 quad_perm:[2,3,0,1] row_mask:0xf bank_mask:0xf
	s_nop 0
	s_add_u32 s6, s12, s6
	v_lshlrev_b32_e32 v0, 1, v0
	s_addc_u32 s7, s13, s7
	v_readlane_b32 s14, v251, 2
	s_nop 1
	v_add_f32_dpp v156, v156, v156 row_half_mirror row_mask:0xf bank_mask:0xf
	v_mul_f32_e32 v156, 0x3c800000, v156
	v_pk_fma_f32 v[158:159], v[196:197], v[194:195], v[156:157] op_sel_hi:[1,1,0] neg_lo:[0,0,1] neg_hi:[0,0,1]
	v_pk_fma_f32 v[188:189], v[190:191], v[188:189], v[156:157] op_sel_hi:[1,1,0] neg_lo:[0,0,1] neg_hi:[0,0,1]
	v_pk_mul_f32 v[182:183], v[158:159], v[158:159]
	v_pk_mul_f32 v[190:191], v[188:189], v[188:189]
	v_pk_fma_f32 v[160:161], v[162:163], v[160:161], v[156:157] op_sel_hi:[1,1,0] neg_lo:[0,0,1] neg_hi:[0,0,1]
	v_add_f32_e32 v162, v182, v183
	v_pk_fma_f32 v[184:185], v[186:187], v[184:185], v[156:157] op_sel_hi:[1,1,0] neg_lo:[0,0,1] neg_hi:[0,0,1]
	v_add_f32_e32 v162, v190, v162
	v_pk_mul_f32 v[186:187], v[184:185], v[184:185]
	v_add_f32_e32 v162, v191, v162
	v_add_f32_e32 v162, v186, v162
	v_pk_mul_f32 v[156:157], v[160:161], v[160:161]
	v_add_f32_e32 v162, v187, v162
	v_add_f32_e32 v156, v156, v162
	v_add_f32_e32 v156, v157, v156
	s_nop 0
	s_waitcnt vmcnt(45)
; #define LAS __attribute__((address_space(3)))
; __device__ __forceinline__ float geluf(float x) { return x * __builtin_amdgcn_rcpf(1.f + __builtin_amdgcn_exp2f(x * (-0.10294324f * x * x - 2.3022082f))); }
; __device__ __forceinline__ float lx_xor(float v, int m, int lane) { return __int_as_float(__builtin_amdgcn_ds_bpermute((lane ^ m) << 2, __float_as_int(v))); }
; __device__ __forceinline__ unsigned cvtpk_h(float lo, float hi) { f32x2 v = {lo, hi}; h16x2 b = __builtin_convertvector(v, h16x2); return __builtin_bit_cast(unsigned, b); }
; __device__ __forceinline__ void gmlp_unit(unsigned char* ws, h16* Y, const h16* Ws16  , const float* bs  , size_t r0, LAS unsigned char* lds, int tid) {
;     ...
;     for (int j = 0; j < 8; ++j) { const int i = tid + 512 * j, row = i >> 5, c8 = i & 31, gg = c8 >> 3, cg = (c8 & 7) * 8;
;         const h16x8 hv = __builtin_bit_cast(h16x8, stg[j]); float x[8]; float sm = 0.f;
; #pragma unroll
;         for (int k = 0; k < 8; ++k) { x[k] = geluf((float)hv[k]); sm += x[k]; }
;         sm += lx_xor(sm, 1, lane); sm += lx_xor(sm, 2, lane); sm += lx_xor(sm, 4, lane);
;         const float mu = sm * (1.f / 64.f); float q = 0.f;
; #pragma unroll
;         for (int k = 0; k < 8; ++k) { x[k] -= mu; q += x[k] * x[k]; }
;         q += lx_xor(q, 1, lane); q += lx_xor(q, 2, lane); q += lx_xor(q, 4, lane);
;         const float rd = __builtin_amdgcn_rsqf(q * (1.f / 64.f) + EPS);
;         u32x4 o; o.x = cvtpk_h(x[0] * rd, x[1] * rd); o.y = cvtpk_h(x[2] * rd, x[3] * rd); o.z = cvtpk_h(x[4] * rd, x[5] * rd); o.w = cvtpk_h(x[6] * rd, x[7] * rd);
;         *(LAS u32x4*)(lds + gg * 16384 + (cg >> 5) * 8192 + row * 64 + (cg & 31) * 2) = o; }
	v_cvt_f32_f16_e32 v190, v152
	v_cvt_f32_f16_sdwa v191, v152 dst_sel:DWORD dst_unused:UNUSED_PAD src0_sel:WORD_1
	v_readlane_b32 s15, v251, 3
	v_readlane_b32 s16, v251, 4
	s_nop 1
	v_add_f32_dpp v156, v156, v156 quad_perm:[1,0,3,2] row_mask:0xf bank_mask:0xf
	s_nop 0
	v_readlane_b32 s17, v251, 5
	v_readlane_b32 s18, v251, 6
	v_readlane_b32 s19, v251, 7
	s_nop 1
	v_add_f32_dpp v156, v156, v156 quad_perm:[2,3,0,1] row_mask:0xf bank_mask:0xf
	s_nop 0
	s_nop 1
	v_add_f32_dpp v156, v156, v156 row_half_mirror row_mask:0xf bank_mask:0xf
	v_fmamk_f32 v156, v156, 0x3c800000, v229
	v_rsq_f32_e32 v162, v156
	s_nop 0
	v_pk_mul_f32 v[156:157], v[158:159], v[162:163] op_sel_hi:[1,0]
	v_pk_mul_f32 v[158:159], v[188:189], v[162:163] op_sel_hi:[1,0]
	v_cvt_pk_f16_f32 v156, v156, v157
	v_cvt_pk_f16_f32 v157, v158, v159
	v_pk_mul_f32 v[158:159], v[184:185], v[162:163] op_sel_hi:[1,0]
	v_cvt_f32_f16_e32 v184, v153
	v_cvt_f32_f16_sdwa v185, v153 dst_sel:DWORD dst_unused:UNUSED_PAD src0_sel:WORD_1
	v_pk_mul_f32 v[160:161], v[160:161], v[162:163] op_sel_hi:[1,0]
	v_cvt_pk_f16_f32 v158, v158, v159
	v_mul_f32_e32 v181, 0x3dd2d3e8, v184
	v_fma_mix_f32 v181, -v181, v153, s9 op_sel_hi:[0,1,0]
	v_mul_f32_e32 v181, v181, v184
	v_exp_f32_e32 v181, v181
	v_cvt_pk_f16_f32 v159, v160, v161
	ds_write_b128 v179, v[156:159] offset:1024
	v_cvt_f32_f16_e32 v156, v155
	v_add_f32_e32 v181, 1.0, v181
	v_cvt_f32_f16_sdwa v157, v155 dst_sel:DWORD dst_unused:UNUSED_PAD src0_sel:WORD_1
	v_rcp_f32_e32 v186, v181
	v_mul_f32_e32 v181, 0x3dd2d3e8, v185
	v_fma_mix_f32 v153, -v181, v153, s9 op_sel:[0,1,0] op_sel_hi:[0,1,0]
	v_mul_f32_e32 v153, v153, v185
	v_exp_f32_e32 v153, v153
	v_mul_f32_e32 v158, 0x3dd2d3e8, v156
	v_mul_f32_e32 v159, 0x3dd2d3e8, v157
	v_fma_mix_f32 v158, -v158, v155, s9 op_sel_hi:[0,1,0]
	v_fma_mix_f32 v155, -v159, v155, s9 op_sel:[0,1,0] op_sel_hi:[0,1,0]
	v_mul_f32_e32 v155, v155, v157
	v_exp_f32_e32 v155, v155
	v_add_f32_e32 v153, 1.0, v153
	v_cvt_f32_f16_e32 v162, v154
	v_rcp_f32_e32 v187, v153
	v_mul_f32_e32 v153, 0x3dd2d3e8, v190
	v_fma_mix_f32 v153, -v153, v152, s9 op_sel_hi:[0,1,0]
	v_mul_f32_e32 v153, v153, v190
	v_add_f32_e32 v155, 1.0, v155
	v_exp_f32_e32 v153, v153
	v_rcp_f32_e32 v159, v155
	v_mul_f32_e32 v155, 0x3dd2d3e8, v162
	v_fma_mix_f32 v155, -v155, v154, s9 op_sel_hi:[0,1,0]
	v_mul_f32_e32 v155, v155, v162
	v_exp_f32_e32 v155, v155
	v_add_f32_e32 v153, 1.0, v153
	v_cvt_f32_f16_sdwa v163, v154 dst_sel:DWORD dst_unused:UNUSED_PAD src0_sel:WORD_1
	v_rcp_f32_e32 v192, v153
	v_mul_f32_e32 v153, 0x3dd2d3e8, v191
	v_fma_mix_f32 v152, -v153, v152, s9 op_sel:[0,1,0] op_sel_hi:[0,1,0]
	v_mul_f32_e32 v152, v152, v191
	v_add_f32_e32 v155, 1.0, v155
	v_exp_f32_e32 v152, v152
	v_rcp_f32_e32 v182, v155
	v_mul_f32_e32 v155, 0x3dd2d3e8, v163
	v_fma_mix_f32 v154, -v155, v154, s9 op_sel:[0,1,0] op_sel_hi:[0,1,0]
	v_mul_f32_e32 v154, v154, v163
	v_exp_f32_e32 v154, v154
	v_add_f32_e32 v152, 1.0, v152
	v_mul_f32_e32 v158, v158, v156
	v_rcp_f32_e32 v193, v152
	v_exp_f32_e32 v158, v158
	v_add_f32_e32 v154, 1.0, v154
	v_rcp_f32_e32 v183, v154
	v_pk_mul_f32 v[152:153], v[192:193], v[190:191]
	v_add_f32_e32 v158, 1.0, v158
	v_add_f32_e32 v152, 0, v152
	v_rcp_f32_e32 v158, v158
	v_pk_mul_f32 v[188:189], v[186:187], v[184:185]
	v_add_f32_e32 v152, v153, v152
	v_add_f32_e32 v152, v188, v152
	v_pk_mul_f32 v[154:155], v[182:183], v[162:163]
	v_add_f32_e32 v152, v189, v152
	v_add_f32_e32 v152, v154, v152
	v_pk_mul_f32 v[160:161], v[158:159], v[156:157]
	v_add_f32_e32 v152, v155, v152
	v_add_f32_e32 v152, v160, v152
	v_add_f32_e32 v152, v161, v152
	s_nop 0
	s_nop 1
	v_add_f32_dpp v152, v152, v152 quad_perm:[1,0,3,2] row_mask:0xf bank_mask:0xf
	s_nop 0
	s_nop 1
	v_add_f32_dpp v152, v152, v152 quad_perm:[2,3,0,1] row_mask:0xf bank_mask:0xf
	s_nop 0
	s_nop 1
	v_add_f32_dpp v152, v152, v152 row_half_mirror row_mask:0xf bank_mask:0xf
	v_mul_f32_e32 v152, 0x3c800000, v152
	v_pk_fma_f32 v[154:155], v[192:193], v[190:191], v[152:153] op_sel_hi:[1,1,0] neg_lo:[0,0,1] neg_hi:[0,0,1]
	v_pk_fma_f32 v[184:185], v[186:187], v[184:185], v[152:153] op_sel_hi:[1,1,0] neg_lo:[0,0,1] neg_hi:[0,0,1]
	v_pk_mul_f32 v[160:161], v[154:155], v[154:155]
	v_pk_mul_f32 v[186:187], v[184:185], v[184:185]
	v_pk_fma_f32 v[156:157], v[158:159], v[156:157], v[152:153] op_sel_hi:[1,1,0] neg_lo:[0,0,1] neg_hi:[0,0,1]
	v_add_f32_e32 v158, v160, v161
	v_pk_fma_f32 v[162:163], v[182:183], v[162:163], v[152:153] op_sel_hi:[1,1,0] neg_lo:[0,0,1] neg_hi:[0,0,1]
	v_add_f32_e32 v158, v186, v158
	v_pk_mul_f32 v[182:183], v[162:163], v[162:163]
	v_add_f32_e32 v158, v187, v158
	v_add_f32_e32 v158, v182, v158
	v_pk_mul_f32 v[152:153], v[156:157], v[156:157]
	v_add_f32_e32 v158, v183, v158
	v_add_f32_e32 v152, v152, v158
	v_add_f32_e32 v152, v153, v152
	s_nop 0
	s_waitcnt vmcnt(44)
; #define LAS __attribute__((address_space(3)))
; __device__ __forceinline__ float geluf(float x) { return x * __builtin_amdgcn_rcpf(1.f + __builtin_amdgcn_exp2f(x * (-0.10294324f * x * x - 2.3022082f))); }
; __device__ __forceinline__ float lx_xor(float v, int m, int lane) { return __int_as_float(__builtin_amdgcn_ds_bpermute((lane ^ m) << 2, __float_as_int(v))); }
; __device__ __forceinline__ unsigned cvtpk_h(float lo, float hi) { f32x2 v = {lo, hi}; h16x2 b = __builtin_convertvector(v, h16x2); return __builtin_bit_cast(unsigned, b); }
; __device__ __forceinline__ void gmlp_unit(unsigned char* ws, h16* Y, const h16* Ws16  , const float* bs  , size_t r0, LAS unsigned char* lds, int tid) {
;     ...
;     for (int j = 0; j < 8; ++j) { const int i = tid + 512 * j, row = i >> 5, c8 = i & 31, gg = c8 >> 3, cg = (c8 & 7) * 8;
;         const h16x8 hv = __builtin_bit_cast(h16x8, stg[j]); float x[8]; float sm = 0.f;
; #pragma unroll
;         for (int k = 0; k < 8; ++k) { x[k] = geluf((float)hv[k]); sm += x[k]; }
;         sm += lx_xor(sm, 1, lane); sm += lx_xor(sm, 2, lane); sm += lx_xor(sm, 4, lane);
;         const float mu = sm * (1.f / 64.f); float q = 0.f;
; #pragma unroll
;         for (int k = 0; k < 8; ++k) { x[k] -= mu; q += x[k] * x[k]; }
;         q += lx_xor(q, 1, lane); q += lx_xor(q, 2, lane); q += lx_xor(q, 4, lane);
;         const float rd = __builtin_amdgcn_rsqf(q * (1.f / 64.f) + EPS);
;         u32x4 o; o.x = cvtpk_h(x[0] * rd, x[1] * rd); o.y = cvtpk_h(x[2] * rd, x[3] * rd); o.z = cvtpk_h(x[4] * rd, x[5] * rd); o.w = cvtpk_h(x[6] * rd, x[7] * rd);
;         *(LAS u32x4*)(lds + gg * 16384 + (cg >> 5) * 8192 + row * 64 + (cg & 31) * 2) = o; }
	v_cvt_f32_f16_e32 v186, v148
	v_cvt_f32_f16_sdwa v187, v148 dst_sel:DWORD dst_unused:UNUSED_PAD src0_sel:WORD_1
	s_nop 1
	v_add_f32_dpp v152, v152, v152 quad_perm:[1,0,3,2] row_mask:0xf bank_mask:0xf
	s_nop 0
	s_nop 1
	v_add_f32_dpp v152, v152, v152 quad_perm:[2,3,0,1] row_mask:0xf bank_mask:0xf
	s_nop 0
	s_nop 1
	v_add_f32_dpp v152, v152, v152 row_half_mirror row_mask:0xf bank_mask:0xf
	v_fmamk_f32 v152, v152, 0x3c800000, v229
	v_rsq_f32_e32 v158, v152
	s_nop 0
	v_pk_mul_f32 v[152:153], v[154:155], v[158:159] op_sel_hi:[1,0]
	v_pk_mul_f32 v[154:155], v[184:185], v[158:159] op_sel_hi:[1,0]
	v_cvt_pk_f16_f32 v152, v152, v153
	v_cvt_pk_f16_f32 v153, v154, v155
	v_pk_mul_f32 v[154:155], v[162:163], v[158:159] op_sel_hi:[1,0]
	v_cvt_f32_f16_e32 v162, v149
	v_cvt_f32_f16_sdwa v163, v149 dst_sel:DWORD dst_unused:UNUSED_PAD src0_sel:WORD_1
	v_pk_mul_f32 v[156:157], v[156:157], v[158:159] op_sel_hi:[1,0]
	v_cvt_pk_f16_f32 v154, v154, v155
	v_mul_f32_e32 v181, 0x3dd2d3e8, v162
	v_fma_mix_f32 v181, -v181, v149, s9 op_sel_hi:[0,1,0]
	v_mul_f32_e32 v181, v181, v162
	v_exp_f32_e32 v181, v181
	v_cvt_pk_f16_f32 v155, v156, v157
	ds_write_b128 v179, v[152:155] offset:2048
	v_cvt_f32_f16_e32 v152, v151
	v_add_f32_e32 v181, 1.0, v181
	v_cvt_f32_f16_sdwa v153, v151 dst_sel:DWORD dst_unused:UNUSED_PAD src0_sel:WORD_1
	v_rcp_f32_e32 v182, v181
	v_mul_f32_e32 v181, 0x3dd2d3e8, v163
	v_fma_mix_f32 v149, -v181, v149, s9 op_sel:[0,1,0] op_sel_hi:[0,1,0]
	v_mul_f32_e32 v149, v149, v163
	v_exp_f32_e32 v149, v149
	v_mul_f32_e32 v154, 0x3dd2d3e8, v152
	v_mul_f32_e32 v155, 0x3dd2d3e8, v153
	v_fma_mix_f32 v154, -v154, v151, s9 op_sel_hi:[0,1,0]
	v_fma_mix_f32 v151, -v155, v151, s9 op_sel:[0,1,0] op_sel_hi:[0,1,0]
	v_mul_f32_e32 v151, v151, v153
	v_exp_f32_e32 v151, v151
	v_add_f32_e32 v149, 1.0, v149
	v_cvt_f32_f16_e32 v158, v150
	v_rcp_f32_e32 v183, v149
	v_mul_f32_e32 v149, 0x3dd2d3e8, v186
	v_fma_mix_f32 v149, -v149, v148, s9 op_sel_hi:[0,1,0]
	v_mul_f32_e32 v149, v149, v186
	v_add_f32_e32 v151, 1.0, v151
	v_exp_f32_e32 v149, v149
	v_rcp_f32_e32 v155, v151
	v_mul_f32_e32 v151, 0x3dd2d3e8, v158
	v_fma_mix_f32 v151, -v151, v150, s9 op_sel_hi:[0,1,0]
	v_mul_f32_e32 v151, v151, v158
	v_exp_f32_e32 v151, v151
	v_add_f32_e32 v149, 1.0, v149
	v_cvt_f32_f16_sdwa v159, v150 dst_sel:DWORD dst_unused:UNUSED_PAD src0_sel:WORD_1
	v_rcp_f32_e32 v188, v149
	v_mul_f32_e32 v149, 0x3dd2d3e8, v187
	v_fma_mix_f32 v148, -v149, v148, s9 op_sel:[0,1,0] op_sel_hi:[0,1,0]
	v_mul_f32_e32 v148, v148, v187
	v_add_f32_e32 v151, 1.0, v151
	v_exp_f32_e32 v148, v148
	v_rcp_f32_e32 v160, v151
	v_mul_f32_e32 v151, 0x3dd2d3e8, v159
	v_fma_mix_f32 v150, -v151, v150, s9 op_sel:[0,1,0] op_sel_hi:[0,1,0]
	v_mul_f32_e32 v150, v150, v159
	v_exp_f32_e32 v150, v150
	v_add_f32_e32 v148, 1.0, v148
	v_mul_f32_e32 v154, v154, v152
	v_rcp_f32_e32 v189, v148
	v_exp_f32_e32 v154, v154
	v_add_f32_e32 v150, 1.0, v150
	v_rcp_f32_e32 v161, v150
	v_pk_mul_f32 v[148:149], v[188:189], v[186:187]
	v_add_f32_e32 v154, 1.0, v154
	v_add_f32_e32 v148, 0, v148
	v_rcp_f32_e32 v154, v154
	v_pk_mul_f32 v[184:185], v[182:183], v[162:163]
	v_add_f32_e32 v148, v149, v148
	v_add_f32_e32 v148, v184, v148
	v_pk_mul_f32 v[150:151], v[160:161], v[158:159]
	v_add_f32_e32 v148, v185, v148
	v_add_f32_e32 v148, v150, v148
	v_pk_mul_f32 v[156:157], v[154:155], v[152:153]
	v_add_f32_e32 v148, v151, v148
	v_add_f32_e32 v148, v156, v148
	v_add_f32_e32 v148, v157, v148
	s_nop 0
	s_nop 1
	v_add_f32_dpp v148, v148, v148 quad_perm:[1,0,3,2] row_mask:0xf bank_mask:0xf
	s_nop 0
	s_nop 1
	v_add_f32_dpp v148, v148, v148 quad_perm:[2,3,0,1] row_mask:0xf bank_mask:0xf
	s_nop 0
	s_nop 1
	v_add_f32_dpp v148, v148, v148 row_half_mirror row_mask:0xf bank_mask:0xf
	v_mul_f32_e32 v148, 0x3c800000, v148
	v_pk_fma_f32 v[150:151], v[188:189], v[186:187], v[148:149] op_sel_hi:[1,1,0] neg_lo:[0,0,1] neg_hi:[0,0,1]
	v_pk_fma_f32 v[162:163], v[182:183], v[162:163], v[148:149] op_sel_hi:[1,1,0] neg_lo:[0,0,1] neg_hi:[0,0,1]
	v_pk_mul_f32 v[156:157], v[150:151], v[150:151]
	v_pk_mul_f32 v[182:183], v[162:163], v[162:163]
	v_pk_fma_f32 v[152:153], v[154:155], v[152:153], v[148:149] op_sel_hi:[1,1,0] neg_lo:[0,0,1] neg_hi:[0,0,1]
	v_add_f32_e32 v154, v156, v157
	v_pk_fma_f32 v[158:159], v[160:161], v[158:159], v[148:149] op_sel_hi:[1,1,0] neg_lo:[0,0,1] neg_hi:[0,0,1]
	v_add_f32_e32 v154, v182, v154
	v_pk_mul_f32 v[160:161], v[158:159], v[158:159]
	v_add_f32_e32 v154, v183, v154
	v_add_f32_e32 v154, v160, v154
	v_pk_mul_f32 v[148:149], v[152:153], v[152:153]
	v_add_f32_e32 v154, v161, v154
	v_add_f32_e32 v148, v148, v154
	v_add_f32_e32 v148, v149, v148
	s_nop 0
	s_waitcnt vmcnt(43)
; #define LAS __attribute__((address_space(3)))
; __device__ __forceinline__ float geluf(float x) { return x * __builtin_amdgcn_rcpf(1.f + __builtin_amdgcn_exp2f(x * (-0.10294324f * x * x - 2.3022082f))); }
; __device__ __forceinline__ float lx_xor(float v, int m, int lane) { return __int_as_float(__builtin_amdgcn_ds_bpermute((lane ^ m) << 2, __float_as_int(v))); }
; __device__ __forceinline__ unsigned cvtpk_h(float lo, float hi) { f32x2 v = {lo, hi}; h16x2 b = __builtin_convertvector(v, h16x2); return __builtin_bit_cast(unsigned, b); }
; __device__ __forceinline__ void gmlp_unit(unsigned char* ws, h16* Y, const h16* Ws16  , const float* bs  , size_t r0, LAS unsigned char* lds, int tid) {
;     ...
;     for (int j = 0; j < 8; ++j) { const int i = tid + 512 * j, row = i >> 5, c8 = i & 31, gg = c8 >> 3, cg = (c8 & 7) * 8;
;         const h16x8 hv = __builtin_bit_cast(h16x8, stg[j]); float x[8]; float sm = 0.f;
; #pragma unroll
;         for (int k = 0; k < 8; ++k) { x[k] = geluf((float)hv[k]); sm += x[k]; }
;         sm += lx_xor(sm, 1, lane); sm += lx_xor(sm, 2, lane); sm += lx_xor(sm, 4, lane);
;         const float mu = sm * (1.f / 64.f); float q = 0.f;
; #pragma unroll
;         for (int k = 0; k < 8; ++k) { x[k] -= mu; q += x[k] * x[k]; }
;         q += lx_xor(q, 1, lane); q += lx_xor(q, 2, lane); q += lx_xor(q, 4, lane);
;         const float rd = __builtin_amdgcn_rsqf(q * (1.f / 64.f) + EPS);
;         u32x4 o; o.x = cvtpk_h(x[0] * rd, x[1] * rd); o.y = cvtpk_h(x[2] * rd, x[3] * rd); o.z = cvtpk_h(x[4] * rd, x[5] * rd); o.w = cvtpk_h(x[6] * rd, x[7] * rd);
;         *(LAS u32x4*)(lds + gg * 16384 + (cg >> 5) * 8192 + row * 64 + (cg & 31) * 2) = o; }
	v_cvt_f32_f16_e32 v182, v14
	v_cvt_f32_f16_sdwa v183, v14 dst_sel:DWORD dst_unused:UNUSED_PAD src0_sel:WORD_1
	s_nop 1
	v_add_f32_dpp v148, v148, v148 quad_perm:[1,0,3,2] row_mask:0xf bank_mask:0xf
	s_nop 0
	s_nop 1
	v_add_f32_dpp v148, v148, v148 quad_perm:[2,3,0,1] row_mask:0xf bank_mask:0xf
	s_nop 0
	s_nop 1
	v_add_f32_dpp v148, v148, v148 row_half_mirror row_mask:0xf bank_mask:0xf
	v_fmamk_f32 v148, v148, 0x3c800000, v229
	v_rsq_f32_e32 v154, v148
	s_nop 0
	v_pk_mul_f32 v[148:149], v[150:151], v[154:155] op_sel_hi:[1,0]
	v_pk_mul_f32 v[150:151], v[162:163], v[154:155] op_sel_hi:[1,0]
	v_cvt_pk_f16_f32 v148, v148, v149
	v_cvt_pk_f16_f32 v149, v150, v151
	v_pk_mul_f32 v[150:151], v[158:159], v[154:155] op_sel_hi:[1,0]
	v_cvt_f32_f16_e32 v158, v15
	v_cvt_f32_f16_sdwa v159, v15 dst_sel:DWORD dst_unused:UNUSED_PAD src0_sel:WORD_1
	v_pk_mul_f32 v[152:153], v[152:153], v[154:155] op_sel_hi:[1,0]
	v_cvt_pk_f16_f32 v150, v150, v151
	v_cvt_pk_f16_f32 v151, v152, v153
	ds_write_b128 v179, v[148:151] offset:3072
	v_cvt_f32_f16_e32 v148, v17
	v_cvt_f32_f16_sdwa v149, v17 dst_sel:DWORD dst_unused:UNUSED_PAD src0_sel:WORD_1
	v_mul_f32_e32 v160, 0x3dd2d3e8, v158
	v_mul_f32_e32 v161, 0x3dd2d3e8, v159
	v_fma_mix_f32 v160, -v160, v15, s9 op_sel_hi:[0,1,0]
	v_fma_mix_f32 v15, -v161, v15, s9 op_sel:[0,1,0] op_sel_hi:[0,1,0]
	v_mul_f32_e32 v15, v15, v159
	v_exp_f32_e32 v15, v15
	v_mul_f32_e32 v150, 0x3dd2d3e8, v148
	v_mul_f32_e32 v151, 0x3dd2d3e8, v149
	v_fma_mix_f32 v150, -v150, v17, s9 op_sel_hi:[0,1,0]
	v_fma_mix_f32 v17, -v151, v17, s9 op_sel:[0,1,0] op_sel_hi:[0,1,0]
	v_mul_f32_e32 v17, v17, v149
	v_exp_f32_e32 v17, v17
	v_add_f32_e32 v15, 1.0, v15
	v_cvt_f32_f16_e32 v154, v16
	v_rcp_f32_e32 v161, v15
	v_mul_f32_e32 v15, 0x3dd2d3e8, v182
	v_fma_mix_f32 v15, -v15, v14, s9 op_sel_hi:[0,1,0]
	v_mul_f32_e32 v15, v15, v182
	v_add_f32_e32 v17, 1.0, v17
	v_exp_f32_e32 v15, v15
	v_rcp_f32_e32 v151, v17
	v_mul_f32_e32 v17, 0x3dd2d3e8, v154
	v_fma_mix_f32 v17, -v17, v16, s9 op_sel_hi:[0,1,0]
	v_mul_f32_e32 v17, v17, v154
	v_exp_f32_e32 v17, v17
	v_add_f32_e32 v15, 1.0, v15
	v_cvt_f32_f16_sdwa v155, v16 dst_sel:DWORD dst_unused:UNUSED_PAD src0_sel:WORD_1
	v_rcp_f32_e32 v184, v15
	v_mul_f32_e32 v15, 0x3dd2d3e8, v183
	v_fma_mix_f32 v14, -v15, v14, s9 op_sel:[0,1,0] op_sel_hi:[0,1,0]
	v_mul_f32_e32 v14, v14, v183
	v_add_f32_e32 v17, 1.0, v17
	v_exp_f32_e32 v14, v14
	v_rcp_f32_e32 v156, v17
	v_mul_f32_e32 v17, 0x3dd2d3e8, v155
	v_mul_f32_e32 v160, v160, v158
	v_fma_mix_f32 v16, -v17, v16, s9 op_sel:[0,1,0] op_sel_hi:[0,1,0]
	v_exp_f32_e32 v160, v160
	v_mul_f32_e32 v16, v16, v155
	v_exp_f32_e32 v16, v16
	v_add_f32_e32 v14, 1.0, v14
	v_mul_f32_e32 v150, v150, v148
	v_rcp_f32_e32 v185, v14
	v_exp_f32_e32 v150, v150
	v_add_f32_e32 v160, 1.0, v160
	v_rcp_f32_e32 v160, v160
	v_add_f32_e32 v16, 1.0, v16
	v_rcp_f32_e32 v157, v16
	v_pk_mul_f32 v[14:15], v[184:185], v[182:183]
	v_add_f32_e32 v150, 1.0, v150
	v_add_f32_e32 v14, 0, v14
	v_rcp_f32_e32 v150, v150
	v_pk_mul_f32 v[162:163], v[160:161], v[158:159]
	v_add_f32_e32 v14, v15, v14
	v_add_f32_e32 v14, v162, v14
	v_pk_mul_f32 v[16:17], v[156:157], v[154:155]
	v_add_f32_e32 v14, v163, v14
	v_add_f32_e32 v14, v16, v14
	v_pk_mul_f32 v[152:153], v[150:151], v[148:149]
	v_add_f32_e32 v14, v17, v14
	v_add_f32_e32 v14, v152, v14
	v_add_f32_e32 v14, v153, v14
	s_nop 0
	s_nop 1
	v_add_f32_dpp v14, v14, v14 quad_perm:[1,0,3,2] row_mask:0xf bank_mask:0xf
	s_nop 0
	s_nop 1
	v_add_f32_dpp v14, v14, v14 quad_perm:[2,3,0,1] row_mask:0xf bank_mask:0xf
	s_nop 0
	s_nop 1
	v_add_f32_dpp v14, v14, v14 row_half_mirror row_mask:0xf bank_mask:0xf
	v_mul_f32_e32 v14, 0x3c800000, v14
	v_pk_fma_f32 v[16:17], v[184:185], v[182:183], v[14:15] op_sel_hi:[1,1,0] neg_lo:[0,0,1] neg_hi:[0,0,1]
	v_pk_fma_f32 v[158:159], v[160:161], v[158:159], v[14:15] op_sel_hi:[1,1,0] neg_lo:[0,0,1] neg_hi:[0,0,1]
	v_pk_mul_f32 v[152:153], v[16:17], v[16:17]
	v_pk_mul_f32 v[160:161], v[158:159], v[158:159]
	v_pk_fma_f32 v[148:149], v[150:151], v[148:149], v[14:15] op_sel_hi:[1,1,0] neg_lo:[0,0,1] neg_hi:[0,0,1]
	v_add_f32_e32 v150, v152, v153
	v_pk_fma_f32 v[154:155], v[156:157], v[154:155], v[14:15] op_sel_hi:[1,1,0] neg_lo:[0,0,1] neg_hi:[0,0,1]
	v_add_f32_e32 v150, v160, v150
	v_pk_mul_f32 v[156:157], v[154:155], v[154:155]
	v_add_f32_e32 v150, v161, v150
	v_add_f32_e32 v150, v156, v150
	v_pk_mul_f32 v[14:15], v[148:149], v[148:149]
	v_add_f32_e32 v150, v157, v150
	v_add_f32_e32 v14, v14, v150
	v_add_f32_e32 v14, v15, v14
	s_nop 0
	s_waitcnt vmcnt(42)
; #define LAS __attribute__((address_space(3)))
; __device__ __forceinline__ float geluf(float x) { return x * __builtin_amdgcn_rcpf(1.f + __builtin_amdgcn_exp2f(x * (-0.10294324f * x * x - 2.3022082f))); }
; __device__ __forceinline__ float lx_xor(float v, int m, int lane) { return __int_as_float(__builtin_amdgcn_ds_bpermute((lane ^ m) << 2, __float_as_int(v))); }
; __device__ __forceinline__ unsigned cvtpk_h(float lo, float hi) { f32x2 v = {lo, hi}; h16x2 b = __builtin_convertvector(v, h16x2); return __builtin_bit_cast(unsigned, b); }
; __device__ __forceinline__ void gmlp_unit(unsigned char* ws, h16* Y, const h16* Ws16  , const float* bs  , size_t r0, LAS unsigned char* lds, int tid) {
;     ...
;     for (int j = 0; j < 8; ++j) { const int i = tid + 512 * j, row = i >> 5, c8 = i & 31, gg = c8 >> 3, cg = (c8 & 7) * 8;
;         const h16x8 hv = __builtin_bit_cast(h16x8, stg[j]); float x[8]; float sm = 0.f;
; #pragma unroll
;         for (int k = 0; k < 8; ++k) { x[k] = geluf((float)hv[k]); sm += x[k]; }
;         sm += lx_xor(sm, 1, lane); sm += lx_xor(sm, 2, lane); sm += lx_xor(sm, 4, lane);
;         const float mu = sm * (1.f / 64.f); float q = 0.f;
; #pragma unroll
;         for (int k = 0; k < 8; ++k) { x[k] -= mu; q += x[k] * x[k]; }
;         q += lx_xor(q, 1, lane); q += lx_xor(q, 2, lane); q += lx_xor(q, 4, lane);
;         const float rd = __builtin_amdgcn_rsqf(q * (1.f / 64.f) + EPS);
;         u32x4 o; o.x = cvtpk_h(x[0] * rd, x[1] * rd); o.y = cvtpk_h(x[2] * rd, x[3] * rd); o.z = cvtpk_h(x[4] * rd, x[5] * rd); o.w = cvtpk_h(x[6] * rd, x[7] * rd);
;         *(LAS u32x4*)(lds + gg * 16384 + (cg >> 5) * 8192 + row * 64 + (cg & 31) * 2) = o; }
	v_cvt_f32_f16_e32 v160, v10
	v_cvt_f32_f16_sdwa v161, v10 dst_sel:DWORD dst_unused:UNUSED_PAD src0_sel:WORD_1
	s_nop 1
	v_add_f32_dpp v14, v14, v14 quad_perm:[1,0,3,2] row_mask:0xf bank_mask:0xf
	s_nop 0
	s_nop 1
	v_add_f32_dpp v14, v14, v14 quad_perm:[2,3,0,1] row_mask:0xf bank_mask:0xf
	s_nop 0
	s_nop 1
	v_add_f32_dpp v14, v14, v14 row_half_mirror row_mask:0xf bank_mask:0xf
	v_fmamk_f32 v14, v14, 0x3c800000, v229
	v_rsq_f32_e32 v150, v14
	s_nop 0
	v_pk_mul_f32 v[14:15], v[16:17], v[150:151] op_sel_hi:[1,0]
	v_pk_mul_f32 v[16:17], v[158:159], v[150:151] op_sel_hi:[1,0]
	v_cvt_pk_f16_f32 v14, v14, v15
	v_cvt_pk_f16_f32 v15, v16, v17
	v_pk_mul_f32 v[16:17], v[154:155], v[150:151] op_sel_hi:[1,0]
	v_cvt_f32_f16_e32 v154, v11
	v_cvt_f32_f16_sdwa v155, v11 dst_sel:DWORD dst_unused:UNUSED_PAD src0_sel:WORD_1
	v_pk_mul_f32 v[148:149], v[148:149], v[150:151] op_sel_hi:[1,0]
	v_cvt_pk_f16_f32 v16, v16, v17
	v_cvt_pk_f16_f32 v17, v148, v149
	ds_write_b128 v179, v[14:17] offset:4096
	v_cvt_f32_f16_e32 v14, v13
	v_cvt_f32_f16_sdwa v15, v13 dst_sel:DWORD dst_unused:UNUSED_PAD src0_sel:WORD_1
	v_mul_f32_e32 v156, 0x3dd2d3e8, v154
	v_mul_f32_e32 v157, 0x3dd2d3e8, v155
	v_fma_mix_f32 v156, -v156, v11, s9 op_sel_hi:[0,1,0]
	v_fma_mix_f32 v11, -v157, v11, s9 op_sel:[0,1,0] op_sel_hi:[0,1,0]
	v_mul_f32_e32 v11, v11, v155
	v_exp_f32_e32 v11, v11
	v_mul_f32_e32 v16, 0x3dd2d3e8, v14
	v_mul_f32_e32 v17, 0x3dd2d3e8, v15
	v_fma_mix_f32 v16, -v16, v13, s9 op_sel_hi:[0,1,0]
	v_fma_mix_f32 v13, -v17, v13, s9 op_sel:[0,1,0] op_sel_hi:[0,1,0]
	v_mul_f32_e32 v13, v13, v15
	v_exp_f32_e32 v13, v13
	v_add_f32_e32 v11, 1.0, v11
	v_cvt_f32_f16_e32 v150, v12
	v_rcp_f32_e32 v157, v11
	v_mul_f32_e32 v11, 0x3dd2d3e8, v160
	v_fma_mix_f32 v11, -v11, v10, s9 op_sel_hi:[0,1,0]
	v_mul_f32_e32 v11, v11, v160
	v_add_f32_e32 v13, 1.0, v13
	v_exp_f32_e32 v11, v11
	v_rcp_f32_e32 v17, v13
	v_mul_f32_e32 v13, 0x3dd2d3e8, v150
	v_fma_mix_f32 v13, -v13, v12, s9 op_sel_hi:[0,1,0]
	v_mul_f32_e32 v13, v13, v150
	v_exp_f32_e32 v13, v13
	v_add_f32_e32 v11, 1.0, v11
	v_cvt_f32_f16_sdwa v151, v12 dst_sel:DWORD dst_unused:UNUSED_PAD src0_sel:WORD_1
	v_rcp_f32_e32 v162, v11
	v_mul_f32_e32 v11, 0x3dd2d3e8, v161
	v_fma_mix_f32 v10, -v11, v10, s9 op_sel:[0,1,0] op_sel_hi:[0,1,0]
	v_mul_f32_e32 v10, v10, v161
	v_add_f32_e32 v13, 1.0, v13
	v_exp_f32_e32 v10, v10
	v_rcp_f32_e32 v152, v13
	v_mul_f32_e32 v13, 0x3dd2d3e8, v151
	v_mul_f32_e32 v156, v156, v154
	v_fma_mix_f32 v12, -v13, v12, s9 op_sel:[0,1,0] op_sel_hi:[0,1,0]
	v_exp_f32_e32 v156, v156
	v_mul_f32_e32 v12, v12, v151
	v_exp_f32_e32 v12, v12
	v_add_f32_e32 v10, 1.0, v10
	v_mul_f32_e32 v16, v16, v14
	v_rcp_f32_e32 v163, v10
	v_exp_f32_e32 v16, v16
	v_add_f32_e32 v156, 1.0, v156
	v_rcp_f32_e32 v156, v156
	v_add_f32_e32 v12, 1.0, v12
	v_rcp_f32_e32 v153, v12
	v_pk_mul_f32 v[10:11], v[162:163], v[160:161]
	v_add_f32_e32 v16, 1.0, v16
	v_add_f32_e32 v10, 0, v10
	v_rcp_f32_e32 v16, v16
	v_pk_mul_f32 v[158:159], v[156:157], v[154:155]
	v_add_f32_e32 v10, v11, v10
	v_add_f32_e32 v10, v158, v10
	v_pk_mul_f32 v[12:13], v[152:153], v[150:151]
	v_add_f32_e32 v10, v159, v10
	v_add_f32_e32 v10, v12, v10
	v_pk_mul_f32 v[148:149], v[16:17], v[14:15]
	v_add_f32_e32 v10, v13, v10
	v_add_f32_e32 v10, v148, v10
	v_add_f32_e32 v10, v149, v10
	s_nop 0
	s_nop 1
	v_add_f32_dpp v10, v10, v10 quad_perm:[1,0,3,2] row_mask:0xf bank_mask:0xf
	s_nop 0
	s_nop 1
	v_add_f32_dpp v10, v10, v10 quad_perm:[2,3,0,1] row_mask:0xf bank_mask:0xf
	s_nop 0
	s_nop 1
	v_add_f32_dpp v10, v10, v10 row_half_mirror row_mask:0xf bank_mask:0xf
	v_mul_f32_e32 v10, 0x3c800000, v10
	v_pk_fma_f32 v[12:13], v[162:163], v[160:161], v[10:11] op_sel_hi:[1,1,0] neg_lo:[0,0,1] neg_hi:[0,0,1]
	v_pk_fma_f32 v[154:155], v[156:157], v[154:155], v[10:11] op_sel_hi:[1,1,0] neg_lo:[0,0,1] neg_hi:[0,0,1]
	v_pk_mul_f32 v[148:149], v[12:13], v[12:13]
	v_pk_mul_f32 v[156:157], v[154:155], v[154:155]
	v_pk_fma_f32 v[14:15], v[16:17], v[14:15], v[10:11] op_sel_hi:[1,1,0] neg_lo:[0,0,1] neg_hi:[0,0,1]
	v_add_f32_e32 v16, v148, v149
	v_pk_fma_f32 v[150:151], v[152:153], v[150:151], v[10:11] op_sel_hi:[1,1,0] neg_lo:[0,0,1] neg_hi:[0,0,1]
	v_add_f32_e32 v16, v156, v16
	v_pk_mul_f32 v[152:153], v[150:151], v[150:151]
	v_add_f32_e32 v16, v157, v16
	v_add_f32_e32 v16, v152, v16
	v_pk_mul_f32 v[10:11], v[14:15], v[14:15]
	v_add_f32_e32 v16, v153, v16
	v_add_f32_e32 v10, v10, v16
	v_add_f32_e32 v10, v11, v10
	s_nop 0
	s_waitcnt vmcnt(41)
; #define LAS __attribute__((address_space(3)))
; __device__ __forceinline__ float geluf(float x) { return x * __builtin_amdgcn_rcpf(1.f + __builtin_amdgcn_exp2f(x * (-0.10294324f * x * x - 2.3022082f))); }
; __device__ __forceinline__ float lx_xor(float v, int m, int lane) { return __int_as_float(__builtin_amdgcn_ds_bpermute((lane ^ m) << 2, __float_as_int(v))); }
; __device__ __forceinline__ unsigned cvtpk_h(float lo, float hi) { f32x2 v = {lo, hi}; h16x2 b = __builtin_convertvector(v, h16x2); return __builtin_bit_cast(unsigned, b); }
; __device__ __forceinline__ void gmlp_unit(unsigned char* ws, h16* Y, const h16* Ws16  , const float* bs  , size_t r0, LAS unsigned char* lds, int tid) {
;     ...
;     for (int j = 0; j < 8; ++j) { const int i = tid + 512 * j, row = i >> 5, c8 = i & 31, gg = c8 >> 3, cg = (c8 & 7) * 8;
;         const h16x8 hv = __builtin_bit_cast(h16x8, stg[j]); float x[8]; float sm = 0.f;
; #pragma unroll
;         for (int k = 0; k < 8; ++k) { x[k] = geluf((float)hv[k]); sm += x[k]; }
;         sm += lx_xor(sm, 1, lane); sm += lx_xor(sm, 2, lane); sm += lx_xor(sm, 4, lane);
;         const float mu = sm * (1.f / 64.f); float q = 0.f;
; #pragma unroll
;         for (int k = 0; k < 8; ++k) { x[k] -= mu; q += x[k] * x[k]; }
;         q += lx_xor(q, 1, lane); q += lx_xor(q, 2, lane); q += lx_xor(q, 4, lane);
;         const float rd = __builtin_amdgcn_rsqf(q * (1.f / 64.f) + EPS);
;         u32x4 o; o.x = cvtpk_h(x[0] * rd, x[1] * rd); o.y = cvtpk_h(x[2] * rd, x[3] * rd); o.z = cvtpk_h(x[4] * rd, x[5] * rd); o.w = cvtpk_h(x[6] * rd, x[7] * rd);
;         *(LAS u32x4*)(lds + gg * 16384 + (cg >> 5) * 8192 + row * 64 + (cg & 31) * 2) = o; }
	v_cvt_f32_f16_e32 v156, v6
	v_cvt_f32_f16_sdwa v157, v6 dst_sel:DWORD dst_unused:UNUSED_PAD src0_sel:WORD_1
	s_nop 1
	v_add_f32_dpp v10, v10, v10 quad_perm:[1,0,3,2] row_mask:0xf bank_mask:0xf
	s_nop 0
	s_nop 1
	v_add_f32_dpp v10, v10, v10 quad_perm:[2,3,0,1] row_mask:0xf bank_mask:0xf
	s_nop 0
	s_nop 1
	v_add_f32_dpp v10, v10, v10 row_half_mirror row_mask:0xf bank_mask:0xf
	v_fmamk_f32 v10, v10, 0x3c800000, v229
	v_rsq_f32_e32 v16, v10
	s_nop 0
	v_pk_mul_f32 v[10:11], v[12:13], v[16:17] op_sel_hi:[1,0]
	v_pk_mul_f32 v[12:13], v[154:155], v[16:17] op_sel_hi:[1,0]
	v_cvt_pk_f16_f32 v10, v10, v11
	v_cvt_pk_f16_f32 v11, v12, v13
	v_pk_mul_f32 v[12:13], v[150:151], v[16:17] op_sel_hi:[1,0]
	v_cvt_f32_f16_e32 v150, v7
	v_cvt_f32_f16_sdwa v151, v7 dst_sel:DWORD dst_unused:UNUSED_PAD src0_sel:WORD_1
	v_pk_mul_f32 v[14:15], v[14:15], v[16:17] op_sel_hi:[1,0]
	v_cvt_pk_f16_f32 v12, v12, v13
	v_cvt_pk_f16_f32 v13, v14, v15
	ds_write_b128 v179, v[10:13] offset:5120
	v_cvt_f32_f16_e32 v10, v9
	v_cvt_f32_f16_sdwa v11, v9 dst_sel:DWORD dst_unused:UNUSED_PAD src0_sel:WORD_1
	v_mul_f32_e32 v152, 0x3dd2d3e8, v150
	v_mul_f32_e32 v153, 0x3dd2d3e8, v151
	v_fma_mix_f32 v152, -v152, v7, s9 op_sel_hi:[0,1,0]
	v_fma_mix_f32 v7, -v153, v7, s9 op_sel:[0,1,0] op_sel_hi:[0,1,0]
	v_mul_f32_e32 v7, v7, v151
	v_exp_f32_e32 v7, v7
	v_mul_f32_e32 v12, 0x3dd2d3e8, v10
	v_mul_f32_e32 v13, 0x3dd2d3e8, v11
	v_fma_mix_f32 v12, -v12, v9, s9 op_sel_hi:[0,1,0]
	v_fma_mix_f32 v9, -v13, v9, s9 op_sel:[0,1,0] op_sel_hi:[0,1,0]
	v_mul_f32_e32 v9, v9, v11
	v_exp_f32_e32 v9, v9
	v_add_f32_e32 v7, 1.0, v7
	v_cvt_f32_f16_e32 v16, v8
	v_rcp_f32_e32 v153, v7
	v_mul_f32_e32 v7, 0x3dd2d3e8, v156
	v_fma_mix_f32 v7, -v7, v6, s9 op_sel_hi:[0,1,0]
	v_mul_f32_e32 v7, v7, v156
	v_add_f32_e32 v9, 1.0, v9
	v_exp_f32_e32 v7, v7
	v_rcp_f32_e32 v13, v9
	v_mul_f32_e32 v9, 0x3dd2d3e8, v16
	v_fma_mix_f32 v9, -v9, v8, s9 op_sel_hi:[0,1,0]
	v_mul_f32_e32 v9, v9, v16
	v_exp_f32_e32 v9, v9
	v_add_f32_e32 v7, 1.0, v7
	v_cvt_f32_f16_sdwa v17, v8 dst_sel:DWORD dst_unused:UNUSED_PAD src0_sel:WORD_1
	v_rcp_f32_e32 v158, v7
	v_mul_f32_e32 v7, 0x3dd2d3e8, v157
	v_fma_mix_f32 v6, -v7, v6, s9 op_sel:[0,1,0] op_sel_hi:[0,1,0]
	v_mul_f32_e32 v6, v6, v157
	v_add_f32_e32 v9, 1.0, v9
	v_exp_f32_e32 v6, v6
	v_rcp_f32_e32 v148, v9
	v_mul_f32_e32 v9, 0x3dd2d3e8, v17
	v_mul_f32_e32 v152, v152, v150
	v_fma_mix_f32 v8, -v9, v8, s9 op_sel:[0,1,0] op_sel_hi:[0,1,0]
	v_exp_f32_e32 v152, v152
	v_mul_f32_e32 v8, v8, v17
	v_exp_f32_e32 v8, v8
	v_add_f32_e32 v6, 1.0, v6
	v_mul_f32_e32 v12, v12, v10
	v_rcp_f32_e32 v159, v6
	v_exp_f32_e32 v12, v12
	v_add_f32_e32 v152, 1.0, v152
	v_rcp_f32_e32 v152, v152
	v_add_f32_e32 v8, 1.0, v8
	v_rcp_f32_e32 v149, v8
	v_pk_mul_f32 v[6:7], v[158:159], v[156:157]
	v_add_f32_e32 v12, 1.0, v12
	v_add_f32_e32 v6, 0, v6
	v_rcp_f32_e32 v12, v12
	v_pk_mul_f32 v[154:155], v[152:153], v[150:151]
	v_add_f32_e32 v6, v7, v6
	v_add_f32_e32 v6, v154, v6
	v_pk_mul_f32 v[8:9], v[148:149], v[16:17]
	v_add_f32_e32 v6, v155, v6
	v_add_f32_e32 v6, v8, v6
	v_pk_mul_f32 v[14:15], v[12:13], v[10:11]
	v_add_f32_e32 v6, v9, v6
	v_add_f32_e32 v6, v14, v6
	v_add_f32_e32 v6, v15, v6
	s_nop 0
	s_nop 1
	v_add_f32_dpp v6, v6, v6 quad_perm:[1,0,3,2] row_mask:0xf bank_mask:0xf
	s_nop 0
	s_nop 1
	v_add_f32_dpp v6, v6, v6 quad_perm:[2,3,0,1] row_mask:0xf bank_mask:0xf
	s_nop 0
	s_nop 1
	v_add_f32_dpp v6, v6, v6 row_half_mirror row_mask:0xf bank_mask:0xf
	v_mul_f32_e32 v6, 0x3c800000, v6
	v_pk_fma_f32 v[8:9], v[158:159], v[156:157], v[6:7] op_sel_hi:[1,1,0] neg_lo:[0,0,1] neg_hi:[0,0,1]
	v_pk_fma_f32 v[150:151], v[152:153], v[150:151], v[6:7] op_sel_hi:[1,1,0] neg_lo:[0,0,1] neg_hi:[0,0,1]
	v_pk_mul_f32 v[14:15], v[8:9], v[8:9]
	v_pk_mul_f32 v[152:153], v[150:151], v[150:151]
	v_pk_fma_f32 v[10:11], v[12:13], v[10:11], v[6:7] op_sel_hi:[1,1,0] neg_lo:[0,0,1] neg_hi:[0,0,1]
	v_add_f32_e32 v12, v14, v15
	v_pk_fma_f32 v[16:17], v[148:149], v[16:17], v[6:7] op_sel_hi:[1,1,0] neg_lo:[0,0,1] neg_hi:[0,0,1]
	v_add_f32_e32 v12, v152, v12
	v_pk_mul_f32 v[148:149], v[16:17], v[16:17]
	v_add_f32_e32 v12, v153, v12
	v_add_f32_e32 v12, v148, v12
	v_pk_mul_f32 v[6:7], v[10:11], v[10:11]
	v_add_f32_e32 v12, v149, v12
	v_add_f32_e32 v6, v6, v12
	v_add_f32_e32 v6, v7, v6
	s_nop 0
	s_waitcnt vmcnt(40)
; #define LAS __attribute__((address_space(3)))
; __device__ __forceinline__ float geluf(float x) { return x * __builtin_amdgcn_rcpf(1.f + __builtin_amdgcn_exp2f(x * (-0.10294324f * x * x - 2.3022082f))); }
; __device__ __forceinline__ float lx_xor(float v, int m, int lane) { return __int_as_float(__builtin_amdgcn_ds_bpermute((lane ^ m) << 2, __float_as_int(v))); }
; __device__ __forceinline__ unsigned cvtpk_h(float lo, float hi) { f32x2 v = {lo, hi}; h16x2 b = __builtin_convertvector(v, h16x2); return __builtin_bit_cast(unsigned, b); }
; #define BAR_LDS() asm volatile("s_waitcnt lgkmcnt(0)\n\ts_barrier" ::: "memory")
; __device__ __forceinline__ void gmlp_unit(unsigned char* ws, h16* Y, const h16* Ws16  , const float* bs  , size_t r0, LAS unsigned char* lds, int tid) {
;     ...
;     for (int j = 0; j < 8; ++j) { const int i = tid + 512 * j, row = i >> 5, c8 = i & 31, gg = c8 >> 3, cg = (c8 & 7) * 8;
;         const h16x8 hv = __builtin_bit_cast(h16x8, stg[j]); float x[8]; float sm = 0.f;
; #pragma unroll
;         for (int k = 0; k < 8; ++k) { x[k] = geluf((float)hv[k]); sm += x[k]; }
;         sm += lx_xor(sm, 1, lane); sm += lx_xor(sm, 2, lane); sm += lx_xor(sm, 4, lane);
;         const float mu = sm * (1.f / 64.f); float q = 0.f;
; #pragma unroll
;         for (int k = 0; k < 8; ++k) { x[k] -= mu; q += x[k] * x[k]; }
;         q += lx_xor(q, 1, lane); q += lx_xor(q, 2, lane); q += lx_xor(q, 4, lane);
;         const float rd = __builtin_amdgcn_rsqf(q * (1.f / 64.f) + EPS);
;         u32x4 o; o.x = cvtpk_h(x[0] * rd, x[1] * rd); o.y = cvtpk_h(x[2] * rd, x[3] * rd); o.z = cvtpk_h(x[4] * rd, x[5] * rd); o.w = cvtpk_h(x[6] * rd, x[7] * rd);
;         *(LAS u32x4*)(lds + gg * 16384 + (cg >> 5) * 8192 + row * 64 + (cg & 31) * 2) = o; }
;     BAR_LDS();
	v_cvt_f32_f16_e32 v152, v2
	v_cvt_f32_f16_sdwa v153, v2 dst_sel:DWORD dst_unused:UNUSED_PAD src0_sel:WORD_1
	s_nop 1
	v_add_f32_dpp v6, v6, v6 quad_perm:[1,0,3,2] row_mask:0xf bank_mask:0xf
	s_nop 0
	s_nop 1
	v_add_f32_dpp v6, v6, v6 quad_perm:[2,3,0,1] row_mask:0xf bank_mask:0xf
	s_nop 0
	s_nop 1
	v_add_f32_dpp v6, v6, v6 row_half_mirror row_mask:0xf bank_mask:0xf
	v_fmamk_f32 v6, v6, 0x3c800000, v229
	v_rsq_f32_e32 v12, v6
	s_nop 0
	v_pk_mul_f32 v[6:7], v[8:9], v[12:13] op_sel_hi:[1,0]
	v_pk_mul_f32 v[8:9], v[150:151], v[12:13] op_sel_hi:[1,0]
	v_cvt_pk_f16_f32 v6, v6, v7
	v_cvt_pk_f16_f32 v7, v8, v9
	v_pk_mul_f32 v[8:9], v[16:17], v[12:13] op_sel_hi:[1,0]
	v_cvt_f32_f16_e32 v16, v3
	v_cvt_f32_f16_sdwa v17, v3 dst_sel:DWORD dst_unused:UNUSED_PAD src0_sel:WORD_1
	v_pk_mul_f32 v[10:11], v[10:11], v[12:13] op_sel_hi:[1,0]
	v_cvt_pk_f16_f32 v8, v8, v9
	v_cvt_pk_f16_f32 v9, v10, v11
	ds_write_b128 v179, v[6:9] offset:6144
	v_cvt_f32_f16_e32 v6, v5
	v_cvt_f32_f16_sdwa v7, v5 dst_sel:DWORD dst_unused:UNUSED_PAD src0_sel:WORD_1
	v_mul_f32_e32 v148, 0x3dd2d3e8, v16
	v_mul_f32_e32 v149, 0x3dd2d3e8, v17
	v_fma_mix_f32 v148, -v148, v3, s9 op_sel_hi:[0,1,0]
	v_fma_mix_f32 v3, -v149, v3, s9 op_sel:[0,1,0] op_sel_hi:[0,1,0]
	v_mul_f32_e32 v3, v3, v17
	v_exp_f32_e32 v3, v3
	v_mul_f32_e32 v8, 0x3dd2d3e8, v6
	v_mul_f32_e32 v9, 0x3dd2d3e8, v7
	v_fma_mix_f32 v8, -v8, v5, s9 op_sel_hi:[0,1,0]
	v_fma_mix_f32 v5, -v9, v5, s9 op_sel:[0,1,0] op_sel_hi:[0,1,0]
	v_mul_f32_e32 v5, v5, v7
	v_exp_f32_e32 v5, v5
	v_add_f32_e32 v3, 1.0, v3
	v_cvt_f32_f16_e32 v12, v4
	v_rcp_f32_e32 v149, v3
	v_mul_f32_e32 v3, 0x3dd2d3e8, v152
	v_fma_mix_f32 v3, -v3, v2, s9 op_sel_hi:[0,1,0]
	v_mul_f32_e32 v3, v3, v152
	v_add_f32_e32 v5, 1.0, v5
	v_exp_f32_e32 v3, v3
	v_rcp_f32_e32 v9, v5
	v_mul_f32_e32 v5, 0x3dd2d3e8, v12
	v_fma_mix_f32 v5, -v5, v4, s9 op_sel_hi:[0,1,0]
	v_mul_f32_e32 v5, v5, v12
	v_exp_f32_e32 v5, v5
	v_add_f32_e32 v3, 1.0, v3
	v_cvt_f32_f16_sdwa v13, v4 dst_sel:DWORD dst_unused:UNUSED_PAD src0_sel:WORD_1
	v_rcp_f32_e32 v154, v3
	v_mul_f32_e32 v3, 0x3dd2d3e8, v153
	v_fma_mix_f32 v2, -v3, v2, s9 op_sel:[0,1,0] op_sel_hi:[0,1,0]
	v_mul_f32_e32 v2, v2, v153
	v_add_f32_e32 v5, 1.0, v5
	v_exp_f32_e32 v2, v2
	v_rcp_f32_e32 v14, v5
	v_mul_f32_e32 v5, 0x3dd2d3e8, v13
	v_mul_f32_e32 v148, v148, v16
	v_fma_mix_f32 v4, -v5, v4, s9 op_sel:[0,1,0] op_sel_hi:[0,1,0]
	v_exp_f32_e32 v148, v148
	v_mul_f32_e32 v4, v4, v13
	v_exp_f32_e32 v4, v4
	v_add_f32_e32 v2, 1.0, v2
	v_mul_f32_e32 v8, v8, v6
	v_rcp_f32_e32 v155, v2
	v_exp_f32_e32 v8, v8
	v_add_f32_e32 v148, 1.0, v148
	v_rcp_f32_e32 v148, v148
	v_add_f32_e32 v4, 1.0, v4
	v_rcp_f32_e32 v15, v4
	v_pk_mul_f32 v[2:3], v[154:155], v[152:153]
	v_add_f32_e32 v8, 1.0, v8
	v_add_f32_e32 v2, 0, v2
	v_rcp_f32_e32 v8, v8
	v_pk_mul_f32 v[150:151], v[148:149], v[16:17]
	v_add_f32_e32 v2, v3, v2
	v_add_f32_e32 v2, v150, v2
	v_pk_mul_f32 v[4:5], v[14:15], v[12:13]
	v_add_f32_e32 v2, v151, v2
	v_add_f32_e32 v2, v4, v2
	v_pk_mul_f32 v[10:11], v[8:9], v[6:7]
	v_add_f32_e32 v2, v5, v2
	v_add_f32_e32 v2, v10, v2
	v_add_f32_e32 v2, v11, v2
	s_nop 0
	v_lshlrev_b32_e32 v150, 1, v169
	s_nop 1
	v_add_f32_dpp v2, v2, v2 quad_perm:[1,0,3,2] row_mask:0xf bank_mask:0xf
	s_nop 0
	s_nop 1
	v_add_f32_dpp v2, v2, v2 quad_perm:[2,3,0,1] row_mask:0xf bank_mask:0xf
	s_nop 0
	s_nop 1
	v_add_f32_dpp v2, v2, v2 row_half_mirror row_mask:0xf bank_mask:0xf
	v_mul_f32_e32 v2, 0x3c800000, v2
	v_pk_fma_f32 v[4:5], v[154:155], v[152:153], v[2:3] op_sel_hi:[1,1,0] neg_lo:[0,0,1] neg_hi:[0,0,1]
	v_pk_fma_f32 v[16:17], v[148:149], v[16:17], v[2:3] op_sel_hi:[1,1,0] neg_lo:[0,0,1] neg_hi:[0,0,1]
	v_pk_mul_f32 v[10:11], v[4:5], v[4:5]
	v_pk_mul_f32 v[148:149], v[16:17], v[16:17]
	v_pk_fma_f32 v[6:7], v[8:9], v[6:7], v[2:3] op_sel_hi:[1,1,0] neg_lo:[0,0,1] neg_hi:[0,0,1]
	v_add_f32_e32 v8, v10, v11
	v_pk_fma_f32 v[12:13], v[14:15], v[12:13], v[2:3] op_sel_hi:[1,1,0] neg_lo:[0,0,1] neg_hi:[0,0,1]
	v_add_f32_e32 v8, v148, v8
	v_pk_mul_f32 v[14:15], v[12:13], v[12:13]
	v_add_f32_e32 v8, v149, v8
	v_add_f32_e32 v8, v14, v8
	v_pk_mul_f32 v[2:3], v[6:7], v[6:7]
	v_add_f32_e32 v8, v15, v8
	v_add_f32_e32 v2, v2, v8
	v_add_f32_e32 v2, v3, v2
	s_nop 0
	v_lshl_add_u64 v[148:149], s[6:7], 0, v[0:1]
	s_nop 1
	v_add_f32_dpp v2, v2, v2 quad_perm:[1,0,3,2] row_mask:0xf bank_mask:0xf
	s_nop 0
	s_nop 1
	v_add_f32_dpp v2, v2, v2 quad_perm:[2,3,0,1] row_mask:0xf bank_mask:0xf
	s_nop 0
	s_nop 1
	v_add_f32_dpp v2, v2, v2 row_half_mirror row_mask:0xf bank_mask:0xf
	v_fmamk_f32 v2, v2, 0x3c800000, v229
	v_rsq_f32_e32 v8, v2
	s_nop 0
	v_pk_mul_f32 v[2:3], v[4:5], v[8:9] op_sel_hi:[1,0]
	v_pk_mul_f32 v[4:5], v[16:17], v[8:9] op_sel_hi:[1,0]
	v_cvt_pk_f16_f32 v2, v2, v3
	v_cvt_pk_f16_f32 v3, v4, v5
	v_pk_mul_f32 v[4:5], v[12:13], v[8:9] op_sel_hi:[1,0]
	v_pk_mul_f32 v[6:7], v[6:7], v[8:9] op_sel_hi:[1,0]
	v_cvt_pk_f16_f32 v4, v4, v5
	v_cvt_pk_f16_f32 v5, v6, v7
	ds_write_b128 v179, v[2:5] offset:7168
	v_and_b32_e32 v3, 16, v247
	v_and_or_b32 v3, v164, 12, v3
	v_and_b32_e32 v2, 0x2c0, v171
	v_lshlrev_b32_e32 v3, 1, v3
	s_waitcnt lgkmcnt(0)
	s_barrier
; #define LAS __attribute__((address_space(3)))
; __device__ __forceinline__ float siluf(float x) { return x * __builtin_amdgcn_rcpf(1.f + __builtin_amdgcn_exp2f(-1.4426950408889634f * x)); }
; __device__ __forceinline__ float geluf(float x) { return x * __builtin_amdgcn_rcpf(1.f + __builtin_amdgcn_exp2f(x * (-0.10294324f * x * x - 2.3022082f))); }
; #define LDS_WAIT() asm volatile("s_waitcnt lgkmcnt(0)" ::: "memory")
; __device__ __forceinline__ int crow(int r, int hi) { return (r & 3) + 8 * (r >> 2) + 4 * hi; }
; __device__ __forceinline__ void gmlp_unit(unsigned char* ws, h16* Y, const h16* Ws16  , const float* bs  , size_t r0, LAS unsigned char* lds, int tid) {
;     ...
;     LAS h16* scr = (LAS h16*)(lds + GM_SCR) + wid * (32 * 72);
; #pragma unroll
;     for (int q = 0; q < 2; ++q) {
; #pragma unroll
;         for (int db = 0; db < 2; ++db) {
;             s16x8 bf[8];
; #pragma unroll
;             for (int ks = 0; ks < 8; ++ks) bf[ks] = tr_frag((LAS const char*)lds + g * 16384, 8192, db, ks, lane);
;             f32x16 acc = f32x16{};
; #pragma unroll
;             for (int ks = 0; ks < 8; ++ks) acc = __builtin_amdgcn_mfma_f32_32x32x16_f16(H8(af[q][ks]), H8(bf[ks]), acc, 0, 0, 0);
; #pragma unroll
;             for (int r = 0; r < 16; ++r) scr[crow(r, hi) * 72 + 32 * db + r32] = (h16)acc[r];
;         }
;         LDS_WAIT();
; #pragma unroll
;         for (int ps = 0; ps < 4; ++ps) { const int row = 8 * ps + erow;
;             const h16x8 sv = *(const LAS h16x8*)(scr + row * 72 + 8 * ech);
;             float y[8];
; #pragma unroll
;             for (int k = 0; k < 8; ++k) y[k] = geluf((float)gu[q][ps][k]) * ((float)sv[k] + bias[q][ps]) * siluf((float)sz[q][ps][k]);
	v_add3_u32 v151, s4, v2, v3
	ds_read_b64_tr_b16 v[2:3], v151
	ds_read_b64_tr_b16 v[4:5], v151 offset:256
	ds_read_b64_tr_b16 v[152:153], v151 offset:1024
	ds_read_b64_tr_b16 v[154:155], v151 offset:1280
	ds_read_b64_tr_b16 v[156:157], v151 offset:2048
	ds_read_b64_tr_b16 v[158:159], v151 offset:2304
	ds_read_b64_tr_b16 v[160:161], v151 offset:3072
	ds_read_b64_tr_b16 v[162:163], v151 offset:3328
	ds_read_b64_tr_b16 v[182:183], v151 offset:4096
	ds_read_b64_tr_b16 v[184:185], v151 offset:4352
	ds_read_b64_tr_b16 v[186:187], v151 offset:5120
	ds_read_b64_tr_b16 v[188:189], v151 offset:5376
	ds_read_b64_tr_b16 v[190:191], v151 offset:6144
	ds_read_b64_tr_b16 v[192:193], v151 offset:6400
	ds_read_b64_tr_b16 v[194:195], v151 offset:7168
	ds_read_b64_tr_b16 v[196:197], v151 offset:7424
	s_waitcnt vmcnt(39) lgkmcnt(14)
	v_mfma_f32_32x32x16_f16 v[2:17], v[140:143], v[2:5], 0
	s_or_b32 s4, s2, s5
	v_or_b32_e32 v164, s4, v167
	s_or_b32 s2, s2, s3
	s_waitcnt vmcnt(38) lgkmcnt(12)
	v_mfma_f32_32x32x16_f16 v[2:17], v[144:147], v[152:155], v[2:17]
	v_mul_u32_u24_e32 v152, 0x240, v248
	v_add3_u32 v150, s8, v150, v152
	s_waitcnt vmcnt(37) lgkmcnt(10)
	v_mfma_f32_32x32x16_f16 v[2:17], v[136:139], v[156:159], v[2:17]
	s_waitcnt vmcnt(36) lgkmcnt(8)
	v_mfma_f32_32x32x16_f16 v[2:17], v[132:135], v[160:163], v[2:17]
	s_waitcnt vmcnt(35) lgkmcnt(6)
	v_mfma_f32_32x32x16_f16 v[2:17], v[126:129], v[182:185], v[2:17]
	s_waitcnt vmcnt(34) lgkmcnt(4)
	v_mfma_f32_32x32x16_f16 v[2:17], v[122:125], v[186:189], v[2:17]
	s_waitcnt vmcnt(33) lgkmcnt(2)
	v_mfma_f32_32x32x16_f16 v[2:17], v[118:121], v[190:193], v[2:17]
	s_waitcnt vmcnt(32) lgkmcnt(0)
	v_mfma_f32_32x32x16_f16 v[2:17], v[114:117], v[194:197], v[2:17]
	s_nop 11
	v_cvt_f16_f32_e32 v2, v2
	ds_write_b16 v150, v2
	v_cvt_f16_f32_e32 v2, v3
	ds_write_b16 v150, v2 offset:144
	v_cvt_f16_f32_e32 v2, v4
	ds_write_b16 v150, v2 offset:288
	v_cvt_f16_f32_e32 v2, v5
	ds_write_b16 v150, v2 offset:432
	v_cvt_f16_f32_e32 v2, v6
	ds_write_b16 v150, v2 offset:1152
	v_cvt_f16_f32_e32 v2, v7
	ds_write_b16 v150, v2 offset:1296
	v_cvt_f16_f32_e32 v2, v8
	ds_write_b16 v150, v2 offset:1440
	v_cvt_f16_f32_e32 v2, v9
	ds_write_b16 v150, v2 offset:1584
	v_cvt_f16_f32_e32 v2, v10
	ds_write_b16 v150, v2 offset:2304
	v_cvt_f16_f32_e32 v2, v11
	ds_write_b16 v150, v2 offset:2448
	v_cvt_f16_f32_e32 v2, v12
	ds_write_b16 v150, v2 offset:2592
	v_cvt_f16_f32_e32 v2, v13
	ds_write_b16 v150, v2 offset:2736
	v_cvt_f16_f32_e32 v2, v14
	ds_write_b16 v150, v2 offset:3456
	v_cvt_f16_f32_e32 v2, v15
	ds_write_b16 v150, v2 offset:3600
	v_cvt_f16_f32_e32 v2, v16
	ds_write_b16 v150, v2 offset:3744
	v_cvt_f16_f32_e32 v2, v17
	ds_write_b16 v150, v2 offset:3888
	ds_read_b64_tr_b16 v[2:3], v151 offset:8192
	ds_read_b64_tr_b16 v[4:5], v151 offset:8448
	ds_read_b64_tr_b16 v[152:153], v151 offset:9216
	ds_read_b64_tr_b16 v[154:155], v151 offset:9472
	ds_read_b64_tr_b16 v[156:157], v151 offset:10240
	ds_read_b64_tr_b16 v[158:159], v151 offset:10496
	ds_read_b64_tr_b16 v[160:161], v151 offset:11264
	ds_read_b64_tr_b16 v[162:163], v151 offset:11520
	ds_read_b64_tr_b16 v[182:183], v151 offset:12288
	ds_read_b64_tr_b16 v[184:185], v151 offset:12544
	ds_read_b64_tr_b16 v[186:187], v151 offset:13312
	ds_read_b64_tr_b16 v[188:189], v151 offset:13568
	ds_read_b64_tr_b16 v[190:191], v151 offset:14336
	ds_read_b64_tr_b16 v[192:193], v151 offset:14592
	ds_read_b64_tr_b16 v[194:195], v151 offset:15360
	ds_read_b64_tr_b16 v[196:197], v151 offset:15616
	s_waitcnt lgkmcnt(14)
	v_mfma_f32_32x32x16_f16 v[2:17], v[140:143], v[2:5], 0
	s_waitcnt lgkmcnt(12)
	v_mfma_f32_32x32x16_f16 v[2:17], v[144:147], v[152:155], v[2:17]
	s_waitcnt lgkmcnt(10)
	v_mfma_f32_32x32x16_f16 v[2:17], v[136:139], v[156:159], v[2:17]
	s_waitcnt lgkmcnt(8)
	v_mfma_f32_32x32x16_f16 v[2:17], v[132:135], v[160:163], v[2:17]
	s_waitcnt lgkmcnt(6)
	v_mfma_f32_32x32x16_f16 v[2:17], v[126:129], v[182:185], v[2:17]
	s_waitcnt lgkmcnt(4)
	v_mfma_f32_32x32x16_f16 v[2:17], v[122:125], v[186:189], v[2:17]
	s_waitcnt lgkmcnt(2)
	v_mfma_f32_32x32x16_f16 v[2:17], v[118:121], v[190:193], v[2:17]
	s_waitcnt lgkmcnt(0)
	v_mfma_f32_32x32x16_f16 v[2:17], v[114:117], v[194:197], v[2:17]
	s_nop 11
	v_cvt_f16_f32_e32 v2, v2
	ds_write_b16 v150, v2 offset:64
	v_cvt_f16_f32_e32 v2, v3
	ds_write_b16 v150, v2 offset:208
	v_cvt_f16_f32_e32 v2, v4
	ds_write_b16 v150, v2 offset:352
	v_cvt_f16_f32_e32 v2, v5
	ds_write_b16 v150, v2 offset:496
	v_cvt_f16_f32_e32 v2, v6
	s_waitcnt vmcnt(23)
	v_cvt_f32_f16_e32 v6, v106
	ds_write_b16 v150, v2 offset:1216
	v_cvt_f16_f32_e32 v2, v7
	v_cvt_f32_f16_sdwa v7, v106 dst_sel:DWORD dst_unused:UNUSED_PAD src0_sel:WORD_1
	ds_write_b16 v150, v2 offset:1360
	v_cvt_f16_f32_e32 v2, v8
	v_mul_f32_e32 v8, 0x3dd2d3e8, v6
	v_fma_mix_f32 v8, -v8, v106, s9 op_sel_hi:[0,1,0]
	v_mul_f32_e32 v8, v8, v6
	ds_write_b16 v150, v2 offset:1504
	v_cvt_f16_f32_e32 v2, v9
	v_exp_f32_e32 v8, v8
	ds_write_b16 v150, v2 offset:1648
	v_cvt_f16_f32_e32 v2, v10
	s_waitcnt vmcnt(21)
	v_cvt_f32_f16_e32 v10, v110
	v_add_f32_e32 v8, 1.0, v8
	v_rcp_f32_e32 v8, v8
	ds_write_b16 v150, v2 offset:2368
	v_cvt_f16_f32_e32 v2, v11
	v_mul_f32_e32 v9, 0xbfb8aa3b, v10
	v_exp_f32_e32 v9, v9
	v_cvt_f32_f16_sdwa v11, v110 dst_sel:DWORD dst_unused:UNUSED_PAD src0_sel:WORD_1
	ds_write_b16 v150, v2 offset:2512
	v_cvt_f16_f32_e32 v2, v12
	v_add_f32_e32 v9, 1.0, v9
	v_rcp_f32_e32 v12, v9
	v_mul_f32_e32 v9, 0x3dd2d3e8, v7
	ds_write_b16 v150, v2 offset:2656
	v_cvt_f16_f32_e32 v2, v13
	v_fma_mix_f32 v9, -v9, v106, s9 op_sel:[0,1,0] op_sel_hi:[0,1,0]
	v_mul_f32_e32 v9, v9, v7
	v_exp_f32_e32 v9, v9
	ds_write_b16 v150, v2 offset:2800
	v_cvt_f16_f32_e32 v2, v14
	v_or_b32_e32 v106, 8, v167
	v_add_f32_e32 v9, 1.0, v9
	v_rcp_f32_e32 v9, v9
	ds_write_b16 v150, v2 offset:3520
	v_cvt_f16_f32_e32 v2, v15
	v_pk_mul_f32 v[6:7], v[8:9], v[6:7]
	ds_write_b16 v150, v2 offset:3664
	v_cvt_f16_f32_e32 v2, v16
	ds_write_b16 v150, v2 offset:3808
	v_cvt_f16_f32_e32 v2, v17
	ds_write_b16 v150, v2 offset:3952
	v_mul_u32_u24_e32 v2, 0x90, v167
	s_waitcnt lgkmcnt(0)
; #define LAS __attribute__((address_space(3)))
; #define GAS __attribute__((address_space(1)))
; __device__ __forceinline__ float siluf(float x) { return x * __builtin_amdgcn_rcpf(1.f + __builtin_amdgcn_exp2f(-1.4426950408889634f * x)); }
; __device__ __forceinline__ float geluf(float x) { return x * __builtin_amdgcn_rcpf(1.f + __builtin_amdgcn_exp2f(x * (-0.10294324f * x * x - 2.3022082f))); }
; __device__ __forceinline__ unsigned cvtpk_h(float lo, float hi) { f32x2 v = {lo, hi}; h16x2 b = __builtin_convertvector(v, h16x2); return __builtin_bit_cast(unsigned, b); }
; __device__ __forceinline__ void gmlp_unit(unsigned char* ws, h16* Y, const h16* Ws16  , const float* bs  , size_t r0, LAS unsigned char* lds, int tid) {
;     ...
; #pragma unroll
;         for (int ps = 0; ps < 4; ++ps) { const int row = 8 * ps + erow;
;             const h16x8 sv = *(const LAS h16x8*)(scr + row * 72 + 8 * ech);
;             float y[8];
; #pragma unroll
;             for (int k = 0; k < 8; ++k) y[k] = geluf((float)gu[q][ps][k]) * ((float)sv[k] + bias[q][ps]) * siluf((float)sz[q][ps][k]);
;             u32x4 w0; w0.x = cvtpk_h(y[0], y[1]); w0.y = cvtpk_h(y[2], y[3]); w0.z = cvtpk_h(y[4], y[5]); w0.w = cvtpk_h(y[6], y[7]);
;             *(GAS u32x4*)(Y + (r0 + 32 * (2 * ph + q) + row) * D + g * 64 + 8 * ech) = w0; }
	v_add3_u32 v0, s8, v0, v2
	ds_read_b128 v[2:5], v0
	s_waitcnt lgkmcnt(0)
	v_cvt_f32_f16_e32 v8, v2
	v_cvt_f32_f16_sdwa v9, v2 dst_sel:DWORD dst_unused:UNUSED_PAD src0_sel:WORD_1
	v_mul_f32_e32 v2, 0xbfb8aa3b, v11
	v_exp_f32_e32 v2, v2
	v_pk_add_f32 v[8:9], v[180:181], v[8:9] op_sel_hi:[0,1]
	v_pk_mul_f32 v[6:7], v[6:7], v[8:9]
	v_add_f32_e32 v2, 1.0, v2
	v_rcp_f32_e32 v13, v2
	s_nop 0
	v_pk_mul_f32 v[8:9], v[12:13], v[10:11]
	s_nop 0
	v_pk_mul_f32 v[6:7], v[8:9], v[6:7]
	v_cvt_f32_f16_e32 v8, v107
	v_cvt_f32_f16_sdwa v9, v107 dst_sel:DWORD dst_unused:UNUSED_PAD src0_sel:WORD_1
	v_cvt_f32_f16_e32 v12, v111
	v_cvt_f32_f16_sdwa v13, v111 dst_sel:DWORD dst_unused:UNUSED_PAD src0_sel:WORD_1
	v_mul_f32_e32 v2, 0x3dd2d3e8, v8
	v_mul_f32_e32 v11, 0x3dd2d3e8, v9
	v_fma_mix_f32 v2, -v2, v107, s9 op_sel_hi:[0,1,0]
	v_fma_mix_f32 v11, -v11, v107, s9 op_sel:[0,1,0] op_sel_hi:[0,1,0]
	v_mul_f32_e32 v2, v2, v8
	v_mul_f32_e32 v11, v11, v9
	v_exp_f32_e32 v2, v2
	v_exp_f32_e32 v11, v11
	v_add_f32_e32 v2, 1.0, v2
	v_add_f32_e32 v11, 1.0, v11
	v_rcp_f32_e32 v10, v2
	v_rcp_f32_e32 v11, v11
	v_mul_f32_e32 v2, 0xbfb8aa3b, v12
	v_exp_f32_e32 v2, v2
	v_pk_mul_f32 v[8:9], v[10:11], v[8:9]
	v_cvt_f32_f16_e32 v10, v3
	v_cvt_f32_f16_sdwa v11, v3 dst_sel:DWORD dst_unused:UNUSED_PAD src0_sel:WORD_1
	v_mul_f32_e32 v3, 0xbfb8aa3b, v13
	v_exp_f32_e32 v3, v3
	v_add_f32_e32 v2, 1.0, v2
	v_rcp_f32_e32 v2, v2
	v_pk_add_f32 v[10:11], v[180:181], v[10:11] op_sel_hi:[0,1]
	v_add_f32_e32 v3, 1.0, v3
	v_rcp_f32_e32 v3, v3
	v_pk_mul_f32 v[8:9], v[8:9], v[10:11]
	v_pk_mul_f32 v[2:3], v[2:3], v[12:13]
	v_cvt_f32_f16_e32 v12, v112
	v_pk_mul_f32 v[8:9], v[2:3], v[8:9]
	v_cvt_f32_f16_e32 v2, v108
	v_cvt_f32_f16_sdwa v3, v108 dst_sel:DWORD dst_unused:UNUSED_PAD src0_sel:WORD_1
	v_mul_f32_e32 v11, 0xbfb8aa3b, v12
	v_exp_f32_e32 v11, v11
	v_mul_f32_e32 v10, 0x3dd2d3e8, v2
	v_fma_mix_f32 v10, -v10, v108, s9 op_sel_hi:[0,1,0]
	v_mul_f32_e32 v10, v10, v2
	v_add_f32_e32 v11, 1.0, v11
	v_rcp_f32_e32 v14, v11
	v_mul_f32_e32 v11, 0x3dd2d3e8, v3
	v_fma_mix_f32 v11, -v11, v108, s9 op_sel:[0,1,0] op_sel_hi:[0,1,0]
	v_mul_f32_e32 v11, v11, v3
	v_exp_f32_e32 v10, v10
	v_exp_f32_e32 v11, v11
	v_cvt_f32_f16_sdwa v13, v112 dst_sel:DWORD dst_unused:UNUSED_PAD src0_sel:WORD_1
	v_add_f32_e32 v10, 1.0, v10
	v_add_f32_e32 v11, 1.0, v11
	v_rcp_f32_e32 v10, v10
	v_rcp_f32_e32 v11, v11
	s_nop 0
	v_pk_mul_f32 v[2:3], v[10:11], v[2:3]
	v_cvt_f32_f16_e32 v10, v4
	v_cvt_f32_f16_sdwa v11, v4 dst_sel:DWORD dst_unused:UNUSED_PAD src0_sel:WORD_1
	v_mul_f32_e32 v4, 0xbfb8aa3b, v13
	v_exp_f32_e32 v4, v4
	v_pk_add_f32 v[10:11], v[180:181], v[10:11] op_sel_hi:[0,1]
	v_pk_mul_f32 v[2:3], v[2:3], v[10:11]
	v_add_f32_e32 v4, 1.0, v4
	v_rcp_f32_e32 v15, v4
	s_nop 0
	v_pk_mul_f32 v[10:11], v[14:15], v[12:13]
	s_nop 0
	v_pk_mul_f32 v[10:11], v[10:11], v[2:3]
	v_cvt_f32_f16_e32 v2, v109
	v_cvt_f32_f16_sdwa v3, v109 dst_sel:DWORD dst_unused:UNUSED_PAD src0_sel:WORD_1
	v_cvt_f32_f16_e32 v14, v113
	v_cvt_f32_f16_sdwa v15, v113 dst_sel:DWORD dst_unused:UNUSED_PAD src0_sel:WORD_1
	v_mul_f32_e32 v4, 0x3dd2d3e8, v2
	v_mul_f32_e32 v13, 0x3dd2d3e8, v3
	v_fma_mix_f32 v4, -v4, v109, s9 op_sel_hi:[0,1,0]
	v_fma_mix_f32 v13, -v13, v109, s9 op_sel:[0,1,0] op_sel_hi:[0,1,0]
	v_mul_f32_e32 v4, v4, v2
	v_mul_f32_e32 v13, v13, v3
	v_exp_f32_e32 v4, v4
	v_exp_f32_e32 v13, v13
	v_add_f32_e32 v4, 1.0, v4
	v_add_f32_e32 v13, 1.0, v13
	v_rcp_f32_e32 v12, v4
	v_rcp_f32_e32 v13, v13
	v_mul_f32_e32 v4, 0xbfb8aa3b, v14
	v_exp_f32_e32 v4, v4
	v_pk_mul_f32 v[2:3], v[12:13], v[2:3]
	v_cvt_f32_f16_e32 v12, v5
	v_cvt_f32_f16_sdwa v13, v5 dst_sel:DWORD dst_unused:UNUSED_PAD src0_sel:WORD_1
	v_mul_f32_e32 v5, 0xbfb8aa3b, v15
	v_exp_f32_e32 v5, v5
	v_add_f32_e32 v4, 1.0, v4
	v_rcp_f32_e32 v4, v4
	v_pk_add_f32 v[12:13], v[180:181], v[12:13] op_sel_hi:[0,1]
	v_add_f32_e32 v5, 1.0, v5
	v_rcp_f32_e32 v5, v5
	v_pk_mul_f32 v[2:3], v[2:3], v[12:13]
	v_pk_mul_f32 v[4:5], v[4:5], v[14:15]
	s_nop 0
	v_pk_mul_f32 v[12:13], v[4:5], v[2:3]
	v_cvt_pk_f16_f32 v4, v10, v11
	s_waitcnt vmcnt(18)
	v_cvt_f32_f16_e32 v10, v102
	v_cvt_pk_f16_f32 v2, v6, v7
	v_cvt_pk_f16_f32 v3, v8, v9
	v_lshlrev_b64 v[6:7], 11, v[164:165]
	v_mul_f32_e32 v9, 0xbfb8aa3b, v10
	v_cvt_pk_f16_f32 v5, v12, v13
	v_lshl_add_u64 v[6:7], v[148:149], 0, v[6:7]
	v_exp_f32_e32 v9, v9
	global_store_dwordx4 v[6:7], v[2:5], off sc1
	v_cvt_f32_f16_e32 v6, v98
	v_cvt_f32_f16_sdwa v7, v98 dst_sel:DWORD dst_unused:UNUSED_PAD src0_sel:WORD_1
	v_add_f32_e32 v9, 1.0, v9
	v_rcp_f32_e32 v12, v9
	v_mul_f32_e32 v8, 0x3dd2d3e8, v6
	v_mul_f32_e32 v9, 0x3dd2d3e8, v7
	v_fma_mix_f32 v8, -v8, v98, s9 op_sel_hi:[0,1,0]
	v_fma_mix_f32 v9, -v9, v98, s9 op_sel:[0,1,0] op_sel_hi:[0,1,0]
	v_mul_f32_e32 v8, v8, v6
	v_mul_f32_e32 v9, v9, v7
	v_exp_f32_e32 v8, v8
	v_exp_f32_e32 v9, v9
	ds_read_b128 v[2:5], v0 offset:1152
	v_cvt_f32_f16_sdwa v11, v102 dst_sel:DWORD dst_unused:UNUSED_PAD src0_sel:WORD_1
	v_add_f32_e32 v8, 1.0, v8
	v_add_f32_e32 v9, 1.0, v9
	v_rcp_f32_e32 v8, v8
	v_rcp_f32_e32 v9, v9
	v_or_b32_e32 v164, s4, v106
	v_or_b32_e32 v98, 16, v167
	v_pk_mul_f32 v[6:7], v[8:9], v[6:7]
	s_waitcnt lgkmcnt(0)
; #define LAS __attribute__((address_space(3)))
; #define GAS __attribute__((address_space(1)))
; __device__ __forceinline__ float siluf(float x) { return x * __builtin_amdgcn_rcpf(1.f + __builtin_amdgcn_exp2f(-1.4426950408889634f * x)); }
; __device__ __forceinline__ float geluf(float x) { return x * __builtin_amdgcn_rcpf(1.f + __builtin_amdgcn_exp2f(x * (-0.10294324f * x * x - 2.3022082f))); }
; __device__ __forceinline__ unsigned cvtpk_h(float lo, float hi) { f32x2 v = {lo, hi}; h16x2 b = __builtin_convertvector(v, h16x2); return __builtin_bit_cast(unsigned, b); }
; __device__ __forceinline__ void gmlp_unit(unsigned char* ws, h16* Y, const h16* Ws16  , const float* bs  , size_t r0, LAS unsigned char* lds, int tid) {
;     ...
; #pragma unroll
;         for (int ps = 0; ps < 4; ++ps) { const int row = 8 * ps + erow;
;             const h16x8 sv = *(const LAS h16x8*)(scr + row * 72 + 8 * ech);
;             float y[8];
; #pragma unroll
;             for (int k = 0; k < 8; ++k) y[k] = geluf((float)gu[q][ps][k]) * ((float)sv[k] + bias[q][ps]) * siluf((float)sz[q][ps][k]);
;             u32x4 w0; w0.x = cvtpk_h(y[0], y[1]); w0.y = cvtpk_h(y[2], y[3]); w0.z = cvtpk_h(y[4], y[5]); w0.w = cvtpk_h(y[6], y[7]);
;             *(GAS u32x4*)(Y + (r0 + 32 * (2 * ph + q) + row) * D + g * 64 + 8 * ech) = w0; }
	v_cvt_f32_f16_e32 v8, v2
	v_cvt_f32_f16_sdwa v9, v2 dst_sel:DWORD dst_unused:UNUSED_PAD src0_sel:WORD_1
	v_mul_f32_e32 v2, 0xbfb8aa3b, v11
	v_exp_f32_e32 v2, v2
	v_pk_add_f32 v[8:9], v[178:179], v[8:9] op_sel_hi:[0,1]
	v_pk_mul_f32 v[6:7], v[6:7], v[8:9]
	v_add_f32_e32 v2, 1.0, v2
	v_rcp_f32_e32 v13, v2
	s_nop 0
	v_pk_mul_f32 v[8:9], v[12:13], v[10:11]
	s_nop 0
	v_pk_mul_f32 v[6:7], v[8:9], v[6:7]
	v_cvt_f32_f16_e32 v8, v99
	v_cvt_f32_f16_sdwa v9, v99 dst_sel:DWORD dst_unused:UNUSED_PAD src0_sel:WORD_1
	v_cvt_f32_f16_e32 v12, v103
	v_cvt_f32_f16_sdwa v13, v103 dst_sel:DWORD dst_unused:UNUSED_PAD src0_sel:WORD_1
	v_mul_f32_e32 v2, 0x3dd2d3e8, v8
	v_mul_f32_e32 v11, 0x3dd2d3e8, v9
	v_fma_mix_f32 v2, -v2, v99, s9 op_sel_hi:[0,1,0]
	v_fma_mix_f32 v11, -v11, v99, s9 op_sel:[0,1,0] op_sel_hi:[0,1,0]
	v_mul_f32_e32 v2, v2, v8
	v_mul_f32_e32 v11, v11, v9
	v_exp_f32_e32 v2, v2
	v_exp_f32_e32 v11, v11
	v_add_f32_e32 v2, 1.0, v2
	v_add_f32_e32 v11, 1.0, v11
	v_rcp_f32_e32 v10, v2
	v_rcp_f32_e32 v11, v11
	v_mul_f32_e32 v2, 0xbfb8aa3b, v12
	v_exp_f32_e32 v2, v2
	v_pk_mul_f32 v[8:9], v[10:11], v[8:9]
	v_cvt_f32_f16_e32 v10, v3
	v_cvt_f32_f16_sdwa v11, v3 dst_sel:DWORD dst_unused:UNUSED_PAD src0_sel:WORD_1
	v_mul_f32_e32 v3, 0xbfb8aa3b, v13
	v_exp_f32_e32 v3, v3
	v_add_f32_e32 v2, 1.0, v2
	v_rcp_f32_e32 v2, v2
	v_pk_add_f32 v[10:11], v[178:179], v[10:11] op_sel_hi:[0,1]
	v_add_f32_e32 v3, 1.0, v3
	v_rcp_f32_e32 v3, v3
	v_pk_mul_f32 v[8:9], v[8:9], v[10:11]
	v_pk_mul_f32 v[2:3], v[2:3], v[12:13]
	v_cvt_f32_f16_e32 v12, v104
	v_pk_mul_f32 v[2:3], v[2:3], v[8:9]
	v_cvt_f32_f16_e32 v8, v100
	v_cvt_f32_f16_sdwa v9, v100 dst_sel:DWORD dst_unused:UNUSED_PAD src0_sel:WORD_1
	v_mul_f32_e32 v11, 0xbfb8aa3b, v12
	v_exp_f32_e32 v11, v11
	v_mul_f32_e32 v10, 0x3dd2d3e8, v8
	v_fma_mix_f32 v10, -v10, v100, s9 op_sel_hi:[0,1,0]
	v_mul_f32_e32 v10, v10, v8
	v_add_f32_e32 v11, 1.0, v11
	v_rcp_f32_e32 v14, v11
	v_mul_f32_e32 v11, 0x3dd2d3e8, v9
	v_fma_mix_f32 v11, -v11, v100, s9 op_sel:[0,1,0] op_sel_hi:[0,1,0]
	v_mul_f32_e32 v11, v11, v9
	v_exp_f32_e32 v10, v10
	v_exp_f32_e32 v11, v11
	v_cvt_f32_f16_sdwa v13, v104 dst_sel:DWORD dst_unused:UNUSED_PAD src0_sel:WORD_1
	v_add_f32_e32 v10, 1.0, v10
	v_add_f32_e32 v11, 1.0, v11
	v_rcp_f32_e32 v10, v10
	v_rcp_f32_e32 v11, v11
	s_nop 0
	v_pk_mul_f32 v[8:9], v[10:11], v[8:9]
	v_cvt_f32_f16_e32 v10, v4
	v_cvt_f32_f16_sdwa v11, v4 dst_sel:DWORD dst_unused:UNUSED_PAD src0_sel:WORD_1
	v_mul_f32_e32 v4, 0xbfb8aa3b, v13
	v_exp_f32_e32 v4, v4
	v_pk_add_f32 v[10:11], v[178:179], v[10:11] op_sel_hi:[0,1]
	v_pk_mul_f32 v[8:9], v[8:9], v[10:11]
	v_add_f32_e32 v4, 1.0, v4
	v_rcp_f32_e32 v15, v4
	s_nop 0
	v_pk_mul_f32 v[10:11], v[14:15], v[12:13]
	s_nop 0
	v_pk_mul_f32 v[8:9], v[10:11], v[8:9]
	v_cvt_f32_f16_e32 v10, v101
	v_cvt_f32_f16_sdwa v11, v101 dst_sel:DWORD dst_unused:UNUSED_PAD src0_sel:WORD_1
	v_cvt_f32_f16_e32 v14, v105
	v_cvt_f32_f16_sdwa v15, v105 dst_sel:DWORD dst_unused:UNUSED_PAD src0_sel:WORD_1
	v_mul_f32_e32 v4, 0x3dd2d3e8, v10
	v_mul_f32_e32 v13, 0x3dd2d3e8, v11
	v_fma_mix_f32 v4, -v4, v101, s9 op_sel_hi:[0,1,0]
	v_fma_mix_f32 v13, -v13, v101, s9 op_sel:[0,1,0] op_sel_hi:[0,1,0]
	v_mul_f32_e32 v4, v4, v10
	v_mul_f32_e32 v13, v13, v11
	v_exp_f32_e32 v4, v4
	v_exp_f32_e32 v13, v13
	v_add_f32_e32 v4, 1.0, v4
	v_add_f32_e32 v13, 1.0, v13
	v_rcp_f32_e32 v12, v4
	v_rcp_f32_e32 v13, v13
	v_mul_f32_e32 v4, 0xbfb8aa3b, v14
	v_exp_f32_e32 v4, v4
	v_pk_mul_f32 v[10:11], v[12:13], v[10:11]
	v_cvt_f32_f16_e32 v12, v5
	v_cvt_f32_f16_sdwa v13, v5 dst_sel:DWORD dst_unused:UNUSED_PAD src0_sel:WORD_1
	v_mul_f32_e32 v5, 0xbfb8aa3b, v15
	v_exp_f32_e32 v5, v5
	v_add_f32_e32 v4, 1.0, v4
	v_rcp_f32_e32 v4, v4
	v_pk_add_f32 v[12:13], v[178:179], v[12:13] op_sel_hi:[0,1]
	v_add_f32_e32 v5, 1.0, v5
	v_rcp_f32_e32 v5, v5
	v_pk_mul_f32 v[10:11], v[10:11], v[12:13]
	v_pk_mul_f32 v[4:5], v[4:5], v[14:15]
	s_nop 0
	v_pk_mul_f32 v[10:11], v[4:5], v[10:11]
	v_cvt_pk_f16_f32 v4, v6, v7
	v_cvt_pk_f16_f32 v7, v10, v11
	s_waitcnt vmcnt(16)
	v_cvt_f32_f16_e32 v10, v94
	v_cvt_pk_f16_f32 v5, v2, v3
	v_cvt_pk_f16_f32 v6, v8, v9
	v_lshlrev_b64 v[2:3], 11, v[164:165]
	v_mul_f32_e32 v9, 0xbfb8aa3b, v10
	v_lshl_add_u64 v[2:3], v[148:149], 0, v[2:3]
	v_exp_f32_e32 v9, v9
	global_store_dwordx4 v[2:3], v[4:7], off sc1
	ds_read_b128 v[2:5], v0 offset:2304
	v_cvt_f32_f16_sdwa v11, v94 dst_sel:DWORD dst_unused:UNUSED_PAD src0_sel:WORD_1
	v_cvt_f32_f16_e32 v6, v90
	v_cvt_f32_f16_sdwa v7, v90 dst_sel:DWORD dst_unused:UNUSED_PAD src0_sel:WORD_1
	v_add_f32_e32 v9, 1.0, v9
	v_rcp_f32_e32 v12, v9
	v_mul_f32_e32 v8, 0x3dd2d3e8, v6
	v_mul_f32_e32 v9, 0x3dd2d3e8, v7
	v_fma_mix_f32 v8, -v8, v90, s9 op_sel_hi:[0,1,0]
	v_fma_mix_f32 v9, -v9, v90, s9 op_sel:[0,1,0] op_sel_hi:[0,1,0]
	v_mul_f32_e32 v8, v8, v6
	v_mul_f32_e32 v9, v9, v7
	v_exp_f32_e32 v8, v8
	v_exp_f32_e32 v9, v9
	v_or_b32_e32 v164, s4, v98
	v_or_b32_e32 v90, 24, v167
	v_add_f32_e32 v8, 1.0, v8
	v_add_f32_e32 v9, 1.0, v9
	v_rcp_f32_e32 v8, v8
	v_rcp_f32_e32 v9, v9
	s_nop 0
	v_pk_mul_f32 v[6:7], v[8:9], v[6:7]
	s_waitcnt lgkmcnt(0)
; #define LAS __attribute__((address_space(3)))
; #define GAS __attribute__((address_space(1)))
; __device__ __forceinline__ float siluf(float x) { return x * __builtin_amdgcn_rcpf(1.f + __builtin_amdgcn_exp2f(-1.4426950408889634f * x)); }
; __device__ __forceinline__ float geluf(float x) { return x * __builtin_amdgcn_rcpf(1.f + __builtin_amdgcn_exp2f(x * (-0.10294324f * x * x - 2.3022082f))); }
; __device__ __forceinline__ unsigned cvtpk_h(float lo, float hi) { f32x2 v = {lo, hi}; h16x2 b = __builtin_convertvector(v, h16x2); return __builtin_bit_cast(unsigned, b); }
; __device__ __forceinline__ void gmlp_unit(unsigned char* ws, h16* Y, const h16* Ws16  , const float* bs  , size_t r0, LAS unsigned char* lds, int tid) {
;     ...
; #pragma unroll
;         for (int ps = 0; ps < 4; ++ps) { const int row = 8 * ps + erow;
;             const h16x8 sv = *(const LAS h16x8*)(scr + row * 72 + 8 * ech);
;             float y[8];
; #pragma unroll
;             for (int k = 0; k < 8; ++k) y[k] = geluf((float)gu[q][ps][k]) * ((float)sv[k] + bias[q][ps]) * siluf((float)sz[q][ps][k]);
;             u32x4 w0; w0.x = cvtpk_h(y[0], y[1]); w0.y = cvtpk_h(y[2], y[3]); w0.z = cvtpk_h(y[4], y[5]); w0.w = cvtpk_h(y[6], y[7]);
;             *(GAS u32x4*)(Y + (r0 + 32 * (2 * ph + q) + row) * D + g * 64 + 8 * ech) = w0; }
	v_cvt_f32_f16_e32 v8, v2
	v_cvt_f32_f16_sdwa v9, v2 dst_sel:DWORD dst_unused:UNUSED_PAD src0_sel:WORD_1
	v_mul_f32_e32 v2, 0xbfb8aa3b, v11
	v_exp_f32_e32 v2, v2
	v_pk_add_f32 v[8:9], v[176:177], v[8:9] op_sel_hi:[0,1]
	v_pk_mul_f32 v[6:7], v[6:7], v[8:9]
	v_add_f32_e32 v2, 1.0, v2
	v_rcp_f32_e32 v13, v2
	s_nop 0
	v_pk_mul_f32 v[8:9], v[12:13], v[10:11]
	s_nop 0
	v_pk_mul_f32 v[6:7], v[8:9], v[6:7]
	v_cvt_f32_f16_e32 v8, v91
	v_cvt_f32_f16_sdwa v9, v91 dst_sel:DWORD dst_unused:UNUSED_PAD src0_sel:WORD_1
	v_cvt_f32_f16_e32 v12, v95
	v_cvt_f32_f16_sdwa v13, v95 dst_sel:DWORD dst_unused:UNUSED_PAD src0_sel:WORD_1
	v_mul_f32_e32 v2, 0x3dd2d3e8, v8
	v_mul_f32_e32 v11, 0x3dd2d3e8, v9
	v_fma_mix_f32 v2, -v2, v91, s9 op_sel_hi:[0,1,0]
	v_fma_mix_f32 v11, -v11, v91, s9 op_sel:[0,1,0] op_sel_hi:[0,1,0]
	v_mul_f32_e32 v2, v2, v8
	v_mul_f32_e32 v11, v11, v9
	v_exp_f32_e32 v2, v2
	v_exp_f32_e32 v11, v11
	v_add_f32_e32 v2, 1.0, v2
	v_add_f32_e32 v11, 1.0, v11
	v_rcp_f32_e32 v10, v2
	v_rcp_f32_e32 v11, v11
	v_mul_f32_e32 v2, 0xbfb8aa3b, v12
	v_exp_f32_e32 v2, v2
	v_pk_mul_f32 v[8:9], v[10:11], v[8:9]
	v_cvt_f32_f16_e32 v10, v3
	v_cvt_f32_f16_sdwa v11, v3 dst_sel:DWORD dst_unused:UNUSED_PAD src0_sel:WORD_1
	v_mul_f32_e32 v3, 0xbfb8aa3b, v13
	v_exp_f32_e32 v3, v3
	v_add_f32_e32 v2, 1.0, v2
	v_rcp_f32_e32 v2, v2
	v_pk_add_f32 v[10:11], v[176:177], v[10:11] op_sel_hi:[0,1]
	v_add_f32_e32 v3, 1.0, v3
	v_rcp_f32_e32 v3, v3
	v_pk_mul_f32 v[8:9], v[8:9], v[10:11]
	v_pk_mul_f32 v[2:3], v[2:3], v[12:13]
	v_cvt_f32_f16_e32 v12, v96
	v_pk_mul_f32 v[8:9], v[2:3], v[8:9]
	v_cvt_f32_f16_e32 v2, v92
	v_cvt_f32_f16_sdwa v3, v92 dst_sel:DWORD dst_unused:UNUSED_PAD src0_sel:WORD_1
	v_mul_f32_e32 v11, 0xbfb8aa3b, v12
	v_exp_f32_e32 v11, v11
	v_mul_f32_e32 v10, 0x3dd2d3e8, v2
	v_fma_mix_f32 v10, -v10, v92, s9 op_sel_hi:[0,1,0]
	v_mul_f32_e32 v10, v10, v2
	v_add_f32_e32 v11, 1.0, v11
	v_rcp_f32_e32 v14, v11
	v_mul_f32_e32 v11, 0x3dd2d3e8, v3
	v_fma_mix_f32 v11, -v11, v92, s9 op_sel:[0,1,0] op_sel_hi:[0,1,0]
	v_mul_f32_e32 v11, v11, v3
	v_exp_f32_e32 v10, v10
	v_exp_f32_e32 v11, v11
	v_cvt_f32_f16_sdwa v13, v96 dst_sel:DWORD dst_unused:UNUSED_PAD src0_sel:WORD_1
	v_add_f32_e32 v10, 1.0, v10
	v_add_f32_e32 v11, 1.0, v11
	v_rcp_f32_e32 v10, v10
	v_rcp_f32_e32 v11, v11
	s_nop 0
	v_pk_mul_f32 v[2:3], v[10:11], v[2:3]
	v_cvt_f32_f16_e32 v10, v4
	v_cvt_f32_f16_sdwa v11, v4 dst_sel:DWORD dst_unused:UNUSED_PAD src0_sel:WORD_1
	v_mul_f32_e32 v4, 0xbfb8aa3b, v13
	v_exp_f32_e32 v4, v4
	v_pk_add_f32 v[10:11], v[176:177], v[10:11] op_sel_hi:[0,1]
	v_pk_mul_f32 v[2:3], v[2:3], v[10:11]
	v_add_f32_e32 v4, 1.0, v4
	v_rcp_f32_e32 v15, v4
	s_nop 0
	v_pk_mul_f32 v[10:11], v[14:15], v[12:13]
	s_nop 0
	v_pk_mul_f32 v[10:11], v[10:11], v[2:3]
	v_cvt_f32_f16_e32 v2, v93
	v_cvt_f32_f16_sdwa v3, v93 dst_sel:DWORD dst_unused:UNUSED_PAD src0_sel:WORD_1
	v_cvt_f32_f16_e32 v14, v97
	v_cvt_f32_f16_sdwa v15, v97 dst_sel:DWORD dst_unused:UNUSED_PAD src0_sel:WORD_1
	v_mul_f32_e32 v4, 0x3dd2d3e8, v2
	v_mul_f32_e32 v13, 0x3dd2d3e8, v3
	v_fma_mix_f32 v4, -v4, v93, s9 op_sel_hi:[0,1,0]
	v_fma_mix_f32 v13, -v13, v93, s9 op_sel:[0,1,0] op_sel_hi:[0,1,0]
	v_mul_f32_e32 v4, v4, v2
	v_mul_f32_e32 v13, v13, v3
	v_exp_f32_e32 v4, v4
	v_exp_f32_e32 v13, v13
	v_add_f32_e32 v4, 1.0, v4
	v_add_f32_e32 v13, 1.0, v13
	v_rcp_f32_e32 v12, v4
	v_rcp_f32_e32 v13, v13
	v_mul_f32_e32 v4, 0xbfb8aa3b, v14
	v_exp_f32_e32 v4, v4
	v_pk_mul_f32 v[2:3], v[12:13], v[2:3]
	v_cvt_f32_f16_e32 v12, v5
	v_cvt_f32_f16_sdwa v13, v5 dst_sel:DWORD dst_unused:UNUSED_PAD src0_sel:WORD_1
	v_mul_f32_e32 v5, 0xbfb8aa3b, v15
	v_exp_f32_e32 v5, v5
	v_add_f32_e32 v4, 1.0, v4
	v_rcp_f32_e32 v4, v4
	v_pk_add_f32 v[12:13], v[176:177], v[12:13] op_sel_hi:[0,1]
	v_add_f32_e32 v5, 1.0, v5
	v_rcp_f32_e32 v5, v5
	v_pk_mul_f32 v[2:3], v[2:3], v[12:13]
	v_pk_mul_f32 v[4:5], v[4:5], v[14:15]
	s_nop 0
	v_pk_mul_f32 v[12:13], v[4:5], v[2:3]
	v_cvt_pk_f16_f32 v4, v10, v11
	s_waitcnt vmcnt(14)
	v_cvt_f32_f16_e32 v10, v86
	v_cvt_pk_f16_f32 v2, v6, v7
	v_cvt_pk_f16_f32 v3, v8, v9
	v_lshlrev_b64 v[6:7], 11, v[164:165]
	v_mul_f32_e32 v9, 0xbfb8aa3b, v10
	v_cvt_pk_f16_f32 v5, v12, v13
	v_lshl_add_u64 v[6:7], v[148:149], 0, v[6:7]
	v_exp_f32_e32 v9, v9
	global_store_dwordx4 v[6:7], v[2:5], off sc1
	v_cvt_f32_f16_e32 v6, v82
	v_cvt_f32_f16_sdwa v7, v82 dst_sel:DWORD dst_unused:UNUSED_PAD src0_sel:WORD_1
	v_add_f32_e32 v9, 1.0, v9
	v_rcp_f32_e32 v12, v9
	v_mul_f32_e32 v8, 0x3dd2d3e8, v6
	v_mul_f32_e32 v9, 0x3dd2d3e8, v7
	v_fma_mix_f32 v8, -v8, v82, s9 op_sel_hi:[0,1,0]
	v_fma_mix_f32 v9, -v9, v82, s9 op_sel:[0,1,0] op_sel_hi:[0,1,0]
	v_mul_f32_e32 v8, v8, v6
	v_mul_f32_e32 v9, v9, v7
	v_exp_f32_e32 v8, v8
	v_exp_f32_e32 v9, v9
	ds_read_b128 v[2:5], v0 offset:3456
	v_cvt_f32_f16_sdwa v11, v86 dst_sel:DWORD dst_unused:UNUSED_PAD src0_sel:WORD_1
	v_add_f32_e32 v8, 1.0, v8
	v_add_f32_e32 v9, 1.0, v9
	v_rcp_f32_e32 v8, v8
	v_rcp_f32_e32 v9, v9
	v_or_b32_e32 v164, s4, v90
	v_pk_mul_f32 v[6:7], v[8:9], v[6:7]
	s_waitcnt lgkmcnt(0)
; #define LAS __attribute__((address_space(3)))
; #define GAS __attribute__((address_space(1)))
; __device__ __forceinline__ float siluf(float x) { return x * __builtin_amdgcn_rcpf(1.f + __builtin_amdgcn_exp2f(-1.4426950408889634f * x)); }
; __device__ __forceinline__ float geluf(float x) { return x * __builtin_amdgcn_rcpf(1.f + __builtin_amdgcn_exp2f(x * (-0.10294324f * x * x - 2.3022082f))); }
; __device__ __forceinline__ unsigned cvtpk_h(float lo, float hi) { f32x2 v = {lo, hi}; h16x2 b = __builtin_convertvector(v, h16x2); return __builtin_bit_cast(unsigned, b); }
; __device__ __forceinline__ void gmlp_unit(unsigned char* ws, h16* Y, const h16* Ws16  , const float* bs  , size_t r0, LAS unsigned char* lds, int tid) {
;     ...
;         for (int db = 0; db < 2; ++db) {
;             s16x8 bf[8];
; #pragma unroll
;             for (int ks = 0; ks < 8; ++ks) bf[ks] = tr_frag((LAS const char*)lds + g * 16384, 8192, db, ks, lane);
;             f32x16 acc = f32x16{};
; #pragma unroll
;             for (int ks = 0; ks < 8; ++ks) acc = __builtin_amdgcn_mfma_f32_32x32x16_f16(H8(af[q][ks]), H8(bf[ks]), acc, 0, 0, 0);
;     ...
; #pragma unroll
;         for (int ps = 0; ps < 4; ++ps) { const int row = 8 * ps + erow;
;             const h16x8 sv = *(const LAS h16x8*)(scr + row * 72 + 8 * ech);
;             float y[8];
; #pragma unroll
;             for (int k = 0; k < 8; ++k) y[k] = geluf((float)gu[q][ps][k]) * ((float)sv[k] + bias[q][ps]) * siluf((float)sz[q][ps][k]);
;             u32x4 w0; w0.x = cvtpk_h(y[0], y[1]); w0.y = cvtpk_h(y[2], y[3]); w0.z = cvtpk_h(y[4], y[5]); w0.w = cvtpk_h(y[6], y[7]);
;             *(GAS u32x4*)(Y + (r0 + 32 * (2 * ph + q) + row) * D + g * 64 + 8 * ech) = w0; }
	v_cvt_f32_f16_e32 v8, v2
	v_cvt_f32_f16_sdwa v9, v2 dst_sel:DWORD dst_unused:UNUSED_PAD src0_sel:WORD_1
	v_mul_f32_e32 v2, 0xbfb8aa3b, v11
	v_exp_f32_e32 v2, v2
	v_pk_add_f32 v[8:9], v[174:175], v[8:9] op_sel_hi:[0,1]
	v_pk_mul_f32 v[6:7], v[6:7], v[8:9]
	v_add_f32_e32 v2, 1.0, v2
	v_rcp_f32_e32 v13, v2
	s_nop 0
	v_pk_mul_f32 v[8:9], v[12:13], v[10:11]
	s_nop 0
	v_pk_mul_f32 v[6:7], v[8:9], v[6:7]
	v_cvt_f32_f16_e32 v8, v83
	v_cvt_f32_f16_sdwa v9, v83 dst_sel:DWORD dst_unused:UNUSED_PAD src0_sel:WORD_1
	v_cvt_f32_f16_e32 v12, v87
	v_cvt_f32_f16_sdwa v13, v87 dst_sel:DWORD dst_unused:UNUSED_PAD src0_sel:WORD_1
	v_mul_f32_e32 v2, 0x3dd2d3e8, v8
	v_mul_f32_e32 v11, 0x3dd2d3e8, v9
	v_fma_mix_f32 v2, -v2, v83, s9 op_sel_hi:[0,1,0]
	v_fma_mix_f32 v11, -v11, v83, s9 op_sel:[0,1,0] op_sel_hi:[0,1,0]
	v_mul_f32_e32 v2, v2, v8
	v_mul_f32_e32 v11, v11, v9
	v_exp_f32_e32 v2, v2
	v_exp_f32_e32 v11, v11
	v_add_f32_e32 v2, 1.0, v2
	v_add_f32_e32 v11, 1.0, v11
	v_rcp_f32_e32 v10, v2
	v_rcp_f32_e32 v11, v11
	v_mul_f32_e32 v2, 0xbfb8aa3b, v12
	v_exp_f32_e32 v2, v2
	v_pk_mul_f32 v[8:9], v[10:11], v[8:9]
	v_cvt_f32_f16_e32 v10, v3
	v_cvt_f32_f16_sdwa v11, v3 dst_sel:DWORD dst_unused:UNUSED_PAD src0_sel:WORD_1
	v_mul_f32_e32 v3, 0xbfb8aa3b, v13
	v_exp_f32_e32 v3, v3
	v_add_f32_e32 v2, 1.0, v2
	v_rcp_f32_e32 v2, v2
	v_pk_add_f32 v[10:11], v[174:175], v[10:11] op_sel_hi:[0,1]
	v_add_f32_e32 v3, 1.0, v3
	v_rcp_f32_e32 v3, v3
	v_pk_mul_f32 v[8:9], v[8:9], v[10:11]
	v_pk_mul_f32 v[2:3], v[2:3], v[12:13]
	v_cvt_f32_f16_e32 v12, v88
	v_pk_mul_f32 v[2:3], v[2:3], v[8:9]
	v_cvt_f32_f16_e32 v8, v84
	v_cvt_f32_f16_sdwa v9, v84 dst_sel:DWORD dst_unused:UNUSED_PAD src0_sel:WORD_1
	v_mul_f32_e32 v11, 0xbfb8aa3b, v12
	v_exp_f32_e32 v11, v11
	v_mul_f32_e32 v10, 0x3dd2d3e8, v8
	v_fma_mix_f32 v10, -v10, v84, s9 op_sel_hi:[0,1,0]
	v_mul_f32_e32 v10, v10, v8
	v_add_f32_e32 v11, 1.0, v11
	v_rcp_f32_e32 v14, v11
	v_mul_f32_e32 v11, 0x3dd2d3e8, v9
	v_fma_mix_f32 v11, -v11, v84, s9 op_sel:[0,1,0] op_sel_hi:[0,1,0]
	v_mul_f32_e32 v11, v11, v9
	v_exp_f32_e32 v10, v10
	v_exp_f32_e32 v11, v11
	v_cvt_f32_f16_sdwa v13, v88 dst_sel:DWORD dst_unused:UNUSED_PAD src0_sel:WORD_1
	v_add_f32_e32 v10, 1.0, v10
	v_add_f32_e32 v11, 1.0, v11
	v_rcp_f32_e32 v10, v10
	v_rcp_f32_e32 v11, v11
	s_nop 0
	v_pk_mul_f32 v[8:9], v[10:11], v[8:9]
	v_cvt_f32_f16_e32 v10, v4
	v_cvt_f32_f16_sdwa v11, v4 dst_sel:DWORD dst_unused:UNUSED_PAD src0_sel:WORD_1
	v_mul_f32_e32 v4, 0xbfb8aa3b, v13
	v_exp_f32_e32 v4, v4
	v_pk_add_f32 v[10:11], v[174:175], v[10:11] op_sel_hi:[0,1]
	v_pk_mul_f32 v[8:9], v[8:9], v[10:11]
	v_add_f32_e32 v4, 1.0, v4
	v_rcp_f32_e32 v15, v4
	s_nop 0
	v_pk_mul_f32 v[10:11], v[14:15], v[12:13]
	s_nop 0
	v_pk_mul_f32 v[8:9], v[10:11], v[8:9]
	v_cvt_f32_f16_e32 v10, v85
	v_cvt_f32_f16_sdwa v11, v85 dst_sel:DWORD dst_unused:UNUSED_PAD src0_sel:WORD_1
	v_cvt_f32_f16_e32 v14, v89
	v_cvt_f32_f16_sdwa v15, v89 dst_sel:DWORD dst_unused:UNUSED_PAD src0_sel:WORD_1
	v_mul_f32_e32 v4, 0x3dd2d3e8, v10
	v_mul_f32_e32 v13, 0x3dd2d3e8, v11
	v_fma_mix_f32 v4, -v4, v85, s9 op_sel_hi:[0,1,0]
	v_fma_mix_f32 v13, -v13, v85, s9 op_sel:[0,1,0] op_sel_hi:[0,1,0]
	v_mul_f32_e32 v4, v4, v10
	v_mul_f32_e32 v13, v13, v11
	v_exp_f32_e32 v4, v4
	v_exp_f32_e32 v13, v13
	v_add_f32_e32 v4, 1.0, v4
	v_add_f32_e32 v13, 1.0, v13
	v_rcp_f32_e32 v12, v4
	v_rcp_f32_e32 v13, v13
	v_mul_f32_e32 v4, 0xbfb8aa3b, v14
	v_exp_f32_e32 v4, v4
	v_pk_mul_f32 v[10:11], v[12:13], v[10:11]
	v_cvt_f32_f16_e32 v12, v5
	v_cvt_f32_f16_sdwa v13, v5 dst_sel:DWORD dst_unused:UNUSED_PAD src0_sel:WORD_1
	v_mul_f32_e32 v5, 0xbfb8aa3b, v15
	v_exp_f32_e32 v5, v5
	v_add_f32_e32 v4, 1.0, v4
	v_rcp_f32_e32 v4, v4
	v_pk_add_f32 v[12:13], v[174:175], v[12:13] op_sel_hi:[0,1]
	v_add_f32_e32 v5, 1.0, v5
	v_rcp_f32_e32 v5, v5
	v_pk_mul_f32 v[10:11], v[10:11], v[12:13]
	v_pk_mul_f32 v[4:5], v[4:5], v[14:15]
	s_nop 0
	v_pk_mul_f32 v[10:11], v[4:5], v[10:11]
	v_cvt_pk_f16_f32 v5, v2, v3
	v_lshlrev_b64 v[2:3], 11, v[164:165]
	v_cvt_pk_f16_f32 v4, v6, v7
	v_cvt_pk_f16_f32 v6, v8, v9
	v_cvt_pk_f16_f32 v7, v10, v11
	v_lshl_add_u64 v[2:3], v[148:149], 0, v[2:3]
	global_store_dwordx4 v[2:3], v[4:7], off sc1
	s_waitcnt lgkmcnt(0)
	ds_read_b64_tr_b16 v[2:3], v151
	ds_read_b64_tr_b16 v[4:5], v151 offset:256
	ds_read_b64_tr_b16 v[82:83], v151 offset:1024
	ds_read_b64_tr_b16 v[84:85], v151 offset:1280
	ds_read_b64_tr_b16 v[86:87], v151 offset:2048
	ds_read_b64_tr_b16 v[88:89], v151 offset:2304
	ds_read_b64_tr_b16 v[92:93], v151 offset:3072
	ds_read_b64_tr_b16 v[94:95], v151 offset:3328
	ds_read_b64_tr_b16 v[100:101], v151 offset:4096
	ds_read_b64_tr_b16 v[102:103], v151 offset:4352
	ds_read_b64_tr_b16 v[108:109], v151 offset:5120
	ds_read_b64_tr_b16 v[110:111], v151 offset:5376
	ds_read_b64_tr_b16 v[112:113], v151 offset:6144
	ds_read_b64_tr_b16 v[114:115], v151 offset:6400
	ds_read_b64_tr_b16 v[116:117], v151 offset:7168
	ds_read_b64_tr_b16 v[118:119], v151 offset:7424
	s_waitcnt lgkmcnt(14)
	v_mfma_f32_32x32x16_f16 v[2:17], v[78:81], v[2:5], 0
	v_or_b32_e32 v164, s2, v167
	s_waitcnt lgkmcnt(12)
	v_mfma_f32_32x32x16_f16 v[2:17], v[74:77], v[82:85], v[2:17]
	s_waitcnt lgkmcnt(10)
	v_mfma_f32_32x32x16_f16 v[2:17], v[70:73], v[86:89], v[2:17]
	s_waitcnt lgkmcnt(8)
	v_mfma_f32_32x32x16_f16 v[2:17], v[66:69], v[92:95], v[2:17]
	s_waitcnt lgkmcnt(6)
	v_mfma_f32_32x32x16_f16 v[2:17], v[62:65], v[100:103], v[2:17]
	s_waitcnt lgkmcnt(4)
	v_mfma_f32_32x32x16_f16 v[2:17], v[58:61], v[108:111], v[2:17]
	s_waitcnt lgkmcnt(2)
	v_mfma_f32_32x32x16_f16 v[2:17], v[54:57], v[112:115], v[2:17]
	s_waitcnt lgkmcnt(0)
; #define LAS __attribute__((address_space(3)))
; __device__ __forceinline__ float siluf(float x) { return x * __builtin_amdgcn_rcpf(1.f + __builtin_amdgcn_exp2f(-1.4426950408889634f * x)); }
; __device__ __forceinline__ float geluf(float x) { return x * __builtin_amdgcn_rcpf(1.f + __builtin_amdgcn_exp2f(x * (-0.10294324f * x * x - 2.3022082f))); }
; #define LDS_WAIT() asm volatile("s_waitcnt lgkmcnt(0)" ::: "memory")
; __device__ __forceinline__ int crow(int r, int hi) { return (r & 3) + 8 * (r >> 2) + 4 * hi; }
; __device__ __forceinline__ void gmlp_unit(unsigned char* ws, h16* Y, const h16* Ws16  , const float* bs  , size_t r0, LAS unsigned char* lds, int tid) {
;     ...
;         for (int db = 0; db < 2; ++db) {
;             s16x8 bf[8];
; #pragma unroll
;             for (int ks = 0; ks < 8; ++ks) bf[ks] = tr_frag((LAS const char*)lds + g * 16384, 8192, db, ks, lane);
;             f32x16 acc = f32x16{};
; #pragma unroll
;             for (int ks = 0; ks < 8; ++ks) acc = __builtin_amdgcn_mfma_f32_32x32x16_f16(H8(af[q][ks]), H8(bf[ks]), acc, 0, 0, 0);
; #pragma unroll
;             for (int r = 0; r < 16; ++r) scr[crow(r, hi) * 72 + 32 * db + r32] = (h16)acc[r];
;         }
;         LDS_WAIT();
; #pragma unroll
;         for (int ps = 0; ps < 4; ++ps) { const int row = 8 * ps + erow;
;             const h16x8 sv = *(const LAS h16x8*)(scr + row * 72 + 8 * ech);
;             float y[8];
; #pragma unroll
;             for (int k = 0; k < 8; ++k) y[k] = geluf((float)gu[q][ps][k]) * ((float)sv[k] + bias[q][ps]) * siluf((float)sz[q][ps][k]);
	v_mfma_f32_32x32x16_f16 v[2:17], v[50:53], v[116:119], v[2:17]
	s_nop 11
	v_cvt_f16_f32_e32 v2, v2
	ds_write_b16 v150, v2
	v_cvt_f16_f32_e32 v2, v3
	ds_write_b16 v150, v2 offset:144
	v_cvt_f16_f32_e32 v2, v4
	ds_write_b16 v150, v2 offset:288
	v_cvt_f16_f32_e32 v2, v5
	ds_write_b16 v150, v2 offset:432
	v_cvt_f16_f32_e32 v2, v6
	ds_write_b16 v150, v2 offset:1152
	v_cvt_f16_f32_e32 v2, v7
	ds_write_b16 v150, v2 offset:1296
	v_cvt_f16_f32_e32 v2, v8
	ds_write_b16 v150, v2 offset:1440
	v_cvt_f16_f32_e32 v2, v9
	ds_write_b16 v150, v2 offset:1584
	v_cvt_f16_f32_e32 v2, v10
	ds_write_b16 v150, v2 offset:2304
	v_cvt_f16_f32_e32 v2, v11
	ds_write_b16 v150, v2 offset:2448
	v_cvt_f16_f32_e32 v2, v12
	ds_write_b16 v150, v2 offset:2592
	v_cvt_f16_f32_e32 v2, v13
	ds_write_b16 v150, v2 offset:2736
	v_cvt_f16_f32_e32 v2, v14
	ds_write_b16 v150, v2 offset:3456
	v_cvt_f16_f32_e32 v2, v15
	ds_write_b16 v150, v2 offset:3600
	v_cvt_f16_f32_e32 v2, v16
	ds_write_b16 v150, v2 offset:3744
	v_cvt_f16_f32_e32 v2, v17
	ds_write_b16 v150, v2 offset:3888
	ds_read_b64_tr_b16 v[2:3], v151 offset:8192
	ds_read_b64_tr_b16 v[4:5], v151 offset:8448
	ds_read_b64_tr_b16 v[82:83], v151 offset:9216
	ds_read_b64_tr_b16 v[84:85], v151 offset:9472
	ds_read_b64_tr_b16 v[86:87], v151 offset:10240
	ds_read_b64_tr_b16 v[88:89], v151 offset:10496
	ds_read_b64_tr_b16 v[92:93], v151 offset:11264
	ds_read_b64_tr_b16 v[94:95], v151 offset:11520
	ds_read_b64_tr_b16 v[100:101], v151 offset:12288
	ds_read_b64_tr_b16 v[102:103], v151 offset:12544
	ds_read_b64_tr_b16 v[108:109], v151 offset:13312
	ds_read_b64_tr_b16 v[110:111], v151 offset:13568
	ds_read_b64_tr_b16 v[112:113], v151 offset:14336
	ds_read_b64_tr_b16 v[114:115], v151 offset:14592
	ds_read_b64_tr_b16 v[116:117], v151 offset:15360
	ds_read_b64_tr_b16 v[118:119], v151 offset:15616
	s_waitcnt lgkmcnt(14)
	v_mfma_f32_32x32x16_f16 v[2:17], v[78:81], v[2:5], 0
	s_waitcnt lgkmcnt(12)
	v_mfma_f32_32x32x16_f16 v[2:17], v[74:77], v[82:85], v[2:17]
	s_waitcnt lgkmcnt(10)
	v_mfma_f32_32x32x16_f16 v[2:17], v[70:73], v[86:89], v[2:17]
	s_waitcnt lgkmcnt(8)
	v_mfma_f32_32x32x16_f16 v[2:17], v[66:69], v[92:95], v[2:17]
	s_waitcnt lgkmcnt(6)
	v_mfma_f32_32x32x16_f16 v[2:17], v[62:65], v[100:103], v[2:17]
	s_waitcnt lgkmcnt(4)
	v_mfma_f32_32x32x16_f16 v[2:17], v[58:61], v[108:111], v[2:17]
	s_waitcnt lgkmcnt(2)
	v_mfma_f32_32x32x16_f16 v[2:17], v[54:57], v[112:115], v[2:17]
	s_waitcnt lgkmcnt(0)
	v_mfma_f32_32x32x16_f16 v[2:17], v[50:53], v[116:119], v[2:17]
	s_nop 11
	v_cvt_f16_f32_e32 v2, v2
	ds_write_b16 v150, v2 offset:64
	v_cvt_f16_f32_e32 v2, v3
	ds_write_b16 v150, v2 offset:208
	v_cvt_f16_f32_e32 v2, v4
	ds_write_b16 v150, v2 offset:352
	v_cvt_f16_f32_e32 v2, v5
	ds_write_b16 v150, v2 offset:496
	v_cvt_f16_f32_e32 v2, v6
	s_waitcnt vmcnt(15)
	v_cvt_f32_f16_e32 v6, v42
	ds_write_b16 v150, v2 offset:1216
	v_cvt_f16_f32_e32 v2, v7
	v_cvt_f32_f16_sdwa v7, v42 dst_sel:DWORD dst_unused:UNUSED_PAD src0_sel:WORD_1
	ds_write_b16 v150, v2 offset:1360
	v_cvt_f16_f32_e32 v2, v8
	v_mul_f32_e32 v8, 0x3dd2d3e8, v6
	v_fma_mix_f32 v8, -v8, v42, s9 op_sel_hi:[0,1,0]
	v_mul_f32_e32 v8, v8, v6
	ds_write_b16 v150, v2 offset:1504
	v_cvt_f16_f32_e32 v2, v9
	v_exp_f32_e32 v8, v8
	ds_write_b16 v150, v2 offset:1648
	v_cvt_f16_f32_e32 v2, v10
	s_waitcnt vmcnt(13)
	v_cvt_f32_f16_e32 v10, v46
	v_add_f32_e32 v8, 1.0, v8
	v_rcp_f32_e32 v8, v8
	ds_write_b16 v150, v2 offset:2368
	v_cvt_f16_f32_e32 v2, v11
	v_mul_f32_e32 v9, 0xbfb8aa3b, v10
	v_exp_f32_e32 v9, v9
	v_cvt_f32_f16_sdwa v11, v46 dst_sel:DWORD dst_unused:UNUSED_PAD src0_sel:WORD_1
	ds_write_b16 v150, v2 offset:2512
	v_cvt_f16_f32_e32 v2, v12
	v_add_f32_e32 v9, 1.0, v9
	v_rcp_f32_e32 v12, v9
	v_mul_f32_e32 v9, 0x3dd2d3e8, v7
	ds_write_b16 v150, v2 offset:2656
	v_cvt_f16_f32_e32 v2, v13
	v_fma_mix_f32 v9, -v9, v42, s9 op_sel:[0,1,0] op_sel_hi:[0,1,0]
	v_mul_f32_e32 v9, v9, v7
	v_exp_f32_e32 v9, v9
	ds_write_b16 v150, v2 offset:2800
	v_cvt_f16_f32_e32 v2, v14
	v_add_f32_e32 v9, 1.0, v9
	v_rcp_f32_e32 v9, v9
	ds_write_b16 v150, v2 offset:3520
	v_cvt_f16_f32_e32 v2, v15
	v_pk_mul_f32 v[6:7], v[8:9], v[6:7]
	ds_write_b16 v150, v2 offset:3664
	v_cvt_f16_f32_e32 v2, v16
	ds_write_b16 v150, v2 offset:3808
	v_cvt_f16_f32_e32 v2, v17
	ds_write_b16 v150, v2 offset:3952
	s_waitcnt lgkmcnt(0)
	ds_read_b128 v[2:5], v0
	s_waitcnt lgkmcnt(0)
; #define LAS __attribute__((address_space(3)))
; #define GAS __attribute__((address_space(1)))
; __device__ __forceinline__ float siluf(float x) { return x * __builtin_amdgcn_rcpf(1.f + __builtin_amdgcn_exp2f(-1.4426950408889634f * x)); }
; __device__ __forceinline__ float geluf(float x) { return x * __builtin_amdgcn_rcpf(1.f + __builtin_amdgcn_exp2f(x * (-0.10294324f * x * x - 2.3022082f))); }
; __device__ __forceinline__ unsigned cvtpk_h(float lo, float hi) { f32x2 v = {lo, hi}; h16x2 b = __builtin_convertvector(v, h16x2); return __builtin_bit_cast(unsigned, b); }
; __device__ __forceinline__ void gmlp_unit(unsigned char* ws, h16* Y, const h16* Ws16  , const float* bs  , size_t r0, LAS unsigned char* lds, int tid) {
;     ...
; #pragma unroll
;         for (int ps = 0; ps < 4; ++ps) { const int row = 8 * ps + erow;
;             const h16x8 sv = *(const LAS h16x8*)(scr + row * 72 + 8 * ech);
;             float y[8];
; #pragma unroll
;             for (int k = 0; k < 8; ++k) y[k] = geluf((float)gu[q][ps][k]) * ((float)sv[k] + bias[q][ps]) * siluf((float)sz[q][ps][k]);
;             u32x4 w0; w0.x = cvtpk_h(y[0], y[1]); w0.y = cvtpk_h(y[2], y[3]); w0.z = cvtpk_h(y[4], y[5]); w0.w = cvtpk_h(y[6], y[7]);
;             *(GAS u32x4*)(Y + (r0 + 32 * (2 * ph + q) + row) * D + g * 64 + 8 * ech) = w0; }
	v_cvt_f32_f16_e32 v8, v2
	v_cvt_f32_f16_sdwa v9, v2 dst_sel:DWORD dst_unused:UNUSED_PAD src0_sel:WORD_1
	v_mul_f32_e32 v2, 0xbfb8aa3b, v11
	v_exp_f32_e32 v2, v2
	v_pk_add_f32 v[8:9], v[172:173], v[8:9] op_sel_hi:[0,1]
	v_pk_mul_f32 v[6:7], v[6:7], v[8:9]
	v_add_f32_e32 v2, 1.0, v2
	v_rcp_f32_e32 v13, v2
	s_nop 0
	v_pk_mul_f32 v[8:9], v[12:13], v[10:11]
	s_nop 0
	v_pk_mul_f32 v[6:7], v[8:9], v[6:7]
	v_cvt_f32_f16_e32 v8, v43
	v_cvt_f32_f16_sdwa v9, v43 dst_sel:DWORD dst_unused:UNUSED_PAD src0_sel:WORD_1
	v_cvt_f32_f16_e32 v12, v47
	v_cvt_f32_f16_sdwa v13, v47 dst_sel:DWORD dst_unused:UNUSED_PAD src0_sel:WORD_1
	v_mul_f32_e32 v2, 0x3dd2d3e8, v8
	v_mul_f32_e32 v11, 0x3dd2d3e8, v9
	v_fma_mix_f32 v2, -v2, v43, s9 op_sel_hi:[0,1,0]
	v_fma_mix_f32 v11, -v11, v43, s9 op_sel:[0,1,0] op_sel_hi:[0,1,0]
	v_mul_f32_e32 v2, v2, v8
	v_mul_f32_e32 v11, v11, v9
	v_exp_f32_e32 v2, v2
	v_exp_f32_e32 v11, v11
	v_add_f32_e32 v2, 1.0, v2
	v_add_f32_e32 v11, 1.0, v11
	v_rcp_f32_e32 v10, v2
	v_rcp_f32_e32 v11, v11
	v_mul_f32_e32 v2, 0xbfb8aa3b, v12
	v_exp_f32_e32 v2, v2
	v_pk_mul_f32 v[8:9], v[10:11], v[8:9]
	v_cvt_f32_f16_e32 v10, v3
	v_cvt_f32_f16_sdwa v11, v3 dst_sel:DWORD dst_unused:UNUSED_PAD src0_sel:WORD_1
	v_mul_f32_e32 v3, 0xbfb8aa3b, v13
	v_exp_f32_e32 v3, v3
	v_add_f32_e32 v2, 1.0, v2
	v_rcp_f32_e32 v2, v2
	v_pk_add_f32 v[10:11], v[172:173], v[10:11] op_sel_hi:[0,1]
	v_add_f32_e32 v3, 1.0, v3
	v_rcp_f32_e32 v3, v3
	v_pk_mul_f32 v[8:9], v[8:9], v[10:11]
	v_pk_mul_f32 v[2:3], v[2:3], v[12:13]
	v_cvt_f32_f16_e32 v12, v48
	v_pk_mul_f32 v[8:9], v[2:3], v[8:9]
	v_cvt_f32_f16_e32 v2, v44
	v_cvt_f32_f16_sdwa v3, v44 dst_sel:DWORD dst_unused:UNUSED_PAD src0_sel:WORD_1
	v_mul_f32_e32 v11, 0xbfb8aa3b, v12
	v_exp_f32_e32 v11, v11
	v_mul_f32_e32 v10, 0x3dd2d3e8, v2
	v_fma_mix_f32 v10, -v10, v44, s9 op_sel_hi:[0,1,0]
	v_mul_f32_e32 v10, v10, v2
	v_add_f32_e32 v11, 1.0, v11
	v_rcp_f32_e32 v14, v11
	v_mul_f32_e32 v11, 0x3dd2d3e8, v3
	v_fma_mix_f32 v11, -v11, v44, s9 op_sel:[0,1,0] op_sel_hi:[0,1,0]
	v_mul_f32_e32 v11, v11, v3
	v_exp_f32_e32 v10, v10
	v_exp_f32_e32 v11, v11
	v_cvt_f32_f16_sdwa v13, v48 dst_sel:DWORD dst_unused:UNUSED_PAD src0_sel:WORD_1
	v_add_f32_e32 v10, 1.0, v10
	v_add_f32_e32 v11, 1.0, v11
	v_rcp_f32_e32 v10, v10
	v_rcp_f32_e32 v11, v11
	s_nop 0
	v_pk_mul_f32 v[2:3], v[10:11], v[2:3]
	v_cvt_f32_f16_e32 v10, v4
	v_cvt_f32_f16_sdwa v11, v4 dst_sel:DWORD dst_unused:UNUSED_PAD src0_sel:WORD_1
	v_mul_f32_e32 v4, 0xbfb8aa3b, v13
	v_exp_f32_e32 v4, v4
	v_pk_add_f32 v[10:11], v[172:173], v[10:11] op_sel_hi:[0,1]
	v_pk_mul_f32 v[2:3], v[2:3], v[10:11]
	v_add_f32_e32 v4, 1.0, v4
	v_rcp_f32_e32 v15, v4
	s_nop 0
	v_pk_mul_f32 v[10:11], v[14:15], v[12:13]
	s_nop 0
	v_pk_mul_f32 v[10:11], v[10:11], v[2:3]
	v_cvt_f32_f16_e32 v2, v45
	v_cvt_f32_f16_sdwa v3, v45 dst_sel:DWORD dst_unused:UNUSED_PAD src0_sel:WORD_1
	v_cvt_f32_f16_e32 v14, v49
	v_cvt_f32_f16_sdwa v15, v49 dst_sel:DWORD dst_unused:UNUSED_PAD src0_sel:WORD_1
	v_mul_f32_e32 v4, 0x3dd2d3e8, v2
	v_mul_f32_e32 v13, 0x3dd2d3e8, v3
	v_fma_mix_f32 v4, -v4, v45, s9 op_sel_hi:[0,1,0]
	v_fma_mix_f32 v13, -v13, v45, s9 op_sel:[0,1,0] op_sel_hi:[0,1,0]
	v_mul_f32_e32 v4, v4, v2
	v_mul_f32_e32 v13, v13, v3
	v_exp_f32_e32 v4, v4
	v_exp_f32_e32 v13, v13
	v_add_f32_e32 v4, 1.0, v4
	v_add_f32_e32 v13, 1.0, v13
	v_rcp_f32_e32 v12, v4
	v_rcp_f32_e32 v13, v13
	v_mul_f32_e32 v4, 0xbfb8aa3b, v14
	v_exp_f32_e32 v4, v4
	v_pk_mul_f32 v[2:3], v[12:13], v[2:3]
	v_cvt_f32_f16_e32 v12, v5
	v_cvt_f32_f16_sdwa v13, v5 dst_sel:DWORD dst_unused:UNUSED_PAD src0_sel:WORD_1
	v_mul_f32_e32 v5, 0xbfb8aa3b, v15
	v_exp_f32_e32 v5, v5
	v_add_f32_e32 v4, 1.0, v4
	v_rcp_f32_e32 v4, v4
	v_pk_add_f32 v[12:13], v[172:173], v[12:13] op_sel_hi:[0,1]
	v_add_f32_e32 v5, 1.0, v5
	v_rcp_f32_e32 v5, v5
	v_pk_mul_f32 v[2:3], v[2:3], v[12:13]
	v_pk_mul_f32 v[4:5], v[4:5], v[14:15]
	s_nop 0
	v_pk_mul_f32 v[12:13], v[4:5], v[2:3]
	v_cvt_pk_f16_f32 v4, v10, v11
	s_waitcnt vmcnt(10)
	v_cvt_f32_f16_e32 v10, v38
	v_cvt_pk_f16_f32 v2, v6, v7
	v_cvt_pk_f16_f32 v3, v8, v9
	v_lshlrev_b64 v[6:7], 11, v[164:165]
	v_mul_f32_e32 v9, 0xbfb8aa3b, v10
	v_cvt_pk_f16_f32 v5, v12, v13
	v_lshl_add_u64 v[6:7], v[148:149], 0, v[6:7]
	v_exp_f32_e32 v9, v9
	global_store_dwordx4 v[6:7], v[2:5], off sc1
	v_cvt_f32_f16_e32 v6, v34
	v_cvt_f32_f16_sdwa v7, v34 dst_sel:DWORD dst_unused:UNUSED_PAD src0_sel:WORD_1
	v_add_f32_e32 v9, 1.0, v9
	v_rcp_f32_e32 v12, v9
	v_mul_f32_e32 v8, 0x3dd2d3e8, v6
	v_mul_f32_e32 v9, 0x3dd2d3e8, v7
	v_fma_mix_f32 v8, -v8, v34, s9 op_sel_hi:[0,1,0]
	v_fma_mix_f32 v9, -v9, v34, s9 op_sel:[0,1,0] op_sel_hi:[0,1,0]
	v_mul_f32_e32 v8, v8, v6
	v_mul_f32_e32 v9, v9, v7
	v_exp_f32_e32 v8, v8
	v_exp_f32_e32 v9, v9
	ds_read_b128 v[2:5], v0 offset:1152
	v_cvt_f32_f16_sdwa v11, v38 dst_sel:DWORD dst_unused:UNUSED_PAD src0_sel:WORD_1
	v_add_f32_e32 v8, 1.0, v8
	v_add_f32_e32 v9, 1.0, v9
	v_rcp_f32_e32 v8, v8
	v_rcp_f32_e32 v9, v9
	v_or_b32_e32 v164, s2, v106
	v_pk_mul_f32 v[6:7], v[8:9], v[6:7]
	s_waitcnt lgkmcnt(0)
; #define LAS __attribute__((address_space(3)))
; #define GAS __attribute__((address_space(1)))
; __device__ __forceinline__ float siluf(float x) { return x * __builtin_amdgcn_rcpf(1.f + __builtin_amdgcn_exp2f(-1.4426950408889634f * x)); }
; __device__ __forceinline__ float geluf(float x) { return x * __builtin_amdgcn_rcpf(1.f + __builtin_amdgcn_exp2f(x * (-0.10294324f * x * x - 2.3022082f))); }
; __device__ __forceinline__ unsigned cvtpk_h(float lo, float hi) { f32x2 v = {lo, hi}; h16x2 b = __builtin_convertvector(v, h16x2); return __builtin_bit_cast(unsigned, b); }
; __device__ __forceinline__ void gmlp_unit(unsigned char* ws, h16* Y, const h16* Ws16  , const float* bs  , size_t r0, LAS unsigned char* lds, int tid) {
;     ...
; #pragma unroll
;         for (int ps = 0; ps < 4; ++ps) { const int row = 8 * ps + erow;
;             const h16x8 sv = *(const LAS h16x8*)(scr + row * 72 + 8 * ech);
;             float y[8];
; #pragma unroll
;             for (int k = 0; k < 8; ++k) y[k] = geluf((float)gu[q][ps][k]) * ((float)sv[k] + bias[q][ps]) * siluf((float)sz[q][ps][k]);
;             u32x4 w0; w0.x = cvtpk_h(y[0], y[1]); w0.y = cvtpk_h(y[2], y[3]); w0.z = cvtpk_h(y[4], y[5]); w0.w = cvtpk_h(y[6], y[7]);
;             *(GAS u32x4*)(Y + (r0 + 32 * (2 * ph + q) + row) * D + g * 64 + 8 * ech) = w0; }
	v_cvt_f32_f16_e32 v8, v2
	v_cvt_f32_f16_sdwa v9, v2 dst_sel:DWORD dst_unused:UNUSED_PAD src0_sel:WORD_1
	v_mul_f32_e32 v2, 0xbfb8aa3b, v11
	v_exp_f32_e32 v2, v2
	v_pk_add_f32 v[8:9], v[170:171], v[8:9] op_sel_hi:[0,1]
	v_pk_mul_f32 v[6:7], v[6:7], v[8:9]
	v_add_f32_e32 v2, 1.0, v2
	v_rcp_f32_e32 v13, v2
	s_nop 0
	v_pk_mul_f32 v[8:9], v[12:13], v[10:11]
	s_nop 0
	v_pk_mul_f32 v[6:7], v[8:9], v[6:7]
	v_cvt_f32_f16_e32 v8, v35
	v_cvt_f32_f16_sdwa v9, v35 dst_sel:DWORD dst_unused:UNUSED_PAD src0_sel:WORD_1
	v_cvt_f32_f16_e32 v12, v39
	v_cvt_f32_f16_sdwa v13, v39 dst_sel:DWORD dst_unused:UNUSED_PAD src0_sel:WORD_1
	v_mul_f32_e32 v2, 0x3dd2d3e8, v8
	v_mul_f32_e32 v11, 0x3dd2d3e8, v9
	v_fma_mix_f32 v2, -v2, v35, s9 op_sel_hi:[0,1,0]
	v_fma_mix_f32 v11, -v11, v35, s9 op_sel:[0,1,0] op_sel_hi:[0,1,0]
	v_mul_f32_e32 v2, v2, v8
	v_mul_f32_e32 v11, v11, v9
	v_exp_f32_e32 v2, v2
	v_exp_f32_e32 v11, v11
	v_add_f32_e32 v2, 1.0, v2
	v_add_f32_e32 v11, 1.0, v11
	v_rcp_f32_e32 v10, v2
	v_rcp_f32_e32 v11, v11
	v_mul_f32_e32 v2, 0xbfb8aa3b, v12
	v_exp_f32_e32 v2, v2
	v_pk_mul_f32 v[8:9], v[10:11], v[8:9]
	v_cvt_f32_f16_e32 v10, v3
	v_cvt_f32_f16_sdwa v11, v3 dst_sel:DWORD dst_unused:UNUSED_PAD src0_sel:WORD_1
	v_mul_f32_e32 v3, 0xbfb8aa3b, v13
	v_exp_f32_e32 v3, v3
	v_add_f32_e32 v2, 1.0, v2
	v_rcp_f32_e32 v2, v2
	v_pk_add_f32 v[10:11], v[170:171], v[10:11] op_sel_hi:[0,1]
	v_add_f32_e32 v3, 1.0, v3
	v_rcp_f32_e32 v3, v3
	v_pk_mul_f32 v[8:9], v[8:9], v[10:11]
	v_pk_mul_f32 v[2:3], v[2:3], v[12:13]
	v_cvt_f32_f16_e32 v12, v40
	v_pk_mul_f32 v[2:3], v[2:3], v[8:9]
	v_cvt_f32_f16_e32 v8, v36
	v_cvt_f32_f16_sdwa v9, v36 dst_sel:DWORD dst_unused:UNUSED_PAD src0_sel:WORD_1
	v_mul_f32_e32 v11, 0xbfb8aa3b, v12
	v_exp_f32_e32 v11, v11
	v_mul_f32_e32 v10, 0x3dd2d3e8, v8
	v_fma_mix_f32 v10, -v10, v36, s9 op_sel_hi:[0,1,0]
	v_mul_f32_e32 v10, v10, v8
	v_add_f32_e32 v11, 1.0, v11
	v_rcp_f32_e32 v14, v11
	v_mul_f32_e32 v11, 0x3dd2d3e8, v9
	v_fma_mix_f32 v11, -v11, v36, s9 op_sel:[0,1,0] op_sel_hi:[0,1,0]
	v_mul_f32_e32 v11, v11, v9
	v_exp_f32_e32 v10, v10
	v_exp_f32_e32 v11, v11
	v_cvt_f32_f16_sdwa v13, v40 dst_sel:DWORD dst_unused:UNUSED_PAD src0_sel:WORD_1
	v_add_f32_e32 v10, 1.0, v10
	v_add_f32_e32 v11, 1.0, v11
	v_rcp_f32_e32 v10, v10
	v_rcp_f32_e32 v11, v11
	s_nop 0
	v_pk_mul_f32 v[8:9], v[10:11], v[8:9]
	v_cvt_f32_f16_e32 v10, v4
	v_cvt_f32_f16_sdwa v11, v4 dst_sel:DWORD dst_unused:UNUSED_PAD src0_sel:WORD_1
	v_mul_f32_e32 v4, 0xbfb8aa3b, v13
	v_exp_f32_e32 v4, v4
	v_pk_add_f32 v[10:11], v[170:171], v[10:11] op_sel_hi:[0,1]
	v_pk_mul_f32 v[8:9], v[8:9], v[10:11]
	v_add_f32_e32 v4, 1.0, v4
	v_rcp_f32_e32 v15, v4
	s_nop 0
	v_pk_mul_f32 v[10:11], v[14:15], v[12:13]
	s_nop 0
	v_pk_mul_f32 v[8:9], v[10:11], v[8:9]
	v_cvt_f32_f16_e32 v10, v37
	v_cvt_f32_f16_sdwa v11, v37 dst_sel:DWORD dst_unused:UNUSED_PAD src0_sel:WORD_1
	v_cvt_f32_f16_e32 v14, v41
	v_cvt_f32_f16_sdwa v15, v41 dst_sel:DWORD dst_unused:UNUSED_PAD src0_sel:WORD_1
	v_mul_f32_e32 v4, 0x3dd2d3e8, v10
	v_mul_f32_e32 v13, 0x3dd2d3e8, v11
	v_fma_mix_f32 v4, -v4, v37, s9 op_sel_hi:[0,1,0]
	v_fma_mix_f32 v13, -v13, v37, s9 op_sel:[0,1,0] op_sel_hi:[0,1,0]
	v_mul_f32_e32 v4, v4, v10
	v_mul_f32_e32 v13, v13, v11
	v_exp_f32_e32 v4, v4
	v_exp_f32_e32 v13, v13
	v_add_f32_e32 v4, 1.0, v4
	v_add_f32_e32 v13, 1.0, v13
	v_rcp_f32_e32 v12, v4
	v_rcp_f32_e32 v13, v13
	v_mul_f32_e32 v4, 0xbfb8aa3b, v14
	v_exp_f32_e32 v4, v4
	v_pk_mul_f32 v[10:11], v[12:13], v[10:11]
	v_cvt_f32_f16_e32 v12, v5
	v_cvt_f32_f16_sdwa v13, v5 dst_sel:DWORD dst_unused:UNUSED_PAD src0_sel:WORD_1
	v_mul_f32_e32 v5, 0xbfb8aa3b, v15
	v_exp_f32_e32 v5, v5
	v_add_f32_e32 v4, 1.0, v4
	v_rcp_f32_e32 v4, v4
	v_pk_add_f32 v[12:13], v[170:171], v[12:13] op_sel_hi:[0,1]
	v_add_f32_e32 v5, 1.0, v5
	v_rcp_f32_e32 v5, v5
	v_pk_mul_f32 v[10:11], v[10:11], v[12:13]
	v_pk_mul_f32 v[4:5], v[4:5], v[14:15]
	s_nop 0
	v_pk_mul_f32 v[10:11], v[4:5], v[10:11]
	v_cvt_pk_f16_f32 v4, v6, v7
	v_cvt_pk_f16_f32 v7, v10, v11
	s_waitcnt vmcnt(8)
	v_cvt_f32_f16_e32 v10, v30
	v_cvt_pk_f16_f32 v5, v2, v3
	v_cvt_pk_f16_f32 v6, v8, v9
	v_lshlrev_b64 v[2:3], 11, v[164:165]
	v_mul_f32_e32 v9, 0xbfb8aa3b, v10
	v_lshl_add_u64 v[2:3], v[148:149], 0, v[2:3]
	v_exp_f32_e32 v9, v9
	global_store_dwordx4 v[2:3], v[4:7], off sc1
	ds_read_b128 v[2:5], v0 offset:2304
	v_cvt_f32_f16_sdwa v11, v30 dst_sel:DWORD dst_unused:UNUSED_PAD src0_sel:WORD_1
	v_cvt_f32_f16_e32 v6, v26
	v_cvt_f32_f16_sdwa v7, v26 dst_sel:DWORD dst_unused:UNUSED_PAD src0_sel:WORD_1
	v_add_f32_e32 v9, 1.0, v9
	v_rcp_f32_e32 v12, v9
	v_mul_f32_e32 v8, 0x3dd2d3e8, v6
	v_mul_f32_e32 v9, 0x3dd2d3e8, v7
	v_fma_mix_f32 v8, -v8, v26, s9 op_sel_hi:[0,1,0]
	v_fma_mix_f32 v9, -v9, v26, s9 op_sel:[0,1,0] op_sel_hi:[0,1,0]
	v_mul_f32_e32 v8, v8, v6
	v_mul_f32_e32 v9, v9, v7
	v_exp_f32_e32 v8, v8
	v_exp_f32_e32 v9, v9
	v_or_b32_e32 v164, s2, v98
	v_add_f32_e32 v8, 1.0, v8
	v_add_f32_e32 v9, 1.0, v9
	v_rcp_f32_e32 v8, v8
	v_rcp_f32_e32 v9, v9
	s_nop 0
	v_pk_mul_f32 v[6:7], v[8:9], v[6:7]
	s_waitcnt lgkmcnt(0)
; #define LAS __attribute__((address_space(3)))
; #define GAS __attribute__((address_space(1)))
; __device__ __forceinline__ float siluf(float x) { return x * __builtin_amdgcn_rcpf(1.f + __builtin_amdgcn_exp2f(-1.4426950408889634f * x)); }
; __device__ __forceinline__ float geluf(float x) { return x * __builtin_amdgcn_rcpf(1.f + __builtin_amdgcn_exp2f(x * (-0.10294324f * x * x - 2.3022082f))); }
; __device__ __forceinline__ unsigned cvtpk_h(float lo, float hi) { f32x2 v = {lo, hi}; h16x2 b = __builtin_convertvector(v, h16x2); return __builtin_bit_cast(unsigned, b); }
; __device__ __forceinline__ void gmlp_unit(unsigned char* ws, h16* Y, const h16* Ws16  , const float* bs  , size_t r0, LAS unsigned char* lds, int tid) {
;     ...
; #pragma unroll
;         for (int ps = 0; ps < 4; ++ps) { const int row = 8 * ps + erow;
;             const h16x8 sv = *(const LAS h16x8*)(scr + row * 72 + 8 * ech);
;             float y[8];
; #pragma unroll
;             for (int k = 0; k < 8; ++k) y[k] = geluf((float)gu[q][ps][k]) * ((float)sv[k] + bias[q][ps]) * siluf((float)sz[q][ps][k]);
;             u32x4 w0; w0.x = cvtpk_h(y[0], y[1]); w0.y = cvtpk_h(y[2], y[3]); w0.z = cvtpk_h(y[4], y[5]); w0.w = cvtpk_h(y[6], y[7]);
;             *(GAS u32x4*)(Y + (r0 + 32 * (2 * ph + q) + row) * D + g * 64 + 8 * ech) = w0; }
	v_cvt_f32_f16_e32 v8, v2
	v_cvt_f32_f16_sdwa v9, v2 dst_sel:DWORD dst_unused:UNUSED_PAD src0_sel:WORD_1
	v_mul_f32_e32 v2, 0xbfb8aa3b, v11
	v_exp_f32_e32 v2, v2
	v_pk_add_f32 v[8:9], v[168:169], v[8:9] op_sel_hi:[0,1]
	v_pk_mul_f32 v[6:7], v[6:7], v[8:9]
	v_add_f32_e32 v2, 1.0, v2
	v_rcp_f32_e32 v13, v2
	s_nop 0
	v_pk_mul_f32 v[8:9], v[12:13], v[10:11]
	s_nop 0
	v_pk_mul_f32 v[6:7], v[8:9], v[6:7]
	v_cvt_f32_f16_e32 v8, v27
	v_cvt_f32_f16_sdwa v9, v27 dst_sel:DWORD dst_unused:UNUSED_PAD src0_sel:WORD_1
	v_cvt_f32_f16_e32 v12, v31
	v_cvt_f32_f16_sdwa v13, v31 dst_sel:DWORD dst_unused:UNUSED_PAD src0_sel:WORD_1
	v_mul_f32_e32 v2, 0x3dd2d3e8, v8
	v_mul_f32_e32 v11, 0x3dd2d3e8, v9
	v_fma_mix_f32 v2, -v2, v27, s9 op_sel_hi:[0,1,0]
	v_fma_mix_f32 v11, -v11, v27, s9 op_sel:[0,1,0] op_sel_hi:[0,1,0]
	v_mul_f32_e32 v2, v2, v8
	v_mul_f32_e32 v11, v11, v9
	v_exp_f32_e32 v2, v2
	v_exp_f32_e32 v11, v11
	v_add_f32_e32 v2, 1.0, v2
	v_add_f32_e32 v11, 1.0, v11
	v_rcp_f32_e32 v10, v2
	v_rcp_f32_e32 v11, v11
	v_mul_f32_e32 v2, 0xbfb8aa3b, v12
	v_exp_f32_e32 v2, v2
	v_pk_mul_f32 v[8:9], v[10:11], v[8:9]
	v_cvt_f32_f16_e32 v10, v3
	v_cvt_f32_f16_sdwa v11, v3 dst_sel:DWORD dst_unused:UNUSED_PAD src0_sel:WORD_1
	v_mul_f32_e32 v3, 0xbfb8aa3b, v13
	v_exp_f32_e32 v3, v3
	v_add_f32_e32 v2, 1.0, v2
	v_rcp_f32_e32 v2, v2
	v_pk_add_f32 v[10:11], v[168:169], v[10:11] op_sel_hi:[0,1]
	v_add_f32_e32 v3, 1.0, v3
	v_rcp_f32_e32 v3, v3
	v_pk_mul_f32 v[8:9], v[8:9], v[10:11]
	v_pk_mul_f32 v[2:3], v[2:3], v[12:13]
	v_cvt_f32_f16_e32 v12, v32
	v_pk_mul_f32 v[8:9], v[2:3], v[8:9]
	v_cvt_f32_f16_e32 v2, v28
	v_cvt_f32_f16_sdwa v3, v28 dst_sel:DWORD dst_unused:UNUSED_PAD src0_sel:WORD_1
	v_mul_f32_e32 v11, 0xbfb8aa3b, v12
	v_exp_f32_e32 v11, v11
	v_mul_f32_e32 v10, 0x3dd2d3e8, v2
	v_fma_mix_f32 v10, -v10, v28, s9 op_sel_hi:[0,1,0]
	v_mul_f32_e32 v10, v10, v2
	v_add_f32_e32 v11, 1.0, v11
	v_rcp_f32_e32 v14, v11
	v_mul_f32_e32 v11, 0x3dd2d3e8, v3
	v_fma_mix_f32 v11, -v11, v28, s9 op_sel:[0,1,0] op_sel_hi:[0,1,0]
	v_mul_f32_e32 v11, v11, v3
	v_exp_f32_e32 v10, v10
	v_exp_f32_e32 v11, v11
	v_cvt_f32_f16_sdwa v13, v32 dst_sel:DWORD dst_unused:UNUSED_PAD src0_sel:WORD_1
	v_add_f32_e32 v10, 1.0, v10
	v_add_f32_e32 v11, 1.0, v11
	v_rcp_f32_e32 v10, v10
	v_rcp_f32_e32 v11, v11
	s_nop 0
	v_pk_mul_f32 v[2:3], v[10:11], v[2:3]
	v_cvt_f32_f16_e32 v10, v4
	v_cvt_f32_f16_sdwa v11, v4 dst_sel:DWORD dst_unused:UNUSED_PAD src0_sel:WORD_1
	v_mul_f32_e32 v4, 0xbfb8aa3b, v13
	v_exp_f32_e32 v4, v4
	v_pk_add_f32 v[10:11], v[168:169], v[10:11] op_sel_hi:[0,1]
	v_pk_mul_f32 v[2:3], v[2:3], v[10:11]
	v_add_f32_e32 v4, 1.0, v4
	v_rcp_f32_e32 v15, v4
	s_nop 0
	v_pk_mul_f32 v[10:11], v[14:15], v[12:13]
	s_nop 0
	v_pk_mul_f32 v[10:11], v[10:11], v[2:3]
	v_cvt_f32_f16_e32 v2, v29
	v_cvt_f32_f16_sdwa v3, v29 dst_sel:DWORD dst_unused:UNUSED_PAD src0_sel:WORD_1
	v_cvt_f32_f16_e32 v14, v33
	v_cvt_f32_f16_sdwa v15, v33 dst_sel:DWORD dst_unused:UNUSED_PAD src0_sel:WORD_1
	v_mul_f32_e32 v4, 0x3dd2d3e8, v2
	v_mul_f32_e32 v13, 0x3dd2d3e8, v3
	v_fma_mix_f32 v4, -v4, v29, s9 op_sel_hi:[0,1,0]
	v_fma_mix_f32 v13, -v13, v29, s9 op_sel:[0,1,0] op_sel_hi:[0,1,0]
	v_mul_f32_e32 v4, v4, v2
	v_mul_f32_e32 v13, v13, v3
	v_exp_f32_e32 v4, v4
	v_exp_f32_e32 v13, v13
	v_add_f32_e32 v4, 1.0, v4
	v_add_f32_e32 v13, 1.0, v13
	v_rcp_f32_e32 v12, v4
	v_rcp_f32_e32 v13, v13
	v_mul_f32_e32 v4, 0xbfb8aa3b, v14
	v_exp_f32_e32 v4, v4
	v_pk_mul_f32 v[2:3], v[12:13], v[2:3]
	v_cvt_f32_f16_e32 v12, v5
	v_cvt_f32_f16_sdwa v13, v5 dst_sel:DWORD dst_unused:UNUSED_PAD src0_sel:WORD_1
	v_mul_f32_e32 v5, 0xbfb8aa3b, v15
	v_exp_f32_e32 v5, v5
	v_add_f32_e32 v4, 1.0, v4
	v_rcp_f32_e32 v4, v4
	v_pk_add_f32 v[12:13], v[168:169], v[12:13] op_sel_hi:[0,1]
	v_add_f32_e32 v5, 1.0, v5
	v_rcp_f32_e32 v5, v5
	v_pk_mul_f32 v[2:3], v[2:3], v[12:13]
	v_pk_mul_f32 v[4:5], v[4:5], v[14:15]
	s_nop 0
	v_pk_mul_f32 v[12:13], v[4:5], v[2:3]
	v_cvt_pk_f16_f32 v2, v6, v7
	v_lshlrev_b64 v[6:7], 11, v[164:165]
	v_cvt_pk_f16_f32 v3, v8, v9
	v_cvt_pk_f16_f32 v4, v10, v11
	v_cvt_pk_f16_f32 v5, v12, v13
	v_lshl_add_u64 v[6:7], v[148:149], 0, v[6:7]
	global_store_dwordx4 v[6:7], v[2:5], off sc1
	s_waitcnt vmcnt(8)
	v_cvt_f32_f16_e32 v6, v18
	ds_read_b128 v[2:5], v0 offset:3456
	s_waitcnt vmcnt(7)
; #define LAS __attribute__((address_space(3)))
; #define GAS __attribute__((address_space(1)))
; __device__ __forceinline__ float siluf(float x) { return x * __builtin_amdgcn_rcpf(1.f + __builtin_amdgcn_exp2f(-1.4426950408889634f * x)); }
; __device__ __forceinline__ float geluf(float x) { return x * __builtin_amdgcn_rcpf(1.f + __builtin_amdgcn_exp2f(x * (-0.10294324f * x * x - 2.3022082f))); }
; __device__ __forceinline__ unsigned cvtpk_h(float lo, float hi) { f32x2 v = {lo, hi}; h16x2 b = __builtin_convertvector(v, h16x2); return __builtin_bit_cast(unsigned, b); }
; #define LDS_WAIT() asm volatile("s_waitcnt lgkmcnt(0)" ::: "memory")
; #define BAR_LDS() asm volatile("s_waitcnt lgkmcnt(0)\n\ts_barrier" ::: "memory")
; __device__ __forceinline__ void gmlp_unit(unsigned char* ws, h16* Y, const h16* Ws16  , const float* bs  , size_t r0, LAS unsigned char* lds, int tid) {
;     ...
; #pragma unroll
;         for (int ps = 0; ps < 4; ++ps) { const int row = 8 * ps + erow;
;             const h16x8 sv = *(const LAS h16x8*)(scr + row * 72 + 8 * ech);
;             float y[8];
; #pragma unroll
;             for (int k = 0; k < 8; ++k) y[k] = geluf((float)gu[q][ps][k]) * ((float)sv[k] + bias[q][ps]) * siluf((float)sz[q][ps][k]);
;             u32x4 w0; w0.x = cvtpk_h(y[0], y[1]); w0.y = cvtpk_h(y[2], y[3]); w0.z = cvtpk_h(y[4], y[5]); w0.w = cvtpk_h(y[6], y[7]);
;             *(GAS u32x4*)(Y + (r0 + 32 * (2 * ph + q) + row) * D + g * 64 + 8 * ech) = w0; }
;         LDS_WAIT();
;     }
;     BAR_LDS();
	v_cvt_f32_f16_e32 v10, v22
	v_cvt_f32_f16_sdwa v7, v18 dst_sel:DWORD dst_unused:UNUSED_PAD src0_sel:WORD_1
	v_mul_f32_e32 v0, 0x3dd2d3e8, v6
	v_fma_mix_f32 v0, -v0, v18, s9 op_sel_hi:[0,1,0]
	v_mul_f32_e32 v0, v0, v6
	v_exp_f32_e32 v0, v0
	v_cvt_f32_f16_sdwa v11, v22 dst_sel:DWORD dst_unused:UNUSED_PAD src0_sel:WORD_1
	v_or_b32_e32 v164, s2, v90
	s_mov_b64 s[2:3], 0
	v_add_f32_e32 v0, 1.0, v0
	v_rcp_f32_e32 v8, v0
	v_mul_f32_e32 v0, 0xbfb8aa3b, v10
	v_exp_f32_e32 v0, v0
	s_nop 0
	v_add_f32_e32 v0, 1.0, v0
	v_rcp_f32_e32 v12, v0
	v_mul_f32_e32 v0, 0x3dd2d3e8, v7
	v_fma_mix_f32 v0, -v0, v18, s9 op_sel:[0,1,0] op_sel_hi:[0,1,0]
	v_mul_f32_e32 v0, v0, v7
	v_exp_f32_e32 v0, v0
	s_nop 0
	v_add_f32_e32 v0, 1.0, v0
	v_rcp_f32_e32 v9, v0
	v_mul_f32_e32 v0, 0xbfb8aa3b, v11
	v_exp_f32_e32 v0, v0
	v_pk_mul_f32 v[6:7], v[8:9], v[6:7]
	s_waitcnt lgkmcnt(0)
	v_cvt_f32_f16_e32 v8, v2
	v_cvt_f32_f16_sdwa v9, v2 dst_sel:DWORD dst_unused:UNUSED_PAD src0_sel:WORD_1
	v_add_f32_e32 v0, 1.0, v0
	v_rcp_f32_e32 v13, v0
	v_pk_add_f32 v[8:9], v[166:167], v[8:9] op_sel_hi:[0,1]
	v_pk_mul_f32 v[6:7], v[6:7], v[8:9]
	v_pk_mul_f32 v[8:9], v[12:13], v[10:11]
	v_cvt_f32_f16_e32 v12, v23
	v_pk_mul_f32 v[6:7], v[8:9], v[6:7]
	v_cvt_f32_f16_e32 v8, v19
	v_cvt_f32_f16_sdwa v9, v19 dst_sel:DWORD dst_unused:UNUSED_PAD src0_sel:WORD_1
	v_cvt_f32_f16_sdwa v13, v23 dst_sel:DWORD dst_unused:UNUSED_PAD src0_sel:WORD_1
	v_mul_f32_e32 v0, 0x3dd2d3e8, v8
	v_fma_mix_f32 v0, -v0, v19, s9 op_sel_hi:[0,1,0]
	v_mul_f32_e32 v0, v0, v8
	v_exp_f32_e32 v0, v0
	s_nop 0
	v_add_f32_e32 v0, 1.0, v0
	v_rcp_f32_e32 v10, v0
	v_mul_f32_e32 v0, 0xbfb8aa3b, v12
	v_exp_f32_e32 v0, v0
	s_nop 0
	v_add_f32_e32 v0, 1.0, v0
	v_rcp_f32_e32 v2, v0
	v_mul_f32_e32 v0, 0x3dd2d3e8, v9
	v_fma_mix_f32 v0, -v0, v19, s9 op_sel:[0,1,0] op_sel_hi:[0,1,0]
	v_mul_f32_e32 v0, v0, v9
	v_exp_f32_e32 v0, v0
	s_nop 0
	v_add_f32_e32 v0, 1.0, v0
	v_rcp_f32_e32 v11, v0
	v_mul_f32_e32 v0, 0xbfb8aa3b, v13
	v_exp_f32_e32 v0, v0
	v_pk_mul_f32 v[8:9], v[10:11], v[8:9]
	v_cvt_f32_f16_e32 v10, v3
	v_cvt_f32_f16_sdwa v11, v3 dst_sel:DWORD dst_unused:UNUSED_PAD src0_sel:WORD_1
	v_add_f32_e32 v0, 1.0, v0
	v_rcp_f32_e32 v3, v0
	v_pk_add_f32 v[10:11], v[166:167], v[10:11] op_sel_hi:[0,1]
	v_pk_mul_f32 v[8:9], v[8:9], v[10:11]
	v_pk_mul_f32 v[2:3], v[2:3], v[12:13]
	v_cvt_f32_f16_e32 v12, v24
	v_pk_mul_f32 v[2:3], v[2:3], v[8:9]
	v_cvt_f32_f16_e32 v8, v20
	v_cvt_f32_f16_sdwa v9, v20 dst_sel:DWORD dst_unused:UNUSED_PAD src0_sel:WORD_1
	v_cvt_f32_f16_sdwa v13, v24 dst_sel:DWORD dst_unused:UNUSED_PAD src0_sel:WORD_1
	v_mul_f32_e32 v0, 0x3dd2d3e8, v8
	v_fma_mix_f32 v0, -v0, v20, s9 op_sel_hi:[0,1,0]
	v_mul_f32_e32 v0, v0, v8
	v_exp_f32_e32 v0, v0
	s_nop 0
	v_add_f32_e32 v0, 1.0, v0
	v_rcp_f32_e32 v10, v0
	v_mul_f32_e32 v0, 0xbfb8aa3b, v12
	v_exp_f32_e32 v0, v0
	s_nop 0
	v_add_f32_e32 v0, 1.0, v0
	v_rcp_f32_e32 v14, v0
	v_mul_f32_e32 v0, 0x3dd2d3e8, v9
	v_fma_mix_f32 v0, -v0, v20, s9 op_sel:[0,1,0] op_sel_hi:[0,1,0]
	v_mul_f32_e32 v0, v0, v9
	v_exp_f32_e32 v0, v0
	s_nop 0
	v_add_f32_e32 v0, 1.0, v0
	v_rcp_f32_e32 v11, v0
	v_mul_f32_e32 v0, 0xbfb8aa3b, v13
	v_exp_f32_e32 v0, v0
	v_pk_mul_f32 v[8:9], v[10:11], v[8:9]
	v_cvt_f32_f16_e32 v10, v4
	v_cvt_f32_f16_sdwa v11, v4 dst_sel:DWORD dst_unused:UNUSED_PAD src0_sel:WORD_1
	v_add_f32_e32 v0, 1.0, v0
	v_rcp_f32_e32 v15, v0
	v_pk_add_f32 v[10:11], v[166:167], v[10:11] op_sel_hi:[0,1]
	v_pk_mul_f32 v[8:9], v[8:9], v[10:11]
	v_pk_mul_f32 v[10:11], v[14:15], v[12:13]
	v_cvt_f32_f16_e32 v14, v25
	v_pk_mul_f32 v[8:9], v[10:11], v[8:9]
	v_cvt_f32_f16_e32 v10, v21
	v_cvt_f32_f16_sdwa v11, v21 dst_sel:DWORD dst_unused:UNUSED_PAD src0_sel:WORD_1
	v_cvt_f32_f16_sdwa v15, v25 dst_sel:DWORD dst_unused:UNUSED_PAD src0_sel:WORD_1
	v_mul_f32_e32 v0, 0x3dd2d3e8, v10
	v_fma_mix_f32 v0, -v0, v21, s9 op_sel_hi:[0,1,0]
	v_mul_f32_e32 v0, v0, v10
	v_exp_f32_e32 v0, v0
	s_nop 0
	v_add_f32_e32 v0, 1.0, v0
	v_rcp_f32_e32 v12, v0
	v_mul_f32_e32 v0, 0xbfb8aa3b, v14
	v_exp_f32_e32 v0, v0
	s_nop 0
	v_add_f32_e32 v0, 1.0, v0
	v_rcp_f32_e32 v4, v0
	v_mul_f32_e32 v0, 0x3dd2d3e8, v11
	v_fma_mix_f32 v0, -v0, v21, s9 op_sel:[0,1,0] op_sel_hi:[0,1,0]
	v_mul_f32_e32 v0, v0, v11
	v_exp_f32_e32 v0, v0
	s_nop 0
	v_add_f32_e32 v0, 1.0, v0
	v_rcp_f32_e32 v13, v0
	v_mul_f32_e32 v0, 0xbfb8aa3b, v15
	v_exp_f32_e32 v0, v0
	v_pk_mul_f32 v[10:11], v[12:13], v[10:11]
	v_cvt_f32_f16_e32 v12, v5
	v_cvt_f32_f16_sdwa v13, v5 dst_sel:DWORD dst_unused:UNUSED_PAD src0_sel:WORD_1
	v_add_f32_e32 v0, 1.0, v0
	v_rcp_f32_e32 v5, v0
	v_pk_add_f32 v[12:13], v[166:167], v[12:13] op_sel_hi:[0,1]
	v_pk_mul_f32 v[10:11], v[10:11], v[12:13]
	v_pk_mul_f32 v[4:5], v[4:5], v[14:15]
	s_nop 0
	v_pk_mul_f32 v[10:11], v[4:5], v[10:11]
	v_cvt_pk_f16_f32 v5, v2, v3
	v_lshlrev_b64 v[2:3], 11, v[164:165]
	v_cvt_pk_f16_f32 v4, v6, v7
	v_cvt_pk_f16_f32 v6, v8, v9
	v_cvt_pk_f16_f32 v7, v10, v11
	v_lshl_add_u64 v[2:3], v[148:149], 0, v[2:3]
	global_store_dwordx4 v[2:3], v[4:7], off sc1
	s_waitcnt lgkmcnt(0)
	s_waitcnt lgkmcnt(0)
	s_barrier

; #define SBAR() __builtin_amdgcn_sched_barrier(0)
; #define RESC() do { if (!FIXM && resc) { asm volatile("s_waitcnt lgkmcnt(0)" ::: "memory"); \
;       _Pragma("unroll") for (int d_ = 0; d_ < 2; ++d_) _Pragma("unroll") for (int r = 0; r < 16; ++r) o[d_][r] *= wsf[crow(r, hi)]; } } while (0)
; #define PKW(P, B) cvtpk_h(P[B], P[B + 1])
; #define PKW(P, B) cvtpk_h(P[B], P[B + 1])
; template <int THRL, bool FIXM> __device__ __forceinline__ bool attn_unit(const h16* Qrows, const h16* __restrict__ Kh, const h16* __restrict__ Vh, const int NT, h16* Yrows, const h16* BZrows, char* shm, const int tid, const float mfix, ...
;     ...
;   STEP(pB0, pB1, pA0, pA1, NT - 1, false, false, false); RESC();
;   { float sacc = pB0[0] + pB0[1]; _Pragma("unroll") for (int r = 2; r < 16; ++r) sacc += pB0[r]; _Pragma("unroll") for (int r = 0; r < 16; ++r) sacc += pB1[r]; l_reg += sacc;
;     pw0 = (u32x4){PKW(pB0, 0), PKW(pB0, 2), PKW(pB0, 4), PKW(pB0, 6)}; pw1 = (u32x4){PKW(pB0, 8), PKW(pB0, 10), PKW(pB0, 12), PKW(pB0, 14)}; pw2 = (u32x4){PKW(pB1, 0), PKW(pB1, 2), PKW(pB1, 4), PKW(pB1, 6)}; pw3 = (u32x4){PKW(pB1, 8), PKW(pB1, 10), PKW(pB1, 12), PKW(pB1, 14)};
;     SBAR(); pv(o, vb0 + sl_cur, __builtin_bit_cast(s16x8, pw0), __builtin_bit_cast(s16x8, pw1), __builtin_bit_cast(s16x8, pw2), __builtin_bit_cast(s16x8, pw3)); }
.LBB0_124:
	s_and_b32 s12, s29, 0x3fffffc0
	s_lshl_b32 s12, s12, 2
	s_add_i32 s14, s41, s12
	v_add_u32_e32 v0, s51, v233
	ds_read_b64_tr_b16 v[52:53], v0 offset:24576
	ds_read_b64_tr_b16 v[54:55], v0 offset:25088
	v_add_f32_e32 v51, v82, v83
	v_add_f32_e32 v51, v84, v51
	v_add_f32_e32 v51, v85, v51
	v_add_f32_e32 v51, v86, v51
	v_add_f32_e32 v51, v87, v51
	v_cvt_pk_f16_f32 v160, v82, v83
	v_cvt_pk_f16_f32 v161, v84, v85
	s_waitcnt lgkmcnt(9)
	v_mfma_f32_32x32x16_f16 v[98:113], v[192:195], v[144:147], v[2:17]
	ds_read_b64_tr_b16 v[56:57], v0 offset:28672
	ds_read_b64_tr_b16 v[58:59], v0 offset:29184
	s_waitcnt lgkmcnt(10)
	v_mfma_f32_32x32x16_f16 v[2:17], v[188:191], v[144:147], v[2:17]
	v_add_f32_e32 v51, v88, v51
	v_add_f32_e32 v51, v89, v51
	v_add_f32_e32 v51, v90, v51
	v_add_f32_e32 v51, v91, v51
	v_cvt_pk_f16_f32 v162, v86, v87
	v_cvt_pk_f16_f32 v163, v88, v89
	ds_read_b64_tr_b16 v[60:61], v0 offset:25600
	ds_read_b64_tr_b16 v[62:63], v0 offset:26112
	v_add_f32_e32 v51, v92, v51
	v_add_f32_e32 v51, v93, v51
	v_add_f32_e32 v51, v94, v51
	v_add_f32_e32 v51, v95, v51
	v_cvt_pk_f16_f32 v156, v90, v91
	v_cvt_pk_f16_f32 v157, v92, v93
	s_waitcnt lgkmcnt(11)
	v_mfma_f32_32x32x16_f16 v[98:113], v[184:187], v[140:143], v[98:113]
	ds_read_b64_tr_b16 v[82:83], v0 offset:29696
	ds_read_b64_tr_b16 v[84:85], v0 offset:30208
	s_waitcnt lgkmcnt(12)
	v_mfma_f32_32x32x16_f16 v[2:17], v[180:183], v[140:143], v[2:17]
	v_add_f32_e32 v51, v96, v51
	v_add_f32_e32 v51, v97, v51
	v_add_f32_e32 v51, v66, v51
	v_add_f32_e32 v51, v67, v51
	v_cvt_pk_f16_f32 v158, v94, v95
	v_cvt_pk_f16_f32 v159, v96, v97
	ds_read_b64_tr_b16 v[86:87], v0 offset:26624
	ds_read_b64_tr_b16 v[88:89], v0 offset:27136
	v_add_f32_e32 v51, v68, v51
	v_add_f32_e32 v51, v69, v51
	v_add_f32_e32 v51, v70, v51
	v_add_f32_e32 v51, v71, v51
	v_cvt_pk_f16_f32 v152, v66, v67
	v_cvt_pk_f16_f32 v153, v68, v69
	s_waitcnt lgkmcnt(13)
	v_mfma_f32_32x32x16_f16 v[98:113], v[176:179], v[136:139], v[98:113]
	ds_read_b64_tr_b16 v[64:65], v0 offset:30720
	ds_read_b64_tr_b16 v[66:67], v0 offset:31232
	s_waitcnt lgkmcnt(14)
	v_mfma_f32_32x32x16_f16 v[2:17], v[172:175], v[136:139], v[2:17]
	v_add_f32_e32 v51, v72, v51
	v_add_f32_e32 v51, v73, v51
	v_add_f32_e32 v51, v74, v51
	v_add_f32_e32 v51, v75, v51
	v_cvt_pk_f16_f32 v154, v70, v71
	v_cvt_pk_f16_f32 v155, v72, v73
	ds_read_b64_tr_b16 v[68:69], v0 offset:27648
	ds_read_b64_tr_b16 v[70:71], v0 offset:28160
	v_add_f32_e32 v51, v76, v51
	v_add_f32_e32 v51, v77, v51
	v_add_f32_e32 v51, v78, v51
	v_add_f32_e32 v51, v79, v51
	v_cvt_pk_f16_f32 v148, v74, v75
	v_cvt_pk_f16_f32 v149, v76, v77
	s_waitcnt lgkmcnt(14)
	v_mfma_f32_32x32x16_f16 v[98:113], v[168:171], v[132:135], v[98:113]
	ds_read_b64_tr_b16 v[72:73], v0 offset:31744
	ds_read_b64_tr_b16 v[74:75], v0 offset:32256
	v_mfma_f32_32x32x16_f16 v[2:17], v[164:167], v[132:135], v[2:17]
	v_add_f32_e32 v0, v80, v51
	v_add_f32_e32 v0, v81, v0
	v_add_f32_e32 v0, 0, v0
	v_cvt_pk_f16_f32 v150, v78, v79
	v_cvt_pk_f16_f32 v151, v80, v81
	s_waitcnt lgkmcnt(14)
	v_mfma_f32_32x32x16_f16 v[18:33], v[160:163], v[52:55], v[18:33]
	s_nop 1
	v_exp_f32_e32 v98, v98
	v_exp_f32_e32 v99, v99
	v_exp_f32_e32 v100, v100
	v_exp_f32_e32 v101, v101
	s_waitcnt lgkmcnt(12)
	v_mfma_f32_32x32x16_f16 v[34:49], v[160:163], v[56:59], v[34:49]
	v_exp_f32_e32 v102, v102
	v_exp_f32_e32 v103, v103
	v_exp_f32_e32 v104, v104
	v_exp_f32_e32 v105, v105
	s_waitcnt lgkmcnt(10)
	v_mfma_f32_32x32x16_f16 v[18:33], v[156:159], v[60:63], v[18:33]
	v_exp_f32_e32 v106, v106
	v_exp_f32_e32 v107, v107
	v_exp_f32_e32 v108, v108
	v_exp_f32_e32 v109, v109
	s_waitcnt lgkmcnt(8)
	v_mfma_f32_32x32x16_f16 v[34:49], v[156:159], v[82:85], v[34:49]
	v_exp_f32_e32 v110, v110
	v_exp_f32_e32 v111, v111
	v_exp_f32_e32 v112, v112
	v_exp_f32_e32 v113, v113
	s_waitcnt lgkmcnt(6)
	v_mfma_f32_32x32x16_f16 v[18:33], v[152:155], v[86:89], v[18:33]
	v_exp_f32_e32 v2, v2
	v_exp_f32_e32 v3, v3
	v_exp_f32_e32 v4, v4
	v_exp_f32_e32 v5, v5
	s_waitcnt lgkmcnt(4)
	v_mfma_f32_32x32x16_f16 v[34:49], v[152:155], v[64:67], v[34:49]
	v_exp_f32_e32 v6, v6
	v_exp_f32_e32 v7, v7
	v_exp_f32_e32 v8, v8
	v_exp_f32_e32 v9, v9
	s_waitcnt lgkmcnt(2)
	v_mfma_f32_32x32x16_f16 v[18:33], v[148:151], v[68:71], v[18:33]
	v_exp_f32_e32 v10, v10
	v_exp_f32_e32 v11, v11
	v_exp_f32_e32 v12, v12
	v_exp_f32_e32 v13, v13
	s_waitcnt lgkmcnt(0)
	v_mfma_f32_32x32x16_f16 v[34:49], v[148:151], v[72:75], v[34:49]
	v_exp_f32_e32 v14, v14
	v_exp_f32_e32 v15, v15
	v_exp_f32_e32 v16, v16
	v_exp_f32_e32 v17, v17
	v_add_f32_e32 v51, v98, v99
	v_add_f32_e32 v51, v100, v51
	v_add_f32_e32 v51, v101, v51
	v_add_f32_e32 v51, v102, v51
	v_add_f32_e32 v51, v103, v51
	v_add_f32_e32 v51, v104, v51
	v_add_f32_e32 v51, v105, v51
	v_add_f32_e32 v51, v106, v51
	v_add_f32_e32 v51, v107, v51
	v_add_f32_e32 v51, v108, v51
	v_add_f32_e32 v51, v109, v51
	v_add_f32_e32 v51, v110, v51
	v_add_f32_e32 v51, v111, v51
	v_add_f32_e32 v51, v112, v51
	v_add_f32_e32 v82, v113, v51
	v_add_f32_e32 v83, v50, v0
	v_cvt_pk_f16_f32 v50, v98, v99
	v_cvt_pk_f16_f32 v51, v100, v101
	v_cvt_pk_f16_f32 v52, v102, v103
	v_cvt_pk_f16_f32 v53, v104, v105
	v_cvt_pk_f16_f32 v54, v106, v107
	v_cvt_pk_f16_f32 v55, v108, v109
	v_cvt_pk_f16_f32 v56, v110, v111
	v_cvt_pk_f16_f32 v57, v112, v113
	v_cvt_pk_f16_f32 v66, v2, v3
	v_cvt_pk_f16_f32 v67, v4, v5
	v_cvt_pk_f16_f32 v68, v6, v7
	v_cvt_pk_f16_f32 v69, v8, v9
	v_cvt_pk_f16_f32 v70, v10, v11
	v_cvt_pk_f16_f32 v71, v12, v13
	v_cvt_pk_f16_f32 v72, v14, v15
	v_cvt_pk_f16_f32 v73, v16, v17
	v_or3_b32 v0, v243, v232, v231
	s_add_i32 s12, s77, s17
	v_add_u32_e32 v0, s12, v0
	ds_read_b64_tr_b16 v[58:59],v0 offset:0
	ds_read_b64_tr_b16 v[60:61],v0 offset:512
	ds_read_b64_tr_b16 v[62:63],v0 offset:1024
	ds_read_b64_tr_b16 v[64:65],v0 offset:1536
	ds_read_b64_tr_b16 v[74:75],v0 offset:2048
	ds_read_b64_tr_b16 v[76:77],v0 offset:2560
	ds_read_b64_tr_b16 v[78:79],v0 offset:3072
	ds_read_b64_tr_b16 v[80:81],v0 offset:3584
	s_waitcnt lgkmcnt(0)
; #define GAS __attribute__((address_space(1)))
; __device__ __forceinline__ int crow(int r, int hi) { return (r & 3) + 8 * (r >> 2) + 4 * hi; }
; #define SBAR() __builtin_amdgcn_sched_barrier(0)
; #define RESC() do { if (!FIXM && resc) { asm volatile("s_waitcnt lgkmcnt(0)" ::: "memory"); \
;       _Pragma("unroll") for (int d_ = 0; d_ < 2; ++d_) _Pragma("unroll") for (int r = 0; r < 16; ++r) o[d_][r] *= wsf[crow(r, hi)]; } } while (0)
; #define PKW(P, B) cvtpk_h(P[B], P[B + 1])
; #define PKW(P, B) cvtpk_h(P[B], P[B + 1])
; template <int THRL, bool FIXM> __device__ __forceinline__ bool attn_unit(const h16* Qrows, const h16* __restrict__ Kh, const h16* __restrict__ Vh, const int NT, h16* Yrows, const h16* BZrows, char* shm, const int tid, const float mfix, ...
;     ...
;   STEP(pB0, pB1, pA0, pA1, NT - 1, false, false, false); RESC();
;   { float sacc = pB0[0] + pB0[1]; _Pragma("unroll") for (int r = 2; r < 16; ++r) sacc += pB0[r]; _Pragma("unroll") for (int r = 0; r < 16; ++r) sacc += pB1[r]; l_reg += sacc;
;     pw0 = (u32x4){PKW(pB0, 0), PKW(pB0, 2), PKW(pB0, 4), PKW(pB0, 6)}; pw1 = (u32x4){PKW(pB0, 8), PKW(pB0, 10), PKW(pB0, 12), PKW(pB0, 14)}; pw2 = (u32x4){PKW(pB1, 0), PKW(pB1, 2), PKW(pB1, 4), PKW(pB1, 6)}; pw3 = (u32x4){PKW(pB1, 8), PKW(pB1, 10), PKW(pB1, 12), PKW(pB1, 14)};
;     SBAR(); pv(o, vb0 + sl_cur, __builtin_bit_cast(s16x8, pw0), __builtin_bit_cast(s16x8, pw1), __builtin_bit_cast(s16x8, pw2), __builtin_bit_cast(s16x8, pw3)); }
;   h16x8 zg[4];
;   { const h16* Zw0 = BZrows + (long)(wid * QBLK) * ZP;
; #pragma unroll
;     for (int i = 0; i < 4; ++i) zg[i] = *(const GAS h16x8*)(Zw0 + (long)(i * 8 + (lane >> 3)) * ZP + (lane & 7) * 8); }
;     ...
;   { auto rr = __builtin_amdgcn_permlane32_swap(__float_as_uint(l_reg), __float_as_uint(l_reg), false, false); l_reg = __uint_as_float(rr[0]) + __uint_as_float(rr[1]); }
;   if (hi == 0) wsf[32 + r32] = l_reg; asm volatile("s_waitcnt lgkmcnt(0)" ::: "memory");
;   float rli[16];
; #pragma unroll
;   for (int r = 0; r < 16; ++r) rli[r] = __builtin_amdgcn_rcpf(wsf[32 + crow(r, hi)]);
;   h16* Yw = Yrows + (long)(wid * QBLK) * YP;
;   { h16* stg = (h16*)(shm + LDS_OST) + wid * 2048;
; #pragma unroll
;     for (int r = 0; r < 16; ++r) { const int orow = crow(r, hi);
; #pragma unroll
;       for (int d0 = 0; d0 < 2; ++d0) stg[orow * 64 + d0 * 32 + r32] = (h16)(o[d0][r] * rli[r]); }
	s_nop 0
	v_mfma_f32_32x32x16_f16 v[18:33], v[50:53], v[58:61], v[18:33]
	ds_read_b64_tr_b16 v[58:59],v0 offset:4096
	ds_read_b64_tr_b16 v[60:61],v0 offset:4608
	v_mfma_f32_32x32x16_f16 v[18:33], v[54:57], v[62:65], v[18:33]
	ds_read_b64_tr_b16 v[62:63],v0 offset:5120
	ds_read_b64_tr_b16 v[64:65],v0 offset:5632
	v_mfma_f32_32x32x16_f16 v[18:33], v[66:69], v[74:77], v[18:33]
	ds_read_b64_tr_b16 v[74:75],v0 offset:6144
	ds_read_b64_tr_b16 v[76:77],v0 offset:6656
	v_mfma_f32_32x32x16_f16 v[18:33], v[70:73], v[78:81], v[18:33]
	ds_read_b64_tr_b16 v[78:79],v0 offset:7168
	ds_read_b64_tr_b16 v[80:81],v0 offset:7680
	s_waitcnt lgkmcnt(0)
	v_mfma_f32_32x32x16_f16 v[34:49], v[50:53], v[58:61], v[34:49]
	s_lshl_b64 s[12:13], s[24:25], 1
	s_add_u32 s12, s82, s12
	v_and_b32_e32 v0, 56, v131
	s_addc_u32 s13, s81, s13
	v_and_b32_e32 v52, 0xe00, v230
	v_lshlrev_b32_e32 v0, 1, v0
	v_lshl_add_u64 v[50:51], s[12:13], 0, v[0:1]
	v_lshlrev_b32_e32 v52, 1, v52
	v_mov_b32_e32 v53, v1
	v_lshl_add_u64 v[50:51], v[50:51], 0, v[52:53]
	s_movk_i32 s12, 0x2000
	v_add_co_u32_e32 v52, vcc, s12, v50
	s_movk_i32 s12, 0x4000
	s_nop 0
	v_addc_co_u32_e32 v53, vcc, 0, v51, vcc
	v_mfma_f32_32x32x16_f16 v[34:49], v[54:57], v[62:65], v[34:49]
	global_load_dwordx4 v[62:65], v[50:51], off
	global_load_dwordx4 v[58:61], v[52:53], off
	v_add_co_u32_e32 v52, vcc, s12, v50
	v_add_f32_e32 v2, v2, v82
	s_nop 0
	v_addc_co_u32_e32 v53, vcc, 0, v51, vcc
	v_add_co_u32_e32 v50, vcc, s90, v50
	v_add_f32_e32 v2, v3, v2
	s_nop 0
	v_addc_co_u32_e32 v51, vcc, 0, v51, vcc
	global_load_dwordx4 v[54:57], v[52:53], off
	s_nop 0
	global_load_dwordx4 v[50:53], v[50:51], off
	v_add_f32_e32 v2, v4, v2
	v_mfma_f32_32x32x16_f16 v[34:49], v[66:69], v[74:77], v[34:49]
	v_add_f32_e32 v2, v5, v2
	v_add_f32_e32 v2, v6, v2
	v_add_f32_e32 v2, v7, v2
	v_add_f32_e32 v2, v8, v2
	v_add_f32_e32 v2, v9, v2
	v_add_f32_e32 v2, v10, v2
	v_add_f32_e32 v2, v11, v2
	v_add_f32_e32 v2, v12, v2
	v_mfma_f32_32x32x16_f16 v[34:49], v[70:73], v[78:81], v[34:49]
	v_add_f32_e32 v2, v13, v2
	v_add_f32_e32 v2, v14, v2
	v_add_f32_e32 v2, v15, v2
	v_add_f32_e32 v2, v16, v2
	v_add_f32_e32 v2, v17, v2
	v_add_f32_e32 v2, v83, v2
	v_mov_b32_e32 v3, v2
	s_nop 1
	v_permlane32_swap_b32_e32 v2, v3
	v_cmp_gt_u32_e32 vcc, 32, v249
	s_and_saveexec_b64 s[12:13], vcc
	v_lshl_add_u32 v4, v250, 2, s14
	v_add_f32_e32 v2, v2, v3
	ds_write_b32 v4, v2 offset:49280
	s_or_b64 exec, exec, s[12:13]
	v_lshl_add_u32 v4, v248, 4, s14
	s_waitcnt lgkmcnt(0)
	v_add_u32_e32 v2, 0xc080, v4
	ds_read2_b32 v[164:165], v2 offset1:1
	ds_read2_b32 v[166:167], v2 offset0:2 offset1:3
	ds_read2_b32 v[168:169], v2 offset0:8 offset1:9
	ds_read2_b32 v[170:171], v2 offset0:10 offset1:11
	ds_read2_b32 v[172:173], v2 offset0:16 offset1:17
	ds_read2_b32 v[174:175], v2 offset0:18 offset1:19
	ds_read2_b32 v[176:177], v2 offset0:24 offset1:25
	ds_read2_b32 v[178:179], v2 offset0:26 offset1:27
	s_lshl_b32 s12, s16, 12
	s_add_i32 s12, s41, s12
	v_lshlrev_b32_e32 v67, 1, v250
	s_lshl_b64 s[10:11], s[10:11], 11
	s_add_u32 s10, s79, s10
	s_addc_u32 s11, s80, s11
	s_mov_b32 s51, 0x41000000
	s_waitcnt lgkmcnt(0)
	v_rcp_f32_e32 v5, v164
	v_rcp_f32_e32 v6, v165
	v_rcp_f32_e32 v7, v166
	v_rcp_f32_e32 v8, v167
	v_rcp_f32_e32 v9, v168
	v_rcp_f32_e32 v10, v169
	v_rcp_f32_e32 v11, v170
	v_rcp_f32_e32 v12, v171
	v_rcp_f32_e32 v13, v172
	v_rcp_f32_e32 v14, v173
	v_rcp_f32_e32 v15, v174
	v_rcp_f32_e32 v16, v175
	v_rcp_f32_e32 v17, v176
	v_fma_mixlo_f16 v4, v18, v5, 0
	v_lshlrev_b32_e32 v18, 1, v240
	v_add3_u32 v18, s12, v18, v67
	ds_write_b16 v18, v4 offset:51200
	v_fma_mixlo_f16 v4, v34, v5, 0
	ds_write_b16 v18, v4 offset:51264
	v_fma_mixlo_f16 v4, v19, v6, 0
	ds_write_b16 v18, v4 offset:51328
	v_fma_mixlo_f16 v4, v35, v6, 0
	ds_write_b16 v18, v4 offset:51392
	v_fma_mixlo_f16 v4, v20, v7, 0
	ds_write_b16 v18, v4 offset:51456
	v_fma_mixlo_f16 v4, v36, v7, 0
	ds_write_b16 v18, v4 offset:51520
	v_fma_mixlo_f16 v4, v21, v8, 0
	ds_write_b16 v18, v4 offset:51584
	v_fma_mixlo_f16 v4, v37, v8, 0
	ds_write_b16 v18, v4 offset:51648
	v_fma_mixlo_f16 v4, v22, v9, 0
	ds_write_b16 v18, v4 offset:52224
	v_fma_mixlo_f16 v4, v38, v9, 0
	ds_write_b16 v18, v4 offset:52288
	v_fma_mixlo_f16 v4, v23, v10, 0
	ds_write_b16 v18, v4 offset:52352
	v_fma_mixlo_f16 v4, v39, v10, 0
	ds_write_b16 v18, v4 offset:52416
	v_fma_mixlo_f16 v4, v24, v11, 0
	ds_write_b16 v18, v4 offset:52480
	v_fma_mixlo_f16 v4, v40, v11, 0
	ds_write_b16 v18, v4 offset:52544
	v_fma_mixlo_f16 v4, v25, v12, 0
	ds_write_b16 v18, v4 offset:52608
	v_fma_mixlo_f16 v4, v41, v12, 0
	ds_write_b16 v18, v4 offset:52672
	v_fma_mixlo_f16 v4, v26, v13, 0
	ds_write_b16 v18, v4 offset:53248
	v_fma_mixlo_f16 v4, v42, v13, 0
	ds_write_b16 v18, v4 offset:53312
	v_fma_mixlo_f16 v4, v27, v14, 0
	v_rcp_f32_e32 v66, v177
	s_nop 0
	ds_write_b16 v18, v4 offset:53376
	v_fma_mixlo_f16 v4, v43, v14, 0
	ds_write_b16 v18, v4 offset:53440
	v_fma_mixlo_f16 v4, v28, v15, 0
	ds_write_b16 v18, v4 offset:53504
	v_fma_mixlo_f16 v4, v44, v15, 0
	ds_write_b16 v18, v4 offset:53568
	v_fma_mixlo_f16 v4, v29, v16, 0
	ds_write_b16 v18, v4 offset:53632
	v_fma_mixlo_f16 v4, v45, v16, 0
	s_nop 0
	v_rcp_f32_e32 v2, v178
	ds_write_b16 v18, v4 offset:53696
	v_fma_mixlo_f16 v4, v30, v17, 0
	v_rcp_f32_e32 v3, v179
	ds_write_b16 v18, v4 offset:54272
	v_fma_mixlo_f16 v4, v46, v17, 0
	ds_write_b16 v18, v4 offset:54336
	v_fma_mixlo_f16 v4, v31, v66, 0
	ds_write_b16 v18, v4 offset:54400
	v_fma_mixlo_f16 v4, v47, v66, 0
	ds_write_b16 v18, v4 offset:54464
	v_fma_mixlo_f16 v4, v32, v2, 0
	v_fma_mixlo_f16 v2, v48, v2, 0
	ds_write_b16 v18, v2 offset:54592
	v_fma_mixlo_f16 v2, v33, v3, 0
	s_waitcnt vmcnt(3)
; #define GAS __attribute__((address_space(1)))
; __device__ __forceinline__ float siluf(float x) { return x * __builtin_amdgcn_rcpf(1.f + __builtin_amdgcn_exp2f(-1.4426950408889634f * x)); }
; __device__ __forceinline__ unsigned cvtpk_h(float lo, float hi) { f32x2 v = {lo, hi}; h16x2 b = __builtin_convertvector(v, h16x2); return __builtin_bit_cast(unsigned, b); }
; __device__ __forceinline__ int crow(int r, int hi) { return (r & 3) + 8 * (r >> 2) + 4 * hi; }
; template <int THRL, bool FIXM> __device__ __forceinline__ bool attn_unit(const h16* Qrows, const h16* __restrict__ Kh, const h16* __restrict__ Vh, const int NT, h16* Yrows, const h16* BZrows, char* shm, const int tid, const float mfix, ...
;     ...
;   { h16* stg = (h16*)(shm + LDS_OST) + wid * 2048;
; #pragma unroll
;     for (int r = 0; r < 16; ++r) { const int orow = crow(r, hi);
; #pragma unroll
;       for (int d0 = 0; d0 < 2; ++d0) stg[orow * 64 + d0 * 32 + r32] = (h16)(o[d0][r] * rli[r]); }
;     asm volatile("s_waitcnt lgkmcnt(0)" ::: "memory");
; #pragma unroll
;     for (int i = 0; i < 4; ++i) { const int row = i * 8 + (lane >> 3), ch = lane & 7; const h16x8 v = *(const h16x8*)(stg + row * 64 + ch * 8); const h16x8 z = zg[i];
;       u32x4 w; w.x = cvtpk_h((float)v[0] * siluf((float)z[0]), (float)v[1] * siluf((float)z[1])); w.y = cvtpk_h((float)v[2] * siluf((float)z[2]), (float)v[3] * siluf((float)z[3]));
;       w.z = cvtpk_h((float)v[4] * siluf((float)z[4]), (float)v[5] * siluf((float)z[5])); w.w = cvtpk_h((float)v[6] * siluf((float)z[6]), (float)v[7] * siluf((float)z[7]));
;       *(GAS u32x4*)(Yw + (long)row * YP + ch * 8) = w; } }
	v_cvt_f32_f16_e32 v8, v62
	ds_write_b16 v18, v2 offset:54656
	v_fma_mixlo_f16 v2, v49, v3, 0
	ds_write_b16 v18, v4 offset:54528
	ds_write_b16 v18, v2 offset:54720
	v_lshrrev_b32_e32 v10, 3, v249
	v_add_u32_e32 v11, s12, v0
	s_waitcnt lgkmcnt(0)
	v_lshl_add_u64 v[6:7], s[10:11], 0, v[0:1]
	v_lshl_add_u32 v0, v10, 7, v11
	ds_read_b128 v[2:5], v0 offset:51200
	v_mul_f32_e32 v0, 0xbfb8aa3b, v8
	v_exp_f32_e32 v0, v0
	v_cvt_f32_f16_sdwa v9, v62 dst_sel:DWORD dst_unused:UNUSED_PAD src0_sel:WORD_1
	s_mov_b64 s[10:11], 0
	s_waitcnt lgkmcnt(0)
	v_cvt_f32_f16_e32 v14, v2
	v_add_f32_e32 v0, 1.0, v0
	v_rcp_f32_e32 v12, v0
	v_mul_f32_e32 v0, 0xbfb8aa3b, v9
	v_exp_f32_e32 v0, v0
	v_cvt_f32_f16_sdwa v15, v2 dst_sel:DWORD dst_unused:UNUSED_PAD src0_sel:WORD_1
	v_add_f32_e32 v0, 1.0, v0
	v_rcp_f32_e32 v13, v0
	s_nop 0
	v_pk_mul_f32 v[8:9], v[12:13], v[8:9]
	s_nop 0
	v_pk_mul_f32 v[8:9], v[8:9], v[14:15]
	v_cvt_f32_f16_e32 v14, v3
	v_cvt_pk_f16_f32 v2, v8, v9
	v_cvt_f32_f16_e32 v8, v63
	v_cvt_f32_f16_sdwa v9, v63 dst_sel:DWORD dst_unused:UNUSED_PAD src0_sel:WORD_1
	v_cvt_f32_f16_sdwa v15, v3 dst_sel:DWORD dst_unused:UNUSED_PAD src0_sel:WORD_1
	v_mul_f32_e32 v0, 0xbfb8aa3b, v8
	v_exp_f32_e32 v0, v0
	s_nop 0
	v_add_f32_e32 v0, 1.0, v0
	v_rcp_f32_e32 v12, v0
	v_mul_f32_e32 v0, 0xbfb8aa3b, v9
	v_exp_f32_e32 v0, v0
	s_nop 0
	v_add_f32_e32 v0, 1.0, v0
	v_rcp_f32_e32 v13, v0
	s_nop 0
	v_pk_mul_f32 v[8:9], v[12:13], v[8:9]
	s_nop 0
	v_pk_mul_f32 v[8:9], v[8:9], v[14:15]
	v_cvt_f32_f16_e32 v14, v4
	v_cvt_pk_f16_f32 v3, v8, v9
	v_cvt_f32_f16_e32 v8, v64
	v_cvt_f32_f16_sdwa v9, v64 dst_sel:DWORD dst_unused:UNUSED_PAD src0_sel:WORD_1
	v_cvt_f32_f16_sdwa v15, v4 dst_sel:DWORD dst_unused:UNUSED_PAD src0_sel:WORD_1
	v_mul_f32_e32 v0, 0xbfb8aa3b, v8
	v_exp_f32_e32 v0, v0
	s_nop 0
	v_add_f32_e32 v0, 1.0, v0
	v_rcp_f32_e32 v12, v0
	v_mul_f32_e32 v0, 0xbfb8aa3b, v9
	v_exp_f32_e32 v0, v0
	s_nop 0
	v_add_f32_e32 v0, 1.0, v0
	v_rcp_f32_e32 v13, v0
	s_nop 0
	v_pk_mul_f32 v[8:9], v[12:13], v[8:9]
	s_nop 0
	v_pk_mul_f32 v[8:9], v[8:9], v[14:15]
	v_cvt_f32_f16_e32 v14, v5
	v_cvt_pk_f16_f32 v4, v8, v9
	v_cvt_f32_f16_e32 v8, v65
	v_cvt_f32_f16_sdwa v9, v65 dst_sel:DWORD dst_unused:UNUSED_PAD src0_sel:WORD_1
	v_cvt_f32_f16_sdwa v15, v5 dst_sel:DWORD dst_unused:UNUSED_PAD src0_sel:WORD_1
	v_mul_f32_e32 v0, 0xbfb8aa3b, v8
	v_exp_f32_e32 v0, v0
	s_nop 0
	v_add_f32_e32 v0, 1.0, v0
	v_rcp_f32_e32 v12, v0
	v_mul_f32_e32 v0, 0xbfb8aa3b, v9
	v_exp_f32_e32 v0, v0
	s_nop 0
	v_add_f32_e32 v0, 1.0, v0
	v_rcp_f32_e32 v13, v0
	v_lshlrev_b32_e32 v0, 11, v10
	v_pk_mul_f32 v[8:9], v[12:13], v[8:9]
	s_nop 0
	v_pk_mul_f32 v[8:9], v[8:9], v[14:15]
	s_nop 0
	v_cvt_pk_f16_f32 v5, v8, v9
	v_lshl_add_u64 v[8:9], v[6:7], 0, v[0:1]
	v_or_b32_e32 v0, 8, v10
	global_store_dwordx4 v[8:9], v[2:5], off offset:512 sc1
	s_waitcnt vmcnt(3)
	v_cvt_f32_f16_sdwa v9, v58 dst_sel:DWORD dst_unused:UNUSED_PAD src0_sel:WORD_1
	v_cvt_f32_f16_e32 v8, v58
	v_lshl_add_u32 v2, v0, 7, v11
	ds_read_b128 v[2:5], v2 offset:51200
	v_lshlrev_b32_e32 v0, 11, v0
	v_mul_f32_e32 v12, 0xbfb8aa3b, v8
	v_exp_f32_e32 v12, v12
	s_waitcnt lgkmcnt(0)
	v_cvt_f32_f16_e32 v14, v2
	v_cvt_f32_f16_sdwa v15, v2 dst_sel:DWORD dst_unused:UNUSED_PAD src0_sel:WORD_1
	v_mul_f32_e32 v2, 0xbfb8aa3b, v9
	v_exp_f32_e32 v2, v2
	v_add_f32_e32 v12, 1.0, v12
	v_rcp_f32_e32 v12, v12
	v_add_f32_e32 v2, 1.0, v2
	v_rcp_f32_e32 v13, v2
	s_nop 0
	v_pk_mul_f32 v[8:9], v[12:13], v[8:9]
	s_nop 0
	v_pk_mul_f32 v[8:9], v[8:9], v[14:15]
	v_cvt_f32_f16_e32 v14, v3
	v_cvt_pk_f16_f32 v2, v8, v9
	v_cvt_f32_f16_sdwa v9, v59 dst_sel:DWORD dst_unused:UNUSED_PAD src0_sel:WORD_1
	v_cvt_f32_f16_e32 v8, v59
	v_cvt_f32_f16_sdwa v15, v3 dst_sel:DWORD dst_unused:UNUSED_PAD src0_sel:WORD_1
	v_mul_f32_e32 v3, 0xbfb8aa3b, v9
	v_mul_f32_e32 v12, 0xbfb8aa3b, v8
	v_exp_f32_e32 v12, v12
	v_exp_f32_e32 v3, v3
	v_add_f32_e32 v12, 1.0, v12
	v_add_f32_e32 v3, 1.0, v3
	v_rcp_f32_e32 v12, v12
	v_rcp_f32_e32 v13, v3
	s_nop 0
	v_pk_mul_f32 v[8:9], v[12:13], v[8:9]
	s_nop 0
	v_pk_mul_f32 v[8:9], v[8:9], v[14:15]
	v_cvt_f32_f16_e32 v14, v4
	v_cvt_pk_f16_f32 v3, v8, v9
	v_cvt_f32_f16_sdwa v9, v60 dst_sel:DWORD dst_unused:UNUSED_PAD src0_sel:WORD_1
	v_cvt_f32_f16_e32 v8, v60
	v_cvt_f32_f16_sdwa v15, v4 dst_sel:DWORD dst_unused:UNUSED_PAD src0_sel:WORD_1
	v_mul_f32_e32 v4, 0xbfb8aa3b, v9
	v_mul_f32_e32 v12, 0xbfb8aa3b, v8
	v_exp_f32_e32 v12, v12
	v_exp_f32_e32 v4, v4
	v_add_f32_e32 v12, 1.0, v12
	v_add_f32_e32 v4, 1.0, v4
	v_rcp_f32_e32 v12, v12
	v_rcp_f32_e32 v13, v4
	s_nop 0
	v_pk_mul_f32 v[8:9], v[12:13], v[8:9]
	s_nop 0
	v_pk_mul_f32 v[8:9], v[8:9], v[14:15]
	v_cvt_f32_f16_e32 v14, v5
	v_cvt_pk_f16_f32 v4, v8, v9
	v_cvt_f32_f16_sdwa v9, v61 dst_sel:DWORD dst_unused:UNUSED_PAD src0_sel:WORD_1
	v_cvt_f32_f16_e32 v8, v61
	v_cvt_f32_f16_sdwa v15, v5 dst_sel:DWORD dst_unused:UNUSED_PAD src0_sel:WORD_1
	v_mul_f32_e32 v5, 0xbfb8aa3b, v9
	v_mul_f32_e32 v12, 0xbfb8aa3b, v8
	v_exp_f32_e32 v12, v12
	v_exp_f32_e32 v5, v5
	v_add_f32_e32 v12, 1.0, v12
	v_add_f32_e32 v5, 1.0, v5
	v_rcp_f32_e32 v12, v12
	v_rcp_f32_e32 v13, v5
	s_nop 0
	v_pk_mul_f32 v[8:9], v[12:13], v[8:9]
	s_nop 0
	v_pk_mul_f32 v[8:9], v[8:9], v[14:15]
	s_nop 0
	v_cvt_pk_f16_f32 v5, v8, v9
	v_lshl_add_u64 v[8:9], v[6:7], 0, v[0:1]
	v_or_b32_e32 v0, 16, v10
	global_store_dwordx4 v[8:9], v[2:5], off offset:512 sc1
	s_waitcnt vmcnt(3)
; #define GAS __attribute__((address_space(1)))
; __device__ __forceinline__ float siluf(float x) { return x * __builtin_amdgcn_rcpf(1.f + __builtin_amdgcn_exp2f(-1.4426950408889634f * x)); }
; __device__ __forceinline__ unsigned cvtpk_h(float lo, float hi) { f32x2 v = {lo, hi}; h16x2 b = __builtin_convertvector(v, h16x2); return __builtin_bit_cast(unsigned, b); }
; __device__ __forceinline__ int crow(int r, int hi) { return (r & 3) + 8 * (r >> 2) + 4 * hi; }
; template <int THRL, bool FIXM> __device__ __forceinline__ bool attn_unit(const h16* Qrows, const h16* __restrict__ Kh, const h16* __restrict__ Vh, const int NT, h16* Yrows, const h16* BZrows, char* shm, const int tid, const float mfix, ...
;     ...
;   { h16* stg = (h16*)(shm + LDS_OST) + wid * 2048;
; #pragma unroll
;     for (int r = 0; r < 16; ++r) { const int orow = crow(r, hi);
; #pragma unroll
;       for (int d0 = 0; d0 < 2; ++d0) stg[orow * 64 + d0 * 32 + r32] = (h16)(o[d0][r] * rli[r]); }
;     asm volatile("s_waitcnt lgkmcnt(0)" ::: "memory");
; #pragma unroll
;     for (int i = 0; i < 4; ++i) { const int row = i * 8 + (lane >> 3), ch = lane & 7; const h16x8 v = *(const h16x8*)(stg + row * 64 + ch * 8); const h16x8 z = zg[i];
;       u32x4 w; w.x = cvtpk_h((float)v[0] * siluf((float)z[0]), (float)v[1] * siluf((float)z[1])); w.y = cvtpk_h((float)v[2] * siluf((float)z[2]), (float)v[3] * siluf((float)z[3]));
;       w.z = cvtpk_h((float)v[4] * siluf((float)z[4]), (float)v[5] * siluf((float)z[5])); w.w = cvtpk_h((float)v[6] * siluf((float)z[6]), (float)v[7] * siluf((float)z[7]));
;       *(GAS u32x4*)(Yw + (long)row * YP + ch * 8) = w; } }
;   asm volatile("s_waitcnt lgkmcnt(0)\n\ts_barrier" ::: "memory");
	v_cvt_f32_f16_sdwa v9, v54 dst_sel:DWORD dst_unused:UNUSED_PAD src0_sel:WORD_1
	v_cvt_f32_f16_e32 v8, v54
	v_lshl_add_u32 v2, v0, 7, v11
	ds_read_b128 v[2:5], v2 offset:51200
	v_lshlrev_b32_e32 v0, 11, v0
	v_mul_f32_e32 v12, 0xbfb8aa3b, v8
	v_exp_f32_e32 v12, v12
	s_waitcnt lgkmcnt(0)
	v_cvt_f32_f16_e32 v14, v2
	v_cvt_f32_f16_sdwa v15, v2 dst_sel:DWORD dst_unused:UNUSED_PAD src0_sel:WORD_1
	v_mul_f32_e32 v2, 0xbfb8aa3b, v9
	v_exp_f32_e32 v2, v2
	v_add_f32_e32 v12, 1.0, v12
	v_rcp_f32_e32 v12, v12
	v_add_f32_e32 v2, 1.0, v2
	v_rcp_f32_e32 v13, v2
	s_nop 0
	v_pk_mul_f32 v[8:9], v[12:13], v[8:9]
	s_nop 0
	v_pk_mul_f32 v[8:9], v[8:9], v[14:15]
	v_cvt_f32_f16_e32 v14, v3
	v_cvt_pk_f16_f32 v2, v8, v9
	v_cvt_f32_f16_sdwa v9, v55 dst_sel:DWORD dst_unused:UNUSED_PAD src0_sel:WORD_1
	v_cvt_f32_f16_e32 v8, v55
	v_cvt_f32_f16_sdwa v15, v3 dst_sel:DWORD dst_unused:UNUSED_PAD src0_sel:WORD_1
	v_mul_f32_e32 v3, 0xbfb8aa3b, v9
	v_mul_f32_e32 v12, 0xbfb8aa3b, v8
	v_exp_f32_e32 v12, v12
	v_exp_f32_e32 v3, v3
	v_add_f32_e32 v12, 1.0, v12
	v_add_f32_e32 v3, 1.0, v3
	v_rcp_f32_e32 v12, v12
	v_rcp_f32_e32 v13, v3
	s_nop 0
	v_pk_mul_f32 v[8:9], v[12:13], v[8:9]
	s_nop 0
	v_pk_mul_f32 v[8:9], v[8:9], v[14:15]
	v_cvt_f32_f16_e32 v14, v4
	v_cvt_pk_f16_f32 v3, v8, v9
	v_cvt_f32_f16_sdwa v9, v56 dst_sel:DWORD dst_unused:UNUSED_PAD src0_sel:WORD_1
	v_cvt_f32_f16_e32 v8, v56
	v_cvt_f32_f16_sdwa v15, v4 dst_sel:DWORD dst_unused:UNUSED_PAD src0_sel:WORD_1
	v_mul_f32_e32 v4, 0xbfb8aa3b, v9
	v_mul_f32_e32 v12, 0xbfb8aa3b, v8
	v_exp_f32_e32 v12, v12
	v_exp_f32_e32 v4, v4
	v_add_f32_e32 v12, 1.0, v12
	v_add_f32_e32 v4, 1.0, v4
	v_rcp_f32_e32 v12, v12
	v_rcp_f32_e32 v13, v4
	s_nop 0
	v_pk_mul_f32 v[8:9], v[12:13], v[8:9]
	s_nop 0
	v_pk_mul_f32 v[8:9], v[8:9], v[14:15]
	v_cvt_f32_f16_e32 v14, v5
	v_cvt_pk_f16_f32 v4, v8, v9
	v_cvt_f32_f16_sdwa v9, v57 dst_sel:DWORD dst_unused:UNUSED_PAD src0_sel:WORD_1
	v_cvt_f32_f16_e32 v8, v57
	v_cvt_f32_f16_sdwa v15, v5 dst_sel:DWORD dst_unused:UNUSED_PAD src0_sel:WORD_1
	v_mul_f32_e32 v5, 0xbfb8aa3b, v9
	v_mul_f32_e32 v12, 0xbfb8aa3b, v8
	v_exp_f32_e32 v12, v12
	v_exp_f32_e32 v5, v5
	v_add_f32_e32 v12, 1.0, v12
	v_add_f32_e32 v5, 1.0, v5
	v_rcp_f32_e32 v12, v12
	v_rcp_f32_e32 v13, v5
	s_nop 0
	v_pk_mul_f32 v[8:9], v[12:13], v[8:9]
	s_nop 0
	v_pk_mul_f32 v[8:9], v[8:9], v[14:15]
	s_nop 0
	v_cvt_pk_f16_f32 v5, v8, v9
	v_lshl_add_u64 v[8:9], v[6:7], 0, v[0:1]
	v_or_b32_e32 v0, 24, v10
	global_store_dwordx4 v[8:9], v[2:5], off offset:512 sc1
	s_waitcnt vmcnt(3)
	v_cvt_f32_f16_sdwa v9, v50 dst_sel:DWORD dst_unused:UNUSED_PAD src0_sel:WORD_1
	v_cvt_f32_f16_e32 v8, v50
	v_lshl_add_u32 v2, v0, 7, v11
	ds_read_b128 v[2:5], v2 offset:51200
	v_lshlrev_b32_e32 v0, 11, v0
	v_mul_f32_e32 v10, 0xbfb8aa3b, v8
	v_exp_f32_e32 v10, v10
	v_lshl_add_u64 v[6:7], v[6:7], 0, v[0:1]
	s_waitcnt lgkmcnt(0)
	v_cvt_f32_f16_e32 v12, v2
	v_cvt_f32_f16_sdwa v13, v2 dst_sel:DWORD dst_unused:UNUSED_PAD src0_sel:WORD_1
	v_mul_f32_e32 v2, 0xbfb8aa3b, v9
	v_exp_f32_e32 v2, v2
	v_add_f32_e32 v10, 1.0, v10
	v_rcp_f32_e32 v10, v10
	v_add_f32_e32 v2, 1.0, v2
	v_rcp_f32_e32 v11, v2
	s_nop 0
	v_pk_mul_f32 v[8:9], v[10:11], v[8:9]
	s_nop 0
	v_pk_mul_f32 v[8:9], v[8:9], v[12:13]
	v_cvt_f32_f16_e32 v12, v3
	v_cvt_pk_f16_f32 v2, v8, v9
	v_cvt_f32_f16_sdwa v9, v51 dst_sel:DWORD dst_unused:UNUSED_PAD src0_sel:WORD_1
	v_cvt_f32_f16_e32 v8, v51
	v_cvt_f32_f16_sdwa v13, v3 dst_sel:DWORD dst_unused:UNUSED_PAD src0_sel:WORD_1
	v_mul_f32_e32 v3, 0xbfb8aa3b, v9
	v_mul_f32_e32 v10, 0xbfb8aa3b, v8
	v_exp_f32_e32 v10, v10
	v_exp_f32_e32 v3, v3
	v_add_f32_e32 v10, 1.0, v10
	v_add_f32_e32 v3, 1.0, v3
	v_rcp_f32_e32 v10, v10
	v_rcp_f32_e32 v11, v3
	s_nop 0
	v_pk_mul_f32 v[8:9], v[10:11], v[8:9]
	s_nop 0
	v_pk_mul_f32 v[8:9], v[8:9], v[12:13]
	v_cvt_f32_f16_e32 v12, v4
	v_cvt_pk_f16_f32 v3, v8, v9
	v_cvt_f32_f16_sdwa v9, v52 dst_sel:DWORD dst_unused:UNUSED_PAD src0_sel:WORD_1
	v_cvt_f32_f16_e32 v8, v52
	v_cvt_f32_f16_sdwa v13, v4 dst_sel:DWORD dst_unused:UNUSED_PAD src0_sel:WORD_1
	v_mul_f32_e32 v4, 0xbfb8aa3b, v9
	v_mul_f32_e32 v10, 0xbfb8aa3b, v8
	v_exp_f32_e32 v10, v10
	v_exp_f32_e32 v4, v4
	v_add_f32_e32 v10, 1.0, v10
	v_add_f32_e32 v4, 1.0, v4
	v_rcp_f32_e32 v10, v10
	v_rcp_f32_e32 v11, v4
	s_nop 0
	v_pk_mul_f32 v[8:9], v[10:11], v[8:9]
	s_nop 0
	v_pk_mul_f32 v[8:9], v[8:9], v[12:13]
	v_cvt_f32_f16_e32 v12, v5
	v_cvt_pk_f16_f32 v4, v8, v9
	v_cvt_f32_f16_sdwa v9, v53 dst_sel:DWORD dst_unused:UNUSED_PAD src0_sel:WORD_1
	v_cvt_f32_f16_e32 v8, v53
	v_cvt_f32_f16_sdwa v13, v5 dst_sel:DWORD dst_unused:UNUSED_PAD src0_sel:WORD_1
	v_mul_f32_e32 v5, 0xbfb8aa3b, v9
	v_mul_f32_e32 v10, 0xbfb8aa3b, v8
	v_exp_f32_e32 v10, v10
	v_exp_f32_e32 v5, v5
	v_add_f32_e32 v10, 1.0, v10
	v_add_f32_e32 v5, 1.0, v5
	v_rcp_f32_e32 v10, v10
	v_rcp_f32_e32 v11, v5
	s_nop 0
	v_pk_mul_f32 v[8:9], v[10:11], v[8:9]
	s_nop 0
	v_pk_mul_f32 v[8:9], v[8:9], v[12:13]
	s_nop 0
	v_cvt_pk_f16_f32 v5, v8, v9
	global_store_dwordx4 v[6:7], v[2:5], off offset:512 sc1
	s_waitcnt lgkmcnt(0)
	s_barrier

; #define GAS __attribute__((address_space(1)))
; __device__ __forceinline__ int crow(int r, int hi) { return (r & 3) + 8 * (r >> 2) + 4 * hi; }
; #define SBAR() __builtin_amdgcn_sched_barrier(0)
; #define PKW(P, B) cvtpk_h(P[B], P[B + 1])
; #define PKW(P, B) cvtpk_h(P[B], P[B + 1])
; template <int THRL, bool FIXM> __device__ __forceinline__ bool attn_unit(const h16* Qrows, const h16* __restrict__ Kh, const h16* __restrict__ Vh, const int NT, h16* Yrows, const h16* BZrows, char* shm, const int tid, const float mfix, ...
;     ...
;   { float sacc = pB0[0] + pB0[1]; _Pragma("unroll") for (int r = 2; r < 16; ++r) sacc += pB0[r]; _Pragma("unroll") for (int r = 0; r < 16; ++r) sacc += pB1[r]; l_reg += sacc;
;     pw0 = (u32x4){PKW(pB0, 0), PKW(pB0, 2), PKW(pB0, 4), PKW(pB0, 6)}; pw1 = (u32x4){PKW(pB0, 8), PKW(pB0, 10), PKW(pB0, 12), PKW(pB0, 14)}; pw2 = (u32x4){PKW(pB1, 0), PKW(pB1, 2), PKW(pB1, 4), PKW(pB1, 6)}; pw3 = (u32x4){PKW(pB1, 8), PKW(pB1, 10), PKW(pB1, 12), PKW(pB1, 14)};
;     SBAR(); pv(o, vb0 + sl_cur, __builtin_bit_cast(s16x8, pw0), __builtin_bit_cast(s16x8, pw1), __builtin_bit_cast(s16x8, pw2), __builtin_bit_cast(s16x8, pw3)); }
;   h16x8 zg[4];
;   { const h16* Zw0 = BZrows + (long)(wid * QBLK) * ZP;
; #pragma unroll
;     for (int i = 0; i < 4; ++i) zg[i] = *(const GAS h16x8*)(Zw0 + (long)(i * 8 + (lane >> 3)) * ZP + (lane & 7) * 8); }
;     ...
;   { auto rr = __builtin_amdgcn_permlane32_swap(__float_as_uint(l_reg), __float_as_uint(l_reg), false, false); l_reg = __uint_as_float(rr[0]) + __uint_as_float(rr[1]); }
;   if (hi == 0) wsf[32 + r32] = l_reg; asm volatile("s_waitcnt lgkmcnt(0)" ::: "memory");
;   float rli[16];
; #pragma unroll
;   for (int r = 0; r < 16; ++r) rli[r] = __builtin_amdgcn_rcpf(wsf[32 + crow(r, hi)]);
;   h16* Yw = Yrows + (long)(wid * QBLK) * YP;
;   { h16* stg = (h16*)(shm + LDS_OST) + wid * 2048;
; #pragma unroll
;     for (int r = 0; r < 16; ++r) { const int orow = crow(r, hi);
; #pragma unroll
;       for (int d0 = 0; d0 < 2; ++d0) stg[orow * 64 + d0 * 32 + r32] = (h16)(o[d0][r] * rli[r]); }
.LBB0_224:
	v_add_f32_e32 v0, v82, v83
	v_add_f32_e32 v0, v84, v0
	v_add_f32_e32 v0, v85, v0
	v_add_f32_e32 v0, v86, v0
	v_add_f32_e32 v0, v87, v0
	v_add_f32_e32 v0, v88, v0
	v_add_f32_e32 v0, v89, v0
	v_add_f32_e32 v0, v90, v0
	v_add_f32_e32 v0, v91, v0
	v_add_f32_e32 v0, v92, v0
	v_add_f32_e32 v0, v93, v0
	v_add_f32_e32 v0, v94, v0
	v_add_f32_e32 v0, v95, v0
	v_add_f32_e32 v0, v96, v0
	v_add_f32_e32 v0, v97, v0
	v_add_f32_e32 v0, v34, v0
	v_add_f32_e32 v0, v35, v0
	v_add_f32_e32 v0, v36, v0
	v_add_f32_e32 v0, v37, v0
	v_add_f32_e32 v0, v38, v0
	v_add_f32_e32 v0, v39, v0
	v_add_f32_e32 v0, v40, v0
	v_add_f32_e32 v0, v41, v0
	v_add_f32_e32 v0, v42, v0
	v_add_f32_e32 v0, v43, v0
	v_add_f32_e32 v0, v44, v0
	v_add_f32_e32 v0, v45, v0
	v_add_f32_e32 v0, v46, v0
	v_add_f32_e32 v0, v47, v0
	v_add_f32_e32 v0, v48, v0
	v_add_f32_e32 v51, v49, v0
	v_cvt_pk_f16_f32 v52, v82, v83
	v_cvt_pk_f16_f32 v34, v34, v35
	v_cvt_pk_f16_f32 v35, v36, v37
	v_cvt_pk_f16_f32 v36, v38, v39
	v_cvt_pk_f16_f32 v37, v40, v41
	v_cvt_pk_f16_f32 v53, v84, v85
	v_cvt_pk_f16_f32 v54, v86, v87
	v_cvt_pk_f16_f32 v55, v88, v89
	v_cvt_pk_f16_f32 v56, v90, v91
	v_cvt_pk_f16_f32 v57, v92, v93
	v_cvt_pk_f16_f32 v58, v94, v95
	v_cvt_pk_f16_f32 v59, v96, v97
	v_cvt_pk_f16_f32 v60, v42, v43
	v_cvt_pk_f16_f32 v61, v44, v45
	v_cvt_pk_f16_f32 v62, v46, v47
	v_cvt_pk_f16_f32 v63, v48, v49
	v_or3_b32 v0, v243, v204, v205
	s_add_i32 s0, s17, s48
	v_add_u32_e32 v0, s0, v0
	ds_read_b64_tr_b16 v[38:39],v0 offset:0
	ds_read_b64_tr_b16 v[40:41],v0 offset:512
	ds_read_b64_tr_b16 v[64:65],v0 offset:1024
	ds_read_b64_tr_b16 v[66:67],v0 offset:1536
	ds_read_b64_tr_b16 v[68:69],v0 offset:2048
	ds_read_b64_tr_b16 v[70:71],v0 offset:2560
	ds_read_b64_tr_b16 v[72:73],v0 offset:3072
	ds_read_b64_tr_b16 v[74:75],v0 offset:3584
	s_waitcnt lgkmcnt(0)
	ds_read_b64_tr_b16 v[42:43],v0 offset:4096
	ds_read_b64_tr_b16 v[44:45],v0 offset:4608
	ds_read_b64_tr_b16 v[46:47],v0 offset:5120
	ds_read_b64_tr_b16 v[48:49],v0 offset:5632
	ds_read_b64_tr_b16 v[76:77],v0 offset:6144
	ds_read_b64_tr_b16 v[78:79],v0 offset:6656
	ds_read_b64_tr_b16 v[80:81],v0 offset:7168
	ds_read_b64_tr_b16 v[82:83],v0 offset:7680
	s_waitcnt lgkmcnt(0)
	s_nop 0
	v_mfma_f32_32x32x16_f16 v[2:17], v[52:55], v[42:45], v[2:17]
	s_lshl_b64 s[0:1], s[14:15], 1
	s_add_u32 s0, s82, s0
	v_and_b32_e32 v0, 56, v131
	v_and_b32_e32 v44, 0xe00, v230
	s_addc_u32 s1, s81, s1
	v_lshlrev_b32_e32 v0, 1, v0
	v_lshl_add_u64 v[42:43], s[0:1], 0, v[0:1]
	v_mfma_f32_32x32x16_f16 v[18:33], v[52:55], v[38:41], v[18:33]
	v_lshlrev_b32_e32 v44, 1, v44
	v_mov_b32_e32 v45, v1
	s_movk_i32 s0, 0x2000
	v_add_f32_e32 v51, v114, v51
	v_mfma_f32_32x32x16_f16 v[2:17], v[56:59], v[46:49], v[2:17]
	v_mfma_f32_32x32x16_f16 v[18:33], v[56:59], v[64:67], v[18:33]
	v_mfma_f32_32x32x16_f16 v[2:17], v[34:37], v[76:79], v[2:17]
	v_lshl_add_u64 v[76:77], v[42:43], 0, v[44:45]
	v_add_co_u32_e32 v42, vcc, s0, v76
	s_nop 1
	v_addc_co_u32_e32 v43, vcc, 0, v77, vcc
	v_add_co_u32_e32 v38, vcc, 0x4000, v76
	global_load_dwordx4 v[46:49], v[76:77], off
	s_nop 0
	global_load_dwordx4 v[42:45], v[42:43], off
	v_addc_co_u32_e32 v39, vcc, 0, v77, vcc
	v_add_co_u32_e32 v52, vcc, 0x6000, v76
	v_mfma_f32_32x32x16_f16 v[18:33], v[34:37], v[68:71], v[18:33]
	s_nop 0
	v_addc_co_u32_e32 v53, vcc, 0, v77, vcc
	global_load_dwordx4 v[38:41], v[38:39], off
	s_nop 0
	global_load_dwordx4 v[34:37], v[52:53], off
	v_mov_b32_e32 v52, v51
	s_nop 1
	v_permlane32_swap_b32_e32 v51, v52
	v_cmp_gt_u32_e32 vcc, 32, v249
	v_mfma_f32_32x32x16_f16 v[2:17], v[60:63], v[80:83], v[2:17]
	v_mfma_f32_32x32x16_f16 v[18:33], v[60:63], v[72:75], v[18:33]
	s_and_saveexec_b64 s[0:1], vcc
	v_add_f32_e32 v51, v51, v52
	ds_write_b32 v203, v51 offset:49280
	s_or_b64 exec, exec, s[0:1]
	s_waitcnt lgkmcnt(0)
	v_add_u32_e32 v51, 0xc080, v50
	ds_read2_b32 v[52:53], v51 offset1:1
	v_add_u32_e32 v51, 0xc088, v50
	s_lshl_b32 s4, s29, 12
	s_add_i32 s4, s41, s4
	v_lshlrev_b32_e32 v66, 1, v202
	s_waitcnt lgkmcnt(0)
	v_rcp_f32_e32 v54, v52
	v_rcp_f32_e32 v55, v53
	ds_read2_b32 v[52:53], v51 offset1:1
	v_add_u32_e32 v51, 0xc0a0, v50
	v_lshlrev_b32_e32 v67, 1, v250
	v_add3_u32 v66, s4, v66, v67
	v_fma_mixlo_f16 v2, v2, v54, 0
	s_waitcnt lgkmcnt(0)
	v_rcp_f32_e32 v56, v52
	v_rcp_f32_e32 v57, v53
	ds_read2_b32 v[52:53], v51 offset1:1
	v_add_u32_e32 v51, 0xc0a8, v50
	ds_write_b16 v66, v2 offset:51264
	v_fma_mixlo_f16 v2, v19, v55, 0
	ds_write_b16 v66, v2 offset:51328
	s_waitcnt lgkmcnt(2)
	v_rcp_f32_e32 v58, v52
	v_rcp_f32_e32 v59, v53
	ds_read2_b32 v[52:53], v51 offset1:1
	v_fma_mixlo_f16 v2, v3, v55, 0
	v_add_u32_e32 v51, 0xc0c0, v50
	ds_write_b16 v66, v2 offset:51392
	v_fma_mixlo_f16 v2, v20, v56, 0
	s_waitcnt lgkmcnt(1)
	v_rcp_f32_e32 v60, v52
	v_rcp_f32_e32 v61, v53
	ds_read2_b32 v[52:53], v51 offset1:1
	ds_write_b16 v66, v2 offset:51456
	v_fma_mixlo_f16 v2, v4, v56, 0
	ds_write_b16 v66, v2 offset:51520
	v_fma_mixlo_f16 v2, v21, v57, 0
	ds_write_b16 v66, v2 offset:51584
	v_fma_mixlo_f16 v2, v5, v57, 0
	ds_write_b16 v66, v2 offset:51648
	v_fma_mixlo_f16 v2, v22, v58, 0
	v_add_u32_e32 v51, 0xc0c8, v50
	ds_write_b16 v66, v2 offset:52224
	v_fma_mixlo_f16 v2, v6, v58, 0
	s_waitcnt lgkmcnt(5)
	v_rcp_f32_e32 v62, v52
	v_rcp_f32_e32 v63, v53
	ds_read2_b32 v[52:53], v51 offset1:1
	ds_write_b16 v66, v2 offset:52288
	v_fma_mixlo_f16 v2, v23, v59, 0
	ds_write_b16 v66, v2 offset:52352
	v_fma_mixlo_f16 v2, v7, v59, 0
	ds_write_b16 v66, v2 offset:52416
	v_fma_mixlo_f16 v2, v24, v60, 0
	ds_write_b16 v66, v2 offset:52480
	v_fma_mixlo_f16 v2, v8, v60, 0
	v_add_u32_e32 v51, 0xc0e0, v50
	ds_write_b16 v66, v2 offset:52544
	v_fma_mixlo_f16 v2, v25, v61, 0
	s_waitcnt lgkmcnt(5)
; #define GAS __attribute__((address_space(1)))
; __device__ __forceinline__ float siluf(float x) { return x * __builtin_amdgcn_rcpf(1.f + __builtin_amdgcn_exp2f(-1.4426950408889634f * x)); }
; __device__ __forceinline__ unsigned cvtpk_h(float lo, float hi) { f32x2 v = {lo, hi}; h16x2 b = __builtin_convertvector(v, h16x2); return __builtin_bit_cast(unsigned, b); }
; __device__ __forceinline__ int crow(int r, int hi) { return (r & 3) + 8 * (r >> 2) + 4 * hi; }
; template <int THRL, bool FIXM> __device__ __forceinline__ bool attn_unit(const h16* Qrows, const h16* __restrict__ Kh, const h16* __restrict__ Vh, const int NT, h16* Yrows, const h16* BZrows, char* shm, const int tid, const float mfix, ...
;     ...
;   float rli[16];
; #pragma unroll
;   for (int r = 0; r < 16; ++r) rli[r] = __builtin_amdgcn_rcpf(wsf[32 + crow(r, hi)]);
;   h16* Yw = Yrows + (long)(wid * QBLK) * YP;
;   { h16* stg = (h16*)(shm + LDS_OST) + wid * 2048;
; #pragma unroll
;     for (int r = 0; r < 16; ++r) { const int orow = crow(r, hi);
; #pragma unroll
;       for (int d0 = 0; d0 < 2; ++d0) stg[orow * 64 + d0 * 32 + r32] = (h16)(o[d0][r] * rli[r]); }
;     asm volatile("s_waitcnt lgkmcnt(0)" ::: "memory");
; #pragma unroll
;     for (int i = 0; i < 4; ++i) { const int row = i * 8 + (lane >> 3), ch = lane & 7; const h16x8 v = *(const h16x8*)(stg + row * 64 + ch * 8); const h16x8 z = zg[i];
;       u32x4 w; w.x = cvtpk_h((float)v[0] * siluf((float)z[0]), (float)v[1] * siluf((float)z[1])); w.y = cvtpk_h((float)v[2] * siluf((float)z[2]), (float)v[3] * siluf((float)z[3]));
;       w.z = cvtpk_h((float)v[4] * siluf((float)z[4]), (float)v[5] * siluf((float)z[5])); w.w = cvtpk_h((float)v[6] * siluf((float)z[6]), (float)v[7] * siluf((float)z[7]));
;       *(GAS u32x4*)(Yw + (long)row * YP + ch * 8) = w; } }
	v_rcp_f32_e32 v64, v52
	v_rcp_f32_e32 v65, v53
	ds_read2_b32 v[52:53], v51 offset1:1
	ds_write_b16 v66, v2 offset:52608
	v_fma_mixlo_f16 v2, v9, v61, 0
	ds_write_b16 v66, v2 offset:52672
	v_fma_mixlo_f16 v2, v26, v62, 0
	ds_write_b16 v66, v2 offset:53248
	v_fma_mixlo_f16 v2, v10, v62, 0
	v_add_u32_e32 v50, 0xc0e8, v50
	ds_write_b16 v66, v2 offset:53312
	v_fma_mixlo_f16 v2, v27, v63, 0
	ds_read2_b32 v[50:51], v50 offset1:1
	ds_write_b16 v66, v2 offset:53376
	v_fma_mixlo_f16 v2, v11, v63, 0
	s_waitcnt lgkmcnt(6)
	v_rcp_f32_e32 v52, v52
	ds_write_b16 v66, v2 offset:53440
	v_fma_mixlo_f16 v2, v28, v64, 0
	ds_write_b16 v66, v2 offset:53504
	v_fma_mixlo_f16 v2, v12, v64, 0
	v_rcp_f32_e32 v53, v53
	ds_write_b16 v66, v2 offset:53568
	v_fma_mixlo_f16 v2, v29, v65, 0
	ds_write_b16 v66, v2 offset:53632
	v_fma_mixlo_f16 v2, v13, v65, 0
	s_waitcnt lgkmcnt(5)
	v_rcp_f32_e32 v50, v50
	ds_write_b16 v66, v2 offset:53696
	v_fma_mixlo_f16 v2, v30, v52, 0
	ds_write_b16 v66, v2 offset:54272
	v_fma_mixlo_f16 v2, v14, v52, 0
	v_rcp_f32_e32 v51, v51
	ds_write_b16 v66, v2 offset:54336
	v_fma_mixlo_f16 v2, v31, v53, 0
	ds_write_b16 v66, v2 offset:54400
	v_fma_mixlo_f16 v2, v15, v53, 0
	ds_write_b16 v66, v2 offset:54464
	v_fma_mixlo_f16 v2, v32, v50, 0
	ds_write_b16 v66, v2 offset:54528
	v_fma_mixlo_f16 v2, v16, v50, 0
	s_lshl_b64 s[0:1], s[8:9], 11
	ds_write_b16 v66, v2 offset:54592
	v_fma_mixlo_f16 v2, v33, v51, 0
	s_waitcnt vmcnt(3)
	v_cvt_f32_f16_e32 v8, v46
	v_fma_mixlo_f16 v18, v18, v54, 0
	ds_write_b16 v66, v2 offset:54656
	v_fma_mixlo_f16 v2, v17, v51, 0
	s_add_u32 s0, s79, s0
	ds_write_b16 v66, v18 offset:51200
	ds_write_b16 v66, v2 offset:54720
	s_addc_u32 s1, s80, s1
	v_lshrrev_b32_e32 v10, 3, v249
	v_add_u32_e32 v11, s4, v0
	s_waitcnt lgkmcnt(0)
	v_lshl_add_u64 v[6:7], s[0:1], 0, v[0:1]
	v_lshl_add_u32 v0, v10, 7, v11
	ds_read_b128 v[2:5], v0 offset:51200
	v_mul_f32_e32 v0, 0xbfb8aa3b, v8
	v_exp_f32_e32 v0, v0
	v_cvt_f32_f16_sdwa v9, v46 dst_sel:DWORD dst_unused:UNUSED_PAD src0_sel:WORD_1
	s_waitcnt lgkmcnt(0)
	v_cvt_f32_f16_e32 v14, v2
	v_add_f32_e32 v0, 1.0, v0
	v_rcp_f32_e32 v12, v0
	v_mul_f32_e32 v0, 0xbfb8aa3b, v9
	v_exp_f32_e32 v0, v0
	v_cvt_f32_f16_sdwa v15, v2 dst_sel:DWORD dst_unused:UNUSED_PAD src0_sel:WORD_1
	v_add_f32_e32 v0, 1.0, v0
	v_rcp_f32_e32 v13, v0
	s_nop 0
	v_pk_mul_f32 v[8:9], v[12:13], v[8:9]
	s_nop 0
	v_pk_mul_f32 v[8:9], v[8:9], v[14:15]
	v_cvt_f32_f16_e32 v14, v3
	v_cvt_pk_f16_f32 v2, v8, v9
	v_cvt_f32_f16_e32 v8, v47
	v_cvt_f32_f16_sdwa v9, v47 dst_sel:DWORD dst_unused:UNUSED_PAD src0_sel:WORD_1
	v_cvt_f32_f16_sdwa v15, v3 dst_sel:DWORD dst_unused:UNUSED_PAD src0_sel:WORD_1
	v_mul_f32_e32 v0, 0xbfb8aa3b, v8
	v_exp_f32_e32 v0, v0
	s_nop 0
	v_add_f32_e32 v0, 1.0, v0
	v_rcp_f32_e32 v12, v0
	v_mul_f32_e32 v0, 0xbfb8aa3b, v9
	v_exp_f32_e32 v0, v0
	s_nop 0
	v_add_f32_e32 v0, 1.0, v0
	v_rcp_f32_e32 v13, v0
	s_nop 0
	v_pk_mul_f32 v[8:9], v[12:13], v[8:9]
	s_nop 0
	v_pk_mul_f32 v[8:9], v[8:9], v[14:15]
	v_cvt_f32_f16_e32 v14, v4
	v_cvt_pk_f16_f32 v3, v8, v9
	v_cvt_f32_f16_e32 v8, v48
	v_cvt_f32_f16_sdwa v9, v48 dst_sel:DWORD dst_unused:UNUSED_PAD src0_sel:WORD_1
	v_cvt_f32_f16_sdwa v15, v4 dst_sel:DWORD dst_unused:UNUSED_PAD src0_sel:WORD_1
	v_mul_f32_e32 v0, 0xbfb8aa3b, v8
	v_exp_f32_e32 v0, v0
	s_nop 0
	v_add_f32_e32 v0, 1.0, v0
	v_rcp_f32_e32 v12, v0
	v_mul_f32_e32 v0, 0xbfb8aa3b, v9
	v_exp_f32_e32 v0, v0
	s_nop 0
	v_add_f32_e32 v0, 1.0, v0
	v_rcp_f32_e32 v13, v0
	s_nop 0
	v_pk_mul_f32 v[8:9], v[12:13], v[8:9]
	s_nop 0
	v_pk_mul_f32 v[8:9], v[8:9], v[14:15]
	v_cvt_f32_f16_e32 v14, v5
	v_cvt_pk_f16_f32 v4, v8, v9
	v_cvt_f32_f16_e32 v8, v49
	v_cvt_f32_f16_sdwa v9, v49 dst_sel:DWORD dst_unused:UNUSED_PAD src0_sel:WORD_1
	v_cvt_f32_f16_sdwa v15, v5 dst_sel:DWORD dst_unused:UNUSED_PAD src0_sel:WORD_1
	v_mul_f32_e32 v0, 0xbfb8aa3b, v8
	v_exp_f32_e32 v0, v0
	s_nop 0
	v_add_f32_e32 v0, 1.0, v0
	v_rcp_f32_e32 v12, v0
	v_mul_f32_e32 v0, 0xbfb8aa3b, v9
	v_exp_f32_e32 v0, v0
	s_nop 0
	v_add_f32_e32 v0, 1.0, v0
	v_rcp_f32_e32 v13, v0
	v_lshlrev_b32_e32 v0, 11, v10
	v_pk_mul_f32 v[8:9], v[12:13], v[8:9]
	s_nop 0
	v_pk_mul_f32 v[8:9], v[8:9], v[14:15]
	s_nop 0
	v_cvt_pk_f16_f32 v5, v8, v9
	v_lshl_add_u64 v[8:9], v[6:7], 0, v[0:1]
	v_or_b32_e32 v0, 8, v10
	global_store_dwordx4 v[8:9], v[2:5], off offset:512 sc1
	s_waitcnt vmcnt(3)
	v_cvt_f32_f16_sdwa v9, v42 dst_sel:DWORD dst_unused:UNUSED_PAD src0_sel:WORD_1
	v_cvt_f32_f16_e32 v8, v42
	v_lshl_add_u32 v2, v0, 7, v11
	ds_read_b128 v[2:5], v2 offset:51200
	v_lshlrev_b32_e32 v0, 11, v0
	v_mul_f32_e32 v12, 0xbfb8aa3b, v8
	v_exp_f32_e32 v12, v12
	s_waitcnt lgkmcnt(0)
; #define GAS __attribute__((address_space(1)))
; __device__ __forceinline__ float siluf(float x) { return x * __builtin_amdgcn_rcpf(1.f + __builtin_amdgcn_exp2f(-1.4426950408889634f * x)); }
; __device__ __forceinline__ unsigned cvtpk_h(float lo, float hi) { f32x2 v = {lo, hi}; h16x2 b = __builtin_convertvector(v, h16x2); return __builtin_bit_cast(unsigned, b); }
; template <int THRL, bool FIXM> __device__ __forceinline__ bool attn_unit(const h16* Qrows, const h16* __restrict__ Kh, const h16* __restrict__ Vh, const int NT, h16* Yrows, const h16* BZrows, char* shm, const int tid, const float mfix, ...
;     ...
;     for (int i = 0; i < 4; ++i) { const int row = i * 8 + (lane >> 3), ch = lane & 7; const h16x8 v = *(const h16x8*)(stg + row * 64 + ch * 8); const h16x8 z = zg[i];
;       u32x4 w; w.x = cvtpk_h((float)v[0] * siluf((float)z[0]), (float)v[1] * siluf((float)z[1])); w.y = cvtpk_h((float)v[2] * siluf((float)z[2]), (float)v[3] * siluf((float)z[3]));
;       w.z = cvtpk_h((float)v[4] * siluf((float)z[4]), (float)v[5] * siluf((float)z[5])); w.w = cvtpk_h((float)v[6] * siluf((float)z[6]), (float)v[7] * siluf((float)z[7]));
;       *(GAS u32x4*)(Yw + (long)row * YP + ch * 8) = w; } }
	v_cvt_f32_f16_e32 v14, v2
	v_cvt_f32_f16_sdwa v15, v2 dst_sel:DWORD dst_unused:UNUSED_PAD src0_sel:WORD_1
	v_mul_f32_e32 v2, 0xbfb8aa3b, v9
	v_exp_f32_e32 v2, v2
	v_add_f32_e32 v12, 1.0, v12
	v_rcp_f32_e32 v12, v12
	v_add_f32_e32 v2, 1.0, v2
	v_rcp_f32_e32 v13, v2
	s_nop 0
	v_pk_mul_f32 v[8:9], v[12:13], v[8:9]
	s_nop 0
	v_pk_mul_f32 v[8:9], v[8:9], v[14:15]
	v_cvt_f32_f16_e32 v14, v3
	v_cvt_pk_f16_f32 v2, v8, v9
	v_cvt_f32_f16_sdwa v9, v43 dst_sel:DWORD dst_unused:UNUSED_PAD src0_sel:WORD_1
	v_cvt_f32_f16_e32 v8, v43
	v_cvt_f32_f16_sdwa v15, v3 dst_sel:DWORD dst_unused:UNUSED_PAD src0_sel:WORD_1
	v_mul_f32_e32 v3, 0xbfb8aa3b, v9
	v_mul_f32_e32 v12, 0xbfb8aa3b, v8
	v_exp_f32_e32 v12, v12
	v_exp_f32_e32 v3, v3
	v_add_f32_e32 v12, 1.0, v12
	v_add_f32_e32 v3, 1.0, v3
	v_rcp_f32_e32 v12, v12
	v_rcp_f32_e32 v13, v3
	s_nop 0
	v_pk_mul_f32 v[8:9], v[12:13], v[8:9]
	s_nop 0
	v_pk_mul_f32 v[8:9], v[8:9], v[14:15]
	v_cvt_f32_f16_e32 v14, v4
	v_cvt_pk_f16_f32 v3, v8, v9
	v_cvt_f32_f16_sdwa v9, v44 dst_sel:DWORD dst_unused:UNUSED_PAD src0_sel:WORD_1
	v_cvt_f32_f16_e32 v8, v44
	v_cvt_f32_f16_sdwa v15, v4 dst_sel:DWORD dst_unused:UNUSED_PAD src0_sel:WORD_1
	v_mul_f32_e32 v4, 0xbfb8aa3b, v9
	v_mul_f32_e32 v12, 0xbfb8aa3b, v8
	v_exp_f32_e32 v12, v12
	v_exp_f32_e32 v4, v4
	v_add_f32_e32 v12, 1.0, v12
	v_add_f32_e32 v4, 1.0, v4
	v_rcp_f32_e32 v12, v12
	v_rcp_f32_e32 v13, v4
	s_nop 0
	v_pk_mul_f32 v[8:9], v[12:13], v[8:9]
	s_nop 0
	v_pk_mul_f32 v[8:9], v[8:9], v[14:15]
	v_cvt_f32_f16_e32 v14, v5
	v_cvt_pk_f16_f32 v4, v8, v9
	v_cvt_f32_f16_sdwa v9, v45 dst_sel:DWORD dst_unused:UNUSED_PAD src0_sel:WORD_1
	v_cvt_f32_f16_e32 v8, v45
	v_cvt_f32_f16_sdwa v15, v5 dst_sel:DWORD dst_unused:UNUSED_PAD src0_sel:WORD_1
	v_mul_f32_e32 v5, 0xbfb8aa3b, v9
	v_mul_f32_e32 v12, 0xbfb8aa3b, v8
	v_exp_f32_e32 v12, v12
	v_exp_f32_e32 v5, v5
	v_add_f32_e32 v12, 1.0, v12
	v_add_f32_e32 v5, 1.0, v5
	v_rcp_f32_e32 v12, v12
	v_rcp_f32_e32 v13, v5
	s_nop 0
	v_pk_mul_f32 v[8:9], v[12:13], v[8:9]
	s_nop 0
	v_pk_mul_f32 v[8:9], v[8:9], v[14:15]
	s_nop 0
	v_cvt_pk_f16_f32 v5, v8, v9
	v_lshl_add_u64 v[8:9], v[6:7], 0, v[0:1]
	v_or_b32_e32 v0, 16, v10
	global_store_dwordx4 v[8:9], v[2:5], off offset:512 sc1
	s_waitcnt vmcnt(3)
	v_cvt_f32_f16_sdwa v9, v38 dst_sel:DWORD dst_unused:UNUSED_PAD src0_sel:WORD_1
	v_cvt_f32_f16_e32 v8, v38
	v_lshl_add_u32 v2, v0, 7, v11
	ds_read_b128 v[2:5], v2 offset:51200
	v_lshlrev_b32_e32 v0, 11, v0
	v_mul_f32_e32 v12, 0xbfb8aa3b, v8
	v_exp_f32_e32 v12, v12
	s_waitcnt lgkmcnt(0)
; #define GAS __attribute__((address_space(1)))
; __device__ __forceinline__ float siluf(float x) { return x * __builtin_amdgcn_rcpf(1.f + __builtin_amdgcn_exp2f(-1.4426950408889634f * x)); }
; __device__ __forceinline__ unsigned cvtpk_h(float lo, float hi) { f32x2 v = {lo, hi}; h16x2 b = __builtin_convertvector(v, h16x2); return __builtin_bit_cast(unsigned, b); }
; template <int THRL, bool FIXM> __device__ __forceinline__ bool attn_unit(const h16* Qrows, const h16* __restrict__ Kh, const h16* __restrict__ Vh, const int NT, h16* Yrows, const h16* BZrows, char* shm, const int tid, const float mfix, ...
;     ...
;     for (int i = 0; i < 4; ++i) { const int row = i * 8 + (lane >> 3), ch = lane & 7; const h16x8 v = *(const h16x8*)(stg + row * 64 + ch * 8); const h16x8 z = zg[i];
;       u32x4 w; w.x = cvtpk_h((float)v[0] * siluf((float)z[0]), (float)v[1] * siluf((float)z[1])); w.y = cvtpk_h((float)v[2] * siluf((float)z[2]), (float)v[3] * siluf((float)z[3]));
;       w.z = cvtpk_h((float)v[4] * siluf((float)z[4]), (float)v[5] * siluf((float)z[5])); w.w = cvtpk_h((float)v[6] * siluf((float)z[6]), (float)v[7] * siluf((float)z[7]));
;       *(GAS u32x4*)(Yw + (long)row * YP + ch * 8) = w; } }
;   asm volatile("s_waitcnt lgkmcnt(0)\n\ts_barrier" ::: "memory");
	v_cvt_f32_f16_e32 v14, v2
	v_cvt_f32_f16_sdwa v15, v2 dst_sel:DWORD dst_unused:UNUSED_PAD src0_sel:WORD_1
	v_mul_f32_e32 v2, 0xbfb8aa3b, v9
	v_exp_f32_e32 v2, v2
	v_add_f32_e32 v12, 1.0, v12
	v_rcp_f32_e32 v12, v12
	v_add_f32_e32 v2, 1.0, v2
	v_rcp_f32_e32 v13, v2
	s_nop 0
	v_pk_mul_f32 v[8:9], v[12:13], v[8:9]
	s_nop 0
	v_pk_mul_f32 v[8:9], v[8:9], v[14:15]
	v_cvt_f32_f16_e32 v14, v3
	v_cvt_pk_f16_f32 v2, v8, v9
	v_cvt_f32_f16_sdwa v9, v39 dst_sel:DWORD dst_unused:UNUSED_PAD src0_sel:WORD_1
	v_cvt_f32_f16_e32 v8, v39
	v_cvt_f32_f16_sdwa v15, v3 dst_sel:DWORD dst_unused:UNUSED_PAD src0_sel:WORD_1
	v_mul_f32_e32 v3, 0xbfb8aa3b, v9
	v_mul_f32_e32 v12, 0xbfb8aa3b, v8
	v_exp_f32_e32 v12, v12
	v_exp_f32_e32 v3, v3
	v_add_f32_e32 v12, 1.0, v12
	v_add_f32_e32 v3, 1.0, v3
	v_rcp_f32_e32 v12, v12
	v_rcp_f32_e32 v13, v3
	s_nop 0
	v_pk_mul_f32 v[8:9], v[12:13], v[8:9]
	s_nop 0
	v_pk_mul_f32 v[8:9], v[8:9], v[14:15]
	v_cvt_f32_f16_e32 v14, v4
	v_cvt_pk_f16_f32 v3, v8, v9
	v_cvt_f32_f16_sdwa v9, v40 dst_sel:DWORD dst_unused:UNUSED_PAD src0_sel:WORD_1
	v_cvt_f32_f16_e32 v8, v40
	v_cvt_f32_f16_sdwa v15, v4 dst_sel:DWORD dst_unused:UNUSED_PAD src0_sel:WORD_1
	v_mul_f32_e32 v4, 0xbfb8aa3b, v9
	v_mul_f32_e32 v12, 0xbfb8aa3b, v8
	v_exp_f32_e32 v12, v12
	v_exp_f32_e32 v4, v4
	v_add_f32_e32 v12, 1.0, v12
	v_add_f32_e32 v4, 1.0, v4
	v_rcp_f32_e32 v12, v12
	v_rcp_f32_e32 v13, v4
	s_nop 0
	v_pk_mul_f32 v[8:9], v[12:13], v[8:9]
	s_nop 0
	v_pk_mul_f32 v[8:9], v[8:9], v[14:15]
	v_cvt_f32_f16_e32 v14, v5
	v_cvt_pk_f16_f32 v4, v8, v9
	v_cvt_f32_f16_sdwa v9, v41 dst_sel:DWORD dst_unused:UNUSED_PAD src0_sel:WORD_1
	v_cvt_f32_f16_e32 v8, v41
	v_cvt_f32_f16_sdwa v15, v5 dst_sel:DWORD dst_unused:UNUSED_PAD src0_sel:WORD_1
	v_mul_f32_e32 v5, 0xbfb8aa3b, v9
	v_mul_f32_e32 v12, 0xbfb8aa3b, v8
	v_exp_f32_e32 v12, v12
	v_exp_f32_e32 v5, v5
	v_add_f32_e32 v12, 1.0, v12
	v_add_f32_e32 v5, 1.0, v5
	v_rcp_f32_e32 v12, v12
	v_rcp_f32_e32 v13, v5
	s_nop 0
	v_pk_mul_f32 v[8:9], v[12:13], v[8:9]
	s_nop 0
	v_pk_mul_f32 v[8:9], v[8:9], v[14:15]
	s_nop 0
	v_cvt_pk_f16_f32 v5, v8, v9
	v_lshl_add_u64 v[8:9], v[6:7], 0, v[0:1]
	v_or_b32_e32 v0, 24, v10
	global_store_dwordx4 v[8:9], v[2:5], off offset:512 sc1
	s_waitcnt vmcnt(3)
	v_cvt_f32_f16_sdwa v9, v34 dst_sel:DWORD dst_unused:UNUSED_PAD src0_sel:WORD_1
	v_cvt_f32_f16_e32 v8, v34
	v_lshl_add_u32 v2, v0, 7, v11
	ds_read_b128 v[2:5], v2 offset:51200
	v_lshlrev_b32_e32 v0, 11, v0
	v_mul_f32_e32 v10, 0xbfb8aa3b, v8
	v_exp_f32_e32 v10, v10
	v_lshl_add_u64 v[6:7], v[6:7], 0, v[0:1]
	s_waitcnt lgkmcnt(0)
	v_cvt_f32_f16_e32 v12, v2
	v_cvt_f32_f16_sdwa v13, v2 dst_sel:DWORD dst_unused:UNUSED_PAD src0_sel:WORD_1
	v_mul_f32_e32 v2, 0xbfb8aa3b, v9
	v_exp_f32_e32 v2, v2
	v_add_f32_e32 v10, 1.0, v10
	v_rcp_f32_e32 v10, v10
	v_add_f32_e32 v2, 1.0, v2
	v_rcp_f32_e32 v11, v2
	s_nop 0
	v_pk_mul_f32 v[8:9], v[10:11], v[8:9]
	s_nop 0
	v_pk_mul_f32 v[8:9], v[8:9], v[12:13]
	v_cvt_f32_f16_e32 v12, v3
	v_cvt_pk_f16_f32 v2, v8, v9
	v_cvt_f32_f16_sdwa v9, v35 dst_sel:DWORD dst_unused:UNUSED_PAD src0_sel:WORD_1
	v_cvt_f32_f16_e32 v8, v35
	v_cvt_f32_f16_sdwa v13, v3 dst_sel:DWORD dst_unused:UNUSED_PAD src0_sel:WORD_1
	v_mul_f32_e32 v3, 0xbfb8aa3b, v9
	v_mul_f32_e32 v10, 0xbfb8aa3b, v8
	v_exp_f32_e32 v10, v10
	v_exp_f32_e32 v3, v3
	v_add_f32_e32 v10, 1.0, v10
	v_add_f32_e32 v3, 1.0, v3
	v_rcp_f32_e32 v10, v10
	v_rcp_f32_e32 v11, v3
	s_nop 0
	v_pk_mul_f32 v[8:9], v[10:11], v[8:9]
	s_nop 0
	v_pk_mul_f32 v[8:9], v[8:9], v[12:13]
	v_cvt_f32_f16_e32 v12, v4
	v_cvt_pk_f16_f32 v3, v8, v9
	v_cvt_f32_f16_sdwa v9, v36 dst_sel:DWORD dst_unused:UNUSED_PAD src0_sel:WORD_1
	v_cvt_f32_f16_e32 v8, v36
	v_cvt_f32_f16_sdwa v13, v4 dst_sel:DWORD dst_unused:UNUSED_PAD src0_sel:WORD_1
	v_mul_f32_e32 v4, 0xbfb8aa3b, v9
	v_mul_f32_e32 v10, 0xbfb8aa3b, v8
	v_exp_f32_e32 v10, v10
	v_exp_f32_e32 v4, v4
	v_add_f32_e32 v10, 1.0, v10
	v_add_f32_e32 v4, 1.0, v4
	v_rcp_f32_e32 v10, v10
	v_rcp_f32_e32 v11, v4
	s_nop 0
	v_pk_mul_f32 v[8:9], v[10:11], v[8:9]
	s_nop 0
	v_pk_mul_f32 v[8:9], v[8:9], v[12:13]
	v_cvt_f32_f16_e32 v12, v5
	v_cvt_pk_f16_f32 v4, v8, v9
	v_cvt_f32_f16_sdwa v9, v37 dst_sel:DWORD dst_unused:UNUSED_PAD src0_sel:WORD_1
	v_cvt_f32_f16_e32 v8, v37
	v_cvt_f32_f16_sdwa v13, v5 dst_sel:DWORD dst_unused:UNUSED_PAD src0_sel:WORD_1
	v_mul_f32_e32 v5, 0xbfb8aa3b, v9
	v_mul_f32_e32 v10, 0xbfb8aa3b, v8
	v_exp_f32_e32 v10, v10
	v_exp_f32_e32 v5, v5
	v_add_f32_e32 v10, 1.0, v10
	v_add_f32_e32 v5, 1.0, v5
	v_rcp_f32_e32 v10, v10
	v_rcp_f32_e32 v11, v5
	s_nop 0
	v_pk_mul_f32 v[8:9], v[10:11], v[8:9]
	s_nop 0
	v_pk_mul_f32 v[8:9], v[8:9], v[12:13]
	s_nop 0
	v_cvt_pk_f16_f32 v5, v8, v9
	global_store_dwordx4 v[6:7], v[2:5], off offset:512 sc1
	s_waitcnt lgkmcnt(0)
	s_barrier

.LBB0_265:
	s_add_i32 s82, s22, s19
	s_add_i32 s6, s82, -5
	s_mul_hi_i32 s7, s6, 0x2200
	s_mulk_i32 s6, 0x2200
	s_add_u32 s12, s16, s6
	v_cndmask_b32_e64 v0, 0, 1, s[8:9]
	s_addc_u32 s13, s17, s7
	v_cmp_ne_u32_e64 s[6:7], 1, v0
	s_andn2_b64 vcc, exec, s[8:9]
	s_cbranch_vccnz .LBB0_271
	v_cvt_f16_f32_e32 v0, v112
	ds_write_b16 v107, v0
	v_cvt_f16_f32_e32 v0, v113
	ds_write_b16 v107, v0 offset:128
	v_cvt_f16_f32_e32 v0, v114
	ds_write_b16 v107, v0 offset:256
	v_cvt_f16_f32_e32 v0, v115
	ds_write_b16 v107, v0 offset:384
	v_cvt_f16_f32_e32 v0, v116
	ds_write_b16 v107, v0 offset:1024
	v_cvt_f16_f32_e32 v0, v117
	ds_write_b16 v107, v0 offset:1152
	v_cvt_f16_f32_e32 v0, v118
	ds_write_b16 v107, v0 offset:1280
	v_cvt_f16_f32_e32 v0, v119
	ds_write_b16 v107, v0 offset:1408
	v_cvt_f16_f32_e32 v0, v120
	ds_write_b16 v107, v0 offset:2048
	v_cvt_f16_f32_e32 v0, v121
	ds_write_b16 v107, v0 offset:2176
	v_cvt_f16_f32_e32 v0, v122
	ds_write_b16 v107, v0 offset:2304
	v_cvt_f16_f32_e32 v0, v123
	ds_write_b16 v107, v0 offset:2432
	v_cvt_f16_f32_e32 v0, v124
	ds_write_b16 v107, v0 offset:3072
	v_cvt_f16_f32_e32 v0, v125
	ds_write_b16 v107, v0 offset:3200
	v_cvt_f16_f32_e32 v0, v126
	ds_write_b16 v107, v0 offset:3328
	v_cvt_f16_f32_e32 v0, v127
	ds_write_b16 v107, v0 offset:3456
	s_and_saveexec_b64 s[14:15], s[38:39]
	s_cbranch_execz .LBB0_268
	s_lshl_b32 s41, s20, 2
	s_add_u32 s42, s12, s41
	s_addc_u32 s43, s13, 0
	v_lshlrev_b32_e32 v0, 2, v106
	v_lshl_add_u64 v[2:3], s[42:43], 0, v[0:1]
	v_add_co_u32_e32 v2, vcc, 0x2000, v2
	s_nop 1
	v_addc_co_u32_e32 v3, vcc, 0, v3, vcc
	global_store_dword v[2:3], v110, off sc1
.LBB0_268:
	s_or_b64 exec, exec, s[14:15]
	s_and_saveexec_b64 s[14:15], s[10:11]
	s_cbranch_execz .LBB0_270
	global_store_dword v242, v111, s[12:13] offset:256 sc1

.LBB0_271:
	s_add_i32 s83, s23, s75
	v_lshl_add_u64 v[6:7], s[12:13], 0, v[108:109]
	s_add_i32 s12, s83, 0x12400
	s_waitcnt lgkmcnt(0)
	s_barrier
	v_add_u32_e32 v140, s18, v108
	v_mov_b32_e32 v0, s12
	ds_read_b128 v[2:5], v140
	ds_read_b32 v141, v0
	s_add_i32 s12, s83, 0x12480
	v_mov_b32_e32 v0, s12
	ds_read_b32 v0, v0
	s_waitcnt lgkmcnt(2)
	global_store_dwordx4 v[6:7], v[2:5], off sc1
	s_and_b64 vcc, exec, s[6:7]
	s_waitcnt lgkmcnt(1)
	v_max_f32_e32 v2, v141, v141
	v_max_f32_e32 v3, v111, v111
	v_max_f32_e32 v139, v3, v2
	s_cbranch_vccnz .LBB0_289
	v_add_u32_e32 v142, v128, v129
	v_add_u32_e32 v143, v134, v129
	s_nop 0
	ds_read_b64_tr_b16 v[18:19], v142
	ds_read_b64_tr_b16 v[20:21], v142 offset:256
	ds_read_b64_tr_b16 v[98:99], v143 offset:32768
	ds_read_b64_tr_b16 v[100:101], v143 offset:33024
	ds_read_b64_tr_b16 v[152:153], v142 offset:1024
	ds_read_b64_tr_b16 v[154:155], v142 offset:1280
	ds_read_b64_tr_b16 v[156:157], v143 offset:33792
	ds_read_b64_tr_b16 v[158:159], v143 offset:34048
	ds_read_b64_tr_b16 v[160:161], v142 offset:2048
	ds_read_b64_tr_b16 v[162:163], v142 offset:2304
	ds_read_b64_tr_b16 v[164:165], v143 offset:34816
	ds_read_b64_tr_b16 v[166:167], v143 offset:35072
	s_mov_b32 s41, s40
	s_mov_b32 s42, s40
	s_mov_b32 s43, s40
	s_waitcnt lgkmcnt(8)
	v_mfma_f32_32x32x16_f16 v[18:33], v[18:21], v[98:101], 0
	s_mov_b32 s44, s40
	s_mov_b32 s45, s40
	s_mov_b32 s46, s40
	s_mov_b32 s47, s40
	s_mov_b32 s48, s40
	s_mov_b32 s49, s40
	s_mov_b32 s50, s40
	s_mov_b32 s51, s40
	s_mov_b32 s52, s40
	s_mov_b32 s53, s40
	s_mov_b32 s54, s40
	s_mov_b32 s55, s40
	v_mov_b64_e32 v[2:3], s[40:41]
	v_mov_b64_e32 v[4:5], s[42:43]
	v_mov_b64_e32 v[6:7], s[44:45]
	v_mov_b64_e32 v[8:9], s[46:47]
	v_mov_b64_e32 v[10:11], s[48:49]
	v_mov_b64_e32 v[12:13], s[50:51]
	v_mov_b64_e32 v[14:15], s[52:53]
	v_mov_b64_e32 v[16:17], s[54:55]
	s_and_b64 vcc, exec, s[4:5]
	s_cbranch_vccnz .LBB0_274
	v_mov_b32_e32 v131, v130
	v_mov_b32_e32 v132, v130
	v_mov_b32_e32 v133, v130
	s_nop 1
	v_mfma_f32_32x32x16_f16 v[2:17], v[130:133], v[98:101], 0

.LBB0_291:
	s_add_i32 s12, s82, -4
	s_mul_hi_i32 s13, s12, 0x2200
	s_mulk_i32 s12, 0x2200
	s_add_u32 s12, s16, s12
	s_addc_u32 s13, s17, s13
	s_and_b64 vcc, exec, s[6:7]
	v_add_f32_e32 v111, v0, v139
	s_cbranch_vccnz .LBB0_297
	v_cvt_f16_f32_e32 v0, v112
	ds_write_b16 v135, v0
	v_cvt_f16_f32_e32 v0, v113
	ds_write_b16 v135, v0 offset:128
	v_cvt_f16_f32_e32 v0, v114
	ds_write_b16 v135, v0 offset:256
	v_cvt_f16_f32_e32 v0, v115
	ds_write_b16 v135, v0 offset:384
	v_cvt_f16_f32_e32 v0, v116
	ds_write_b16 v135, v0 offset:1024
	v_cvt_f16_f32_e32 v0, v117
	ds_write_b16 v135, v0 offset:1152
	v_cvt_f16_f32_e32 v0, v118
	ds_write_b16 v135, v0 offset:1280
	v_cvt_f16_f32_e32 v0, v119
	ds_write_b16 v135, v0 offset:1408
	v_cvt_f16_f32_e32 v0, v120
	ds_write_b16 v135, v0 offset:2048
	v_cvt_f16_f32_e32 v0, v121
	ds_write_b16 v135, v0 offset:2176
	v_cvt_f16_f32_e32 v0, v122
	ds_write_b16 v135, v0 offset:2304
	v_cvt_f16_f32_e32 v0, v123
	ds_write_b16 v135, v0 offset:2432
	v_cvt_f16_f32_e32 v0, v124
	ds_write_b16 v135, v0 offset:3072
	v_cvt_f16_f32_e32 v0, v125
	ds_write_b16 v135, v0 offset:3200
	v_cvt_f16_f32_e32 v0, v126
	ds_write_b16 v135, v0 offset:3328
	v_cvt_f16_f32_e32 v0, v127
	ds_write_b16 v135, v0 offset:3456
	s_and_saveexec_b64 s[14:15], s[38:39]
	s_cbranch_execz .LBB0_294
	s_lshl_b32 s41, s20, 2
	s_add_u32 s42, s12, s41
	s_addc_u32 s43, s13, 0
	v_lshlrev_b32_e32 v0, 2, v106
	v_lshl_add_u64 v[2:3], s[42:43], 0, v[0:1]
	v_add_co_u32_e32 v2, vcc, 0x2000, v2
	s_nop 1
	v_addc_co_u32_e32 v3, vcc, 0, v3, vcc
	global_store_dword v[2:3], v110, off sc1

.LBB0_297:
	v_lshl_add_u64 v[6:7], s[12:13], 0, v[108:109]
	s_add_i32 s12, s83, 0x12404
	s_waitcnt lgkmcnt(0)
	s_barrier
	v_add_u32_e32 v139, s21, v108
	v_mov_b32_e32 v0, s12
	ds_read_b128 v[2:5], v139
	ds_read_b32 v142, v0
	s_add_i32 s12, s83, 0x12484
	v_mov_b32_e32 v0, s12
	ds_read_b32 v0, v0
	s_waitcnt lgkmcnt(2)
	global_store_dwordx4 v[6:7], v[2:5], off sc1
	s_and_b64 vcc, exec, s[6:7]
	s_waitcnt lgkmcnt(1)
	v_max_f32_e32 v2, v142, v142
	v_max_f32_e32 v3, v111, v111
	v_max_f32_e32 v141, v3, v2
	s_cbranch_vccz .LBB0_300
	s_add_i32 s12, s19, -3
	s_cmp_gt_u32 s12, 17
	s_waitcnt lgkmcnt(0)
	v_add_f32_e32 v111, v0, v141
	s_cbranch_scc0 .LBB0_317

.LBB0_319:
	s_add_i32 s12, s82, -3
	s_mul_hi_i32 s13, s12, 0x2200
	s_mulk_i32 s12, 0x2200
	s_add_u32 s12, s16, s12
	s_addc_u32 s13, s17, s13
	s_and_b64 vcc, exec, s[6:7]
	s_cbranch_vccnz .LBB0_325
	v_cvt_f16_f32_e32 v0, v112
	ds_write_b16 v107, v0
	v_cvt_f16_f32_e32 v0, v113
	ds_write_b16 v107, v0 offset:128
	v_cvt_f16_f32_e32 v0, v114
	ds_write_b16 v107, v0 offset:256
	v_cvt_f16_f32_e32 v0, v115
	ds_write_b16 v107, v0 offset:384
	v_cvt_f16_f32_e32 v0, v116
	ds_write_b16 v107, v0 offset:1024
	v_cvt_f16_f32_e32 v0, v117
	ds_write_b16 v107, v0 offset:1152
	v_cvt_f16_f32_e32 v0, v118
	ds_write_b16 v107, v0 offset:1280
	v_cvt_f16_f32_e32 v0, v119
	ds_write_b16 v107, v0 offset:1408
	v_cvt_f16_f32_e32 v0, v120
	ds_write_b16 v107, v0 offset:2048
	v_cvt_f16_f32_e32 v0, v121
	ds_write_b16 v107, v0 offset:2176
	v_cvt_f16_f32_e32 v0, v122
	ds_write_b16 v107, v0 offset:2304
	v_cvt_f16_f32_e32 v0, v123
	ds_write_b16 v107, v0 offset:2432
	v_cvt_f16_f32_e32 v0, v124
	ds_write_b16 v107, v0 offset:3072
	v_cvt_f16_f32_e32 v0, v125
	ds_write_b16 v107, v0 offset:3200
	v_cvt_f16_f32_e32 v0, v126
	ds_write_b16 v107, v0 offset:3328
	v_cvt_f16_f32_e32 v0, v127
	ds_write_b16 v107, v0 offset:3456
	s_and_saveexec_b64 s[14:15], s[38:39]
	s_cbranch_execz .LBB0_322
	s_lshl_b32 s41, s20, 2
	s_add_u32 s42, s12, s41
	s_addc_u32 s43, s13, 0
	v_lshlrev_b32_e32 v0, 2, v106
	v_lshl_add_u64 v[2:3], s[42:43], 0, v[0:1]
	v_add_co_u32_e32 v2, vcc, 0x2000, v2
	s_nop 1
	v_addc_co_u32_e32 v3, vcc, 0, v3, vcc
	global_store_dword v[2:3], v110, off sc1

.LBB0_325:
	v_lshl_add_u64 v[6:7], s[12:13], 0, v[108:109]
	s_add_i32 s12, s83, 0x12408
	s_waitcnt lgkmcnt(0)
	s_barrier
	v_mov_b32_e32 v0, s12
	ds_read_b128 v[2:5], v140
	ds_read_b32 v141, v0
	s_add_i32 s12, s83, 0x12488
	v_mov_b32_e32 v0, s12
	ds_read_b32 v0, v0
	s_waitcnt lgkmcnt(2)
	global_store_dwordx4 v[6:7], v[2:5], off sc1
	s_and_b64 vcc, exec, s[6:7]
	s_waitcnt lgkmcnt(1)
	v_max_f32_e32 v2, v141, v141
	v_max_f32_e32 v3, v111, v111
	v_max_f32_e32 v140, v3, v2
	s_cbranch_vccnz .LBB0_343
	v_add_u32_e32 v142, v128, v129
	v_add_u32_e32 v143, v134, v129
	ds_read_b64_tr_b16 v[18:19], v142
	ds_read_b64_tr_b16 v[20:21], v142 offset:256
	ds_read_b64_tr_b16 v[98:99], v143 offset:32768
	ds_read_b64_tr_b16 v[100:101], v143 offset:33024
	ds_read_b64_tr_b16 v[152:153], v142 offset:1024
	ds_read_b64_tr_b16 v[154:155], v142 offset:1280
	ds_read_b64_tr_b16 v[156:157], v143 offset:33792
	ds_read_b64_tr_b16 v[158:159], v143 offset:34048
	ds_read_b64_tr_b16 v[160:161], v142 offset:2048
	ds_read_b64_tr_b16 v[162:163], v142 offset:2304
	ds_read_b64_tr_b16 v[164:165], v143 offset:34816
	ds_read_b64_tr_b16 v[166:167], v143 offset:35072
	s_mov_b32 s41, s40
	s_mov_b32 s42, s40
	s_mov_b32 s43, s40
	s_waitcnt lgkmcnt(8)
	v_mfma_f32_32x32x16_f16 v[18:33], v[18:21], v[98:101], 0
	s_mov_b32 s44, s40
	s_mov_b32 s45, s40
	s_mov_b32 s46, s40
	s_mov_b32 s47, s40
	s_mov_b32 s48, s40
	s_mov_b32 s49, s40
	s_mov_b32 s50, s40
	s_mov_b32 s51, s40
	s_mov_b32 s52, s40
	s_mov_b32 s53, s40
	s_mov_b32 s54, s40
	s_mov_b32 s55, s40
	v_mov_b64_e32 v[2:3], s[40:41]
	v_mov_b64_e32 v[4:5], s[42:43]
	v_mov_b64_e32 v[6:7], s[44:45]
	v_mov_b64_e32 v[8:9], s[46:47]
	v_mov_b64_e32 v[10:11], s[48:49]
	v_mov_b64_e32 v[12:13], s[50:51]
	v_mov_b64_e32 v[14:15], s[52:53]
	v_mov_b64_e32 v[16:17], s[54:55]
	s_and_b64 vcc, exec, s[4:5]
	s_cbranch_vccnz .LBB0_328
	v_mov_b32_e32 v131, v130
	v_mov_b32_e32 v132, v130
	v_mov_b32_e32 v133, v130
	s_nop 1
	v_mfma_f32_32x32x16_f16 v[2:17], v[130:133], v[98:101], 0

.LBB0_346:
	s_add_i32 s12, s82, -2
	s_mul_hi_i32 s13, s12, 0x2200
	s_mulk_i32 s12, 0x2200
	s_add_u32 s12, s16, s12
	s_addc_u32 s13, s17, s13
	s_and_b64 vcc, exec, s[6:7]
	s_cbranch_vccnz .LBB0_352
	v_cvt_f16_f32_e32 v0, v112
	ds_write_b16 v135, v0
	v_cvt_f16_f32_e32 v0, v113
	ds_write_b16 v135, v0 offset:128
	v_cvt_f16_f32_e32 v0, v114
	ds_write_b16 v135, v0 offset:256
	v_cvt_f16_f32_e32 v0, v115
	ds_write_b16 v135, v0 offset:384
	v_cvt_f16_f32_e32 v0, v116
	ds_write_b16 v135, v0 offset:1024
	v_cvt_f16_f32_e32 v0, v117
	ds_write_b16 v135, v0 offset:1152
	v_cvt_f16_f32_e32 v0, v118
	ds_write_b16 v135, v0 offset:1280
	v_cvt_f16_f32_e32 v0, v119
	ds_write_b16 v135, v0 offset:1408
	v_cvt_f16_f32_e32 v0, v120
	ds_write_b16 v135, v0 offset:2048
	v_cvt_f16_f32_e32 v0, v121
	ds_write_b16 v135, v0 offset:2176
	v_cvt_f16_f32_e32 v0, v122
	ds_write_b16 v135, v0 offset:2304
	v_cvt_f16_f32_e32 v0, v123
	ds_write_b16 v135, v0 offset:2432
	v_cvt_f16_f32_e32 v0, v124
	ds_write_b16 v135, v0 offset:3072
	v_cvt_f16_f32_e32 v0, v125
	ds_write_b16 v135, v0 offset:3200
	v_cvt_f16_f32_e32 v0, v126
	ds_write_b16 v135, v0 offset:3328
	v_cvt_f16_f32_e32 v0, v127
	ds_write_b16 v135, v0 offset:3456
	s_and_saveexec_b64 s[14:15], s[38:39]
	s_cbranch_execz .LBB0_349
	s_lshl_b32 s41, s20, 2
	s_add_u32 s42, s12, s41
	s_addc_u32 s43, s13, 0
	v_lshlrev_b32_e32 v0, 2, v106
	v_lshl_add_u64 v[2:3], s[42:43], 0, v[0:1]
	v_add_co_u32_e32 v2, vcc, 0x2000, v2
	s_nop 1
	v_addc_co_u32_e32 v3, vcc, 0, v3, vcc
	global_store_dword v[2:3], v110, off sc1

.LBB0_352:
	v_lshl_add_u64 v[6:7], s[12:13], 0, v[108:109]
	s_add_i32 s12, s83, 0x1240c
	s_waitcnt lgkmcnt(0)
	s_barrier
	v_mov_b32_e32 v0, s12
	ds_read_b128 v[2:5], v139
	ds_read_b32 v139, v0
	s_add_i32 s12, s83, 0x1248c
	v_mov_b32_e32 v0, s12
	ds_read_b32 v0, v0
	s_waitcnt lgkmcnt(2)
	global_store_dwordx4 v[6:7], v[2:5], off sc1
	s_and_b64 vcc, exec, s[6:7]
	s_waitcnt lgkmcnt(1)
	v_max_f32_e32 v2, v139, v139
	v_max_f32_e32 v3, v111, v111
	v_max_f32_e32 v138, v3, v2
	s_cbranch_vccnz .LBB0_261
	v_add_u32_e32 v140, v128, v129
	v_add_u32_e32 v141, v134, v129
	ds_read_b64_tr_b16 v[18:19], v140 offset:16384
	ds_read_b64_tr_b16 v[20:21], v140 offset:16640
	ds_read_b64_tr_b16 v[98:99], v141 offset:49152
	ds_read_b64_tr_b16 v[100:101], v141 offset:49408
	ds_read_b64_tr_b16 v[152:153], v140 offset:17408
	ds_read_b64_tr_b16 v[154:155], v140 offset:17664
	ds_read_b64_tr_b16 v[156:157], v141 offset:50176
	ds_read_b64_tr_b16 v[158:159], v141 offset:50432
	ds_read_b64_tr_b16 v[160:161], v140 offset:18432
	ds_read_b64_tr_b16 v[162:163], v140 offset:18688
	ds_read_b64_tr_b16 v[164:165], v141 offset:51200
	ds_read_b64_tr_b16 v[166:167], v141 offset:51456
	s_mov_b32 s41, s40
	s_mov_b32 s42, s40
	s_mov_b32 s43, s40
	s_waitcnt lgkmcnt(8)
	v_mfma_f32_32x32x16_f16 v[18:33], v[18:21], v[98:101], 0
	s_mov_b32 s44, s40
	s_mov_b32 s45, s40
	s_mov_b32 s46, s40
	s_mov_b32 s47, s40
	s_mov_b32 s48, s40
	s_mov_b32 s49, s40
	s_mov_b32 s50, s40
	s_mov_b32 s51, s40
	s_mov_b32 s52, s40
	s_mov_b32 s53, s40
	s_mov_b32 s54, s40
	s_mov_b32 s55, s40
	v_mov_b64_e32 v[2:3], s[40:41]
	v_mov_b64_e32 v[4:5], s[42:43]
	v_mov_b64_e32 v[6:7], s[44:45]
	v_mov_b64_e32 v[8:9], s[46:47]
	v_mov_b64_e32 v[10:11], s[48:49]
	v_mov_b64_e32 v[12:13], s[50:51]
	v_mov_b64_e32 v[14:15], s[52:53]
	v_mov_b64_e32 v[16:17], s[54:55]
	s_and_b64 vcc, exec, s[4:5]
	s_cbranch_vccnz .LBB0_355
	v_mov_b32_e32 v131, v130
	v_mov_b32_e32 v132, v130
	v_mov_b32_e32 v133, v130
	s_nop 1
	v_mfma_f32_32x32x16_f16 v[2:17], v[130:133], v[98:101], 0

; #define VM_WAIT() asm volatile("s_waitcnt vmcnt(0)" ::: "memory")
; __device__ __forceinline__ void scan_unit(unsigned char* ws, int b, int h, int dir, gu32* flag, LAS unsigned char* lds, int tid) {
;     ...
;     VM_WAIT(); __syncthreads();
;     if (tid == 0) { __builtin_amdgcn_fence(__ATOMIC_RELEASE, "agent"); VM_WAIT(); __hip_atomic_store(flag, 1u, RLX_AGENT); }
.LBB0_369:
	s_waitcnt vmcnt(0)
	v_cmp_eq_u32_e32 vcc, 0, v247
	s_barrier
	s_and_saveexec_b64 s[0:1], vcc
	s_cbranch_execz .LBB0_371
	s_lshl_b32 s2, s84, 6
	s_ashr_i32 s3, s2, 31
	s_lshl_b64 s[2:3], s[2:3], 2
	v_readlane_b32 s4, v253, 12
	s_nop 0
	s_waitcnt vmcnt(0)
	s_waitcnt vmcnt(0)
	v_readlane_b32 s5, v253, 13
	s_add_u32 s2, s4, s2
	s_addc_u32 s3, s5, s3
	global_store_dword v1, v240, s[2:3] sc1

; #define LAS __attribute__((address_space(3)))
; __device__ __forceinline__ float siluf(float x) { return x * __builtin_amdgcn_rcpf(1.f + __builtin_amdgcn_exp2f(-1.4426950408889634f * x)); }
; __device__ __forceinline__ float sigmf(float x) { return __builtin_amdgcn_rcpf(1.f + __builtin_amdgcn_exp2f(-1.4426950408889634f * x)); }
; __device__ __forceinline__ float oct_sum(float s) { s += dpp_f<0xB1>(s); s += dpp_f<0x4E>(s); s += dpp_f<0x141>(s); return s; }
; #define LDS_WAIT() asm volatile("s_waitcnt lgkmcnt(0)" ::: "memory")
; #define BAR_LDS() asm volatile("s_waitcnt lgkmcnt(0)\n\ts_barrier" ::: "memory")
; __device__ __forceinline__ int crow(int r, int hi) { return (r & 3) + 8 * (r >> 2) + 4 * hi; }
; __device__ __forceinline__ void mlstm_out_loop(unsigned char* ws, h16* Y, const float* ghead  , int u  , const int o_mout, const int o_end, const int ntc, const bool ctx_out, ...
;     ...
;         LAS float* wsf = (LAS float*)(lds + MO_WS) + wid * 64;
;         if (hi == 0) wsf[r32] = __builtin_amdgcn_rcpf(hden);
;         LDS_WAIT();
;         LAS h16* ost = (LAS h16*)(lds + MO_OST) + wid * 2048;
; #pragma unroll
;         for (int r = 0; r < 16; ++r) { const int orow = crow(r, hi); const float rl = wsf[orow];
; #pragma unroll
;             for (int d0 = 0; d0 < 2; ++d0) ost[orow * 64 + d0 * 32 + r32] = (h16)(o[d0][r] * rl); }
;         BAR_LDS();
; #pragma unroll
;         for (int ps = 0; ps < 2; ++ps) { const int row = 64 * ps + frow, wt = row >> 5, tr = row & 31; const LAS h16* pf = (const LAS h16*)(lds + MO_OST) + wt * 2048 + tr * 64 + fc8 * 8; const LAS h16* pb = pf + 4 * 2048;
;           const h16x8 af = *(const LAS h16x8*)pf, ab = *(const LAS h16x8*)pb;
;           float x[8]; float ss = 0.f;
; #pragma unroll
;           for (int j = 0; j < 8; ++j) { x[j] = (float)af[j] + (float)ab[j]; ss += x[j] * x[j]; }
;           ss = oct_sum(ss);
;           const float rn = __builtin_amdgcn_rsqf(ss * (1.f / 64.f) + EPS); const LAS float* gh = (const LAS float*)(lds + MO_GH) + h * 64 + fc8 * 8;
;           const h16x8 co = ps ? co1 : co0, cz = ps ? cz1 : cz0;
;           float y[8];
; #pragma unroll
;           for (int j = 0; j < 8; ++j) y[j] = sigmf((float)co[j]) * (x[j] * rn * gh[j]) * siluf((float)cz[j]);
.LBB0_391:
	s_or_b64 exec, exec, s[0:1]
	s_waitcnt lgkmcnt(0)
	v_add_u32_e32 v34, 0x9400, v180
	ds_read2_b32 v[34:35], v34 offset1:1
	s_waitcnt vmcnt(1)
	v_cvt_f32_f16_e32 v38, v106
	v_cvt_f32_f16_sdwa v39, v106 dst_sel:DWORD dst_unused:UNUSED_PAD src0_sel:WORD_1
	v_readlane_b32 s44, v251, 0
	v_readlane_b32 s45, v251, 1
	s_waitcnt lgkmcnt(0)
	v_fma_mixlo_f16 v2, v2, v34, 0
	ds_write_b16 v193, v2 offset:40960
	v_fma_mixlo_f16 v2, v18, v34, 0
	ds_write_b16 v193, v2 offset:41024
	v_fma_mixlo_f16 v2, v3, v35, 0
	ds_write_b16 v194, v2 offset:40960
	v_fma_mixlo_f16 v2, v19, v35, 0
	ds_write_b16 v194, v2 offset:41024
	v_add_u32_e32 v2, 0x9408, v180
	ds_read2_b32 v[2:3], v2 offset1:1
	s_mov_b32 s21, s40
	s_and_b64 vcc, exec, s[6:7]
	s_mov_b32 s76, s25
	v_readlane_b32 s46, v251, 2
	s_waitcnt lgkmcnt(0)
	v_fma_mixlo_f16 v4, v4, v2, 0
	v_fma_mixlo_f16 v2, v20, v2, 0
	ds_write_b16 v195, v2 offset:41024
	v_fma_mixlo_f16 v2, v5, v3, 0
	ds_write_b16 v196, v2 offset:40960
	v_fma_mixlo_f16 v2, v21, v3, 0
	ds_write_b16 v196, v2 offset:41024
	v_add_u32_e32 v2, 0x9420, v180
	ds_read2_b32 v[2:3], v2 offset1:1
	ds_write_b16 v195, v4 offset:40960
	v_readlane_b32 s47, v251, 3
	v_readlane_b32 s48, v251, 4
	v_readlane_b32 s49, v251, 5
	s_waitcnt lgkmcnt(1)
	v_fma_mixlo_f16 v4, v6, v2, 0
	v_fma_mixlo_f16 v2, v22, v2, 0
	ds_write_b16 v197, v2 offset:41024
	v_fma_mixlo_f16 v2, v7, v3, 0
	ds_write_b16 v198, v2 offset:40960
	v_fma_mixlo_f16 v2, v23, v3, 0
	ds_write_b16 v198, v2 offset:41024
	v_add_u32_e32 v2, 0x9428, v180
	ds_read2_b32 v[2:3], v2 offset1:1
	ds_write_b16 v197, v4 offset:40960
	v_readlane_b32 s50, v251, 6
	v_readlane_b32 s51, v251, 7
	s_waitcnt lgkmcnt(1)
	v_fma_mixlo_f16 v4, v8, v2, 0
	v_fma_mixlo_f16 v2, v24, v2, 0
	ds_write_b16 v199, v2 offset:41024
	v_fma_mixlo_f16 v2, v9, v3, 0
	ds_write_b16 v200, v2 offset:40960
	v_fma_mixlo_f16 v2, v25, v3, 0
	ds_write_b16 v200, v2 offset:41024
	v_add_u32_e32 v2, 0x9440, v180
	ds_read2_b32 v[2:3], v2 offset1:1
	ds_write_b16 v199, v4 offset:40960
	s_waitcnt lgkmcnt(1)
	v_fma_mixlo_f16 v4, v10, v2, 0
	v_fma_mixlo_f16 v2, v26, v2, 0
	ds_write_b16 v201, v2 offset:41024
	v_fma_mixlo_f16 v2, v11, v3, 0
	ds_write_b16 v202, v2 offset:40960
	v_fma_mixlo_f16 v2, v27, v3, 0
	ds_write_b16 v202, v2 offset:41024
	v_add_u32_e32 v2, 0x9448, v180
	ds_read2_b32 v[2:3], v2 offset1:1
	ds_write_b16 v201, v4 offset:40960
	v_cvt_f32_f16_e32 v10, v110
	s_waitcnt lgkmcnt(1)
	v_fma_mixlo_f16 v4, v12, v2, 0
	v_fma_mixlo_f16 v2, v28, v2, 0
	ds_write_b16 v203, v2 offset:41024
	v_fma_mixlo_f16 v2, v13, v3, 0
	ds_write_b16 v204, v2 offset:40960
	v_fma_mixlo_f16 v2, v29, v3, 0
	ds_write_b16 v204, v2 offset:41024
	v_add_u32_e32 v2, 0x9460, v180
	ds_read2_b32 v[2:3], v2 offset1:1
	ds_write_b16 v203, v4 offset:40960
	v_mul_f32_e32 v10, 0xbfb8aa3b, v10
	v_exp_f32_e32 v10, v10
	v_lshl_add_u32 v28, s20, 2, v164
	s_waitcnt lgkmcnt(1)
	v_fma_mixlo_f16 v4, v14, v2, 0
	v_fma_mixlo_f16 v2, v30, v2, 0
	ds_write_b16 v205, v2 offset:41024
	v_fma_mixlo_f16 v2, v15, v3, 0
	ds_write_b16 v206, v2 offset:40960
	v_fma_mixlo_f16 v2, v31, v3, 0
	ds_write_b16 v206, v2 offset:41024
	v_add_u32_e32 v2, 0x9468, v180
	ds_read2_b32 v[2:3], v2 offset1:1
	v_add_f32_e32 v10, 1.0, v10
	ds_write_b16 v205, v4 offset:40960
	v_mul_f32_e32 v29, 0xbfb8aa3b, v39
	v_exp_f32_e32 v29, v29
	s_waitcnt lgkmcnt(1)
	v_fma_mixlo_f16 v4, v16, v2, 0
	v_rcp_f32_e32 v16, v10
	v_cvt_f32_f16_sdwa v10, v110 dst_sel:DWORD dst_unused:UNUSED_PAD src0_sel:WORD_1
	v_fma_mixlo_f16 v2, v32, v2, 0
	ds_write_b16 v207, v2 offset:41024
	v_fma_mixlo_f16 v2, v17, v3, 0
	v_mul_f32_e32 v10, 0xbfb8aa3b, v10
	v_exp_f32_e32 v10, v10
	ds_write_b16 v213, v2 offset:40960
	v_fma_mixlo_f16 v2, v33, v3, 0
	ds_write_b16 v207, v4 offset:40960
	v_add_f32_e32 v10, 1.0, v10
	v_rcp_f32_e32 v17, v10
	v_cvt_f32_f16_e32 v10, v111
	ds_write_b16 v213, v2 offset:41024
	s_waitcnt lgkmcnt(0)
	s_barrier
	ds_read_b128 v[6:9], v181 offset:40960
	ds_read_b128 v[2:5], v181 offset:57344
	v_mul_f32_e32 v10, 0xbfb8aa3b, v10
	v_exp_f32_e32 v10, v10
	v_add_f32_e32 v29, 1.0, v29
	s_waitcnt lgkmcnt(1)
	v_cvt_f32_f16_sdwa v11, v9 dst_sel:DWORD dst_unused:UNUSED_PAD src0_sel:WORD_1
	s_waitcnt lgkmcnt(0)
	v_cvt_f32_f16_sdwa v13, v5 dst_sel:DWORD dst_unused:UNUSED_PAD src0_sel:WORD_1
	v_add_f32_e32 v10, 1.0, v10
	v_rcp_f32_e32 v18, v10
	v_cvt_f32_f16_sdwa v10, v111 dst_sel:DWORD dst_unused:UNUSED_PAD src0_sel:WORD_1
	v_cvt_f32_f16_e32 v12, v5
	v_cvt_f32_f16_sdwa v5, v4 dst_sel:DWORD dst_unused:UNUSED_PAD src0_sel:WORD_1
	v_cvt_f32_f16_e32 v4, v4
	v_mul_f32_e32 v10, 0xbfb8aa3b, v10
	v_exp_f32_e32 v10, v10
	v_rcp_f32_e32 v41, v29
	s_lshl_b32 s20, s20, 1
	v_add_f32_e32 v10, 1.0, v10
	v_rcp_f32_e32 v19, v10
	v_cvt_f32_f16_e32 v10, v112
	v_mul_f32_e32 v10, 0xbfb8aa3b, v10
	v_exp_f32_e32 v10, v10
	s_nop 0
	v_add_f32_e32 v10, 1.0, v10
	v_rcp_f32_e32 v22, v10
	v_cvt_f32_f16_sdwa v10, v112 dst_sel:DWORD dst_unused:UNUSED_PAD src0_sel:WORD_1
	v_mul_f32_e32 v10, 0xbfb8aa3b, v10
	v_exp_f32_e32 v10, v10
	s_nop 0
	v_add_f32_e32 v10, 1.0, v10
	v_rcp_f32_e32 v23, v10
	v_cvt_f32_f16_e32 v10, v113
	v_mul_f32_e32 v10, 0xbfb8aa3b, v10
	v_exp_f32_e32 v10, v10
	s_nop 0
	v_add_f32_e32 v10, 1.0, v10
	v_rcp_f32_e32 v20, v10
	v_cvt_f32_f16_sdwa v10, v113 dst_sel:DWORD dst_unused:UNUSED_PAD src0_sel:WORD_1
	v_mul_f32_e32 v10, 0xbfb8aa3b, v10
	v_exp_f32_e32 v10, v10
	s_nop 0
	v_add_f32_e32 v10, 1.0, v10
	v_rcp_f32_e32 v21, v10
	v_cvt_f32_f16_e32 v10, v9
	v_cvt_f32_f16_sdwa v9, v8 dst_sel:DWORD dst_unused:UNUSED_PAD src0_sel:WORD_1
	v_cvt_f32_f16_e32 v8, v8
	v_pk_add_f32 v[24:25], v[10:11], v[12:13]
	v_cvt_f32_f16_sdwa v13, v108 dst_sel:DWORD dst_unused:UNUSED_PAD src0_sel:WORD_1
; #define LAS __attribute__((address_space(3)))
; #define GAS __attribute__((address_space(1)))
; __device__ __forceinline__ float siluf(float x) { return x * __builtin_amdgcn_rcpf(1.f + __builtin_amdgcn_exp2f(-1.4426950408889634f * x)); }
; __device__ __forceinline__ float sigmf(float x) { return __builtin_amdgcn_rcpf(1.f + __builtin_amdgcn_exp2f(-1.4426950408889634f * x)); }
; __device__ __forceinline__ float oct_sum(float s) { s += dpp_f<0xB1>(s); s += dpp_f<0x4E>(s); s += dpp_f<0x141>(s); return s; }
; __device__ __forceinline__ unsigned cvtpk_h(float lo, float hi) { f32x2 v = {lo, hi}; h16x2 b = __builtin_convertvector(v, h16x2); return __builtin_bit_cast(unsigned, b); }
; __device__ __forceinline__ void mlstm_out_loop(unsigned char* ws, h16* Y, const float* ghead  , int u  , const int o_mout, const int o_end, const int ntc, const bool ctx_out, ...
;     ...
; #pragma unroll
;         for (int ps = 0; ps < 2; ++ps) { const int row = 64 * ps + frow, wt = row >> 5, tr = row & 31; const LAS h16* pf = (const LAS h16*)(lds + MO_OST) + wt * 2048 + tr * 64 + fc8 * 8; const LAS h16* pb = pf + 4 * 2048;
;           const h16x8 af = *(const LAS h16x8*)pf, ab = *(const LAS h16x8*)pb;
;           float x[8]; float ss = 0.f;
; #pragma unroll
;           for (int j = 0; j < 8; ++j) { x[j] = (float)af[j] + (float)ab[j]; ss += x[j] * x[j]; }
;           ss = oct_sum(ss);
;           const float rn = __builtin_amdgcn_rsqf(ss * (1.f / 64.f) + EPS); const LAS float* gh = (const LAS float*)(lds + MO_GH) + h * 64 + fc8 * 8;
;           const h16x8 co = ps ? co1 : co0, cz = ps ? cz1 : cz0;
;           float y[8];
; #pragma unroll
;           for (int j = 0; j < 8; ++j) y[j] = sigmf((float)co[j]) * (x[j] * rn * gh[j]) * siluf((float)cz[j]);
;           u32x4 w0; w0.x = cvtpk_h(y[0], y[1]); w0.y = cvtpk_h(y[2], y[3]); w0.z = cvtpk_h(y[4], y[5]); w0.w = cvtpk_h(y[6], y[7]);
;           *(GAS u32x4*)(Y + (rb + row) * D + 768 + h * 64 + fc8 * 8) = w0; }
	v_cvt_f32_f16_e32 v12, v108
	v_pk_add_f32 v[8:9], v[8:9], v[4:5]
	v_pk_mul_f32 v[26:27], v[24:25], v[24:25]
	v_mul_f32_e32 v15, 0xbfb8aa3b, v13
	v_mul_f32_e32 v10, 0xbfb8aa3b, v12
	v_exp_f32_e32 v10, v10
	v_exp_f32_e32 v15, v15
	v_pk_mul_f32 v[4:5], v[8:9], v[8:9]
	v_add_f32_e32 v10, 1.0, v10
	v_add_f32_e32 v15, 1.0, v15
	v_rcp_f32_e32 v14, v10
	v_rcp_f32_e32 v15, v15
	ds_read2_b32 v[10:11], v28 offset0:4 offset1:5
	v_pk_mul_f32 v[30:31], v[14:15], v[12:13]
	v_cvt_f32_f16_sdwa v13, v7 dst_sel:DWORD dst_unused:UNUSED_PAD src0_sel:WORD_1
	v_cvt_f32_f16_e32 v12, v7
	v_cvt_f32_f16_sdwa v15, v3 dst_sel:DWORD dst_unused:UNUSED_PAD src0_sel:WORD_1
	v_cvt_f32_f16_e32 v14, v3
	v_cvt_f32_f16_sdwa v7, v6 dst_sel:DWORD dst_unused:UNUSED_PAD src0_sel:WORD_1
	v_cvt_f32_f16_e32 v6, v6
	v_pk_add_f32 v[32:33], v[12:13], v[14:15]
	v_cvt_f32_f16_e32 v14, v107
	v_cvt_f32_f16_sdwa v15, v107 dst_sel:DWORD dst_unused:UNUSED_PAD src0_sel:WORD_1
	v_pk_mul_f32 v[34:35], v[32:33], v[32:33]
	ds_read2_b32 v[12:13], v28 offset0:2 offset1:3
	v_mul_f32_e32 v3, 0xbfb8aa3b, v14
	v_exp_f32_e32 v3, v3
	s_nop 0
	v_add_f32_e32 v3, 1.0, v3
	v_rcp_f32_e32 v36, v3
	v_mul_f32_e32 v3, 0xbfb8aa3b, v15
	v_exp_f32_e32 v3, v3
	s_nop 0
	v_add_f32_e32 v3, 1.0, v3
	v_rcp_f32_e32 v37, v3
	v_cvt_f32_f16_sdwa v3, v2 dst_sel:DWORD dst_unused:UNUSED_PAD src0_sel:WORD_1
	v_cvt_f32_f16_e32 v2, v2
	v_pk_mul_f32 v[36:37], v[36:37], v[14:15]
	v_mul_f32_e32 v14, 0xbfb8aa3b, v38
	v_pk_add_f32 v[2:3], v[6:7], v[2:3]
	v_exp_f32_e32 v14, v14
	v_pk_mul_f32 v[6:7], v[2:3], v[2:3]
	v_add_f32_e32 v14, 1.0, v14
	v_add_f32_e32 v6, v6, v7
	v_add_f32_e32 v6, v34, v6
	v_add_f32_e32 v6, v35, v6
	v_add_f32_e32 v4, v4, v6
	v_add_f32_e32 v4, v5, v4
	v_add_f32_e32 v4, v26, v4
	v_add_f32_e32 v4, v27, v4
	v_rcp_f32_e32 v40, v14
	ds_read2_b32 v[14:15], v28 offset1:1
	v_add_f32_dpp v4, v4, v4 quad_perm:[1,0,3,2] row_mask:0xf bank_mask:0xf bound_ctrl:1
	v_pk_mul_f32 v[38:39], v[40:41], v[38:39]
	s_nop 0
	v_add_f32_dpp v4, v4, v4 quad_perm:[2,3,0,1] row_mask:0xf bank_mask:0xf bound_ctrl:1
	s_nop 1
	v_add_f32_dpp v4, v4, v4 row_half_mirror row_mask:0xf bank_mask:0xf bound_ctrl:1
	v_fmamk_f32 v4, v4, 0x3c800000, v229
	v_rsq_f32_e32 v26, v4
	s_nop 0
	v_pk_mul_f32 v[6:7], v[8:9], v[26:27] op_sel_hi:[1,0]
	v_cvt_f32_f16_e32 v8, v109
	v_pk_mul_f32 v[2:3], v[2:3], v[26:27] op_sel_hi:[1,0]
	v_cvt_f32_f16_sdwa v9, v109 dst_sel:DWORD dst_unused:UNUSED_PAD src0_sel:WORD_1
	s_waitcnt lgkmcnt(0)
	v_pk_mul_f32 v[2:3], v[14:15], v[2:3]
	v_pk_mul_f32 v[4:5], v[32:33], v[26:27] op_sel_hi:[1,0]
	v_pk_mul_f32 v[2:3], v[16:17], v[2:3]
	v_mul_f32_e32 v16, 0xbfb8aa3b, v8
	v_pk_mul_f32 v[4:5], v[12:13], v[4:5]
	v_exp_f32_e32 v16, v16
	v_pk_mul_f32 v[4:5], v[18:19], v[4:5]
	v_mul_f32_e32 v19, 0xbfb8aa3b, v9
	v_exp_f32_e32 v19, v19
	v_add_f32_e32 v16, 1.0, v16
	v_rcp_f32_e32 v18, v16
	ds_read2_b32 v[16:17], v28 offset0:6 offset1:7
	v_add_f32_e32 v19, 1.0, v19
	v_pk_mul_f32 v[6:7], v[10:11], v[6:7]
	v_rcp_f32_e32 v19, v19
	v_pk_mul_f32 v[6:7], v[22:23], v[6:7]
	v_pk_mul_f32 v[2:3], v[38:39], v[2:3]
	v_pk_mul_f32 v[4:5], v[36:37], v[4:5]
	v_pk_mul_f32 v[6:7], v[30:31], v[6:7]
	v_pk_mul_f32 v[22:23], v[24:25], v[26:27] op_sel_hi:[1,0]
	v_cvt_pk_f16_f32 v2, v2, v3
	s_waitcnt lgkmcnt(0)
	v_pk_mul_f32 v[22:23], v[16:17], v[22:23]
	v_cvt_pk_f16_f32 v3, v4, v5
	v_cvt_pk_f16_f32 v4, v6, v7
	v_lshlrev_b64 v[6:7], 11, v[158:159]
	v_pk_mul_f32 v[20:21], v[20:21], v[22:23]
	v_pk_mul_f32 v[8:9], v[18:19], v[8:9]
	v_lshl_add_u64 v[6:7], s[44:45], 0, v[6:7]
	v_pk_mul_f32 v[8:9], v[8:9], v[20:21]
	v_lshl_add_u64 v[6:7], v[6:7], 0, s[20:21]
	v_cvt_pk_f16_f32 v5, v8, v9
	v_lshl_add_u64 v[6:7], v[6:7], 0, v[0:1]
	global_store_dwordx4 v[6:7], v[2:5], off offset:1536 sc1
	ds_read_b128 v[6:9], v182 offset:40960
	ds_read_b128 v[2:5], v182 offset:57344
	s_waitcnt vmcnt(1)
	v_cvt_f32_f16_e32 v36, v99
	v_cvt_f32_f16_sdwa v31, v100 dst_sel:DWORD dst_unused:UNUSED_PAD src0_sel:WORD_1
	v_cvt_f32_f16_e32 v30, v100
	v_cvt_f32_f16_sdwa v37, v99 dst_sel:DWORD dst_unused:UNUSED_PAD src0_sel:WORD_1
	s_waitcnt lgkmcnt(0)
; #define LAS __attribute__((address_space(3)))
; #define GAS __attribute__((address_space(1)))
; __device__ __forceinline__ float siluf(float x) { return x * __builtin_amdgcn_rcpf(1.f + __builtin_amdgcn_exp2f(-1.4426950408889634f * x)); }
; __device__ __forceinline__ float sigmf(float x) { return __builtin_amdgcn_rcpf(1.f + __builtin_amdgcn_exp2f(-1.4426950408889634f * x)); }
; __device__ __forceinline__ float oct_sum(float s) { s += dpp_f<0xB1>(s); s += dpp_f<0x4E>(s); s += dpp_f<0x141>(s); return s; }
; __device__ __forceinline__ unsigned cvtpk_h(float lo, float hi) { f32x2 v = {lo, hi}; h16x2 b = __builtin_convertvector(v, h16x2); return __builtin_bit_cast(unsigned, b); }
; #define BAR_LDS() asm volatile("s_waitcnt lgkmcnt(0)\n\ts_barrier" ::: "memory")
; __device__ __forceinline__ void mlstm_out_loop(unsigned char* ws, h16* Y, const float* ghead  , int u  , const int o_mout, const int o_end, const int ntc, const bool ctx_out, ...
;     ...
; #pragma unroll
;         for (int ps = 0; ps < 2; ++ps) { const int row = 64 * ps + frow, wt = row >> 5, tr = row & 31; const LAS h16* pf = (const LAS h16*)(lds + MO_OST) + wt * 2048 + tr * 64 + fc8 * 8; const LAS h16* pb = pf + 4 * 2048;
;           const h16x8 af = *(const LAS h16x8*)pf, ab = *(const LAS h16x8*)pb;
;           float x[8]; float ss = 0.f;
; #pragma unroll
;           for (int j = 0; j < 8; ++j) { x[j] = (float)af[j] + (float)ab[j]; ss += x[j] * x[j]; }
;           ss = oct_sum(ss);
;           const float rn = __builtin_amdgcn_rsqf(ss * (1.f / 64.f) + EPS); const LAS float* gh = (const LAS float*)(lds + MO_GH) + h * 64 + fc8 * 8;
;           const h16x8 co = ps ? co1 : co0, cz = ps ? cz1 : cz0;
;           float y[8];
; #pragma unroll
;           for (int j = 0; j < 8; ++j) y[j] = sigmf((float)co[j]) * (x[j] * rn * gh[j]) * siluf((float)cz[j]);
;           u32x4 w0; w0.x = cvtpk_h(y[0], y[1]); w0.y = cvtpk_h(y[2], y[3]); w0.z = cvtpk_h(y[4], y[5]); w0.w = cvtpk_h(y[6], y[7]);
;           *(GAS u32x4*)(Y + (rb + row) * D + 768 + h * 64 + fc8 * 8) = w0; }
;         BAR_LDS();
;         if (!more) break;
	v_cvt_f32_f16_sdwa v35, v3 dst_sel:DWORD dst_unused:UNUSED_PAD src0_sel:WORD_1
	v_cvt_f32_f16_e32 v34, v3
	v_mul_f32_e32 v3, 0xbfb8aa3b, v36
	v_exp_f32_e32 v3, v3
	v_mul_f32_e32 v32, 0xbfb8aa3b, v30
	v_mul_f32_e32 v33, 0xbfb8aa3b, v31
	v_exp_f32_e32 v32, v32
	v_exp_f32_e32 v33, v33
	v_add_f32_e32 v3, 1.0, v3
	v_rcp_f32_e32 v38, v3
	v_mul_f32_e32 v3, 0xbfb8aa3b, v37
	v_add_f32_e32 v32, 1.0, v32
	v_add_f32_e32 v33, 1.0, v33
	v_exp_f32_e32 v3, v3
	v_rcp_f32_e32 v32, v32
	v_rcp_f32_e32 v33, v33
	v_cvt_f32_f16_sdwa v27, v9 dst_sel:DWORD dst_unused:UNUSED_PAD src0_sel:WORD_1
	v_add_f32_e32 v3, 1.0, v3
	v_rcp_f32_e32 v39, v3
	v_pk_mul_f32 v[30:31], v[32:33], v[30:31]
	v_cvt_f32_f16_sdwa v33, v7 dst_sel:DWORD dst_unused:UNUSED_PAD src0_sel:WORD_1
	v_cvt_f32_f16_e32 v32, v7
	v_cvt_f32_f16_sdwa v7, v6 dst_sel:DWORD dst_unused:UNUSED_PAD src0_sel:WORD_1
	v_cvt_f32_f16_e32 v6, v6
	v_cvt_f32_f16_sdwa v3, v2 dst_sel:DWORD dst_unused:UNUSED_PAD src0_sel:WORD_1
	v_cvt_f32_f16_e32 v2, v2
	v_cvt_f32_f16_e32 v26, v9
	v_cvt_f32_f16_sdwa v29, v5 dst_sel:DWORD dst_unused:UNUSED_PAD src0_sel:WORD_1
	v_cvt_f32_f16_e32 v28, v5
	v_cvt_f32_f16_sdwa v9, v8 dst_sel:DWORD dst_unused:UNUSED_PAD src0_sel:WORD_1
	v_cvt_f32_f16_e32 v8, v8
	v_cvt_f32_f16_sdwa v5, v4 dst_sel:DWORD dst_unused:UNUSED_PAD src0_sel:WORD_1
	v_cvt_f32_f16_e32 v4, v4
	v_pk_add_f32 v[2:3], v[6:7], v[2:3]
	v_pk_add_f32 v[32:33], v[32:33], v[34:35]
	v_pk_mul_f32 v[6:7], v[2:3], v[2:3]
	v_pk_mul_f32 v[34:35], v[32:33], v[32:33]
	v_add_f32_e32 v6, v6, v7
	v_pk_add_f32 v[4:5], v[8:9], v[4:5]
	v_add_f32_e32 v6, v34, v6
	v_pk_mul_f32 v[8:9], v[4:5], v[4:5]
	v_add_f32_e32 v6, v35, v6
	v_pk_add_f32 v[26:27], v[26:27], v[28:29]
	v_add_f32_e32 v6, v8, v6
	v_pk_mul_f32 v[28:29], v[26:27], v[26:27]
	v_add_f32_e32 v6, v9, v6
	v_add_f32_e32 v6, v28, v6
	v_add_f32_e32 v6, v29, v6
	v_cvt_f32_f16_e32 v22, v104
	v_cvt_f32_f16_sdwa v23, v104 dst_sel:DWORD dst_unused:UNUSED_PAD src0_sel:WORD_1
	v_add_f32_dpp v6, v6, v6 quad_perm:[1,0,3,2] row_mask:0xf bank_mask:0xf bound_ctrl:1
	v_cvt_f32_f16_e32 v24, v105
	v_cvt_f32_f16_sdwa v25, v105 dst_sel:DWORD dst_unused:UNUSED_PAD src0_sel:WORD_1
	v_add_f32_dpp v6, v6, v6 quad_perm:[2,3,0,1] row_mask:0xf bank_mask:0xf bound_ctrl:1
	v_cvt_f32_f16_e32 v18, v102
	v_cvt_f32_f16_sdwa v19, v102 dst_sel:DWORD dst_unused:UNUSED_PAD src0_sel:WORD_1
	v_add_f32_dpp v6, v6, v6 row_half_mirror row_mask:0xf bank_mask:0xf bound_ctrl:1
	v_fmamk_f32 v6, v6, 0x3c800000, v229
	v_rsq_f32_e32 v6, v6
	v_cvt_f32_f16_e32 v20, v103
	v_cvt_f32_f16_sdwa v21, v103 dst_sel:DWORD dst_unused:UNUSED_PAD src0_sel:WORD_1
	v_mul_f32_e32 v22, 0xbfb8aa3b, v22
	v_pk_mul_f32 v[4:5], v[4:5], v[6:7] op_sel_hi:[1,0]
	v_pk_mul_f32 v[8:9], v[32:33], v[6:7] op_sel_hi:[1,0]
	v_pk_mul_f32 v[4:5], v[10:11], v[4:5]
	v_cvt_f32_f16_sdwa v11, v101 dst_sel:DWORD dst_unused:UNUSED_PAD src0_sel:WORD_1
	v_cvt_f32_f16_e32 v10, v101
	v_mul_f32_e32 v23, 0xbfb8aa3b, v23
	v_mul_f32_e32 v24, 0xbfb8aa3b, v24
	v_mul_f32_e32 v25, 0xbfb8aa3b, v25
	v_pk_mul_f32 v[36:37], v[38:39], v[36:37]
	v_cvt_f32_f16_sdwa v39, v98 dst_sel:DWORD dst_unused:UNUSED_PAD src0_sel:WORD_1
	v_cvt_f32_f16_e32 v38, v98
	v_pk_mul_f32 v[2:3], v[2:3], v[6:7] op_sel_hi:[1,0]
	v_pk_mul_f32 v[8:9], v[12:13], v[8:9]
	v_mul_f32_e32 v7, 0xbfb8aa3b, v10
	v_mul_f32_e32 v13, 0xbfb8aa3b, v11
	v_exp_f32_e32 v22, v22
	v_exp_f32_e32 v23, v23
	v_exp_f32_e32 v24, v24
	v_exp_f32_e32 v25, v25
	v_exp_f32_e32 v7, v7
	v_exp_f32_e32 v13, v13
	v_mul_f32_e32 v18, 0xbfb8aa3b, v18
	v_mul_f32_e32 v19, 0xbfb8aa3b, v19
	v_mul_f32_e32 v20, 0xbfb8aa3b, v20
	v_mul_f32_e32 v21, 0xbfb8aa3b, v21
	v_mul_f32_e32 v40, 0xbfb8aa3b, v38
	v_mul_f32_e32 v41, 0xbfb8aa3b, v39
	v_exp_f32_e32 v18, v18
	v_exp_f32_e32 v19, v19
	v_exp_f32_e32 v20, v20
	v_exp_f32_e32 v21, v21
	v_add_f32_e32 v22, 1.0, v22
	v_add_f32_e32 v23, 1.0, v23
	v_add_f32_e32 v24, 1.0, v24
	v_add_f32_e32 v25, 1.0, v25
	v_exp_f32_e32 v40, v40
	v_exp_f32_e32 v41, v41
	v_add_f32_e32 v7, 1.0, v7
	v_add_f32_e32 v13, 1.0, v13
	v_rcp_f32_e32 v22, v22
	v_rcp_f32_e32 v23, v23
	v_rcp_f32_e32 v24, v24
	v_rcp_f32_e32 v25, v25
	v_rcp_f32_e32 v12, v7
	v_rcp_f32_e32 v13, v13
	v_pk_mul_f32 v[6:7], v[26:27], v[6:7] op_sel_hi:[1,0]
	v_add_f32_e32 v18, 1.0, v18
	v_add_f32_e32 v19, 1.0, v19
	v_add_f32_e32 v20, 1.0, v20
	v_add_f32_e32 v21, 1.0, v21
	v_add_f32_e32 v40, 1.0, v40
	v_add_f32_e32 v41, 1.0, v41
	v_pk_mul_f32 v[6:7], v[16:17], v[6:7]
	v_rcp_f32_e32 v18, v18
	v_rcp_f32_e32 v19, v19
	v_rcp_f32_e32 v20, v20
	v_rcp_f32_e32 v21, v21
	v_rcp_f32_e32 v40, v40
	v_rcp_f32_e32 v41, v41
	v_pk_mul_f32 v[4:5], v[22:23], v[4:5]
	v_pk_mul_f32 v[6:7], v[24:25], v[6:7]
	v_pk_mul_f32 v[10:11], v[12:13], v[10:11]
	v_pk_mul_f32 v[4:5], v[30:31], v[4:5]
	v_pk_mul_f32 v[6:7], v[10:11], v[6:7]
	v_cvt_pk_f16_f32 v4, v4, v5
	v_cvt_pk_f16_f32 v5, v6, v7
	v_lshl_add_u64 v[6:7], s[16:17], 0, v[156:157]
	v_pk_mul_f32 v[2:3], v[14:15], v[2:3]
	v_lshlrev_b64 v[6:7], 11, v[6:7]
	v_pk_mul_f32 v[38:39], v[40:41], v[38:39]
	v_pk_mul_f32 v[2:3], v[18:19], v[2:3]
	v_pk_mul_f32 v[8:9], v[20:21], v[8:9]
	v_lshl_add_u64 v[6:7], s[44:45], 0, v[6:7]
	v_pk_mul_f32 v[2:3], v[38:39], v[2:3]
	v_pk_mul_f32 v[8:9], v[36:37], v[8:9]
	v_lshl_add_u64 v[6:7], v[6:7], 0, s[20:21]
	v_cvt_pk_f16_f32 v2, v2, v3
	v_cvt_pk_f16_f32 v3, v8, v9
	v_lshl_add_u64 v[6:7], v[6:7], 0, v[0:1]
	global_store_dwordx4 v[6:7], v[2:5], off offset:1536 sc1
	s_waitcnt lgkmcnt(0)
	s_barrier
	s_mov_b64 s[16:17], -1
	s_nop 0
	v_mov_b32_e32 v3, v215
	s_cbranch_vccnz .LBB0_436

; #define GAS __attribute__((address_space(1)))
; __device__ __forceinline__ unsigned cvtpk_h(float lo, float hi) { f32x2 v = {lo, hi}; h16x2 b = __builtin_convertvector(v, h16x2); return __builtin_bit_cast(unsigned, b); }
;     __device__ __forceinline__ void operator()(const f32x4 (&acc)[2][2][4][2], const pg8::Unit& u, int wr, int wc, int fr, int fq) const {
;     ...
;             for (int m = 0; m < 4; ++m) { if (half && ai == 1) continue; const unsigned rr = (unsigned)(ai * 128 + m * 16); const unsigned o = eoA + rr * (D * 2u); float ss = 0.f;
;                 const u32x4 la = *(const GAS u32x4*)((const GAS char*)ws + (unsigned)WS_X16 + o), lb = *(const GAS u32x4*)((const GAS char*)ws + (unsigned)WS_X16 + o + D * 2u);
;                 u32x4 xr[2];
; #pragma unroll
;                 for (int c = 0; c < 4; ++c) { const unsigned pa = (unsigned)__builtin_amdgcn_update_dpp(0, (int)la[c], 0xB1, 0xF, 0xF, false), pb = (unsigned)__builtin_amdgcn_update_dpp(0, (int)lb[c], 0xB1, 0xF, 0xF, false);
;                     xr[0][c] = odd ? pb : la[c]; xr[1][c] = odd ? lb[c] : pa; }
;                 u32x4 w[2], v[2];
; #pragma unroll
;                 for (int bj = 0; bj < 2; ++bj) { const h16x8 xb = __builtin_bit_cast(h16x8, xr[bj]);
;                     const f32x4 x0 = (f32x4){(float)xb[0], (float)xb[1], (float)xb[2], (float)xb[3]} + g4[bj][0] * acc[ai][bj][m][0], x1 = (f32x4){(float)xb[4], (float)xb[5], (float)xb[6], (float)xb[7]} + g4[bj][1] * acc[ai][bj][m][1];
;                     ss += ((x0[0] * x0[0] + x0[1] * x0[1]) + (x0[2] * x0[2] + x0[3] * x0[3])) + ((x1[0] * x1[0] + x1[1] * x1[1]) + (x1[2] * x1[2] + x1[3] * x1[3]));
;                     w[bj].x = cvtpk_h(x0[0], x0[1]); w[bj].y = cvtpk_h(x0[2], x0[3]); w[bj].z = cvtpk_h(x1[0], x1[1]); w[bj].w = cvtpk_h(x1[2], x1[3]);
;                     const f32x4 y0 = x0 * a4[bj][0], y1 = x1 * a4[bj][1]; v[bj].x = cvtpk_h(y0[0], y0[1]); v[bj].y = cvtpk_h(y0[2], y0[3]); v[bj].z = cvtpk_h(y1[0], y1[1]); v[bj].w = cvtpk_h(y1[2], y1[3]); }
;                 stg_line_pair(ws, (unsigned)WS_X16 + o, D * 2u, w[0], w[1], odd);
;                 if (an_off) stg_line_pair(ws, (unsigned)WS_XS + o, D * 2u, v[0], v[1], odd);
.LBB0_463:
	s_lshl_b32 s19, s0, 8
	v_and_b32_e32 v172, 0x1ffffe, v191
	s_add_i32 s19, s19, s84
	v_add_u32_e32 v172, s19, v172
	v_lshl_add_u32 v172, v172, 10, s5
	v_and_b32_e32 v0, 1, v191
	v_or_b32_e32 v172, s29, v172
	v_cmp_eq_u32_e64 s[0:1], 0, v0
	v_lshlrev_b32_e32 v172, 1, v172
	v_lshlrev_b32_e32 v0, 6, v0
	v_lshlrev_b32_e32 v173, 4, v192
	s_add_u32 s42, s38, 0x16f80000
	v_add3_u32 v0, v0, v173, v172
	s_addc_u32 s43, s39, 0
	global_load_dwordx4 v[172:175], v0, s[42:43]
	global_load_dwordx4 v[176:179], v0, s[42:43] offset:2048
	v_mov_b32_e32 v193, v1
	v_mov_b32_e32 v194, v1
	s_and_b64 vcc, exec, s[2:3]
	s_waitcnt vmcnt(0)
	v_add_u32_e32 v222, 0x8000, v0
	global_load_dwordx4 v[214:217], v222, s[42:43]
	global_load_dwordx4 v[218:221], v222, s[42:43] offset:2048
	v_mov_b32_dpp v193, v172 quad_perm:[1,0,3,2] row_mask:0xf bank_mask:0xf
	v_mov_b32_dpp v194, v176 quad_perm:[1,0,3,2] row_mask:0xf bank_mask:0xf
	v_cndmask_b32_e64 v194, v194, v172, s[0:1]
	v_cndmask_b32_e64 v195, v176, v193, s[0:1]
	v_mov_b32_e32 v172, v1
	v_mov_b32_e32 v176, v1
	s_nop 0
	v_mov_b32_dpp v172, v173 quad_perm:[1,0,3,2] row_mask:0xf bank_mask:0xf
	v_mov_b32_dpp v176, v177 quad_perm:[1,0,3,2] row_mask:0xf bank_mask:0xf
	v_cndmask_b32_e64 v176, v176, v173, s[0:1]
	v_cndmask_b32_e64 v196, v177, v172, s[0:1]
	v_mov_b32_e32 v172, v1
	v_mov_b32_e32 v173, v1
	s_nop 0
	v_mov_b32_dpp v172, v174 quad_perm:[1,0,3,2] row_mask:0xf bank_mask:0xf
	v_mov_b32_dpp v173, v178 quad_perm:[1,0,3,2] row_mask:0xf bank_mask:0xf
	v_cndmask_b32_e64 v193, v173, v174, s[0:1]
	v_cndmask_b32_e64 v197, v178, v172, s[0:1]
	v_mov_b32_e32 v172, v1
	v_mov_b32_e32 v173, v1
	v_cvt_f32_f16_e32 v174, v176
	v_mov_b32_dpp v172, v175 quad_perm:[1,0,3,2] row_mask:0xf bank_mask:0xf
	v_mov_b32_dpp v173, v179 quad_perm:[1,0,3,2] row_mask:0xf bank_mask:0xf
	v_cndmask_b32_e64 v178, v173, v175, s[0:1]
	v_cndmask_b32_e64 v198, v179, v172, s[0:1]
	v_cvt_f32_f16_e32 v172, v194
	v_cvt_f32_f16_sdwa v173, v194 dst_sel:DWORD dst_unused:UNUSED_PAD src0_sel:WORD_1
	v_cvt_f32_f16_sdwa v175, v176 dst_sel:DWORD dst_unused:UNUSED_PAD src0_sel:WORD_1
	v_add_u32_e32 v194, 0x16f80000, v0
	v_pk_fma_f32 v[176:177], v[160:161], v[50:51], v[172:173]
	v_cvt_f32_f16_e32 v160, v193
	v_cvt_f32_f16_sdwa v161, v193 dst_sel:DWORD dst_unused:UNUSED_PAD src0_sel:WORD_1
	v_cvt_f32_f16_e32 v172, v178
	v_cvt_f32_f16_sdwa v173, v178 dst_sel:DWORD dst_unused:UNUSED_PAD src0_sel:WORD_1
	v_pk_fma_f32 v[162:163], v[162:163], v[52:53], v[174:175]
	v_cvt_pk_f16_f32 v199, v176, v177
	v_cvt_pk_f16_f32 v200, v162, v163
	v_pk_fma_f32 v[158:159], v[158:159], v[56:57], v[172:173]
	v_pk_fma_f32 v[172:173], v[156:157], v[54:55], v[160:161]
	v_cvt_f32_f16_e32 v156, v195
	v_cvt_f32_f16_sdwa v157, v195 dst_sel:DWORD dst_unused:UNUSED_PAD src0_sel:WORD_1
	v_cvt_f32_f16_e32 v160, v196
	v_cvt_f32_f16_sdwa v161, v196 dst_sel:DWORD dst_unused:UNUSED_PAD src0_sel:WORD_1
	v_cvt_pk_f16_f32 v201, v172, v173
	v_pk_fma_f32 v[178:179], v[152:153], v[58:59], v[156:157]
	v_cvt_f32_f16_e32 v152, v197
	v_cvt_f32_f16_sdwa v153, v197 dst_sel:DWORD dst_unused:UNUSED_PAD src0_sel:WORD_1
	v_pk_fma_f32 v[160:161], v[154:155], v[60:61], v[160:161]
	v_cvt_f32_f16_e32 v154, v198
	v_cvt_f32_f16_sdwa v155, v198 dst_sel:DWORD dst_unused:UNUSED_PAD src0_sel:WORD_1
	v_pk_fma_f32 v[174:175], v[148:149], v[62:63], v[152:153]
	v_mov_b32_e32 v153, v1
	v_cvt_pk_f16_f32 v148, v178, v179
	v_pk_fma_f32 v[156:157], v[150:151], v[64:65], v[154:155]
	v_mov_b32_e32 v152, v1
	v_mov_b32_dpp v153, v199 quad_perm:[1,0,3,2] row_mask:0xf bank_mask:0xf
	v_mov_b32_e32 v154, v1
	v_cvt_pk_f16_f32 v149, v160, v161
	v_mov_b32_dpp v152, v148 quad_perm:[1,0,3,2] row_mask:0xf bank_mask:0xf
	v_cndmask_b32_e64 v148, v148, v153, s[0:1]
	v_mov_b32_e32 v153, v1
	v_mov_b32_dpp v154, v200 quad_perm:[1,0,3,2] row_mask:0xf bank_mask:0xf
	v_mov_b32_e32 v155, v1
	v_cvt_pk_f16_f32 v150, v174, v175
	v_mov_b32_dpp v153, v149 quad_perm:[1,0,3,2] row_mask:0xf bank_mask:0xf
	v_cndmask_b32_e64 v149, v149, v154, s[0:1]
	v_mov_b32_e32 v154, v1
	v_mov_b32_dpp v155, v201 quad_perm:[1,0,3,2] row_mask:0xf bank_mask:0xf
	v_cvt_pk_f16_f32 v151, v156, v157
	v_mov_b32_dpp v154, v150 quad_perm:[1,0,3,2] row_mask:0xf bank_mask:0xf
	v_cndmask_b32_e64 v150, v150, v155, s[0:1]
	v_mov_b32_e32 v155, v1
	v_cvt_pk_f16_f32 v193, v158, v159
	v_mov_b32_e32 v195, v1
	v_mov_b32_dpp v155, v151 quad_perm:[1,0,3,2] row_mask:0xf bank_mask:0xf
	v_cndmask_b32_e64 v152, v152, v199, s[0:1]
	v_cndmask_b32_e64 v153, v153, v200, s[0:1]
	v_cndmask_b32_e64 v154, v154, v201, s[0:1]
	v_mov_b32_dpp v195, v193 quad_perm:[1,0,3,2] row_mask:0xf bank_mask:0xf
	v_cndmask_b32_e64 v155, v155, v193, s[0:1]
	v_cndmask_b32_e64 v151, v151, v195, s[0:1]
	global_store_dwordx4 v194, v[152:155], s[38:39] sc1
	s_nop 1
	v_add_u32_e32 v152, 0x16f80800, v0
	global_store_dwordx4 v152, v[148:151], s[38:39] sc1
	s_cbranch_vccnz .LBB0_465
	s_nop 0
	v_pk_mul_f32 v[148:149], v[32:33], v[156:157]
	v_pk_mul_f32 v[150:151], v[30:31], v[174:175]
	v_cvt_pk_f16_f32 v155, v148, v149
	v_cvt_pk_f16_f32 v154, v150, v151
	v_pk_mul_f32 v[148:149], v[28:29], v[160:161]
	v_pk_mul_f32 v[150:151], v[26:27], v[178:179]
	v_cvt_pk_f16_f32 v153, v148, v149
	v_cvt_pk_f16_f32 v152, v150, v151
	v_pk_mul_f32 v[148:149], v[24:25], v[158:159]
	v_pk_mul_f32 v[150:151], v[22:23], v[172:173]
	v_cvt_pk_f16_f32 v193, v148, v149
	v_cvt_pk_f16_f32 v194, v150, v151
	v_pk_mul_f32 v[148:149], v[20:21], v[162:163]
	v_pk_mul_f32 v[150:151], v[18:19], v[176:177]
	v_cvt_pk_f16_f32 v149, v148, v149
	v_cvt_pk_f16_f32 v148, v150, v151
	v_mov_b32_e32 v151, v1
	v_mov_b32_e32 v150, v1
	v_add_u32_e32 v195, 0x3d80000, v0
	v_mov_b32_dpp v151, v148 quad_perm:[1,0,3,2] row_mask:0xf bank_mask:0xf
	v_mov_b32_dpp v150, v152 quad_perm:[1,0,3,2] row_mask:0xf bank_mask:0xf
	v_cndmask_b32_e64 v152, v152, v151, s[0:1]
	v_mov_b32_e32 v151, v1
	v_cndmask_b32_e64 v148, v150, v148, s[0:1]
	v_mov_b32_e32 v150, v1
	v_mov_b32_dpp v151, v149 quad_perm:[1,0,3,2] row_mask:0xf bank_mask:0xf
	s_nop 0
	v_mov_b32_dpp v150, v153 quad_perm:[1,0,3,2] row_mask:0xf bank_mask:0xf
	v_cndmask_b32_e64 v153, v153, v151, s[0:1]
	v_mov_b32_e32 v151, v1
	v_cndmask_b32_e64 v149, v150, v149, s[0:1]
	v_mov_b32_e32 v150, v1
	v_mov_b32_dpp v151, v194 quad_perm:[1,0,3,2] row_mask:0xf bank_mask:0xf
	s_nop 0
	v_mov_b32_dpp v150, v154 quad_perm:[1,0,3,2] row_mask:0xf bank_mask:0xf
	v_cndmask_b32_e64 v154, v154, v151, s[0:1]
	v_mov_b32_e32 v151, v1
	v_cndmask_b32_e64 v150, v150, v194, s[0:1]
	v_mov_b32_e32 v194, v1
	v_mov_b32_dpp v151, v155 quad_perm:[1,0,3,2] row_mask:0xf bank_mask:0xf
	v_cndmask_b32_e64 v151, v151, v193, s[0:1]
	v_mov_b32_dpp v194, v193 quad_perm:[1,0,3,2] row_mask:0xf bank_mask:0xf
	v_cndmask_b32_e64 v155, v155, v194, s[0:1]
	global_store_dwordx4 v195, v[148:151], s[38:39] sc1
	s_nop 1
	v_add_u32_e32 v148, 0x3d80800, v0
	global_store_dwordx4 v148, v[152:155], s[38:39] sc1
; __device__ __forceinline__ unsigned cvtpk_h(float lo, float hi) { f32x2 v = {lo, hi}; h16x2 b = __builtin_convertvector(v, h16x2); return __builtin_bit_cast(unsigned, b); }
;     __device__ __forceinline__ void operator()(const f32x4 (&acc)[2][2][4][2], const pg8::Unit& u, int wr, int wc, int fr, int fq) const {
;     ...
;                     ss += ((x0[0] * x0[0] + x0[1] * x0[1]) + (x0[2] * x0[2] + x0[3] * x0[3])) + ((x1[0] * x1[0] + x1[1] * x1[1]) + (x1[2] * x1[2] + x1[3] * x1[3]));
;                     w[bj].x = cvtpk_h(x0[0], x0[1]); w[bj].y = cvtpk_h(x0[2], x0[3]); w[bj].z = cvtpk_h(x1[0], x1[1]); w[bj].w = cvtpk_h(x1[2], x1[3]);
;                     const f32x4 y0 = x0 * a4[bj][0], y1 = x1 * a4[bj][1]; v[bj].x = cvtpk_h(y0[0], y0[1]); v[bj].y = cvtpk_h(y0[2], y0[3]); v[bj].z = cvtpk_h(y1[0], y1[1]); v[bj].w = cvtpk_h(y1[2], y1[3]); }
;                 stg_line_pair(ws, (unsigned)WS_X16 + o, D * 2u, w[0], w[1], odd);
;                 if (an_off) stg_line_pair(ws, (unsigned)WS_XS + o, D * 2u, v[0], v[1], odd);
;                 ss = red4(ss, fq * 16 + fr); if (fq == 0) stg_f1(ws, rqo + rr * 4u, ss);
.LBB0_465:
	s_nop 0
	v_mul_f32_e32 v149, v177, v177
	v_mul_f32_e32 v150, v163, v163
	v_fmac_f32_e32 v149, v176, v176
	v_fmac_f32_e32 v150, v162, v162
	v_add_f32_e32 v149, v149, v150
	v_mul_f32_e32 v150, v173, v173
	v_mul_f32_e32 v151, v159, v159
	v_fmac_f32_e32 v150, v172, v172
	v_fmac_f32_e32 v151, v158, v158
	v_add_f32_e32 v150, v150, v151
	v_add_f32_e32 v149, v149, v150
	v_mul_f32_e32 v150, v179, v179
	v_mul_f32_e32 v151, v161, v161
	v_fmac_f32_e32 v150, v178, v178
	v_fmac_f32_e32 v151, v160, v160
	v_add_f32_e32 v150, v150, v151
	v_mul_f32_e32 v151, v175, v175
	v_mul_f32_e32 v152, v157, v157
	v_fmac_f32_e32 v151, v174, v174
	v_fmac_f32_e32 v152, v156, v156
	v_add_f32_e32 v151, v151, v152
	v_add_f32_e32 v150, v150, v151
	v_add_f32_e32 v149, v150, v149
	s_lshl_b32 s4, s4, 2
	v_mov_b32_e32 v150, v149
	s_or_b32 s4, s4, s83
	s_nop 0
	v_permlane16_swap_b32_e32 v149, v150
	s_mul_i32 s21, s4, 0x9000
	v_add_f32_e32 v149, v149, v150
	s_add_i32 s19, s19, s21
	v_mov_b32_e32 v150, v149
	v_cmp_eq_u32_e64 s[4:5], 0, v192
	v_add_u32_e32 v148, s19, v191
	v_permlane32_swap_b32_e32 v149, v150
	s_and_saveexec_b64 s[44:45], s[4:5]
	s_cbranch_execz .LBB0_467
	v_add_f32_e32 v149, v149, v150
	v_lshl_add_u32 v150, v148, 2, v247
	global_store_dword v150, v149, s[38:39] sc1

; #define GAS __attribute__((address_space(1)))
; __device__ __forceinline__ unsigned cvtpk_h(float lo, float hi) { f32x2 v = {lo, hi}; h16x2 b = __builtin_convertvector(v, h16x2); return __builtin_bit_cast(unsigned, b); }
;     __device__ __forceinline__ void operator()(const f32x4 (&acc)[2][2][4][2], const pg8::Unit& u, int wr, int wc, int fr, int fq) const {
;     ...
;             for (int m = 0; m < 4; ++m) { if (half && ai == 1) continue; const unsigned rr = (unsigned)(ai * 128 + m * 16); const unsigned o = eoA + rr * (D * 2u); float ss = 0.f;
;                 const u32x4 la = *(const GAS u32x4*)((const GAS char*)ws + (unsigned)WS_X16 + o), lb = *(const GAS u32x4*)((const GAS char*)ws + (unsigned)WS_X16 + o + D * 2u);
;                 u32x4 xr[2];
; #pragma unroll
;                 for (int c = 0; c < 4; ++c) { const unsigned pa = (unsigned)__builtin_amdgcn_update_dpp(0, (int)la[c], 0xB1, 0xF, 0xF, false), pb = (unsigned)__builtin_amdgcn_update_dpp(0, (int)lb[c], 0xB1, 0xF, 0xF, false);
;                     xr[0][c] = odd ? pb : la[c]; xr[1][c] = odd ? lb[c] : pa; }
;                 u32x4 w[2], v[2];
; #pragma unroll
;                 for (int bj = 0; bj < 2; ++bj) { const h16x8 xb = __builtin_bit_cast(h16x8, xr[bj]);
;                     const f32x4 x0 = (f32x4){(float)xb[0], (float)xb[1], (float)xb[2], (float)xb[3]} + g4[bj][0] * acc[ai][bj][m][0], x1 = (f32x4){(float)xb[4], (float)xb[5], (float)xb[6], (float)xb[7]} + g4[bj][1] * acc[ai][bj][m][1];
;                     ss += ((x0[0] * x0[0] + x0[1] * x0[1]) + (x0[2] * x0[2] + x0[3] * x0[3])) + ((x1[0] * x1[0] + x1[1] * x1[1]) + (x1[2] * x1[2] + x1[3] * x1[3]));
;                     w[bj].x = cvtpk_h(x0[0], x0[1]); w[bj].y = cvtpk_h(x0[2], x0[3]); w[bj].z = cvtpk_h(x1[0], x1[1]); w[bj].w = cvtpk_h(x1[2], x1[3]);
;                     const f32x4 y0 = x0 * a4[bj][0], y1 = x1 * a4[bj][1]; v[bj].x = cvtpk_h(y0[0], y0[1]); v[bj].y = cvtpk_h(y0[2], y0[3]); v[bj].z = cvtpk_h(y1[0], y1[1]); v[bj].w = cvtpk_h(y1[2], y1[3]); }
;                 stg_line_pair(ws, (unsigned)WS_X16 + o, D * 2u, w[0], w[1], odd);
;                 if (an_off) stg_line_pair(ws, (unsigned)WS_XS + o, D * 2u, v[0], v[1], odd);
.Lo_wd_1:
	v_mov_b32_e32 v150, v214
	v_mov_b32_e32 v151, v215
	v_mov_b32_e32 v152, v216
	v_mov_b32_e32 v153, v217
	v_mov_b32_e32 v154, v218
	v_mov_b32_e32 v155, v219
	v_mov_b32_e32 v156, v220
	v_mov_b32_e32 v157, v221
	v_add_u32_e32 v222, 0x10000, v0
	global_load_dwordx4 v[214:217], v222, s[42:43]
	global_load_dwordx4 v[218:221], v222, s[42:43] offset:2048
	v_mov_b32_e32 v149, v1
	v_mov_b32_e32 v158, v1
	v_add_u32_e32 v161, 0x16f88000, v0
	s_and_b64 vcc, exec, s[2:3]
	v_mov_b32_dpp v149, v150 quad_perm:[1,0,3,2] row_mask:0xf bank_mask:0xf
	v_mov_b32_dpp v158, v154 quad_perm:[1,0,3,2] row_mask:0xf bank_mask:0xf
	v_cndmask_b32_e64 v158, v158, v150, s[0:1]
	v_cndmask_b32_e64 v149, v154, v149, s[0:1]
	v_mov_b32_e32 v150, v1
	v_mov_b32_e32 v154, v1
	s_nop 0
	v_mov_b32_dpp v150, v151 quad_perm:[1,0,3,2] row_mask:0xf bank_mask:0xf
	v_mov_b32_dpp v154, v155 quad_perm:[1,0,3,2] row_mask:0xf bank_mask:0xf
	v_cndmask_b32_e64 v154, v154, v151, s[0:1]
	v_cndmask_b32_e64 v155, v155, v150, s[0:1]
	v_mov_b32_e32 v150, v1
	v_mov_b32_e32 v151, v1
	s_nop 0
	v_mov_b32_dpp v150, v152 quad_perm:[1,0,3,2] row_mask:0xf bank_mask:0xf
	v_mov_b32_dpp v151, v156 quad_perm:[1,0,3,2] row_mask:0xf bank_mask:0xf
	v_cndmask_b32_e64 v159, v151, v152, s[0:1]
	v_cndmask_b32_e64 v156, v156, v150, s[0:1]
	v_mov_b32_e32 v150, v1
	v_mov_b32_e32 v151, v1
	v_cvt_f32_f16_e32 v152, v154
	v_mov_b32_dpp v150, v153 quad_perm:[1,0,3,2] row_mask:0xf bank_mask:0xf
	v_mov_b32_dpp v151, v157 quad_perm:[1,0,3,2] row_mask:0xf bank_mask:0xf
	v_cndmask_b32_e64 v160, v151, v153, s[0:1]
	v_cndmask_b32_e64 v157, v157, v150, s[0:1]
	v_cvt_f32_f16_e32 v150, v158
	v_cvt_f32_f16_sdwa v151, v158 dst_sel:DWORD dst_unused:UNUSED_PAD src0_sel:WORD_1
	v_cvt_f32_f16_sdwa v153, v154 dst_sel:DWORD dst_unused:UNUSED_PAD src0_sel:WORD_1
	v_pk_fma_f32 v[144:145], v[144:145], v[50:51], v[150:151]
	v_cvt_f32_f16_e32 v150, v159
	v_cvt_f32_f16_sdwa v151, v159 dst_sel:DWORD dst_unused:UNUSED_PAD src0_sel:WORD_1
	v_pk_fma_f32 v[146:147], v[146:147], v[52:53], v[152:153]
	v_cvt_f32_f16_e32 v152, v160
	v_cvt_f32_f16_sdwa v153, v160 dst_sel:DWORD dst_unused:UNUSED_PAD src0_sel:WORD_1
	v_pk_fma_f32 v[140:141], v[140:141], v[54:55], v[150:151]
	v_cvt_f32_f16_e32 v150, v149
	v_cvt_f32_f16_sdwa v151, v149 dst_sel:DWORD dst_unused:UNUSED_PAD src0_sel:WORD_1
	v_pk_fma_f32 v[142:143], v[142:143], v[56:57], v[152:153]
	v_cvt_f32_f16_e32 v152, v155
	v_cvt_f32_f16_sdwa v153, v155 dst_sel:DWORD dst_unused:UNUSED_PAD src0_sel:WORD_1
	v_pk_fma_f32 v[136:137], v[136:137], v[58:59], v[150:151]
	v_cvt_f32_f16_e32 v150, v156
	v_cvt_f32_f16_sdwa v151, v156 dst_sel:DWORD dst_unused:UNUSED_PAD src0_sel:WORD_1
	v_pk_fma_f32 v[138:139], v[138:139], v[60:61], v[152:153]
	v_cvt_f32_f16_e32 v152, v157
	v_cvt_f32_f16_sdwa v153, v157 dst_sel:DWORD dst_unused:UNUSED_PAD src0_sel:WORD_1
	v_cvt_pk_f16_f32 v154, v144, v145
	v_pk_fma_f32 v[132:133], v[132:133], v[62:63], v[150:151]
	v_cvt_pk_f16_f32 v149, v136, v137
	v_mov_b32_e32 v150, v1
	v_mov_b32_e32 v151, v1
	v_pk_fma_f32 v[134:135], v[134:135], v[64:65], v[152:153]
	v_mov_b32_dpp v150, v149 quad_perm:[1,0,3,2] row_mask:0xf bank_mask:0xf
	v_mov_b32_dpp v151, v154 quad_perm:[1,0,3,2] row_mask:0xf bank_mask:0xf
	v_cvt_pk_f16_f32 v152, v138, v139
	v_cndmask_b32_e64 v150, v150, v154, s[0:1]
	v_cndmask_b32_e64 v154, v149, v151, s[0:1]
	v_mov_b32_e32 v149, v1
	v_cvt_pk_f16_f32 v158, v146, v147
	v_cvt_pk_f16_f32 v153, v132, v133
	v_mov_b32_dpp v149, v152 quad_perm:[1,0,3,2] row_mask:0xf bank_mask:0xf
	v_mov_b32_e32 v155, v1
	v_cndmask_b32_e64 v151, v149, v158, s[0:1]
	v_mov_b32_e32 v149, v1
	v_cvt_pk_f16_f32 v159, v140, v141
	v_mov_b32_dpp v155, v158 quad_perm:[1,0,3,2] row_mask:0xf bank_mask:0xf
	v_mov_b32_dpp v149, v153 quad_perm:[1,0,3,2] row_mask:0xf bank_mask:0xf
	v_cvt_pk_f16_f32 v160, v142, v143
	v_cvt_pk_f16_f32 v157, v134, v135
	v_cndmask_b32_e64 v155, v152, v155, s[0:1]
	v_mov_b32_e32 v156, v1
	v_cndmask_b32_e64 v152, v149, v159, s[0:1]
	v_mov_b32_e32 v149, v1
	v_mov_b32_e32 v158, v1
	v_mov_b32_dpp v156, v159 quad_perm:[1,0,3,2] row_mask:0xf bank_mask:0xf
	v_mov_b32_dpp v149, v157 quad_perm:[1,0,3,2] row_mask:0xf bank_mask:0xf
	v_mov_b32_dpp v158, v160 quad_perm:[1,0,3,2] row_mask:0xf bank_mask:0xf
	v_cndmask_b32_e64 v156, v153, v156, s[0:1]
	v_cndmask_b32_e64 v153, v149, v160, s[0:1]
	v_cndmask_b32_e64 v157, v157, v158, s[0:1]
	v_add_u32_e32 v149, 0x16f88800, v0
	global_store_dwordx4 v161, v[150:153], s[38:39] sc1
	global_store_dwordx4 v149, v[154:157], s[38:39] sc1
	s_cbranch_vccnz .LBB0_469
	v_pk_mul_f32 v[150:151], v[32:33], v[134:135]
	v_pk_mul_f32 v[152:153], v[30:31], v[132:133]
	v_cvt_pk_f16_f32 v149, v150, v151
	v_cvt_pk_f16_f32 v156, v152, v153
	v_pk_mul_f32 v[150:151], v[28:29], v[138:139]
	v_pk_mul_f32 v[152:153], v[26:27], v[136:137]
	v_cvt_pk_f16_f32 v155, v150, v151
	v_cvt_pk_f16_f32 v154, v152, v153
	v_pk_mul_f32 v[150:151], v[24:25], v[142:143]
	v_pk_mul_f32 v[152:153], v[22:23], v[140:141]
	v_cvt_pk_f16_f32 v157, v150, v151
	v_cvt_pk_f16_f32 v158, v152, v153
	v_pk_mul_f32 v[150:151], v[20:21], v[146:147]
	v_pk_mul_f32 v[152:153], v[18:19], v[144:145]
	v_cvt_pk_f16_f32 v151, v150, v151
	v_cvt_pk_f16_f32 v150, v152, v153
	v_mov_b32_e32 v152, v1
	v_mov_b32_e32 v153, v1
	v_add_u32_e32 v159, 0x3d88000, v0
	v_mov_b32_dpp v152, v154 quad_perm:[1,0,3,2] row_mask:0xf bank_mask:0xf
	v_mov_b32_dpp v153, v150 quad_perm:[1,0,3,2] row_mask:0xf bank_mask:0xf
	v_cndmask_b32_e64 v150, v152, v150, s[0:1]
	v_cndmask_b32_e64 v154, v154, v153, s[0:1]
	v_mov_b32_e32 v152, v1
	v_mov_b32_e32 v153, v1
	s_nop 0
	v_mov_b32_dpp v152, v155 quad_perm:[1,0,3,2] row_mask:0xf bank_mask:0xf
	v_mov_b32_dpp v153, v151 quad_perm:[1,0,3,2] row_mask:0xf bank_mask:0xf
	v_cndmask_b32_e64 v151, v152, v151, s[0:1]
	v_cndmask_b32_e64 v155, v155, v153, s[0:1]
	v_mov_b32_e32 v152, v1
	v_mov_b32_e32 v153, v1
	s_nop 0
	v_mov_b32_dpp v152, v156 quad_perm:[1,0,3,2] row_mask:0xf bank_mask:0xf
	v_mov_b32_dpp v153, v158 quad_perm:[1,0,3,2] row_mask:0xf bank_mask:0xf
	v_cndmask_b32_e64 v152, v152, v158, s[0:1]
	v_cndmask_b32_e64 v156, v156, v153, s[0:1]
	v_mov_b32_e32 v153, v1
	v_mov_b32_e32 v158, v1
	s_nop 0
	v_mov_b32_dpp v153, v149 quad_perm:[1,0,3,2] row_mask:0xf bank_mask:0xf
	v_mov_b32_dpp v158, v157 quad_perm:[1,0,3,2] row_mask:0xf bank_mask:0xf
	v_cndmask_b32_e64 v153, v153, v157, s[0:1]
	v_cndmask_b32_e64 v157, v149, v158, s[0:1]
	v_add_u32_e32 v149, 0x3d88800, v0
	global_store_dwordx4 v159, v[150:153], s[38:39] sc1
	global_store_dwordx4 v149, v[154:157], s[38:39] sc1
; __device__ __forceinline__ unsigned cvtpk_h(float lo, float hi) { f32x2 v = {lo, hi}; h16x2 b = __builtin_convertvector(v, h16x2); return __builtin_bit_cast(unsigned, b); }
;     __device__ __forceinline__ void operator()(const f32x4 (&acc)[2][2][4][2], const pg8::Unit& u, int wr, int wc, int fr, int fq) const {
;     ...
;                     ss += ((x0[0] * x0[0] + x0[1] * x0[1]) + (x0[2] * x0[2] + x0[3] * x0[3])) + ((x1[0] * x1[0] + x1[1] * x1[1]) + (x1[2] * x1[2] + x1[3] * x1[3]));
;                     w[bj].x = cvtpk_h(x0[0], x0[1]); w[bj].y = cvtpk_h(x0[2], x0[3]); w[bj].z = cvtpk_h(x1[0], x1[1]); w[bj].w = cvtpk_h(x1[2], x1[3]);
;                     const f32x4 y0 = x0 * a4[bj][0], y1 = x1 * a4[bj][1]; v[bj].x = cvtpk_h(y0[0], y0[1]); v[bj].y = cvtpk_h(y0[2], y0[3]); v[bj].z = cvtpk_h(y1[0], y1[1]); v[bj].w = cvtpk_h(y1[2], y1[3]); }
;                 stg_line_pair(ws, (unsigned)WS_X16 + o, D * 2u, w[0], w[1], odd);
;                 if (an_off) stg_line_pair(ws, (unsigned)WS_XS + o, D * 2u, v[0], v[1], odd);
;                 ss = red4(ss, fq * 16 + fr); if (fq == 0) stg_f1(ws, rqo + rr * 4u, ss);
.LBB0_469:
	v_mul_f32_e32 v145, v145, v145
	v_mul_f32_e32 v141, v141, v141
	v_mul_f32_e32 v137, v137, v137
	v_mul_f32_e32 v133, v133, v133
	v_fmac_f32_e32 v145, v144, v144
	v_mul_f32_e32 v144, v147, v147
	v_fmac_f32_e32 v141, v140, v140
	v_mul_f32_e32 v140, v143, v143
	v_fmac_f32_e32 v137, v136, v136
	v_mul_f32_e32 v136, v139, v139
	v_fmac_f32_e32 v133, v132, v132
	v_mul_f32_e32 v132, v135, v135
	v_fmac_f32_e32 v144, v146, v146
	v_fmac_f32_e32 v140, v142, v142
	v_fmac_f32_e32 v136, v138, v138
	v_fmac_f32_e32 v132, v134, v134
	v_add_f32_e32 v144, v145, v144
	v_add_f32_e32 v140, v141, v140
	v_add_f32_e32 v136, v137, v136
	v_add_f32_e32 v132, v133, v132
	v_add_f32_e32 v140, v144, v140
	v_add_f32_e32 v132, v136, v132
	v_add_f32_e32 v132, v132, v140
	v_mov_b32_e32 v133, v132
	s_nop 1
	v_permlane16_swap_b32_e32 v132, v133
	v_add_f32_e32 v132, v132, v133
	v_mov_b32_e32 v133, v132
	s_nop 1
	v_permlane32_swap_b32_e32 v132, v133
	s_and_saveexec_b64 s[44:45], s[4:5]
	s_cbranch_execz .LBB0_471
	v_add_f32_e32 v132, v132, v133
	v_mov_b32_e32 v133, 0x2880040
	v_lshl_add_u32 v133, v148, 2, v133
	global_store_dword v133, v132, s[38:39] sc1

; #define GAS __attribute__((address_space(1)))
; __device__ __forceinline__ unsigned cvtpk_h(float lo, float hi) { f32x2 v = {lo, hi}; h16x2 b = __builtin_convertvector(v, h16x2); return __builtin_bit_cast(unsigned, b); }
;     __device__ __forceinline__ void operator()(const f32x4 (&acc)[2][2][4][2], const pg8::Unit& u, int wr, int wc, int fr, int fq) const {
;     ...
;             for (int m = 0; m < 4; ++m) { if (half && ai == 1) continue; const unsigned rr = (unsigned)(ai * 128 + m * 16); const unsigned o = eoA + rr * (D * 2u); float ss = 0.f;
;                 const u32x4 la = *(const GAS u32x4*)((const GAS char*)ws + (unsigned)WS_X16 + o), lb = *(const GAS u32x4*)((const GAS char*)ws + (unsigned)WS_X16 + o + D * 2u);
;                 u32x4 xr[2];
; #pragma unroll
;                 for (int c = 0; c < 4; ++c) { const unsigned pa = (unsigned)__builtin_amdgcn_update_dpp(0, (int)la[c], 0xB1, 0xF, 0xF, false), pb = (unsigned)__builtin_amdgcn_update_dpp(0, (int)lb[c], 0xB1, 0xF, 0xF, false);
;                     xr[0][c] = odd ? pb : la[c]; xr[1][c] = odd ? lb[c] : pa; }
;                 u32x4 w[2], v[2];
; #pragma unroll
;                 for (int bj = 0; bj < 2; ++bj) { const h16x8 xb = __builtin_bit_cast(h16x8, xr[bj]);
;                     const f32x4 x0 = (f32x4){(float)xb[0], (float)xb[1], (float)xb[2], (float)xb[3]} + g4[bj][0] * acc[ai][bj][m][0], x1 = (f32x4){(float)xb[4], (float)xb[5], (float)xb[6], (float)xb[7]} + g4[bj][1] * acc[ai][bj][m][1];
;                     ss += ((x0[0] * x0[0] + x0[1] * x0[1]) + (x0[2] * x0[2] + x0[3] * x0[3])) + ((x1[0] * x1[0] + x1[1] * x1[1]) + (x1[2] * x1[2] + x1[3] * x1[3]));
;                     w[bj].x = cvtpk_h(x0[0], x0[1]); w[bj].y = cvtpk_h(x0[2], x0[3]); w[bj].z = cvtpk_h(x1[0], x1[1]); w[bj].w = cvtpk_h(x1[2], x1[3]);
;                     const f32x4 y0 = x0 * a4[bj][0], y1 = x1 * a4[bj][1]; v[bj].x = cvtpk_h(y0[0], y0[1]); v[bj].y = cvtpk_h(y0[2], y0[3]); v[bj].z = cvtpk_h(y1[0], y1[1]); v[bj].w = cvtpk_h(y1[2], y1[3]); }
;                 stg_line_pair(ws, (unsigned)WS_X16 + o, D * 2u, w[0], w[1], odd);
;                 if (an_off) stg_line_pair(ws, (unsigned)WS_XS + o, D * 2u, v[0], v[1], odd);
.Lo_wd_2:
	v_mov_b32_e32 v132, v214
	v_mov_b32_e32 v133, v215
	v_mov_b32_e32 v134, v216
	v_mov_b32_e32 v135, v217
	v_mov_b32_e32 v136, v218
	v_mov_b32_e32 v137, v219
	v_mov_b32_e32 v138, v220
	v_mov_b32_e32 v139, v221
	v_add_u32_e32 v222, 0x18000, v0
	global_load_dwordx4 v[214:217], v222, s[42:43]
	global_load_dwordx4 v[218:221], v222, s[42:43] offset:2048
	v_mov_b32_e32 v140, v1
	v_mov_b32_e32 v141, v1
	v_add_u32_e32 v144, 0x16f90000, v0
	s_and_b64 vcc, exec, s[2:3]
	v_mov_b32_dpp v140, v132 quad_perm:[1,0,3,2] row_mask:0xf bank_mask:0xf
	v_mov_b32_dpp v141, v136 quad_perm:[1,0,3,2] row_mask:0xf bank_mask:0xf
	v_cndmask_b32_e64 v141, v141, v132, s[0:1]
	v_cndmask_b32_e64 v136, v136, v140, s[0:1]
	v_mov_b32_e32 v132, v1
	v_mov_b32_e32 v140, v1
	s_nop 0
	v_mov_b32_dpp v132, v133 quad_perm:[1,0,3,2] row_mask:0xf bank_mask:0xf
	v_mov_b32_dpp v140, v137 quad_perm:[1,0,3,2] row_mask:0xf bank_mask:0xf
	v_cndmask_b32_e64 v140, v140, v133, s[0:1]
	v_cndmask_b32_e64 v137, v137, v132, s[0:1]
	v_mov_b32_e32 v132, v1
	v_mov_b32_e32 v133, v1
	s_nop 0
	v_mov_b32_dpp v132, v134 quad_perm:[1,0,3,2] row_mask:0xf bank_mask:0xf
	v_mov_b32_dpp v133, v138 quad_perm:[1,0,3,2] row_mask:0xf bank_mask:0xf
	v_cndmask_b32_e64 v142, v133, v134, s[0:1]
	v_cndmask_b32_e64 v138, v138, v132, s[0:1]
	v_mov_b32_e32 v132, v1
	v_mov_b32_e32 v133, v1
	v_cvt_f32_f16_e32 v134, v140
	v_mov_b32_dpp v132, v135 quad_perm:[1,0,3,2] row_mask:0xf bank_mask:0xf
	v_mov_b32_dpp v133, v139 quad_perm:[1,0,3,2] row_mask:0xf bank_mask:0xf
	v_cndmask_b32_e64 v143, v133, v135, s[0:1]
	v_cndmask_b32_e64 v139, v139, v132, s[0:1]
	v_cvt_f32_f16_e32 v132, v141
	v_cvt_f32_f16_sdwa v133, v141 dst_sel:DWORD dst_unused:UNUSED_PAD src0_sel:WORD_1
	v_cvt_f32_f16_sdwa v135, v140 dst_sel:DWORD dst_unused:UNUSED_PAD src0_sel:WORD_1
	v_pk_fma_f32 v[126:127], v[126:127], v[50:51], v[132:133]
	v_cvt_f32_f16_e32 v132, v142
	v_cvt_f32_f16_sdwa v133, v142 dst_sel:DWORD dst_unused:UNUSED_PAD src0_sel:WORD_1
	v_pk_fma_f32 v[128:129], v[128:129], v[52:53], v[134:135]
	v_cvt_f32_f16_e32 v134, v143
	v_cvt_f32_f16_sdwa v135, v143 dst_sel:DWORD dst_unused:UNUSED_PAD src0_sel:WORD_1
	v_pk_fma_f32 v[122:123], v[122:123], v[54:55], v[132:133]
	v_cvt_f32_f16_e32 v132, v136
	v_cvt_f32_f16_sdwa v133, v136 dst_sel:DWORD dst_unused:UNUSED_PAD src0_sel:WORD_1
	v_pk_fma_f32 v[124:125], v[124:125], v[56:57], v[134:135]
	v_cvt_f32_f16_e32 v134, v137
	v_cvt_f32_f16_sdwa v135, v137 dst_sel:DWORD dst_unused:UNUSED_PAD src0_sel:WORD_1
	v_pk_fma_f32 v[118:119], v[118:119], v[58:59], v[132:133]
	v_cvt_f32_f16_e32 v132, v138
	v_cvt_f32_f16_sdwa v133, v138 dst_sel:DWORD dst_unused:UNUSED_PAD src0_sel:WORD_1
	v_pk_fma_f32 v[120:121], v[120:121], v[60:61], v[134:135]
	v_cvt_f32_f16_e32 v134, v139
	v_cvt_f32_f16_sdwa v135, v139 dst_sel:DWORD dst_unused:UNUSED_PAD src0_sel:WORD_1
	v_cvt_pk_f16_f32 v140, v126, v127
	v_mov_b32_e32 v136, v1
	v_cvt_pk_f16_f32 v141, v128, v129
	v_pk_fma_f32 v[114:115], v[114:115], v[62:63], v[132:133]
	v_cvt_pk_f16_f32 v133, v118, v119
	v_mov_b32_e32 v132, v1
	v_mov_b32_dpp v136, v140 quad_perm:[1,0,3,2] row_mask:0xf bank_mask:0xf
	v_mov_b32_e32 v137, v1
	v_cvt_pk_f16_f32 v142, v122, v123
	v_pk_fma_f32 v[116:117], v[116:117], v[64:65], v[134:135]
	v_cvt_pk_f16_f32 v134, v120, v121
	v_mov_b32_dpp v132, v133 quad_perm:[1,0,3,2] row_mask:0xf bank_mask:0xf
	v_cndmask_b32_e64 v136, v133, v136, s[0:1]
	v_mov_b32_e32 v133, v1
	v_mov_b32_dpp v137, v141 quad_perm:[1,0,3,2] row_mask:0xf bank_mask:0xf
	v_mov_b32_e32 v138, v1
	v_cvt_pk_f16_f32 v135, v114, v115
	v_mov_b32_dpp v133, v134 quad_perm:[1,0,3,2] row_mask:0xf bank_mask:0xf
	v_cndmask_b32_e64 v137, v134, v137, s[0:1]
	v_mov_b32_e32 v134, v1
	v_mov_b32_dpp v138, v142 quad_perm:[1,0,3,2] row_mask:0xf bank_mask:0xf
	v_cvt_pk_f16_f32 v139, v116, v117
	v_mov_b32_dpp v134, v135 quad_perm:[1,0,3,2] row_mask:0xf bank_mask:0xf
	v_cndmask_b32_e64 v138, v135, v138, s[0:1]
	v_mov_b32_e32 v135, v1
	v_cvt_pk_f16_f32 v143, v124, v125
	v_cndmask_b32_e64 v132, v132, v140, s[0:1]
	v_mov_b32_dpp v135, v139 quad_perm:[1,0,3,2] row_mask:0xf bank_mask:0xf
	v_mov_b32_e32 v140, v1
	v_cndmask_b32_e64 v133, v133, v141, s[0:1]
	v_cndmask_b32_e64 v134, v134, v142, s[0:1]
	v_mov_b32_dpp v140, v143 quad_perm:[1,0,3,2] row_mask:0xf bank_mask:0xf
	v_cndmask_b32_e64 v135, v135, v143, s[0:1]
	v_cndmask_b32_e64 v139, v139, v140, s[0:1]
	global_store_dwordx4 v144, v[132:135], s[38:39] sc1
	s_nop 1
	v_add_u32_e32 v132, 0x16f90800, v0
	global_store_dwordx4 v132, v[136:139], s[38:39] sc1
	s_cbranch_vccnz .LBB0_473
	v_pk_mul_f32 v[132:133], v[32:33], v[116:117]
	v_pk_mul_f32 v[134:135], v[30:31], v[114:115]
	v_cvt_pk_f16_f32 v139, v132, v133
	v_cvt_pk_f16_f32 v138, v134, v135
	v_pk_mul_f32 v[132:133], v[28:29], v[120:121]
	v_pk_mul_f32 v[134:135], v[26:27], v[118:119]
	v_cvt_pk_f16_f32 v137, v132, v133
	v_cvt_pk_f16_f32 v136, v134, v135
	v_pk_mul_f32 v[132:133], v[24:25], v[124:125]
	v_pk_mul_f32 v[134:135], v[22:23], v[122:123]
	v_cvt_pk_f16_f32 v140, v132, v133
	v_cvt_pk_f16_f32 v141, v134, v135
	v_pk_mul_f32 v[132:133], v[20:21], v[128:129]
	v_pk_mul_f32 v[134:135], v[18:19], v[126:127]
	v_cvt_pk_f16_f32 v133, v132, v133
	v_cvt_pk_f16_f32 v132, v134, v135
	v_mov_b32_e32 v135, v1
	v_mov_b32_e32 v134, v1
	v_add_u32_e32 v142, 0x3d90000, v0
	v_mov_b32_dpp v135, v132 quad_perm:[1,0,3,2] row_mask:0xf bank_mask:0xf
	v_mov_b32_dpp v134, v136 quad_perm:[1,0,3,2] row_mask:0xf bank_mask:0xf
	v_cndmask_b32_e64 v136, v136, v135, s[0:1]
	v_mov_b32_e32 v135, v1
	v_cndmask_b32_e64 v132, v134, v132, s[0:1]
	v_mov_b32_e32 v134, v1
	v_mov_b32_dpp v135, v133 quad_perm:[1,0,3,2] row_mask:0xf bank_mask:0xf
	s_nop 0
	v_mov_b32_dpp v134, v137 quad_perm:[1,0,3,2] row_mask:0xf bank_mask:0xf
	v_cndmask_b32_e64 v137, v137, v135, s[0:1]
	v_mov_b32_e32 v135, v1
	v_cndmask_b32_e64 v133, v134, v133, s[0:1]
	v_mov_b32_e32 v134, v1
	v_mov_b32_dpp v135, v141 quad_perm:[1,0,3,2] row_mask:0xf bank_mask:0xf
	s_nop 0
	v_mov_b32_dpp v134, v138 quad_perm:[1,0,3,2] row_mask:0xf bank_mask:0xf
	v_cndmask_b32_e64 v138, v138, v135, s[0:1]
	v_mov_b32_e32 v135, v1
	v_cndmask_b32_e64 v134, v134, v141, s[0:1]
	v_mov_b32_e32 v141, v1
	v_mov_b32_dpp v135, v139 quad_perm:[1,0,3,2] row_mask:0xf bank_mask:0xf
	v_cndmask_b32_e64 v135, v135, v140, s[0:1]
	v_mov_b32_dpp v141, v140 quad_perm:[1,0,3,2] row_mask:0xf bank_mask:0xf
	v_cndmask_b32_e64 v139, v139, v141, s[0:1]
	global_store_dwordx4 v142, v[132:135], s[38:39] sc1
	s_nop 1
	v_add_u32_e32 v132, 0x3d90800, v0
	global_store_dwordx4 v132, v[136:139], s[38:39] sc1
; __device__ __forceinline__ unsigned cvtpk_h(float lo, float hi) { f32x2 v = {lo, hi}; h16x2 b = __builtin_convertvector(v, h16x2); return __builtin_bit_cast(unsigned, b); }
;     __device__ __forceinline__ void operator()(const f32x4 (&acc)[2][2][4][2], const pg8::Unit& u, int wr, int wc, int fr, int fq) const {
;     ...
;                     ss += ((x0[0] * x0[0] + x0[1] * x0[1]) + (x0[2] * x0[2] + x0[3] * x0[3])) + ((x1[0] * x1[0] + x1[1] * x1[1]) + (x1[2] * x1[2] + x1[3] * x1[3]));
;                     w[bj].x = cvtpk_h(x0[0], x0[1]); w[bj].y = cvtpk_h(x0[2], x0[3]); w[bj].z = cvtpk_h(x1[0], x1[1]); w[bj].w = cvtpk_h(x1[2], x1[3]);
;                     const f32x4 y0 = x0 * a4[bj][0], y1 = x1 * a4[bj][1]; v[bj].x = cvtpk_h(y0[0], y0[1]); v[bj].y = cvtpk_h(y0[2], y0[3]); v[bj].z = cvtpk_h(y1[0], y1[1]); v[bj].w = cvtpk_h(y1[2], y1[3]); }
;                 stg_line_pair(ws, (unsigned)WS_X16 + o, D * 2u, w[0], w[1], odd);
;                 if (an_off) stg_line_pair(ws, (unsigned)WS_XS + o, D * 2u, v[0], v[1], odd);
;                 ss = red4(ss, fq * 16 + fr); if (fq == 0) stg_f1(ws, rqo + rr * 4u, ss);
.LBB0_473:
	v_mul_f32_e32 v127, v127, v127
	v_mul_f32_e32 v123, v123, v123
	v_mul_f32_e32 v119, v119, v119
	v_mul_f32_e32 v115, v115, v115
	v_fmac_f32_e32 v127, v126, v126
	v_mul_f32_e32 v126, v129, v129
	v_fmac_f32_e32 v123, v122, v122
	v_mul_f32_e32 v122, v125, v125
	v_fmac_f32_e32 v119, v118, v118
	v_mul_f32_e32 v118, v121, v121
	v_fmac_f32_e32 v115, v114, v114
	v_mul_f32_e32 v114, v117, v117
	v_fmac_f32_e32 v126, v128, v128
	v_fmac_f32_e32 v122, v124, v124
	v_fmac_f32_e32 v118, v120, v120
	v_fmac_f32_e32 v114, v116, v116
	v_add_f32_e32 v126, v127, v126
	v_add_f32_e32 v122, v123, v122
	v_add_f32_e32 v118, v119, v118
	v_add_f32_e32 v114, v115, v114
	v_add_f32_e32 v122, v126, v122
	v_add_f32_e32 v114, v118, v114
	v_add_f32_e32 v114, v114, v122
	v_mov_b32_e32 v115, v114
	s_nop 1
	v_permlane16_swap_b32_e32 v114, v115
	v_add_f32_e32 v114, v114, v115
	v_mov_b32_e32 v115, v114
	s_nop 1
	v_permlane32_swap_b32_e32 v114, v115
	s_and_saveexec_b64 s[44:45], s[4:5]
	s_cbranch_execz .LBB0_475
	v_add_f32_e32 v114, v114, v115
	v_mov_b32_e32 v115, 0x2880080
	v_lshl_add_u32 v115, v148, 2, v115
	global_store_dword v115, v114, s[38:39] sc1

; #define GAS __attribute__((address_space(1)))
; __device__ __forceinline__ unsigned cvtpk_h(float lo, float hi) { f32x2 v = {lo, hi}; h16x2 b = __builtin_convertvector(v, h16x2); return __builtin_bit_cast(unsigned, b); }
;     __device__ __forceinline__ void operator()(const f32x4 (&acc)[2][2][4][2], const pg8::Unit& u, int wr, int wc, int fr, int fq) const {
;     ...
;             for (int m = 0; m < 4; ++m) { if (half && ai == 1) continue; const unsigned rr = (unsigned)(ai * 128 + m * 16); const unsigned o = eoA + rr * (D * 2u); float ss = 0.f;
;                 const u32x4 la = *(const GAS u32x4*)((const GAS char*)ws + (unsigned)WS_X16 + o), lb = *(const GAS u32x4*)((const GAS char*)ws + (unsigned)WS_X16 + o + D * 2u);
;                 u32x4 xr[2];
; #pragma unroll
;                 for (int c = 0; c < 4; ++c) { const unsigned pa = (unsigned)__builtin_amdgcn_update_dpp(0, (int)la[c], 0xB1, 0xF, 0xF, false), pb = (unsigned)__builtin_amdgcn_update_dpp(0, (int)lb[c], 0xB1, 0xF, 0xF, false);
;                     xr[0][c] = odd ? pb : la[c]; xr[1][c] = odd ? lb[c] : pa; }
;                 u32x4 w[2], v[2];
; #pragma unroll
;                 for (int bj = 0; bj < 2; ++bj) { const h16x8 xb = __builtin_bit_cast(h16x8, xr[bj]);
;                     const f32x4 x0 = (f32x4){(float)xb[0], (float)xb[1], (float)xb[2], (float)xb[3]} + g4[bj][0] * acc[ai][bj][m][0], x1 = (f32x4){(float)xb[4], (float)xb[5], (float)xb[6], (float)xb[7]} + g4[bj][1] * acc[ai][bj][m][1];
;                     ss += ((x0[0] * x0[0] + x0[1] * x0[1]) + (x0[2] * x0[2] + x0[3] * x0[3])) + ((x1[0] * x1[0] + x1[1] * x1[1]) + (x1[2] * x1[2] + x1[3] * x1[3]));
;                     w[bj].x = cvtpk_h(x0[0], x0[1]); w[bj].y = cvtpk_h(x0[2], x0[3]); w[bj].z = cvtpk_h(x1[0], x1[1]); w[bj].w = cvtpk_h(x1[2], x1[3]);
;                     const f32x4 y0 = x0 * a4[bj][0], y1 = x1 * a4[bj][1]; v[bj].x = cvtpk_h(y0[0], y0[1]); v[bj].y = cvtpk_h(y0[2], y0[3]); v[bj].z = cvtpk_h(y1[0], y1[1]); v[bj].w = cvtpk_h(y1[2], y1[3]); }
;                 stg_line_pair(ws, (unsigned)WS_X16 + o, D * 2u, w[0], w[1], odd);
;                 if (an_off) stg_line_pair(ws, (unsigned)WS_XS + o, D * 2u, v[0], v[1], odd);
.Lo_wd_3:
	v_mov_b32_e32 v114, v214
	v_mov_b32_e32 v115, v215
	v_mov_b32_e32 v116, v216
	v_mov_b32_e32 v117, v217
	v_mov_b32_e32 v118, v218
	v_mov_b32_e32 v119, v219
	v_mov_b32_e32 v120, v220
	v_mov_b32_e32 v121, v221
	v_add_u32_e32 v222, 0x40000, v0
	global_load_dwordx4 v[214:217], v222, s[42:43]
	global_load_dwordx4 v[218:221], v222, s[42:43] offset:2048
	v_mov_b32_e32 v122, v1
	v_mov_b32_e32 v123, v1
	v_add_u32_e32 v126, 0x16f98000, v0
	s_and_b64 vcc, exec, s[2:3]
	v_mov_b32_dpp v122, v114 quad_perm:[1,0,3,2] row_mask:0xf bank_mask:0xf
	v_mov_b32_dpp v123, v118 quad_perm:[1,0,3,2] row_mask:0xf bank_mask:0xf
	v_cndmask_b32_e64 v123, v123, v114, s[0:1]
	v_cndmask_b32_e64 v118, v118, v122, s[0:1]
	v_mov_b32_e32 v114, v1
	v_mov_b32_e32 v122, v1
	s_nop 0
	v_mov_b32_dpp v114, v115 quad_perm:[1,0,3,2] row_mask:0xf bank_mask:0xf
	v_mov_b32_dpp v122, v119 quad_perm:[1,0,3,2] row_mask:0xf bank_mask:0xf
	v_cndmask_b32_e64 v122, v122, v115, s[0:1]
	v_cndmask_b32_e64 v119, v119, v114, s[0:1]
	v_mov_b32_e32 v114, v1
	v_mov_b32_e32 v115, v1
	s_nop 0
	v_mov_b32_dpp v114, v116 quad_perm:[1,0,3,2] row_mask:0xf bank_mask:0xf
	v_mov_b32_dpp v115, v120 quad_perm:[1,0,3,2] row_mask:0xf bank_mask:0xf
	v_cndmask_b32_e64 v124, v115, v116, s[0:1]
	v_cndmask_b32_e64 v120, v120, v114, s[0:1]
	v_mov_b32_e32 v114, v1
	v_mov_b32_e32 v115, v1
	v_cvt_f32_f16_e32 v116, v122
	v_mov_b32_dpp v114, v117 quad_perm:[1,0,3,2] row_mask:0xf bank_mask:0xf
	v_mov_b32_dpp v115, v121 quad_perm:[1,0,3,2] row_mask:0xf bank_mask:0xf
	v_cndmask_b32_e64 v125, v115, v117, s[0:1]
	v_cndmask_b32_e64 v121, v121, v114, s[0:1]
	v_cvt_f32_f16_e32 v114, v123
	v_cvt_f32_f16_sdwa v115, v123 dst_sel:DWORD dst_unused:UNUSED_PAD src0_sel:WORD_1
	v_cvt_f32_f16_sdwa v117, v122 dst_sel:DWORD dst_unused:UNUSED_PAD src0_sel:WORD_1
	v_pk_fma_f32 v[110:111], v[110:111], v[50:51], v[114:115]
	v_cvt_f32_f16_e32 v114, v124
	v_cvt_f32_f16_sdwa v115, v124 dst_sel:DWORD dst_unused:UNUSED_PAD src0_sel:WORD_1
	v_pk_fma_f32 v[112:113], v[112:113], v[52:53], v[116:117]
	v_cvt_f32_f16_e32 v116, v125
	v_cvt_f32_f16_sdwa v117, v125 dst_sel:DWORD dst_unused:UNUSED_PAD src0_sel:WORD_1
	v_pk_fma_f32 v[106:107], v[106:107], v[54:55], v[114:115]
	v_cvt_f32_f16_e32 v114, v118
	v_cvt_f32_f16_sdwa v115, v118 dst_sel:DWORD dst_unused:UNUSED_PAD src0_sel:WORD_1
	v_pk_fma_f32 v[108:109], v[108:109], v[56:57], v[116:117]
	v_cvt_f32_f16_e32 v116, v119
	v_cvt_f32_f16_sdwa v117, v119 dst_sel:DWORD dst_unused:UNUSED_PAD src0_sel:WORD_1
	v_pk_fma_f32 v[102:103], v[102:103], v[58:59], v[114:115]
	v_cvt_f32_f16_e32 v114, v120
	v_cvt_f32_f16_sdwa v115, v120 dst_sel:DWORD dst_unused:UNUSED_PAD src0_sel:WORD_1
	v_pk_fma_f32 v[104:105], v[104:105], v[60:61], v[116:117]
	v_cvt_f32_f16_e32 v116, v121
	v_cvt_f32_f16_sdwa v117, v121 dst_sel:DWORD dst_unused:UNUSED_PAD src0_sel:WORD_1
	v_cvt_pk_f16_f32 v122, v110, v111
	v_mov_b32_e32 v118, v1
	v_cvt_pk_f16_f32 v123, v112, v113
	v_pk_fma_f32 v[98:99], v[98:99], v[62:63], v[114:115]
	v_cvt_pk_f16_f32 v115, v102, v103
	v_mov_b32_e32 v114, v1
	v_mov_b32_dpp v118, v122 quad_perm:[1,0,3,2] row_mask:0xf bank_mask:0xf
	v_mov_b32_e32 v119, v1
	v_cvt_pk_f16_f32 v124, v106, v107
	v_pk_fma_f32 v[100:101], v[100:101], v[64:65], v[116:117]
	v_cvt_pk_f16_f32 v116, v104, v105
	v_mov_b32_dpp v114, v115 quad_perm:[1,0,3,2] row_mask:0xf bank_mask:0xf
	v_cndmask_b32_e64 v118, v115, v118, s[0:1]
	v_mov_b32_e32 v115, v1
	v_mov_b32_dpp v119, v123 quad_perm:[1,0,3,2] row_mask:0xf bank_mask:0xf
	v_mov_b32_e32 v120, v1
	v_cvt_pk_f16_f32 v117, v98, v99
	v_mov_b32_dpp v115, v116 quad_perm:[1,0,3,2] row_mask:0xf bank_mask:0xf
	v_cndmask_b32_e64 v119, v116, v119, s[0:1]
	v_mov_b32_e32 v116, v1
	v_mov_b32_dpp v120, v124 quad_perm:[1,0,3,2] row_mask:0xf bank_mask:0xf
	v_cvt_pk_f16_f32 v121, v100, v101
	v_mov_b32_dpp v116, v117 quad_perm:[1,0,3,2] row_mask:0xf bank_mask:0xf
	v_cndmask_b32_e64 v120, v117, v120, s[0:1]
	v_mov_b32_e32 v117, v1
	v_cvt_pk_f16_f32 v125, v108, v109
	v_cndmask_b32_e64 v114, v114, v122, s[0:1]
	v_mov_b32_dpp v117, v121 quad_perm:[1,0,3,2] row_mask:0xf bank_mask:0xf
	v_mov_b32_e32 v122, v1
	v_cndmask_b32_e64 v115, v115, v123, s[0:1]
	v_cndmask_b32_e64 v116, v116, v124, s[0:1]
	v_mov_b32_dpp v122, v125 quad_perm:[1,0,3,2] row_mask:0xf bank_mask:0xf
	v_cndmask_b32_e64 v117, v117, v125, s[0:1]
	v_cndmask_b32_e64 v121, v121, v122, s[0:1]
	global_store_dwordx4 v126, v[114:117], s[38:39] sc1
	s_nop 1
	v_add_u32_e32 v114, 0x16f98800, v0
	global_store_dwordx4 v114, v[118:121], s[38:39] sc1
	s_cbranch_vccnz .LBB0_477
	v_pk_mul_f32 v[114:115], v[32:33], v[100:101]
	v_pk_mul_f32 v[116:117], v[30:31], v[98:99]
	v_cvt_pk_f16_f32 v121, v114, v115
	v_cvt_pk_f16_f32 v120, v116, v117
	v_pk_mul_f32 v[114:115], v[28:29], v[104:105]
	v_pk_mul_f32 v[116:117], v[26:27], v[102:103]
	v_cvt_pk_f16_f32 v119, v114, v115
	v_cvt_pk_f16_f32 v118, v116, v117
	v_pk_mul_f32 v[114:115], v[24:25], v[108:109]
	v_pk_mul_f32 v[116:117], v[22:23], v[106:107]
	v_cvt_pk_f16_f32 v122, v114, v115
	v_cvt_pk_f16_f32 v123, v116, v117
	v_pk_mul_f32 v[114:115], v[20:21], v[112:113]
	v_pk_mul_f32 v[116:117], v[18:19], v[110:111]
	v_cvt_pk_f16_f32 v115, v114, v115
	v_cvt_pk_f16_f32 v114, v116, v117
	v_mov_b32_e32 v117, v1
	v_mov_b32_e32 v116, v1
	v_add_u32_e32 v124, 0x3d98000, v0
	v_mov_b32_dpp v117, v114 quad_perm:[1,0,3,2] row_mask:0xf bank_mask:0xf
	v_mov_b32_dpp v116, v118 quad_perm:[1,0,3,2] row_mask:0xf bank_mask:0xf
	v_cndmask_b32_e64 v118, v118, v117, s[0:1]
	v_mov_b32_e32 v117, v1
	v_cndmask_b32_e64 v114, v116, v114, s[0:1]
	v_mov_b32_e32 v116, v1
	v_mov_b32_dpp v117, v115 quad_perm:[1,0,3,2] row_mask:0xf bank_mask:0xf
	s_nop 0
	v_mov_b32_dpp v116, v119 quad_perm:[1,0,3,2] row_mask:0xf bank_mask:0xf
	v_cndmask_b32_e64 v119, v119, v117, s[0:1]
	v_mov_b32_e32 v117, v1
	v_cndmask_b32_e64 v115, v116, v115, s[0:1]
	v_mov_b32_e32 v116, v1
	v_mov_b32_dpp v117, v123 quad_perm:[1,0,3,2] row_mask:0xf bank_mask:0xf
	s_nop 0
	v_mov_b32_dpp v116, v120 quad_perm:[1,0,3,2] row_mask:0xf bank_mask:0xf
	v_cndmask_b32_e64 v120, v120, v117, s[0:1]
	v_mov_b32_e32 v117, v1
	v_cndmask_b32_e64 v116, v116, v123, s[0:1]
	v_mov_b32_e32 v123, v1
	v_mov_b32_dpp v117, v121 quad_perm:[1,0,3,2] row_mask:0xf bank_mask:0xf
	v_cndmask_b32_e64 v117, v117, v122, s[0:1]
	v_mov_b32_dpp v123, v122 quad_perm:[1,0,3,2] row_mask:0xf bank_mask:0xf
	v_cndmask_b32_e64 v121, v121, v123, s[0:1]
	global_store_dwordx4 v124, v[114:117], s[38:39] sc1
	s_nop 1
	v_add_u32_e32 v114, 0x3d98800, v0
	global_store_dwordx4 v114, v[118:121], s[38:39] sc1
; __device__ __forceinline__ unsigned cvtpk_h(float lo, float hi) { f32x2 v = {lo, hi}; h16x2 b = __builtin_convertvector(v, h16x2); return __builtin_bit_cast(unsigned, b); }
;     __device__ __forceinline__ void operator()(const f32x4 (&acc)[2][2][4][2], const pg8::Unit& u, int wr, int wc, int fr, int fq) const {
;     ...
;                     ss += ((x0[0] * x0[0] + x0[1] * x0[1]) + (x0[2] * x0[2] + x0[3] * x0[3])) + ((x1[0] * x1[0] + x1[1] * x1[1]) + (x1[2] * x1[2] + x1[3] * x1[3]));
;                     w[bj].x = cvtpk_h(x0[0], x0[1]); w[bj].y = cvtpk_h(x0[2], x0[3]); w[bj].z = cvtpk_h(x1[0], x1[1]); w[bj].w = cvtpk_h(x1[2], x1[3]);
;                     const f32x4 y0 = x0 * a4[bj][0], y1 = x1 * a4[bj][1]; v[bj].x = cvtpk_h(y0[0], y0[1]); v[bj].y = cvtpk_h(y0[2], y0[3]); v[bj].z = cvtpk_h(y1[0], y1[1]); v[bj].w = cvtpk_h(y1[2], y1[3]); }
;                 stg_line_pair(ws, (unsigned)WS_X16 + o, D * 2u, w[0], w[1], odd);
;                 if (an_off) stg_line_pair(ws, (unsigned)WS_XS + o, D * 2u, v[0], v[1], odd);
;                 ss = red4(ss, fq * 16 + fr); if (fq == 0) stg_f1(ws, rqo + rr * 4u, ss);
.LBB0_477:
	v_mul_f32_e32 v111, v111, v111
	v_mul_f32_e32 v107, v107, v107
	v_mul_f32_e32 v103, v103, v103
	v_mul_f32_e32 v99, v99, v99
	v_fmac_f32_e32 v111, v110, v110
	v_mul_f32_e32 v110, v113, v113
	v_fmac_f32_e32 v107, v106, v106
	v_mul_f32_e32 v106, v109, v109
	v_fmac_f32_e32 v103, v102, v102
	v_mul_f32_e32 v102, v105, v105
	v_fmac_f32_e32 v99, v98, v98
	v_mul_f32_e32 v98, v101, v101
	v_fmac_f32_e32 v110, v112, v112
	v_fmac_f32_e32 v106, v108, v108
	v_fmac_f32_e32 v102, v104, v104
	v_fmac_f32_e32 v98, v100, v100
	v_add_f32_e32 v110, v111, v110
	v_add_f32_e32 v106, v107, v106
	v_add_f32_e32 v102, v103, v102
	v_add_f32_e32 v98, v99, v98
	v_add_f32_e32 v106, v110, v106
	v_add_f32_e32 v98, v102, v98
	v_add_f32_e32 v98, v98, v106
	v_mov_b32_e32 v99, v98
	s_nop 1
	v_permlane16_swap_b32_e32 v98, v99
	v_add_f32_e32 v98, v98, v99
	v_mov_b32_e32 v99, v98
	s_nop 1
	v_permlane32_swap_b32_e32 v98, v99
	s_and_saveexec_b64 s[44:45], s[4:5]
	s_cbranch_execz .LBB0_479
	v_add_f32_e32 v98, v98, v99
	v_mov_b32_e32 v99, 0x28800c0
	v_lshl_add_u32 v99, v148, 2, v99
	global_store_dword v99, v98, s[38:39] sc1

; #define GAS __attribute__((address_space(1)))
; __device__ __forceinline__ unsigned cvtpk_h(float lo, float hi) { f32x2 v = {lo, hi}; h16x2 b = __builtin_convertvector(v, h16x2); return __builtin_bit_cast(unsigned, b); }
;     __device__ __forceinline__ void operator()(const f32x4 (&acc)[2][2][4][2], const pg8::Unit& u, int wr, int wc, int fr, int fq) const {
;     ...
;             for (int m = 0; m < 4; ++m) { if (half && ai == 1) continue; const unsigned rr = (unsigned)(ai * 128 + m * 16); const unsigned o = eoA + rr * (D * 2u); float ss = 0.f;
;                 const u32x4 la = *(const GAS u32x4*)((const GAS char*)ws + (unsigned)WS_X16 + o), lb = *(const GAS u32x4*)((const GAS char*)ws + (unsigned)WS_X16 + o + D * 2u);
;                 u32x4 xr[2];
; #pragma unroll
;                 for (int c = 0; c < 4; ++c) { const unsigned pa = (unsigned)__builtin_amdgcn_update_dpp(0, (int)la[c], 0xB1, 0xF, 0xF, false), pb = (unsigned)__builtin_amdgcn_update_dpp(0, (int)lb[c], 0xB1, 0xF, 0xF, false);
;                     xr[0][c] = odd ? pb : la[c]; xr[1][c] = odd ? lb[c] : pa; }
;                 u32x4 w[2], v[2];
; #pragma unroll
;                 for (int bj = 0; bj < 2; ++bj) { const h16x8 xb = __builtin_bit_cast(h16x8, xr[bj]);
;                     const f32x4 x0 = (f32x4){(float)xb[0], (float)xb[1], (float)xb[2], (float)xb[3]} + g4[bj][0] * acc[ai][bj][m][0], x1 = (f32x4){(float)xb[4], (float)xb[5], (float)xb[6], (float)xb[7]} + g4[bj][1] * acc[ai][bj][m][1];
;                     ss += ((x0[0] * x0[0] + x0[1] * x0[1]) + (x0[2] * x0[2] + x0[3] * x0[3])) + ((x1[0] * x1[0] + x1[1] * x1[1]) + (x1[2] * x1[2] + x1[3] * x1[3]));
;                     w[bj].x = cvtpk_h(x0[0], x0[1]); w[bj].y = cvtpk_h(x0[2], x0[3]); w[bj].z = cvtpk_h(x1[0], x1[1]); w[bj].w = cvtpk_h(x1[2], x1[3]);
;                     const f32x4 y0 = x0 * a4[bj][0], y1 = x1 * a4[bj][1]; v[bj].x = cvtpk_h(y0[0], y0[1]); v[bj].y = cvtpk_h(y0[2], y0[3]); v[bj].z = cvtpk_h(y1[0], y1[1]); v[bj].w = cvtpk_h(y1[2], y1[3]); }
;                 stg_line_pair(ws, (unsigned)WS_X16 + o, D * 2u, w[0], w[1], odd);
;                 if (an_off) stg_line_pair(ws, (unsigned)WS_XS + o, D * 2u, v[0], v[1], odd);
.Lo_wd_4:
	v_mov_b32_e32 v98, v214
	v_mov_b32_e32 v99, v215
	v_mov_b32_e32 v100, v216
	v_mov_b32_e32 v101, v217
	v_mov_b32_e32 v102, v218
	v_mov_b32_e32 v103, v219
	v_mov_b32_e32 v104, v220
	v_mov_b32_e32 v105, v221
	v_add_u32_e32 v222, 0x48000, v0
	global_load_dwordx4 v[214:217], v222, s[42:43]
	global_load_dwordx4 v[218:221], v222, s[42:43] offset:2048
	v_mov_b32_e32 v106, v1
	v_mov_b32_e32 v107, v1
	v_add_u32_e32 v110, 0x16fc0000, v0
	s_and_b64 vcc, exec, s[2:3]
	v_mov_b32_dpp v106, v98 quad_perm:[1,0,3,2] row_mask:0xf bank_mask:0xf
	v_mov_b32_dpp v107, v102 quad_perm:[1,0,3,2] row_mask:0xf bank_mask:0xf
	v_cndmask_b32_e64 v107, v107, v98, s[0:1]
	v_cndmask_b32_e64 v102, v102, v106, s[0:1]
	v_mov_b32_e32 v98, v1
	v_mov_b32_e32 v106, v1
	s_nop 0
	v_mov_b32_dpp v98, v99 quad_perm:[1,0,3,2] row_mask:0xf bank_mask:0xf
	v_mov_b32_dpp v106, v103 quad_perm:[1,0,3,2] row_mask:0xf bank_mask:0xf
	v_cndmask_b32_e64 v106, v106, v99, s[0:1]
	v_cndmask_b32_e64 v103, v103, v98, s[0:1]
	v_mov_b32_e32 v98, v1
	v_mov_b32_e32 v99, v1
	s_nop 0
	v_mov_b32_dpp v98, v100 quad_perm:[1,0,3,2] row_mask:0xf bank_mask:0xf
	v_mov_b32_dpp v99, v104 quad_perm:[1,0,3,2] row_mask:0xf bank_mask:0xf
	v_cndmask_b32_e64 v108, v99, v100, s[0:1]
	v_cndmask_b32_e64 v104, v104, v98, s[0:1]
	v_mov_b32_e32 v98, v1
	v_mov_b32_e32 v99, v1
	v_cvt_f32_f16_e32 v100, v106
	v_mov_b32_dpp v98, v101 quad_perm:[1,0,3,2] row_mask:0xf bank_mask:0xf
	v_mov_b32_dpp v99, v105 quad_perm:[1,0,3,2] row_mask:0xf bank_mask:0xf
	v_cndmask_b32_e64 v109, v99, v101, s[0:1]
	v_cndmask_b32_e64 v105, v105, v98, s[0:1]
	v_cvt_f32_f16_e32 v98, v107
	v_cvt_f32_f16_sdwa v99, v107 dst_sel:DWORD dst_unused:UNUSED_PAD src0_sel:WORD_1
	v_cvt_f32_f16_sdwa v101, v106 dst_sel:DWORD dst_unused:UNUSED_PAD src0_sel:WORD_1
	v_pk_fma_f32 v[94:95], v[94:95], v[50:51], v[98:99]
	v_cvt_f32_f16_e32 v98, v108
	v_cvt_f32_f16_sdwa v99, v108 dst_sel:DWORD dst_unused:UNUSED_PAD src0_sel:WORD_1
	v_pk_fma_f32 v[96:97], v[96:97], v[52:53], v[100:101]
	v_cvt_f32_f16_e32 v100, v109
	v_cvt_f32_f16_sdwa v101, v109 dst_sel:DWORD dst_unused:UNUSED_PAD src0_sel:WORD_1
	v_pk_fma_f32 v[90:91], v[90:91], v[54:55], v[98:99]
	v_cvt_f32_f16_e32 v98, v102
	v_cvt_f32_f16_sdwa v99, v102 dst_sel:DWORD dst_unused:UNUSED_PAD src0_sel:WORD_1
	v_pk_fma_f32 v[92:93], v[92:93], v[56:57], v[100:101]
	v_cvt_f32_f16_e32 v100, v103
	v_cvt_f32_f16_sdwa v101, v103 dst_sel:DWORD dst_unused:UNUSED_PAD src0_sel:WORD_1
	v_pk_fma_f32 v[86:87], v[86:87], v[58:59], v[98:99]
	v_cvt_f32_f16_e32 v98, v104
	v_cvt_f32_f16_sdwa v99, v104 dst_sel:DWORD dst_unused:UNUSED_PAD src0_sel:WORD_1
	v_pk_fma_f32 v[88:89], v[88:89], v[60:61], v[100:101]
	v_cvt_f32_f16_e32 v100, v105
	v_cvt_f32_f16_sdwa v101, v105 dst_sel:DWORD dst_unused:UNUSED_PAD src0_sel:WORD_1
	v_cvt_pk_f16_f32 v106, v94, v95
	v_mov_b32_e32 v102, v1
	v_cvt_pk_f16_f32 v107, v96, v97
	v_pk_fma_f32 v[82:83], v[82:83], v[62:63], v[98:99]
	v_cvt_pk_f16_f32 v99, v86, v87
	v_mov_b32_e32 v98, v1
	v_mov_b32_dpp v102, v106 quad_perm:[1,0,3,2] row_mask:0xf bank_mask:0xf
	v_mov_b32_e32 v103, v1
	v_cvt_pk_f16_f32 v108, v90, v91
	v_pk_fma_f32 v[84:85], v[84:85], v[64:65], v[100:101]
	v_cvt_pk_f16_f32 v100, v88, v89
	v_mov_b32_dpp v98, v99 quad_perm:[1,0,3,2] row_mask:0xf bank_mask:0xf
	v_cndmask_b32_e64 v102, v99, v102, s[0:1]
	v_mov_b32_e32 v99, v1
	v_mov_b32_dpp v103, v107 quad_perm:[1,0,3,2] row_mask:0xf bank_mask:0xf
	v_mov_b32_e32 v104, v1
	v_cvt_pk_f16_f32 v101, v82, v83
	v_mov_b32_dpp v99, v100 quad_perm:[1,0,3,2] row_mask:0xf bank_mask:0xf
	v_cndmask_b32_e64 v103, v100, v103, s[0:1]
	v_mov_b32_e32 v100, v1
	v_mov_b32_dpp v104, v108 quad_perm:[1,0,3,2] row_mask:0xf bank_mask:0xf
	v_cvt_pk_f16_f32 v105, v84, v85
	v_mov_b32_dpp v100, v101 quad_perm:[1,0,3,2] row_mask:0xf bank_mask:0xf
	v_cndmask_b32_e64 v104, v101, v104, s[0:1]
	v_mov_b32_e32 v101, v1
	v_cvt_pk_f16_f32 v109, v92, v93
	v_cndmask_b32_e64 v98, v98, v106, s[0:1]
	v_mov_b32_dpp v101, v105 quad_perm:[1,0,3,2] row_mask:0xf bank_mask:0xf
	v_mov_b32_e32 v106, v1
	v_cndmask_b32_e64 v99, v99, v107, s[0:1]
	v_cndmask_b32_e64 v100, v100, v108, s[0:1]
	v_mov_b32_dpp v106, v109 quad_perm:[1,0,3,2] row_mask:0xf bank_mask:0xf
	v_cndmask_b32_e64 v101, v101, v109, s[0:1]
	v_cndmask_b32_e64 v105, v105, v106, s[0:1]
	global_store_dwordx4 v110, v[98:101], s[38:39] sc1
	s_nop 1
	v_add_u32_e32 v98, 0x16fc0800, v0
	global_store_dwordx4 v98, v[102:105], s[38:39] sc1
	s_cbranch_vccnz .LBB0_481
	v_pk_mul_f32 v[98:99], v[32:33], v[84:85]
	v_pk_mul_f32 v[100:101], v[30:31], v[82:83]
	v_cvt_pk_f16_f32 v105, v98, v99
	v_cvt_pk_f16_f32 v104, v100, v101
	v_pk_mul_f32 v[98:99], v[28:29], v[88:89]
	v_pk_mul_f32 v[100:101], v[26:27], v[86:87]
	v_cvt_pk_f16_f32 v103, v98, v99
	v_cvt_pk_f16_f32 v102, v100, v101
	v_pk_mul_f32 v[98:99], v[24:25], v[92:93]
	v_pk_mul_f32 v[100:101], v[22:23], v[90:91]
	v_cvt_pk_f16_f32 v106, v98, v99
	v_cvt_pk_f16_f32 v107, v100, v101
	v_pk_mul_f32 v[98:99], v[20:21], v[96:97]
	v_pk_mul_f32 v[100:101], v[18:19], v[94:95]
	v_cvt_pk_f16_f32 v99, v98, v99
	v_cvt_pk_f16_f32 v98, v100, v101
	v_mov_b32_e32 v101, v1
	v_mov_b32_e32 v100, v1
	v_add_u32_e32 v108, 0x3dc0000, v0
	v_mov_b32_dpp v101, v98 quad_perm:[1,0,3,2] row_mask:0xf bank_mask:0xf
	v_mov_b32_dpp v100, v102 quad_perm:[1,0,3,2] row_mask:0xf bank_mask:0xf
	v_cndmask_b32_e64 v102, v102, v101, s[0:1]
	v_mov_b32_e32 v101, v1
	v_cndmask_b32_e64 v98, v100, v98, s[0:1]
	v_mov_b32_e32 v100, v1
	v_mov_b32_dpp v101, v99 quad_perm:[1,0,3,2] row_mask:0xf bank_mask:0xf
	s_nop 0
	v_mov_b32_dpp v100, v103 quad_perm:[1,0,3,2] row_mask:0xf bank_mask:0xf
	v_cndmask_b32_e64 v103, v103, v101, s[0:1]
	v_mov_b32_e32 v101, v1
	v_cndmask_b32_e64 v99, v100, v99, s[0:1]
	v_mov_b32_e32 v100, v1
	v_mov_b32_dpp v101, v107 quad_perm:[1,0,3,2] row_mask:0xf bank_mask:0xf
	s_nop 0
	v_mov_b32_dpp v100, v104 quad_perm:[1,0,3,2] row_mask:0xf bank_mask:0xf
	v_cndmask_b32_e64 v104, v104, v101, s[0:1]
	v_mov_b32_e32 v101, v1
	v_cndmask_b32_e64 v100, v100, v107, s[0:1]
	v_mov_b32_e32 v107, v1
	v_mov_b32_dpp v101, v105 quad_perm:[1,0,3,2] row_mask:0xf bank_mask:0xf
	v_cndmask_b32_e64 v101, v101, v106, s[0:1]
	v_mov_b32_dpp v107, v106 quad_perm:[1,0,3,2] row_mask:0xf bank_mask:0xf
	v_cndmask_b32_e64 v105, v105, v107, s[0:1]
	global_store_dwordx4 v108, v[98:101], s[38:39] sc1
	s_nop 1
	v_add_u32_e32 v98, 0x3dc0800, v0
	global_store_dwordx4 v98, v[102:105], s[38:39] sc1
; __device__ __forceinline__ unsigned cvtpk_h(float lo, float hi) { f32x2 v = {lo, hi}; h16x2 b = __builtin_convertvector(v, h16x2); return __builtin_bit_cast(unsigned, b); }
;     __device__ __forceinline__ void operator()(const f32x4 (&acc)[2][2][4][2], const pg8::Unit& u, int wr, int wc, int fr, int fq) const {
;     ...
;                     ss += ((x0[0] * x0[0] + x0[1] * x0[1]) + (x0[2] * x0[2] + x0[3] * x0[3])) + ((x1[0] * x1[0] + x1[1] * x1[1]) + (x1[2] * x1[2] + x1[3] * x1[3]));
;                     w[bj].x = cvtpk_h(x0[0], x0[1]); w[bj].y = cvtpk_h(x0[2], x0[3]); w[bj].z = cvtpk_h(x1[0], x1[1]); w[bj].w = cvtpk_h(x1[2], x1[3]);
;                     const f32x4 y0 = x0 * a4[bj][0], y1 = x1 * a4[bj][1]; v[bj].x = cvtpk_h(y0[0], y0[1]); v[bj].y = cvtpk_h(y0[2], y0[3]); v[bj].z = cvtpk_h(y1[0], y1[1]); v[bj].w = cvtpk_h(y1[2], y1[3]); }
;                 stg_line_pair(ws, (unsigned)WS_X16 + o, D * 2u, w[0], w[1], odd);
;                 if (an_off) stg_line_pair(ws, (unsigned)WS_XS + o, D * 2u, v[0], v[1], odd);
;                 ss = red4(ss, fq * 16 + fr); if (fq == 0) stg_f1(ws, rqo + rr * 4u, ss);
.LBB0_481:
	v_mul_f32_e32 v95, v95, v95
	v_mul_f32_e32 v91, v91, v91
	v_mul_f32_e32 v87, v87, v87
	v_mul_f32_e32 v83, v83, v83
	v_fmac_f32_e32 v95, v94, v94
	v_mul_f32_e32 v94, v97, v97
	v_fmac_f32_e32 v91, v90, v90
	v_mul_f32_e32 v90, v93, v93
	v_fmac_f32_e32 v87, v86, v86
	v_mul_f32_e32 v86, v89, v89
	v_fmac_f32_e32 v83, v82, v82
	v_mul_f32_e32 v82, v85, v85
	v_fmac_f32_e32 v94, v96, v96
	v_fmac_f32_e32 v90, v92, v92
	v_fmac_f32_e32 v86, v88, v88
	v_fmac_f32_e32 v82, v84, v84
	v_add_f32_e32 v94, v95, v94
	v_add_f32_e32 v90, v91, v90
	v_add_f32_e32 v86, v87, v86
	v_add_f32_e32 v82, v83, v82
	v_add_f32_e32 v90, v94, v90
	v_add_f32_e32 v82, v86, v82
	v_add_f32_e32 v82, v82, v90
	v_mov_b32_e32 v83, v82
	s_nop 1
	v_permlane16_swap_b32_e32 v82, v83
	v_add_f32_e32 v82, v82, v83
	v_mov_b32_e32 v83, v82
	s_nop 1
	v_permlane32_swap_b32_e32 v82, v83
	s_and_saveexec_b64 s[44:45], s[4:5]
	s_cbranch_execz .LBB0_483
	v_add_f32_e32 v82, v82, v83
	v_mov_b32_e32 v83, 0x2880200
	v_lshl_add_u32 v83, v148, 2, v83
	global_store_dword v83, v82, s[38:39] sc1

; #define GAS __attribute__((address_space(1)))
; __device__ __forceinline__ unsigned cvtpk_h(float lo, float hi) { f32x2 v = {lo, hi}; h16x2 b = __builtin_convertvector(v, h16x2); return __builtin_bit_cast(unsigned, b); }
;     __device__ __forceinline__ void operator()(const f32x4 (&acc)[2][2][4][2], const pg8::Unit& u, int wr, int wc, int fr, int fq) const {
;     ...
;             for (int m = 0; m < 4; ++m) { if (half && ai == 1) continue; const unsigned rr = (unsigned)(ai * 128 + m * 16); const unsigned o = eoA + rr * (D * 2u); float ss = 0.f;
;                 const u32x4 la = *(const GAS u32x4*)((const GAS char*)ws + (unsigned)WS_X16 + o), lb = *(const GAS u32x4*)((const GAS char*)ws + (unsigned)WS_X16 + o + D * 2u);
;                 u32x4 xr[2];
; #pragma unroll
;                 for (int c = 0; c < 4; ++c) { const unsigned pa = (unsigned)__builtin_amdgcn_update_dpp(0, (int)la[c], 0xB1, 0xF, 0xF, false), pb = (unsigned)__builtin_amdgcn_update_dpp(0, (int)lb[c], 0xB1, 0xF, 0xF, false);
;                     xr[0][c] = odd ? pb : la[c]; xr[1][c] = odd ? lb[c] : pa; }
;                 u32x4 w[2], v[2];
; #pragma unroll
;                 for (int bj = 0; bj < 2; ++bj) { const h16x8 xb = __builtin_bit_cast(h16x8, xr[bj]);
;                     const f32x4 x0 = (f32x4){(float)xb[0], (float)xb[1], (float)xb[2], (float)xb[3]} + g4[bj][0] * acc[ai][bj][m][0], x1 = (f32x4){(float)xb[4], (float)xb[5], (float)xb[6], (float)xb[7]} + g4[bj][1] * acc[ai][bj][m][1];
;                     ss += ((x0[0] * x0[0] + x0[1] * x0[1]) + (x0[2] * x0[2] + x0[3] * x0[3])) + ((x1[0] * x1[0] + x1[1] * x1[1]) + (x1[2] * x1[2] + x1[3] * x1[3]));
;                     w[bj].x = cvtpk_h(x0[0], x0[1]); w[bj].y = cvtpk_h(x0[2], x0[3]); w[bj].z = cvtpk_h(x1[0], x1[1]); w[bj].w = cvtpk_h(x1[2], x1[3]);
;                     const f32x4 y0 = x0 * a4[bj][0], y1 = x1 * a4[bj][1]; v[bj].x = cvtpk_h(y0[0], y0[1]); v[bj].y = cvtpk_h(y0[2], y0[3]); v[bj].z = cvtpk_h(y1[0], y1[1]); v[bj].w = cvtpk_h(y1[2], y1[3]); }
;                 stg_line_pair(ws, (unsigned)WS_X16 + o, D * 2u, w[0], w[1], odd);
;                 if (an_off) stg_line_pair(ws, (unsigned)WS_XS + o, D * 2u, v[0], v[1], odd);
.Lo_wd_5:
	v_mov_b32_e32 v82, v214
	v_mov_b32_e32 v83, v215
	v_mov_b32_e32 v84, v216
	v_mov_b32_e32 v85, v217
	v_mov_b32_e32 v86, v218
	v_mov_b32_e32 v87, v219
	v_mov_b32_e32 v88, v220
	v_mov_b32_e32 v89, v221
	v_add_u32_e32 v222, 0x50000, v0
	global_load_dwordx4 v[214:217], v222, s[42:43]
	global_load_dwordx4 v[218:221], v222, s[42:43] offset:2048
	v_mov_b32_e32 v90, v1
	v_mov_b32_e32 v91, v1
	v_add_u32_e32 v94, 0x16fc8000, v0
	s_and_b64 vcc, exec, s[2:3]
	v_mov_b32_dpp v90, v82 quad_perm:[1,0,3,2] row_mask:0xf bank_mask:0xf
	v_mov_b32_dpp v91, v86 quad_perm:[1,0,3,2] row_mask:0xf bank_mask:0xf
	v_cndmask_b32_e64 v91, v91, v82, s[0:1]
	v_cndmask_b32_e64 v86, v86, v90, s[0:1]
	v_mov_b32_e32 v82, v1
	v_mov_b32_e32 v90, v1
	s_nop 0
	v_mov_b32_dpp v82, v83 quad_perm:[1,0,3,2] row_mask:0xf bank_mask:0xf
	v_mov_b32_dpp v90, v87 quad_perm:[1,0,3,2] row_mask:0xf bank_mask:0xf
	v_cndmask_b32_e64 v90, v90, v83, s[0:1]
	v_cndmask_b32_e64 v87, v87, v82, s[0:1]
	v_mov_b32_e32 v82, v1
	v_mov_b32_e32 v83, v1
	s_nop 0
	v_mov_b32_dpp v82, v84 quad_perm:[1,0,3,2] row_mask:0xf bank_mask:0xf
	v_mov_b32_dpp v83, v88 quad_perm:[1,0,3,2] row_mask:0xf bank_mask:0xf
	v_cndmask_b32_e64 v92, v83, v84, s[0:1]
	v_cndmask_b32_e64 v88, v88, v82, s[0:1]
	v_mov_b32_e32 v82, v1
	v_mov_b32_e32 v83, v1
	v_cvt_f32_f16_e32 v84, v90
	v_mov_b32_dpp v82, v85 quad_perm:[1,0,3,2] row_mask:0xf bank_mask:0xf
	v_mov_b32_dpp v83, v89 quad_perm:[1,0,3,2] row_mask:0xf bank_mask:0xf
	v_cndmask_b32_e64 v93, v83, v85, s[0:1]
	v_cndmask_b32_e64 v89, v89, v82, s[0:1]
	v_cvt_f32_f16_e32 v82, v91
	v_cvt_f32_f16_sdwa v83, v91 dst_sel:DWORD dst_unused:UNUSED_PAD src0_sel:WORD_1
	v_cvt_f32_f16_sdwa v85, v90 dst_sel:DWORD dst_unused:UNUSED_PAD src0_sel:WORD_1
	v_pk_fma_f32 v[78:79], v[78:79], v[50:51], v[82:83]
	v_cvt_f32_f16_e32 v82, v92
	v_cvt_f32_f16_sdwa v83, v92 dst_sel:DWORD dst_unused:UNUSED_PAD src0_sel:WORD_1
	v_pk_fma_f32 v[80:81], v[80:81], v[52:53], v[84:85]
	v_cvt_f32_f16_e32 v84, v93
	v_cvt_f32_f16_sdwa v85, v93 dst_sel:DWORD dst_unused:UNUSED_PAD src0_sel:WORD_1
	v_pk_fma_f32 v[74:75], v[74:75], v[54:55], v[82:83]
	v_cvt_f32_f16_e32 v82, v86
	v_cvt_f32_f16_sdwa v83, v86 dst_sel:DWORD dst_unused:UNUSED_PAD src0_sel:WORD_1
	v_pk_fma_f32 v[76:77], v[76:77], v[56:57], v[84:85]
	v_cvt_f32_f16_e32 v84, v87
	v_cvt_f32_f16_sdwa v85, v87 dst_sel:DWORD dst_unused:UNUSED_PAD src0_sel:WORD_1
	v_pk_fma_f32 v[70:71], v[70:71], v[58:59], v[82:83]
	v_cvt_f32_f16_e32 v82, v88
	v_cvt_f32_f16_sdwa v83, v88 dst_sel:DWORD dst_unused:UNUSED_PAD src0_sel:WORD_1
	v_pk_fma_f32 v[72:73], v[72:73], v[60:61], v[84:85]
	v_cvt_f32_f16_e32 v84, v89
	v_cvt_f32_f16_sdwa v85, v89 dst_sel:DWORD dst_unused:UNUSED_PAD src0_sel:WORD_1
	v_cvt_pk_f16_f32 v90, v78, v79
	v_mov_b32_e32 v86, v1
	v_cvt_pk_f16_f32 v91, v80, v81
	v_pk_fma_f32 v[66:67], v[66:67], v[62:63], v[82:83]
	v_cvt_pk_f16_f32 v83, v70, v71
	v_mov_b32_e32 v82, v1
	v_mov_b32_dpp v86, v90 quad_perm:[1,0,3,2] row_mask:0xf bank_mask:0xf
	v_mov_b32_e32 v87, v1
	v_cvt_pk_f16_f32 v92, v74, v75
	v_pk_fma_f32 v[68:69], v[68:69], v[64:65], v[84:85]
	v_cvt_pk_f16_f32 v84, v72, v73
	v_mov_b32_dpp v82, v83 quad_perm:[1,0,3,2] row_mask:0xf bank_mask:0xf
	v_cndmask_b32_e64 v86, v83, v86, s[0:1]
	v_mov_b32_e32 v83, v1
	v_mov_b32_dpp v87, v91 quad_perm:[1,0,3,2] row_mask:0xf bank_mask:0xf
	v_mov_b32_e32 v88, v1
	v_cvt_pk_f16_f32 v85, v66, v67
	v_mov_b32_dpp v83, v84 quad_perm:[1,0,3,2] row_mask:0xf bank_mask:0xf
	v_cndmask_b32_e64 v87, v84, v87, s[0:1]
	v_mov_b32_e32 v84, v1
	v_mov_b32_dpp v88, v92 quad_perm:[1,0,3,2] row_mask:0xf bank_mask:0xf
	v_cvt_pk_f16_f32 v89, v68, v69
	v_mov_b32_dpp v84, v85 quad_perm:[1,0,3,2] row_mask:0xf bank_mask:0xf
	v_cndmask_b32_e64 v88, v85, v88, s[0:1]
	v_mov_b32_e32 v85, v1
	v_cvt_pk_f16_f32 v93, v76, v77
	v_cndmask_b32_e64 v82, v82, v90, s[0:1]
	v_mov_b32_dpp v85, v89 quad_perm:[1,0,3,2] row_mask:0xf bank_mask:0xf
	v_mov_b32_e32 v90, v1
	v_cndmask_b32_e64 v83, v83, v91, s[0:1]
	v_cndmask_b32_e64 v84, v84, v92, s[0:1]
	v_mov_b32_dpp v90, v93 quad_perm:[1,0,3,2] row_mask:0xf bank_mask:0xf
	v_cndmask_b32_e64 v85, v85, v93, s[0:1]
	v_cndmask_b32_e64 v89, v89, v90, s[0:1]
	global_store_dwordx4 v94, v[82:85], s[38:39] sc1
	s_nop 1
	v_add_u32_e32 v82, 0x16fc8800, v0
	global_store_dwordx4 v82, v[86:89], s[38:39] sc1
	s_cbranch_vccnz .LBB0_485
	v_pk_mul_f32 v[82:83], v[32:33], v[68:69]
	v_pk_mul_f32 v[84:85], v[30:31], v[66:67]
	v_cvt_pk_f16_f32 v89, v82, v83
	v_cvt_pk_f16_f32 v88, v84, v85
	v_pk_mul_f32 v[82:83], v[28:29], v[72:73]
	v_pk_mul_f32 v[84:85], v[26:27], v[70:71]
	v_cvt_pk_f16_f32 v87, v82, v83
	v_cvt_pk_f16_f32 v86, v84, v85
	v_pk_mul_f32 v[82:83], v[24:25], v[76:77]
	v_pk_mul_f32 v[84:85], v[22:23], v[74:75]
	v_cvt_pk_f16_f32 v90, v82, v83
	v_cvt_pk_f16_f32 v91, v84, v85
	v_pk_mul_f32 v[82:83], v[20:21], v[80:81]
	v_pk_mul_f32 v[84:85], v[18:19], v[78:79]
	v_cvt_pk_f16_f32 v83, v82, v83
	v_cvt_pk_f16_f32 v82, v84, v85
	v_mov_b32_e32 v85, v1
	v_mov_b32_e32 v84, v1
	v_add_u32_e32 v92, 0x3dc8000, v0
	v_mov_b32_dpp v85, v82 quad_perm:[1,0,3,2] row_mask:0xf bank_mask:0xf
	v_mov_b32_dpp v84, v86 quad_perm:[1,0,3,2] row_mask:0xf bank_mask:0xf
	v_cndmask_b32_e64 v86, v86, v85, s[0:1]
	v_mov_b32_e32 v85, v1
	v_cndmask_b32_e64 v82, v84, v82, s[0:1]
	v_mov_b32_e32 v84, v1
	v_mov_b32_dpp v85, v83 quad_perm:[1,0,3,2] row_mask:0xf bank_mask:0xf
	s_nop 0
	v_mov_b32_dpp v84, v87 quad_perm:[1,0,3,2] row_mask:0xf bank_mask:0xf
	v_cndmask_b32_e64 v87, v87, v85, s[0:1]
	v_mov_b32_e32 v85, v1
	v_cndmask_b32_e64 v83, v84, v83, s[0:1]
	v_mov_b32_e32 v84, v1
	v_mov_b32_dpp v85, v91 quad_perm:[1,0,3,2] row_mask:0xf bank_mask:0xf
	s_nop 0
	v_mov_b32_dpp v84, v88 quad_perm:[1,0,3,2] row_mask:0xf bank_mask:0xf
	v_cndmask_b32_e64 v88, v88, v85, s[0:1]
	v_mov_b32_e32 v85, v1
	v_cndmask_b32_e64 v84, v84, v91, s[0:1]
	v_mov_b32_e32 v91, v1
	v_mov_b32_dpp v85, v89 quad_perm:[1,0,3,2] row_mask:0xf bank_mask:0xf
	v_cndmask_b32_e64 v85, v85, v90, s[0:1]
	v_mov_b32_dpp v91, v90 quad_perm:[1,0,3,2] row_mask:0xf bank_mask:0xf
	v_cndmask_b32_e64 v89, v89, v91, s[0:1]
	global_store_dwordx4 v92, v[82:85], s[38:39] sc1
	s_nop 1
	v_add_u32_e32 v82, 0x3dc8800, v0
	global_store_dwordx4 v82, v[86:89], s[38:39] sc1
; __device__ __forceinline__ unsigned cvtpk_h(float lo, float hi) { f32x2 v = {lo, hi}; h16x2 b = __builtin_convertvector(v, h16x2); return __builtin_bit_cast(unsigned, b); }
;     __device__ __forceinline__ void operator()(const f32x4 (&acc)[2][2][4][2], const pg8::Unit& u, int wr, int wc, int fr, int fq) const {
;     ...
;                     ss += ((x0[0] * x0[0] + x0[1] * x0[1]) + (x0[2] * x0[2] + x0[3] * x0[3])) + ((x1[0] * x1[0] + x1[1] * x1[1]) + (x1[2] * x1[2] + x1[3] * x1[3]));
;                     w[bj].x = cvtpk_h(x0[0], x0[1]); w[bj].y = cvtpk_h(x0[2], x0[3]); w[bj].z = cvtpk_h(x1[0], x1[1]); w[bj].w = cvtpk_h(x1[2], x1[3]);
;                     const f32x4 y0 = x0 * a4[bj][0], y1 = x1 * a4[bj][1]; v[bj].x = cvtpk_h(y0[0], y0[1]); v[bj].y = cvtpk_h(y0[2], y0[3]); v[bj].z = cvtpk_h(y1[0], y1[1]); v[bj].w = cvtpk_h(y1[2], y1[3]); }
;                 stg_line_pair(ws, (unsigned)WS_X16 + o, D * 2u, w[0], w[1], odd);
;                 if (an_off) stg_line_pair(ws, (unsigned)WS_XS + o, D * 2u, v[0], v[1], odd);
;                 ss = red4(ss, fq * 16 + fr); if (fq == 0) stg_f1(ws, rqo + rr * 4u, ss);
.LBB0_485:
	v_mul_f32_e32 v79, v79, v79
	v_mul_f32_e32 v75, v75, v75
	v_mul_f32_e32 v71, v71, v71
	v_mul_f32_e32 v67, v67, v67
	v_fmac_f32_e32 v79, v78, v78
	v_mul_f32_e32 v78, v81, v81
	v_fmac_f32_e32 v75, v74, v74
	v_mul_f32_e32 v74, v77, v77
	v_fmac_f32_e32 v71, v70, v70
	v_mul_f32_e32 v70, v73, v73
	v_fmac_f32_e32 v67, v66, v66
	v_mul_f32_e32 v66, v69, v69
	v_fmac_f32_e32 v78, v80, v80
	v_fmac_f32_e32 v74, v76, v76
	v_fmac_f32_e32 v70, v72, v72
	v_fmac_f32_e32 v66, v68, v68
	v_add_f32_e32 v78, v79, v78
	v_add_f32_e32 v74, v75, v74
	v_add_f32_e32 v70, v71, v70
	v_add_f32_e32 v66, v67, v66
	v_add_f32_e32 v74, v78, v74
	v_add_f32_e32 v66, v70, v66
	v_add_f32_e32 v66, v66, v74
	v_mov_b32_e32 v67, v66
	s_nop 1
	v_permlane16_swap_b32_e32 v66, v67
	v_add_f32_e32 v66, v66, v67
	v_mov_b32_e32 v67, v66
	s_nop 1
	v_permlane32_swap_b32_e32 v66, v67
	s_and_saveexec_b64 s[44:45], s[4:5]
	s_cbranch_execz .LBB0_487
	v_add_f32_e32 v66, v66, v67
	v_mov_b32_e32 v67, 0x2880240
	v_lshl_add_u32 v67, v148, 2, v67
	global_store_dword v67, v66, s[38:39] sc1

; #define GAS __attribute__((address_space(1)))
; __device__ __forceinline__ unsigned cvtpk_h(float lo, float hi) { f32x2 v = {lo, hi}; h16x2 b = __builtin_convertvector(v, h16x2); return __builtin_bit_cast(unsigned, b); }
;     __device__ __forceinline__ void operator()(const f32x4 (&acc)[2][2][4][2], const pg8::Unit& u, int wr, int wc, int fr, int fq) const {
;     ...
;             for (int m = 0; m < 4; ++m) { if (half && ai == 1) continue; const unsigned rr = (unsigned)(ai * 128 + m * 16); const unsigned o = eoA + rr * (D * 2u); float ss = 0.f;
;                 const u32x4 la = *(const GAS u32x4*)((const GAS char*)ws + (unsigned)WS_X16 + o), lb = *(const GAS u32x4*)((const GAS char*)ws + (unsigned)WS_X16 + o + D * 2u);
;                 u32x4 xr[2];
; #pragma unroll
;                 for (int c = 0; c < 4; ++c) { const unsigned pa = (unsigned)__builtin_amdgcn_update_dpp(0, (int)la[c], 0xB1, 0xF, 0xF, false), pb = (unsigned)__builtin_amdgcn_update_dpp(0, (int)lb[c], 0xB1, 0xF, 0xF, false);
;                     xr[0][c] = odd ? pb : la[c]; xr[1][c] = odd ? lb[c] : pa; }
;                 u32x4 w[2], v[2];
; #pragma unroll
;                 for (int bj = 0; bj < 2; ++bj) { const h16x8 xb = __builtin_bit_cast(h16x8, xr[bj]);
;                     const f32x4 x0 = (f32x4){(float)xb[0], (float)xb[1], (float)xb[2], (float)xb[3]} + g4[bj][0] * acc[ai][bj][m][0], x1 = (f32x4){(float)xb[4], (float)xb[5], (float)xb[6], (float)xb[7]} + g4[bj][1] * acc[ai][bj][m][1];
;                     ss += ((x0[0] * x0[0] + x0[1] * x0[1]) + (x0[2] * x0[2] + x0[3] * x0[3])) + ((x1[0] * x1[0] + x1[1] * x1[1]) + (x1[2] * x1[2] + x1[3] * x1[3]));
;                     w[bj].x = cvtpk_h(x0[0], x0[1]); w[bj].y = cvtpk_h(x0[2], x0[3]); w[bj].z = cvtpk_h(x1[0], x1[1]); w[bj].w = cvtpk_h(x1[2], x1[3]);
;                     const f32x4 y0 = x0 * a4[bj][0], y1 = x1 * a4[bj][1]; v[bj].x = cvtpk_h(y0[0], y0[1]); v[bj].y = cvtpk_h(y0[2], y0[3]); v[bj].z = cvtpk_h(y1[0], y1[1]); v[bj].w = cvtpk_h(y1[2], y1[3]); }
;                 stg_line_pair(ws, (unsigned)WS_X16 + o, D * 2u, w[0], w[1], odd);
;                 if (an_off) stg_line_pair(ws, (unsigned)WS_XS + o, D * 2u, v[0], v[1], odd);
.Lo_wd_6:
	v_mov_b32_e32 v66, v214
	v_mov_b32_e32 v67, v215
	v_mov_b32_e32 v68, v216
	v_mov_b32_e32 v69, v217
	v_mov_b32_e32 v70, v218
	v_mov_b32_e32 v71, v219
	v_mov_b32_e32 v72, v220
	v_mov_b32_e32 v73, v221
	v_add_u32_e32 v222, 0x58000, v0
	global_load_dwordx4 v[214:217], v222, s[42:43]
	global_load_dwordx4 v[218:221], v222, s[42:43] offset:2048
	v_mov_b32_e32 v74, v1
	v_mov_b32_e32 v75, v1
	v_add_u32_e32 v78, 0x16fd0000, v0
	s_and_b64 vcc, exec, s[2:3]
	v_mov_b32_dpp v74, v66 quad_perm:[1,0,3,2] row_mask:0xf bank_mask:0xf
	v_mov_b32_dpp v75, v70 quad_perm:[1,0,3,2] row_mask:0xf bank_mask:0xf
	v_cndmask_b32_e64 v75, v75, v66, s[0:1]
	v_cndmask_b32_e64 v70, v70, v74, s[0:1]
	v_mov_b32_e32 v66, v1
	v_mov_b32_e32 v74, v1
	s_nop 0
	v_mov_b32_dpp v66, v67 quad_perm:[1,0,3,2] row_mask:0xf bank_mask:0xf
	v_mov_b32_dpp v74, v71 quad_perm:[1,0,3,2] row_mask:0xf bank_mask:0xf
	v_cndmask_b32_e64 v74, v74, v67, s[0:1]
	v_cndmask_b32_e64 v71, v71, v66, s[0:1]
	v_mov_b32_e32 v66, v1
	v_mov_b32_e32 v67, v1
	s_nop 0
	v_mov_b32_dpp v66, v68 quad_perm:[1,0,3,2] row_mask:0xf bank_mask:0xf
	v_mov_b32_dpp v67, v72 quad_perm:[1,0,3,2] row_mask:0xf bank_mask:0xf
	v_cndmask_b32_e64 v76, v67, v68, s[0:1]
	v_cndmask_b32_e64 v72, v72, v66, s[0:1]
	v_mov_b32_e32 v66, v1
	v_mov_b32_e32 v67, v1
	v_cvt_f32_f16_e32 v68, v74
	v_mov_b32_dpp v66, v69 quad_perm:[1,0,3,2] row_mask:0xf bank_mask:0xf
	v_mov_b32_dpp v67, v73 quad_perm:[1,0,3,2] row_mask:0xf bank_mask:0xf
	v_cndmask_b32_e64 v77, v67, v69, s[0:1]
	v_cndmask_b32_e64 v73, v73, v66, s[0:1]
	v_cvt_f32_f16_e32 v66, v75
	v_cvt_f32_f16_sdwa v67, v75 dst_sel:DWORD dst_unused:UNUSED_PAD src0_sel:WORD_1
	v_cvt_f32_f16_sdwa v69, v74 dst_sel:DWORD dst_unused:UNUSED_PAD src0_sel:WORD_1
	v_pk_fma_f32 v[46:47], v[46:47], v[50:51], v[66:67]
	v_cvt_f32_f16_e32 v66, v76
	v_cvt_f32_f16_sdwa v67, v76 dst_sel:DWORD dst_unused:UNUSED_PAD src0_sel:WORD_1
	v_pk_fma_f32 v[48:49], v[48:49], v[52:53], v[68:69]
	v_cvt_f32_f16_e32 v68, v77
	v_cvt_f32_f16_sdwa v69, v77 dst_sel:DWORD dst_unused:UNUSED_PAD src0_sel:WORD_1
	v_pk_fma_f32 v[42:43], v[42:43], v[54:55], v[66:67]
	v_cvt_f32_f16_e32 v66, v70
	v_cvt_f32_f16_sdwa v67, v70 dst_sel:DWORD dst_unused:UNUSED_PAD src0_sel:WORD_1
	v_pk_fma_f32 v[44:45], v[44:45], v[56:57], v[68:69]
	v_cvt_f32_f16_e32 v68, v71
	v_cvt_f32_f16_sdwa v69, v71 dst_sel:DWORD dst_unused:UNUSED_PAD src0_sel:WORD_1
	v_pk_fma_f32 v[38:39], v[38:39], v[58:59], v[66:67]
	v_cvt_f32_f16_e32 v66, v72
	v_cvt_f32_f16_sdwa v67, v72 dst_sel:DWORD dst_unused:UNUSED_PAD src0_sel:WORD_1
	v_pk_fma_f32 v[40:41], v[40:41], v[60:61], v[68:69]
	v_cvt_f32_f16_e32 v68, v73
	v_cvt_f32_f16_sdwa v69, v73 dst_sel:DWORD dst_unused:UNUSED_PAD src0_sel:WORD_1
	v_cvt_pk_f16_f32 v74, v46, v47
	v_mov_b32_e32 v70, v1
	v_cvt_pk_f16_f32 v75, v48, v49
	v_pk_fma_f32 v[34:35], v[34:35], v[62:63], v[66:67]
	v_cvt_pk_f16_f32 v67, v38, v39
	v_mov_b32_e32 v66, v1
	v_mov_b32_dpp v70, v74 quad_perm:[1,0,3,2] row_mask:0xf bank_mask:0xf
	v_mov_b32_e32 v71, v1
	v_cvt_pk_f16_f32 v76, v42, v43
	v_pk_fma_f32 v[36:37], v[36:37], v[64:65], v[68:69]
	v_cvt_pk_f16_f32 v68, v40, v41
	v_mov_b32_dpp v66, v67 quad_perm:[1,0,3,2] row_mask:0xf bank_mask:0xf
	v_cndmask_b32_e64 v70, v67, v70, s[0:1]
	v_mov_b32_e32 v67, v1
	v_mov_b32_dpp v71, v75 quad_perm:[1,0,3,2] row_mask:0xf bank_mask:0xf
	v_mov_b32_e32 v72, v1
	v_cvt_pk_f16_f32 v69, v34, v35
	v_mov_b32_dpp v67, v68 quad_perm:[1,0,3,2] row_mask:0xf bank_mask:0xf
	v_cndmask_b32_e64 v71, v68, v71, s[0:1]
	v_mov_b32_e32 v68, v1
	v_mov_b32_dpp v72, v76 quad_perm:[1,0,3,2] row_mask:0xf bank_mask:0xf
	v_cvt_pk_f16_f32 v73, v36, v37
	v_mov_b32_dpp v68, v69 quad_perm:[1,0,3,2] row_mask:0xf bank_mask:0xf
	v_cndmask_b32_e64 v72, v69, v72, s[0:1]
	v_mov_b32_e32 v69, v1
	v_cvt_pk_f16_f32 v77, v44, v45
	v_cndmask_b32_e64 v66, v66, v74, s[0:1]
	v_mov_b32_dpp v69, v73 quad_perm:[1,0,3,2] row_mask:0xf bank_mask:0xf
	v_mov_b32_e32 v74, v1
	v_cndmask_b32_e64 v67, v67, v75, s[0:1]
	v_cndmask_b32_e64 v68, v68, v76, s[0:1]
	v_mov_b32_dpp v74, v77 quad_perm:[1,0,3,2] row_mask:0xf bank_mask:0xf
	v_cndmask_b32_e64 v69, v69, v77, s[0:1]
	v_cndmask_b32_e64 v73, v73, v74, s[0:1]
	global_store_dwordx4 v78, v[66:69], s[38:39] sc1
	s_nop 1
	v_add_u32_e32 v66, 0x16fd0800, v0
	global_store_dwordx4 v66, v[70:73], s[38:39] sc1
	s_cbranch_vccnz .LBB0_489
	v_pk_mul_f32 v[66:67], v[32:33], v[36:37]
	v_pk_mul_f32 v[68:69], v[30:31], v[34:35]
	v_cvt_pk_f16_f32 v73, v66, v67
	v_cvt_pk_f16_f32 v72, v68, v69
	v_pk_mul_f32 v[66:67], v[28:29], v[40:41]
	v_pk_mul_f32 v[68:69], v[26:27], v[38:39]
	v_cvt_pk_f16_f32 v71, v66, v67
	v_cvt_pk_f16_f32 v70, v68, v69
	v_pk_mul_f32 v[66:67], v[24:25], v[44:45]
	v_pk_mul_f32 v[68:69], v[22:23], v[42:43]
	v_cvt_pk_f16_f32 v74, v66, v67
	v_cvt_pk_f16_f32 v75, v68, v69
	v_pk_mul_f32 v[66:67], v[20:21], v[48:49]
	v_pk_mul_f32 v[68:69], v[18:19], v[46:47]
	v_cvt_pk_f16_f32 v67, v66, v67
	v_cvt_pk_f16_f32 v66, v68, v69
	v_mov_b32_e32 v69, v1
	v_mov_b32_e32 v68, v1
	v_add_u32_e32 v76, 0x3dd0000, v0
	v_mov_b32_dpp v69, v66 quad_perm:[1,0,3,2] row_mask:0xf bank_mask:0xf
	v_mov_b32_dpp v68, v70 quad_perm:[1,0,3,2] row_mask:0xf bank_mask:0xf
	v_cndmask_b32_e64 v70, v70, v69, s[0:1]
	v_mov_b32_e32 v69, v1
	v_cndmask_b32_e64 v66, v68, v66, s[0:1]
	v_mov_b32_e32 v68, v1
	v_mov_b32_dpp v69, v67 quad_perm:[1,0,3,2] row_mask:0xf bank_mask:0xf
	s_nop 0
	v_mov_b32_dpp v68, v71 quad_perm:[1,0,3,2] row_mask:0xf bank_mask:0xf
	v_cndmask_b32_e64 v71, v71, v69, s[0:1]
	v_mov_b32_e32 v69, v1
	v_cndmask_b32_e64 v67, v68, v67, s[0:1]
	v_mov_b32_e32 v68, v1
	v_mov_b32_dpp v69, v75 quad_perm:[1,0,3,2] row_mask:0xf bank_mask:0xf
	s_nop 0
	v_mov_b32_dpp v68, v72 quad_perm:[1,0,3,2] row_mask:0xf bank_mask:0xf
	v_cndmask_b32_e64 v72, v72, v69, s[0:1]
	v_mov_b32_e32 v69, v1
	v_cndmask_b32_e64 v68, v68, v75, s[0:1]
	v_mov_b32_e32 v75, v1
	v_mov_b32_dpp v69, v73 quad_perm:[1,0,3,2] row_mask:0xf bank_mask:0xf
	v_cndmask_b32_e64 v69, v69, v74, s[0:1]
	v_mov_b32_dpp v75, v74 quad_perm:[1,0,3,2] row_mask:0xf bank_mask:0xf
	v_cndmask_b32_e64 v73, v73, v75, s[0:1]
	global_store_dwordx4 v76, v[66:69], s[38:39] sc1
	s_nop 1
	v_add_u32_e32 v66, 0x3dd0800, v0
	global_store_dwordx4 v66, v[70:73], s[38:39] sc1
; __device__ __forceinline__ unsigned cvtpk_h(float lo, float hi) { f32x2 v = {lo, hi}; h16x2 b = __builtin_convertvector(v, h16x2); return __builtin_bit_cast(unsigned, b); }
;     __device__ __forceinline__ void operator()(const f32x4 (&acc)[2][2][4][2], const pg8::Unit& u, int wr, int wc, int fr, int fq) const {
;     ...
;                     ss += ((x0[0] * x0[0] + x0[1] * x0[1]) + (x0[2] * x0[2] + x0[3] * x0[3])) + ((x1[0] * x1[0] + x1[1] * x1[1]) + (x1[2] * x1[2] + x1[3] * x1[3]));
;                     w[bj].x = cvtpk_h(x0[0], x0[1]); w[bj].y = cvtpk_h(x0[2], x0[3]); w[bj].z = cvtpk_h(x1[0], x1[1]); w[bj].w = cvtpk_h(x1[2], x1[3]);
;                     const f32x4 y0 = x0 * a4[bj][0], y1 = x1 * a4[bj][1]; v[bj].x = cvtpk_h(y0[0], y0[1]); v[bj].y = cvtpk_h(y0[2], y0[3]); v[bj].z = cvtpk_h(y1[0], y1[1]); v[bj].w = cvtpk_h(y1[2], y1[3]); }
;                 stg_line_pair(ws, (unsigned)WS_X16 + o, D * 2u, w[0], w[1], odd);
;                 if (an_off) stg_line_pair(ws, (unsigned)WS_XS + o, D * 2u, v[0], v[1], odd);
;                 ss = red4(ss, fq * 16 + fr); if (fq == 0) stg_f1(ws, rqo + rr * 4u, ss);
.LBB0_489:
	v_mul_f32_e32 v47, v47, v47
	v_mul_f32_e32 v43, v43, v43
	v_mul_f32_e32 v39, v39, v39
	v_mul_f32_e32 v35, v35, v35
	v_fmac_f32_e32 v47, v46, v46
	v_mul_f32_e32 v46, v49, v49
	v_fmac_f32_e32 v43, v42, v42
	v_mul_f32_e32 v42, v45, v45
	v_fmac_f32_e32 v39, v38, v38
	v_mul_f32_e32 v38, v41, v41
	v_fmac_f32_e32 v35, v34, v34
	v_mul_f32_e32 v34, v37, v37
	v_fmac_f32_e32 v46, v48, v48
	v_fmac_f32_e32 v42, v44, v44
	v_fmac_f32_e32 v38, v40, v40
	v_fmac_f32_e32 v34, v36, v36
	v_add_f32_e32 v46, v47, v46
	v_add_f32_e32 v42, v43, v42
	v_add_f32_e32 v38, v39, v38
	v_add_f32_e32 v34, v35, v34
	v_add_f32_e32 v42, v46, v42
	v_add_f32_e32 v34, v38, v34
	v_add_f32_e32 v34, v34, v42
	v_mov_b32_e32 v35, v34
	s_nop 1
	v_permlane16_swap_b32_e32 v34, v35
	v_add_f32_e32 v34, v34, v35
	v_mov_b32_e32 v35, v34
	s_nop 1
	v_permlane32_swap_b32_e32 v34, v35
	s_and_saveexec_b64 s[44:45], s[4:5]
	s_cbranch_execz .LBB0_491
	v_add_f32_e32 v34, v34, v35
	v_mov_b32_e32 v35, 0x2880280
	v_lshl_add_u32 v35, v148, 2, v35
	global_store_dword v35, v34, s[38:39] sc1

; #define GAS __attribute__((address_space(1)))
; __device__ __forceinline__ unsigned cvtpk_h(float lo, float hi) { f32x2 v = {lo, hi}; h16x2 b = __builtin_convertvector(v, h16x2); return __builtin_bit_cast(unsigned, b); }
;     __device__ __forceinline__ void operator()(const f32x4 (&acc)[2][2][4][2], const pg8::Unit& u, int wr, int wc, int fr, int fq) const {
;     ...
;             for (int m = 0; m < 4; ++m) { if (half && ai == 1) continue; const unsigned rr = (unsigned)(ai * 128 + m * 16); const unsigned o = eoA + rr * (D * 2u); float ss = 0.f;
;                 const u32x4 la = *(const GAS u32x4*)((const GAS char*)ws + (unsigned)WS_X16 + o), lb = *(const GAS u32x4*)((const GAS char*)ws + (unsigned)WS_X16 + o + D * 2u);
;                 u32x4 xr[2];
; #pragma unroll
;                 for (int c = 0; c < 4; ++c) { const unsigned pa = (unsigned)__builtin_amdgcn_update_dpp(0, (int)la[c], 0xB1, 0xF, 0xF, false), pb = (unsigned)__builtin_amdgcn_update_dpp(0, (int)lb[c], 0xB1, 0xF, 0xF, false);
;                     xr[0][c] = odd ? pb : la[c]; xr[1][c] = odd ? lb[c] : pa; }
;                 u32x4 w[2], v[2];
; #pragma unroll
;                 for (int bj = 0; bj < 2; ++bj) { const h16x8 xb = __builtin_bit_cast(h16x8, xr[bj]);
;                     const f32x4 x0 = (f32x4){(float)xb[0], (float)xb[1], (float)xb[2], (float)xb[3]} + g4[bj][0] * acc[ai][bj][m][0], x1 = (f32x4){(float)xb[4], (float)xb[5], (float)xb[6], (float)xb[7]} + g4[bj][1] * acc[ai][bj][m][1];
;                     ss += ((x0[0] * x0[0] + x0[1] * x0[1]) + (x0[2] * x0[2] + x0[3] * x0[3])) + ((x1[0] * x1[0] + x1[1] * x1[1]) + (x1[2] * x1[2] + x1[3] * x1[3]));
;                     w[bj].x = cvtpk_h(x0[0], x0[1]); w[bj].y = cvtpk_h(x0[2], x0[3]); w[bj].z = cvtpk_h(x1[0], x1[1]); w[bj].w = cvtpk_h(x1[2], x1[3]);
;                     const f32x4 y0 = x0 * a4[bj][0], y1 = x1 * a4[bj][1]; v[bj].x = cvtpk_h(y0[0], y0[1]); v[bj].y = cvtpk_h(y0[2], y0[3]); v[bj].z = cvtpk_h(y1[0], y1[1]); v[bj].w = cvtpk_h(y1[2], y1[3]); }
;                 stg_line_pair(ws, (unsigned)WS_X16 + o, D * 2u, w[0], w[1], odd);
;                 if (an_off) stg_line_pair(ws, (unsigned)WS_XS + o, D * 2u, v[0], v[1], odd);
;                 ss = red4(ss, fq * 16 + fr); if (fq == 0) stg_f1(ws, rqo + rr * 4u, ss);
.Lo_wd_7:
	v_mov_b32_e32 v34, v214
	v_mov_b32_e32 v35, v215
	v_mov_b32_e32 v36, v216
	v_mov_b32_e32 v37, v217
	v_mov_b32_e32 v38, v218
	v_mov_b32_e32 v39, v219
	v_mov_b32_e32 v40, v220
	v_mov_b32_e32 v41, v221
	v_mov_b32_e32 v42, v1
	v_mov_b32_e32 v43, v1
	v_add_u32_e32 v46, 0x16fd8000, v0
	s_and_b64 vcc, exec, s[2:3]
	v_mov_b32_dpp v42, v34 quad_perm:[1,0,3,2] row_mask:0xf bank_mask:0xf
	v_mov_b32_dpp v43, v38 quad_perm:[1,0,3,2] row_mask:0xf bank_mask:0xf
	v_cndmask_b32_e64 v43, v43, v34, s[0:1]
	v_cndmask_b32_e64 v38, v38, v42, s[0:1]
	v_mov_b32_e32 v34, v1
	v_mov_b32_e32 v42, v1
	s_nop 0
	v_mov_b32_dpp v34, v35 quad_perm:[1,0,3,2] row_mask:0xf bank_mask:0xf
	v_mov_b32_dpp v42, v39 quad_perm:[1,0,3,2] row_mask:0xf bank_mask:0xf
	v_cndmask_b32_e64 v42, v42, v35, s[0:1]
	v_cndmask_b32_e64 v39, v39, v34, s[0:1]
	v_mov_b32_e32 v34, v1
	v_mov_b32_e32 v35, v1
	s_nop 0
	v_mov_b32_dpp v34, v36 quad_perm:[1,0,3,2] row_mask:0xf bank_mask:0xf
	v_mov_b32_dpp v35, v40 quad_perm:[1,0,3,2] row_mask:0xf bank_mask:0xf
	v_cndmask_b32_e64 v44, v35, v36, s[0:1]
	v_cndmask_b32_e64 v40, v40, v34, s[0:1]
	v_mov_b32_e32 v34, v1
	v_mov_b32_e32 v35, v1
	v_cvt_f32_f16_e32 v36, v42
	v_mov_b32_dpp v34, v37 quad_perm:[1,0,3,2] row_mask:0xf bank_mask:0xf
	v_mov_b32_dpp v35, v41 quad_perm:[1,0,3,2] row_mask:0xf bank_mask:0xf
	v_cndmask_b32_e64 v45, v35, v37, s[0:1]
	v_cndmask_b32_e64 v41, v41, v34, s[0:1]
	v_cvt_f32_f16_e32 v34, v43
	v_cvt_f32_f16_sdwa v35, v43 dst_sel:DWORD dst_unused:UNUSED_PAD src0_sel:WORD_1
	v_cvt_f32_f16_sdwa v37, v42 dst_sel:DWORD dst_unused:UNUSED_PAD src0_sel:WORD_1
	v_pk_fma_f32 v[14:15], v[14:15], v[50:51], v[34:35]
	v_cvt_f32_f16_e32 v34, v44
	v_cvt_f32_f16_sdwa v35, v44 dst_sel:DWORD dst_unused:UNUSED_PAD src0_sel:WORD_1
	v_pk_fma_f32 v[16:17], v[16:17], v[52:53], v[36:37]
	v_cvt_f32_f16_e32 v36, v45
	v_cvt_f32_f16_sdwa v37, v45 dst_sel:DWORD dst_unused:UNUSED_PAD src0_sel:WORD_1
	v_pk_fma_f32 v[10:11], v[10:11], v[54:55], v[34:35]
	v_cvt_f32_f16_e32 v34, v38
	v_cvt_f32_f16_sdwa v35, v38 dst_sel:DWORD dst_unused:UNUSED_PAD src0_sel:WORD_1
	v_pk_fma_f32 v[12:13], v[12:13], v[56:57], v[36:37]
	v_cvt_f32_f16_e32 v36, v39
	v_cvt_f32_f16_sdwa v37, v39 dst_sel:DWORD dst_unused:UNUSED_PAD src0_sel:WORD_1
	v_pk_fma_f32 v[6:7], v[6:7], v[58:59], v[34:35]
	v_cvt_f32_f16_e32 v34, v40
	v_cvt_f32_f16_sdwa v35, v40 dst_sel:DWORD dst_unused:UNUSED_PAD src0_sel:WORD_1
	v_pk_fma_f32 v[8:9], v[8:9], v[60:61], v[36:37]
	v_cvt_f32_f16_e32 v36, v41
	v_cvt_f32_f16_sdwa v37, v41 dst_sel:DWORD dst_unused:UNUSED_PAD src0_sel:WORD_1
	v_cvt_pk_f16_f32 v42, v14, v15
	v_mov_b32_e32 v38, v1
	v_cvt_pk_f16_f32 v43, v16, v17
	v_pk_fma_f32 v[2:3], v[2:3], v[62:63], v[34:35]
	v_cvt_pk_f16_f32 v35, v6, v7
	v_mov_b32_e32 v34, v1
	v_mov_b32_dpp v38, v42 quad_perm:[1,0,3,2] row_mask:0xf bank_mask:0xf
	v_mov_b32_e32 v39, v1
	v_cvt_pk_f16_f32 v44, v10, v11
	v_pk_fma_f32 v[4:5], v[4:5], v[64:65], v[36:37]
	v_cvt_pk_f16_f32 v36, v8, v9
	v_mov_b32_dpp v34, v35 quad_perm:[1,0,3,2] row_mask:0xf bank_mask:0xf
	v_cndmask_b32_e64 v38, v35, v38, s[0:1]
	v_mov_b32_e32 v35, v1
	v_mov_b32_dpp v39, v43 quad_perm:[1,0,3,2] row_mask:0xf bank_mask:0xf
	v_mov_b32_e32 v40, v1
	v_cvt_pk_f16_f32 v37, v2, v3
	v_mov_b32_dpp v35, v36 quad_perm:[1,0,3,2] row_mask:0xf bank_mask:0xf
	v_cndmask_b32_e64 v39, v36, v39, s[0:1]
	v_mov_b32_e32 v36, v1
	v_mov_b32_dpp v40, v44 quad_perm:[1,0,3,2] row_mask:0xf bank_mask:0xf
	v_cvt_pk_f16_f32 v41, v4, v5
	v_mov_b32_dpp v36, v37 quad_perm:[1,0,3,2] row_mask:0xf bank_mask:0xf
	v_cndmask_b32_e64 v40, v37, v40, s[0:1]
	v_mov_b32_e32 v37, v1
	v_cvt_pk_f16_f32 v45, v12, v13
	v_cndmask_b32_e64 v34, v34, v42, s[0:1]
	v_mov_b32_dpp v37, v41 quad_perm:[1,0,3,2] row_mask:0xf bank_mask:0xf
	v_mov_b32_e32 v42, v1
	v_cndmask_b32_e64 v35, v35, v43, s[0:1]
	v_cndmask_b32_e64 v36, v36, v44, s[0:1]
	v_mov_b32_dpp v42, v45 quad_perm:[1,0,3,2] row_mask:0xf bank_mask:0xf
	v_cndmask_b32_e64 v37, v37, v45, s[0:1]
	v_cndmask_b32_e64 v41, v41, v42, s[0:1]
	global_store_dwordx4 v46, v[34:37], s[38:39] sc1
	s_nop 1
	v_add_u32_e32 v34, 0x16fd8800, v0
	global_store_dwordx4 v34, v[38:41], s[38:39] sc1
	s_cbranch_vccnz .LBB0_493
	v_pk_mul_f32 v[26:27], v[26:27], v[6:7]
	v_pk_mul_f32 v[20:21], v[20:21], v[16:17]
	v_pk_mul_f32 v[18:19], v[18:19], v[14:15]
	v_cvt_pk_f16_f32 v26, v26, v27
	v_cvt_pk_f16_f32 v20, v20, v21
	v_cvt_pk_f16_f32 v18, v18, v19
	v_mov_b32_e32 v19, v1
	v_mov_b32_e32 v21, v1
	v_pk_mul_f32 v[28:29], v[28:29], v[8:9]
	v_pk_mul_f32 v[24:25], v[24:25], v[12:13]
	v_pk_mul_f32 v[22:23], v[22:23], v[10:11]
	v_mov_b32_dpp v19, v26 quad_perm:[1,0,3,2] row_mask:0xf bank_mask:0xf
	v_mov_b32_dpp v21, v18 quad_perm:[1,0,3,2] row_mask:0xf bank_mask:0xf
	v_cvt_pk_f16_f32 v28, v28, v29
	v_cvt_pk_f16_f32 v25, v24, v25
	v_cvt_pk_f16_f32 v24, v22, v23
	v_cndmask_b32_e64 v18, v19, v18, s[0:1]
	v_cndmask_b32_e64 v22, v26, v21, s[0:1]
	v_mov_b32_e32 v19, v1
	v_mov_b32_e32 v21, v1
	v_pk_mul_f32 v[30:31], v[30:31], v[2:3]
	v_mov_b32_dpp v19, v28 quad_perm:[1,0,3,2] row_mask:0xf bank_mask:0xf
	v_mov_b32_dpp v21, v20 quad_perm:[1,0,3,2] row_mask:0xf bank_mask:0xf
	v_cvt_pk_f16_f32 v30, v30, v31
	v_cndmask_b32_e64 v19, v19, v20, s[0:1]
	v_cndmask_b32_e64 v23, v28, v21, s[0:1]
	v_mov_b32_e32 v20, v1
	v_mov_b32_e32 v21, v1
	v_pk_mul_f32 v[32:33], v[32:33], v[4:5]
	v_mov_b32_dpp v20, v30 quad_perm:[1,0,3,2] row_mask:0xf bank_mask:0xf
	v_mov_b32_dpp v21, v24 quad_perm:[1,0,3,2] row_mask:0xf bank_mask:0xf
	v_cvt_pk_f16_f32 v32, v32, v33
	v_cndmask_b32_e64 v20, v20, v24, s[0:1]
	v_cndmask_b32_e64 v24, v30, v21, s[0:1]
	v_mov_b32_e32 v21, v1
	v_mov_b32_e32 v26, v1
	v_add_u32_e32 v27, 0x3dd8000, v0
	v_mov_b32_dpp v21, v32 quad_perm:[1,0,3,2] row_mask:0xf bank_mask:0xf
	v_mov_b32_dpp v26, v25 quad_perm:[1,0,3,2] row_mask:0xf bank_mask:0xf
	v_cndmask_b32_e64 v21, v21, v25, s[0:1]
	v_cndmask_b32_e64 v25, v32, v26, s[0:1]
	v_add_u32_e32 v0, 0x3dd8800, v0
	global_store_dwordx4 v27, v[18:21], s[38:39] sc1
	global_store_dwordx4 v0, v[22:25], s[38:39] sc1
.LBB0_493:
	v_mul_f32_e32 v0, v15, v15
	v_mul_f32_e32 v11, v11, v11
	v_mul_f32_e32 v7, v7, v7
	v_mul_f32_e32 v3, v3, v3
	v_fmac_f32_e32 v0, v14, v14
	v_mul_f32_e32 v14, v17, v17
	v_fmac_f32_e32 v11, v10, v10
	v_mul_f32_e32 v10, v13, v13
	v_fmac_f32_e32 v7, v6, v6
	v_mul_f32_e32 v6, v9, v9
	v_fmac_f32_e32 v3, v2, v2
	v_mul_f32_e32 v2, v5, v5
	v_fmac_f32_e32 v14, v16, v16
	v_fmac_f32_e32 v10, v12, v12
	v_fmac_f32_e32 v6, v8, v8
	v_fmac_f32_e32 v2, v4, v4
	v_add_f32_e32 v0, v0, v14
	v_add_f32_e32 v10, v11, v10
	v_add_f32_e32 v6, v7, v6
	v_add_f32_e32 v2, v3, v2
	v_add_f32_e32 v0, v0, v10
	v_add_f32_e32 v2, v6, v2
	v_add_f32_e32 v0, v2, v0
	v_mov_b32_e32 v2, v0
	s_nop 1
	v_permlane16_swap_b32_e32 v0, v2
	v_add_f32_e32 v0, v0, v2
	v_mov_b32_e32 v2, v0
	s_nop 1
	v_permlane32_swap_b32_e32 v0, v2
	s_and_saveexec_b64 s[0:1], s[4:5]
	s_cbranch_execz .LBB0_495
	v_add_f32_e32 v0, v0, v2
	v_mov_b32_e32 v2, 0x28802c0
	v_lshl_add_u32 v2, v148, 2, v2
	global_store_dword v2, v0, s[38:39] sc1

; #define GAS __attribute__((address_space(1)))
;     __device__ __forceinline__ void operator()(const f32x4 (&acc)[2][2][4][2], const pg8::Unit& u, int wr, int wc, int fr, int fq) const {
;     ...
;         const unsigned eoA = (((unsigned)u.pm * 256u + hmo + (unsigned)(wr * 64 + (fr & ~1))) * D + u.pn * 256 + wc * 64) * 2u + (odd ? 64u : 0u) + 16u * fq;
; #pragma unroll
;         for (int ai = 0; ai < 2; ++ai)
; #pragma unroll
;             for (int m = 0; m < 4; ++m) { if (half && ai == 1) continue; const unsigned rr = (unsigned)(ai * 128 + m * 16); const unsigned o = eoA + rr * (D * 2u); float ss = 0.f;
;                 const u32x4 la = *(const GAS u32x4*)((const GAS char*)ws + (unsigned)WS_X16 + o), lb = *(const GAS u32x4*)((const GAS char*)ws + (unsigned)WS_X16 + o + D * 2u);
;                 u32x4 xr[2];
; #pragma unroll
;                 for (int c = 0; c < 4; ++c) { const unsigned pa = (unsigned)__builtin_amdgcn_update_dpp(0, (int)la[c], 0xB1, 0xF, 0xF, false), pb = (unsigned)__builtin_amdgcn_update_dpp(0, (int)lb[c], 0xB1, 0xF, 0xF, false);
;                     xr[0][c] = odd ? pb : la[c]; xr[1][c] = odd ? lb[c] : pa; }
;                 u32x4 w[2], v[2];
; #pragma unroll
;                 for (int bj = 0; bj < 2; ++bj) { const h16x8 xb = __builtin_bit_cast(h16x8, xr[bj]);
;                     const f32x4 x0 = (f32x4){(float)xb[0], (float)xb[1], (float)xb[2], (float)xb[3]} + g4[bj][0] * acc[ai][bj][m][0], x1 = (f32x4){(float)xb[4], (float)xb[5], (float)xb[6], (float)xb[7]} + g4[bj][1] * acc[ai][bj][m][1];
;                     ss += ((x0[0] * x0[0] + x0[1] * x0[1]) + (x0[2] * x0[2] + x0[3] * x0[3])) + ((x1[0] * x1[0] + x1[1] * x1[1]) + (x1[2] * x1[2] + x1[3] * x1[3]));
;                     w[bj].x = cvtpk_h(x0[0], x0[1]); w[bj].y = cvtpk_h(x0[2], x0[3]); w[bj].z = cvtpk_h(x1[0], x1[1]); w[bj].w = cvtpk_h(x1[2], x1[3]);
;                     const f32x4 y0 = x0 * a4[bj][0], y1 = x1 * a4[bj][1]; v[bj].x = cvtpk_h(y0[0], y0[1]); v[bj].y = cvtpk_h(y0[2], y0[3]); v[bj].z = cvtpk_h(y1[0], y1[1]); v[bj].w = cvtpk_h(y1[2], y1[3]); }
;                 stg_line_pair(ws, (unsigned)WS_X16 + o, D * 2u, w[0], w[1], odd);
;                 if (an_off) stg_line_pair(ws, (unsigned)WS_XS + o, D * 2u, v[0], v[1], odd);
.LBB0_515:
	s_lshl_b32 s8, s14, 7
	s_lshl_b32 s0, s0, 8
	s_add_i32 s10, s1, s8
	v_and_b32_e32 v0, 0x1ffffe, v131
	s_add_i32 s10, s10, s0
	v_add_u32_e32 v0, s10, v0
	v_lshl_add_u32 v0, v0, 10, s12
	v_and_b32_e32 v106, 1, v131
	v_or_b32_e32 v0, s11, v0
	v_lshlrev_b32_e32 v0, 1, v0
	v_lshlrev_b32_e32 v98, 6, v106
	v_lshlrev_b32_e32 v99, 4, v180
	s_add_u32 s8, s6, 0x16f80000
	v_add3_u32 v0, v98, v99, v0
	s_addc_u32 s9, s7, 0
	global_load_dwordx4 v[98:101], v0, s[8:9]
	global_load_dwordx4 v[102:105], v0, s[8:9] offset:2048
	v_mov_b32_e32 v107, v1
	v_mov_b32_e32 v108, v1
	v_mov_b32_e32 v109, v1
	v_mov_b32_e32 v111, v1
	v_mov_b32_e32 v113, v1
	v_mov_b32_e32 v114, v1
	v_mov_b32_e32 v110, v1
	v_mov_b32_e32 v112, v1
	v_cmp_eq_u32_e64 s[0:1], 0, v106
	v_mov_b32_e32 v115, v1
	v_mov_b32_e32 v117, v1
	v_mov_b32_e32 v119, v1
	v_mov_b32_e32 v121, v1
	v_mov_b32_e32 v116, v1
	v_mov_b32_e32 v118, v1
	v_mov_b32_e32 v120, v1
	v_mov_b32_e32 v122, v1
	v_add_u32_e32 v123, 0x16f80000, v0
	s_and_b64 vcc, exec, s[2:3]
	s_waitcnt vmcnt(0)
	v_mov_b32_dpp v107, v98 quad_perm:[1,0,3,2] row_mask:0xf bank_mask:0xf
	v_mov_b32_dpp v108, v102 quad_perm:[1,0,3,2] row_mask:0xf bank_mask:0xf
	v_mov_b32_dpp v109, v99 quad_perm:[1,0,3,2] row_mask:0xf bank_mask:0xf
	v_mov_b32_dpp v111, v100 quad_perm:[1,0,3,2] row_mask:0xf bank_mask:0xf
	v_mov_b32_dpp v113, v101 quad_perm:[1,0,3,2] row_mask:0xf bank_mask:0xf
	v_mov_b32_dpp v114, v105 quad_perm:[1,0,3,2] row_mask:0xf bank_mask:0xf
	v_mov_b32_dpp v110, v103 quad_perm:[1,0,3,2] row_mask:0xf bank_mask:0xf
	v_mov_b32_dpp v112, v104 quad_perm:[1,0,3,2] row_mask:0xf bank_mask:0xf
	v_cndmask_b32_e64 v106, v108, v98, s[0:1]
	v_cndmask_b32_e64 v107, v102, v107, s[0:1]
	v_cndmask_b32_e64 v109, v103, v109, s[0:1]
	v_cndmask_b32_e64 v111, v104, v111, s[0:1]
	v_cndmask_b32_e64 v108, v114, v101, s[0:1]
	v_cndmask_b32_e64 v113, v105, v113, s[0:1]
	v_cndmask_b32_e64 v102, v110, v99, s[0:1]
	v_cndmask_b32_e64 v103, v112, v100, s[0:1]
	v_cvt_f32_f16_e32 v98, v106
	v_cvt_f32_f16_sdwa v99, v106 dst_sel:DWORD dst_unused:UNUSED_PAD src0_sel:WORD_1
	v_cvt_f32_f16_e32 v104, v108
	v_cvt_f32_f16_sdwa v105, v108 dst_sel:DWORD dst_unused:UNUSED_PAD src0_sel:WORD_1
	v_cvt_f32_f16_e32 v106, v107
	v_cvt_f32_f16_sdwa v107, v107 dst_sel:DWORD dst_unused:UNUSED_PAD src0_sel:WORD_1
	v_cvt_f32_f16_e32 v108, v109
	v_cvt_f32_f16_sdwa v109, v109 dst_sel:DWORD dst_unused:UNUSED_PAD src0_sel:WORD_1
	v_cvt_f32_f16_e32 v110, v111
	v_cvt_f32_f16_sdwa v111, v111 dst_sel:DWORD dst_unused:UNUSED_PAD src0_sel:WORD_1
	v_cvt_f32_f16_e32 v112, v113
	v_cvt_f32_f16_sdwa v113, v113 dst_sel:DWORD dst_unused:UNUSED_PAD src0_sel:WORD_1
	v_cvt_f32_f16_e32 v100, v102
	v_cvt_f32_f16_sdwa v101, v102 dst_sel:DWORD dst_unused:UNUSED_PAD src0_sel:WORD_1
	v_cvt_f32_f16_e32 v102, v103
	v_cvt_f32_f16_sdwa v103, v103 dst_sel:DWORD dst_unused:UNUSED_PAD src0_sel:WORD_1
	v_pk_fma_f32 v[88:89], v[88:89], v[44:45], v[108:109]
	v_pk_fma_f32 v[86:87], v[86:87], v[42:43], v[106:107]
	v_pk_fma_f32 v[84:85], v[84:85], v[48:49], v[112:113]
	v_pk_fma_f32 v[82:83], v[82:83], v[46:47], v[110:111]
	v_pk_fma_f32 v[96:97], v[96:97], v[36:37], v[100:101]
	v_pk_fma_f32 v[94:95], v[94:95], v[34:35], v[98:99]
	v_pk_fma_f32 v[92:93], v[92:93], v[40:41], v[104:105]
	v_pk_fma_f32 v[90:91], v[90:91], v[38:39], v[102:103]
	v_cvt_pk_f16_f32 v102, v86, v87
	v_cvt_pk_f16_f32 v103, v88, v89
	v_cvt_pk_f16_f32 v104, v82, v83
	v_cvt_pk_f16_f32 v105, v84, v85
	v_cvt_pk_f16_f32 v98, v94, v95
	v_cvt_pk_f16_f32 v99, v96, v97
	v_cvt_pk_f16_f32 v100, v90, v91
	v_cvt_pk_f16_f32 v101, v92, v93
	v_mov_b32_dpp v115, v102 quad_perm:[1,0,3,2] row_mask:0xf bank_mask:0xf
	v_mov_b32_dpp v117, v103 quad_perm:[1,0,3,2] row_mask:0xf bank_mask:0xf
	v_mov_b32_dpp v119, v104 quad_perm:[1,0,3,2] row_mask:0xf bank_mask:0xf
	v_mov_b32_dpp v121, v105 quad_perm:[1,0,3,2] row_mask:0xf bank_mask:0xf
	v_mov_b32_dpp v116, v98 quad_perm:[1,0,3,2] row_mask:0xf bank_mask:0xf
	v_mov_b32_dpp v118, v99 quad_perm:[1,0,3,2] row_mask:0xf bank_mask:0xf
	v_mov_b32_dpp v120, v100 quad_perm:[1,0,3,2] row_mask:0xf bank_mask:0xf
	v_mov_b32_dpp v122, v101 quad_perm:[1,0,3,2] row_mask:0xf bank_mask:0xf
	v_cndmask_b32_e64 v98, v115, v98, s[0:1]
	v_cndmask_b32_e64 v99, v117, v99, s[0:1]
	v_cndmask_b32_e64 v100, v119, v100, s[0:1]
	v_cndmask_b32_e64 v101, v121, v101, s[0:1]
	v_cndmask_b32_e64 v102, v102, v116, s[0:1]
	v_cndmask_b32_e64 v103, v103, v118, s[0:1]
	v_cndmask_b32_e64 v104, v104, v120, s[0:1]
	v_cndmask_b32_e64 v105, v105, v122, s[0:1]
	global_store_dwordx4 v123, v[98:101], s[6:7] sc1
	s_nop 1
	v_add_u32_e32 v98, 0x16f80800, v0
	global_store_dwordx4 v98, v[102:105], s[6:7] sc1
	s_cbranch_vccnz .LBB0_517
	v_pk_mul_f32 v[98:99], v[16:17], v[84:85]
	v_pk_mul_f32 v[100:101], v[14:15], v[82:83]
	v_cvt_pk_f16_f32 v105, v98, v99
	v_cvt_pk_f16_f32 v104, v100, v101
	v_pk_mul_f32 v[98:99], v[12:13], v[88:89]
	v_pk_mul_f32 v[100:101], v[10:11], v[86:87]
	v_cvt_pk_f16_f32 v103, v98, v99
	v_cvt_pk_f16_f32 v102, v100, v101
	v_pk_mul_f32 v[98:99], v[8:9], v[92:93]
	v_pk_mul_f32 v[100:101], v[6:7], v[90:91]
	v_cvt_pk_f16_f32 v106, v98, v99
	v_cvt_pk_f16_f32 v107, v100, v101
	v_pk_mul_f32 v[98:99], v[4:5], v[96:97]
	v_pk_mul_f32 v[100:101], v[2:3], v[94:95]
	v_cvt_pk_f16_f32 v99, v98, v99
	v_cvt_pk_f16_f32 v98, v100, v101
	v_mov_b32_e32 v101, v1
	v_mov_b32_e32 v100, v1
	v_add_u32_e32 v108, 0x3d80000, v0
	v_mov_b32_dpp v101, v98 quad_perm:[1,0,3,2] row_mask:0xf bank_mask:0xf
	v_mov_b32_dpp v100, v102 quad_perm:[1,0,3,2] row_mask:0xf bank_mask:0xf
	v_cndmask_b32_e64 v102, v102, v101, s[0:1]
	v_mov_b32_e32 v101, v1
	v_cndmask_b32_e64 v98, v100, v98, s[0:1]
	v_mov_b32_e32 v100, v1
	v_mov_b32_dpp v101, v99 quad_perm:[1,0,3,2] row_mask:0xf bank_mask:0xf
	s_nop 0
	v_mov_b32_dpp v100, v103 quad_perm:[1,0,3,2] row_mask:0xf bank_mask:0xf
	v_cndmask_b32_e64 v103, v103, v101, s[0:1]
	v_mov_b32_e32 v101, v1
	v_cndmask_b32_e64 v99, v100, v99, s[0:1]
	v_mov_b32_e32 v100, v1
	v_mov_b32_dpp v101, v107 quad_perm:[1,0,3,2] row_mask:0xf bank_mask:0xf
	s_nop 0
	v_mov_b32_dpp v100, v104 quad_perm:[1,0,3,2] row_mask:0xf bank_mask:0xf
	v_cndmask_b32_e64 v104, v104, v101, s[0:1]
	v_mov_b32_e32 v101, v1
	v_cndmask_b32_e64 v100, v100, v107, s[0:1]
	v_mov_b32_e32 v107, v1
	v_mov_b32_dpp v101, v105 quad_perm:[1,0,3,2] row_mask:0xf bank_mask:0xf
	v_cndmask_b32_e64 v101, v101, v106, s[0:1]
	v_mov_b32_dpp v107, v106 quad_perm:[1,0,3,2] row_mask:0xf bank_mask:0xf
	v_cndmask_b32_e64 v105, v105, v107, s[0:1]
	global_store_dwordx4 v108, v[98:101], s[6:7] sc1
	s_nop 1
	v_add_u32_e32 v98, 0x3d80800, v0
	global_store_dwordx4 v98, v[102:105], s[6:7] sc1
; #define GAS __attribute__((address_space(1)))
; __device__ __forceinline__ unsigned cvtpk_h(float lo, float hi) { f32x2 v = {lo, hi}; h16x2 b = __builtin_convertvector(v, h16x2); return __builtin_bit_cast(unsigned, b); }
;     __device__ __forceinline__ void operator()(const f32x4 (&acc)[2][2][4][2], const pg8::Unit& u, int wr, int wc, int fr, int fq) const {
;     ...
;             for (int m = 0; m < 4; ++m) { if (half && ai == 1) continue; const unsigned rr = (unsigned)(ai * 128 + m * 16); const unsigned o = eoA + rr * (D * 2u); float ss = 0.f;
;                 const u32x4 la = *(const GAS u32x4*)((const GAS char*)ws + (unsigned)WS_X16 + o), lb = *(const GAS u32x4*)((const GAS char*)ws + (unsigned)WS_X16 + o + D * 2u);
;                 u32x4 xr[2];
; #pragma unroll
;                 for (int c = 0; c < 4; ++c) { const unsigned pa = (unsigned)__builtin_amdgcn_update_dpp(0, (int)la[c], 0xB1, 0xF, 0xF, false), pb = (unsigned)__builtin_amdgcn_update_dpp(0, (int)lb[c], 0xB1, 0xF, 0xF, false);
;                     xr[0][c] = odd ? pb : la[c]; xr[1][c] = odd ? lb[c] : pa; }
;                 u32x4 w[2], v[2];
; #pragma unroll
;                 for (int bj = 0; bj < 2; ++bj) { const h16x8 xb = __builtin_bit_cast(h16x8, xr[bj]);
;                     const f32x4 x0 = (f32x4){(float)xb[0], (float)xb[1], (float)xb[2], (float)xb[3]} + g4[bj][0] * acc[ai][bj][m][0], x1 = (f32x4){(float)xb[4], (float)xb[5], (float)xb[6], (float)xb[7]} + g4[bj][1] * acc[ai][bj][m][1];
;                     ss += ((x0[0] * x0[0] + x0[1] * x0[1]) + (x0[2] * x0[2] + x0[3] * x0[3])) + ((x1[0] * x1[0] + x1[1] * x1[1]) + (x1[2] * x1[2] + x1[3] * x1[3]));
;                     w[bj].x = cvtpk_h(x0[0], x0[1]); w[bj].y = cvtpk_h(x0[2], x0[3]); w[bj].z = cvtpk_h(x1[0], x1[1]); w[bj].w = cvtpk_h(x1[2], x1[3]);
;                     const f32x4 y0 = x0 * a4[bj][0], y1 = x1 * a4[bj][1]; v[bj].x = cvtpk_h(y0[0], y0[1]); v[bj].y = cvtpk_h(y0[2], y0[3]); v[bj].z = cvtpk_h(y1[0], y1[1]); v[bj].w = cvtpk_h(y1[2], y1[3]); }
;                 stg_line_pair(ws, (unsigned)WS_X16 + o, D * 2u, w[0], w[1], odd);
;                 if (an_off) stg_line_pair(ws, (unsigned)WS_XS + o, D * 2u, v[0], v[1], odd);
;                 ss = red4(ss, fq * 16 + fr); if (fq == 0) stg_f1(ws, rqo + rr * 4u, ss);
.LBB0_517:
	v_mul_f32_e32 v95, v95, v95
	v_mul_f32_e32 v91, v91, v91
	v_mul_f32_e32 v87, v87, v87
	v_mul_f32_e32 v83, v83, v83
	v_fmac_f32_e32 v95, v94, v94
	v_mul_f32_e32 v94, v97, v97
	v_fmac_f32_e32 v91, v90, v90
	v_mul_f32_e32 v90, v93, v93
	v_fmac_f32_e32 v87, v86, v86
	v_mul_f32_e32 v86, v89, v89
	v_fmac_f32_e32 v83, v82, v82
	v_mul_f32_e32 v82, v85, v85
	v_fmac_f32_e32 v94, v96, v96
	v_fmac_f32_e32 v90, v92, v92
	v_fmac_f32_e32 v86, v88, v88
	v_fmac_f32_e32 v82, v84, v84
	v_add_f32_e32 v94, v95, v94
	v_add_f32_e32 v90, v91, v90
	v_add_f32_e32 v86, v87, v86
	v_add_f32_e32 v82, v83, v82
	v_add_f32_e32 v90, v94, v90
	v_add_f32_e32 v82, v86, v82
	v_add_f32_e32 v82, v82, v90
	s_lshl_b32 s4, s4, 2
	v_mov_b32_e32 v83, v82
	s_or_b32 s4, s4, s5
	s_nop 0
	v_permlane16_swap_b32_e32 v82, v83
	s_mul_i32 s11, s4, 0x9000
	v_add_f32_e32 v82, v82, v83
	s_add_i32 s10, s10, s11
	v_mov_b32_e32 v83, v82
	v_cmp_eq_u32_e64 s[4:5], 0, v180
	v_add_u32_e32 v98, s10, v131
	v_permlane32_swap_b32_e32 v82, v83
	s_and_saveexec_b64 s[10:11], s[4:5]
	s_cbranch_execz .LBB0_519
	v_add_f32_e32 v82, v82, v83
	v_lshl_add_u32 v83, v98, 2, v247
	global_store_dword v83, v82, s[6:7] sc1
.LBB0_519:
	s_or_b64 exec, exec, s[10:11]
	v_add_u32_e32 v86, 0x8000, v0
	global_load_dwordx4 v[82:85], v86, s[8:9]
	s_nop 0
	global_load_dwordx4 v[86:89], v86, s[8:9] offset:2048
	v_mov_b32_e32 v90, v1
	v_mov_b32_e32 v91, v1
	v_add_u32_e32 v94, 0x16f88000, v0
	s_and_b64 vcc, exec, s[2:3]
	s_waitcnt vmcnt(0)
	v_mov_b32_dpp v90, v82 quad_perm:[1,0,3,2] row_mask:0xf bank_mask:0xf
	v_mov_b32_dpp v91, v86 quad_perm:[1,0,3,2] row_mask:0xf bank_mask:0xf
	v_cndmask_b32_e64 v91, v91, v82, s[0:1]
	v_cndmask_b32_e64 v86, v86, v90, s[0:1]
	v_mov_b32_e32 v82, v1
	v_mov_b32_e32 v90, v1
	s_nop 0
	v_mov_b32_dpp v82, v83 quad_perm:[1,0,3,2] row_mask:0xf bank_mask:0xf
	v_mov_b32_dpp v90, v87 quad_perm:[1,0,3,2] row_mask:0xf bank_mask:0xf
	v_cndmask_b32_e64 v90, v90, v83, s[0:1]
	v_cndmask_b32_e64 v87, v87, v82, s[0:1]
	v_mov_b32_e32 v82, v1
	v_mov_b32_e32 v83, v1
	s_nop 0
	v_mov_b32_dpp v82, v84 quad_perm:[1,0,3,2] row_mask:0xf bank_mask:0xf
	v_mov_b32_dpp v83, v88 quad_perm:[1,0,3,2] row_mask:0xf bank_mask:0xf
	v_cndmask_b32_e64 v92, v83, v84, s[0:1]
	v_cndmask_b32_e64 v88, v88, v82, s[0:1]
	v_mov_b32_e32 v82, v1
	v_mov_b32_e32 v83, v1
	v_cvt_f32_f16_e32 v84, v90
	v_mov_b32_dpp v82, v85 quad_perm:[1,0,3,2] row_mask:0xf bank_mask:0xf
	v_mov_b32_dpp v83, v89 quad_perm:[1,0,3,2] row_mask:0xf bank_mask:0xf
	v_cndmask_b32_e64 v93, v83, v85, s[0:1]
	v_cndmask_b32_e64 v89, v89, v82, s[0:1]
	v_cvt_f32_f16_e32 v82, v91
	v_cvt_f32_f16_sdwa v83, v91 dst_sel:DWORD dst_unused:UNUSED_PAD src0_sel:WORD_1
	v_cvt_f32_f16_sdwa v85, v90 dst_sel:DWORD dst_unused:UNUSED_PAD src0_sel:WORD_1
	v_pk_fma_f32 v[78:79], v[78:79], v[34:35], v[82:83]
	v_cvt_f32_f16_e32 v82, v92
	v_cvt_f32_f16_sdwa v83, v92 dst_sel:DWORD dst_unused:UNUSED_PAD src0_sel:WORD_1
	v_pk_fma_f32 v[80:81], v[80:81], v[36:37], v[84:85]
	v_cvt_f32_f16_e32 v84, v93
	v_cvt_f32_f16_sdwa v85, v93 dst_sel:DWORD dst_unused:UNUSED_PAD src0_sel:WORD_1
	v_pk_fma_f32 v[74:75], v[74:75], v[38:39], v[82:83]
	v_cvt_f32_f16_e32 v82, v86
	v_cvt_f32_f16_sdwa v83, v86 dst_sel:DWORD dst_unused:UNUSED_PAD src0_sel:WORD_1
	v_pk_fma_f32 v[76:77], v[76:77], v[40:41], v[84:85]
	v_cvt_f32_f16_e32 v84, v87
	v_cvt_f32_f16_sdwa v85, v87 dst_sel:DWORD dst_unused:UNUSED_PAD src0_sel:WORD_1
	v_pk_fma_f32 v[70:71], v[70:71], v[42:43], v[82:83]
	v_cvt_f32_f16_e32 v82, v88
	v_cvt_f32_f16_sdwa v83, v88 dst_sel:DWORD dst_unused:UNUSED_PAD src0_sel:WORD_1
	v_pk_fma_f32 v[72:73], v[72:73], v[44:45], v[84:85]
	v_cvt_f32_f16_e32 v84, v89
	v_cvt_f32_f16_sdwa v85, v89 dst_sel:DWORD dst_unused:UNUSED_PAD src0_sel:WORD_1
	v_cvt_pk_f16_f32 v90, v78, v79
	v_mov_b32_e32 v86, v1
	v_cvt_pk_f16_f32 v91, v80, v81
	v_pk_fma_f32 v[66:67], v[66:67], v[46:47], v[82:83]
	v_cvt_pk_f16_f32 v83, v70, v71
	v_mov_b32_e32 v82, v1
	v_mov_b32_dpp v86, v90 quad_perm:[1,0,3,2] row_mask:0xf bank_mask:0xf
	v_mov_b32_e32 v87, v1
	v_cvt_pk_f16_f32 v92, v74, v75
	v_pk_fma_f32 v[68:69], v[68:69], v[48:49], v[84:85]
	v_cvt_pk_f16_f32 v84, v72, v73
	v_mov_b32_dpp v82, v83 quad_perm:[1,0,3,2] row_mask:0xf bank_mask:0xf
	v_cndmask_b32_e64 v86, v83, v86, s[0:1]
	v_mov_b32_e32 v83, v1
	v_mov_b32_dpp v87, v91 quad_perm:[1,0,3,2] row_mask:0xf bank_mask:0xf
	v_mov_b32_e32 v88, v1
	v_cvt_pk_f16_f32 v85, v66, v67
	v_mov_b32_dpp v83, v84 quad_perm:[1,0,3,2] row_mask:0xf bank_mask:0xf
	v_cndmask_b32_e64 v87, v84, v87, s[0:1]
	v_mov_b32_e32 v84, v1
	v_mov_b32_dpp v88, v92 quad_perm:[1,0,3,2] row_mask:0xf bank_mask:0xf
	v_cvt_pk_f16_f32 v89, v68, v69
	v_mov_b32_dpp v84, v85 quad_perm:[1,0,3,2] row_mask:0xf bank_mask:0xf
	v_cndmask_b32_e64 v88, v85, v88, s[0:1]
	v_mov_b32_e32 v85, v1
	v_cvt_pk_f16_f32 v93, v76, v77
	v_cndmask_b32_e64 v82, v82, v90, s[0:1]
	v_mov_b32_dpp v85, v89 quad_perm:[1,0,3,2] row_mask:0xf bank_mask:0xf
	v_mov_b32_e32 v90, v1
	v_cndmask_b32_e64 v83, v83, v91, s[0:1]
	v_cndmask_b32_e64 v84, v84, v92, s[0:1]
	v_mov_b32_dpp v90, v93 quad_perm:[1,0,3,2] row_mask:0xf bank_mask:0xf
	v_cndmask_b32_e64 v85, v85, v93, s[0:1]
	v_cndmask_b32_e64 v89, v89, v90, s[0:1]
	global_store_dwordx4 v94, v[82:85], s[6:7] sc1
	s_nop 1
	v_add_u32_e32 v82, 0x16f88800, v0
	global_store_dwordx4 v82, v[86:89], s[6:7] sc1
	s_cbranch_vccnz .LBB0_521
; #define GAS __attribute__((address_space(1)))
; __device__ __forceinline__ unsigned cvtpk_h(float lo, float hi) { f32x2 v = {lo, hi}; h16x2 b = __builtin_convertvector(v, h16x2); return __builtin_bit_cast(unsigned, b); }
;     __device__ __forceinline__ void operator()(const f32x4 (&acc)[2][2][4][2], const pg8::Unit& u, int wr, int wc, int fr, int fq) const {
;     ...
;             for (int m = 0; m < 4; ++m) { if (half && ai == 1) continue; const unsigned rr = (unsigned)(ai * 128 + m * 16); const unsigned o = eoA + rr * (D * 2u); float ss = 0.f;
;                 const u32x4 la = *(const GAS u32x4*)((const GAS char*)ws + (unsigned)WS_X16 + o), lb = *(const GAS u32x4*)((const GAS char*)ws + (unsigned)WS_X16 + o + D * 2u);
;                 u32x4 xr[2];
; #pragma unroll
;                 for (int c = 0; c < 4; ++c) { const unsigned pa = (unsigned)__builtin_amdgcn_update_dpp(0, (int)la[c], 0xB1, 0xF, 0xF, false), pb = (unsigned)__builtin_amdgcn_update_dpp(0, (int)lb[c], 0xB1, 0xF, 0xF, false);
;                     xr[0][c] = odd ? pb : la[c]; xr[1][c] = odd ? lb[c] : pa; }
;                 u32x4 w[2], v[2];
; #pragma unroll
;                 for (int bj = 0; bj < 2; ++bj) { const h16x8 xb = __builtin_bit_cast(h16x8, xr[bj]);
;                     const f32x4 x0 = (f32x4){(float)xb[0], (float)xb[1], (float)xb[2], (float)xb[3]} + g4[bj][0] * acc[ai][bj][m][0], x1 = (f32x4){(float)xb[4], (float)xb[5], (float)xb[6], (float)xb[7]} + g4[bj][1] * acc[ai][bj][m][1];
;                     ss += ((x0[0] * x0[0] + x0[1] * x0[1]) + (x0[2] * x0[2] + x0[3] * x0[3])) + ((x1[0] * x1[0] + x1[1] * x1[1]) + (x1[2] * x1[2] + x1[3] * x1[3]));
;                     w[bj].x = cvtpk_h(x0[0], x0[1]); w[bj].y = cvtpk_h(x0[2], x0[3]); w[bj].z = cvtpk_h(x1[0], x1[1]); w[bj].w = cvtpk_h(x1[2], x1[3]);
;                     const f32x4 y0 = x0 * a4[bj][0], y1 = x1 * a4[bj][1]; v[bj].x = cvtpk_h(y0[0], y0[1]); v[bj].y = cvtpk_h(y0[2], y0[3]); v[bj].z = cvtpk_h(y1[0], y1[1]); v[bj].w = cvtpk_h(y1[2], y1[3]); }
;                 stg_line_pair(ws, (unsigned)WS_X16 + o, D * 2u, w[0], w[1], odd);
;                 if (an_off) stg_line_pair(ws, (unsigned)WS_XS + o, D * 2u, v[0], v[1], odd);
;                 ss = red4(ss, fq * 16 + fr); if (fq == 0) stg_f1(ws, rqo + rr * 4u, ss);
	v_pk_mul_f32 v[82:83], v[16:17], v[68:69]
	v_pk_mul_f32 v[84:85], v[14:15], v[66:67]
	v_cvt_pk_f16_f32 v89, v82, v83
	v_cvt_pk_f16_f32 v88, v84, v85
	v_pk_mul_f32 v[82:83], v[12:13], v[72:73]
	v_pk_mul_f32 v[84:85], v[10:11], v[70:71]
	v_cvt_pk_f16_f32 v87, v82, v83
	v_cvt_pk_f16_f32 v86, v84, v85
	v_pk_mul_f32 v[82:83], v[8:9], v[76:77]
	v_pk_mul_f32 v[84:85], v[6:7], v[74:75]
	v_cvt_pk_f16_f32 v90, v82, v83
	v_cvt_pk_f16_f32 v91, v84, v85
	v_pk_mul_f32 v[82:83], v[4:5], v[80:81]
	v_pk_mul_f32 v[84:85], v[2:3], v[78:79]
	v_cvt_pk_f16_f32 v83, v82, v83
	v_cvt_pk_f16_f32 v82, v84, v85
	v_mov_b32_e32 v85, v1
	v_mov_b32_e32 v84, v1
	v_add_u32_e32 v92, 0x3d88000, v0
	v_mov_b32_dpp v85, v82 quad_perm:[1,0,3,2] row_mask:0xf bank_mask:0xf
	v_mov_b32_dpp v84, v86 quad_perm:[1,0,3,2] row_mask:0xf bank_mask:0xf
	v_cndmask_b32_e64 v86, v86, v85, s[0:1]
	v_mov_b32_e32 v85, v1
	v_cndmask_b32_e64 v82, v84, v82, s[0:1]
	v_mov_b32_e32 v84, v1
	v_mov_b32_dpp v85, v83 quad_perm:[1,0,3,2] row_mask:0xf bank_mask:0xf
	s_nop 0
	v_mov_b32_dpp v84, v87 quad_perm:[1,0,3,2] row_mask:0xf bank_mask:0xf
	v_cndmask_b32_e64 v87, v87, v85, s[0:1]
	v_mov_b32_e32 v85, v1
	v_cndmask_b32_e64 v83, v84, v83, s[0:1]
	v_mov_b32_e32 v84, v1
	v_mov_b32_dpp v85, v91 quad_perm:[1,0,3,2] row_mask:0xf bank_mask:0xf
	s_nop 0
	v_mov_b32_dpp v84, v88 quad_perm:[1,0,3,2] row_mask:0xf bank_mask:0xf
	v_cndmask_b32_e64 v88, v88, v85, s[0:1]
	v_mov_b32_e32 v85, v1
	v_cndmask_b32_e64 v84, v84, v91, s[0:1]
	v_mov_b32_e32 v91, v1
	v_mov_b32_dpp v85, v89 quad_perm:[1,0,3,2] row_mask:0xf bank_mask:0xf
	v_cndmask_b32_e64 v85, v85, v90, s[0:1]
	v_mov_b32_dpp v91, v90 quad_perm:[1,0,3,2] row_mask:0xf bank_mask:0xf
	v_cndmask_b32_e64 v89, v89, v91, s[0:1]
	global_store_dwordx4 v92, v[82:85], s[6:7] sc1
	s_nop 1
	v_add_u32_e32 v82, 0x3d88800, v0
	global_store_dwordx4 v82, v[86:89], s[6:7] sc1
.LBB0_521:
	v_mul_f32_e32 v79, v79, v79
	v_mul_f32_e32 v75, v75, v75
	v_mul_f32_e32 v71, v71, v71
	v_mul_f32_e32 v67, v67, v67
	v_fmac_f32_e32 v79, v78, v78
	v_mul_f32_e32 v78, v81, v81
	v_fmac_f32_e32 v75, v74, v74
	v_mul_f32_e32 v74, v77, v77
	v_fmac_f32_e32 v71, v70, v70
	v_mul_f32_e32 v70, v73, v73
	v_fmac_f32_e32 v67, v66, v66
	v_mul_f32_e32 v66, v69, v69
	v_fmac_f32_e32 v78, v80, v80
	v_fmac_f32_e32 v74, v76, v76
	v_fmac_f32_e32 v70, v72, v72
	v_fmac_f32_e32 v66, v68, v68
	v_add_f32_e32 v78, v79, v78
	v_add_f32_e32 v74, v75, v74
	v_add_f32_e32 v70, v71, v70
	v_add_f32_e32 v66, v67, v66
	v_add_f32_e32 v74, v78, v74
	v_add_f32_e32 v66, v70, v66
	v_add_f32_e32 v66, v66, v74
	v_mov_b32_e32 v67, v66
	s_nop 1
	v_permlane16_swap_b32_e32 v66, v67
	v_add_f32_e32 v66, v66, v67
	v_mov_b32_e32 v67, v66
	s_nop 1
	v_permlane32_swap_b32_e32 v66, v67
	s_and_saveexec_b64 s[10:11], s[4:5]
	s_cbranch_execz .LBB0_523
	v_add_f32_e32 v66, v66, v67
	v_mov_b32_e32 v67, 0x2880040
	v_lshl_add_u32 v67, v98, 2, v67
	global_store_dword v67, v66, s[6:7] sc1
.LBB0_523:
	s_or_b64 exec, exec, s[10:11]
	v_add_u32_e32 v70, 0x10000, v0
	global_load_dwordx4 v[66:69], v70, s[8:9]
	s_nop 0
	global_load_dwordx4 v[70:73], v70, s[8:9] offset:2048
	v_mov_b32_e32 v74, v1
	v_mov_b32_e32 v75, v1
	v_add_u32_e32 v78, 0x16f90000, v0
	s_and_b64 vcc, exec, s[2:3]
	s_waitcnt vmcnt(0)
	v_mov_b32_dpp v74, v66 quad_perm:[1,0,3,2] row_mask:0xf bank_mask:0xf
	v_mov_b32_dpp v75, v70 quad_perm:[1,0,3,2] row_mask:0xf bank_mask:0xf
	v_cndmask_b32_e64 v75, v75, v66, s[0:1]
	v_cndmask_b32_e64 v70, v70, v74, s[0:1]
	v_mov_b32_e32 v66, v1
	v_mov_b32_e32 v74, v1
	s_nop 0
	v_mov_b32_dpp v66, v67 quad_perm:[1,0,3,2] row_mask:0xf bank_mask:0xf
	v_mov_b32_dpp v74, v71 quad_perm:[1,0,3,2] row_mask:0xf bank_mask:0xf
	v_cndmask_b32_e64 v74, v74, v67, s[0:1]
	v_cndmask_b32_e64 v71, v71, v66, s[0:1]
	v_mov_b32_e32 v66, v1
	v_mov_b32_e32 v67, v1
	s_nop 0
	v_mov_b32_dpp v66, v68 quad_perm:[1,0,3,2] row_mask:0xf bank_mask:0xf
	v_mov_b32_dpp v67, v72 quad_perm:[1,0,3,2] row_mask:0xf bank_mask:0xf
	v_cndmask_b32_e64 v76, v67, v68, s[0:1]
	v_cndmask_b32_e64 v72, v72, v66, s[0:1]
	v_mov_b32_e32 v66, v1
	v_mov_b32_e32 v67, v1
	v_cvt_f32_f16_e32 v68, v74
	v_mov_b32_dpp v66, v69 quad_perm:[1,0,3,2] row_mask:0xf bank_mask:0xf
	v_mov_b32_dpp v67, v73 quad_perm:[1,0,3,2] row_mask:0xf bank_mask:0xf
	v_cndmask_b32_e64 v77, v67, v69, s[0:1]
	v_cndmask_b32_e64 v73, v73, v66, s[0:1]
	v_cvt_f32_f16_e32 v66, v75
	v_cvt_f32_f16_sdwa v67, v75 dst_sel:DWORD dst_unused:UNUSED_PAD src0_sel:WORD_1
	v_cvt_f32_f16_sdwa v69, v74 dst_sel:DWORD dst_unused:UNUSED_PAD src0_sel:WORD_1
	v_pk_fma_f32 v[62:63], v[62:63], v[34:35], v[66:67]
	v_cvt_f32_f16_e32 v66, v76
	v_cvt_f32_f16_sdwa v67, v76 dst_sel:DWORD dst_unused:UNUSED_PAD src0_sel:WORD_1
	v_pk_fma_f32 v[64:65], v[64:65], v[36:37], v[68:69]
	v_cvt_f32_f16_e32 v68, v77
	v_cvt_f32_f16_sdwa v69, v77 dst_sel:DWORD dst_unused:UNUSED_PAD src0_sel:WORD_1
	v_pk_fma_f32 v[58:59], v[58:59], v[38:39], v[66:67]
	v_cvt_f32_f16_e32 v66, v70
	v_cvt_f32_f16_sdwa v67, v70 dst_sel:DWORD dst_unused:UNUSED_PAD src0_sel:WORD_1
	v_pk_fma_f32 v[60:61], v[60:61], v[40:41], v[68:69]
	v_cvt_f32_f16_e32 v68, v71
	v_cvt_f32_f16_sdwa v69, v71 dst_sel:DWORD dst_unused:UNUSED_PAD src0_sel:WORD_1
	v_pk_fma_f32 v[54:55], v[54:55], v[42:43], v[66:67]
	v_cvt_f32_f16_e32 v66, v72
	v_cvt_f32_f16_sdwa v67, v72 dst_sel:DWORD dst_unused:UNUSED_PAD src0_sel:WORD_1
	v_pk_fma_f32 v[56:57], v[56:57], v[44:45], v[68:69]
	v_cvt_f32_f16_e32 v68, v73
	v_cvt_f32_f16_sdwa v69, v73 dst_sel:DWORD dst_unused:UNUSED_PAD src0_sel:WORD_1
	v_cvt_pk_f16_f32 v74, v62, v63
	v_mov_b32_e32 v70, v1
	v_cvt_pk_f16_f32 v75, v64, v65
	v_pk_fma_f32 v[50:51], v[50:51], v[46:47], v[66:67]
	v_cvt_pk_f16_f32 v67, v54, v55
; #define GAS __attribute__((address_space(1)))
; __device__ __forceinline__ unsigned cvtpk_h(float lo, float hi) { f32x2 v = {lo, hi}; h16x2 b = __builtin_convertvector(v, h16x2); return __builtin_bit_cast(unsigned, b); }
;     __device__ __forceinline__ void operator()(const f32x4 (&acc)[2][2][4][2], const pg8::Unit& u, int wr, int wc, int fr, int fq) const {
;     ...
;             for (int m = 0; m < 4; ++m) { if (half && ai == 1) continue; const unsigned rr = (unsigned)(ai * 128 + m * 16); const unsigned o = eoA + rr * (D * 2u); float ss = 0.f;
;                 const u32x4 la = *(const GAS u32x4*)((const GAS char*)ws + (unsigned)WS_X16 + o), lb = *(const GAS u32x4*)((const GAS char*)ws + (unsigned)WS_X16 + o + D * 2u);
;                 u32x4 xr[2];
; #pragma unroll
;                 for (int c = 0; c < 4; ++c) { const unsigned pa = (unsigned)__builtin_amdgcn_update_dpp(0, (int)la[c], 0xB1, 0xF, 0xF, false), pb = (unsigned)__builtin_amdgcn_update_dpp(0, (int)lb[c], 0xB1, 0xF, 0xF, false);
;                     xr[0][c] = odd ? pb : la[c]; xr[1][c] = odd ? lb[c] : pa; }
;                 u32x4 w[2], v[2];
; #pragma unroll
;                 for (int bj = 0; bj < 2; ++bj) { const h16x8 xb = __builtin_bit_cast(h16x8, xr[bj]);
;                     const f32x4 x0 = (f32x4){(float)xb[0], (float)xb[1], (float)xb[2], (float)xb[3]} + g4[bj][0] * acc[ai][bj][m][0], x1 = (f32x4){(float)xb[4], (float)xb[5], (float)xb[6], (float)xb[7]} + g4[bj][1] * acc[ai][bj][m][1];
;                     ss += ((x0[0] * x0[0] + x0[1] * x0[1]) + (x0[2] * x0[2] + x0[3] * x0[3])) + ((x1[0] * x1[0] + x1[1] * x1[1]) + (x1[2] * x1[2] + x1[3] * x1[3]));
;                     w[bj].x = cvtpk_h(x0[0], x0[1]); w[bj].y = cvtpk_h(x0[2], x0[3]); w[bj].z = cvtpk_h(x1[0], x1[1]); w[bj].w = cvtpk_h(x1[2], x1[3]);
;                     const f32x4 y0 = x0 * a4[bj][0], y1 = x1 * a4[bj][1]; v[bj].x = cvtpk_h(y0[0], y0[1]); v[bj].y = cvtpk_h(y0[2], y0[3]); v[bj].z = cvtpk_h(y1[0], y1[1]); v[bj].w = cvtpk_h(y1[2], y1[3]); }
;                 stg_line_pair(ws, (unsigned)WS_X16 + o, D * 2u, w[0], w[1], odd);
;                 if (an_off) stg_line_pair(ws, (unsigned)WS_XS + o, D * 2u, v[0], v[1], odd);
;                 ss = red4(ss, fq * 16 + fr); if (fq == 0) stg_f1(ws, rqo + rr * 4u, ss);
	v_mov_b32_e32 v66, v1
	v_mov_b32_dpp v70, v74 quad_perm:[1,0,3,2] row_mask:0xf bank_mask:0xf
	v_mov_b32_e32 v71, v1
	v_cvt_pk_f16_f32 v76, v58, v59
	v_pk_fma_f32 v[52:53], v[52:53], v[48:49], v[68:69]
	v_cvt_pk_f16_f32 v68, v56, v57
	v_mov_b32_dpp v66, v67 quad_perm:[1,0,3,2] row_mask:0xf bank_mask:0xf
	v_cndmask_b32_e64 v70, v67, v70, s[0:1]
	v_mov_b32_e32 v67, v1
	v_mov_b32_dpp v71, v75 quad_perm:[1,0,3,2] row_mask:0xf bank_mask:0xf
	v_mov_b32_e32 v72, v1
	v_cvt_pk_f16_f32 v69, v50, v51
	v_mov_b32_dpp v67, v68 quad_perm:[1,0,3,2] row_mask:0xf bank_mask:0xf
	v_cndmask_b32_e64 v71, v68, v71, s[0:1]
	v_mov_b32_e32 v68, v1
	v_mov_b32_dpp v72, v76 quad_perm:[1,0,3,2] row_mask:0xf bank_mask:0xf
	v_cvt_pk_f16_f32 v73, v52, v53
	v_mov_b32_dpp v68, v69 quad_perm:[1,0,3,2] row_mask:0xf bank_mask:0xf
	v_cndmask_b32_e64 v72, v69, v72, s[0:1]
	v_mov_b32_e32 v69, v1
	v_cvt_pk_f16_f32 v77, v60, v61
	v_cndmask_b32_e64 v66, v66, v74, s[0:1]
	v_mov_b32_dpp v69, v73 quad_perm:[1,0,3,2] row_mask:0xf bank_mask:0xf
	v_mov_b32_e32 v74, v1
	v_cndmask_b32_e64 v67, v67, v75, s[0:1]
	v_cndmask_b32_e64 v68, v68, v76, s[0:1]
	v_mov_b32_dpp v74, v77 quad_perm:[1,0,3,2] row_mask:0xf bank_mask:0xf
	v_cndmask_b32_e64 v69, v69, v77, s[0:1]
	v_cndmask_b32_e64 v73, v73, v74, s[0:1]
	global_store_dwordx4 v78, v[66:69], s[6:7] sc1
	s_nop 1
	v_add_u32_e32 v66, 0x16f90800, v0
	global_store_dwordx4 v66, v[70:73], s[6:7] sc1
	s_cbranch_vccnz .LBB0_525
	v_pk_mul_f32 v[66:67], v[16:17], v[52:53]
	v_pk_mul_f32 v[68:69], v[14:15], v[50:51]
	v_cvt_pk_f16_f32 v73, v66, v67
	v_cvt_pk_f16_f32 v72, v68, v69
	v_pk_mul_f32 v[66:67], v[12:13], v[56:57]
	v_pk_mul_f32 v[68:69], v[10:11], v[54:55]
	v_cvt_pk_f16_f32 v71, v66, v67
	v_cvt_pk_f16_f32 v70, v68, v69
	v_pk_mul_f32 v[66:67], v[8:9], v[60:61]
	v_pk_mul_f32 v[68:69], v[6:7], v[58:59]
	v_cvt_pk_f16_f32 v74, v66, v67
	v_cvt_pk_f16_f32 v75, v68, v69
	v_pk_mul_f32 v[66:67], v[4:5], v[64:65]
	v_pk_mul_f32 v[68:69], v[2:3], v[62:63]
	v_cvt_pk_f16_f32 v67, v66, v67
	v_cvt_pk_f16_f32 v66, v68, v69
	v_mov_b32_e32 v69, v1
	v_mov_b32_e32 v68, v1
	v_add_u32_e32 v76, 0x3d90000, v0
	v_mov_b32_dpp v69, v66 quad_perm:[1,0,3,2] row_mask:0xf bank_mask:0xf
	v_mov_b32_dpp v68, v70 quad_perm:[1,0,3,2] row_mask:0xf bank_mask:0xf
	v_cndmask_b32_e64 v70, v70, v69, s[0:1]
	v_mov_b32_e32 v69, v1
	v_cndmask_b32_e64 v66, v68, v66, s[0:1]
	v_mov_b32_e32 v68, v1
	v_mov_b32_dpp v69, v67 quad_perm:[1,0,3,2] row_mask:0xf bank_mask:0xf
	s_nop 0
	v_mov_b32_dpp v68, v71 quad_perm:[1,0,3,2] row_mask:0xf bank_mask:0xf
	v_cndmask_b32_e64 v71, v71, v69, s[0:1]
	v_mov_b32_e32 v69, v1
	v_cndmask_b32_e64 v67, v68, v67, s[0:1]
	v_mov_b32_e32 v68, v1
	v_mov_b32_dpp v69, v75 quad_perm:[1,0,3,2] row_mask:0xf bank_mask:0xf
	s_nop 0
	v_mov_b32_dpp v68, v72 quad_perm:[1,0,3,2] row_mask:0xf bank_mask:0xf
	v_cndmask_b32_e64 v72, v72, v69, s[0:1]
	v_mov_b32_e32 v69, v1
	v_cndmask_b32_e64 v68, v68, v75, s[0:1]
	v_mov_b32_e32 v75, v1
	v_mov_b32_dpp v69, v73 quad_perm:[1,0,3,2] row_mask:0xf bank_mask:0xf
	v_cndmask_b32_e64 v69, v69, v74, s[0:1]
	v_mov_b32_dpp v75, v74 quad_perm:[1,0,3,2] row_mask:0xf bank_mask:0xf
	v_cndmask_b32_e64 v73, v73, v75, s[0:1]
	global_store_dwordx4 v76, v[66:69], s[6:7] sc1
	s_nop 1
	v_add_u32_e32 v66, 0x3d90800, v0
	global_store_dwordx4 v66, v[70:73], s[6:7] sc1
.LBB0_525:
	v_mul_f32_e32 v63, v63, v63
	v_mul_f32_e32 v59, v59, v59
	v_mul_f32_e32 v55, v55, v55
	v_mul_f32_e32 v51, v51, v51
	v_fmac_f32_e32 v63, v62, v62
	v_mul_f32_e32 v62, v65, v65
	v_fmac_f32_e32 v59, v58, v58
	v_mul_f32_e32 v58, v61, v61
	v_fmac_f32_e32 v55, v54, v54
	v_mul_f32_e32 v54, v57, v57
	v_fmac_f32_e32 v51, v50, v50
	v_mul_f32_e32 v50, v53, v53
	v_fmac_f32_e32 v62, v64, v64
	v_fmac_f32_e32 v58, v60, v60
	v_fmac_f32_e32 v54, v56, v56
	v_fmac_f32_e32 v50, v52, v52
	v_add_f32_e32 v62, v63, v62
	v_add_f32_e32 v58, v59, v58
	v_add_f32_e32 v54, v55, v54
	v_add_f32_e32 v50, v51, v50
	v_add_f32_e32 v58, v62, v58
	v_add_f32_e32 v50, v54, v50
	v_add_f32_e32 v50, v50, v58
	v_mov_b32_e32 v51, v50
	s_nop 1
	v_permlane16_swap_b32_e32 v50, v51
	v_add_f32_e32 v50, v50, v51
	v_mov_b32_e32 v51, v50
	s_nop 1
	v_permlane32_swap_b32_e32 v50, v51
	s_and_saveexec_b64 s[10:11], s[4:5]
	s_cbranch_execz .LBB0_527
	v_add_f32_e32 v50, v50, v51
	v_mov_b32_e32 v51, 0x2880080
	v_lshl_add_u32 v51, v98, 2, v51
	global_store_dword v51, v50, s[6:7] sc1
; #define GAS __attribute__((address_space(1)))
; __device__ __forceinline__ unsigned cvtpk_h(float lo, float hi) { f32x2 v = {lo, hi}; h16x2 b = __builtin_convertvector(v, h16x2); return __builtin_bit_cast(unsigned, b); }
;     __device__ __forceinline__ void operator()(const f32x4 (&acc)[2][2][4][2], const pg8::Unit& u, int wr, int wc, int fr, int fq) const {
;     ...
;             for (int m = 0; m < 4; ++m) { if (half && ai == 1) continue; const unsigned rr = (unsigned)(ai * 128 + m * 16); const unsigned o = eoA + rr * (D * 2u); float ss = 0.f;
;                 const u32x4 la = *(const GAS u32x4*)((const GAS char*)ws + (unsigned)WS_X16 + o), lb = *(const GAS u32x4*)((const GAS char*)ws + (unsigned)WS_X16 + o + D * 2u);
;                 u32x4 xr[2];
; #pragma unroll
;                 for (int c = 0; c < 4; ++c) { const unsigned pa = (unsigned)__builtin_amdgcn_update_dpp(0, (int)la[c], 0xB1, 0xF, 0xF, false), pb = (unsigned)__builtin_amdgcn_update_dpp(0, (int)lb[c], 0xB1, 0xF, 0xF, false);
;                     xr[0][c] = odd ? pb : la[c]; xr[1][c] = odd ? lb[c] : pa; }
;                 u32x4 w[2], v[2];
; #pragma unroll
;                 for (int bj = 0; bj < 2; ++bj) { const h16x8 xb = __builtin_bit_cast(h16x8, xr[bj]);
;                     const f32x4 x0 = (f32x4){(float)xb[0], (float)xb[1], (float)xb[2], (float)xb[3]} + g4[bj][0] * acc[ai][bj][m][0], x1 = (f32x4){(float)xb[4], (float)xb[5], (float)xb[6], (float)xb[7]} + g4[bj][1] * acc[ai][bj][m][1];
;                     ss += ((x0[0] * x0[0] + x0[1] * x0[1]) + (x0[2] * x0[2] + x0[3] * x0[3])) + ((x1[0] * x1[0] + x1[1] * x1[1]) + (x1[2] * x1[2] + x1[3] * x1[3]));
;                     w[bj].x = cvtpk_h(x0[0], x0[1]); w[bj].y = cvtpk_h(x0[2], x0[3]); w[bj].z = cvtpk_h(x1[0], x1[1]); w[bj].w = cvtpk_h(x1[2], x1[3]);
;                     const f32x4 y0 = x0 * a4[bj][0], y1 = x1 * a4[bj][1]; v[bj].x = cvtpk_h(y0[0], y0[1]); v[bj].y = cvtpk_h(y0[2], y0[3]); v[bj].z = cvtpk_h(y1[0], y1[1]); v[bj].w = cvtpk_h(y1[2], y1[3]); }
;                 stg_line_pair(ws, (unsigned)WS_X16 + o, D * 2u, w[0], w[1], odd);
;                 if (an_off) stg_line_pair(ws, (unsigned)WS_XS + o, D * 2u, v[0], v[1], odd);
;                 ss = red4(ss, fq * 16 + fr); if (fq == 0) stg_f1(ws, rqo + rr * 4u, ss);
.LBB0_527:
	s_or_b64 exec, exec, s[10:11]
	v_add_u32_e32 v54, 0x18000, v0
	global_load_dwordx4 v[50:53], v54, s[8:9]
	s_nop 0
	global_load_dwordx4 v[54:57], v54, s[8:9] offset:2048
	v_mov_b32_e32 v58, v1
	v_mov_b32_e32 v59, v1
	s_and_b64 vcc, exec, s[2:3]
	s_waitcnt vmcnt(0)
	v_mov_b32_dpp v58, v50 quad_perm:[1,0,3,2] row_mask:0xf bank_mask:0xf
	v_mov_b32_dpp v59, v54 quad_perm:[1,0,3,2] row_mask:0xf bank_mask:0xf
	v_cndmask_b32_e64 v59, v59, v50, s[0:1]
	v_cndmask_b32_e64 v54, v54, v58, s[0:1]
	v_mov_b32_e32 v50, v1
	v_mov_b32_e32 v58, v1
	s_nop 0
	v_mov_b32_dpp v50, v51 quad_perm:[1,0,3,2] row_mask:0xf bank_mask:0xf
	v_mov_b32_dpp v58, v55 quad_perm:[1,0,3,2] row_mask:0xf bank_mask:0xf
	v_cndmask_b32_e64 v58, v58, v51, s[0:1]
	v_cndmask_b32_e64 v55, v55, v50, s[0:1]
	v_mov_b32_e32 v50, v1
	v_mov_b32_e32 v51, v1
	s_nop 0
	v_mov_b32_dpp v50, v52 quad_perm:[1,0,3,2] row_mask:0xf bank_mask:0xf
	v_mov_b32_dpp v51, v56 quad_perm:[1,0,3,2] row_mask:0xf bank_mask:0xf
	v_cndmask_b32_e64 v60, v51, v52, s[0:1]
	v_cndmask_b32_e64 v56, v56, v50, s[0:1]
	v_mov_b32_e32 v50, v1
	v_mov_b32_e32 v51, v1
	v_cvt_f32_f16_e32 v52, v58
	v_mov_b32_dpp v50, v53 quad_perm:[1,0,3,2] row_mask:0xf bank_mask:0xf
	v_mov_b32_dpp v51, v57 quad_perm:[1,0,3,2] row_mask:0xf bank_mask:0xf
	v_cndmask_b32_e64 v61, v51, v53, s[0:1]
	v_cndmask_b32_e64 v57, v57, v50, s[0:1]
	v_cvt_f32_f16_e32 v50, v59
	v_cvt_f32_f16_sdwa v51, v59 dst_sel:DWORD dst_unused:UNUSED_PAD src0_sel:WORD_1
	v_cvt_f32_f16_sdwa v53, v58 dst_sel:DWORD dst_unused:UNUSED_PAD src0_sel:WORD_1
	v_pk_fma_f32 v[30:31], v[30:31], v[34:35], v[50:51]
	v_cvt_f32_f16_e32 v34, v60
	v_cvt_f32_f16_sdwa v35, v60 dst_sel:DWORD dst_unused:UNUSED_PAD src0_sel:WORD_1
	v_pk_fma_f32 v[32:33], v[32:33], v[36:37], v[52:53]
	v_cvt_f32_f16_e32 v36, v61
	v_cvt_f32_f16_sdwa v37, v61 dst_sel:DWORD dst_unused:UNUSED_PAD src0_sel:WORD_1
	v_pk_fma_f32 v[26:27], v[26:27], v[38:39], v[34:35]
	v_cvt_f32_f16_e32 v34, v54
	v_cvt_f32_f16_sdwa v35, v54 dst_sel:DWORD dst_unused:UNUSED_PAD src0_sel:WORD_1
	v_pk_fma_f32 v[28:29], v[28:29], v[40:41], v[36:37]
	v_cvt_f32_f16_e32 v36, v55
	v_cvt_f32_f16_sdwa v37, v55 dst_sel:DWORD dst_unused:UNUSED_PAD src0_sel:WORD_1
	v_pk_fma_f32 v[22:23], v[22:23], v[42:43], v[34:35]
	v_cvt_f32_f16_e32 v34, v56
	v_cvt_f32_f16_sdwa v35, v56 dst_sel:DWORD dst_unused:UNUSED_PAD src0_sel:WORD_1
	v_pk_fma_f32 v[24:25], v[24:25], v[44:45], v[36:37]
	v_cvt_f32_f16_e32 v36, v57
	v_cvt_f32_f16_sdwa v37, v57 dst_sel:DWORD dst_unused:UNUSED_PAD src0_sel:WORD_1
	v_cvt_pk_f16_f32 v38, v30, v31
	v_pk_fma_f32 v[18:19], v[18:19], v[46:47], v[34:35]
	v_cvt_pk_f16_f32 v35, v22, v23
	v_mov_b32_e32 v34, v1
	v_mov_b32_e32 v44, v1
	v_cvt_pk_f16_f32 v39, v32, v33
	v_mov_b32_dpp v34, v35 quad_perm:[1,0,3,2] row_mask:0xf bank_mask:0xf
	v_mov_b32_dpp v44, v38 quad_perm:[1,0,3,2] row_mask:0xf bank_mask:0xf
	v_pk_fma_f32 v[20:21], v[20:21], v[48:49], v[36:37]
	v_cvt_pk_f16_f32 v36, v24, v25
	v_cndmask_b32_e64 v34, v34, v38, s[0:1]
	v_cndmask_b32_e64 v38, v35, v44, s[0:1]
	v_mov_b32_e32 v35, v1
	v_mov_b32_e32 v44, v1
	v_cvt_pk_f16_f32 v40, v26, v27
	v_mov_b32_dpp v35, v36 quad_perm:[1,0,3,2] row_mask:0xf bank_mask:0xf
	v_mov_b32_dpp v44, v39 quad_perm:[1,0,3,2] row_mask:0xf bank_mask:0xf
	v_cvt_pk_f16_f32 v37, v18, v19
	v_cndmask_b32_e64 v35, v35, v39, s[0:1]
	v_cndmask_b32_e64 v39, v36, v44, s[0:1]
	v_mov_b32_e32 v36, v1
	v_mov_b32_e32 v44, v1
	v_cvt_pk_f16_f32 v42, v20, v21
	v_mov_b32_dpp v36, v37 quad_perm:[1,0,3,2] row_mask:0xf bank_mask:0xf
	v_mov_b32_dpp v44, v40 quad_perm:[1,0,3,2] row_mask:0xf bank_mask:0xf
	v_cndmask_b32_e64 v36, v36, v40, s[0:1]
	v_cndmask_b32_e64 v40, v37, v44, s[0:1]
	v_mov_b32_e32 v37, v1
	v_cvt_pk_f16_f32 v41, v28, v29
	v_mov_b32_e32 v44, v1
	v_mov_b32_dpp v37, v42 quad_perm:[1,0,3,2] row_mask:0xf bank_mask:0xf
	v_add_u32_e32 v43, 0x16f98000, v0
	v_mov_b32_dpp v44, v41 quad_perm:[1,0,3,2] row_mask:0xf bank_mask:0xf
	v_cndmask_b32_e64 v37, v37, v41, s[0:1]
	v_cndmask_b32_e64 v41, v42, v44, s[0:1]
	global_store_dwordx4 v43, v[34:37], s[6:7] sc1
	s_nop 1
	v_add_u32_e32 v34, 0x16f98800, v0
	global_store_dwordx4 v34, v[38:41], s[6:7] sc1
	s_cbranch_vccnz .LBB0_529
	v_pk_mul_f32 v[10:11], v[10:11], v[22:23]
	v_pk_mul_f32 v[4:5], v[4:5], v[32:33]
	v_pk_mul_f32 v[2:3], v[2:3], v[30:31]
	v_cvt_pk_f16_f32 v10, v10, v11
	v_cvt_pk_f16_f32 v4, v4, v5
	v_cvt_pk_f16_f32 v2, v2, v3
	v_mov_b32_e32 v3, v1
	v_mov_b32_e32 v5, v1
	v_pk_mul_f32 v[12:13], v[12:13], v[24:25]
	v_pk_mul_f32 v[8:9], v[8:9], v[28:29]
	v_pk_mul_f32 v[6:7], v[6:7], v[26:27]
	v_mov_b32_dpp v3, v10 quad_perm:[1,0,3,2] row_mask:0xf bank_mask:0xf
	v_mov_b32_dpp v5, v2 quad_perm:[1,0,3,2] row_mask:0xf bank_mask:0xf
	v_cvt_pk_f16_f32 v12, v12, v13
	v_cvt_pk_f16_f32 v9, v8, v9
	v_cvt_pk_f16_f32 v8, v6, v7
	v_cndmask_b32_e64 v2, v3, v2, s[0:1]
	v_cndmask_b32_e64 v6, v10, v5, s[0:1]
	v_mov_b32_e32 v3, v1
	v_mov_b32_e32 v5, v1
	v_pk_mul_f32 v[14:15], v[14:15], v[18:19]
	v_mov_b32_dpp v3, v12 quad_perm:[1,0,3,2] row_mask:0xf bank_mask:0xf
	v_mov_b32_dpp v5, v4 quad_perm:[1,0,3,2] row_mask:0xf bank_mask:0xf
	v_cvt_pk_f16_f32 v14, v14, v15
	v_cndmask_b32_e64 v3, v3, v4, s[0:1]
	v_cndmask_b32_e64 v7, v12, v5, s[0:1]
	v_mov_b32_e32 v4, v1
	v_mov_b32_e32 v5, v1
	v_pk_mul_f32 v[16:17], v[16:17], v[20:21]
	v_mov_b32_dpp v4, v14 quad_perm:[1,0,3,2] row_mask:0xf bank_mask:0xf
	v_mov_b32_dpp v5, v8 quad_perm:[1,0,3,2] row_mask:0xf bank_mask:0xf
	v_cvt_pk_f16_f32 v16, v16, v17
	v_cndmask_b32_e64 v4, v4, v8, s[0:1]
	v_cndmask_b32_e64 v8, v14, v5, s[0:1]
	v_mov_b32_e32 v5, v1
	v_mov_b32_e32 v10, v1
	v_add_u32_e32 v11, 0x3d98000, v0
	v_mov_b32_dpp v5, v16 quad_perm:[1,0,3,2] row_mask:0xf bank_mask:0xf
	v_mov_b32_dpp v10, v9 quad_perm:[1,0,3,2] row_mask:0xf bank_mask:0xf
	v_cndmask_b32_e64 v5, v5, v9, s[0:1]
	v_cndmask_b32_e64 v9, v16, v10, s[0:1]
	v_add_u32_e32 v0, 0x3d98800, v0
	global_store_dwordx4 v11, v[2:5], s[6:7] sc1
	global_store_dwordx4 v0, v[6:9], s[6:7] sc1
.LBB0_529:
	v_mul_f32_e32 v0, v31, v31
	v_mul_f32_e32 v2, v33, v33
	v_fmac_f32_e32 v0, v30, v30
	v_fmac_f32_e32 v2, v32, v32
	v_add_f32_e32 v0, v0, v2
	v_mul_f32_e32 v2, v27, v27
	v_mul_f32_e32 v3, v29, v29
	v_fmac_f32_e32 v2, v26, v26
	v_fmac_f32_e32 v3, v28, v28
	v_add_f32_e32 v2, v2, v3
	v_add_f32_e32 v0, v0, v2
	v_mul_f32_e32 v2, v23, v23
	v_mul_f32_e32 v3, v25, v25
	v_fmac_f32_e32 v2, v22, v22
	v_fmac_f32_e32 v3, v24, v24
	v_add_f32_e32 v2, v2, v3
	v_mul_f32_e32 v3, v19, v19
	v_mul_f32_e32 v4, v21, v21
	v_fmac_f32_e32 v3, v18, v18
	v_fmac_f32_e32 v4, v20, v20
	v_add_f32_e32 v3, v3, v4
	v_add_f32_e32 v2, v2, v3
	v_add_f32_e32 v0, v2, v0
	v_mov_b32_e32 v2, v0
	s_nop 1
	v_permlane16_swap_b32_e32 v0, v2
	v_add_f32_e32 v0, v0, v2
	v_mov_b32_e32 v2, v0
	s_nop 1
	v_permlane32_swap_b32_e32 v0, v2
	s_and_saveexec_b64 s[0:1], s[4:5]
	s_cbranch_execz .LBB0_531
	v_add_f32_e32 v0, v0, v2
	v_mov_b32_e32 v2, 0x28800c0
	v_lshl_add_u32 v2, v98, 2, v2
	global_store_dword v2, v0, s[6:7] sc1

; #define LAS __attribute__((address_space(3)))
; __device__ __forceinline__ unsigned cvtpk_h(float lo, float hi) { f32x2 v = {lo, hi}; h16x2 b = __builtin_convertvector(v, h16x2); return __builtin_bit_cast(unsigned, b); }
;     __device__ __forceinline__ void operator()(const f32x4 (&acc)[2][2][4][2], const pg8::Unit& u, int wr, int wc, int fr, int fq) const {
;     ...
; #pragma unroll
;         for (int ai = 0; ai < 2; ++ai)
; #pragma unroll
;             for (int m = 0; m < 4; ++m) { const float r = rs[ai][m]; f32x4 v[2][2]; float ss = 0.f;
; #pragma unroll
;                 for (int bj = 0; bj < 2; ++bj)
; #pragma unroll
;                     for (int n = 0; n < 2; ++n) { v[bj][n] = acc[ai][bj][m][n] * r + bv[bj][n]; ss += (v[bj][n][0] * v[bj][n][0] + v[bj][n][1] * v[bj][n][1]) + (v[bj][n][2] * v[bj][n][2] + v[bj][n][3] * v[bj][n][3]); }
;                 const float rn = __builtin_amdgcn_rsqf(red4(ss, fq * 16 + fr) * (1.f / 64.f) + EPS);
; #pragma unroll
;                 for (int bj = 0; bj < 2; ++bj)
; #pragma unroll
;                     for (int n = 0; n < 2; ++n) v[bj][n] = v[bj][n] * rn * g4[bj][n];
;                 if (lat) { const unsigned t = (rbase + ai * 128 + m * 16) & (SEQ - 1);
; #pragma unroll
;                     for (int bj = 0; bj < 2; ++bj) { const unsigned pos = bj ? (t & 63u) : (t >> 6); const f32x4 cs = *(const LAS f32x4*)(ropel + pos * 16u + 4u * fq), sn = *(const LAS f32x4*)(ropel + 1024u + pos * 16u + 4u * fq);
;                         const f32x4 x1 = v[bj][0], x2 = v[bj][1]; v[bj][0] = x1 * cs - x2 * sn; v[bj][1] = x2 * cs + x1 * sn; } }
;                 const unsigned ro = offA + (unsigned)(ai * 8 + m) * 32u * pitch;
;                 u32x4 w[2];
; #pragma unroll
;                 for (int bj = 0; bj < 2; ++bj) { w[bj].x = cvtpk_h(v[bj][0][0], v[bj][0][1]); w[bj].y = cvtpk_h(v[bj][0][2], v[bj][0][3]); w[bj].z = cvtpk_h(v[bj][1][0], v[bj][1][1]); w[bj].w = cvtpk_h(v[bj][1][2], v[bj][1][3]); }
;                 stg_line_pair(wst, ro, 2u * pitch, w[0], w[1], odd);
;                 asm volatile("" ::: "memory"); }
.LBB0_577:
	v_and_b32_e32 v186, 1, v202
	v_lshlrev_b32_e32 v206, 6, v186
	v_add3_u32 v206, v206, v203, v187
	v_add_u32_e32 v187, 16, v202
	v_and_b32_e32 v210, 63, v187
	v_cvt_pk_f16_f32 v152, v152, v153
	v_cvt_pk_f16_f32 v149, v148, v149
	v_mov_b32_e32 v148, v1
	v_mov_b32_e32 v187, v1
	v_cmp_eq_u32_e64 s[2:3], 0, v186
	v_mov_b32_dpp v148, v149 quad_perm:[1,0,3,2] row_mask:0xf bank_mask:0xf
	v_mov_b32_dpp v187, v152 quad_perm:[1,0,3,2] row_mask:0xf bank_mask:0xf
	v_cvt_pk_f16_f32 v153, v154, v155
	v_cvt_pk_f16_f32 v150, v150, v151
	v_cndmask_b32_e64 v148, v148, v152, s[2:3]
	v_cndmask_b32_e64 v152, v149, v187, s[2:3]
	v_mov_b32_e32 v149, v1
	v_mov_b32_e32 v187, v1
	v_cvt_pk_f16_f32 v154, v190, v191
	v_mov_b32_dpp v149, v150 quad_perm:[1,0,3,2] row_mask:0xf bank_mask:0xf
	v_mov_b32_dpp v187, v153 quad_perm:[1,0,3,2] row_mask:0xf bank_mask:0xf
	v_cvt_pk_f16_f32 v151, v194, v195
	v_cndmask_b32_e64 v149, v149, v153, s[2:3]
	v_cndmask_b32_e64 v153, v150, v187, s[2:3]
	v_mov_b32_e32 v150, v1
	v_mov_b32_e32 v187, v1
	v_cvt_pk_f16_f32 v186, v192, v193
	v_mov_b32_dpp v150, v151 quad_perm:[1,0,3,2] row_mask:0xf bank_mask:0xf
	v_mov_b32_dpp v187, v154 quad_perm:[1,0,3,2] row_mask:0xf bank_mask:0xf
	v_cndmask_b32_e64 v150, v150, v154, s[2:3]
	v_cndmask_b32_e64 v154, v151, v187, s[2:3]
	v_mov_b32_e32 v151, v1
	v_cvt_pk_f16_f32 v155, v188, v189
	v_mov_b32_e32 v187, v1
	v_mov_b32_dpp v151, v186 quad_perm:[1,0,3,2] row_mask:0xf bank_mask:0xf
	v_cndmask_b32_e64 v151, v151, v155, s[2:3]
	v_mov_b32_dpp v187, v155 quad_perm:[1,0,3,2] row_mask:0xf bank_mask:0xf
	v_cndmask_b32_e64 v155, v186, v187, s[2:3]
	s_mov_b32 s100, 2
	global_store_dwordx4 v206, v[148:151], s[36:37] sc1
	s_and_b64 vcc, exec, s[4:5]
	v_lshlrev_b32_e32 v213, 6, v210
	v_add_u32_e32 v148, s9, v206
	s_mov_b32 s100, 2
	global_store_dwordx4 v148, v[152:155], s[36:37] sc1
	v_mov_b32_e32 v148, v177
	v_pk_fma_f32 v[150:151], v[52:53], v[148:149], v[138:139] op_sel_hi:[1,0,1]
	v_pk_fma_f32 v[152:153], v[50:51], v[148:149], v[136:137] op_sel_hi:[1,0,1]
	v_mul_f32_e32 v154, v151, v151
	v_mul_f32_e32 v149, v153, v153
	v_fmac_f32_e32 v149, v152, v152
	v_fmac_f32_e32 v154, v150, v150
	v_add_f32_e32 v149, v149, v154
	v_pk_fma_f32 v[186:187], v[48:49], v[148:149], v[134:135] op_sel_hi:[1,0,1]
	v_pk_fma_f32 v[188:189], v[46:47], v[148:149], v[132:133] op_sel_hi:[1,0,1]
	v_mul_f32_e32 v155, v187, v187
	v_mul_f32_e32 v154, v189, v189
	v_fmac_f32_e32 v154, v188, v188
	v_fmac_f32_e32 v155, v186, v186
	v_add_f32_e32 v154, v154, v155
	v_add_f32_e32 v149, v149, v154
	v_pk_fma_f32 v[190:191], v[120:121], v[148:149], v[142:143] op_sel_hi:[1,0,1]
	v_pk_fma_f32 v[192:193], v[118:119], v[148:149], v[140:141] op_sel_hi:[1,0,1]
	v_mul_f32_e32 v155, v191, v191
	v_mul_f32_e32 v154, v193, v193
	v_fmac_f32_e32 v154, v192, v192
	v_fmac_f32_e32 v155, v190, v190
	v_add_f32_e32 v154, v154, v155
	v_add_f32_e32 v149, v149, v154
	v_pk_fma_f32 v[194:195], v[116:117], v[148:149], v[146:147] op_sel_hi:[1,0,1]
	v_pk_fma_f32 v[216:217], v[114:115], v[148:149], v[144:145] op_sel_hi:[1,0,1]
	v_mul_f32_e32 v154, v195, v195
	v_mul_f32_e32 v148, v217, v217
	v_fmac_f32_e32 v148, v216, v216
	v_fmac_f32_e32 v154, v194, v194
	v_add_f32_e32 v148, v148, v154
	v_add_f32_e32 v148, v149, v148
	v_mov_b32_e32 v149, v148
	s_nop 1
	v_permlane16_swap_b32_e32 v148, v149
	v_add_f32_e32 v148, v148, v149
	v_mov_b32_e32 v149, v148
	s_nop 1
	v_permlane32_swap_b32_e32 v148, v149
	v_add_f32_e32 v148, v148, v149
	v_fmamk_f32 v148, v148, 0x3c800000, v229
	v_rsq_f32_e32 v218, v148
	s_nop 0
	v_pk_mul_f32 v[148:149], v[152:153], v[218:219] op_sel_hi:[1,0]
	v_pk_mul_f32 v[150:151], v[150:151], v[218:219] op_sel_hi:[1,0]
	v_pk_mul_f32 v[152:153], v[184:185], v[148:149]
	v_pk_mul_f32 v[154:155], v[182:183], v[150:151]
	v_pk_mul_f32 v[148:149], v[188:189], v[218:219] op_sel_hi:[1,0]
	v_pk_mul_f32 v[150:151], v[186:187], v[218:219] op_sel_hi:[1,0]
	v_pk_mul_f32 v[188:189], v[180:181], v[148:149]
	v_pk_mul_f32 v[186:187], v[178:179], v[150:151]
	v_pk_mul_f32 v[148:149], v[192:193], v[218:219] op_sel_hi:[1,0]
	v_pk_mul_f32 v[150:151], v[190:191], v[218:219] op_sel_hi:[1,0]
	v_pk_mul_f32 v[192:193], v[216:217], v[218:219] op_sel_hi:[1,0]
	v_pk_mul_f32 v[190:191], v[194:195], v[218:219] op_sel_hi:[1,0]
	v_pk_mul_f32 v[150:151], v[160:161], v[150:151]
	v_pk_mul_f32 v[148:149], v[162:163], v[148:149]
	v_pk_mul_f32 v[190:191], v[156:157], v[190:191]
	v_pk_mul_f32 v[192:193], v[158:159], v[192:193]
	s_cbranch_vccnz .LBB0_579
	v_add_u32_e32 v194, 16, v201
	v_and_b32_e32 v194, 0x7c0, v194
	v_add_u32_e32 v195, v205, v194
	v_add_u32_e32 v194, v204, v194
	ds_read_b128 v[216:219], v195
	ds_read_b128 v[220:223], v194
	s_waitcnt lgkmcnt(0)
	v_pk_mul_f32 v[224:225], v[188:189], v[220:221]
	v_pk_mul_f32 v[194:195], v[186:187], v[222:223]
	v_pk_fma_f32 v[224:225], v[152:153], v[216:217], v[224:225] neg_lo:[0,0,1] neg_hi:[0,0,1]
	v_pk_mul_f32 v[152:153], v[152:153], v[220:221]
	v_pk_fma_f32 v[226:227], v[154:155], v[218:219], v[194:195] neg_lo:[0,0,1] neg_hi:[0,0,1]
	v_pk_mul_f32 v[154:155], v[154:155], v[222:223]
	v_pk_fma_f32 v[188:189], v[188:189], v[216:217], v[152:153]
	v_add_u32_e32 v152, v205, v213
	v_add_u32_e32 v194, v204, v213
	v_pk_fma_f32 v[186:187], v[186:187], v[218:219], v[154:155]
	ds_read_b128 v[152:155], v152
	ds_read_b128 v[216:219], v194
	s_waitcnt lgkmcnt(0)
	v_pk_mul_f32 v[194:195], v[190:191], v[218:219]
	v_pk_mul_f32 v[220:221], v[192:193], v[216:217]
	v_pk_fma_f32 v[222:223], v[150:151], v[154:155], v[194:195] neg_lo:[0,0,1] neg_hi:[0,0,1]
	v_pk_fma_f32 v[220:221], v[148:149], v[152:153], v[220:221] neg_lo:[0,0,1] neg_hi:[0,0,1]
	v_pk_mul_f32 v[150:151], v[150:151], v[218:219]
	v_pk_mul_f32 v[148:149], v[148:149], v[216:217]
	v_pk_fma_f32 v[190:191], v[190:191], v[154:155], v[150:151]
	v_pk_fma_f32 v[192:193], v[192:193], v[152:153], v[148:149]
	v_mov_b64_e32 v[148:149], v[220:221]
	v_mov_b64_e32 v[152:153], v[224:225]
	v_mov_b64_e32 v[150:151], v[222:223]
	v_mov_b64_e32 v[154:155], v[226:227]
; #define LAS __attribute__((address_space(3)))
; __device__ __forceinline__ unsigned cvtpk_h(float lo, float hi) { f32x2 v = {lo, hi}; h16x2 b = __builtin_convertvector(v, h16x2); return __builtin_bit_cast(unsigned, b); }
;     __device__ __forceinline__ void operator()(const f32x4 (&acc)[2][2][4][2], const pg8::Unit& u, int wr, int wc, int fr, int fq) const {
;     ...
; #pragma unroll
;         for (int ai = 0; ai < 2; ++ai)
; #pragma unroll
;             for (int m = 0; m < 4; ++m) { const float r = rs[ai][m]; f32x4 v[2][2]; float ss = 0.f;
; #pragma unroll
;                 for (int bj = 0; bj < 2; ++bj)
; #pragma unroll
;                     for (int n = 0; n < 2; ++n) { v[bj][n] = acc[ai][bj][m][n] * r + bv[bj][n]; ss += (v[bj][n][0] * v[bj][n][0] + v[bj][n][1] * v[bj][n][1]) + (v[bj][n][2] * v[bj][n][2] + v[bj][n][3] * v[bj][n][3]); }
;                 const float rn = __builtin_amdgcn_rsqf(red4(ss, fq * 16 + fr) * (1.f / 64.f) + EPS);
; #pragma unroll
;                 for (int bj = 0; bj < 2; ++bj)
; #pragma unroll
;                     for (int n = 0; n < 2; ++n) v[bj][n] = v[bj][n] * rn * g4[bj][n];
;                 if (lat) { const unsigned t = (rbase + ai * 128 + m * 16) & (SEQ - 1);
; #pragma unroll
;                     for (int bj = 0; bj < 2; ++bj) { const unsigned pos = bj ? (t & 63u) : (t >> 6); const f32x4 cs = *(const LAS f32x4*)(ropel + pos * 16u + 4u * fq), sn = *(const LAS f32x4*)(ropel + 1024u + pos * 16u + 4u * fq);
;                         const f32x4 x1 = v[bj][0], x2 = v[bj][1]; v[bj][0] = x1 * cs - x2 * sn; v[bj][1] = x2 * cs + x1 * sn; } }
;                 const unsigned ro = offA + (unsigned)(ai * 8 + m) * 32u * pitch;
;                 u32x4 w[2];
; #pragma unroll
;                 for (int bj = 0; bj < 2; ++bj) { w[bj].x = cvtpk_h(v[bj][0][0], v[bj][0][1]); w[bj].y = cvtpk_h(v[bj][0][2], v[bj][0][3]); w[bj].z = cvtpk_h(v[bj][1][0], v[bj][1][1]); w[bj].w = cvtpk_h(v[bj][1][2], v[bj][1][3]); }
;                 stg_line_pair(wst, ro, 2u * pitch, w[0], w[1], odd);
;                 asm volatile("" ::: "memory"); }
.LBB0_579:
	v_cvt_pk_f16_f32 v152, v152, v153
	v_cvt_pk_f16_f32 v153, v154, v155
	v_cvt_pk_f16_f32 v154, v188, v189
	v_cvt_pk_f16_f32 v149, v148, v149
	v_mov_b32_e32 v148, v1
	v_mov_b32_e32 v188, v1
	v_cvt_pk_f16_f32 v150, v150, v151
	v_mov_b32_dpp v148, v149 quad_perm:[1,0,3,2] row_mask:0xf bank_mask:0xf
	v_mov_b32_dpp v188, v152 quad_perm:[1,0,3,2] row_mask:0xf bank_mask:0xf
	v_cndmask_b32_e64 v148, v148, v152, s[2:3]
	v_cndmask_b32_e64 v152, v149, v188, s[2:3]
	v_mov_b32_e32 v149, v1
	v_mov_b32_e32 v188, v1
	v_cvt_pk_f16_f32 v151, v192, v193
	v_mov_b32_dpp v149, v150 quad_perm:[1,0,3,2] row_mask:0xf bank_mask:0xf
	v_mov_b32_dpp v188, v153 quad_perm:[1,0,3,2] row_mask:0xf bank_mask:0xf
	v_cndmask_b32_e64 v149, v149, v153, s[2:3]
	v_cndmask_b32_e64 v153, v150, v188, s[2:3]
	v_mov_b32_e32 v150, v1
	v_mov_b32_e32 v188, v1
	v_cvt_pk_f16_f32 v155, v186, v187
	v_mov_b32_dpp v150, v151 quad_perm:[1,0,3,2] row_mask:0xf bank_mask:0xf
	v_mov_b32_dpp v188, v154 quad_perm:[1,0,3,2] row_mask:0xf bank_mask:0xf
	v_cvt_pk_f16_f32 v186, v190, v191
	v_cndmask_b32_e64 v150, v150, v154, s[2:3]
	v_cndmask_b32_e64 v154, v151, v188, s[2:3]
	v_mov_b32_e32 v151, v1
	v_mov_b32_e32 v188, v1
	v_lshl_add_u32 v187, 32, s42, v206
	v_mov_b32_dpp v151, v186 quad_perm:[1,0,3,2] row_mask:0xf bank_mask:0xf
	v_mov_b32_dpp v188, v155 quad_perm:[1,0,3,2] row_mask:0xf bank_mask:0xf
	v_cndmask_b32_e64 v151, v151, v155, s[2:3]
	v_cndmask_b32_e64 v155, v186, v188, s[2:3]
	s_mov_b32 s100, 2
	global_store_dwordx4 v187, v[148:151], s[36:37] sc1
	v_pk_fma_f32 v[188:189], v[42:43], v[174:175], v[132:133] op_sel_hi:[1,0,1]
	v_pk_fma_f32 v[190:191], v[112:113], v[174:175], v[142:143] op_sel_hi:[1,0,1]
	v_add_u32_e32 v148, s9, v187
	s_mov_b32 s100, 2
	global_store_dwordx4 v148, v[152:155], s[36:37] sc1
	v_pk_fma_f32 v[148:149], v[56:57], v[174:175], v[138:139] op_sel_hi:[1,0,1]
	v_pk_fma_f32 v[150:151], v[54:55], v[174:175], v[136:137] op_sel_hi:[1,0,1]
	v_mul_f32_e32 v153, v149, v149
	v_mul_f32_e32 v152, v151, v151
	v_fmac_f32_e32 v152, v150, v150
	v_fmac_f32_e32 v153, v148, v148
	v_pk_fma_f32 v[186:187], v[44:45], v[174:175], v[134:135] op_sel_hi:[1,0,1]
	v_add_f32_e32 v152, v152, v153
	v_mul_f32_e32 v153, v189, v189
	v_mul_f32_e32 v154, v187, v187
	v_fmac_f32_e32 v153, v188, v188
	v_fmac_f32_e32 v154, v186, v186
	v_add_f32_e32 v153, v153, v154
	v_pk_fma_f32 v[192:193], v[110:111], v[174:175], v[140:141] op_sel_hi:[1,0,1]
	v_add_f32_e32 v152, v152, v153
	v_mul_f32_e32 v153, v193, v193
	v_mul_f32_e32 v154, v191, v191
	v_fmac_f32_e32 v153, v192, v192
	v_fmac_f32_e32 v154, v190, v190
	v_xor_b32_e32 v210, 32, v214
	v_add_f32_e32 v153, v153, v154
	v_pk_fma_f32 v[194:195], v[108:109], v[174:175], v[146:147] op_sel_hi:[1,0,1]
	v_pk_fma_f32 v[214:215], v[106:107], v[174:175], v[144:145] op_sel_hi:[1,0,1]
	v_add_f32_e32 v152, v152, v153
	v_mul_f32_e32 v153, v215, v215
	v_mul_f32_e32 v154, v195, v195
	v_fmac_f32_e32 v153, v214, v214
	v_fmac_f32_e32 v154, v194, v194
	v_add_f32_e32 v153, v153, v154
	v_add_f32_e32 v152, v152, v153
	v_mov_b32_e32 v153, v152
	s_nop 1
	v_permlane16_swap_b32_e32 v152, v153
	v_add_f32_e32 v152, v152, v153
	v_mov_b32_e32 v153, v152
	s_nop 1
	v_permlane32_swap_b32_e32 v152, v153
	v_add_f32_e32 v152, v152, v153
	v_fmamk_f32 v152, v152, 0x3c800000, v229
	v_rsq_f32_e32 v216, v152
	s_and_b64 vcc, exec, s[4:5]
	v_pk_mul_f32 v[150:151], v[150:151], v[216:217] op_sel_hi:[1,0]
	v_pk_mul_f32 v[148:149], v[148:149], v[216:217] op_sel_hi:[1,0]
	v_pk_mul_f32 v[152:153], v[184:185], v[150:151]
	v_pk_mul_f32 v[154:155], v[182:183], v[148:149]
	v_pk_mul_f32 v[148:149], v[188:189], v[216:217] op_sel_hi:[1,0]
	v_pk_mul_f32 v[150:151], v[186:187], v[216:217] op_sel_hi:[1,0]
	v_pk_mul_f32 v[188:189], v[180:181], v[148:149]
	v_pk_mul_f32 v[186:187], v[178:179], v[150:151]
	v_pk_mul_f32 v[148:149], v[192:193], v[216:217] op_sel_hi:[1,0]
	v_pk_mul_f32 v[150:151], v[190:191], v[216:217] op_sel_hi:[1,0]
	v_pk_mul_f32 v[192:193], v[214:215], v[216:217] op_sel_hi:[1,0]
	v_pk_mul_f32 v[190:191], v[194:195], v[216:217] op_sel_hi:[1,0]
	v_pk_mul_f32 v[150:151], v[160:161], v[150:151]
	v_pk_mul_f32 v[148:149], v[162:163], v[148:149]
	v_pk_mul_f32 v[190:191], v[156:157], v[190:191]
	v_pk_mul_f32 v[192:193], v[158:159], v[192:193]
	v_lshlrev_b32_e32 v195, 6, v210
	s_cbranch_vccnz .LBB0_581
	v_add_u32_e32 v194, 32, v201
	v_and_b32_e32 v194, 0x7c0, v194
	v_add_u32_e32 v210, v205, v194
	v_add_u32_e32 v194, v204, v194
	ds_read_b128 v[214:217], v210
	ds_read_b128 v[218:221], v194
	v_add_u32_e32 v194, v204, v195
	s_waitcnt lgkmcnt(0)
	v_pk_mul_f32 v[222:223], v[186:187], v[220:221]
	v_pk_mul_f32 v[226:227], v[188:189], v[218:219]
	v_pk_fma_f32 v[224:225], v[154:155], v[216:217], v[222:223] neg_lo:[0,0,1] neg_hi:[0,0,1]
	v_pk_fma_f32 v[222:223], v[152:153], v[214:215], v[226:227] neg_lo:[0,0,1] neg_hi:[0,0,1]
	v_pk_mul_f32 v[152:153], v[152:153], v[218:219]
	v_pk_mul_f32 v[154:155], v[154:155], v[220:221]
	v_pk_fma_f32 v[188:189], v[188:189], v[214:215], v[152:153]
	v_add_u32_e32 v152, v205, v195
	v_pk_fma_f32 v[186:187], v[186:187], v[216:217], v[154:155]
	ds_read_b128 v[152:155], v152
	ds_read_b128 v[214:217], v194
	s_waitcnt lgkmcnt(0)
	v_pk_mul_f32 v[218:219], v[190:191], v[216:217]
	v_pk_mul_f32 v[226:227], v[192:193], v[214:215]
	v_pk_fma_f32 v[220:221], v[150:151], v[154:155], v[218:219] neg_lo:[0,0,1] neg_hi:[0,0,1]
	v_pk_fma_f32 v[218:219], v[148:149], v[152:153], v[226:227] neg_lo:[0,0,1] neg_hi:[0,0,1]
	v_pk_mul_f32 v[150:151], v[150:151], v[216:217]
	v_pk_mul_f32 v[148:149], v[148:149], v[214:215]
	v_pk_fma_f32 v[190:191], v[190:191], v[154:155], v[150:151]
	v_pk_fma_f32 v[192:193], v[192:193], v[152:153], v[148:149]
	v_mov_b64_e32 v[148:149], v[218:219]
	v_mov_b64_e32 v[152:153], v[222:223]
	v_mov_b64_e32 v[150:151], v[220:221]
	v_mov_b64_e32 v[154:155], v[224:225]
; #define LAS __attribute__((address_space(3)))
; __device__ __forceinline__ unsigned cvtpk_h(float lo, float hi) { f32x2 v = {lo, hi}; h16x2 b = __builtin_convertvector(v, h16x2); return __builtin_bit_cast(unsigned, b); }
;     __device__ __forceinline__ void operator()(const f32x4 (&acc)[2][2][4][2], const pg8::Unit& u, int wr, int wc, int fr, int fq) const {
;     ...
; #pragma unroll
;         for (int ai = 0; ai < 2; ++ai)
; #pragma unroll
;             for (int m = 0; m < 4; ++m) { const float r = rs[ai][m]; f32x4 v[2][2]; float ss = 0.f;
; #pragma unroll
;                 for (int bj = 0; bj < 2; ++bj)
; #pragma unroll
;                     for (int n = 0; n < 2; ++n) { v[bj][n] = acc[ai][bj][m][n] * r + bv[bj][n]; ss += (v[bj][n][0] * v[bj][n][0] + v[bj][n][1] * v[bj][n][1]) + (v[bj][n][2] * v[bj][n][2] + v[bj][n][3] * v[bj][n][3]); }
;                 const float rn = __builtin_amdgcn_rsqf(red4(ss, fq * 16 + fr) * (1.f / 64.f) + EPS);
; #pragma unroll
;                 for (int bj = 0; bj < 2; ++bj)
; #pragma unroll
;                     for (int n = 0; n < 2; ++n) v[bj][n] = v[bj][n] * rn * g4[bj][n];
;                 if (lat) { const unsigned t = (rbase + ai * 128 + m * 16) & (SEQ - 1);
; #pragma unroll
;                     for (int bj = 0; bj < 2; ++bj) { const unsigned pos = bj ? (t & 63u) : (t >> 6); const f32x4 cs = *(const LAS f32x4*)(ropel + pos * 16u + 4u * fq), sn = *(const LAS f32x4*)(ropel + 1024u + pos * 16u + 4u * fq);
;                         const f32x4 x1 = v[bj][0], x2 = v[bj][1]; v[bj][0] = x1 * cs - x2 * sn; v[bj][1] = x2 * cs + x1 * sn; } }
;                 const unsigned ro = offA + (unsigned)(ai * 8 + m) * 32u * pitch;
;                 u32x4 w[2];
; #pragma unroll
;                 for (int bj = 0; bj < 2; ++bj) { w[bj].x = cvtpk_h(v[bj][0][0], v[bj][0][1]); w[bj].y = cvtpk_h(v[bj][0][2], v[bj][0][3]); w[bj].z = cvtpk_h(v[bj][1][0], v[bj][1][1]); w[bj].w = cvtpk_h(v[bj][1][2], v[bj][1][3]); }
;                 stg_line_pair(wst, ro, 2u * pitch, w[0], w[1], odd);
;                 asm volatile("" ::: "memory"); }
.LBB0_581:
	v_cvt_pk_f16_f32 v152, v152, v153
	v_cvt_pk_f16_f32 v153, v154, v155
	v_cvt_pk_f16_f32 v154, v188, v189
	v_cvt_pk_f16_f32 v149, v148, v149
	v_mov_b32_e32 v148, v1
	v_mov_b32_e32 v188, v1
	v_cvt_pk_f16_f32 v150, v150, v151
	v_mov_b32_dpp v148, v149 quad_perm:[1,0,3,2] row_mask:0xf bank_mask:0xf
	v_mov_b32_dpp v188, v152 quad_perm:[1,0,3,2] row_mask:0xf bank_mask:0xf
	v_cndmask_b32_e64 v148, v148, v152, s[2:3]
	v_cndmask_b32_e64 v152, v149, v188, s[2:3]
	v_mov_b32_e32 v149, v1
	v_mov_b32_e32 v188, v1
	v_cvt_pk_f16_f32 v151, v192, v193
	v_mov_b32_dpp v149, v150 quad_perm:[1,0,3,2] row_mask:0xf bank_mask:0xf
	v_mov_b32_dpp v188, v153 quad_perm:[1,0,3,2] row_mask:0xf bank_mask:0xf
	v_cndmask_b32_e64 v149, v149, v153, s[2:3]
	v_cndmask_b32_e64 v153, v150, v188, s[2:3]
	v_mov_b32_e32 v150, v1
	v_mov_b32_e32 v188, v1
	v_cvt_pk_f16_f32 v155, v186, v187
	v_mov_b32_dpp v150, v151 quad_perm:[1,0,3,2] row_mask:0xf bank_mask:0xf
	v_mov_b32_dpp v188, v154 quad_perm:[1,0,3,2] row_mask:0xf bank_mask:0xf
	v_cvt_pk_f16_f32 v186, v190, v191
	v_cndmask_b32_e64 v150, v150, v154, s[2:3]
	v_cndmask_b32_e64 v154, v151, v188, s[2:3]
	v_mov_b32_e32 v151, v1
	v_mov_b32_e32 v188, v1
	v_lshl_add_u32 v187, 64, s42, v206
	v_mov_b32_dpp v151, v186 quad_perm:[1,0,3,2] row_mask:0xf bank_mask:0xf
	v_mov_b32_dpp v188, v155 quad_perm:[1,0,3,2] row_mask:0xf bank_mask:0xf
	v_cndmask_b32_e64 v151, v151, v155, s[2:3]
	v_cndmask_b32_e64 v155, v186, v188, s[2:3]
	s_mov_b32 s100, 2
	global_store_dwordx4 v187, v[148:151], s[36:37] sc1
	v_add_u32_e32 v194, 48, v202
	v_and_b32_e32 v210, 63, v194
	v_add_u32_e32 v148, s9, v187
	s_mov_b32 s100, 2
	global_store_dwordx4 v148, v[152:155], s[36:37] sc1
	v_mov_b32_e32 v148, v175
	v_pk_fma_f32 v[150:151], v[40:41], v[148:149], v[138:139] op_sel_hi:[1,0,1]
	v_pk_fma_f32 v[152:153], v[38:39], v[148:149], v[136:137] op_sel_hi:[1,0,1]
	v_mul_f32_e32 v154, v151, v151
	v_mul_f32_e32 v149, v153, v153
	v_fmac_f32_e32 v149, v152, v152
	v_fmac_f32_e32 v154, v150, v150
	v_add_f32_e32 v149, v149, v154
	v_pk_fma_f32 v[186:187], v[36:37], v[148:149], v[134:135] op_sel_hi:[1,0,1]
	v_pk_fma_f32 v[188:189], v[34:35], v[148:149], v[132:133] op_sel_hi:[1,0,1]
	v_mul_f32_e32 v155, v187, v187
	v_mul_f32_e32 v154, v189, v189
	v_fmac_f32_e32 v154, v188, v188
	v_fmac_f32_e32 v155, v186, v186
	v_add_f32_e32 v154, v154, v155
	v_add_f32_e32 v149, v149, v154
	v_pk_fma_f32 v[190:191], v[104:105], v[148:149], v[142:143] op_sel_hi:[1,0,1]
	v_pk_fma_f32 v[192:193], v[102:103], v[148:149], v[140:141] op_sel_hi:[1,0,1]
	v_mul_f32_e32 v155, v191, v191
	v_mul_f32_e32 v154, v193, v193
	v_fmac_f32_e32 v154, v192, v192
	v_fmac_f32_e32 v155, v190, v190
	v_add_f32_e32 v154, v154, v155
	v_add_f32_e32 v149, v149, v154
	v_pk_fma_f32 v[214:215], v[100:101], v[148:149], v[146:147] op_sel_hi:[1,0,1]
	v_pk_fma_f32 v[216:217], v[98:99], v[148:149], v[144:145] op_sel_hi:[1,0,1]
	v_mul_f32_e32 v154, v215, v215
	v_mul_f32_e32 v148, v217, v217
	v_fmac_f32_e32 v148, v216, v216
	v_fmac_f32_e32 v154, v214, v214
	v_add_f32_e32 v148, v148, v154
	v_add_f32_e32 v148, v149, v148
	v_mov_b32_e32 v149, v148
	s_nop 1
	v_permlane16_swap_b32_e32 v148, v149
	v_add_f32_e32 v148, v148, v149
	v_mov_b32_e32 v149, v148
	s_nop 1
	v_permlane32_swap_b32_e32 v148, v149
	v_add_f32_e32 v148, v148, v149
	v_fmamk_f32 v148, v148, 0x3c800000, v229
	v_rsq_f32_e32 v194, v148
	s_and_b64 vcc, exec, s[4:5]
	v_pk_mul_f32 v[148:149], v[152:153], v[194:195] op_sel_hi:[1,0]
	v_pk_mul_f32 v[150:151], v[150:151], v[194:195] op_sel_hi:[1,0]
	v_pk_mul_f32 v[152:153], v[184:185], v[148:149]
	v_pk_mul_f32 v[154:155], v[182:183], v[150:151]
	v_pk_mul_f32 v[148:149], v[188:189], v[194:195] op_sel_hi:[1,0]
	v_pk_mul_f32 v[150:151], v[186:187], v[194:195] op_sel_hi:[1,0]
	v_pk_mul_f32 v[188:189], v[180:181], v[148:149]
	v_pk_mul_f32 v[186:187], v[178:179], v[150:151]
	v_pk_mul_f32 v[148:149], v[192:193], v[194:195] op_sel_hi:[1,0]
	v_pk_mul_f32 v[150:151], v[190:191], v[194:195] op_sel_hi:[1,0]
	v_pk_mul_f32 v[192:193], v[216:217], v[194:195] op_sel_hi:[1,0]
	v_pk_mul_f32 v[190:191], v[214:215], v[194:195] op_sel_hi:[1,0]
	v_pk_mul_f32 v[150:151], v[160:161], v[150:151]
	v_pk_mul_f32 v[148:149], v[162:163], v[148:149]
	v_pk_mul_f32 v[190:191], v[156:157], v[190:191]
	v_pk_mul_f32 v[192:193], v[158:159], v[192:193]
	v_lshlrev_b32_e32 v194, 6, v210
	s_cbranch_vccnz .LBB0_583
	v_add_u32_e32 v210, 48, v201
	v_and_b32_e32 v210, 0x7c0, v210
	v_add_u32_e32 v211, v205, v210
	v_add_u32_e32 v210, v204, v210
	ds_read_b128 v[214:217], v211
	ds_read_b128 v[218:221], v210
	v_add_u32_e32 v210, v204, v194
	s_waitcnt lgkmcnt(0)
	v_pk_mul_f32 v[222:223], v[186:187], v[220:221]
	v_pk_mul_f32 v[226:227], v[188:189], v[218:219]
	v_pk_fma_f32 v[224:225], v[154:155], v[216:217], v[222:223] neg_lo:[0,0,1] neg_hi:[0,0,1]
	v_pk_fma_f32 v[222:223], v[152:153], v[214:215], v[226:227] neg_lo:[0,0,1] neg_hi:[0,0,1]
	v_pk_mul_f32 v[152:153], v[152:153], v[218:219]
	v_pk_mul_f32 v[154:155], v[154:155], v[220:221]
	v_pk_fma_f32 v[188:189], v[188:189], v[214:215], v[152:153]
	v_add_u32_e32 v152, v205, v194
	v_pk_fma_f32 v[186:187], v[186:187], v[216:217], v[154:155]
	ds_read_b128 v[152:155], v152
	ds_read_b128 v[214:217], v210
	s_waitcnt lgkmcnt(0)
	v_pk_mul_f32 v[218:219], v[190:191], v[216:217]
	v_pk_mul_f32 v[226:227], v[192:193], v[214:215]
	v_pk_fma_f32 v[220:221], v[150:151], v[154:155], v[218:219] neg_lo:[0,0,1] neg_hi:[0,0,1]
	v_pk_fma_f32 v[218:219], v[148:149], v[152:153], v[226:227] neg_lo:[0,0,1] neg_hi:[0,0,1]
	v_pk_mul_f32 v[150:151], v[150:151], v[216:217]
	v_pk_mul_f32 v[148:149], v[148:149], v[214:215]
	v_pk_fma_f32 v[190:191], v[190:191], v[154:155], v[150:151]
	v_pk_fma_f32 v[192:193], v[192:193], v[152:153], v[148:149]
	v_mov_b64_e32 v[148:149], v[218:219]
	v_mov_b64_e32 v[152:153], v[222:223]
	v_mov_b64_e32 v[150:151], v[220:221]
	v_mov_b64_e32 v[154:155], v[224:225]
; #define LAS __attribute__((address_space(3)))
; __device__ __forceinline__ unsigned cvtpk_h(float lo, float hi) { f32x2 v = {lo, hi}; h16x2 b = __builtin_convertvector(v, h16x2); return __builtin_bit_cast(unsigned, b); }
;     __device__ __forceinline__ void operator()(const f32x4 (&acc)[2][2][4][2], const pg8::Unit& u, int wr, int wc, int fr, int fq) const {
;     ...
; #pragma unroll
;         for (int ai = 0; ai < 2; ++ai)
; #pragma unroll
;             for (int m = 0; m < 4; ++m) { const float r = rs[ai][m]; f32x4 v[2][2]; float ss = 0.f;
; #pragma unroll
;                 for (int bj = 0; bj < 2; ++bj)
; #pragma unroll
;                     for (int n = 0; n < 2; ++n) { v[bj][n] = acc[ai][bj][m][n] * r + bv[bj][n]; ss += (v[bj][n][0] * v[bj][n][0] + v[bj][n][1] * v[bj][n][1]) + (v[bj][n][2] * v[bj][n][2] + v[bj][n][3] * v[bj][n][3]); }
;                 const float rn = __builtin_amdgcn_rsqf(red4(ss, fq * 16 + fr) * (1.f / 64.f) + EPS);
; #pragma unroll
;                 for (int bj = 0; bj < 2; ++bj)
; #pragma unroll
;                     for (int n = 0; n < 2; ++n) v[bj][n] = v[bj][n] * rn * g4[bj][n];
;                 if (lat) { const unsigned t = (rbase + ai * 128 + m * 16) & (SEQ - 1);
; #pragma unroll
;                     for (int bj = 0; bj < 2; ++bj) { const unsigned pos = bj ? (t & 63u) : (t >> 6); const f32x4 cs = *(const LAS f32x4*)(ropel + pos * 16u + 4u * fq), sn = *(const LAS f32x4*)(ropel + 1024u + pos * 16u + 4u * fq);
;                         const f32x4 x1 = v[bj][0], x2 = v[bj][1]; v[bj][0] = x1 * cs - x2 * sn; v[bj][1] = x2 * cs + x1 * sn; } }
;                 const unsigned ro = offA + (unsigned)(ai * 8 + m) * 32u * pitch;
;                 u32x4 w[2];
; #pragma unroll
;                 for (int bj = 0; bj < 2; ++bj) { w[bj].x = cvtpk_h(v[bj][0][0], v[bj][0][1]); w[bj].y = cvtpk_h(v[bj][0][2], v[bj][0][3]); w[bj].z = cvtpk_h(v[bj][1][0], v[bj][1][1]); w[bj].w = cvtpk_h(v[bj][1][2], v[bj][1][3]); }
;                 stg_line_pair(wst, ro, 2u * pitch, w[0], w[1], odd);
;                 asm volatile("" ::: "memory"); }
.LBB0_583:
	v_cvt_pk_f16_f32 v152, v152, v153
	v_cvt_pk_f16_f32 v153, v154, v155
	v_cvt_pk_f16_f32 v154, v188, v189
	v_cvt_pk_f16_f32 v149, v148, v149
	v_mov_b32_e32 v148, v1
	v_mov_b32_e32 v188, v1
	v_cvt_pk_f16_f32 v150, v150, v151
	v_mov_b32_dpp v148, v149 quad_perm:[1,0,3,2] row_mask:0xf bank_mask:0xf
	v_mov_b32_dpp v188, v152 quad_perm:[1,0,3,2] row_mask:0xf bank_mask:0xf
	v_cndmask_b32_e64 v148, v148, v152, s[2:3]
	v_cndmask_b32_e64 v152, v149, v188, s[2:3]
	v_mov_b32_e32 v149, v1
	v_mov_b32_e32 v188, v1
	v_cvt_pk_f16_f32 v151, v192, v193
	v_mov_b32_dpp v149, v150 quad_perm:[1,0,3,2] row_mask:0xf bank_mask:0xf
	v_mov_b32_dpp v188, v153 quad_perm:[1,0,3,2] row_mask:0xf bank_mask:0xf
	v_cndmask_b32_e64 v149, v149, v153, s[2:3]
	v_cndmask_b32_e64 v153, v150, v188, s[2:3]
	v_mov_b32_e32 v150, v1
	v_mov_b32_e32 v188, v1
	v_cvt_pk_f16_f32 v155, v186, v187
	v_mov_b32_dpp v150, v151 quad_perm:[1,0,3,2] row_mask:0xf bank_mask:0xf
	v_mov_b32_dpp v188, v154 quad_perm:[1,0,3,2] row_mask:0xf bank_mask:0xf
	v_cvt_pk_f16_f32 v186, v190, v191
	v_cndmask_b32_e64 v150, v150, v154, s[2:3]
	v_cndmask_b32_e64 v154, v151, v188, s[2:3]
	v_mov_b32_e32 v151, v1
	s_lshl_b32 s38, 0x60, s42
	v_mov_b32_e32 v188, v1
	v_mov_b32_dpp v151, v186 quad_perm:[1,0,3,2] row_mask:0xf bank_mask:0xf
	v_add_u32_e32 v187, s38, v206
	v_mov_b32_dpp v188, v155 quad_perm:[1,0,3,2] row_mask:0xf bank_mask:0xf
	v_cndmask_b32_e64 v151, v151, v155, s[2:3]
	v_cndmask_b32_e64 v155, v186, v188, s[2:3]
	s_mov_b32 s100, 2
	global_store_dwordx4 v187, v[148:151], s[36:37] sc1
	v_pk_fma_f32 v[188:189], v[26:27], v[172:173], v[132:133] op_sel_hi:[1,0,1]
	v_pk_fma_f32 v[190:191], v[96:97], v[172:173], v[142:143] op_sel_hi:[1,0,1]
	v_add_u32_e32 v148, s9, v187
	s_mov_b32 s100, 2
	global_store_dwordx4 v148, v[152:155], s[36:37] sc1
	v_pk_fma_f32 v[148:149], v[32:33], v[172:173], v[138:139] op_sel_hi:[1,0,1]
	v_pk_fma_f32 v[150:151], v[30:31], v[172:173], v[136:137] op_sel_hi:[1,0,1]
	v_mul_f32_e32 v153, v149, v149
	v_mul_f32_e32 v152, v151, v151
	v_fmac_f32_e32 v152, v150, v150
	v_fmac_f32_e32 v153, v148, v148
	v_pk_fma_f32 v[186:187], v[28:29], v[172:173], v[134:135] op_sel_hi:[1,0,1]
	v_add_f32_e32 v152, v152, v153
	v_mul_f32_e32 v153, v189, v189
	v_mul_f32_e32 v154, v187, v187
	v_fmac_f32_e32 v153, v188, v188
	v_fmac_f32_e32 v154, v186, v186
	v_add_f32_e32 v153, v153, v154
	v_pk_fma_f32 v[192:193], v[94:95], v[172:173], v[140:141] op_sel_hi:[1,0,1]
	v_add_f32_e32 v152, v152, v153
	v_mul_f32_e32 v153, v193, v193
	v_mul_f32_e32 v154, v191, v191
	v_fmac_f32_e32 v153, v192, v192
	v_fmac_f32_e32 v154, v190, v190
	v_add_f32_e32 v153, v153, v154
	v_pk_fma_f32 v[214:215], v[92:93], v[172:173], v[146:147] op_sel_hi:[1,0,1]
	v_pk_fma_f32 v[216:217], v[90:91], v[172:173], v[144:145] op_sel_hi:[1,0,1]
	v_add_f32_e32 v152, v153, v152
	v_mul_f32_e32 v153, v217, v217
	v_mul_f32_e32 v154, v215, v215
	v_fmac_f32_e32 v153, v216, v216
	v_fmac_f32_e32 v154, v214, v214
	v_add_f32_e32 v153, v153, v154
	v_add_f32_e32 v152, v153, v152
	v_mov_b32_e32 v153, v152
	s_nop 1
	v_permlane16_swap_b32_e32 v152, v153
	v_add_f32_e32 v152, v152, v153
	v_mov_b32_e32 v153, v152
	s_nop 1
	v_permlane32_swap_b32_e32 v152, v153
	v_add_f32_e32 v152, v152, v153
	v_fmamk_f32 v152, v152, 0x3c800000, v229
	v_rsq_f32_e32 v218, v152
	s_and_b64 vcc, exec, s[4:5]
	v_pk_mul_f32 v[150:151], v[150:151], v[218:219] op_sel_hi:[1,0]
	v_pk_mul_f32 v[148:149], v[148:149], v[218:219] op_sel_hi:[1,0]
	v_pk_mul_f32 v[152:153], v[184:185], v[150:151]
	v_pk_mul_f32 v[154:155], v[182:183], v[148:149]
	v_pk_mul_f32 v[148:149], v[188:189], v[218:219] op_sel_hi:[1,0]
	v_pk_mul_f32 v[150:151], v[186:187], v[218:219] op_sel_hi:[1,0]
	v_pk_mul_f32 v[188:189], v[180:181], v[148:149]
	v_pk_mul_f32 v[186:187], v[178:179], v[150:151]
	v_pk_mul_f32 v[148:149], v[192:193], v[218:219] op_sel_hi:[1,0]
	v_pk_mul_f32 v[150:151], v[190:191], v[218:219] op_sel_hi:[1,0]
	v_pk_mul_f32 v[192:193], v[216:217], v[218:219] op_sel_hi:[1,0]
	v_pk_mul_f32 v[190:191], v[214:215], v[218:219] op_sel_hi:[1,0]
	v_pk_mul_f32 v[150:151], v[160:161], v[150:151]
	v_pk_mul_f32 v[148:149], v[162:163], v[148:149]
	v_pk_mul_f32 v[190:191], v[156:157], v[190:191]
	v_pk_mul_f32 v[192:193], v[158:159], v[192:193]
	s_cbranch_vccnz .LBB0_585
	v_add_u32_e32 v210, 0x80, v201
	v_and_b32_e32 v210, 0x7c0, v210
	v_add_u32_e32 v211, v205, v210
	v_add_u32_e32 v210, v204, v210
	ds_read_b128 v[214:217], v211
	ds_read_b128 v[218:221], v210
	s_waitcnt lgkmcnt(0)
	v_pk_mul_f32 v[222:223], v[186:187], v[220:221]
	v_pk_mul_f32 v[226:227], v[188:189], v[218:219]
	v_pk_fma_f32 v[224:225], v[154:155], v[216:217], v[222:223] neg_lo:[0,0,1] neg_hi:[0,0,1]
	v_pk_fma_f32 v[222:223], v[152:153], v[214:215], v[226:227] neg_lo:[0,0,1] neg_hi:[0,0,1]
	v_pk_mul_f32 v[152:153], v[152:153], v[218:219]
	v_pk_mul_f32 v[154:155], v[154:155], v[220:221]
	v_pk_fma_f32 v[188:189], v[188:189], v[214:215], v[152:153]
	v_add_u32_e32 v152, v205, v207
	v_add_u32_e32 v207, v204, v207
	v_pk_fma_f32 v[186:187], v[186:187], v[216:217], v[154:155]
	ds_read_b128 v[152:155], v152
	ds_read_b128 v[214:217], v207
	s_waitcnt lgkmcnt(0)
	v_pk_mul_f32 v[218:219], v[190:191], v[216:217]
	v_pk_mul_f32 v[226:227], v[192:193], v[214:215]
	v_pk_fma_f32 v[220:221], v[150:151], v[154:155], v[218:219] neg_lo:[0,0,1] neg_hi:[0,0,1]
	v_pk_fma_f32 v[218:219], v[148:149], v[152:153], v[226:227] neg_lo:[0,0,1] neg_hi:[0,0,1]
	v_pk_mul_f32 v[150:151], v[150:151], v[216:217]
	v_pk_mul_f32 v[148:149], v[148:149], v[214:215]
	v_pk_fma_f32 v[190:191], v[190:191], v[154:155], v[150:151]
	v_pk_fma_f32 v[192:193], v[192:193], v[152:153], v[148:149]
	v_mov_b64_e32 v[148:149], v[218:219]
	v_mov_b64_e32 v[152:153], v[222:223]
	v_mov_b64_e32 v[150:151], v[220:221]
	v_mov_b64_e32 v[154:155], v[224:225]
; #define LAS __attribute__((address_space(3)))
; __device__ __forceinline__ unsigned cvtpk_h(float lo, float hi) { f32x2 v = {lo, hi}; h16x2 b = __builtin_convertvector(v, h16x2); return __builtin_bit_cast(unsigned, b); }
;     __device__ __forceinline__ void operator()(const f32x4 (&acc)[2][2][4][2], const pg8::Unit& u, int wr, int wc, int fr, int fq) const {
;     ...
; #pragma unroll
;         for (int ai = 0; ai < 2; ++ai)
; #pragma unroll
;             for (int m = 0; m < 4; ++m) { const float r = rs[ai][m]; f32x4 v[2][2]; float ss = 0.f;
; #pragma unroll
;                 for (int bj = 0; bj < 2; ++bj)
; #pragma unroll
;                     for (int n = 0; n < 2; ++n) { v[bj][n] = acc[ai][bj][m][n] * r + bv[bj][n]; ss += (v[bj][n][0] * v[bj][n][0] + v[bj][n][1] * v[bj][n][1]) + (v[bj][n][2] * v[bj][n][2] + v[bj][n][3] * v[bj][n][3]); }
;                 const float rn = __builtin_amdgcn_rsqf(red4(ss, fq * 16 + fr) * (1.f / 64.f) + EPS);
; #pragma unroll
;                 for (int bj = 0; bj < 2; ++bj)
; #pragma unroll
;                     for (int n = 0; n < 2; ++n) v[bj][n] = v[bj][n] * rn * g4[bj][n];
;                 if (lat) { const unsigned t = (rbase + ai * 128 + m * 16) & (SEQ - 1);
; #pragma unroll
;                     for (int bj = 0; bj < 2; ++bj) { const unsigned pos = bj ? (t & 63u) : (t >> 6); const f32x4 cs = *(const LAS f32x4*)(ropel + pos * 16u + 4u * fq), sn = *(const LAS f32x4*)(ropel + 1024u + pos * 16u + 4u * fq);
;                         const f32x4 x1 = v[bj][0], x2 = v[bj][1]; v[bj][0] = x1 * cs - x2 * sn; v[bj][1] = x2 * cs + x1 * sn; } }
;                 const unsigned ro = offA + (unsigned)(ai * 8 + m) * 32u * pitch;
;                 u32x4 w[2];
; #pragma unroll
;                 for (int bj = 0; bj < 2; ++bj) { w[bj].x = cvtpk_h(v[bj][0][0], v[bj][0][1]); w[bj].y = cvtpk_h(v[bj][0][2], v[bj][0][3]); w[bj].z = cvtpk_h(v[bj][1][0], v[bj][1][1]); w[bj].w = cvtpk_h(v[bj][1][2], v[bj][1][3]); }
;                 stg_line_pair(wst, ro, 2u * pitch, w[0], w[1], odd);
;                 asm volatile("" ::: "memory"); }
.LBB0_585:
	v_cvt_pk_f16_f32 v152, v152, v153
	v_cvt_pk_f16_f32 v153, v154, v155
	v_cvt_pk_f16_f32 v154, v188, v189
	v_cvt_pk_f16_f32 v149, v148, v149
	v_mov_b32_e32 v148, v1
	v_mov_b32_e32 v188, v1
	v_cvt_pk_f16_f32 v150, v150, v151
	v_mov_b32_dpp v148, v149 quad_perm:[1,0,3,2] row_mask:0xf bank_mask:0xf
	v_mov_b32_dpp v188, v152 quad_perm:[1,0,3,2] row_mask:0xf bank_mask:0xf
	v_cndmask_b32_e64 v148, v148, v152, s[2:3]
	v_cndmask_b32_e64 v152, v149, v188, s[2:3]
	v_mov_b32_e32 v149, v1
	v_mov_b32_e32 v188, v1
	v_cvt_pk_f16_f32 v151, v192, v193
	v_mov_b32_dpp v149, v150 quad_perm:[1,0,3,2] row_mask:0xf bank_mask:0xf
	v_mov_b32_dpp v188, v153 quad_perm:[1,0,3,2] row_mask:0xf bank_mask:0xf
	v_cndmask_b32_e64 v149, v149, v153, s[2:3]
	v_cndmask_b32_e64 v153, v150, v188, s[2:3]
	v_mov_b32_e32 v150, v1
	v_mov_b32_e32 v188, v1
	v_cvt_pk_f16_f32 v155, v186, v187
	v_mov_b32_dpp v150, v151 quad_perm:[1,0,3,2] row_mask:0xf bank_mask:0xf
	v_mov_b32_dpp v188, v154 quad_perm:[1,0,3,2] row_mask:0xf bank_mask:0xf
	v_cvt_pk_f16_f32 v186, v190, v191
	v_cndmask_b32_e64 v150, v150, v154, s[2:3]
	v_cndmask_b32_e64 v154, v151, v188, s[2:3]
	v_mov_b32_e32 v151, v1
	s_lshl_b32 s38, 0x100, s42
	v_mov_b32_e32 v188, v1
	v_mov_b32_dpp v151, v186 quad_perm:[1,0,3,2] row_mask:0xf bank_mask:0xf
	v_add_u32_e32 v187, s38, v206
	v_mov_b32_dpp v188, v155 quad_perm:[1,0,3,2] row_mask:0xf bank_mask:0xf
	v_cndmask_b32_e64 v151, v151, v155, s[2:3]
	v_cndmask_b32_e64 v155, v186, v188, s[2:3]
	s_mov_b32 s100, 2
	global_store_dwordx4 v187, v[148:151], s[36:37] sc1
	s_and_b64 vcc, exec, s[4:5]
	s_nop 0
	v_add_u32_e32 v148, s9, v187
	s_mov_b32 s100, 2
	global_store_dwordx4 v148, v[152:155], s[36:37] sc1
	v_mov_b32_e32 v148, v173
	v_pk_fma_f32 v[150:151], v[24:25], v[148:149], v[138:139] op_sel_hi:[1,0,1]
	v_pk_fma_f32 v[152:153], v[22:23], v[148:149], v[136:137] op_sel_hi:[1,0,1]
	v_mul_f32_e32 v154, v151, v151
	v_mul_f32_e32 v149, v153, v153
	v_fmac_f32_e32 v149, v152, v152
	v_fmac_f32_e32 v154, v150, v150
	v_add_f32_e32 v149, v149, v154
	v_pk_fma_f32 v[186:187], v[20:21], v[148:149], v[134:135] op_sel_hi:[1,0,1]
	v_pk_fma_f32 v[188:189], v[18:19], v[148:149], v[132:133] op_sel_hi:[1,0,1]
	v_mul_f32_e32 v155, v187, v187
	v_mul_f32_e32 v154, v189, v189
	v_fmac_f32_e32 v154, v188, v188
	v_fmac_f32_e32 v155, v186, v186
	v_add_f32_e32 v154, v154, v155
	v_add_f32_e32 v149, v149, v154
	v_pk_fma_f32 v[190:191], v[88:89], v[148:149], v[142:143] op_sel_hi:[1,0,1]
	v_pk_fma_f32 v[192:193], v[86:87], v[148:149], v[140:141] op_sel_hi:[1,0,1]
	v_mul_f32_e32 v155, v191, v191
	v_mul_f32_e32 v154, v193, v193
	v_fmac_f32_e32 v154, v192, v192
	v_fmac_f32_e32 v155, v190, v190
	v_add_f32_e32 v154, v154, v155
	v_add_f32_e32 v149, v154, v149
	v_pk_fma_f32 v[214:215], v[84:85], v[148:149], v[146:147] op_sel_hi:[1,0,1]
	v_pk_fma_f32 v[216:217], v[82:83], v[148:149], v[144:145] op_sel_hi:[1,0,1]
	v_mul_f32_e32 v154, v215, v215
	v_mul_f32_e32 v148, v217, v217
	v_fmac_f32_e32 v148, v216, v216
	v_fmac_f32_e32 v154, v214, v214
	v_add_f32_e32 v148, v148, v154
	v_add_f32_e32 v148, v148, v149
	v_mov_b32_e32 v149, v148
	s_nop 1
	v_permlane16_swap_b32_e32 v148, v149
	v_add_f32_e32 v148, v148, v149
	v_mov_b32_e32 v149, v148
	s_nop 1
	v_permlane32_swap_b32_e32 v148, v149
	v_add_f32_e32 v148, v148, v149
	v_fmamk_f32 v148, v148, 0x3c800000, v229
	v_rsq_f32_e32 v218, v148
	s_nop 0
	v_pk_mul_f32 v[148:149], v[152:153], v[218:219] op_sel_hi:[1,0]
	v_pk_mul_f32 v[150:151], v[150:151], v[218:219] op_sel_hi:[1,0]
	v_pk_mul_f32 v[152:153], v[184:185], v[148:149]
	v_pk_mul_f32 v[154:155], v[182:183], v[150:151]
	v_pk_mul_f32 v[148:149], v[188:189], v[218:219] op_sel_hi:[1,0]
	v_pk_mul_f32 v[150:151], v[186:187], v[218:219] op_sel_hi:[1,0]
	v_pk_mul_f32 v[188:189], v[180:181], v[148:149]
	v_pk_mul_f32 v[186:187], v[178:179], v[150:151]
	v_pk_mul_f32 v[148:149], v[192:193], v[218:219] op_sel_hi:[1,0]
	v_pk_mul_f32 v[150:151], v[190:191], v[218:219] op_sel_hi:[1,0]
	v_pk_mul_f32 v[192:193], v[216:217], v[218:219] op_sel_hi:[1,0]
	v_pk_mul_f32 v[190:191], v[214:215], v[218:219] op_sel_hi:[1,0]
	v_pk_mul_f32 v[150:151], v[160:161], v[150:151]
	v_pk_mul_f32 v[148:149], v[162:163], v[148:149]
	v_pk_mul_f32 v[190:191], v[156:157], v[190:191]
	v_pk_mul_f32 v[192:193], v[158:159], v[192:193]
	s_cbranch_vccnz .LBB0_587
	v_add_u32_e32 v207, 0x90, v201
	v_and_b32_e32 v207, 0x7c0, v207
	v_add_u32_e32 v210, v205, v207
	v_add_u32_e32 v207, v204, v207
	ds_read_b128 v[214:217], v210
	ds_read_b128 v[218:221], v207
	v_add_u32_e32 v207, v204, v213
	s_waitcnt lgkmcnt(0)
	v_pk_mul_f32 v[222:223], v[186:187], v[220:221]
	v_pk_mul_f32 v[226:227], v[188:189], v[218:219]
	v_pk_fma_f32 v[224:225], v[154:155], v[216:217], v[222:223] neg_lo:[0,0,1] neg_hi:[0,0,1]
	v_pk_fma_f32 v[222:223], v[152:153], v[214:215], v[226:227] neg_lo:[0,0,1] neg_hi:[0,0,1]
	v_pk_mul_f32 v[152:153], v[152:153], v[218:219]
	v_pk_mul_f32 v[154:155], v[154:155], v[220:221]
	v_pk_fma_f32 v[188:189], v[188:189], v[214:215], v[152:153]
	v_add_u32_e32 v152, v205, v213
	v_pk_fma_f32 v[186:187], v[186:187], v[216:217], v[154:155]
	ds_read_b128 v[152:155], v152
	ds_read_b128 v[214:217], v207
	s_waitcnt lgkmcnt(0)
	v_pk_mul_f32 v[218:219], v[190:191], v[216:217]
	v_pk_mul_f32 v[226:227], v[192:193], v[214:215]
	v_pk_fma_f32 v[220:221], v[150:151], v[154:155], v[218:219] neg_lo:[0,0,1] neg_hi:[0,0,1]
	v_pk_fma_f32 v[218:219], v[148:149], v[152:153], v[226:227] neg_lo:[0,0,1] neg_hi:[0,0,1]
	v_pk_mul_f32 v[150:151], v[150:151], v[216:217]
	v_pk_mul_f32 v[148:149], v[148:149], v[214:215]
	v_pk_fma_f32 v[190:191], v[190:191], v[154:155], v[150:151]
	v_pk_fma_f32 v[192:193], v[192:193], v[152:153], v[148:149]
	v_mov_b64_e32 v[148:149], v[218:219]
	v_mov_b64_e32 v[152:153], v[222:223]
	v_mov_b64_e32 v[150:151], v[220:221]
	v_mov_b64_e32 v[154:155], v[224:225]
; #define LAS __attribute__((address_space(3)))
; __device__ __forceinline__ unsigned cvtpk_h(float lo, float hi) { f32x2 v = {lo, hi}; h16x2 b = __builtin_convertvector(v, h16x2); return __builtin_bit_cast(unsigned, b); }
;     __device__ __forceinline__ void operator()(const f32x4 (&acc)[2][2][4][2], const pg8::Unit& u, int wr, int wc, int fr, int fq) const {
;     ...
; #pragma unroll
;         for (int ai = 0; ai < 2; ++ai)
; #pragma unroll
;             for (int m = 0; m < 4; ++m) { const float r = rs[ai][m]; f32x4 v[2][2]; float ss = 0.f;
; #pragma unroll
;                 for (int bj = 0; bj < 2; ++bj)
; #pragma unroll
;                     for (int n = 0; n < 2; ++n) { v[bj][n] = acc[ai][bj][m][n] * r + bv[bj][n]; ss += (v[bj][n][0] * v[bj][n][0] + v[bj][n][1] * v[bj][n][1]) + (v[bj][n][2] * v[bj][n][2] + v[bj][n][3] * v[bj][n][3]); }
;                 const float rn = __builtin_amdgcn_rsqf(red4(ss, fq * 16 + fr) * (1.f / 64.f) + EPS);
; #pragma unroll
;                 for (int bj = 0; bj < 2; ++bj)
; #pragma unroll
;                     for (int n = 0; n < 2; ++n) v[bj][n] = v[bj][n] * rn * g4[bj][n];
;                 if (lat) { const unsigned t = (rbase + ai * 128 + m * 16) & (SEQ - 1);
; #pragma unroll
;                     for (int bj = 0; bj < 2; ++bj) { const unsigned pos = bj ? (t & 63u) : (t >> 6); const f32x4 cs = *(const LAS f32x4*)(ropel + pos * 16u + 4u * fq), sn = *(const LAS f32x4*)(ropel + 1024u + pos * 16u + 4u * fq);
;                         const f32x4 x1 = v[bj][0], x2 = v[bj][1]; v[bj][0] = x1 * cs - x2 * sn; v[bj][1] = x2 * cs + x1 * sn; } }
;                 const unsigned ro = offA + (unsigned)(ai * 8 + m) * 32u * pitch;
;                 u32x4 w[2];
; #pragma unroll
;                 for (int bj = 0; bj < 2; ++bj) { w[bj].x = cvtpk_h(v[bj][0][0], v[bj][0][1]); w[bj].y = cvtpk_h(v[bj][0][2], v[bj][0][3]); w[bj].z = cvtpk_h(v[bj][1][0], v[bj][1][1]); w[bj].w = cvtpk_h(v[bj][1][2], v[bj][1][3]); }
;                 stg_line_pair(wst, ro, 2u * pitch, w[0], w[1], odd);
;                 asm volatile("" ::: "memory"); }
.LBB0_587:
	v_cvt_pk_f16_f32 v152, v152, v153
	v_cvt_pk_f16_f32 v153, v154, v155
	v_cvt_pk_f16_f32 v154, v188, v189
	v_cvt_pk_f16_f32 v149, v148, v149
	v_mov_b32_e32 v148, v1
	v_mov_b32_e32 v188, v1
	v_cvt_pk_f16_f32 v150, v150, v151
	v_mov_b32_dpp v148, v149 quad_perm:[1,0,3,2] row_mask:0xf bank_mask:0xf
	v_mov_b32_dpp v188, v152 quad_perm:[1,0,3,2] row_mask:0xf bank_mask:0xf
	v_cndmask_b32_e64 v148, v148, v152, s[2:3]
	v_cndmask_b32_e64 v152, v149, v188, s[2:3]
	v_mov_b32_e32 v149, v1
	v_mov_b32_e32 v188, v1
	v_cvt_pk_f16_f32 v151, v192, v193
	v_mov_b32_dpp v149, v150 quad_perm:[1,0,3,2] row_mask:0xf bank_mask:0xf
	v_mov_b32_dpp v188, v153 quad_perm:[1,0,3,2] row_mask:0xf bank_mask:0xf
	v_cndmask_b32_e64 v149, v149, v153, s[2:3]
	v_cndmask_b32_e64 v153, v150, v188, s[2:3]
	v_mov_b32_e32 v150, v1
	v_mov_b32_e32 v188, v1
	v_cvt_pk_f16_f32 v155, v186, v187
	v_mov_b32_dpp v150, v151 quad_perm:[1,0,3,2] row_mask:0xf bank_mask:0xf
	v_mov_b32_dpp v188, v154 quad_perm:[1,0,3,2] row_mask:0xf bank_mask:0xf
	v_cvt_pk_f16_f32 v186, v190, v191
	v_cndmask_b32_e64 v150, v150, v154, s[2:3]
	v_cndmask_b32_e64 v154, v151, v188, s[2:3]
	v_mov_b32_e32 v151, v1
	s_lshl_b32 s38, 0x120, s42
	v_mov_b32_e32 v188, v1
	v_mov_b32_dpp v151, v186 quad_perm:[1,0,3,2] row_mask:0xf bank_mask:0xf
	v_add_u32_e32 v187, s38, v206
	v_mov_b32_dpp v188, v155 quad_perm:[1,0,3,2] row_mask:0xf bank_mask:0xf
	v_cndmask_b32_e64 v151, v151, v155, s[2:3]
	v_cndmask_b32_e64 v155, v186, v188, s[2:3]
	s_mov_b32 s100, 2
	global_store_dwordx4 v187, v[148:151], s[36:37] sc1
	v_pk_fma_f32 v[188:189], v[10:11], v[170:171], v[132:133] op_sel_hi:[1,0,1]
	v_pk_fma_f32 v[190:191], v[80:81], v[170:171], v[142:143] op_sel_hi:[1,0,1]
	v_add_u32_e32 v148, s9, v187
	s_mov_b32 s100, 2
	global_store_dwordx4 v148, v[152:155], s[36:37] sc1
	v_pk_fma_f32 v[148:149], v[16:17], v[170:171], v[138:139] op_sel_hi:[1,0,1]
	v_pk_fma_f32 v[150:151], v[14:15], v[170:171], v[136:137] op_sel_hi:[1,0,1]
	v_mul_f32_e32 v153, v149, v149
	v_mul_f32_e32 v152, v151, v151
	v_fmac_f32_e32 v152, v150, v150
	v_fmac_f32_e32 v153, v148, v148
	v_pk_fma_f32 v[186:187], v[12:13], v[170:171], v[134:135] op_sel_hi:[1,0,1]
	v_add_f32_e32 v152, v152, v153
	v_mul_f32_e32 v153, v189, v189
	v_mul_f32_e32 v154, v187, v187
	v_fmac_f32_e32 v153, v188, v188
	v_fmac_f32_e32 v154, v186, v186
	v_add_f32_e32 v153, v153, v154
	v_pk_fma_f32 v[192:193], v[78:79], v[170:171], v[140:141] op_sel_hi:[1,0,1]
	v_add_f32_e32 v152, v152, v153
	v_mul_f32_e32 v153, v193, v193
	v_mul_f32_e32 v154, v191, v191
	v_fmac_f32_e32 v153, v192, v192
	v_fmac_f32_e32 v154, v190, v190
	v_add_f32_e32 v153, v153, v154
	v_pk_fma_f32 v[214:215], v[76:77], v[170:171], v[146:147] op_sel_hi:[1,0,1]
	v_pk_fma_f32 v[216:217], v[74:75], v[170:171], v[144:145] op_sel_hi:[1,0,1]
	v_add_f32_e32 v152, v153, v152
	v_mul_f32_e32 v153, v217, v217
	v_mul_f32_e32 v154, v215, v215
	v_fmac_f32_e32 v153, v216, v216
	v_fmac_f32_e32 v154, v214, v214
	v_add_f32_e32 v153, v153, v154
	v_add_f32_e32 v152, v153, v152
	v_mov_b32_e32 v153, v152
	s_nop 1
	v_permlane16_swap_b32_e32 v152, v153
	v_add_f32_e32 v152, v152, v153
	v_mov_b32_e32 v153, v152
	s_nop 1
	v_permlane32_swap_b32_e32 v152, v153
	v_add_f32_e32 v152, v152, v153
	v_fmamk_f32 v152, v152, 0x3c800000, v229
	v_rsq_f32_e32 v218, v152
	s_and_b64 vcc, exec, s[4:5]
	v_pk_mul_f32 v[150:151], v[150:151], v[218:219] op_sel_hi:[1,0]
	v_pk_mul_f32 v[148:149], v[148:149], v[218:219] op_sel_hi:[1,0]
	v_pk_mul_f32 v[152:153], v[184:185], v[150:151]
	v_pk_mul_f32 v[154:155], v[182:183], v[148:149]
	v_pk_mul_f32 v[148:149], v[188:189], v[218:219] op_sel_hi:[1,0]
	v_pk_mul_f32 v[150:151], v[186:187], v[218:219] op_sel_hi:[1,0]
	v_pk_mul_f32 v[188:189], v[180:181], v[148:149]
	v_pk_mul_f32 v[186:187], v[178:179], v[150:151]
	v_pk_mul_f32 v[148:149], v[192:193], v[218:219] op_sel_hi:[1,0]
	v_pk_mul_f32 v[150:151], v[190:191], v[218:219] op_sel_hi:[1,0]
	v_pk_mul_f32 v[192:193], v[216:217], v[218:219] op_sel_hi:[1,0]
	v_pk_mul_f32 v[190:191], v[214:215], v[218:219] op_sel_hi:[1,0]
	v_pk_mul_f32 v[150:151], v[160:161], v[150:151]
	v_pk_mul_f32 v[148:149], v[162:163], v[148:149]
	v_pk_mul_f32 v[190:191], v[156:157], v[190:191]
	v_pk_mul_f32 v[192:193], v[158:159], v[192:193]
	s_cbranch_vccnz .LBB0_589
	v_add_u32_e32 v207, 0xa0, v201
	v_and_b32_e32 v207, 0x7c0, v207
	v_add_u32_e32 v210, v205, v207
	v_add_u32_e32 v207, v204, v207
	ds_read_b128 v[214:217], v210
	ds_read_b128 v[218:221], v207
	s_waitcnt lgkmcnt(0)
	v_pk_mul_f32 v[222:223], v[186:187], v[220:221]
	v_pk_mul_f32 v[226:227], v[188:189], v[218:219]
	v_pk_fma_f32 v[224:225], v[154:155], v[216:217], v[222:223] neg_lo:[0,0,1] neg_hi:[0,0,1]
	v_pk_fma_f32 v[222:223], v[152:153], v[214:215], v[226:227] neg_lo:[0,0,1] neg_hi:[0,0,1]
	v_pk_mul_f32 v[152:153], v[152:153], v[218:219]
	v_pk_mul_f32 v[154:155], v[154:155], v[220:221]
	v_pk_fma_f32 v[188:189], v[188:189], v[214:215], v[152:153]
	v_add_u32_e32 v152, v205, v195
	v_add_u32_e32 v195, v204, v195
	v_pk_fma_f32 v[186:187], v[186:187], v[216:217], v[154:155]
	ds_read_b128 v[152:155], v152
	ds_read_b128 v[214:217], v195
	s_waitcnt lgkmcnt(0)
	v_pk_mul_f32 v[218:219], v[190:191], v[216:217]
	v_pk_mul_f32 v[226:227], v[192:193], v[214:215]
	v_pk_fma_f32 v[220:221], v[150:151], v[154:155], v[218:219] neg_lo:[0,0,1] neg_hi:[0,0,1]
	v_pk_fma_f32 v[218:219], v[148:149], v[152:153], v[226:227] neg_lo:[0,0,1] neg_hi:[0,0,1]
	v_pk_mul_f32 v[150:151], v[150:151], v[216:217]
	v_pk_mul_f32 v[148:149], v[148:149], v[214:215]
	v_pk_fma_f32 v[190:191], v[190:191], v[154:155], v[150:151]
	v_pk_fma_f32 v[192:193], v[192:193], v[152:153], v[148:149]
	v_mov_b64_e32 v[148:149], v[218:219]
	v_mov_b64_e32 v[152:153], v[222:223]
	v_mov_b64_e32 v[150:151], v[220:221]
	v_mov_b64_e32 v[154:155], v[224:225]
; #define LAS __attribute__((address_space(3)))
; __device__ __forceinline__ unsigned cvtpk_h(float lo, float hi) { f32x2 v = {lo, hi}; h16x2 b = __builtin_convertvector(v, h16x2); return __builtin_bit_cast(unsigned, b); }
;     __device__ __forceinline__ void operator()(const f32x4 (&acc)[2][2][4][2], const pg8::Unit& u, int wr, int wc, int fr, int fq) const {
;     ...
; #pragma unroll
;         for (int ai = 0; ai < 2; ++ai)
; #pragma unroll
;             for (int m = 0; m < 4; ++m) { const float r = rs[ai][m]; f32x4 v[2][2]; float ss = 0.f;
; #pragma unroll
;                 for (int bj = 0; bj < 2; ++bj)
; #pragma unroll
;                     for (int n = 0; n < 2; ++n) { v[bj][n] = acc[ai][bj][m][n] * r + bv[bj][n]; ss += (v[bj][n][0] * v[bj][n][0] + v[bj][n][1] * v[bj][n][1]) + (v[bj][n][2] * v[bj][n][2] + v[bj][n][3] * v[bj][n][3]); }
;                 const float rn = __builtin_amdgcn_rsqf(red4(ss, fq * 16 + fr) * (1.f / 64.f) + EPS);
; #pragma unroll
;                 for (int bj = 0; bj < 2; ++bj)
; #pragma unroll
;                     for (int n = 0; n < 2; ++n) v[bj][n] = v[bj][n] * rn * g4[bj][n];
;                 if (lat) { const unsigned t = (rbase + ai * 128 + m * 16) & (SEQ - 1);
; #pragma unroll
;                     for (int bj = 0; bj < 2; ++bj) { const unsigned pos = bj ? (t & 63u) : (t >> 6); const f32x4 cs = *(const LAS f32x4*)(ropel + pos * 16u + 4u * fq), sn = *(const LAS f32x4*)(ropel + 1024u + pos * 16u + 4u * fq);
;                         const f32x4 x1 = v[bj][0], x2 = v[bj][1]; v[bj][0] = x1 * cs - x2 * sn; v[bj][1] = x2 * cs + x1 * sn; } }
;                 const unsigned ro = offA + (unsigned)(ai * 8 + m) * 32u * pitch;
;                 u32x4 w[2];
; #pragma unroll
;                 for (int bj = 0; bj < 2; ++bj) { w[bj].x = cvtpk_h(v[bj][0][0], v[bj][0][1]); w[bj].y = cvtpk_h(v[bj][0][2], v[bj][0][3]); w[bj].z = cvtpk_h(v[bj][1][0], v[bj][1][1]); w[bj].w = cvtpk_h(v[bj][1][2], v[bj][1][3]); }
;                 stg_line_pair(wst, ro, 2u * pitch, w[0], w[1], odd);
;                 asm volatile("" ::: "memory"); }
.LBB0_589:
	v_cvt_pk_f16_f32 v152, v152, v153
	v_cvt_pk_f16_f32 v153, v154, v155
	v_cvt_pk_f16_f32 v154, v188, v189
	v_cvt_pk_f16_f32 v149, v148, v149
	v_mov_b32_e32 v148, v1
	v_mov_b32_e32 v188, v1
	v_cvt_pk_f16_f32 v150, v150, v151
	v_mov_b32_dpp v148, v149 quad_perm:[1,0,3,2] row_mask:0xf bank_mask:0xf
	v_mov_b32_dpp v188, v152 quad_perm:[1,0,3,2] row_mask:0xf bank_mask:0xf
	v_cndmask_b32_e64 v148, v148, v152, s[2:3]
	v_cndmask_b32_e64 v152, v149, v188, s[2:3]
	v_mov_b32_e32 v149, v1
	v_mov_b32_e32 v188, v1
	v_cvt_pk_f16_f32 v151, v192, v193
	v_mov_b32_dpp v149, v150 quad_perm:[1,0,3,2] row_mask:0xf bank_mask:0xf
	v_mov_b32_dpp v188, v153 quad_perm:[1,0,3,2] row_mask:0xf bank_mask:0xf
	v_cndmask_b32_e64 v149, v149, v153, s[2:3]
	v_cndmask_b32_e64 v153, v150, v188, s[2:3]
	v_mov_b32_e32 v150, v1
	v_mov_b32_e32 v188, v1
	v_cvt_pk_f16_f32 v155, v186, v187
	v_mov_b32_dpp v150, v151 quad_perm:[1,0,3,2] row_mask:0xf bank_mask:0xf
	v_mov_b32_dpp v188, v154 quad_perm:[1,0,3,2] row_mask:0xf bank_mask:0xf
	v_cvt_pk_f16_f32 v186, v190, v191
	v_cndmask_b32_e64 v150, v150, v154, s[2:3]
	v_cndmask_b32_e64 v154, v151, v188, s[2:3]
	v_mov_b32_e32 v151, v1
	s_lshl_b32 s38, 0x140, s42
	v_mov_b32_e32 v188, v1
	v_mov_b32_dpp v151, v186 quad_perm:[1,0,3,2] row_mask:0xf bank_mask:0xf
	v_add_u32_e32 v187, s38, v206
	v_mov_b32_dpp v188, v155 quad_perm:[1,0,3,2] row_mask:0xf bank_mask:0xf
	v_cndmask_b32_e64 v151, v151, v155, s[2:3]
	v_cndmask_b32_e64 v155, v186, v188, s[2:3]
	s_mov_b32 s100, 2
	global_store_dwordx4 v187, v[148:151], s[36:37] sc1
	s_and_b64 vcc, exec, s[4:5]
	s_nop 0
	v_add_u32_e32 v148, s9, v187
	s_mov_b32 s100, 2
	global_store_dwordx4 v148, v[152:155], s[36:37] sc1
	v_mov_b32_e32 v148, v171
	v_pk_fma_f32 v[150:151], v[8:9], v[148:149], v[138:139] op_sel_hi:[1,0,1]
	v_pk_fma_f32 v[152:153], v[6:7], v[148:149], v[136:137] op_sel_hi:[1,0,1]
	v_mul_f32_e32 v154, v151, v151
	v_mul_f32_e32 v149, v153, v153
	v_fmac_f32_e32 v149, v152, v152
	v_fmac_f32_e32 v154, v150, v150
	v_add_f32_e32 v149, v149, v154
	v_pk_fma_f32 v[186:187], v[4:5], v[148:149], v[134:135] op_sel_hi:[1,0,1]
	v_pk_fma_f32 v[188:189], v[2:3], v[148:149], v[132:133] op_sel_hi:[1,0,1]
	v_mul_f32_e32 v155, v187, v187
	v_mul_f32_e32 v154, v189, v189
	v_fmac_f32_e32 v154, v188, v188
	v_fmac_f32_e32 v155, v186, v186
	v_add_f32_e32 v154, v154, v155
	v_add_f32_e32 v149, v149, v154
	v_pk_fma_f32 v[190:191], v[64:65], v[148:149], v[142:143] op_sel_hi:[1,0,1]
	v_pk_fma_f32 v[192:193], v[62:63], v[148:149], v[140:141] op_sel_hi:[1,0,1]
	v_mul_f32_e32 v155, v191, v191
	v_mul_f32_e32 v154, v193, v193
	v_fmac_f32_e32 v154, v192, v192
	v_fmac_f32_e32 v155, v190, v190
	v_add_f32_e32 v154, v154, v155
	v_add_f32_e32 v149, v154, v149
	v_pk_fma_f32 v[214:215], v[60:61], v[148:149], v[146:147] op_sel_hi:[1,0,1]
	v_pk_fma_f32 v[216:217], v[58:59], v[148:149], v[144:145] op_sel_hi:[1,0,1]
	v_mul_f32_e32 v154, v215, v215
	v_mul_f32_e32 v148, v217, v217
	v_fmac_f32_e32 v148, v216, v216
	v_fmac_f32_e32 v154, v214, v214
	v_add_f32_e32 v148, v148, v154
	v_add_f32_e32 v148, v148, v149
	v_mov_b32_e32 v149, v148
	s_nop 1
	v_permlane16_swap_b32_e32 v148, v149
	v_add_f32_e32 v148, v148, v149
	v_mov_b32_e32 v149, v148
	s_nop 1
	v_permlane32_swap_b32_e32 v148, v149
	v_add_f32_e32 v148, v148, v149
	v_fmamk_f32 v148, v148, 0x3c800000, v229
	v_rsq_f32_e32 v218, v148
	s_nop 0
	v_pk_mul_f32 v[148:149], v[152:153], v[218:219] op_sel_hi:[1,0]
	v_pk_mul_f32 v[150:151], v[150:151], v[218:219] op_sel_hi:[1,0]
	v_pk_mul_f32 v[152:153], v[184:185], v[148:149]
	v_pk_mul_f32 v[154:155], v[182:183], v[150:151]
	v_pk_mul_f32 v[148:149], v[188:189], v[218:219] op_sel_hi:[1,0]
	v_pk_mul_f32 v[150:151], v[186:187], v[218:219] op_sel_hi:[1,0]
	v_pk_mul_f32 v[180:181], v[180:181], v[148:149]
	v_pk_mul_f32 v[178:179], v[178:179], v[150:151]
	v_pk_mul_f32 v[148:149], v[192:193], v[218:219] op_sel_hi:[1,0]
	v_pk_mul_f32 v[150:151], v[190:191], v[218:219] op_sel_hi:[1,0]
	v_pk_mul_f32 v[148:149], v[162:163], v[148:149]
	v_pk_mul_f32 v[150:151], v[160:161], v[150:151]
	v_pk_mul_f32 v[160:161], v[216:217], v[218:219] op_sel_hi:[1,0]
	v_pk_mul_f32 v[162:163], v[214:215], v[218:219] op_sel_hi:[1,0]
	v_pk_mul_f32 v[158:159], v[158:159], v[160:161]
	v_pk_mul_f32 v[156:157], v[156:157], v[162:163]
	s_cbranch_vccnz .LBB0_591
	v_add_u32_e32 v160, 0xb0, v201
	v_and_b32_e32 v182, 0x7c0, v160
	v_add_u32_e32 v160, v205, v182
	v_add_u32_e32 v182, v204, v182
	ds_read_b128 v[160:163], v160
	ds_read_b128 v[182:185], v182
	s_waitcnt lgkmcnt(0)
	v_pk_mul_f32 v[186:187], v[178:179], v[184:185]
	v_pk_mul_f32 v[190:191], v[180:181], v[182:183]
	v_pk_fma_f32 v[188:189], v[154:155], v[162:163], v[186:187] neg_lo:[0,0,1] neg_hi:[0,0,1]
	v_pk_fma_f32 v[186:187], v[152:153], v[160:161], v[190:191] neg_lo:[0,0,1] neg_hi:[0,0,1]
	v_pk_mul_f32 v[152:153], v[152:153], v[182:183]
	v_pk_mul_f32 v[154:155], v[154:155], v[184:185]
	v_pk_fma_f32 v[180:181], v[180:181], v[160:161], v[152:153]
	v_add_u32_e32 v152, v205, v194
	v_add_u32_e32 v160, v204, v194
	v_pk_fma_f32 v[178:179], v[178:179], v[162:163], v[154:155]
	ds_read_b128 v[152:155], v152
	ds_read_b128 v[160:163], v160
	s_waitcnt lgkmcnt(0)
	v_pk_mul_f32 v[182:183], v[156:157], v[162:163]
	v_pk_mul_f32 v[190:191], v[158:159], v[160:161]
	v_pk_fma_f32 v[184:185], v[150:151], v[154:155], v[182:183] neg_lo:[0,0,1] neg_hi:[0,0,1]
	v_pk_fma_f32 v[182:183], v[148:149], v[152:153], v[190:191] neg_lo:[0,0,1] neg_hi:[0,0,1]
	v_pk_mul_f32 v[150:151], v[150:151], v[162:163]
	v_pk_mul_f32 v[148:149], v[148:149], v[160:161]
	v_pk_fma_f32 v[156:157], v[156:157], v[154:155], v[150:151]
	v_pk_fma_f32 v[158:159], v[158:159], v[152:153], v[148:149]
	v_mov_b64_e32 v[148:149], v[182:183]
	v_mov_b64_e32 v[152:153], v[186:187]
	v_mov_b64_e32 v[150:151], v[184:185]
	v_mov_b64_e32 v[154:155], v[188:189]
; __device__ __forceinline__ unsigned cvtpk_h(float lo, float hi) { f32x2 v = {lo, hi}; h16x2 b = __builtin_convertvector(v, h16x2); return __builtin_bit_cast(unsigned, b); }
;     __device__ __forceinline__ void operator()(const f32x4 (&acc)[2][2][4][2], const pg8::Unit& u, int wr, int wc, int fr, int fq) const {
;     ...
;                 for (int bj = 0; bj < 2; ++bj) { w[bj].x = cvtpk_h(v[bj][0][0], v[bj][0][1]); w[bj].y = cvtpk_h(v[bj][0][2], v[bj][0][3]); w[bj].z = cvtpk_h(v[bj][1][0], v[bj][1][1]); w[bj].w = cvtpk_h(v[bj][1][2], v[bj][1][3]); }
;                 stg_line_pair(wst, ro, 2u * pitch, w[0], w[1], odd);
;                 asm volatile("" ::: "memory"); }
.LBB0_591:
	v_cvt_pk_f16_f32 v152, v152, v153
	v_cvt_pk_f16_f32 v149, v148, v149
	v_cvt_pk_f16_f32 v150, v150, v151
	v_cvt_pk_f16_f32 v151, v158, v159
	v_mov_b32_e32 v148, v1
	v_mov_b32_e32 v158, v1
	v_cvt_pk_f16_f32 v153, v154, v155
	v_mov_b32_dpp v148, v149 quad_perm:[1,0,3,2] row_mask:0xf bank_mask:0xf
	v_mov_b32_dpp v158, v152 quad_perm:[1,0,3,2] row_mask:0xf bank_mask:0xf
	v_cndmask_b32_e64 v148, v148, v152, s[2:3]
	v_cndmask_b32_e64 v152, v149, v158, s[2:3]
	v_mov_b32_e32 v149, v1
	v_mov_b32_e32 v158, v1
	v_cvt_pk_f16_f32 v154, v180, v181
	v_mov_b32_dpp v149, v150 quad_perm:[1,0,3,2] row_mask:0xf bank_mask:0xf
	v_mov_b32_dpp v158, v153 quad_perm:[1,0,3,2] row_mask:0xf bank_mask:0xf
	v_cndmask_b32_e64 v149, v149, v153, s[2:3]
	v_cndmask_b32_e64 v153, v150, v158, s[2:3]
	v_mov_b32_e32 v150, v1
	v_mov_b32_e32 v158, v1
	v_cvt_pk_f16_f32 v156, v156, v157
	v_mov_b32_dpp v150, v151 quad_perm:[1,0,3,2] row_mask:0xf bank_mask:0xf
	v_mov_b32_dpp v158, v154 quad_perm:[1,0,3,2] row_mask:0xf bank_mask:0xf
	v_cndmask_b32_e64 v150, v150, v154, s[2:3]
	v_cndmask_b32_e64 v154, v151, v158, s[2:3]
	v_mov_b32_e32 v151, v1
	s_lshl_b32 s4, 0x160, s42
	v_cvt_pk_f16_f32 v155, v178, v179
	v_mov_b32_dpp v151, v156 quad_perm:[1,0,3,2] row_mask:0xf bank_mask:0xf
	v_mov_b32_e32 v158, v1
	v_add_u32_e32 v157, s4, v206
	v_cndmask_b32_e64 v151, v151, v155, s[2:3]
	v_mov_b32_dpp v158, v155 quad_perm:[1,0,3,2] row_mask:0xf bank_mask:0xf
	v_cndmask_b32_e64 v155, v156, v158, s[2:3]
	s_mov_b32 s100, 2
	global_store_dwordx4 v157, v[148:151], s[36:37] sc1
	s_mov_b64 s[2:3], 0
	s_nop 0
	v_add_u32_e32 v148, s9, v157
	s_mov_b32 s100, 2
	global_store_dwordx4 v148, v[152:155], s[36:37] sc1

; __device__ __forceinline__ unsigned cvtpk_h(float lo, float hi) { f32x2 v = {lo, hi}; h16x2 b = __builtin_convertvector(v, h16x2); return __builtin_bit_cast(unsigned, b); }
;     __device__ __forceinline__ void operator()(const f32x4 (&acc)[2][2][4][2], const pg8::Unit& u, int wr, int wc, int fr, int fq) const {
;     ...
;             const bool odd = (fr & 1) != 0;
;             const unsigned offA = base + ((row0 + (unsigned)(wr * 64 + (fr & ~1))) * pitch + coff) * 2u + (odd ? 64u : 0u) + 16u * fq;
; #pragma unroll
;             for (int ai = 0; ai < 2; ++ai)
; #pragma unroll
;                 for (int m = 0; m < 4; ++m) { const unsigned ro = offA + (unsigned)(ai * 8 + m) * rowstep; const float r = rs[ai][m];
;                     u32x4 w[2];
; #pragma unroll
;                     for (int bj = 0; bj < 2; ++bj) { const f32x4 v0 = acc[ai][bj][m][0] * r + bv[bj][0], v1 = acc[ai][bj][m][1] * r + bv[bj][1];
;                         w[bj].x = cvtpk_h(v0[0], v0[1]); w[bj].y = cvtpk_h(v0[2], v0[3]); w[bj].z = cvtpk_h(v1[0], v1[1]); w[bj].w = cvtpk_h(v1[2], v1[3]); }
;                     stg_line_pair(wst, ro, 2u * pitch, w[0], w[1], odd);
;                     asm volatile("" ::: "memory"); }
.LBB0_632:
	v_and_b32_e32 v178, 0x7ffffffe, v202
	s_add_i32 s2, s42, s77
	v_add_u32_e32 v178, s2, v178
	v_and_b32_e32 v186, 1, v202
	v_mul_lo_u32 v178, s9, v178
	v_add_lshl_u32 v178, v178, s38, 1
	v_lshl_add_u32 v179, v186, 6, v203
	v_pk_fma_f32 v[180:181], v[70:71], v[162:163], v[148:149] op_sel_hi:[1,0,1]
	s_waitcnt vmcnt(1)
	v_pk_fma_f32 v[128:129], v[128:129], v[162:163], v[142:143] op_sel_hi:[1,0,1]
	v_pk_fma_f32 v[126:127], v[126:127], v[162:163], v[140:141] op_sel_hi:[1,0,1]
	s_waitcnt vmcnt(0)
	v_pk_fma_f32 v[122:123], v[122:123], v[162:163], v[144:145] op_sel_hi:[1,0,1]
	v_add3_u32 v187, v179, s39, v178
	v_pk_fma_f32 v[178:179], v[72:73], v[162:163], v[150:151] op_sel_hi:[1,0,1]
	v_cvt_pk_f16_f32 v180, v180, v181
	v_pk_fma_f32 v[124:125], v[124:125], v[162:163], v[146:147] op_sel_hi:[1,0,1]
	v_cvt_pk_f16_f32 v126, v126, v127
	v_cvt_pk_f16_f32 v127, v128, v129
	v_cvt_pk_f16_f32 v128, v122, v123
	v_mov_b32_e32 v123, v1
	v_pk_fma_f32 v[184:185], v[66:67], v[162:163], v[152:153] op_sel_hi:[1,0,1]
	v_cvt_pk_f16_f32 v178, v178, v179
	v_cvt_pk_f16_f32 v129, v124, v125
	v_mov_b32_e32 v122, v1
	v_mov_b32_dpp v123, v180 quad_perm:[1,0,3,2] row_mask:0xf bank_mask:0xf
	v_cmp_eq_u32_e32 vcc, 0, v186
	v_mov_b32_e32 v124, v1
	v_cvt_pk_f16_f32 v179, v184, v185
	v_mov_b32_dpp v122, v126 quad_perm:[1,0,3,2] row_mask:0xf bank_mask:0xf
	v_cndmask_b32_e32 v126, v126, v123, vcc
	v_mov_b32_e32 v123, v1
	v_mov_b32_dpp v124, v178 quad_perm:[1,0,3,2] row_mask:0xf bank_mask:0xf
	v_mov_b32_e32 v125, v1
	v_mov_b32_dpp v123, v127 quad_perm:[1,0,3,2] row_mask:0xf bank_mask:0xf
	v_cndmask_b32_e32 v127, v127, v124, vcc
	v_mov_b32_e32 v124, v1
	v_mov_b32_dpp v125, v179 quad_perm:[1,0,3,2] row_mask:0xf bank_mask:0xf
	v_pk_fma_f32 v[182:183], v[68:69], v[162:163], v[154:155] op_sel_hi:[1,0,1]
	v_mov_b32_dpp v124, v128 quad_perm:[1,0,3,2] row_mask:0xf bank_mask:0xf
	v_cndmask_b32_e32 v128, v128, v125, vcc
	v_mov_b32_e32 v125, v1
	v_cvt_pk_f16_f32 v181, v182, v183
	v_cndmask_b32_e32 v123, v123, v178, vcc
	v_mov_b32_dpp v125, v129 quad_perm:[1,0,3,2] row_mask:0xf bank_mask:0xf
	v_mov_b32_e32 v178, v1
	s_lshl_b32 s2, s9, 1
	v_cndmask_b32_e32 v122, v122, v180, vcc
	v_cndmask_b32_e32 v124, v124, v179, vcc
	v_mov_b32_dpp v178, v181 quad_perm:[1,0,3,2] row_mask:0xf bank_mask:0xf
	v_cndmask_b32_e32 v125, v125, v181, vcc
	v_cndmask_b32_e32 v129, v129, v178, vcc
	s_mov_b32 s100, 2
	global_store_dwordx4 v187, v[122:125], s[36:37] sc1
	v_pk_fma_f32 v[120:121], v[120:121], v[162:163], v[142:143] op_sel:[0,1,0]
	v_pk_fma_f32 v[118:119], v[118:119], v[162:163], v[140:141] op_sel:[0,1,0]
	v_add_u32_e32 v122, s2, v187
	s_mov_b32 s100, 2
	global_store_dwordx4 v122, v[126:129], s[36:37] sc1
	v_pk_fma_f32 v[114:115], v[114:115], v[162:163], v[144:145] op_sel:[0,1,0]
	v_pk_fma_f32 v[124:125], v[52:53], v[162:163], v[150:151] op_sel:[0,1,0]
	v_pk_fma_f32 v[126:127], v[50:51], v[162:163], v[148:149] op_sel:[0,1,0]
	v_pk_fma_f32 v[116:117], v[116:117], v[162:163], v[146:147] op_sel:[0,1,0]
	v_cvt_pk_f16_f32 v126, v126, v127
	v_cvt_pk_f16_f32 v118, v118, v119
	v_cvt_pk_f16_f32 v119, v120, v121
	v_cvt_pk_f16_f32 v120, v114, v115
	v_mov_b32_e32 v115, v1
	v_pk_fma_f32 v[178:179], v[46:47], v[162:163], v[152:153] op_sel:[0,1,0]
	v_cvt_pk_f16_f32 v124, v124, v125
	v_cvt_pk_f16_f32 v121, v116, v117
	v_mov_b32_e32 v114, v1
	v_mov_b32_dpp v115, v126 quad_perm:[1,0,3,2] row_mask:0xf bank_mask:0xf
	v_mov_b32_e32 v116, v1
	v_cvt_pk_f16_f32 v125, v178, v179
	v_mov_b32_dpp v114, v118 quad_perm:[1,0,3,2] row_mask:0xf bank_mask:0xf
	v_cndmask_b32_e32 v118, v118, v115, vcc
	v_mov_b32_e32 v115, v1
	v_mov_b32_dpp v116, v124 quad_perm:[1,0,3,2] row_mask:0xf bank_mask:0xf
	v_mov_b32_e32 v117, v1
	v_mov_b32_dpp v115, v119 quad_perm:[1,0,3,2] row_mask:0xf bank_mask:0xf
	v_cndmask_b32_e32 v119, v119, v116, vcc
	v_mov_b32_e32 v116, v1
	v_mov_b32_dpp v117, v125 quad_perm:[1,0,3,2] row_mask:0xf bank_mask:0xf
	v_pk_fma_f32 v[128:129], v[48:49], v[162:163], v[154:155] op_sel:[0,1,0]
	v_mad_u64_u32 v[122:123], s[4:5], s9, 30, v[122:123]
	v_mov_b32_dpp v116, v120 quad_perm:[1,0,3,2] row_mask:0xf bank_mask:0xf
	v_cndmask_b32_e32 v120, v120, v117, vcc
	v_mov_b32_e32 v117, v1
	v_cvt_pk_f16_f32 v127, v128, v129
	v_mov_b32_e32 v123, v1
	v_mov_b32_dpp v117, v121 quad_perm:[1,0,3,2] row_mask:0xf bank_mask:0xf
	v_cndmask_b32_e32 v114, v114, v126, vcc
	v_cndmask_b32_e32 v115, v115, v124, vcc
	v_cndmask_b32_e32 v116, v116, v125, vcc
	v_mov_b32_dpp v123, v127 quad_perm:[1,0,3,2] row_mask:0xf bank_mask:0xf
	v_cndmask_b32_e32 v117, v117, v127, vcc
	v_cndmask_b32_e32 v121, v121, v123, vcc
	s_mov_b32 s100, 2
	global_store_dwordx4 v122, v[114:117], s[36:37] sc1
	v_pk_fma_f32 v[112:113], v[112:113], v[160:161], v[142:143] op_sel_hi:[1,0,1]
	v_pk_fma_f32 v[110:111], v[110:111], v[160:161], v[140:141] op_sel_hi:[1,0,1]
	v_add_u32_e32 v114, s2, v122
	v_pk_fma_f32 v[116:117], v[54:55], v[160:161], v[148:149] op_sel_hi:[1,0,1]
	v_pk_fma_f32 v[106:107], v[106:107], v[160:161], v[144:145] op_sel_hi:[1,0,1]
	s_mov_b32 s100, 2
	global_store_dwordx4 v114, v[118:121], s[36:37] sc1
	v_pk_fma_f32 v[114:115], v[56:57], v[160:161], v[150:151] op_sel_hi:[1,0,1]
	v_cvt_pk_f16_f32 v116, v116, v117
	v_pk_fma_f32 v[108:109], v[108:109], v[160:161], v[146:147] op_sel_hi:[1,0,1]
	v_cvt_pk_f16_f32 v110, v110, v111
	v_cvt_pk_f16_f32 v111, v112, v113
	v_cvt_pk_f16_f32 v112, v106, v107
	v_mov_b32_e32 v107, v1
	v_pk_fma_f32 v[120:121], v[42:43], v[160:161], v[152:153] op_sel_hi:[1,0,1]
	v_cvt_pk_f16_f32 v114, v114, v115
	v_cvt_pk_f16_f32 v113, v108, v109
	v_mov_b32_e32 v106, v1
	v_mov_b32_dpp v107, v116 quad_perm:[1,0,3,2] row_mask:0xf bank_mask:0xf
; __device__ __forceinline__ unsigned cvtpk_h(float lo, float hi) { f32x2 v = {lo, hi}; h16x2 b = __builtin_convertvector(v, h16x2); return __builtin_bit_cast(unsigned, b); }
;     __device__ __forceinline__ void operator()(const f32x4 (&acc)[2][2][4][2], const pg8::Unit& u, int wr, int wc, int fr, int fq) const {
;     ...
;             const bool odd = (fr & 1) != 0;
;             const unsigned offA = base + ((row0 + (unsigned)(wr * 64 + (fr & ~1))) * pitch + coff) * 2u + (odd ? 64u : 0u) + 16u * fq;
; #pragma unroll
;             for (int ai = 0; ai < 2; ++ai)
; #pragma unroll
;                 for (int m = 0; m < 4; ++m) { const unsigned ro = offA + (unsigned)(ai * 8 + m) * rowstep; const float r = rs[ai][m];
;                     u32x4 w[2];
; #pragma unroll
;                     for (int bj = 0; bj < 2; ++bj) { const f32x4 v0 = acc[ai][bj][m][0] * r + bv[bj][0], v1 = acc[ai][bj][m][1] * r + bv[bj][1];
;                         w[bj].x = cvtpk_h(v0[0], v0[1]); w[bj].y = cvtpk_h(v0[2], v0[3]); w[bj].z = cvtpk_h(v1[0], v1[1]); w[bj].w = cvtpk_h(v1[2], v1[3]); }
;                     stg_line_pair(wst, ro, 2u * pitch, w[0], w[1], odd);
;                     asm volatile("" ::: "memory"); }
	v_mov_b32_e32 v108, v1
	v_cvt_pk_f16_f32 v115, v120, v121
	v_mov_b32_dpp v106, v110 quad_perm:[1,0,3,2] row_mask:0xf bank_mask:0xf
	v_cndmask_b32_e32 v110, v110, v107, vcc
	v_mov_b32_e32 v107, v1
	v_mov_b32_dpp v108, v114 quad_perm:[1,0,3,2] row_mask:0xf bank_mask:0xf
	v_mov_b32_e32 v109, v1
	v_mov_b32_dpp v107, v111 quad_perm:[1,0,3,2] row_mask:0xf bank_mask:0xf
	v_cndmask_b32_e32 v111, v111, v108, vcc
	v_mov_b32_e32 v108, v1
	v_mov_b32_dpp v109, v115 quad_perm:[1,0,3,2] row_mask:0xf bank_mask:0xf
	v_pk_fma_f32 v[118:119], v[44:45], v[160:161], v[154:155] op_sel_hi:[1,0,1]
	v_mov_b32_dpp v108, v112 quad_perm:[1,0,3,2] row_mask:0xf bank_mask:0xf
	v_cndmask_b32_e32 v112, v112, v109, vcc
	v_mov_b32_e32 v109, v1
	v_cvt_pk_f16_f32 v117, v118, v119
	s_lshl_b32 s3, s9, 5
	v_cndmask_b32_e32 v107, v107, v114, vcc
	v_mov_b32_dpp v109, v113 quad_perm:[1,0,3,2] row_mask:0xf bank_mask:0xf
	v_mov_b32_e32 v114, v1
	v_add_u32_e32 v118, s3, v122
	v_cndmask_b32_e32 v106, v106, v116, vcc
	v_cndmask_b32_e32 v108, v108, v115, vcc
	v_mov_b32_dpp v114, v117 quad_perm:[1,0,3,2] row_mask:0xf bank_mask:0xf
	v_cndmask_b32_e32 v109, v109, v117, vcc
	v_cndmask_b32_e32 v113, v113, v114, vcc
	s_mov_b32 s100, 2
	global_store_dwordx4 v118, v[106:109], s[36:37] sc1
	v_pk_fma_f32 v[104:105], v[104:105], v[160:161], v[142:143] op_sel:[0,1,0]
	v_pk_fma_f32 v[102:103], v[102:103], v[160:161], v[140:141] op_sel:[0,1,0]
	v_add_u32_e32 v106, s2, v118
	v_pk_fma_f32 v[108:109], v[38:39], v[160:161], v[148:149] op_sel:[0,1,0]
	v_pk_fma_f32 v[98:99], v[98:99], v[160:161], v[144:145] op_sel:[0,1,0]
	s_mov_b32 s100, 2
	global_store_dwordx4 v106, v[110:113], s[36:37] sc1
	v_pk_fma_f32 v[106:107], v[40:41], v[160:161], v[150:151] op_sel:[0,1,0]
	v_cvt_pk_f16_f32 v108, v108, v109
	v_pk_fma_f32 v[100:101], v[100:101], v[160:161], v[146:147] op_sel:[0,1,0]
	v_cvt_pk_f16_f32 v102, v102, v103
	v_cvt_pk_f16_f32 v103, v104, v105
	v_cvt_pk_f16_f32 v104, v98, v99
	v_mov_b32_e32 v99, v1
	v_pk_fma_f32 v[112:113], v[34:35], v[160:161], v[152:153] op_sel:[0,1,0]
	v_cvt_pk_f16_f32 v106, v106, v107
	v_cvt_pk_f16_f32 v105, v100, v101
	v_mov_b32_e32 v98, v1
	v_mov_b32_dpp v99, v108 quad_perm:[1,0,3,2] row_mask:0xf bank_mask:0xf
	v_mov_b32_e32 v100, v1
	v_cvt_pk_f16_f32 v107, v112, v113
	v_mov_b32_dpp v98, v102 quad_perm:[1,0,3,2] row_mask:0xf bank_mask:0xf
	v_cndmask_b32_e32 v102, v102, v99, vcc
	v_mov_b32_e32 v99, v1
	v_mov_b32_dpp v100, v106 quad_perm:[1,0,3,2] row_mask:0xf bank_mask:0xf
	v_mov_b32_e32 v101, v1
	v_mov_b32_dpp v99, v103 quad_perm:[1,0,3,2] row_mask:0xf bank_mask:0xf
	v_cndmask_b32_e32 v103, v103, v100, vcc
	v_mov_b32_e32 v100, v1
	v_mov_b32_dpp v101, v107 quad_perm:[1,0,3,2] row_mask:0xf bank_mask:0xf
	v_pk_fma_f32 v[110:111], v[36:37], v[160:161], v[154:155] op_sel:[0,1,0]
	v_mov_b32_dpp v100, v104 quad_perm:[1,0,3,2] row_mask:0xf bank_mask:0xf
	v_cndmask_b32_e32 v104, v104, v101, vcc
	v_mov_b32_e32 v101, v1
	v_cvt_pk_f16_f32 v109, v110, v111
	v_cndmask_b32_e32 v99, v99, v106, vcc
	v_mov_b32_dpp v101, v105 quad_perm:[1,0,3,2] row_mask:0xf bank_mask:0xf
	v_mov_b32_e32 v106, v1
	v_add_u32_e32 v110, s3, v118
	v_cndmask_b32_e32 v98, v98, v108, vcc
	v_cndmask_b32_e32 v100, v100, v107, vcc
	v_mov_b32_dpp v106, v109 quad_perm:[1,0,3,2] row_mask:0xf bank_mask:0xf
	v_cndmask_b32_e32 v101, v101, v109, vcc
	v_cndmask_b32_e32 v105, v105, v106, vcc
	s_mov_b32 s100, 2
	global_store_dwordx4 v110, v[98:101], s[36:37] sc1
	v_pk_fma_f32 v[96:97], v[96:97], v[158:159], v[142:143] op_sel_hi:[1,0,1]
	v_pk_fma_f32 v[94:95], v[94:95], v[158:159], v[140:141] op_sel_hi:[1,0,1]
	v_add_u32_e32 v98, s2, v110
	v_pk_fma_f32 v[100:101], v[30:31], v[158:159], v[148:149] op_sel_hi:[1,0,1]
	v_pk_fma_f32 v[90:91], v[90:91], v[158:159], v[144:145] op_sel_hi:[1,0,1]
	s_mov_b32 s100, 2
	global_store_dwordx4 v98, v[102:105], s[36:37] sc1
	v_pk_fma_f32 v[98:99], v[32:33], v[158:159], v[150:151] op_sel_hi:[1,0,1]
	v_cvt_pk_f16_f32 v100, v100, v101
	v_pk_fma_f32 v[92:93], v[92:93], v[158:159], v[146:147] op_sel_hi:[1,0,1]
	v_cvt_pk_f16_f32 v94, v94, v95
	v_cvt_pk_f16_f32 v95, v96, v97
	v_cvt_pk_f16_f32 v96, v90, v91
	v_mov_b32_e32 v91, v1
	v_pk_fma_f32 v[104:105], v[26:27], v[158:159], v[152:153] op_sel_hi:[1,0,1]
	v_cvt_pk_f16_f32 v98, v98, v99
	v_cvt_pk_f16_f32 v97, v92, v93
	v_mov_b32_e32 v90, v1
	v_mov_b32_dpp v91, v100 quad_perm:[1,0,3,2] row_mask:0xf bank_mask:0xf
	v_mov_b32_e32 v92, v1
	v_cvt_pk_f16_f32 v99, v104, v105
	v_mov_b32_dpp v90, v94 quad_perm:[1,0,3,2] row_mask:0xf bank_mask:0xf
	v_cndmask_b32_e32 v94, v94, v91, vcc
	v_mov_b32_e32 v91, v1
	v_mov_b32_dpp v92, v98 quad_perm:[1,0,3,2] row_mask:0xf bank_mask:0xf
	v_mov_b32_e32 v93, v1
	v_mov_b32_dpp v91, v95 quad_perm:[1,0,3,2] row_mask:0xf bank_mask:0xf
	v_cndmask_b32_e32 v95, v95, v92, vcc
	v_mov_b32_e32 v92, v1
	v_mov_b32_dpp v93, v99 quad_perm:[1,0,3,2] row_mask:0xf bank_mask:0xf
	v_pk_fma_f32 v[102:103], v[28:29], v[158:159], v[154:155] op_sel_hi:[1,0,1]
	v_mov_b32_dpp v92, v96 quad_perm:[1,0,3,2] row_mask:0xf bank_mask:0xf
	v_cndmask_b32_e32 v96, v96, v93, vcc
	v_mov_b32_e32 v93, v1
	v_cvt_pk_f16_f32 v101, v102, v103
	s_mul_i32 s4, s9, 0xa0
	v_cndmask_b32_e32 v91, v91, v98, vcc
	v_mov_b32_dpp v93, v97 quad_perm:[1,0,3,2] row_mask:0xf bank_mask:0xf
	v_mov_b32_e32 v98, v1
	v_add_u32_e32 v102, s4, v110
	v_cndmask_b32_e32 v90, v90, v100, vcc
	v_cndmask_b32_e32 v92, v92, v99, vcc
	v_mov_b32_dpp v98, v101 quad_perm:[1,0,3,2] row_mask:0xf bank_mask:0xf
	v_cndmask_b32_e32 v93, v93, v101, vcc
	v_cndmask_b32_e32 v97, v97, v98, vcc
	s_mov_b32 s100, 2
	global_store_dwordx4 v102, v[90:93], s[36:37] sc1
	v_pk_fma_f32 v[88:89], v[88:89], v[158:159], v[142:143] op_sel:[0,1,0]
; __device__ __forceinline__ unsigned cvtpk_h(float lo, float hi) { f32x2 v = {lo, hi}; h16x2 b = __builtin_convertvector(v, h16x2); return __builtin_bit_cast(unsigned, b); }
;     __device__ __forceinline__ void operator()(const f32x4 (&acc)[2][2][4][2], const pg8::Unit& u, int wr, int wc, int fr, int fq) const {
;     ...
;             const bool odd = (fr & 1) != 0;
;             const unsigned offA = base + ((row0 + (unsigned)(wr * 64 + (fr & ~1))) * pitch + coff) * 2u + (odd ? 64u : 0u) + 16u * fq;
; #pragma unroll
;             for (int ai = 0; ai < 2; ++ai)
; #pragma unroll
;                 for (int m = 0; m < 4; ++m) { const unsigned ro = offA + (unsigned)(ai * 8 + m) * rowstep; const float r = rs[ai][m];
;                     u32x4 w[2];
; #pragma unroll
;                     for (int bj = 0; bj < 2; ++bj) { const f32x4 v0 = acc[ai][bj][m][0] * r + bv[bj][0], v1 = acc[ai][bj][m][1] * r + bv[bj][1];
;                         w[bj].x = cvtpk_h(v0[0], v0[1]); w[bj].y = cvtpk_h(v0[2], v0[3]); w[bj].z = cvtpk_h(v1[0], v1[1]); w[bj].w = cvtpk_h(v1[2], v1[3]); }
;                     stg_line_pair(wst, ro, 2u * pitch, w[0], w[1], odd);
;                     asm volatile("" ::: "memory"); }
	v_pk_fma_f32 v[86:87], v[86:87], v[158:159], v[140:141] op_sel:[0,1,0]
	v_add_u32_e32 v90, s2, v102
	v_pk_fma_f32 v[92:93], v[22:23], v[158:159], v[148:149] op_sel:[0,1,0]
	v_pk_fma_f32 v[82:83], v[82:83], v[158:159], v[144:145] op_sel:[0,1,0]
	s_mov_b32 s100, 2
	global_store_dwordx4 v90, v[94:97], s[36:37] sc1
	v_pk_fma_f32 v[90:91], v[24:25], v[158:159], v[150:151] op_sel:[0,1,0]
	v_cvt_pk_f16_f32 v92, v92, v93
	v_pk_fma_f32 v[84:85], v[84:85], v[158:159], v[146:147] op_sel:[0,1,0]
	v_cvt_pk_f16_f32 v86, v86, v87
	v_cvt_pk_f16_f32 v87, v88, v89
	v_cvt_pk_f16_f32 v88, v82, v83
	v_mov_b32_e32 v83, v1
	v_pk_fma_f32 v[96:97], v[18:19], v[158:159], v[152:153] op_sel:[0,1,0]
	v_cvt_pk_f16_f32 v90, v90, v91
	v_cvt_pk_f16_f32 v89, v84, v85
	v_mov_b32_e32 v82, v1
	v_mov_b32_dpp v83, v92 quad_perm:[1,0,3,2] row_mask:0xf bank_mask:0xf
	v_mov_b32_e32 v84, v1
	v_cvt_pk_f16_f32 v91, v96, v97
	v_mov_b32_dpp v82, v86 quad_perm:[1,0,3,2] row_mask:0xf bank_mask:0xf
	v_cndmask_b32_e32 v86, v86, v83, vcc
	v_mov_b32_e32 v83, v1
	v_mov_b32_dpp v84, v90 quad_perm:[1,0,3,2] row_mask:0xf bank_mask:0xf
	v_mov_b32_e32 v85, v1
	v_mov_b32_dpp v83, v87 quad_perm:[1,0,3,2] row_mask:0xf bank_mask:0xf
	v_cndmask_b32_e32 v87, v87, v84, vcc
	v_mov_b32_e32 v84, v1
	v_mov_b32_dpp v85, v91 quad_perm:[1,0,3,2] row_mask:0xf bank_mask:0xf
	v_pk_fma_f32 v[94:95], v[20:21], v[158:159], v[154:155] op_sel:[0,1,0]
	v_mov_b32_dpp v84, v88 quad_perm:[1,0,3,2] row_mask:0xf bank_mask:0xf
	v_cndmask_b32_e32 v88, v88, v85, vcc
	v_mov_b32_e32 v85, v1
	v_cvt_pk_f16_f32 v93, v94, v95
	v_cndmask_b32_e32 v83, v83, v90, vcc
	v_mov_b32_dpp v85, v89 quad_perm:[1,0,3,2] row_mask:0xf bank_mask:0xf
	v_mov_b32_e32 v90, v1
	v_add_u32_e32 v94, s3, v102
	v_cndmask_b32_e32 v82, v82, v92, vcc
	v_cndmask_b32_e32 v84, v84, v91, vcc
	v_mov_b32_dpp v90, v93 quad_perm:[1,0,3,2] row_mask:0xf bank_mask:0xf
	v_cndmask_b32_e32 v85, v85, v93, vcc
	v_cndmask_b32_e32 v89, v89, v90, vcc
	s_mov_b32 s100, 2
	global_store_dwordx4 v94, v[82:85], s[36:37] sc1
	v_pk_fma_f32 v[80:81], v[80:81], v[156:157], v[142:143] op_sel_hi:[1,0,1]
	v_pk_fma_f32 v[78:79], v[78:79], v[156:157], v[140:141] op_sel_hi:[1,0,1]
	v_add_u32_e32 v82, s2, v94
	v_pk_fma_f32 v[84:85], v[14:15], v[156:157], v[148:149] op_sel_hi:[1,0,1]
	v_pk_fma_f32 v[74:75], v[74:75], v[156:157], v[144:145] op_sel_hi:[1,0,1]
	s_mov_b32 s100, 2
	global_store_dwordx4 v82, v[86:89], s[36:37] sc1
	v_pk_fma_f32 v[82:83], v[16:17], v[156:157], v[150:151] op_sel_hi:[1,0,1]
	v_cvt_pk_f16_f32 v84, v84, v85
	v_pk_fma_f32 v[76:77], v[76:77], v[156:157], v[146:147] op_sel_hi:[1,0,1]
	v_cvt_pk_f16_f32 v78, v78, v79
	v_cvt_pk_f16_f32 v79, v80, v81
	v_cvt_pk_f16_f32 v80, v74, v75
	v_mov_b32_e32 v75, v1
	v_pk_fma_f32 v[88:89], v[10:11], v[156:157], v[152:153] op_sel_hi:[1,0,1]
	v_cvt_pk_f16_f32 v82, v82, v83
	v_cvt_pk_f16_f32 v81, v76, v77
	v_mov_b32_e32 v74, v1
	v_mov_b32_dpp v75, v84 quad_perm:[1,0,3,2] row_mask:0xf bank_mask:0xf
	v_mov_b32_e32 v76, v1
	v_cvt_pk_f16_f32 v83, v88, v89
	v_mov_b32_dpp v74, v78 quad_perm:[1,0,3,2] row_mask:0xf bank_mask:0xf
	v_cndmask_b32_e32 v78, v78, v75, vcc
	v_mov_b32_e32 v75, v1
	v_mov_b32_dpp v76, v82 quad_perm:[1,0,3,2] row_mask:0xf bank_mask:0xf
	v_mov_b32_e32 v77, v1
	v_mov_b32_dpp v75, v79 quad_perm:[1,0,3,2] row_mask:0xf bank_mask:0xf
	v_cndmask_b32_e32 v79, v79, v76, vcc
	v_mov_b32_e32 v76, v1
	v_mov_b32_dpp v77, v83 quad_perm:[1,0,3,2] row_mask:0xf bank_mask:0xf
	v_pk_fma_f32 v[86:87], v[12:13], v[156:157], v[154:155] op_sel_hi:[1,0,1]
	v_mov_b32_dpp v76, v80 quad_perm:[1,0,3,2] row_mask:0xf bank_mask:0xf
	v_cndmask_b32_e32 v80, v80, v77, vcc
	v_mov_b32_e32 v77, v1
	v_cvt_pk_f16_f32 v85, v86, v87
	v_cndmask_b32_e32 v75, v75, v82, vcc
	v_mov_b32_dpp v77, v81 quad_perm:[1,0,3,2] row_mask:0xf bank_mask:0xf
	v_mov_b32_e32 v82, v1
	v_add_u32_e32 v86, s3, v94
	v_cndmask_b32_e32 v74, v74, v84, vcc
	v_cndmask_b32_e32 v76, v76, v83, vcc
	v_mov_b32_dpp v82, v85 quad_perm:[1,0,3,2] row_mask:0xf bank_mask:0xf
	v_cndmask_b32_e32 v77, v77, v85, vcc
	v_cndmask_b32_e32 v81, v81, v82, vcc
	s_mov_b32 s100, 2
	global_store_dwordx4 v86, v[74:77], s[36:37] sc1
	v_pk_fma_f32 v[64:65], v[64:65], v[156:157], v[142:143] op_sel:[0,1,0]
	v_pk_fma_f32 v[62:63], v[62:63], v[156:157], v[140:141] op_sel:[0,1,0]
	v_add_u32_e32 v74, s2, v86
	v_pk_fma_f32 v[76:77], v[6:7], v[156:157], v[148:149] op_sel:[0,1,0]
	v_pk_fma_f32 v[58:59], v[58:59], v[156:157], v[144:145] op_sel:[0,1,0]
	s_mov_b32 s100, 2
	global_store_dwordx4 v74, v[78:81], s[36:37] sc1
	v_pk_fma_f32 v[74:75], v[8:9], v[156:157], v[150:151] op_sel:[0,1,0]
	v_cvt_pk_f16_f32 v76, v76, v77
	v_pk_fma_f32 v[60:61], v[60:61], v[156:157], v[146:147] op_sel:[0,1,0]
	v_cvt_pk_f16_f32 v62, v62, v63
	v_cvt_pk_f16_f32 v63, v64, v65
	v_cvt_pk_f16_f32 v64, v58, v59
	v_mov_b32_e32 v59, v1
	v_pk_fma_f32 v[80:81], v[2:3], v[156:157], v[152:153] op_sel:[0,1,0]
	v_cvt_pk_f16_f32 v74, v74, v75
	v_cvt_pk_f16_f32 v65, v60, v61
	v_mov_b32_e32 v58, v1
	v_mov_b32_dpp v59, v76 quad_perm:[1,0,3,2] row_mask:0xf bank_mask:0xf
	v_mov_b32_e32 v60, v1
	v_cvt_pk_f16_f32 v75, v80, v81
	v_mov_b32_dpp v58, v62 quad_perm:[1,0,3,2] row_mask:0xf bank_mask:0xf
	v_cndmask_b32_e32 v62, v62, v59, vcc
	v_mov_b32_e32 v59, v1
	v_mov_b32_dpp v60, v74 quad_perm:[1,0,3,2] row_mask:0xf bank_mask:0xf
	v_mov_b32_e32 v61, v1
	v_mov_b32_dpp v59, v63 quad_perm:[1,0,3,2] row_mask:0xf bank_mask:0xf
	v_cndmask_b32_e32 v63, v63, v60, vcc
	v_mov_b32_e32 v60, v1
	v_mov_b32_dpp v61, v75 quad_perm:[1,0,3,2] row_mask:0xf bank_mask:0xf
	v_pk_fma_f32 v[78:79], v[4:5], v[156:157], v[154:155] op_sel:[0,1,0]
	v_mov_b32_dpp v60, v64 quad_perm:[1,0,3,2] row_mask:0xf bank_mask:0xf
	v_cndmask_b32_e32 v64, v64, v61, vcc
	v_mov_b32_e32 v61, v1
	v_cvt_pk_f16_f32 v77, v78, v79
	v_cndmask_b32_e32 v59, v59, v74, vcc
	v_mov_b32_dpp v61, v65 quad_perm:[1,0,3,2] row_mask:0xf bank_mask:0xf
	v_mov_b32_e32 v74, v1
	v_add_u32_e32 v78, s3, v86
	v_cndmask_b32_e32 v58, v58, v76, vcc
	v_cndmask_b32_e32 v60, v60, v75, vcc
	v_mov_b32_dpp v74, v77 quad_perm:[1,0,3,2] row_mask:0xf bank_mask:0xf
	v_cndmask_b32_e32 v61, v61, v77, vcc
	v_cndmask_b32_e32 v65, v65, v74, vcc
	s_mov_b32 s100, 2
	global_store_dwordx4 v78, v[58:61], s[36:37] sc1
	s_nop 1
	v_add_u32_e32 v58, s2, v78
	s_mov_b32 s100, 2
	global_store_dwordx4 v58, v[62:65], s[36:37] sc1
	s_mov_b64 s[2:3], 0
; #define GAS __attribute__((address_space(1)))
; __device__ __forceinline__ float logsigf(float x) { return fminf(x, 0.f) - 0.6931471805599453f * __builtin_amdgcn_logf(1.f + __builtin_amdgcn_exp2f(-1.4426950408889634f * fabsf(x))); }
;     __device__ __forceinline__ void operator()(const f32x4 (&acc)[2][2][4][2], const pg8::Unit& u, int wr, int wc, int fr, int fq) const {
;     ...
;             if (s == 52) {
;                 if (fq < 2) { const f32x4 g0 = *(const GAS f32x4*)(bg + 8 * fq), g1 = *(const GAS f32x4*)(bg + 8 * fq + 4);
; #pragma unroll
;                     for (int ai = 0; ai < 2; ++ai)
; #pragma unroll
;                         for (int m = 0; m < 4; ++m) { const float r = rs[ai][m]; const f32x4 vi = acc[ai][0][m][0] * r + bv[0][0] + g0; f32x4 vf = acc[ai][0][m][1] * r + bv[0][1] + g1;
;                             vf = (f32x4){logsigf(vf[0]), logsigf(vf[1]), logsigf(vf[2]), logsigf(vf[3])};
;                             const unsigned go = (unsigned)WS_G + (rbase + ai * 128 + m * 16) * 64u + 32u * fq; stg_f4(wst, go, vi); stg_f4(wst, go + 16u, vf); } }
;                 return;
.LBB0_633:
	s_and_b64 vcc, exec, s[2:3]
	s_cbranch_vccz .LBB0_637
	v_cmp_gt_i32_e32 vcc, 2, v200
	s_and_saveexec_b64 s[2:3], vcc
	s_cbranch_execz .LBB0_636
	v_lshlrev_b32_e32 v58, 3, v200
	v_readlane_b32 s4, v253, 5
	v_ashrrev_i32_e32 v59, 31, v58
	v_readlane_b32 s5, v253, 6
	v_lshlrev_b32_e32 v75, 6, v201
	s_waitcnt vmcnt(2)
	v_pk_fma_f32 v[68:69], v[68:69], v[176:177], v[134:135] op_sel_hi:[1,0,1]
	v_lshl_add_u64 v[58:59], v[58:59], 2, s[4:5]
	global_load_dwordx4 v[62:65], v[58:59], off
	s_nop 0
	global_load_dwordx4 v[58:61], v[58:59], off offset:16
	v_pk_fma_f32 v[66:67], v[66:67], v[176:177], v[132:133] op_sel_hi:[1,0,1]
	v_mov_b32_e32 v74, v177
	v_pk_fma_f32 v[72:73], v[72:73], v[176:177], v[138:139] op_sel_hi:[1,0,1]
	v_pk_fma_f32 v[70:71], v[70:71], v[176:177], v[136:137] op_sel_hi:[1,0,1]
	v_pk_fma_f32 v[56:57], v[56:57], v[174:175], v[138:139] op_sel_hi:[1,0,1]
	v_pk_fma_f32 v[54:55], v[54:55], v[174:175], v[136:137] op_sel_hi:[1,0,1]
	v_pk_fma_f32 v[76:77], v[44:45], v[174:175], v[134:135] op_sel_hi:[1,0,1]
	v_pk_fma_f32 v[78:79], v[42:43], v[174:175], v[132:133] op_sel_hi:[1,0,1]
	v_lshl_add_u32 v82, v200, 5, v75
	v_pk_fma_f32 v[52:53], v[52:53], v[74:75], v[138:139] op_sel_hi:[1,0,1]
	v_pk_fma_f32 v[50:51], v[50:51], v[74:75], v[136:137] op_sel_hi:[1,0,1]
	v_pk_fma_f32 v[80:81], v[48:49], v[74:75], v[134:135] op_sel_hi:[1,0,1]
	v_pk_fma_f32 v[74:75], v[46:47], v[74:75], v[132:133] op_sel_hi:[1,0,1]
	s_mov_b32 s4, 0xbfb8aa3b
	v_add_u32_e32 v83, 0x2b00000, v82
	v_add_u32_e32 v84, 0x2b00400, v82
	s_mov_b32 s8, 0x3f317218
	v_pk_fma_f32 v[26:27], v[26:27], v[172:173], v[132:133] op_sel_hi:[1,0,1]
	v_pk_fma_f32 v[28:29], v[28:29], v[172:173], v[134:135] op_sel_hi:[1,0,1]
	v_pk_fma_f32 v[32:33], v[32:33], v[172:173], v[138:139] op_sel_hi:[1,0,1]
	v_pk_fma_f32 v[30:31], v[30:31], v[172:173], v[136:137] op_sel_hi:[1,0,1]
	v_pk_fma_f32 v[10:11], v[10:11], v[170:171], v[132:133] op_sel_hi:[1,0,1]
	v_pk_fma_f32 v[12:13], v[12:13], v[170:171], v[134:135] op_sel_hi:[1,0,1]
	v_pk_fma_f32 v[16:17], v[16:17], v[170:171], v[138:139] op_sel_hi:[1,0,1]
	v_pk_fma_f32 v[14:15], v[14:15], v[170:171], v[136:137] op_sel_hi:[1,0,1]
	s_waitcnt vmcnt(1)
	v_pk_add_f32 v[44:45], v[72:73], v[64:65]
	s_waitcnt vmcnt(0)
	v_pk_add_f32 v[68:69], v[68:69], v[60:61]
	v_pk_add_f32 v[66:67], v[66:67], v[58:59]
	v_pk_add_f32 v[42:43], v[70:71], v[62:63]
	v_pk_add_f32 v[48:49], v[52:53], v[64:65]
	v_pk_add_f32 v[46:47], v[50:51], v[62:63]
	v_pk_add_f32 v[70:71], v[80:81], v[60:61]
	v_pk_add_f32 v[72:73], v[74:75], v[58:59]
	v_pk_add_f32 v[52:53], v[56:57], v[64:65]
	v_pk_add_f32 v[50:51], v[54:55], v[62:63]
	v_pk_add_f32 v[54:55], v[76:77], v[60:61]
	v_pk_add_f32 v[56:57], v[78:79], v[58:59]
	v_mul_f32_e64 v76, |v66|, s4
	v_mul_f32_e64 v77, |v67|, s4
	v_mul_f32_e64 v78, |v68|, s4
	v_mul_f32_e64 v79, |v69|, s4
	v_min_f32_e32 v74, 0, v66
	v_min_f32_e32 v66, 0, v68
	s_mov_b32 s100, 2
	global_store_dwordx4 v83, v[42:45], s[36:37] sc1
	v_min_f32_e32 v68, 0, v72
	s_mov_b32 s100, 2
	global_store_dwordx4 v84, v[46:49], s[36:37] sc1
	v_mul_f32_e64 v42, |v72|, s4
	v_mul_f32_e64 v43, |v73|, s4
	v_min_f32_e32 v72, 0, v70
	v_mul_f32_e64 v44, |v70|, s4
	v_mul_f32_e64 v45, |v71|, s4
	v_min_f32_e32 v70, 0, v56
	v_mul_f32_e64 v46, |v56|, s4
	v_exp_f32_e32 v47, v76
	v_exp_f32_e32 v48, v77
	v_exp_f32_e32 v49, v78
	v_exp_f32_e32 v56, v79
	v_exp_f32_e32 v42, v42
	v_exp_f32_e32 v43, v43
	v_exp_f32_e32 v44, v44
	v_exp_f32_e32 v45, v45
	v_exp_f32_e32 v46, v46
	v_add_f32_e32 v47, 1.0, v47
	v_add_f32_e32 v48, 1.0, v48
	v_add_f32_e32 v49, 1.0, v49
	v_add_f32_e32 v56, 1.0, v56
	v_min_f32_e32 v75, 0, v67
	v_min_f32_e32 v67, 0, v69
	v_min_f32_e32 v69, 0, v73
	v_min_f32_e32 v73, 0, v71
	v_min_f32_e32 v71, 0, v57
	v_mul_f32_e64 v80, |v57|, s4
	v_add_f32_e32 v42, 1.0, v42
	v_add_f32_e32 v43, 1.0, v43
	v_add_f32_e32 v44, 1.0, v44
	v_add_f32_e32 v45, 1.0, v45
	v_log_f32_e32 v57, v47
	v_log_f32_e32 v47, v48
	v_log_f32_e32 v48, v49
	v_log_f32_e32 v49, v56
	v_log_f32_e32 v56, v42
	v_log_f32_e32 v76, v43
	v_log_f32_e32 v44, v44
	v_log_f32_e32 v45, v45
	v_add_f32_e32 v46, 1.0, v46
	v_log_f32_e32 v77, v46
	v_xor_b32_e32 v43, 0x80000000, v49
	v_xor_b32_e32 v42, 0x80000000, v48
	v_xor_b32_e32 v47, 0x80000000, v47
	v_xor_b32_e32 v46, 0x80000000, v57
	v_xor_b32_e32 v49, 0x80000000, v45
	v_xor_b32_e32 v48, 0x80000000, v44
	v_xor_b32_e32 v57, 0x80000000, v76
	v_xor_b32_e32 v56, 0x80000000, v56
	v_pk_fma_f32 v[44:45], v[42:43], s[8:9], v[66:67] op_sel_hi:[1,0,1]
	v_pk_fma_f32 v[42:43], v[46:47], s[8:9], v[74:75] op_sel_hi:[1,0,1]
	v_pk_fma_f32 v[48:49], v[48:49], s[8:9], v[72:73] op_sel_hi:[1,0,1]
	v_pk_fma_f32 v[46:47], v[56:57], s[8:9], v[68:69] op_sel_hi:[1,0,1]
	s_mov_b32 s100, 2
	global_store_dwordx4 v83, v[42:45], s[36:37] offset:16 sc1
	s_mov_b32 s100, 2
	global_store_dwordx4 v84, v[46:49], s[36:37] offset:16 sc1
	v_pk_add_f32 v[26:27], v[26:27], v[58:59]
	v_exp_f32_e32 v42, v80
	v_mul_f32_e64 v43, |v54|, s4
	v_mul_f32_e64 v44, |v55|, s4
	v_exp_f32_e32 v43, v43
	v_exp_f32_e32 v44, v44
	v_add_f32_e32 v42, 1.0, v42
	v_log_f32_e32 v46, v42
	v_add_f32_e32 v42, 1.0, v43
	v_add_f32_e32 v43, 1.0, v44
	v_log_f32_e32 v44, v43
	v_log_f32_e32 v47, v42
	v_min_f32_e32 v42, 0, v54
	v_min_f32_e32 v43, 0, v55
	v_xor_b32_e32 v45, 0x80000000, v44
	v_xor_b32_e32 v44, 0x80000000, v47
	v_pk_fma_f32 v[44:45], v[44:45], s[8:9], v[42:43] op_sel_hi:[1,0,1]
	v_xor_b32_e32 v43, 0x80000000, v46
	v_xor_b32_e32 v42, 0x80000000, v77
	v_pk_fma_f32 v[42:43], v[42:43], s[8:9], v[70:71] op_sel_hi:[1,0,1]
	v_add_u32_e32 v46, 0x2b00800, v82
	s_mov_b32 s100, 2
	global_store_dwordx4 v46, v[50:53], s[36:37] sc1
	s_mov_b32 s100, 2
; #define GAS __attribute__((address_space(1)))
; __device__ __forceinline__ float logsigf(float x) { return fminf(x, 0.f) - 0.6931471805599453f * __builtin_amdgcn_logf(1.f + __builtin_amdgcn_exp2f(-1.4426950408889634f * fabsf(x))); }
;     __device__ __forceinline__ void operator()(const f32x4 (&acc)[2][2][4][2], const pg8::Unit& u, int wr, int wc, int fr, int fq) const {
;     ...
;             if (s == 52) {
;                 if (fq < 2) { const f32x4 g0 = *(const GAS f32x4*)(bg + 8 * fq), g1 = *(const GAS f32x4*)(bg + 8 * fq + 4);
; #pragma unroll
;                     for (int ai = 0; ai < 2; ++ai)
; #pragma unroll
;                         for (int m = 0; m < 4; ++m) { const float r = rs[ai][m]; const f32x4 vi = acc[ai][0][m][0] * r + bv[0][0] + g0; f32x4 vf = acc[ai][0][m][1] * r + bv[0][1] + g1;
;                             vf = (f32x4){logsigf(vf[0]), logsigf(vf[1]), logsigf(vf[2]), logsigf(vf[3])};
;                             const unsigned go = (unsigned)WS_G + (rbase + ai * 128 + m * 16) * 64u + 32u * fq; stg_f4(wst, go, vi); stg_f4(wst, go + 16u, vf); } }
;                 return;
	global_store_dwordx4 v46, v[42:45], s[36:37] offset:16 sc1
	v_pk_add_f32 v[28:29], v[28:29], v[60:61]
	v_pk_add_f32 v[32:33], v[32:33], v[64:65]
	v_mov_b32_e32 v42, v175
	v_pk_fma_f32 v[34:35], v[34:35], v[42:43], v[132:133] op_sel_hi:[1,0,1]
	v_pk_fma_f32 v[40:41], v[40:41], v[42:43], v[138:139] op_sel_hi:[1,0,1]
	v_pk_add_f32 v[34:35], v[34:35], v[58:59]
	v_pk_fma_f32 v[38:39], v[38:39], v[42:43], v[136:137] op_sel_hi:[1,0,1]
	v_mul_f32_e64 v43, |v34|, s4
	v_exp_f32_e32 v43, v43
	v_pk_add_f32 v[40:41], v[40:41], v[64:65]
	v_pk_add_f32 v[38:39], v[38:39], v[62:63]
	v_pk_add_f32 v[30:31], v[30:31], v[62:63]
	v_pk_fma_f32 v[36:37], v[36:37], v[42:43], v[134:135] op_sel_hi:[1,0,1]
	v_min_f32_e32 v42, 0, v34
	v_add_f32_e32 v34, 1.0, v43
	v_pk_add_f32 v[36:37], v[36:37], v[60:61]
	v_log_f32_e32 v44, v34
	v_mul_f32_e64 v34, |v35|, s4
	v_min_f32_e32 v43, 0, v35
	v_exp_f32_e32 v34, v34
	v_mul_f32_e64 v35, |v36|, s4
	v_mul_f32_e64 v45, |v37|, s4
	v_exp_f32_e32 v35, v35
	v_exp_f32_e32 v45, v45
	v_add_f32_e32 v34, 1.0, v34
	v_log_f32_e32 v46, v34
	v_add_f32_e32 v34, 1.0, v35
	v_add_f32_e32 v35, 1.0, v45
	v_log_f32_e32 v45, v35
	v_log_f32_e32 v47, v34
	v_min_f32_e32 v34, 0, v36
	v_min_f32_e32 v35, 0, v37
	v_xor_b32_e32 v37, 0x80000000, v45
	v_xor_b32_e32 v36, 0x80000000, v47
	v_pk_fma_f32 v[36:37], v[36:37], s[8:9], v[34:35] op_sel_hi:[1,0,1]
	v_xor_b32_e32 v35, 0x80000000, v46
	v_xor_b32_e32 v34, 0x80000000, v44
	v_pk_fma_f32 v[34:35], v[34:35], s[8:9], v[42:43] op_sel_hi:[1,0,1]
	v_add_u32_e32 v42, 0x2b00c00, v82
	s_mov_b32 s100, 2
	global_store_dwordx4 v42, v[38:41], s[36:37] sc1
	s_mov_b32 s100, 2
	global_store_dwordx4 v42, v[34:37], s[36:37] offset:16 sc1
	v_pk_add_f32 v[10:11], v[10:11], v[58:59]
	v_mul_f32_e64 v38, |v29|, s4
	v_mul_f32_e64 v34, |v26|, s4
	v_exp_f32_e32 v35, v34
	v_min_f32_e32 v34, 0, v26
	v_exp_f32_e32 v38, v38
	v_add_u32_e32 v36, 0x2b02000, v82
	v_add_f32_e32 v26, 1.0, v35
	v_log_f32_e32 v37, v26
	v_mul_f32_e64 v26, |v27|, s4
	v_min_f32_e32 v35, 0, v27
	v_exp_f32_e32 v26, v26
	v_mul_f32_e64 v27, |v28|, s4
	v_exp_f32_e32 v27, v27
	v_pk_add_f32 v[12:13], v[12:13], v[60:61]
	v_add_f32_e32 v26, 1.0, v26
	v_log_f32_e32 v39, v26
	v_add_f32_e32 v26, 1.0, v27
	v_add_f32_e32 v27, 1.0, v38
	v_log_f32_e32 v38, v27
	v_log_f32_e32 v40, v26
	v_min_f32_e32 v26, 0, v28
	v_min_f32_e32 v27, 0, v29
	v_xor_b32_e32 v29, 0x80000000, v38
	v_xor_b32_e32 v28, 0x80000000, v40
	v_pk_fma_f32 v[28:29], v[28:29], s[8:9], v[26:27] op_sel_hi:[1,0,1]
	v_xor_b32_e32 v27, 0x80000000, v39
	v_xor_b32_e32 v26, 0x80000000, v37
	v_pk_fma_f32 v[26:27], v[26:27], s[8:9], v[34:35] op_sel_hi:[1,0,1]
	s_mov_b32 s100, 2
	global_store_dwordx4 v36, v[30:33], s[36:37] sc1
	s_mov_b32 s100, 2
	global_store_dwordx4 v36, v[26:29], s[36:37] offset:16 sc1
	v_pk_add_f32 v[16:17], v[16:17], v[64:65]
	v_pk_add_f32 v[14:15], v[14:15], v[62:63]
	v_mov_b32_e32 v26, v173
	v_pk_fma_f32 v[18:19], v[18:19], v[26:27], v[132:133] op_sel_hi:[1,0,1]
	v_pk_fma_f32 v[24:25], v[24:25], v[26:27], v[138:139] op_sel_hi:[1,0,1]
	v_pk_add_f32 v[18:19], v[18:19], v[58:59]
	v_pk_fma_f32 v[22:23], v[22:23], v[26:27], v[136:137] op_sel_hi:[1,0,1]
	v_mul_f32_e64 v27, |v18|, s4
	v_exp_f32_e32 v27, v27
	v_pk_add_f32 v[24:25], v[24:25], v[64:65]
	v_pk_add_f32 v[22:23], v[22:23], v[62:63]
	v_pk_fma_f32 v[20:21], v[20:21], v[26:27], v[134:135] op_sel_hi:[1,0,1]
	v_min_f32_e32 v26, 0, v18
	v_add_f32_e32 v18, 1.0, v27
	v_pk_add_f32 v[20:21], v[20:21], v[60:61]
	v_log_f32_e32 v28, v18
	v_mul_f32_e64 v18, |v19|, s4
	v_min_f32_e32 v27, 0, v19
	v_exp_f32_e32 v18, v18
	v_mul_f32_e64 v19, |v20|, s4
	v_mul_f32_e64 v29, |v21|, s4
	v_exp_f32_e32 v19, v19
	v_exp_f32_e32 v29, v29
	v_add_f32_e32 v18, 1.0, v18
	v_log_f32_e32 v30, v18
	v_add_f32_e32 v18, 1.0, v19
	v_add_f32_e32 v19, 1.0, v29
	v_log_f32_e32 v29, v19
	v_log_f32_e32 v31, v18
	v_min_f32_e32 v18, 0, v20
	v_min_f32_e32 v19, 0, v21
	v_xor_b32_e32 v21, 0x80000000, v29
	v_xor_b32_e32 v20, 0x80000000, v31
	v_pk_fma_f32 v[20:21], v[20:21], s[8:9], v[18:19] op_sel_hi:[1,0,1]
	v_xor_b32_e32 v19, 0x80000000, v30
	v_xor_b32_e32 v18, 0x80000000, v28
	v_pk_fma_f32 v[18:19], v[18:19], s[8:9], v[26:27] op_sel_hi:[1,0,1]
	v_add_u32_e32 v26, 0x2b02400, v82
	s_mov_b32 s100, 2
	global_store_dwordx4 v26, v[22:25], s[36:37] sc1
	s_mov_b32 s100, 2
	global_store_dwordx4 v26, v[18:21], s[36:37] offset:16 sc1
	s_nop 1
	v_mul_f32_e64 v18, |v10|, s4
	v_exp_f32_e32 v19, v18
	v_min_f32_e32 v18, 0, v10
	v_mul_f32_e64 v21, |v13|, s4
	v_exp_f32_e32 v21, v21
	v_add_f32_e32 v10, 1.0, v19
	v_log_f32_e32 v20, v10
	v_mul_f32_e64 v10, |v11|, s4
	v_min_f32_e32 v19, 0, v11
	v_exp_f32_e32 v10, v10
	v_mul_f32_e64 v11, |v12|, s4
	v_exp_f32_e32 v11, v11
	v_add_f32_e32 v10, 1.0, v10
	v_log_f32_e32 v22, v10
	v_add_f32_e32 v10, 1.0, v11
	v_add_f32_e32 v11, 1.0, v21
	v_log_f32_e32 v21, v11
	v_log_f32_e32 v23, v10
	v_min_f32_e32 v10, 0, v12
	v_min_f32_e32 v11, 0, v13
	v_xor_b32_e32 v13, 0x80000000, v21
	v_xor_b32_e32 v12, 0x80000000, v23
	v_pk_fma_f32 v[12:13], v[12:13], s[8:9], v[10:11] op_sel_hi:[1,0,1]
	v_xor_b32_e32 v11, 0x80000000, v22
	v_xor_b32_e32 v10, 0x80000000, v20
	v_pk_fma_f32 v[10:11], v[10:11], s[8:9], v[18:19] op_sel_hi:[1,0,1]
	v_add_u32_e32 v18, 0x2b02800, v82
	s_mov_b32 s100, 2
	global_store_dwordx4 v18, v[14:17], s[36:37] sc1
	s_mov_b32 s100, 2
	global_store_dwordx4 v18, v[10:13], s[36:37] offset:16 sc1
	s_nop 1
	v_mov_b32_e32 v10, v171
	v_pk_fma_f32 v[2:3], v[2:3], v[10:11], v[132:133] op_sel_hi:[1,0,1]
	v_pk_fma_f32 v[8:9], v[8:9], v[10:11], v[138:139] op_sel_hi:[1,0,1]
	v_pk_add_f32 v[2:3], v[2:3], v[58:59]
	v_pk_fma_f32 v[6:7], v[6:7], v[10:11], v[136:137] op_sel_hi:[1,0,1]
	v_mul_f32_e64 v11, |v2|, s4
	v_exp_f32_e32 v11, v11
	v_pk_add_f32 v[8:9], v[8:9], v[64:65]
	v_pk_add_f32 v[6:7], v[6:7], v[62:63]
	v_pk_fma_f32 v[4:5], v[4:5], v[10:11], v[134:135] op_sel_hi:[1,0,1]
	v_min_f32_e32 v10, 0, v2
	v_add_f32_e32 v2, 1.0, v11
	v_pk_add_f32 v[4:5], v[4:5], v[60:61]
	v_log_f32_e32 v12, v2
	v_mul_f32_e64 v2, |v3|, s4
	v_min_f32_e32 v11, 0, v3
	v_exp_f32_e32 v2, v2
	v_mul_f32_e64 v3, |v4|, s4
	v_mul_f32_e64 v13, |v5|, s4
	v_exp_f32_e32 v3, v3
	v_exp_f32_e32 v13, v13
	v_add_f32_e32 v2, 1.0, v2
	v_log_f32_e32 v14, v2
	v_add_f32_e32 v2, 1.0, v3
	v_add_f32_e32 v3, 1.0, v13
	v_log_f32_e32 v13, v3
	v_log_f32_e32 v15, v2
	v_min_f32_e32 v2, 0, v4
	v_min_f32_e32 v3, 0, v5
	v_xor_b32_e32 v5, 0x80000000, v13
	v_xor_b32_e32 v4, 0x80000000, v15
	v_pk_fma_f32 v[4:5], v[4:5], s[8:9], v[2:3] op_sel_hi:[1,0,1]
	v_xor_b32_e32 v3, 0x80000000, v14
	v_xor_b32_e32 v2, 0x80000000, v12
	v_pk_fma_f32 v[2:3], v[2:3], s[8:9], v[10:11] op_sel_hi:[1,0,1]
	v_add_u32_e32 v10, 0x2b02c00, v82
	s_mov_b32 s100, 2
	global_store_dwordx4 v10, v[6:9], s[36:37] sc1
	s_mov_b32 s100, 2
	global_store_dwordx4 v10, v[2:5], s[36:37] offset:16 sc1

; __device__ __forceinline__ void p0c(Frame& F) {
;     ...
;           for (int o = F.tid; o < 17 * 64; o += NTHREADS) { const int bb = o >> 6, c2 = o & 63; float s = 0.f;
; #pragma unroll
;               for (int g = 0; g < 8; ++g) s += RED[(g * 17 + bb) * 64 + c2];
;               ((float*)(ws + WS_SHW))[((size_t)l * 17 + bb) * NPAD + nb * 64 + c2] = s; }
.LBB0_678:
	v_ashrrev_i32_e32 v6, 6, v4
	v_lshl_add_u32 v5, v6, 8, v73
	ds_read2st64_b32 v[8:9], v5 offset1:17
	s_waitcnt lgkmcnt(0)
	v_add_f32_e32 v7, 0, v8
	v_add_f32_e32 v7, v7, v9
	ds_read2st64_b32 v[8:9], v5 offset0:34 offset1:51
	s_waitcnt lgkmcnt(0)
	v_add_f32_e32 v7, v7, v8
	v_add_f32_e32 v7, v7, v9
	ds_read2st64_b32 v[8:9], v5 offset0:68 offset1:85
	s_waitcnt lgkmcnt(0)
	v_add_f32_e32 v7, v7, v8
	v_add_f32_e32 v7, v7, v9
	ds_read2st64_b32 v[8:9], v5 offset0:102 offset1:119
	s_waitcnt lgkmcnt(0)
	v_add_f32_e32 v5, v7, v8
	v_ashrrev_i32_e32 v7, 31, v6
	v_lshl_add_u64 v[6:7], s[38:39], 0, v[6:7]
	v_add_f32_e32 v5, v5, v9
	v_mad_u64_u32 v[8:9], s[24:25], v6, s91, v[2:3]
	v_mov_b32_e32 v6, v9
	v_mad_u64_u32 v[6:7], s[24:25], v7, s91, v[6:7]
	v_mov_b32_e32 v9, v6
	flat_store_dword v[8:9], v5 sc1
	v_add_u32_e32 v5, 0x200, v4
	v_cmp_lt_i32_e64 s[24:25], s72, v4
	s_or_b64 s[42:43], s[24:25], s[42:43]
	v_mov_b32_e32 v4, v5
	s_andn2_b64 exec, exec, s[42:43]
	s_cbranch_execnz .LBB0_678
	s_branch .LBB0_645

; __device__ __forceinline__ void p0c(Frame& F) {
;     ...
;     { float* AM = (float*)(ws + WS_AMOD); const int gt = F.bid * NTHREADS + F.tid;
;       for (int i = gt; i < DEPTH * 17 * 1024; i += F.G * NTHREADS) { const int k = i & 1023, lb = i >> 10, l = lb / 17; AM[i] = p.gnorm[l * D + k] * (1.f + MOD[(size_t)lb * 3072 + 1024 + k]); } }
.LBB0_700:
	v_ashrrev_i32_e32 v5, 10, v4
	s_mov_b32 s4, 0x78787879
	v_mul_hi_i32 v6, v5, s4
	v_lshrrev_b32_e32 v7, 31, v6
	v_lshrrev_b32_e32 v6, 3, v6
	v_and_b32_e32 v0, 0x3ff, v4
	v_add_u32_e32 v6, v6, v7
	v_lshl_or_b32 v6, v6, 10, v0
	v_ashrrev_i32_e32 v7, 31, v6
	v_lshl_add_u64 v[6:7], v[6:7], 2, s[16:17]
	global_load_dword v8, v[6:7], off
	v_mul_hi_i32_i24_e32 v7, 0x3000, v5
	v_mul_i32_i24_e32 v6, 0x3000, v5
	v_lshl_add_u64 v[6:7], s[36:37], 0, v[6:7]
	v_lshlrev_b32_e32 v0, 2, v0
	v_lshl_add_u64 v[6:7], v[6:7], 0, v[0:1]
	v_add_co_u32_e32 v6, vcc, 0x1000, v6
	v_add_u32_e32 v4, s28, v4
	s_nop 0
	v_addc_co_u32_e32 v7, vcc, 0, v7, vcc
	flat_load_dword v0, v[6:7]
	s_mov_b32 s4, 0x10fff
	v_cmp_lt_i32_e32 vcc, s4, v4
	s_or_b64 s[2:3], vcc, s[2:3]
	s_waitcnt vmcnt(0) lgkmcnt(0)
	v_add_f32_e32 v0, 1.0, v0
	v_mul_f32_e32 v0, v8, v0
	flat_store_dword v[2:3], v0 sc1
	v_lshl_add_u64 v[2:3], v[2:3], 0, s[30:31]
	s_andn2_b64 exec, exec, s[2:3]
	s_cbranch_execnz .LBB0_700

; #define GAS __attribute__((address_space(1)))
; __device__ __forceinline__ float lx_xor(float v, int m, int lane) { return __int_as_float(__builtin_amdgcn_ds_bpermute((lane ^ m) << 2, __float_as_int(v))); }
; __device__ __forceinline__ unsigned cvtpk_h(float lo, float hi) { f32x2 v = {lo, hi}; h16x2 b = __builtin_convertvector(v, h16x2); return __builtin_bit_cast(unsigned, b); }
; __device__ __forceinline__ void p0c(Frame& F) {
;     ...
;     { const int gw = F.bid * NWAVES + F.wave, NGW = F.G * NWAVES; h16* XS = (h16*)(ws + WS_XS); h16* X16 = (h16*)(ws + WS_X16); float* RQ = (float*)(ws + WS_ROWSQ);
;       for (int r0 = gw; r0 < MROWS; r0 += 2 * NGW) {
;           f32x4 xv[2][2][2]; int rr[2]; bool ok[2];
; #pragma unroll
;           for (int q = 0; q < 2; ++q) { rr[q] = r0 + q * NGW; ok[q] = rr[q] < MROWS; const int r = ok[q] ? rr[q] : gw; const float* xr = r < MLAT ? p.x + (size_t)r * D : p.ctx + (size_t)(r - MLAT) * D;
; #pragma unroll
;               for (int j = 0; j < 2; ++j) { const int k = j * 512 + F.lane * 8; xv[q][j][0] = *(const GAS f32x4*)(xr + k); xv[q][j][1] = *(const GAS f32x4*)(xr + k + 4); } }
; #pragma unroll
;           for (int q = 0; q < 2; ++q) { const int r = ok[q] ? rr[q] : gw; const int bb = r < MLAT ? (r >> 11) : 16; const float* mod = MOD + (size_t)bb * 3072 + 1024; float ss = 0.f;
; #pragma unroll
;               for (int j = 0; j < 2; ++j) { const int k = j * 512 + F.lane * 8; u32x4 wx, wy;
; #pragma unroll
;                   for (int hh = 0; hh < 2; ++hh) { const f32x4 v = xv[q][j][hh], g = *(const GAS f32x4*)(p.gnorm + k + 4 * hh), s1 = *(const GAS f32x4*)(mod + k + 4 * hh);
;                       ss += (v[0] * v[0] + v[1] * v[1]) + (v[2] * v[2] + v[3] * v[3]); const f32x4 y = v * (g * (s1 + 1.f));
;                       if (hh == 0) { wy.x = cvtpk_h(y[0], y[1]); wy.y = cvtpk_h(y[2], y[3]); wx.x = cvtpk_h(v[0], v[1]); wx.y = cvtpk_h(v[2], v[3]); } else { wy.z = cvtpk_h(y[0], y[1]); wy.w = cvtpk_h(y[2], y[3]); wx.z = cvtpk_h(v[0], v[1]); wx.w = cvtpk_h(v[2], v[3]); } }
;                   if (ok[q]) { *(GAS u32x4*)(XS + (size_t)r * D + k) = wy; *(GAS u32x4*)(X16 + (size_t)r * D + k) = wx; } }
; #pragma unroll
;               for (int o = 1; o < 64; o <<= 1) ss += lx_xor(ss, o, F.lane);
;               if (ok[q] && F.lane == 0) *(GAS float*)(RQ + r) = ss; } }
.LBB0_704:
	s_add_i32 s2, s6, 0xffff8000
	s_cmp_lt_i32 s6, 0x8000
	v_readlane_b32 s56, v251, 15
	s_cselect_b32 s3, s7, 0
	s_cselect_b32 s2, s6, s2
	v_readlane_b32 s57, v251, 16
	v_readlane_b32 s60, v251, 19
	v_readlane_b32 s61, v251, 20
	s_cselect_b32 s5, s57, s61
	s_cselect_b32 s8, s56, s60
	s_lshl_b64 s[2:3], s[2:3], 12
	s_add_u32 s2, s8, s2
	s_addc_u32 s3, s5, s3
	v_lshlrev_b64 v[44:45], 2, v[36:37]
	s_waitcnt lgkmcnt(0)
	v_lshl_add_u64 v[2:3], s[2:3], 0, v[44:45]
	global_load_dwordx4 v[26:29], v[2:3], off offset:16
	global_load_dwordx4 v[30:33], v[2:3], off
	global_load_dwordx4 v[18:21], v[2:3], off offset:2064
	global_load_dwordx4 v[22:25], v[2:3], off offset:2048
	s_add_i32 s5, s78, s6
	s_cmp_lt_i32 s5, 0x9000
	s_cselect_b64 s[10:11], -1, 0
	s_and_b64 s[2:3], s[10:11], exec
	s_cselect_b32 s8, s5, s4
	s_ashr_i32 s9, s8, 31
	s_add_i32 s2, s8, 0xffff8000
	s_cmp_lt_i32 s8, 0x8000
	s_cselect_b32 s3, s9, 0
	s_cselect_b32 s2, s8, s2
	s_cselect_b32 s5, s57, s61
	s_cselect_b32 s12, s56, s60
	s_lshl_b64 s[2:3], s[2:3], 12
	s_add_u32 s2, s12, s2
	s_addc_u32 s3, s5, s3
	v_lshl_add_u64 v[6:7], s[2:3], 0, v[44:45]
	s_min_i32 s2, s6, 0x8000
	s_ashr_i32 s2, s2, 11
	s_mul_hi_i32 s3, s2, 0x3000
	s_mulk_i32 s2, 0x3000
	s_add_u32 s2, s36, s2
	s_addc_u32 s3, s37, s3
	v_lshl_add_u64 v[60:61], s[2:3], 0, v[44:45]
	s_mov_b64 s[2:3], 0x1000
	v_lshl_add_u64 v[44:45], v[60:61], 0, s[2:3]
	s_movk_i32 s2, 0x1000
	v_add_co_u32_e32 v60, vcc, s2, v60
	global_load_dwordx4 v[10:13], v[6:7], off offset:16
	global_load_dwordx4 v[14:17], v[6:7], off
	global_load_dwordx4 v[2:5], v[6:7], off offset:2064
	s_nop 0
	global_load_dwordx4 v[6:9], v[6:7], off offset:2048
	v_addc_co_u32_e32 v61, vcc, 0, v61, vcc
	v_readlane_b32 s2, v253, 0
	v_readlane_b32 s3, v253, 1
	v_readlane_b32 s58, v251, 17
	v_readlane_b32 s59, v251, 18
	v_readlane_b32 s62, v251, 21
	v_readlane_b32 s63, v251, 22
	v_readlane_b32 s64, v251, 23
	v_readlane_b32 s65, v251, 24
	v_readlane_b32 s66, v251, 25
	v_readlane_b32 s67, v251, 26
	v_readlane_b32 s68, v251, 27
	v_readlane_b32 s69, v251, 28
	v_readlane_b32 s70, v251, 29
	v_readlane_b32 s71, v251, 30
	s_waitcnt vmcnt(0)
	v_mul_f32_e32 v46, v31, v31
	v_mul_f32_e32 v47, v33, v33
	v_fmac_f32_e32 v46, v30, v30
	v_fmac_f32_e32 v47, v32, v32
	v_add_f32_e32 v55, v46, v47
	global_load_dwordx4 v[46:49], v[40:41], off offset:16
	global_load_dwordx4 v[56:59], v[40:41], off
	s_nop 0
	global_load_dwordx4 v[60:63], v[60:61], off
	s_nop 0
	global_load_dwordx4 v[64:67], v[44:45], off offset:16
	s_waitcnt vmcnt(0)
	v_pk_add_f32 v[62:63], v[62:63], 1.0 op_sel_hi:[1,0]
	v_pk_add_f32 v[60:61], v[60:61], 1.0 op_sel_hi:[1,0]
	v_pk_mul_f32 v[58:59], v[58:59], v[62:63]
	v_pk_mul_f32 v[56:57], v[56:57], v[60:61]
	v_pk_mul_f32 v[58:59], v[32:33], v[58:59]
	v_pk_mul_f32 v[56:57], v[30:31], v[56:57]
	v_cvt_pk_f16_f32 v30, v30, v31
	v_cvt_pk_f16_f32 v31, v32, v33
	v_mul_f32_e32 v32, v27, v27
	v_mul_f32_e32 v33, v29, v29
	v_fmac_f32_e32 v32, v26, v26
	v_fmac_f32_e32 v33, v28, v28
	v_add_f32_e32 v32, v32, v33
	v_add_f32_e32 v55, v55, v32
	v_pk_add_f32 v[32:33], v[66:67], 1.0 op_sel_hi:[1,0]
	v_cvt_pk_f16_f32 v56, v56, v57
	v_cvt_pk_f16_f32 v57, v58, v59
	v_pk_add_f32 v[58:59], v[64:65], 1.0 op_sel_hi:[1,0]
	v_pk_mul_f32 v[32:33], v[48:49], v[32:33]
	v_pk_mul_f32 v[46:47], v[46:47], v[58:59]
	v_pk_mul_f32 v[32:33], v[28:29], v[32:33]
	v_pk_mul_f32 v[46:47], v[26:27], v[46:47]
	v_cvt_pk_f16_f32 v59, v32, v33
	v_cvt_pk_f16_f32 v32, v26, v27
	v_lshl_add_u64 v[26:27], s[2:3], 0, v[42:43]
	s_mov_b32 s2, 0x3d80000
	v_cvt_pk_f16_f32 v58, v46, v47
	v_add_co_u32_e32 v46, vcc, s2, v26
	s_mov_b32 s2, 0x16f80000
	s_nop 0
	v_addc_co_u32_e32 v47, vcc, 0, v27, vcc
	v_add_co_u32_e32 v48, vcc, s2, v26
	v_mul_f32_e32 v26, v23, v23
	s_nop 0
	v_addc_co_u32_e32 v49, vcc, 0, v27, vcc
	v_mul_f32_e32 v27, v25, v25
	v_cvt_pk_f16_f32 v33, v28, v29
	v_fmac_f32_e32 v26, v22, v22
	v_fmac_f32_e32 v27, v24, v24
	global_store_dwordx4 v[46:47], v[56:59], off sc1
	global_store_dwordx4 v[48:49], v[30:33], off sc1
	v_add_f32_e32 v26, v26, v27
	v_add_f32_e32 v55, v55, v26
	global_load_dwordx4 v[26:29], v[40:41], off offset:2064
	global_load_dwordx4 v[56:59], v[40:41], off offset:2048
	global_load_dwordx4 v[30:33], v[44:45], off offset:2064
	global_load_dwordx4 v[60:63], v[44:45], off offset:2048
	s_waitcnt vmcnt(0)
	v_pk_add_f32 v[30:31], v[30:31], 1.0 op_sel_hi:[1,0]
	v_pk_add_f32 v[44:45], v[62:63], 1.0 op_sel_hi:[1,0]
	v_pk_add_f32 v[60:61], v[60:61], 1.0 op_sel_hi:[1,0]
	v_pk_mul_f32 v[44:45], v[58:59], v[44:45]
	v_pk_mul_f32 v[56:57], v[56:57], v[60:61]
	v_pk_mul_f32 v[44:45], v[24:25], v[44:45]
	v_pk_mul_f32 v[56:57], v[22:23], v[56:57]
	v_cvt_pk_f16_f32 v22, v22, v23
	v_cvt_pk_f16_f32 v23, v24, v25
	v_mul_f32_e32 v24, v19, v19
	v_mul_f32_e32 v25, v21, v21
	v_fmac_f32_e32 v24, v18, v18
	v_fmac_f32_e32 v25, v20, v20
	v_add_f32_e32 v24, v24, v25
	v_cvt_pk_f16_f32 v56, v56, v57
	v_cvt_pk_f16_f32 v57, v44, v45
	v_add_f32_e32 v44, v55, v24
	v_pk_add_f32 v[24:25], v[32:33], 1.0 op_sel_hi:[1,0]
	v_pk_mul_f32 v[26:27], v[26:27], v[30:31]
	v_pk_mul_f32 v[24:25], v[28:29], v[24:25]
	v_pk_mul_f32 v[26:27], v[18:19], v[26:27]
	v_pk_mul_f32 v[24:25], v[20:21], v[24:25]
	v_cvt_pk_f16_f32 v58, v26, v27
	v_cvt_pk_f16_f32 v59, v24, v25
	v_cvt_pk_f16_f32 v24, v18, v19
	ds_bpermute_b32 v18, v0, v44
	v_cvt_pk_f16_f32 v25, v20, v21
	global_store_dwordx4 v[46:47], v[56:59], off offset:1024 sc1
	global_store_dwordx4 v[48:49], v[22:25], off offset:1024 sc1
	s_waitcnt lgkmcnt(0)
	v_add_f32_e32 v18, v44, v18
	ds_bpermute_b32 v19, v50, v18
	s_waitcnt lgkmcnt(0)
	v_add_f32_e32 v18, v18, v19
	ds_bpermute_b32 v19, v51, v18
	s_waitcnt lgkmcnt(0)
	v_add_f32_e32 v18, v18, v19
	ds_bpermute_b32 v19, v52, v18
	s_waitcnt lgkmcnt(0)
	v_add_f32_e32 v18, v18, v19
	ds_bpermute_b32 v19, v53, v18
	s_waitcnt lgkmcnt(0)
	v_add_f32_e32 v18, v18, v19
	ds_bpermute_b32 v19, v54, v18
	s_and_saveexec_b64 s[2:3], s[0:1]
	s_cbranch_execz .LBB0_706
	v_readlane_b32 s12, v253, 0
	v_readlane_b32 s13, v253, 1
	s_add_u32 s12, s12, s20
	s_addc_u32 s13, s13, s21
	s_waitcnt lgkmcnt(0)
	v_add_f32_e32 v18, v18, v19
	s_nop 0
	global_store_dword v1, v18, s[12:13] sc1
; #define GAS __attribute__((address_space(1)))
; __device__ __forceinline__ float lx_xor(float v, int m, int lane) { return __int_as_float(__builtin_amdgcn_ds_bpermute((lane ^ m) << 2, __float_as_int(v))); }
; __device__ __forceinline__ unsigned cvtpk_h(float lo, float hi) { f32x2 v = {lo, hi}; h16x2 b = __builtin_convertvector(v, h16x2); return __builtin_bit_cast(unsigned, b); }
; __device__ __forceinline__ void p0c(Frame& F) {
;     ...
;     { const int gw = F.bid * NWAVES + F.wave, NGW = F.G * NWAVES; h16* XS = (h16*)(ws + WS_XS); h16* X16 = (h16*)(ws + WS_X16); float* RQ = (float*)(ws + WS_ROWSQ);
;       for (int r0 = gw; r0 < MROWS; r0 += 2 * NGW) {
;           f32x4 xv[2][2][2]; int rr[2]; bool ok[2];
; #pragma unroll
;           for (int q = 0; q < 2; ++q) { rr[q] = r0 + q * NGW; ok[q] = rr[q] < MROWS; const int r = ok[q] ? rr[q] : gw; const float* xr = r < MLAT ? p.x + (size_t)r * D : p.ctx + (size_t)(r - MLAT) * D;
; #pragma unroll
;               for (int j = 0; j < 2; ++j) { const int k = j * 512 + F.lane * 8; xv[q][j][0] = *(const GAS f32x4*)(xr + k); xv[q][j][1] = *(const GAS f32x4*)(xr + k + 4); } }
; #pragma unroll
;           for (int q = 0; q < 2; ++q) { const int r = ok[q] ? rr[q] : gw; const int bb = r < MLAT ? (r >> 11) : 16; const float* mod = MOD + (size_t)bb * 3072 + 1024; float ss = 0.f;
; #pragma unroll
;               for (int j = 0; j < 2; ++j) { const int k = j * 512 + F.lane * 8; u32x4 wx, wy;
; #pragma unroll
;                   for (int hh = 0; hh < 2; ++hh) { const f32x4 v = xv[q][j][hh], g = *(const GAS f32x4*)(p.gnorm + k + 4 * hh), s1 = *(const GAS f32x4*)(mod + k + 4 * hh);
;                       ss += (v[0] * v[0] + v[1] * v[1]) + (v[2] * v[2] + v[3] * v[3]); const f32x4 y = v * (g * (s1 + 1.f));
;                       if (hh == 0) { wy.x = cvtpk_h(y[0], y[1]); wy.y = cvtpk_h(y[2], y[3]); wx.x = cvtpk_h(v[0], v[1]); wx.y = cvtpk_h(v[2], v[3]); } else { wy.z = cvtpk_h(y[0], y[1]); wy.w = cvtpk_h(y[2], y[3]); wx.z = cvtpk_h(v[0], v[1]); wx.w = cvtpk_h(v[2], v[3]); } }
;                   if (ok[q]) { *(GAS u32x4*)(XS + (size_t)r * D + k) = wy; *(GAS u32x4*)(X16 + (size_t)r * D + k) = wx; } }
; #pragma unroll
;               for (int o = 1; o < 64; o <<= 1) ss += lx_xor(ss, o, F.lane);
;               if (ok[q] && F.lane == 0) *(GAS float*)(RQ + r) = ss; } }
.LBB0_706:
	s_or_b64 exec, exec, s[2:3]
	s_min_i32 s2, s8, 0x8000
	s_ashr_i32 s2, s2, 11
	s_mul_hi_i32 s3, s2, 0x3000
	s_mulk_i32 s2, 0x3000
	s_add_u32 s2, s36, s2
	s_addc_u32 s3, s37, s3
	s_add_u32 s12, s2, 0x1000
	s_addc_u32 s13, s3, 0
	s_lshl_b64 s[2:3], s[8:9], 11
	s_add_u32 s22, s16, s2
	s_addc_u32 s23, s17, s3
	s_add_u32 s24, s14, s2
	s_addc_u32 s25, s15, s3
	v_cndmask_b32_e64 v18, 0, 1, s[10:11]
	v_lshlrev_b64 v[20:21], 1, v[36:37]
	v_cmp_ne_u32_e64 s[2:3], 1, v18
	s_andn2_b64 vcc, exec, s[10:11]
	s_waitcnt lgkmcnt(0)
	v_lshl_add_u64 v[18:19], s[22:23], 0, v[20:21]
	v_lshl_add_u64 v[20:21], s[24:25], 0, v[20:21]
	s_cbranch_vccnz .LBB0_708
	v_lshl_add_u64 v[26:27], v[36:37], 2, s[12:13]
	global_load_dwordx4 v[22:25], v[26:27], off
	s_nop 0
	global_load_dwordx4 v[26:29], v[26:27], off offset:16
	s_nop 0
	global_load_dwordx4 v[30:33], v[40:41], off
	global_load_dwordx4 v[44:47], v[40:41], off offset:16
	v_cvt_pk_f16_f32 v56, v14, v15
	v_cvt_pk_f16_f32 v57, v16, v17
	v_cvt_pk_f16_f32 v58, v10, v11
	v_cvt_pk_f16_f32 v59, v12, v13
	s_waitcnt vmcnt(3)
	v_pk_add_f32 v[24:25], v[24:25], 1.0 op_sel_hi:[1,0]
	v_pk_add_f32 v[22:23], v[22:23], 1.0 op_sel_hi:[1,0]
	s_waitcnt vmcnt(2)
	v_pk_add_f32 v[28:29], v[28:29], 1.0 op_sel_hi:[1,0]
	v_pk_add_f32 v[26:27], v[26:27], 1.0 op_sel_hi:[1,0]
	s_waitcnt vmcnt(1)
	v_pk_mul_f32 v[24:25], v[32:33], v[24:25]
	v_pk_mul_f32 v[22:23], v[30:31], v[22:23]
	s_waitcnt vmcnt(0)
	v_pk_mul_f32 v[28:29], v[46:47], v[28:29]
	v_pk_mul_f32 v[26:27], v[44:45], v[26:27]
	v_pk_mul_f32 v[24:25], v[16:17], v[24:25]
	v_pk_mul_f32 v[22:23], v[14:15], v[22:23]
	v_pk_mul_f32 v[28:29], v[12:13], v[28:29]
	v_pk_mul_f32 v[26:27], v[10:11], v[26:27]
	v_cvt_pk_f16_f32 v22, v22, v23
	v_cvt_pk_f16_f32 v23, v24, v25
	v_cvt_pk_f16_f32 v24, v26, v27
	v_cvt_pk_f16_f32 v25, v28, v29
	global_store_dwordx4 v[20:21], v[22:25], off sc1
	global_store_dwordx4 v[18:19], v[56:59], off sc1
.LBB0_708:
	v_readlane_b32 s30, v252, 54
	s_and_b64 vcc, exec, s[2:3]
	v_readlane_b32 s31, v252, 55
	s_cbranch_vccnz .LBB0_710
	v_lshl_add_u64 v[26:27], v[38:39], 2, s[12:13]
	global_load_dwordx4 v[22:25], v[26:27], off
	s_nop 0
	global_load_dwordx4 v[26:29], v[26:27], off offset:16
	s_nop 0
	global_load_dwordx4 v[30:33], v[40:41], off offset:2048
	global_load_dwordx4 v[44:47], v[40:41], off offset:2064
	v_cvt_pk_f16_f32 v56, v6, v7
	v_cvt_pk_f16_f32 v57, v8, v9
	v_cvt_pk_f16_f32 v58, v2, v3
	v_cvt_pk_f16_f32 v59, v4, v5
	s_waitcnt vmcnt(3)
	v_pk_add_f32 v[24:25], v[24:25], 1.0 op_sel_hi:[1,0]
	v_pk_add_f32 v[22:23], v[22:23], 1.0 op_sel_hi:[1,0]
	s_waitcnt vmcnt(2)
	v_pk_add_f32 v[28:29], v[28:29], 1.0 op_sel_hi:[1,0]
	v_pk_add_f32 v[26:27], v[26:27], 1.0 op_sel_hi:[1,0]
	s_waitcnt vmcnt(1)
	v_pk_mul_f32 v[24:25], v[32:33], v[24:25]
	v_pk_mul_f32 v[22:23], v[30:31], v[22:23]
	s_waitcnt vmcnt(0)
	v_pk_mul_f32 v[28:29], v[46:47], v[28:29]
	v_pk_mul_f32 v[26:27], v[44:45], v[26:27]
	v_pk_mul_f32 v[24:25], v[8:9], v[24:25]
	v_pk_mul_f32 v[22:23], v[6:7], v[22:23]
	v_pk_mul_f32 v[28:29], v[4:5], v[28:29]
	v_pk_mul_f32 v[26:27], v[2:3], v[26:27]
	v_cvt_pk_f16_f32 v22, v22, v23
	v_cvt_pk_f16_f32 v23, v24, v25
	v_cvt_pk_f16_f32 v24, v26, v27
	v_cvt_pk_f16_f32 v25, v28, v29
	global_store_dwordx4 v[20:21], v[22:25], off offset:1024 sc1
	global_store_dwordx4 v[18:19], v[56:59], off offset:1024 sc1
.LBB0_710:
	v_mul_f32_e32 v15, v15, v15
	v_mul_f32_e32 v11, v11, v11
	v_fmac_f32_e32 v15, v14, v14
	v_mul_f32_e32 v14, v17, v17
	v_fmac_f32_e32 v11, v10, v10
	v_mul_f32_e32 v10, v13, v13
	v_mul_f32_e32 v7, v7, v7
	v_fmac_f32_e32 v14, v16, v16
	v_fmac_f32_e32 v10, v12, v12
	v_fmac_f32_e32 v7, v6, v6
	v_mul_f32_e32 v6, v9, v9
	v_mul_f32_e32 v3, v3, v3
	v_add_f32_e32 v14, v15, v14
	v_add_f32_e32 v10, v11, v10
	v_fmac_f32_e32 v6, v8, v8
	v_fmac_f32_e32 v3, v2, v2
	v_mul_f32_e32 v2, v5, v5
	v_add_f32_e32 v10, v14, v10
	v_add_f32_e32 v6, v7, v6
	v_fmac_f32_e32 v2, v4, v4
	v_add_f32_e32 v6, v10, v6
	v_add_f32_e32 v2, v3, v2
	v_add_f32_e32 v2, v6, v2
	ds_bpermute_b32 v3, v0, v2
	s_and_b64 s[10:11], s[0:1], s[10:11]
	s_waitcnt lgkmcnt(0)
	v_add_f32_e32 v2, v2, v3
	ds_bpermute_b32 v3, v50, v2
	s_waitcnt lgkmcnt(0)
	v_add_f32_e32 v2, v2, v3
	ds_bpermute_b32 v3, v51, v2
	s_waitcnt lgkmcnt(0)
	v_add_f32_e32 v2, v2, v3
	ds_bpermute_b32 v3, v52, v2
	s_waitcnt lgkmcnt(0)
	v_add_f32_e32 v2, v2, v3
	ds_bpermute_b32 v3, v53, v2
	s_waitcnt lgkmcnt(0)
	v_add_f32_e32 v2, v2, v3
	ds_bpermute_b32 v3, v54, v2
	s_and_saveexec_b64 s[2:3], s[10:11]
	s_cbranch_execz .LBB0_703
	s_lshl_b64 s[8:9], s[8:9], 2
	s_add_u32 s8, s18, s8
	s_addc_u32 s9, s19, s9
	s_waitcnt lgkmcnt(0)
	v_add_f32_e32 v2, v2, v3
	global_store_dword v1, v2, s[8:9] sc1
	s_branch .LBB0_703

; #define GAS __attribute__((address_space(1)))
; __device__ __forceinline__ void p0c(Frame& F) {
;     ...
;       const int gt = F.bid * NTHREADS + F.tid;
;       for (int i = gt; i < 15 * MROWS / 4; i += F.G * NTHREADS) *(GAS f32x4*)(RQ + MROWS + 4 * (size_t)i) = (f32x4){0.f, 0.f, 0.f, 0.f};
.LBB0_714:
	v_add_u32_e32 v34, s28, v34
	s_mov_b32 s4, 0x21bff
	v_cmp_lt_i32_e32 vcc, s4, v34
	global_store_dwordx4 v[2:3], v[234:237], off sc1
	s_or_b64 s[2:3], vcc, s[2:3]
	v_lshl_add_u64 v[2:3], v[2:3], 0, s[88:89]
	s_andn2_b64 exec, exec, s[2:3]
	s_cbranch_execnz .LBB0_714

; #define LAS __attribute__((address_space(3)))
; #define GAS __attribute__((address_space(1)))
; __device__ __forceinline__ unsigned cvtpk_h(float lo, float hi) { f32x2 v = {lo, hi}; h16x2 b = __builtin_convertvector(v, h16x2); return __builtin_bit_cast(unsigned, b); }
; template <bool INPROJ> __device__ __forceinline__ void p0_transpose_tile(Frame& F, const float* W, int N  , h16* WT, int item) {
;     ...
;     for (int j = 0; j < 8; ++j) wv[j] = valid ? *(const GAS f32x4*)(W + (size_t)(k0 + 8 * F.wave + j) * N + nn) : (f32x4){0.f, 0.f, 0.f, 0.f};
; #pragma unroll
;     for (int j = 0; j < 8; ++j) { LAS float* t = T + (8 * F.wave + j) * LS + 4 * F.lane; t[0] = wv[j][0]; t[1] = wv[j][1]; t[2] = wv[j][2]; t[3] = wv[j][3]; }
;     __syncthreads();
;     const int c = F.lane & 7;
; #pragma unroll
;     for (int ps = 0; ps < 4; ++ps) { const int n = 32 * F.wave + 8 * ps + (F.lane >> 3); const LAS float* s = T + (8 * c) * LS + n;
;         u32x4 o; o.x = cvtpk_h(s[0 * LS], s[1 * LS]); o.y = cvtpk_h(s[2 * LS], s[3 * LS]); o.z = cvtpk_h(s[4 * LS], s[5 * LS]); o.w = cvtpk_h(s[6 * LS], s[7 * LS]);
;         const int col = n0 + n, ca = col & 255; const bool mapA = INPROJ && slab_is_mapA(col >> 6);
;         *(GAS u32x4*)(WT + (size_t)(nt * 256 + tile_pos_of_col(ca, mapA)) * K + k0 + 8 * c) = o; }
;     __syncthreads();
.LBB0_720:
	s_or_b64 exec, exec, s[4:5]
	v_add_u32_e32 v0, s11, v39
	s_waitcnt vmcnt(0)
	ds_write2_b32 v0, v6, v7 offset1:1
	ds_write2_b32 v0, v8, v9 offset0:2 offset1:3
	v_add_u32_e32 v6, 0x404, v0
	ds_write2_b32 v6, v2, v3 offset1:1
	v_add_u32_e32 v2, 0x40c, v0
	ds_write2_b32 v2, v4, v5 offset1:1
	v_add_u32_e32 v2, 0x808, v0
	ds_write2_b32 v2, v14, v15 offset1:1
	v_add_u32_e32 v2, 0x810, v0
	ds_write2_b32 v2, v16, v17 offset1:1
	v_add_u32_e32 v2, 0xc0c, v0
	ds_write2_b32 v2, v10, v11 offset1:1
	v_add_u32_e32 v2, 0xc14, v0
	ds_write2_b32 v2, v12, v13 offset1:1
	v_add_u32_e32 v2, 0x1010, v0
	ds_write2_b32 v2, v22, v23 offset1:1
	v_add_u32_e32 v2, 0x1018, v0
	ds_write2_b32 v2, v24, v25 offset1:1
	v_add_u32_e32 v2, 0x1414, v0
	s_mul_hi_i32 s3, s0, 0x700000
	s_mul_i32 s0, s0, 0x700000
	ds_write2_b32 v2, v18, v19 offset1:1
	v_add_u32_e32 v2, 0x141c, v0
	s_add_u32 s0, s8, s0
	ds_write2_b32 v2, v20, v21 offset1:1
	v_add_u32_e32 v2, 0x1818, v0
	s_addc_u32 s4, s9, s3
	ds_write2_b32 v2, v30, v31 offset1:1
	v_add_u32_e32 v2, 0x1820, v0
	s_ashr_i32 s3, s2, 31
	ds_write2_b32 v2, v32, v33 offset1:1
	v_add_u32_e32 v2, 0x1c1c, v0
	s_lshl_b64 s[2:3], s[2:3], 1
	ds_write2_b32 v2, v26, v27 offset1:1
	v_add_u32_e32 v0, 0x1c24, v0
	s_add_u32 s2, s0, s2
	v_add_u32_e32 v26, 0x400, v41
	ds_write2_b32 v0, v28, v29 offset1:1
	s_waitcnt lgkmcnt(0)
	s_barrier
	s_addc_u32 s3, s4, s3
	v_lshlrev_b32_e32 v0, 1, v34
	ds_read2_b32 v[6:7], v26 offset0:1 offset1:9
	ds_read2_b32 v[8:9], v41 offset1:8
	v_lshl_add_u64 v[22:23], s[2:3], 0, v[0:1]
	v_add_u32_e32 v0, s1, v40
	v_ashrrev_i32_e32 v0, 6, v0
	v_add_u32_e32 v0, -12, v0
	v_cmp_gt_u32_e32 vcc, 10, v0
	s_waitcnt lgkmcnt(0)
	v_cvt_pk_f16_f32 v2, v8, v6
	v_add_u32_e32 v27, 0x800, v41
	v_cndmask_b32_e32 v0, v51, v50, vcc
	v_cndmask_b32_e32 v6, v52, v51, vcc
	v_lshlrev_b32_e32 v0, 4, v0
	v_lshlrev_b32_e32 v6, 2, v6
	v_and_b32_e32 v0, 16, v0
	v_and_b32_e32 v6, 12, v6
	v_or3_b32 v0, v53, v0, v6
	v_or3_b32 v24, v0, v42, s1
	v_add_u32_e32 v0, s1, v44
	v_ashrrev_i32_e32 v0, 6, v0
	v_add_u32_e32 v28, 0xc00, v41
	v_add_u32_e32 v29, 0x1000, v41
	v_add_u32_e32 v30, 0x1400, v41
	v_add_u32_e32 v31, 0x1800, v41
	v_add_u32_e32 v32, 0x1c00, v41
	v_add_u32_e32 v0, -12, v0
	ds_read2_b32 v[10:11], v27 offset0:2 offset1:10
	ds_read2_b32 v[12:13], v28 offset0:3 offset1:11
	ds_read2_b32 v[14:15], v29 offset0:4 offset1:12
	ds_read2_b32 v[16:17], v30 offset0:5 offset1:13
	ds_read2_b32 v[18:19], v31 offset0:6 offset1:14
	ds_read2_b32 v[20:21], v32 offset0:7 offset1:15
	v_cmp_gt_u32_e32 vcc, 10, v0
	v_ashrrev_i32_e32 v25, 31, v24
	v_lshlrev_b64 v[24:25], 11, v[24:25]
	v_cndmask_b32_e32 v0, v55, v54, vcc
	v_cndmask_b32_e32 v6, v56, v55, vcc
	v_lshlrev_b32_e32 v0, 4, v0
	v_lshlrev_b32_e32 v6, 2, v6
	v_and_b32_e32 v0, 16, v0
	v_and_b32_e32 v6, 12, v6
	v_or3_b32 v0, v57, v0, v6
	s_waitcnt lgkmcnt(4)
	v_cvt_pk_f16_f32 v3, v10, v12
	s_waitcnt lgkmcnt(2)
	v_cvt_pk_f16_f32 v4, v14, v16
	s_waitcnt lgkmcnt(0)
	v_cvt_pk_f16_f32 v5, v18, v20
	v_lshl_add_u64 v[24:25], v[22:23], 0, v[24:25]
	v_or3_b32 v6, v0, v42, s1
	v_add_u32_e32 v0, s1, v46
	global_store_dwordx4 v[24:25], v[2:5], off sc1
	v_ashrrev_i32_e32 v0, 6, v0
	v_add_u32_e32 v0, -12, v0
	v_cvt_pk_f16_f32 v2, v9, v7
	v_ashrrev_i32_e32 v7, 31, v6
	v_lshlrev_b64 v[6:7], 11, v[6:7]
	v_cvt_pk_f16_f32 v3, v11, v13
	v_cvt_pk_f16_f32 v4, v15, v17
	v_cvt_pk_f16_f32 v5, v19, v21
	v_lshl_add_u64 v[6:7], v[22:23], 0, v[6:7]
	v_cmp_gt_u32_e32 vcc, 10, v0
	ds_read2_b32 v[8:9], v41 offset0:16 offset1:24
	ds_read2_b32 v[10:11], v26 offset0:17 offset1:25
	ds_read2_b32 v[12:13], v27 offset0:18 offset1:26
	ds_read2_b32 v[14:15], v28 offset0:19 offset1:27
	ds_read2_b32 v[16:17], v29 offset0:20 offset1:28
	ds_read2_b32 v[18:19], v30 offset0:21 offset1:29
	ds_read2_b32 v[20:21], v31 offset0:22 offset1:30
	ds_read2_b32 v[24:25], v32 offset0:23 offset1:31
	global_store_dwordx4 v[6:7], v[2:5], off sc1
	v_cndmask_b32_e32 v0, v59, v58, vcc
	v_cndmask_b32_e32 v6, v60, v59, vcc
	v_lshlrev_b32_e32 v0, 4, v0
	v_lshlrev_b32_e32 v6, 2, v6
	v_and_b32_e32 v0, 16, v0
	v_and_b32_e32 v6, 12, v6
	v_or3_b32 v0, v61, v0, v6
	v_or3_b32 v6, v0, v42, s1
	v_add_u32_e32 v0, s1, v48
	v_ashrrev_i32_e32 v7, 31, v6
	v_ashrrev_i32_e32 v0, 6, v0
	v_lshlrev_b64 v[6:7], 11, v[6:7]
	v_add_u32_e32 v0, -12, v0
	s_waitcnt lgkmcnt(6)
	v_cvt_pk_f16_f32 v2, v8, v10
	s_waitcnt lgkmcnt(4)
	v_cvt_pk_f16_f32 v3, v12, v14
	s_waitcnt lgkmcnt(2)
	v_cvt_pk_f16_f32 v4, v16, v18
	s_waitcnt lgkmcnt(0)
	v_cvt_pk_f16_f32 v5, v20, v24
	v_lshl_add_u64 v[6:7], v[22:23], 0, v[6:7]
	v_cmp_gt_u32_e32 vcc, 10, v0
	global_store_dwordx4 v[6:7], v[2:5], off sc1
	s_nop 0
	v_cndmask_b32_e32 v0, v63, v62, vcc
	v_cndmask_b32_e32 v6, v64, v63, vcc
	v_lshlrev_b32_e32 v0, 4, v0
	v_lshlrev_b32_e32 v6, 2, v6
	v_and_b32_e32 v0, 16, v0
	v_and_b32_e32 v6, 12, v6
	v_or3_b32 v0, v65, v0, v6
	v_or3_b32 v6, v0, v42, s1
	v_ashrrev_i32_e32 v7, 31, v6
	v_lshlrev_b64 v[6:7], 11, v[6:7]
	v_cvt_pk_f16_f32 v2, v9, v11
	v_cvt_pk_f16_f32 v3, v13, v15
	v_cvt_pk_f16_f32 v4, v17, v19
	v_cvt_pk_f16_f32 v5, v21, v25
	v_lshl_add_u64 v[6:7], v[22:23], 0, v[6:7]
	global_store_dwordx4 v[6:7], v[2:5], off sc1
	s_barrier

; #define LAS __attribute__((address_space(3)))
; #define GAS __attribute__((address_space(1)))
; __device__ __forceinline__ unsigned cvtpk_h(float lo, float hi) { f32x2 v = {lo, hi}; h16x2 b = __builtin_convertvector(v, h16x2); return __builtin_bit_cast(unsigned, b); }
; template <bool INPROJ> __device__ __forceinline__ void p0_transpose_tile(Frame& F, const float* W, int N  , h16* WT, int item) {
;     ...
;     for (int j = 0; j < 8; ++j) wv[j] = valid ? *(const GAS f32x4*)(W + (size_t)(k0 + 8 * F.wave + j) * N + nn) : (f32x4){0.f, 0.f, 0.f, 0.f};
; #pragma unroll
;     for (int j = 0; j < 8; ++j) { LAS float* t = T + (8 * F.wave + j) * LS + 4 * F.lane; t[0] = wv[j][0]; t[1] = wv[j][1]; t[2] = wv[j][2]; t[3] = wv[j][3]; }
;     __syncthreads();
;     const int c = F.lane & 7;
; #pragma unroll
;     for (int ps = 0; ps < 4; ++ps) { const int n = 32 * F.wave + 8 * ps + (F.lane >> 3); const LAS float* s = T + (8 * c) * LS + n;
;         u32x4 o; o.x = cvtpk_h(s[0 * LS], s[1 * LS]); o.y = cvtpk_h(s[2 * LS], s[3 * LS]); o.z = cvtpk_h(s[4 * LS], s[5 * LS]); o.w = cvtpk_h(s[6 * LS], s[7 * LS]);
;         const int col = n0 + n, ca = col & 255; const bool mapA = INPROJ && slab_is_mapA(col >> 6);
;         *(GAS u32x4*)(WT + (size_t)(nt * 256 + tile_pos_of_col(ca, mapA)) * K + k0 + 8 * c) = o; }
;     __syncthreads();
.LBB0_739:
	s_or_b64 exec, exec, s[4:5]
	v_add_u32_e32 v0, s11, v39
	s_waitcnt vmcnt(0)
	ds_write2_b32 v0, v6, v7 offset1:1
	ds_write2_b32 v0, v8, v9 offset0:2 offset1:3
	v_add_u32_e32 v6, 0x404, v0
	ds_write2_b32 v6, v2, v3 offset1:1
	v_add_u32_e32 v2, 0x40c, v0
	ds_write2_b32 v2, v4, v5 offset1:1
	v_add_u32_e32 v2, 0x808, v0
	ds_write2_b32 v2, v14, v15 offset1:1
	v_add_u32_e32 v2, 0x810, v0
	ds_write2_b32 v2, v16, v17 offset1:1
	v_add_u32_e32 v2, 0xc0c, v0
	ds_write2_b32 v2, v10, v11 offset1:1
	v_add_u32_e32 v2, 0xc14, v0
	ds_write2_b32 v2, v12, v13 offset1:1
	v_add_u32_e32 v2, 0x1010, v0
	ds_write2_b32 v2, v22, v23 offset1:1
	v_add_u32_e32 v2, 0x1018, v0
	ds_write2_b32 v2, v24, v25 offset1:1
	v_add_u32_e32 v2, 0x1414, v0
	ds_write2_b32 v2, v18, v19 offset1:1
	v_add_u32_e32 v2, 0x141c, v0
	ds_write2_b32 v2, v20, v21 offset1:1
	v_add_u32_e32 v2, 0x1818, v0
	s_lshl_b64 s[2:3], s[0:1], 20
	ds_write2_b32 v2, v30, v31 offset1:1
	v_add_u32_e32 v2, 0x1820, v0
	s_lshl_b64 s[2:3], s[2:3], 1
	ds_write2_b32 v2, v32, v33 offset1:1
	v_add_u32_e32 v2, 0x1c1c, v0
	v_add_u32_e32 v0, 0x1c24, v0
	s_add_u32 s1, s6, s2
	ds_write2_b32 v2, v26, v27 offset1:1
	ds_write2_b32 v0, v28, v29 offset1:1
	v_add_u32_e32 v26, 0x400, v41
	v_add_u32_e32 v27, 0x800, v41
	v_add_u32_e32 v28, 0xc00, v41
	v_add_u32_e32 v29, 0x1000, v41
	v_add_u32_e32 v30, 0x1400, v41
	v_add_u32_e32 v31, 0x1800, v41
	v_add_u32_e32 v32, 0x1c00, v41
	s_addc_u32 s3, s7, s3
	s_waitcnt lgkmcnt(0)
	s_barrier
	s_lshl_b32 s2, s18, 1
	ds_read2_b32 v[6:7], v26 offset0:1 offset1:9
	ds_read2_b32 v[8:9], v41 offset1:8
	ds_read2_b32 v[10:11], v27 offset0:2 offset1:10
	ds_read2_b32 v[12:13], v28 offset0:3 offset1:11
	ds_read2_b32 v[14:15], v29 offset0:4 offset1:12
	ds_read2_b32 v[16:17], v30 offset0:5 offset1:13
	ds_read2_b32 v[18:19], v31 offset0:6 offset1:14
	ds_read2_b32 v[20:21], v32 offset0:7 offset1:15
	s_add_u32 s2, s1, s2
	s_addc_u32 s3, s3, 0
	v_lshlrev_b32_e32 v0, 1, v34
	v_lshl_add_u64 v[22:23], s[2:3], 0, v[0:1]
	v_or_b32_e32 v0, s17, v43
	v_lshlrev_b32_e32 v0, 11, v0
	s_waitcnt lgkmcnt(6)
	v_cvt_pk_f16_f32 v2, v8, v6
	s_waitcnt lgkmcnt(4)
	v_cvt_pk_f16_f32 v3, v10, v12
	s_waitcnt lgkmcnt(2)
	v_cvt_pk_f16_f32 v4, v14, v16
	s_waitcnt lgkmcnt(0)
	v_cvt_pk_f16_f32 v5, v18, v20
	v_lshl_add_u64 v[24:25], v[22:23], 0, v[0:1]
	global_store_dwordx4 v[24:25], v[2:5], off sc1
	v_or_b32_e32 v0, s17, v45
	v_lshlrev_b32_e32 v0, 11, v0
	v_cvt_pk_f16_f32 v2, v9, v7
	v_cvt_pk_f16_f32 v3, v11, v13
	v_cvt_pk_f16_f32 v4, v15, v17
	v_cvt_pk_f16_f32 v5, v19, v21
	ds_read2_b32 v[8:9], v41 offset0:16 offset1:24
	ds_read2_b32 v[10:11], v26 offset0:17 offset1:25
	ds_read2_b32 v[12:13], v27 offset0:18 offset1:26
	ds_read2_b32 v[14:15], v28 offset0:19 offset1:27
	ds_read2_b32 v[16:17], v29 offset0:20 offset1:28
	ds_read2_b32 v[18:19], v30 offset0:21 offset1:29
	ds_read2_b32 v[20:21], v31 offset0:22 offset1:30
	ds_read2_b32 v[24:25], v32 offset0:23 offset1:31
	v_lshl_add_u64 v[6:7], v[22:23], 0, v[0:1]
	v_or_b32_e32 v0, s17, v47
	v_lshlrev_b32_e32 v0, 11, v0
	global_store_dwordx4 v[6:7], v[2:5], off sc1
	v_lshl_add_u64 v[6:7], v[22:23], 0, v[0:1]
	v_or_b32_e32 v0, s17, v49
	s_waitcnt lgkmcnt(6)
	v_cvt_pk_f16_f32 v2, v8, v10
	s_waitcnt lgkmcnt(4)
	v_cvt_pk_f16_f32 v3, v12, v14
	s_waitcnt lgkmcnt(2)
	v_cvt_pk_f16_f32 v4, v16, v18
	s_waitcnt lgkmcnt(0)
	v_cvt_pk_f16_f32 v5, v20, v24
	v_lshlrev_b32_e32 v0, 11, v0
	global_store_dwordx4 v[6:7], v[2:5], off sc1
	v_lshl_add_u64 v[6:7], v[22:23], 0, v[0:1]
	s_mov_b64 s[2:3], 0
	v_cvt_pk_f16_f32 v2, v9, v11
	v_cvt_pk_f16_f32 v3, v13, v15
	v_cvt_pk_f16_f32 v4, v17, v19
	v_cvt_pk_f16_f32 v5, v21, v25
	global_store_dwordx4 v[6:7], v[2:5], off sc1
	s_barrier

; __device__ __forceinline__ float lx_xor(float v, int m, int lane) { return __int_as_float(__builtin_amdgcn_ds_bpermute((lane ^ m) << 2, __float_as_int(v))); }
; __device__ __forceinline__ unsigned cvtpk_h(float lo, float hi) { f32x2 v = {lo, hi}; h16x2 b = __builtin_convertvector(v, h16x2); return __builtin_bit_cast(unsigned, b); }
; __device__ __forceinline__ void p0ab(Frame& F) {
;     ...
;       for (int i = gt; i < DEPTH * 4 * 128 * 128 / 4; i += F.G * NTHREADS) { const f32x4 v = ((const f32x4*)p.wsp)[i]; u32x2 w; w.x = cvtpk_h(v[0], v[1]); w.y = cvtpk_h(v[2], v[3]); ((u32x2*)(ws + WS_WS16))[i] = w; }
;       if (F.bid == 1 && F.tid < 64 * DEPTH) { const int l = F.tid >> 6, d = F.lane; float a = fabsf(p.gq[l * 64 + d]), b2 = fabsf(p.gk[l * 64 + d]);
; #pragma unroll
;           for (int o = 1; o < 64; o <<= 1) { a = fmaxf(a, lx_xor(a, o, d)); b2 = fmaxf(b2, lx_xor(b2, o, d)); }
;           if (d == 0) ((float*)(ws + WS_ROPE))[2048 + l] = 8.f * 1.4426950408889634f * a * b2 - 15.f; }
.LBB0_759:
	global_load_dwordx4 v[8:11], v[4:5], off
	v_add_u32_e32 v2, s28, v2
	s_mov_b32 s4, 0xffff
	v_cmp_lt_i32_e32 vcc, s4, v2
	v_lshl_add_u64 v[4:5], v[4:5], 0, s[88:89]
	s_or_b64 s[2:3], vcc, s[2:3]
	s_waitcnt vmcnt(0)
	v_cvt_pk_f16_f32 v8, v8, v9
	v_cvt_pk_f16_f32 v9, v10, v11
	flat_store_dwordx2 v[6:7], v[8:9] sc1
	v_lshl_add_u64 v[6:7], v[6:7], 0, s[70:71]
	s_andn2_b64 exec, exec, s[2:3]
	s_cbranch_execnz .LBB0_759
.LBB0_760:
	s_or_b64 exec, exec, s[0:1]
	s_cmp_lt_i32 s73, 1
	s_mov_b64 s[0:1], -1
	s_cbranch_scc1 .LBB0_767
	s_cmp_eq_u32 s73, 1
	s_cbranch_scc0 .LBB0_766
	v_cmp_gt_i32_e32 vcc, s87, v212
	s_and_saveexec_b64 s[0:1], vcc
	s_cbranch_execz .LBB0_765
	v_and_b32_e32 v0, 0xffffffc0, v212
	v_add_u32_e32 v2, v0, v246
	s_waitcnt lgkmcnt(0)
	v_ashrrev_i32_e32 v3, 31, v2
	v_readlane_b32 s4, v252, 28
	v_lshlrev_b64 v[2:3], 2, v[2:3]
	v_readlane_b32 s8, v252, 32
	v_readlane_b32 s9, v252, 33
	v_readlane_b32 s10, v252, 34
	v_readlane_b32 s11, v252, 35
	v_lshl_add_u64 v[4:5], s[8:9], 0, v[2:3]
	global_load_dword v0, v[4:5], off
	v_lshl_add_u64 v[2:3], s[10:11], 0, v[2:3]
	global_load_dword v2, v[2:3], off
	v_xor_b32_e32 v3, 4, v38
	v_cmp_eq_u32_e32 vcc, 0, v246
	v_readlane_b32 s5, v252, 29
	v_readlane_b32 s6, v252, 30
	v_readlane_b32 s7, v252, 31
	v_readlane_b32 s12, v252, 36
	v_readlane_b32 s13, v252, 37
	v_readlane_b32 s14, v252, 38
	v_readlane_b32 s15, v252, 39
	v_readlane_b32 s16, v252, 40
	v_readlane_b32 s17, v252, 41
	v_readlane_b32 s18, v252, 42
	v_readlane_b32 s19, v252, 43
	s_waitcnt vmcnt(0)
	v_and_b32_e32 v4, 0x7fffffff, v0
	ds_bpermute_b32 v4, v3, v4
	v_and_b32_e32 v5, 0x7fffffff, v2
	ds_bpermute_b32 v3, v3, v5
	v_max_f32_e64 v0, |v0|, |v0|
	v_max_f32_e64 v2, |v2|, |v2|
	s_waitcnt lgkmcnt(1)
	v_max_f32_e32 v4, v4, v4
	v_xor_b32_e32 v5, 8, v38
	s_waitcnt lgkmcnt(0)
	v_max_f32_e32 v3, v3, v3
	v_max_f32_e32 v0, v0, v4
	v_max_f32_e32 v2, v2, v3
	ds_bpermute_b32 v3, v5, v0
	ds_bpermute_b32 v4, v5, v2
	v_xor_b32_e32 v5, 16, v38
	s_waitcnt lgkmcnt(1)
	v_max_f32_e32 v3, v3, v3
	s_waitcnt lgkmcnt(0)
	v_max_f32_e32 v4, v4, v4
	v_max_f32_e32 v0, v0, v3
	v_max_f32_e32 v2, v2, v4
	ds_bpermute_b32 v3, v5, v0
	ds_bpermute_b32 v4, v5, v2
	v_xor_b32_e32 v5, 32, v38
	s_waitcnt lgkmcnt(1)
	v_max_f32_e32 v3, v3, v3
	s_waitcnt lgkmcnt(0)
	v_max_f32_e32 v4, v4, v4
	v_max_f32_e32 v0, v0, v3
	v_max_f32_e32 v2, v2, v4
	ds_bpermute_b32 v3, v5, v0
	ds_bpermute_b32 v4, v5, v2
	v_xor_b32_e32 v5, 64, v38
	s_waitcnt lgkmcnt(1)
	v_max_f32_e32 v3, v3, v3
	s_waitcnt lgkmcnt(0)
	v_max_f32_e32 v4, v4, v4
	v_max_f32_e32 v0, v0, v3
	v_max_f32_e32 v2, v2, v4
	ds_bpermute_b32 v3, v5, v0
	ds_bpermute_b32 v4, v5, v2
	v_xor_b32_e32 v5, 0x80, v38
	s_waitcnt lgkmcnt(1)
	v_max_f32_e32 v3, v3, v3
	s_waitcnt lgkmcnt(0)
	v_max_f32_e32 v4, v4, v4
	v_max_f32_e32 v0, v0, v3
	v_max_f32_e32 v3, v2, v4
	ds_bpermute_b32 v2, v5, v0
	ds_bpermute_b32 v4, v5, v3
	s_and_b64 exec, exec, vcc
	s_cbranch_execz .LBB0_765
	v_readlane_b32 s2, v252, 62
	v_readlane_b32 s3, v252, 63
	s_ashr_i32 s3, s2, 31
	s_waitcnt lgkmcnt(1)
	v_max_f32_e32 v2, v2, v2
	v_max_f32_e32 v0, v0, v0
	s_lshl_b64 s[2:3], s[2:3], 2
	v_readlane_b32 s4, v253, 0
	s_waitcnt lgkmcnt(0)
	v_max_f32_e32 v4, v4, v4
	v_max_f32_e32 v3, v3, v3
	v_max_f32_e32 v0, v0, v2
	v_readlane_b32 s5, v253, 1
	s_add_u32 s2, s4, s2
	v_max_f32_e32 v3, v3, v4
	s_addc_u32 s3, s5, s3
	v_mul_f32_e32 v0, 0x4138aa3b, v0
	v_mov_b32_e32 v2, s2
	v_fmaak_f32 v0, v3, v0, 0xc1700000
	v_add_co_u32_e32 v2, vcc, 0x2802000, v2
	v_mov_b32_e32 v3, s3
	s_nop 0
	v_addc_co_u32_e32 v3, vcc, 0, v3, vcc
	flat_store_dword v[2:3], v0 sc1

; __device__ __forceinline__ void p0ab(Frame& F) {
;     ...
;       if (F.bid == 0) { float* rope = (float*)(ws + WS_ROPE); for (int i = F.tid; i < 1024; i += NTHREADS) { const int pos = i >> 4, fi = i & 15; const float freq = exp2f(-(float)fi * (13.287712379549449f / 16.f)); const float rev = (float)pos * freq * 0.15915494309189535f;
;           const float fr_ = rev - floorf(rev); rope[i] = __builtin_amdgcn_cosf(fr_); rope[1024 + i] = __builtin_amdgcn_sinf(fr_); } }
.LBB0_771:
	v_ashrrev_i32_e32 v5, 4, v4
	v_cvt_f32_i32_e32 v5, v5
	v_add_u32_e32 v7, 0x200, v4
	s_movk_i32 s0, 0x1ff
	v_cmp_lt_i32_e64 s[0:1], s0, v4
	v_mul_f32_e32 v5, v0, v5
	v_mov_b32_e32 v4, v7
	v_mul_f32_e32 v7, 0.15915494, v5
	v_floor_f32_e32 v7, v7
	v_fma_f32 v5, v5, 0.15915494, -v7
	v_cos_f32_e32 v8, v5
	v_sin_f32_e32 v5, v5
	v_add_co_u32_e32 v6, vcc, 0xfffff000, v2
	s_or_b64 s[4:5], s[0:1], s[4:5]
	s_nop 0
	v_addc_co_u32_e32 v7, vcc, -1, v3, vcc
	flat_store_dword v[6:7], v8 sc1
	flat_store_dword v[2:3], v5 sc1
	v_lshl_add_u64 v[2:3], v[2:3], 0, s[60:61]
	s_andn2_b64 exec, exec, s[4:5]
	s_cbranch_execnz .LBB0_771

; __device__ __forceinline__ void skinny_item(Frame& F, const LAS float* AL, LAS float* RED, const float* W, int ldw, int nvalid, int n0, const float* bias, float* out, int ldo) {
;     ...
;     for (int o = F.tid; o < 17 * 64; o += NTHREADS) { const int i = o >> 6, c2 = o & 63; float s = 0.f;
; #pragma unroll
;         for (int g = 0; g < 8; ++g) s += RED[(g * 17 + i) * 64 + c2];
;         const int nn = n0 + c2; if (nn < ldo) out[(size_t)i * ldo + nn] = (nn < nvalid) ? s + (bias ? bias[nn] : 0.f) : 0.f; }
.LBB0_789:
	s_waitcnt lgkmcnt(0)
	v_add_f32_e32 v12, 0, v12
	v_add_f32_e32 v12, v12, v13
	s_waitcnt lgkmcnt(2)
	v_add_f32_e32 v10, v12, v10
	v_add_f32_e32 v10, v10, v11
	s_waitcnt lgkmcnt(1)
	v_add_f32_e32 v8, v10, v8
	v_add_f32_e32 v8, v8, v9
	s_waitcnt lgkmcnt(0)
	v_add_f32_e32 v6, v8, v6
	v_add_f32_e32 v6, v6, v7
	s_waitcnt vmcnt(0)
	v_add_f32_e32 v8, v6, v16
	v_mad_i64_i32 v[6:7], s[14:15], v15, s93, v[4:5]
	flat_store_dword v[6:7], v8 sc1
	v_add_u32_e32 v6, 0x200, v14
	v_cmp_lt_i32_e32 vcc, s72, v14
	s_or_b64 s[6:7], vcc, s[6:7]
	v_mov_b32_e32 v14, v6
	s_andn2_b64 exec, exec, s[6:7]
	s_cbranch_execz .LBB0_775

; __device__ __forceinline__ unsigned xb_add(unsigned* p, unsigned v) { return __hip_atomic_fetch_add(p, v, __ATOMIC_RELAXED, __HIP_MEMORY_SCOPE_AGENT); }
; __device__ __forceinline__ void xcd_barrier(const XcdBarrier& b) {
;     ...
;         const unsigned old = xb_add(&bar[XB_XSUB(b.x)], 1u);
;         const unsigned gen = old / nloc;
;         if (old + 1u == (gen + 1u) * nloc) {
;             __builtin_amdgcn_fence(__ATOMIC_RELEASE, "agent");
;             asm volatile("s_waitcnt vmcnt(0)" ::: "memory");
;             const unsigned og = xb_add(&bar[XB_TOP], 1u);
;             const unsigned tg = og / nx;
;             if (og + 1u == (tg + 1u) * nx) xb_add(&bar[XB_TOPGEN], 1u);
.LBB0_826:
	s_mov_b64 s[2:3], exec
	s_nop 0
	s_waitcnt lgkmcnt(0)
	s_waitcnt vmcnt(0)
	v_mbcnt_lo_u32_b32 v0, s2, 0
	v_mbcnt_hi_u32_b32 v0, s3, v0
	v_cmp_eq_u32_e32 vcc, 0, v0
	s_and_saveexec_b64 s[4:5], vcc
	s_cbranch_execz .LBB0_828
	s_bcnt1_i32_b64 s2, s[2:3]
	v_mov_b32_e32 v3, s2
	v_readlane_b32 s2, v252, 7
	v_readlane_b32 s3, v252, 8
	s_nop 4
	global_atomic_add v3, v1, v3, s[2:3] sc0
